# e16: e15 + write-through (sc0 sc1) on the 369 plain x2/x4 stores ahead of grid barriers in P0-P6, so the barrier's L2 write-back has nothing to flush
# baseline (speedup 1.0000x reference)
; #define LAS __attribute__((address_space(3)))
; __device__ __forceinline__ f32x4 ld_nt(const float* p) { return __builtin_nontemporal_load((const f32x4*)p); }
; __device__ __forceinline__ void transpose_item(const float* W, int K, int pitch, int ncols, f16* WT, LAS float* scr, int item, int lane) {
;     const int nblk = ncols / 32, kb = item / nblk, nb = item % nblk, k0 = 64 * kb, n0 = 32 * nb;
;     const int kr = lane >> 3, nq = (lane & 7) * 4;
;     f32x4 v[8];
; #pragma unroll
;     for (int i = 0; i < 8; ++i) v[i] = ld_nt(W + (size_t)(k0 + kr + 8 * i) * pitch + n0 + nq);
;     __builtin_amdgcn_sched_barrier(0);
; #pragma unroll
;     for (int i = 0; i < 8; ++i) { LAS float* sp = scr + (kr + 8 * i) * 33 + nq; sp[0] = v[i][0]; sp[1] = v[i][1]; sp[2] = v[i][2]; sp[3] = v[i][3]; }
;     asm volatile("s_waitcnt lgkmcnt(0)" ::: "memory");
;     const int c = lane & 7;
; #pragma unroll
;     for (int j = 0; j < 4; ++j) { const int n = (lane >> 3) + 8 * j; const LAS float* sp = scr + (8 * c) * 33 + n;
;         u32x4 o; o.x = pk_f16(sp[0 * 33], sp[1 * 33]); o.y = pk_f16(sp[2 * 33], sp[3 * 33]); o.z = pk_f16(sp[4 * 33], sp[5 * 33]); o.w = pk_f16(sp[6 * 33], sp[7 * 33]);
;         *(u32x4*)(WT + (size_t)(n0 + n) * K + k0 + 8 * c) = o; }
;     asm volatile("s_waitcnt lgkmcnt(0)" ::: "memory");
; }
.LBB0_12:
	s_cmpk_gt_u32 s8, 0x27f
	s_cbranch_scc0 .LBB0_22
	s_cmpk_gt_u32 s8, 0xe7f
	s_cbranch_scc0 .LBB0_19
	s_lshl_b32 s4, s8, 5
	v_and_b32_e32 v7, 7, v0
	s_and_b32 s9, s4, 0x7e0
	v_lshrrev_b32_e32 v8, 3, v212
	v_lshlrev_b32_e32 v1, 2, v7
	s_cmpk_gt_u32 s8, 0x167f
	s_mov_b32 s5, 0
	v_mov_b32_e32 v3, 0
	s_mov_b64 s[6:7], -1
	v_lshlrev_b32_e32 v2, 2, v1
	v_lshlrev_b32_e32 v4, 4, v7
	v_lshlrev_b32_e32 v6, 2, v8
	v_or_b32_e32 v1, s9, v8
	s_cbranch_scc0 .LBB0_16
	s_and_b32 s4, s8, 0x7fffffc0
	s_addk_i32 s4, 0xe980
	s_lshl_b32 s6, s9, 2
	v_or_b32_e32 v34, s4, v8
	s_add_u32 s6, s40, s6
	v_mov_b32_e32 v35, v3
	s_addc_u32 s7, s41, 0
	v_lshlrev_b64 v[10:11], 13, v[34:35]
	v_or_b32_e32 v12, 8, v34
	v_mov_b32_e32 v13, v3
	v_or_b32_e32 v18, 16, v34
	v_mov_b32_e32 v19, v3
	v_or_b32_e32 v20, 24, v34
	v_mov_b32_e32 v21, v3
	v_or_b32_e32 v26, 32, v34
	v_mov_b32_e32 v27, v3
	v_or_b32_e32 v28, 40, v34
	v_mov_b32_e32 v29, v3
	v_or_b32_e32 v38, 48, v34
	v_mov_b32_e32 v39, v3
	v_or_b32_e32 v34, 56, v34
	v_lshl_add_u64 v[36:37], s[6:7], 0, v[2:3]
	v_lshlrev_b64 v[12:13], 13, v[12:13]
	v_lshlrev_b64 v[18:19], 13, v[18:19]
	v_lshlrev_b64 v[20:21], 13, v[20:21]
	v_lshlrev_b64 v[26:27], 13, v[26:27]
	v_lshlrev_b64 v[28:29], 13, v[28:29]
	v_lshlrev_b64 v[38:39], 13, v[38:39]
	v_lshlrev_b64 v[34:35], 13, v[34:35]
	v_lshl_add_u64 v[10:11], v[36:37], 0, v[10:11]
	v_lshl_add_u64 v[14:15], v[36:37], 0, v[12:13]
	v_lshl_add_u64 v[18:19], v[36:37], 0, v[18:19]
	v_lshl_add_u64 v[22:23], v[36:37], 0, v[20:21]
	v_lshl_add_u64 v[26:27], v[36:37], 0, v[26:27]
	v_lshl_add_u64 v[30:31], v[36:37], 0, v[28:29]
	v_lshl_add_u64 v[38:39], v[36:37], 0, v[38:39]
	v_lshl_add_u64 v[40:41], v[36:37], 0, v[34:35]
	global_load_dwordx4 v[10:13], v[10:11], off nt
	s_nop 0
	global_load_dwordx4 v[14:17], v[14:15], off nt
	s_nop 0
	global_load_dwordx4 v[18:21], v[18:19], off nt
	s_nop 0
	global_load_dwordx4 v[22:25], v[22:23], off nt
	s_nop 0
	global_load_dwordx4 v[26:29], v[26:27], off nt
	s_nop 0
	global_load_dwordx4 v[30:33], v[30:31], off nt
	s_nop 0
	global_load_dwordx4 v[34:37], v[38:39], off nt
	s_nop 0
	global_load_dwordx4 v[38:41], v[40:41], off nt
	v_mul_u32_u24_e32 v5, 0x84, v8
	v_add3_u32 v5, s1, v2, v5
	v_add_u32_e32 v9, 0x420, v5
	s_waitcnt vmcnt(7)
	ds_write2_b32 v5, v10, v11 offset1:1
	ds_write2_b32 v5, v12, v13 offset0:2 offset1:3
	s_waitcnt vmcnt(6)
	ds_write2_b32 v9, v14, v15 offset1:1
	v_add_u32_e32 v9, 0x428, v5
	ds_write2_b32 v9, v16, v17 offset1:1
	v_add_u32_e32 v9, 0x840, v5
	s_waitcnt vmcnt(5)
	ds_write2_b32 v9, v18, v19 offset1:1
	v_add_u32_e32 v9, 0x848, v5
	ds_write2_b32 v9, v20, v21 offset1:1
	v_add_u32_e32 v9, 0xc60, v5
	s_waitcnt vmcnt(4)
	ds_write2_b32 v9, v22, v23 offset1:1
	v_add_u32_e32 v9, 0xc68, v5
	ds_write2_b32 v9, v24, v25 offset1:1
	v_add_u32_e32 v9, 0x1080, v5
	s_waitcnt vmcnt(3)
	ds_write2_b32 v9, v26, v27 offset1:1
	v_add_u32_e32 v9, 0x1088, v5
	ds_write2_b32 v9, v28, v29 offset1:1
	v_add_u32_e32 v9, 0x14a0, v5
	s_waitcnt vmcnt(2)
	ds_write2_b32 v9, v30, v31 offset1:1
	v_add_u32_e32 v9, 0x14a8, v5
	ds_write2_b32 v9, v32, v33 offset1:1
	v_add_u32_e32 v9, 0x18c0, v5
	s_waitcnt vmcnt(1)
	ds_write2_b32 v9, v34, v35 offset1:1
	v_add_u32_e32 v9, 0x18c8, v5
	s_lshl_b64 s[4:5], s[4:5], 1
	ds_write2_b32 v9, v36, v37 offset1:1
	v_add_u32_e32 v9, 0x1ce0, v5
	v_add_u32_e32 v5, 0x1ce8, v5
	s_add_u32 s4, s50, s4
	s_waitcnt vmcnt(0)
	ds_write2_b32 v9, v38, v39 offset1:1
	ds_write2_b32 v5, v40, v41 offset1:1
	v_mul_u32_u24_e32 v9, 0x420, v7
	s_addc_u32 s5, s51, s5
	v_mov_b32_e32 v5, v3
	s_waitcnt lgkmcnt(0)
	v_lshl_add_u64 v[10:11], s[4:5], 0, v[4:5]
	v_add3_u32 v5, s1, v9, v6
	ds_read2_b32 v[14:15], v5 offset0:33 offset1:41
	ds_read2_b32 v[16:17], v5 offset1:8
	ds_read2_b32 v[18:19], v5 offset0:66 offset1:74
	ds_read2_b32 v[20:21], v5 offset0:99 offset1:107
	ds_read2_b32 v[22:23], v5 offset0:132 offset1:140
	ds_read2_b32 v[24:25], v5 offset0:165 offset1:173
	ds_read2_b32 v[26:27], v5 offset0:198 offset1:206
	ds_read2_b32 v[28:29], v5 offset0:231 offset1:239
	s_mov_b64 s[4:5], 0x1c00000
	v_lshl_add_u64 v[30:31], v[10:11], 0, s[4:5]
	v_lshlrev_b32_e32 v32, 11, v1
	v_mov_b32_e32 v33, v3
	s_waitcnt lgkmcnt(6)
	v_cvt_pk_bf16_f32 v10, v16, v14
	s_waitcnt lgkmcnt(4)
	v_cvt_pk_bf16_f32 v11, v18, v20
	s_waitcnt lgkmcnt(2)
	v_cvt_pk_bf16_f32 v12, v22, v24
	s_waitcnt lgkmcnt(0)
	v_cvt_pk_bf16_f32 v13, v26, v28
	v_lshl_add_u64 v[34:35], v[30:31], 0, v[32:33]
	global_store_dwordx4 v[34:35], v[10:13], off sc0 sc1
	v_or_b32_e32 v14, 0x4000, v32
	s_mov_b64 s[6:7], 0
	v_cvt_pk_bf16_f32 v10, v17, v15
	v_cvt_pk_bf16_f32 v11, v19, v21
	v_cvt_pk_bf16_f32 v12, v23, v25
	v_cvt_pk_bf16_f32 v13, v27, v29
	ds_read2_b32 v[16:17], v5 offset0:49 offset1:57
	ds_read2_b32 v[18:19], v5 offset0:16 offset1:24
	ds_read2_b32 v[20:21], v5 offset0:82 offset1:90
	ds_read2_b32 v[22:23], v5 offset0:115 offset1:123
	ds_read2_b32 v[24:25], v5 offset0:148 offset1:156
	ds_read2_b32 v[26:27], v5 offset0:181 offset1:189
	ds_read2_b32 v[28:29], v5 offset0:214 offset1:222
	ds_read2_b32 v[34:35], v5 offset0:247 offset1:255
	v_mov_b32_e32 v15, v3
	v_lshl_add_u64 v[14:15], v[30:31], 0, v[14:15]
	global_store_dwordx4 v[14:15], v[10:13], off sc0 sc1
	v_or_b32_e32 v14, 0x8000, v32
	v_mov_b32_e32 v15, v3
	s_waitcnt lgkmcnt(6)
	v_cvt_pk_bf16_f32 v10, v18, v16
	s_waitcnt lgkmcnt(4)
	v_cvt_pk_bf16_f32 v11, v20, v22
	s_waitcnt lgkmcnt(2)
	v_cvt_pk_bf16_f32 v12, v24, v26
	s_waitcnt lgkmcnt(0)
	v_cvt_pk_bf16_f32 v13, v28, v34
	v_lshl_add_u64 v[14:15], v[30:31], 0, v[14:15]
	global_store_dwordx4 v[14:15], v[10:13], off sc0 sc1
	v_or_b32_e32 v14, 0xc000, v32
	v_mov_b32_e32 v15, v3
	v_cvt_pk_bf16_f32 v10, v19, v17
	v_cvt_pk_bf16_f32 v11, v21, v23
	v_cvt_pk_bf16_f32 v12, v25, v27
	v_cvt_pk_bf16_f32 v13, v29, v35
	v_lshl_add_u64 v[14:15], v[30:31], 0, v[14:15]
	global_store_dwordx4 v[14:15], v[10:13], off sc0 sc1
	s_waitcnt lgkmcnt(0)
; #define LAS __attribute__((address_space(3)))
; __device__ __forceinline__ f32x4 ld_nt(const float* p) { return __builtin_nontemporal_load((const f32x4*)p); }
; __device__ __forceinline__ void transpose_item(const float* W, int K, int pitch, int ncols, f16* WT, LAS float* scr, int item, int lane) {
;     const int nblk = ncols / 32, kb = item / nblk, nb = item % nblk, k0 = 64 * kb, n0 = 32 * nb;
;     const int kr = lane >> 3, nq = (lane & 7) * 4;
;     f32x4 v[8];
; #pragma unroll
;     for (int i = 0; i < 8; ++i) v[i] = ld_nt(W + (size_t)(k0 + kr + 8 * i) * pitch + n0 + nq);
;     __builtin_amdgcn_sched_barrier(0);
; #pragma unroll
;     for (int i = 0; i < 8; ++i) { LAS float* sp = scr + (kr + 8 * i) * 33 + nq; sp[0] = v[i][0]; sp[1] = v[i][1]; sp[2] = v[i][2]; sp[3] = v[i][3]; }
;     asm volatile("s_waitcnt lgkmcnt(0)" ::: "memory");
;     const int c = lane & 7;
; #pragma unroll
;     for (int j = 0; j < 4; ++j) { const int n = (lane >> 3) + 8 * j; const LAS float* sp = scr + (8 * c) * 33 + n;
;         u32x4 o; o.x = pk_f16(sp[0 * 33], sp[1 * 33]); o.y = pk_f16(sp[2 * 33], sp[3 * 33]); o.z = pk_f16(sp[4 * 33], sp[5 * 33]); o.w = pk_f16(sp[6 * 33], sp[7 * 33]);
;         *(u32x4*)(WT + (size_t)(n0 + n) * K + k0 + 8 * c) = o; }
;     asm volatile("s_waitcnt lgkmcnt(0)" ::: "memory");
; }
.LBB0_16:
	s_andn2_b64 vcc, exec, s[6:7]
	s_cbranch_vccnz .LBB0_18
	s_add_i32 s4, s8, 0xf180
	s_and_b32 s6, s4, 0xffc0
	s_lshl_b32 s4, s9, 2
	s_add_u32 s4, s44, s4
	v_or_b32_e32 v5, s6, v8
	s_addc_u32 s5, s45, 0
	v_mov_b32_e32 v3, 0
	v_lshl_add_u64 v[10:11], s[4:5], 0, v[2:3]
	v_lshlrev_b32_e32 v12, 13, v5
	v_mov_b32_e32 v13, v3
	v_lshl_add_u64 v[34:35], v[10:11], 0, v[12:13]
	v_add_co_u32_e32 v14, vcc, 0x10000, v34
	s_nop 1
	v_addc_co_u32_e32 v15, vcc, 0, v35, vcc
	v_add_co_u32_e32 v18, vcc, 0x20000, v34
	global_load_dwordx4 v[10:13], v[34:35], off nt
	s_nop 0
	global_load_dwordx4 v[14:17], v[14:15], off nt
	v_addc_co_u32_e32 v19, vcc, 0, v35, vcc
	v_add_co_u32_e32 v22, vcc, 0x30000, v34
	s_nop 1
	v_addc_co_u32_e32 v23, vcc, 0, v35, vcc
	v_add_co_u32_e32 v26, vcc, 0x40000, v34
	global_load_dwordx4 v[18:21], v[18:19], off nt
	s_nop 0
	global_load_dwordx4 v[22:25], v[22:23], off nt
	v_addc_co_u32_e32 v27, vcc, 0, v35, vcc
	v_add_co_u32_e32 v30, vcc, 0x50000, v34
	s_nop 1
	v_addc_co_u32_e32 v31, vcc, 0, v35, vcc
	v_add_co_u32_e32 v36, vcc, 0x60000, v34
	global_load_dwordx4 v[26:29], v[26:27], off nt
	s_nop 0
	global_load_dwordx4 v[30:33], v[30:31], off nt
	v_addc_co_u32_e32 v37, vcc, 0, v35, vcc
	v_add_co_u32_e32 v38, vcc, 0x70000, v34
	s_nop 1
	v_addc_co_u32_e32 v39, vcc, 0, v35, vcc
	global_load_dwordx4 v[34:37], v[36:37], off nt
	s_nop 0
	global_load_dwordx4 v[38:41], v[38:39], off nt
	v_mul_u32_u24_e32 v5, 0x84, v8
	v_add3_u32 v2, s1, v2, v5
	v_add_u32_e32 v5, 0x420, v2
	s_waitcnt vmcnt(7)
	ds_write2_b32 v2, v10, v11 offset1:1
	ds_write2_b32 v2, v12, v13 offset0:2 offset1:3
	s_waitcnt vmcnt(6)
	ds_write2_b32 v5, v14, v15 offset1:1
	v_add_u32_e32 v5, 0x428, v2
	ds_write2_b32 v5, v16, v17 offset1:1
	v_add_u32_e32 v5, 0x840, v2
	s_waitcnt vmcnt(5)
	ds_write2_b32 v5, v18, v19 offset1:1
	v_add_u32_e32 v5, 0x848, v2
	ds_write2_b32 v5, v20, v21 offset1:1
	v_add_u32_e32 v5, 0xc60, v2
	s_waitcnt vmcnt(4)
	ds_write2_b32 v5, v22, v23 offset1:1
	v_add_u32_e32 v5, 0xc68, v2
	ds_write2_b32 v5, v24, v25 offset1:1
	v_add_u32_e32 v5, 0x1080, v2
	s_waitcnt vmcnt(3)
	ds_write2_b32 v5, v26, v27 offset1:1
	v_add_u32_e32 v5, 0x1088, v2
	ds_write2_b32 v5, v28, v29 offset1:1
	v_add_u32_e32 v5, 0x14a0, v2
	s_waitcnt vmcnt(2)
	ds_write2_b32 v5, v30, v31 offset1:1
	v_add_u32_e32 v5, 0x14a8, v2
	ds_write2_b32 v5, v32, v33 offset1:1
	v_add_u32_e32 v5, 0x18c0, v2
	s_waitcnt vmcnt(1)
	ds_write2_b32 v5, v34, v35 offset1:1
	v_add_u32_e32 v5, 0x18c8, v2
	ds_write2_b32 v5, v36, v37 offset1:1
	v_add_u32_e32 v5, 0x1ce0, v2
	v_add_u32_e32 v2, 0x1ce8, v2
	s_waitcnt vmcnt(0)
	ds_write2_b32 v5, v38, v39 offset1:1
	ds_write2_b32 v2, v40, v41 offset1:1
	v_mul_u32_u24_e32 v2, 0x420, v7
	s_waitcnt lgkmcnt(0)
	v_add3_u32 v28, s1, v2, v6
	s_lshl_b32 s4, s6, 1
	ds_read2_b32 v[8:9], v28 offset0:33 offset1:41
	ds_read2_b32 v[10:11], v28 offset1:8
	ds_read2_b32 v[12:13], v28 offset0:66 offset1:74
	ds_read2_b32 v[14:15], v28 offset0:99 offset1:107
	ds_read2_b32 v[16:17], v28 offset0:132 offset1:140
	ds_read2_b32 v[18:19], v28 offset0:165 offset1:173
	ds_read2_b32 v[20:21], v28 offset0:198 offset1:206
	ds_read2_b32 v[22:23], v28 offset0:231 offset1:239
	s_add_u32 s4, s50, s4
	s_addc_u32 s5, s51, 0
	v_mov_b32_e32 v5, v3
	v_lshl_add_u64 v[4:5], s[4:5], 0, v[4:5]
	s_mov_b64 s[4:5], 0x1400000
	v_lshl_add_u64 v[24:25], v[4:5], 0, s[4:5]
	v_lshlrev_b32_e32 v2, 12, v1
	s_waitcnt lgkmcnt(6)
	v_cvt_pk_bf16_f32 v4, v10, v8
	s_waitcnt lgkmcnt(4)
	v_cvt_pk_bf16_f32 v5, v12, v14
	s_waitcnt lgkmcnt(2)
	v_cvt_pk_bf16_f32 v6, v16, v18
	s_waitcnt lgkmcnt(0)
	v_cvt_pk_bf16_f32 v7, v20, v22
	v_lshl_add_u64 v[26:27], v[24:25], 0, v[2:3]
	global_store_dwordx4 v[26:27], v[4:7], off sc0 sc1
	v_or_b32_e32 v8, 0x8000, v2
	s_nop 0
	v_cvt_pk_bf16_f32 v4, v11, v9
	v_cvt_pk_bf16_f32 v5, v13, v15
	v_cvt_pk_bf16_f32 v6, v17, v19
	v_cvt_pk_bf16_f32 v7, v21, v23
	ds_read2_b32 v[10:11], v28 offset0:49 offset1:57
	ds_read2_b32 v[12:13], v28 offset0:16 offset1:24
	ds_read2_b32 v[14:15], v28 offset0:82 offset1:90
	ds_read2_b32 v[16:17], v28 offset0:115 offset1:123
	ds_read2_b32 v[18:19], v28 offset0:148 offset1:156
	ds_read2_b32 v[20:21], v28 offset0:181 offset1:189
	ds_read2_b32 v[22:23], v28 offset0:214 offset1:222
	ds_read2_b32 v[26:27], v28 offset0:247 offset1:255
	v_mov_b32_e32 v9, v3
	v_lshl_add_u64 v[8:9], v[24:25], 0, v[8:9]
	global_store_dwordx4 v[8:9], v[4:7], off sc0 sc1
	v_or_b32_e32 v8, 0x10000, v2
	v_mov_b32_e32 v9, v3
	s_waitcnt lgkmcnt(6)
	v_cvt_pk_bf16_f32 v4, v12, v10
	s_waitcnt lgkmcnt(4)
	v_cvt_pk_bf16_f32 v5, v14, v16
	s_waitcnt lgkmcnt(2)
	v_cvt_pk_bf16_f32 v6, v18, v20
	s_waitcnt lgkmcnt(0)
	v_cvt_pk_bf16_f32 v7, v22, v26
	v_lshl_add_u64 v[8:9], v[24:25], 0, v[8:9]
	v_or_b32_e32 v2, 0x18000, v2
	global_store_dwordx4 v[8:9], v[4:7], off sc0 sc1
	v_lshl_add_u64 v[2:3], v[24:25], 0, v[2:3]
	s_nop 0
	v_cvt_pk_bf16_f32 v4, v13, v11
	v_cvt_pk_bf16_f32 v5, v15, v17
	v_cvt_pk_bf16_f32 v6, v19, v21
	v_cvt_pk_bf16_f32 v7, v23, v27
	global_store_dwordx4 v[2:3], v[4:7], off sc0 sc1
	s_waitcnt lgkmcnt(0)

; #define LAS __attribute__((address_space(3)))
; __device__ __forceinline__ f32x4 ld_nt(const float* p) { return __builtin_nontemporal_load((const f32x4*)p); }
; __device__ __forceinline__ void transpose_item(const float* W, int K, int pitch, int ncols, f16* WT, LAS float* scr, int item, int lane) {
;     const int nblk = ncols / 32, kb = item / nblk, nb = item % nblk, k0 = 64 * kb, n0 = 32 * nb;
;     const int kr = lane >> 3, nq = (lane & 7) * 4;
;     f32x4 v[8];
; #pragma unroll
;     for (int i = 0; i < 8; ++i) v[i] = ld_nt(W + (size_t)(k0 + kr + 8 * i) * pitch + n0 + nq);
;     __builtin_amdgcn_sched_barrier(0);
; #pragma unroll
;     for (int i = 0; i < 8; ++i) { LAS float* sp = scr + (kr + 8 * i) * 33 + nq; sp[0] = v[i][0]; sp[1] = v[i][1]; sp[2] = v[i][2]; sp[3] = v[i][3]; }
;     asm volatile("s_waitcnt lgkmcnt(0)" ::: "memory");
;     const int c = lane & 7;
; #pragma unroll
;     for (int j = 0; j < 4; ++j) { const int n = (lane >> 3) + 8 * j; const LAS float* sp = scr + (8 * c) * 33 + n;
;         u32x4 o; o.x = pk_f16(sp[0 * 33], sp[1 * 33]); o.y = pk_f16(sp[2 * 33], sp[3 * 33]); o.z = pk_f16(sp[4 * 33], sp[5 * 33]); o.w = pk_f16(sp[6 * 33], sp[7 * 33]);
;         *(u32x4*)(WT + (size_t)(n0 + n) * K + k0 + 8 * c) = o; }
;     asm volatile("s_waitcnt lgkmcnt(0)" ::: "memory");
; }
.LBB0_19:
	s_andn2_b64 vcc, exec, s[4:5]
	s_cbranch_vccnz .LBB0_21
	s_add_i32 s4, s8, 0xfd80
	s_and_b32 s5, s4, 0xffff
	s_mul_i32 s5, s5, 0xaaab
	s_lshr_b32 s6, s5, 16
	s_lshr_b32 s5, s5, 22
	s_mulk_i32 s5, 0x60
	s_sub_i32 s4, s4, s5
	s_lshl_b32 s4, s4, 5
	s_and_b32 s7, s4, 0xffe0
	v_readlane_b32 s56, v254, 2
	s_and_b32 s6, s6, 0xffc0
	s_lshl_b32 s4, s7, 2
	v_readlane_b32 s70, v254, 16
	v_lshrrev_b32_e32 v1, 3, v212
	v_and_b32_e32 v36, 7, v0
	v_readlane_b32 s71, v254, 17
	s_add_u32 s4, s70, s4
	v_or_b32_e32 v4, s6, v1
	s_addc_u32 s5, s71, 0
	v_lshlrev_b32_e32 v34, 4, v36
	v_mov_b32_e32 v35, 0
	v_lshl_add_u64 v[2:3], s[4:5], 0, v[34:35]
	v_lshlrev_b32_e32 v4, 14, v4
	v_mov_b32_e32 v5, v35
	v_lshl_add_u64 v[26:27], v[2:3], 0, v[4:5]
	s_movk_i32 s4, 0x1000
	v_add_co_u32_e32 v2, vcc, s4, v26
	s_mov_b32 s4, 0x21000
	s_nop 0
	v_addc_co_u32_e32 v3, vcc, 0, v27, vcc
	v_add_co_u32_e32 v6, vcc, s4, v26
	s_mov_b32 s4, 0x41000
	s_nop 0
	v_addc_co_u32_e32 v7, vcc, 0, v27, vcc
	v_add_co_u32_e32 v10, vcc, s4, v26
	s_mov_b32 s4, 0x61000
	s_nop 0
	v_addc_co_u32_e32 v11, vcc, 0, v27, vcc
	v_add_co_u32_e32 v14, vcc, s4, v26
	s_mov_b32 s4, 0x81000
	s_nop 0
	v_addc_co_u32_e32 v15, vcc, 0, v27, vcc
	v_add_co_u32_e32 v18, vcc, s4, v26
	s_mov_b32 s4, 0xa1000
	s_nop 0
	v_addc_co_u32_e32 v19, vcc, 0, v27, vcc
	v_add_co_u32_e32 v22, vcc, s4, v26
	s_mov_b32 s4, 0xc1000
	s_nop 0
	v_addc_co_u32_e32 v23, vcc, 0, v27, vcc
	v_add_co_u32_e32 v28, vcc, s4, v26
	s_mov_b32 s4, 0xe1000
	s_nop 0
	v_addc_co_u32_e32 v29, vcc, 0, v27, vcc
	v_add_co_u32_e32 v30, vcc, s4, v26
	global_load_dwordx4 v[2:5], v[2:3], off nt
	s_nop 0
	global_load_dwordx4 v[6:9], v[6:7], off nt
	v_addc_co_u32_e32 v31, vcc, 0, v27, vcc
	global_load_dwordx4 v[10:13], v[10:11], off nt
	s_nop 0
	global_load_dwordx4 v[14:17], v[14:15], off nt
	s_nop 0
	global_load_dwordx4 v[18:21], v[18:19], off nt
	s_nop 0
	global_load_dwordx4 v[22:25], v[22:23], off nt
	s_nop 0
	global_load_dwordx4 v[26:29], v[28:29], off nt
	s_nop 0
	global_load_dwordx4 v[30:33], v[30:31], off nt
	v_readlane_b32 s57, v254, 3
	v_readlane_b32 s58, v254, 4
	v_readlane_b32 s59, v254, 5
	v_readlane_b32 s60, v254, 6
	v_readlane_b32 s61, v254, 7
	v_readlane_b32 s62, v254, 8
	v_readlane_b32 s63, v254, 9
	v_readlane_b32 s64, v254, 10
	v_readlane_b32 s65, v254, 11
	v_readlane_b32 s66, v254, 12
	v_readlane_b32 s67, v254, 13
	v_readlane_b32 s68, v254, 14
	v_readlane_b32 s69, v254, 15
	v_mul_u32_u24_e32 v37, 0x84, v1
	v_add3_u32 v37, s1, v34, v37
	s_waitcnt vmcnt(7)
	ds_write2_b32 v37, v2, v3 offset1:1
	ds_write2_b32 v37, v4, v5 offset0:2 offset1:3
	v_add_u32_e32 v2, 0x420, v37
	s_waitcnt vmcnt(6)
	ds_write2_b32 v2, v6, v7 offset1:1
	v_add_u32_e32 v2, 0x428, v37
	ds_write2_b32 v2, v8, v9 offset1:1
	v_add_u32_e32 v2, 0x840, v37
	s_waitcnt vmcnt(5)
	ds_write2_b32 v2, v10, v11 offset1:1
	v_add_u32_e32 v2, 0x848, v37
	ds_write2_b32 v2, v12, v13 offset1:1
	v_add_u32_e32 v2, 0xc60, v37
	s_waitcnt vmcnt(4)
	ds_write2_b32 v2, v14, v15 offset1:1
	v_add_u32_e32 v2, 0xc68, v37
	ds_write2_b32 v2, v16, v17 offset1:1
	v_add_u32_e32 v2, 0x1080, v37
	s_waitcnt vmcnt(3)
	ds_write2_b32 v2, v18, v19 offset1:1
	v_add_u32_e32 v2, 0x1088, v37
	ds_write2_b32 v2, v20, v21 offset1:1
	v_add_u32_e32 v2, 0x14a0, v37
	s_waitcnt vmcnt(2)
	ds_write2_b32 v2, v22, v23 offset1:1
	v_add_u32_e32 v2, 0x14a8, v37
	ds_write2_b32 v2, v24, v25 offset1:1
	v_add_u32_e32 v2, 0x18c0, v37
	s_waitcnt vmcnt(1)
	ds_write2_b32 v2, v26, v27 offset1:1
	v_add_u32_e32 v2, 0x18c8, v37
	ds_write2_b32 v2, v28, v29 offset1:1
	v_add_u32_e32 v2, 0x1ce0, v37
	s_waitcnt vmcnt(0)
	ds_write2_b32 v2, v30, v31 offset1:1
	v_add_u32_e32 v2, 0x1ce8, v37
	ds_write2_b32 v2, v32, v33 offset1:1
	v_mul_u32_u24_e32 v4, 0x420, v36
	v_lshlrev_b32_e32 v5, 2, v1
	s_waitcnt lgkmcnt(0)
	v_add3_u32 v26, s1, v4, v5
	s_lshl_b32 s4, s6, 1
	ds_read2_b32 v[6:7], v26 offset0:33 offset1:41
	ds_read2_b32 v[8:9], v26 offset1:8
	ds_read2_b32 v[10:11], v26 offset0:66 offset1:74
	ds_read2_b32 v[12:13], v26 offset0:99 offset1:107
	ds_read2_b32 v[14:15], v26 offset0:132 offset1:140
	ds_read2_b32 v[16:17], v26 offset0:165 offset1:173
	ds_read2_b32 v[18:19], v26 offset0:198 offset1:206
	ds_read2_b32 v[20:21], v26 offset0:231 offset1:239
	s_add_u32 s4, s50, s4
	s_addc_u32 s5, s51, 0
	v_lshl_add_u64 v[2:3], s[4:5], 0, v[34:35]
	s_mov_b64 s[4:5], 0x800000
	v_or_b32_e32 v1, s7, v1
	v_lshl_add_u64 v[22:23], v[2:3], 0, s[4:5]
	v_lshlrev_b32_e32 v34, 12, v1
	s_waitcnt lgkmcnt(6)
	v_cvt_pk_bf16_f32 v2, v8, v6
	s_waitcnt lgkmcnt(4)
	v_cvt_pk_bf16_f32 v3, v10, v12
	s_waitcnt lgkmcnt(2)
	v_cvt_pk_bf16_f32 v4, v14, v16
	s_waitcnt lgkmcnt(0)
	v_cvt_pk_bf16_f32 v5, v18, v20
	v_lshl_add_u64 v[24:25], v[22:23], 0, v[34:35]
	global_store_dwordx4 v[24:25], v[2:5], off sc0 sc1
	v_or_b32_e32 v6, 0x8000, v34
	s_nop 0
	v_cvt_pk_bf16_f32 v2, v9, v7
	v_cvt_pk_bf16_f32 v3, v11, v13
	v_cvt_pk_bf16_f32 v4, v15, v17
	v_cvt_pk_bf16_f32 v5, v19, v21
	ds_read2_b32 v[8:9], v26 offset0:49 offset1:57
	ds_read2_b32 v[10:11], v26 offset0:16 offset1:24
	ds_read2_b32 v[12:13], v26 offset0:82 offset1:90
	ds_read2_b32 v[14:15], v26 offset0:115 offset1:123
	ds_read2_b32 v[16:17], v26 offset0:148 offset1:156
	ds_read2_b32 v[18:19], v26 offset0:181 offset1:189
	ds_read2_b32 v[20:21], v26 offset0:214 offset1:222
	ds_read2_b32 v[24:25], v26 offset0:247 offset1:255
	v_mov_b32_e32 v7, v35
	v_lshl_add_u64 v[6:7], v[22:23], 0, v[6:7]
	global_store_dwordx4 v[6:7], v[2:5], off sc0 sc1
	v_or_b32_e32 v6, 0x10000, v34
	v_mov_b32_e32 v7, v35
	s_waitcnt lgkmcnt(6)
	v_cvt_pk_bf16_f32 v2, v10, v8
	s_waitcnt lgkmcnt(4)
	v_cvt_pk_bf16_f32 v3, v12, v14
	s_waitcnt lgkmcnt(2)
	v_cvt_pk_bf16_f32 v4, v16, v18
	s_waitcnt lgkmcnt(0)
	v_cvt_pk_bf16_f32 v5, v20, v24
	v_lshl_add_u64 v[6:7], v[22:23], 0, v[6:7]
	v_or_b32_e32 v34, 0x18000, v34
	global_store_dwordx4 v[6:7], v[2:5], off sc0 sc1
	v_lshl_add_u64 v[6:7], v[22:23], 0, v[34:35]
	s_nop 0
	v_cvt_pk_bf16_f32 v2, v11, v9
	v_cvt_pk_bf16_f32 v3, v13, v15
	v_cvt_pk_bf16_f32 v4, v17, v19
	v_cvt_pk_bf16_f32 v5, v21, v25
	global_store_dwordx4 v[6:7], v[2:5], off sc0 sc1
	s_waitcnt lgkmcnt(0)

; __device__ __forceinline__ f32x4 ld_nt(const float* p) { return __builtin_nontemporal_load((const f32x4*)p); }
; __device__ __forceinline__ u32x4 pack8(const f32x4 v0, const f32x4 v1) { u32x4 w; w.x = pk_f16(v0[0], v0[1]); w.y = pk_f16(v0[2], v0[3]); w.z = pk_f16(v1[0], v1[1]); w.w = pk_f16(v1[2], v1[3]); return w; }
; __device__ __forceinline__ void convert_item(const float* W, f16* O, int item, int lane) {
;     f32x4 v[4][4];
; #pragma unroll
;     for (int r = 0; r < 4; ++r)
; #pragma unroll
;         for (int q = 0; q < 4; ++q) v[r][q] = ld_nt(W + (size_t)(item * 4 + r) * 4096 + lane * 16 + q * 4);
;     __builtin_amdgcn_sched_barrier(0);
; #pragma unroll
;     for (int r = 0; r < 4; ++r) { f16* op = O + (size_t)(item * 4 + r) * 1024 + lane * 16; *(u32x4*)op = pack8(v[r][0], v[r][1]); *(u32x4*)(op + 8) = pack8(v[r][2], v[r][3]); }
; }
.LBB0_22:
	s_andn2_b64 vcc, exec, s[4:5]
	s_cbranch_vccnz .LBB0_24
	v_readlane_b32 s56, v254, 2
	s_add_i32 s9, s8, 0xffffff80
	v_lshlrev_b32_e32 v66, 6, v212
	v_mov_b32_e32 v67, 0
	v_readlane_b32 s70, v254, 16
	v_readlane_b32 s71, v254, 17
	s_lshl_b32 s4, s9, 14
	s_mov_b32 s5, 0
	v_lshl_add_u64 v[2:3], s[70:71], 0, v[66:67]
	v_lshl_add_u64 v[50:51], s[4:5], 2, v[2:3]
	v_add_co_u32_e32 v18, vcc, 0x4000, v50
	s_mov_b64 s[6:7], 0x4000
	s_nop 0
	v_addc_co_u32_e32 v19, vcc, 0, v51, vcc
	v_lshl_add_u64 v[30:31], v[50:51], 0, s[6:7]
	s_mov_b64 s[6:7], 0x8000
	v_add_co_u32_e32 v34, vcc, 0x8000, v50
	v_lshl_add_u64 v[46:47], v[50:51], 0, s[6:7]
	s_nop 0
	v_addc_co_u32_e32 v35, vcc, 0, v51, vcc
	s_mov_b64 s[6:7], 0xc000
	global_load_dwordx4 v[2:5], v[50:51], off offset:48 nt
	global_load_dwordx4 v[6:9], v[50:51], off offset:32 nt
	global_load_dwordx4 v[10:13], v[50:51], off offset:16 nt
	global_load_dwordx4 v[14:17], v[50:51], off nt
	v_lshl_add_u64 v[62:63], v[50:51], 0, s[6:7]
	v_add_co_u32_e32 v50, vcc, 0xc000, v50
	global_load_dwordx4 v[18:21], v[18:19], off nt
	s_nop 0
	global_load_dwordx4 v[22:25], v[30:31], off offset:48 nt
	global_load_dwordx4 v[26:29], v[30:31], off offset:32 nt
	s_nop 0
	global_load_dwordx4 v[30:33], v[30:31], off offset:16 nt
	v_addc_co_u32_e32 v51, vcc, 0, v51, vcc
	global_load_dwordx4 v[34:37], v[34:35], off nt
	s_nop 0
	global_load_dwordx4 v[38:41], v[46:47], off offset:48 nt
	global_load_dwordx4 v[42:45], v[46:47], off offset:32 nt
	s_nop 0
	global_load_dwordx4 v[46:49], v[46:47], off offset:16 nt
	s_nop 0
	global_load_dwordx4 v[50:53], v[50:51], off nt
	s_nop 0
	global_load_dwordx4 v[54:57], v[62:63], off offset:48 nt
	global_load_dwordx4 v[58:61], v[62:63], off offset:32 nt
	s_nop 0
	global_load_dwordx4 v[62:65], v[62:63], off offset:16 nt
	v_readlane_b32 s57, v254, 3
	v_readlane_b32 s58, v254, 4
	v_readlane_b32 s59, v254, 5
	v_readlane_b32 s60, v254, 6
	v_readlane_b32 s61, v254, 7
	v_readlane_b32 s62, v254, 8
	v_readlane_b32 s63, v254, 9
	v_readlane_b32 s64, v254, 10
	v_readlane_b32 s65, v254, 11
	v_readlane_b32 s66, v254, 12
	v_readlane_b32 s67, v254, 13
	v_readlane_b32 s68, v254, 14
	v_readlane_b32 s69, v254, 15
	v_lshlrev_b32_e32 v66, 5, v212
	v_lshl_add_u64 v[66:67], s[50:51], 0, v[66:67]
	s_lshl_b32 s4, s9, 13
	v_lshl_add_u64 v[66:67], v[66:67], 0, s[4:5]
	s_mov_b64 s[4:5], 0x13600000
	v_lshl_add_u64 v[68:69], v[66:67], 0, s[4:5]
	s_mov_b32 s4, 0x13601000
	s_waitcnt vmcnt(14)
	v_cvt_pk_bf16_f32 v6, v6, v7
	v_cvt_pk_bf16_f32 v7, v8, v9
	v_cvt_pk_bf16_f32 v8, v2, v3
	v_cvt_pk_bf16_f32 v9, v4, v5
	s_waitcnt vmcnt(11)
	v_cvt_pk_bf16_f32 v2, v18, v19
	v_cvt_pk_bf16_f32 v3, v20, v21
	s_waitcnt vmcnt(8)
	v_cvt_pk_bf16_f32 v4, v30, v31
	v_cvt_pk_bf16_f32 v5, v32, v33
	v_cvt_pk_bf16_f32 v14, v14, v15
	v_cvt_pk_bf16_f32 v15, v16, v17
	v_cvt_pk_bf16_f32 v16, v10, v11
	v_add_co_u32_e32 v10, vcc, s4, v66
	global_store_dwordx4 v[68:69], v[2:5], off offset:2048 sc0 sc1
	s_nop 0
	v_addc_co_u32_e32 v11, vcc, 0, v67, vcc
	v_cvt_pk_bf16_f32 v2, v26, v27
	v_cvt_pk_bf16_f32 v3, v28, v29
	v_cvt_pk_bf16_f32 v4, v22, v23
	v_cvt_pk_bf16_f32 v5, v24, v25
	global_store_dwordx4 v[68:69], v[2:5], off offset:2064 sc0 sc1
	v_cvt_pk_bf16_f32 v17, v12, v13
	global_store_dwordx4 v[10:11], v[14:17], off offset:-4096 sc0 sc1
	s_waitcnt vmcnt(10)
	v_cvt_pk_bf16_f32 v2, v34, v35
	v_cvt_pk_bf16_f32 v3, v36, v37
	s_waitcnt vmcnt(7)
	v_cvt_pk_bf16_f32 v4, v46, v47
	v_cvt_pk_bf16_f32 v5, v48, v49
	global_store_dwordx4 v[10:11], v[2:5], off sc0 sc1
	global_store_dwordx4 v[68:69], v[6:9], off offset:16 sc0 sc1
	s_nop 0
	v_cvt_pk_bf16_f32 v2, v42, v43
	v_cvt_pk_bf16_f32 v3, v44, v45
	v_cvt_pk_bf16_f32 v4, v38, v39
	v_cvt_pk_bf16_f32 v5, v40, v41
	global_store_dwordx4 v[10:11], v[2:5], off offset:16 sc0 sc1
	s_waitcnt vmcnt(9)
	s_nop 0
	v_cvt_pk_bf16_f32 v2, v50, v51
	v_cvt_pk_bf16_f32 v3, v52, v53
	s_waitcnt vmcnt(6)
	v_cvt_pk_bf16_f32 v4, v62, v63
	v_cvt_pk_bf16_f32 v5, v64, v65
	global_store_dwordx4 v[10:11], v[2:5], off offset:2048 sc0 sc1
	s_nop 1
	v_cvt_pk_bf16_f32 v2, v58, v59
	v_cvt_pk_bf16_f32 v3, v60, v61
	v_cvt_pk_bf16_f32 v4, v54, v55
	v_cvt_pk_bf16_f32 v5, v56, v57
	global_store_dwordx4 v[10:11], v[2:5], off offset:2064 sc0 sc1

; #define LAS __attribute__((address_space(3)))
; __device__ __forceinline__ f32x4 ld_nt(const float* p) { return __builtin_nontemporal_load((const f32x4*)p); }
; __device__ __forceinline__ void transpose_item(const float* W, int K, int pitch, int ncols, f16* WT, LAS float* scr, int item, int lane) {
;     const int nblk = ncols / 32, kb = item / nblk, nb = item % nblk, k0 = 64 * kb, n0 = 32 * nb;
;     const int kr = lane >> 3, nq = (lane & 7) * 4;
;     f32x4 v[8];
; #pragma unroll
;     for (int i = 0; i < 8; ++i) v[i] = ld_nt(W + (size_t)(k0 + kr + 8 * i) * pitch + n0 + nq);
;     __builtin_amdgcn_sched_barrier(0);
; #pragma unroll
;     for (int i = 0; i < 8; ++i) { LAS float* sp = scr + (kr + 8 * i) * 33 + nq; sp[0] = v[i][0]; sp[1] = v[i][1]; sp[2] = v[i][2]; sp[3] = v[i][3]; }
;     asm volatile("s_waitcnt lgkmcnt(0)" ::: "memory");
;     const int c = lane & 7;
; #pragma unroll
;     for (int j = 0; j < 4; ++j) { const int n = (lane >> 3) + 8 * j; const LAS float* sp = scr + (8 * c) * 33 + n;
;         u32x4 o; o.x = pk_f16(sp[0 * 33], sp[1 * 33]); o.y = pk_f16(sp[2 * 33], sp[3 * 33]); o.z = pk_f16(sp[4 * 33], sp[5 * 33]); o.w = pk_f16(sp[6 * 33], sp[7 * 33]);
;         *(u32x4*)(WT + (size_t)(n0 + n) * K + k0 + 8 * c) = o; }
;     asm volatile("s_waitcnt lgkmcnt(0)" ::: "memory");
; }
.LBB0_25:
	s_ashr_i32 s4, s8, 31
	s_lshr_b32 s4, s4, 27
	s_add_i32 s9, s8, s4
	s_lshl_b32 s4, s9, 11
	s_and_b32 s4, s4, 0xffff0000
	s_ashr_i32 s5, s4, 31
	s_lshl_b64 s[6:7], s[4:5], 2
	v_readlane_b32 s56, v254, 18
	v_readlane_b32 s57, v254, 19
	s_add_u32 s10, s56, s6
	s_addc_u32 s7, s57, s7
	s_lshl_b64 s[4:5], s[4:5], 1
	s_add_u32 s11, s50, s4
	s_addc_u32 s12, s51, s5
	s_and_b32 s4, s9, 0xffe0
	s_sub_i32 s4, s8, s4
	s_bfe_i32 s5, s4, 0x80000
	s_bfe_u32 s5, s5, 0x3000c
	s_add_i32 s5, s4, s5
	s_bfe_i32 s6, s5, 0x80000
	s_and_b32 s5, s5, 0xf8
	s_sext_i32_i16 s6, s6
	s_sub_i32 s4, s4, s5
	s_sext_i32_i8 s4, s4
	s_lshl_b32 s5, s6, 3
	s_and_b32 s6, s5, 0xffffffc0
	s_lshl_b32 s4, s4, 5
	v_lshrrev_b32_e32 v1, 3, v212
	v_or_b32_e32 v26, s6, v1
	s_ashr_i32 s5, s4, 31
	s_lshl_b64 s[8:9], s[4:5], 2
	v_ashrrev_i32_e32 v27, 31, v26
	v_and_b32_e32 v36, 7, v0
	s_add_u32 s8, s10, s8
	v_lshlrev_b64 v[2:3], 10, v[26:27]
	v_or_b32_e32 v4, 8, v26
	v_or_b32_e32 v10, 16, v26
	v_or_b32_e32 v12, 24, v26
	v_or_b32_e32 v18, 32, v26
	v_or_b32_e32 v20, 40, v26
	v_or_b32_e32 v30, 48, v26
	v_or_b32_e32 v26, 56, v26
	s_addc_u32 s9, s7, s9
	v_lshlrev_b32_e32 v34, 4, v36
	v_mov_b32_e32 v35, 0
	v_ashrrev_i32_e32 v5, 31, v4
	v_ashrrev_i32_e32 v11, 31, v10
	v_ashrrev_i32_e32 v13, 31, v12
	v_ashrrev_i32_e32 v19, 31, v18
	v_ashrrev_i32_e32 v21, 31, v20
	v_ashrrev_i32_e32 v31, 31, v30
	v_ashrrev_i32_e32 v27, 31, v26
	v_lshl_add_u64 v[28:29], s[8:9], 0, v[34:35]
	v_lshlrev_b64 v[4:5], 10, v[4:5]
	v_lshlrev_b64 v[10:11], 10, v[10:11]
	v_lshlrev_b64 v[12:13], 10, v[12:13]
	v_lshlrev_b64 v[18:19], 10, v[18:19]
	v_lshlrev_b64 v[20:21], 10, v[20:21]
	v_lshlrev_b64 v[30:31], 10, v[30:31]
	v_lshlrev_b64 v[26:27], 10, v[26:27]
	v_lshl_add_u64 v[2:3], v[28:29], 0, v[2:3]
	v_lshl_add_u64 v[6:7], v[28:29], 0, v[4:5]
	v_lshl_add_u64 v[10:11], v[28:29], 0, v[10:11]
	v_lshl_add_u64 v[14:15], v[28:29], 0, v[12:13]
	v_lshl_add_u64 v[18:19], v[28:29], 0, v[18:19]
	v_lshl_add_u64 v[22:23], v[28:29], 0, v[20:21]
	v_lshl_add_u64 v[30:31], v[28:29], 0, v[30:31]
	v_lshl_add_u64 v[32:33], v[28:29], 0, v[26:27]
	global_load_dwordx4 v[2:5], v[2:3], off nt
	s_nop 0
	global_load_dwordx4 v[6:9], v[6:7], off nt
	s_nop 0
	global_load_dwordx4 v[10:13], v[10:11], off nt
	s_nop 0
	global_load_dwordx4 v[14:17], v[14:15], off nt
	s_nop 0
	global_load_dwordx4 v[18:21], v[18:19], off nt
	s_nop 0
	global_load_dwordx4 v[22:25], v[22:23], off nt
	s_nop 0
	global_load_dwordx4 v[26:29], v[30:31], off nt
	s_nop 0
	global_load_dwordx4 v[30:33], v[32:33], off nt
	v_readlane_b32 s58, v254, 20
	v_readlane_b32 s59, v254, 21
	v_readlane_b32 s60, v254, 22
	v_readlane_b32 s61, v254, 23
	v_readlane_b32 s62, v254, 24
	v_readlane_b32 s63, v254, 25
	v_readlane_b32 s64, v254, 26
	v_readlane_b32 s65, v254, 27
	v_readlane_b32 s66, v254, 28
	v_readlane_b32 s67, v254, 29
	v_readlane_b32 s68, v254, 30
	v_readlane_b32 s69, v254, 31
	v_readlane_b32 s70, v254, 32
	v_readlane_b32 s71, v254, 33
	v_mul_u32_u24_e32 v37, 0x84, v1
	v_add3_u32 v37, s1, v34, v37
	s_waitcnt vmcnt(7)
	ds_write2_b32 v37, v2, v3 offset1:1
	ds_write2_b32 v37, v4, v5 offset0:2 offset1:3
	v_add_u32_e32 v2, 0x420, v37
	s_waitcnt vmcnt(6)
	ds_write2_b32 v2, v6, v7 offset1:1
	v_add_u32_e32 v2, 0x428, v37
	ds_write2_b32 v2, v8, v9 offset1:1
	v_add_u32_e32 v2, 0x840, v37
	s_waitcnt vmcnt(5)
	ds_write2_b32 v2, v10, v11 offset1:1
	v_add_u32_e32 v2, 0x848, v37
	ds_write2_b32 v2, v12, v13 offset1:1
	v_add_u32_e32 v2, 0xc60, v37
	s_waitcnt vmcnt(4)
	ds_write2_b32 v2, v14, v15 offset1:1
	v_add_u32_e32 v2, 0xc68, v37
	ds_write2_b32 v2, v16, v17 offset1:1
	v_add_u32_e32 v2, 0x1080, v37
	s_waitcnt vmcnt(3)
	ds_write2_b32 v2, v18, v19 offset1:1
	v_add_u32_e32 v2, 0x1088, v37
	ds_write2_b32 v2, v20, v21 offset1:1
	v_add_u32_e32 v2, 0x14a0, v37
	s_waitcnt vmcnt(2)
	ds_write2_b32 v2, v22, v23 offset1:1
	v_add_u32_e32 v2, 0x14a8, v37
	ds_write2_b32 v2, v24, v25 offset1:1
	v_add_u32_e32 v2, 0x18c0, v37
	s_waitcnt vmcnt(1)
	ds_write2_b32 v2, v26, v27 offset1:1
	v_add_u32_e32 v2, 0x18c8, v37
	ds_write2_b32 v2, v28, v29 offset1:1
	v_add_u32_e32 v2, 0x1ce0, v37
	s_waitcnt vmcnt(0)
	ds_write2_b32 v2, v30, v31 offset1:1
	v_add_u32_e32 v2, 0x1ce8, v37
	ds_write2_b32 v2, v32, v33 offset1:1
	v_mul_u32_u24_e32 v4, 0x420, v36
	v_lshlrev_b32_e32 v5, 2, v1
	s_waitcnt lgkmcnt(0)
	s_ashr_i32 s7, s6, 31
	v_add3_u32 v28, s1, v4, v5
	s_lshl_b64 s[6:7], s[6:7], 1
	ds_read2_b32 v[6:7], v28 offset0:33 offset1:41
	ds_read2_b32 v[8:9], v28 offset1:8
	ds_read2_b32 v[10:11], v28 offset0:66 offset1:74
	ds_read2_b32 v[12:13], v28 offset0:99 offset1:107
	ds_read2_b32 v[14:15], v28 offset0:132 offset1:140
	ds_read2_b32 v[16:17], v28 offset0:165 offset1:173
	ds_read2_b32 v[18:19], v28 offset0:198 offset1:206
	ds_read2_b32 v[20:21], v28 offset0:231 offset1:239
	s_add_u32 s6, s11, s6
	s_addc_u32 s7, s12, s7
	v_or_b32_e32 v24, s4, v1
	v_lshl_add_u64 v[2:3], s[6:7], 0, v[34:35]
	s_mov_b64 s[6:7], 0x2000000
	v_ashrrev_i32_e32 v25, 31, v24
	v_lshl_add_u64 v[22:23], v[2:3], 0, s[6:7]
	v_lshlrev_b64 v[26:27], 9, v[24:25]
	s_waitcnt lgkmcnt(6)
	v_cvt_pk_bf16_f32 v2, v8, v6
	s_waitcnt lgkmcnt(4)
	v_cvt_pk_bf16_f32 v3, v10, v12
	s_waitcnt lgkmcnt(2)
	v_cvt_pk_bf16_f32 v4, v14, v16
	s_waitcnt lgkmcnt(0)
	v_cvt_pk_bf16_f32 v5, v18, v20
	v_lshl_add_u64 v[26:27], v[22:23], 0, v[26:27]
	v_or_b32_e32 v6, 8, v24
	global_store_dwordx4 v[26:27], v[2:5], off sc0 sc1
	s_nop 1
	v_cvt_pk_bf16_f32 v2, v9, v7
	v_ashrrev_i32_e32 v7, 31, v6
	v_cvt_pk_bf16_f32 v3, v11, v13
	v_cvt_pk_bf16_f32 v4, v15, v17
	v_cvt_pk_bf16_f32 v5, v19, v21
	v_lshlrev_b64 v[6:7], 9, v[6:7]
	ds_read2_b32 v[8:9], v28 offset0:49 offset1:57
	ds_read2_b32 v[10:11], v28 offset0:16 offset1:24
	ds_read2_b32 v[12:13], v28 offset0:82 offset1:90
	ds_read2_b32 v[14:15], v28 offset0:115 offset1:123
	ds_read2_b32 v[16:17], v28 offset0:148 offset1:156
	ds_read2_b32 v[18:19], v28 offset0:181 offset1:189
	ds_read2_b32 v[20:21], v28 offset0:214 offset1:222
	ds_read2_b32 v[26:27], v28 offset0:247 offset1:255
	v_lshl_add_u64 v[6:7], v[22:23], 0, v[6:7]
	global_store_dwordx4 v[6:7], v[2:5], off sc0 sc1
	v_or_b32_e32 v6, 16, v24
	v_ashrrev_i32_e32 v7, 31, v6
	v_lshlrev_b64 v[6:7], 9, v[6:7]
	s_waitcnt lgkmcnt(6)
	v_cvt_pk_bf16_f32 v2, v10, v8
	s_waitcnt lgkmcnt(4)
	v_cvt_pk_bf16_f32 v3, v12, v14
	s_waitcnt lgkmcnt(2)
	v_cvt_pk_bf16_f32 v4, v16, v18
	s_waitcnt lgkmcnt(0)
	v_cvt_pk_bf16_f32 v5, v20, v26
	v_lshl_add_u64 v[6:7], v[22:23], 0, v[6:7]
	global_store_dwordx4 v[6:7], v[2:5], off sc0 sc1
	v_or_b32_e32 v6, 24, v24
	v_ashrrev_i32_e32 v7, 31, v6
	v_lshlrev_b64 v[6:7], 9, v[6:7]
	v_cvt_pk_bf16_f32 v2, v11, v9
	v_cvt_pk_bf16_f32 v3, v13, v15
	v_cvt_pk_bf16_f32 v4, v17, v19
	v_cvt_pk_bf16_f32 v5, v21, v27
	v_lshl_add_u64 v[6:7], v[22:23], 0, v[6:7]
	global_store_dwordx4 v[6:7], v[2:5], off sc0 sc1
	s_waitcnt lgkmcnt(0)
	s_add_i32 s8, s16, 0xffffff40
	s_cmpk_gt_u32 s16, 0xcf
	s_cbranch_scc1 .LBB0_42
; #define LAS __attribute__((address_space(3)))
; __device__ __forceinline__ f32x4 ld_nt(const float* p) { return __builtin_nontemporal_load((const f32x4*)p); }
; __device__ __forceinline__ void transpose_item(const float* W, int K, int pitch, int ncols, f16* WT, LAS float* scr, int item, int lane) {
;     const int nblk = ncols / 32, kb = item / nblk, nb = item % nblk, k0 = 64 * kb, n0 = 32 * nb;
;     const int kr = lane >> 3, nq = (lane & 7) * 4;
;     f32x4 v[8];
; #pragma unroll
;     for (int i = 0; i < 8; ++i) v[i] = ld_nt(W + (size_t)(k0 + kr + 8 * i) * pitch + n0 + nq);
;     __builtin_amdgcn_sched_barrier(0);
; #pragma unroll
;     for (int i = 0; i < 8; ++i) { LAS float* sp = scr + (kr + 8 * i) * 33 + nq; sp[0] = v[i][0]; sp[1] = v[i][1]; sp[2] = v[i][2]; sp[3] = v[i][3]; }
;     asm volatile("s_waitcnt lgkmcnt(0)" ::: "memory");
;     const int c = lane & 7;
; #pragma unroll
;     for (int j = 0; j < 4; ++j) { const int n = (lane >> 3) + 8 * j; const LAS float* sp = scr + (8 * c) * 33 + n;
;         u32x4 o; o.x = pk_f16(sp[0 * 33], sp[1 * 33]); o.y = pk_f16(sp[2 * 33], sp[3 * 33]); o.z = pk_f16(sp[4 * 33], sp[5 * 33]); o.w = pk_f16(sp[6 * 33], sp[7 * 33]);
;         *(u32x4*)(WT + (size_t)(n0 + n) * K + k0 + 8 * c) = o; }
;     asm volatile("s_waitcnt lgkmcnt(0)" ::: "memory");
; }
.LBB0_26:
	s_lshl_b32 s4, s8, 3
	s_add_i32 s9, s53, s4
	s_cmpk_gt_u32 s9, 0x7f
	s_mov_b64 s[4:5], -1
	s_cbranch_scc0 .LBB0_40
	s_cmpk_gt_u32 s9, 0x27f
	s_cbranch_scc0 .LBB0_37
	s_cmpk_gt_u32 s9, 0xe7f
	s_cbranch_scc0 .LBB0_34
	s_lshl_b32 s4, s9, 5
	v_and_b32_e32 v7, 7, v0
	s_and_b32 s10, s4, 0x7e0
	v_lshrrev_b32_e32 v8, 3, v212
	v_lshlrev_b32_e32 v1, 2, v7
	s_cmpk_gt_u32 s9, 0x167f
	s_mov_b32 s5, 0
	v_mov_b32_e32 v3, 0
	s_mov_b64 s[6:7], -1
	v_lshlrev_b32_e32 v2, 2, v1
	v_lshlrev_b32_e32 v4, 4, v7
	v_lshlrev_b32_e32 v6, 2, v8
	v_or_b32_e32 v1, s10, v8
	s_cbranch_scc0 .LBB0_31
	s_and_b32 s4, s9, 0x7fffffc0
	s_addk_i32 s4, 0xe980
	s_lshl_b32 s6, s10, 2
	v_or_b32_e32 v34, s4, v8
	s_add_u32 s6, s40, s6
	v_mov_b32_e32 v35, v3
	s_addc_u32 s7, s41, 0
	v_lshlrev_b64 v[10:11], 13, v[34:35]
	v_or_b32_e32 v12, 8, v34
	v_mov_b32_e32 v13, v3
	v_or_b32_e32 v18, 16, v34
	v_mov_b32_e32 v19, v3
	v_or_b32_e32 v20, 24, v34
	v_mov_b32_e32 v21, v3
	v_or_b32_e32 v26, 32, v34
	v_mov_b32_e32 v27, v3
	v_or_b32_e32 v28, 40, v34
	v_mov_b32_e32 v29, v3
	v_or_b32_e32 v38, 48, v34
	v_mov_b32_e32 v39, v3
	v_or_b32_e32 v34, 56, v34
	v_lshl_add_u64 v[36:37], s[6:7], 0, v[2:3]
	v_lshlrev_b64 v[12:13], 13, v[12:13]
	v_lshlrev_b64 v[18:19], 13, v[18:19]
	v_lshlrev_b64 v[20:21], 13, v[20:21]
	v_lshlrev_b64 v[26:27], 13, v[26:27]
	v_lshlrev_b64 v[28:29], 13, v[28:29]
	v_lshlrev_b64 v[38:39], 13, v[38:39]
	v_lshlrev_b64 v[34:35], 13, v[34:35]
	v_lshl_add_u64 v[10:11], v[36:37], 0, v[10:11]
	v_lshl_add_u64 v[14:15], v[36:37], 0, v[12:13]
	v_lshl_add_u64 v[18:19], v[36:37], 0, v[18:19]
	v_lshl_add_u64 v[22:23], v[36:37], 0, v[20:21]
	v_lshl_add_u64 v[26:27], v[36:37], 0, v[26:27]
	v_lshl_add_u64 v[30:31], v[36:37], 0, v[28:29]
	v_lshl_add_u64 v[38:39], v[36:37], 0, v[38:39]
	v_lshl_add_u64 v[40:41], v[36:37], 0, v[34:35]
	global_load_dwordx4 v[10:13], v[10:11], off nt
	s_nop 0
	global_load_dwordx4 v[14:17], v[14:15], off nt
	s_nop 0
	global_load_dwordx4 v[18:21], v[18:19], off nt
	s_nop 0
	global_load_dwordx4 v[22:25], v[22:23], off nt
	s_nop 0
	global_load_dwordx4 v[26:29], v[26:27], off nt
	s_nop 0
	global_load_dwordx4 v[30:33], v[30:31], off nt
	s_nop 0
	global_load_dwordx4 v[34:37], v[38:39], off nt
	s_nop 0
	global_load_dwordx4 v[38:41], v[40:41], off nt
	v_mul_u32_u24_e32 v5, 0x84, v8
	v_add3_u32 v5, s1, v2, v5
	v_add_u32_e32 v9, 0x420, v5
	s_waitcnt vmcnt(7)
	ds_write2_b32 v5, v10, v11 offset1:1
	ds_write2_b32 v5, v12, v13 offset0:2 offset1:3
	s_waitcnt vmcnt(6)
	ds_write2_b32 v9, v14, v15 offset1:1
	v_add_u32_e32 v9, 0x428, v5
	ds_write2_b32 v9, v16, v17 offset1:1
	v_add_u32_e32 v9, 0x840, v5
	s_waitcnt vmcnt(5)
	ds_write2_b32 v9, v18, v19 offset1:1
	v_add_u32_e32 v9, 0x848, v5
	ds_write2_b32 v9, v20, v21 offset1:1
	v_add_u32_e32 v9, 0xc60, v5
	s_waitcnt vmcnt(4)
	ds_write2_b32 v9, v22, v23 offset1:1
	v_add_u32_e32 v9, 0xc68, v5
	ds_write2_b32 v9, v24, v25 offset1:1
	v_add_u32_e32 v9, 0x1080, v5
	s_waitcnt vmcnt(3)
	ds_write2_b32 v9, v26, v27 offset1:1
	v_add_u32_e32 v9, 0x1088, v5
	ds_write2_b32 v9, v28, v29 offset1:1
	v_add_u32_e32 v9, 0x14a0, v5
	s_waitcnt vmcnt(2)
	ds_write2_b32 v9, v30, v31 offset1:1
	v_add_u32_e32 v9, 0x14a8, v5
	ds_write2_b32 v9, v32, v33 offset1:1
	v_add_u32_e32 v9, 0x18c0, v5
	s_waitcnt vmcnt(1)
	ds_write2_b32 v9, v34, v35 offset1:1
	v_add_u32_e32 v9, 0x18c8, v5
	s_lshl_b64 s[4:5], s[4:5], 1
	ds_write2_b32 v9, v36, v37 offset1:1
	v_add_u32_e32 v9, 0x1ce0, v5
	v_add_u32_e32 v5, 0x1ce8, v5
	s_add_u32 s4, s50, s4
	s_waitcnt vmcnt(0)
	ds_write2_b32 v9, v38, v39 offset1:1
	ds_write2_b32 v5, v40, v41 offset1:1
	v_mul_u32_u24_e32 v9, 0x420, v7
	s_addc_u32 s5, s51, s5
	v_mov_b32_e32 v5, v3
	s_waitcnt lgkmcnt(0)
	v_lshl_add_u64 v[10:11], s[4:5], 0, v[4:5]
	v_add3_u32 v5, s1, v9, v6
	ds_read2_b32 v[14:15], v5 offset0:33 offset1:41
	ds_read2_b32 v[16:17], v5 offset1:8
	ds_read2_b32 v[18:19], v5 offset0:66 offset1:74
	ds_read2_b32 v[20:21], v5 offset0:99 offset1:107
	ds_read2_b32 v[22:23], v5 offset0:132 offset1:140
	ds_read2_b32 v[24:25], v5 offset0:165 offset1:173
	ds_read2_b32 v[26:27], v5 offset0:198 offset1:206
	ds_read2_b32 v[28:29], v5 offset0:231 offset1:239
	s_mov_b64 s[4:5], 0x1c00000
	v_lshl_add_u64 v[30:31], v[10:11], 0, s[4:5]
	v_lshlrev_b32_e32 v32, 11, v1
	v_mov_b32_e32 v33, v3
	s_waitcnt lgkmcnt(6)
	v_cvt_pk_bf16_f32 v10, v16, v14
	s_waitcnt lgkmcnt(4)
	v_cvt_pk_bf16_f32 v11, v18, v20
	s_waitcnt lgkmcnt(2)
	v_cvt_pk_bf16_f32 v12, v22, v24
	s_waitcnt lgkmcnt(0)
	v_cvt_pk_bf16_f32 v13, v26, v28
	v_lshl_add_u64 v[34:35], v[30:31], 0, v[32:33]
	global_store_dwordx4 v[34:35], v[10:13], off sc0 sc1
	v_or_b32_e32 v14, 0x4000, v32
	s_mov_b64 s[6:7], 0
	v_cvt_pk_bf16_f32 v10, v17, v15
	v_cvt_pk_bf16_f32 v11, v19, v21
	v_cvt_pk_bf16_f32 v12, v23, v25
	v_cvt_pk_bf16_f32 v13, v27, v29
	ds_read2_b32 v[16:17], v5 offset0:49 offset1:57
	ds_read2_b32 v[18:19], v5 offset0:16 offset1:24
	ds_read2_b32 v[20:21], v5 offset0:82 offset1:90
	ds_read2_b32 v[22:23], v5 offset0:115 offset1:123
	ds_read2_b32 v[24:25], v5 offset0:148 offset1:156
	ds_read2_b32 v[26:27], v5 offset0:181 offset1:189
	ds_read2_b32 v[28:29], v5 offset0:214 offset1:222
	ds_read2_b32 v[34:35], v5 offset0:247 offset1:255
	v_mov_b32_e32 v15, v3
	v_lshl_add_u64 v[14:15], v[30:31], 0, v[14:15]
	global_store_dwordx4 v[14:15], v[10:13], off sc0 sc1
	v_or_b32_e32 v14, 0x8000, v32
	v_mov_b32_e32 v15, v3
	s_waitcnt lgkmcnt(6)
	v_cvt_pk_bf16_f32 v10, v18, v16
	s_waitcnt lgkmcnt(4)
	v_cvt_pk_bf16_f32 v11, v20, v22
	s_waitcnt lgkmcnt(2)
	v_cvt_pk_bf16_f32 v12, v24, v26
	s_waitcnt lgkmcnt(0)
	v_cvt_pk_bf16_f32 v13, v28, v34
	v_lshl_add_u64 v[14:15], v[30:31], 0, v[14:15]
	global_store_dwordx4 v[14:15], v[10:13], off sc0 sc1
	v_or_b32_e32 v14, 0xc000, v32
	v_mov_b32_e32 v15, v3
	v_cvt_pk_bf16_f32 v10, v19, v17
	v_cvt_pk_bf16_f32 v11, v21, v23
	v_cvt_pk_bf16_f32 v12, v25, v27
	v_cvt_pk_bf16_f32 v13, v29, v35
	v_lshl_add_u64 v[14:15], v[30:31], 0, v[14:15]
	global_store_dwordx4 v[14:15], v[10:13], off sc0 sc1
	s_waitcnt lgkmcnt(0)
; #define LAS __attribute__((address_space(3)))
; __device__ __forceinline__ f32x4 ld_nt(const float* p) { return __builtin_nontemporal_load((const f32x4*)p); }
; __device__ __forceinline__ void transpose_item(const float* W, int K, int pitch, int ncols, f16* WT, LAS float* scr, int item, int lane) {
;     const int nblk = ncols / 32, kb = item / nblk, nb = item % nblk, k0 = 64 * kb, n0 = 32 * nb;
;     const int kr = lane >> 3, nq = (lane & 7) * 4;
;     f32x4 v[8];
; #pragma unroll
;     for (int i = 0; i < 8; ++i) v[i] = ld_nt(W + (size_t)(k0 + kr + 8 * i) * pitch + n0 + nq);
;     __builtin_amdgcn_sched_barrier(0);
; #pragma unroll
;     for (int i = 0; i < 8; ++i) { LAS float* sp = scr + (kr + 8 * i) * 33 + nq; sp[0] = v[i][0]; sp[1] = v[i][1]; sp[2] = v[i][2]; sp[3] = v[i][3]; }
;     asm volatile("s_waitcnt lgkmcnt(0)" ::: "memory");
;     const int c = lane & 7;
; #pragma unroll
;     for (int j = 0; j < 4; ++j) { const int n = (lane >> 3) + 8 * j; const LAS float* sp = scr + (8 * c) * 33 + n;
;         u32x4 o; o.x = pk_f16(sp[0 * 33], sp[1 * 33]); o.y = pk_f16(sp[2 * 33], sp[3 * 33]); o.z = pk_f16(sp[4 * 33], sp[5 * 33]); o.w = pk_f16(sp[6 * 33], sp[7 * 33]);
;         *(u32x4*)(WT + (size_t)(n0 + n) * K + k0 + 8 * c) = o; }
;     asm volatile("s_waitcnt lgkmcnt(0)" ::: "memory");
; }
.LBB0_31:
	s_andn2_b64 vcc, exec, s[6:7]
	s_cbranch_vccnz .LBB0_33
	s_add_i32 s4, s9, 0xf180
	s_and_b32 s6, s4, 0xffc0
	s_lshl_b32 s4, s10, 2
	s_add_u32 s4, s44, s4
	v_or_b32_e32 v5, s6, v8
	s_addc_u32 s5, s45, 0
	v_mov_b32_e32 v3, 0
	v_lshl_add_u64 v[10:11], s[4:5], 0, v[2:3]
	v_lshlrev_b32_e32 v12, 13, v5
	v_mov_b32_e32 v13, v3
	v_lshl_add_u64 v[34:35], v[10:11], 0, v[12:13]
	v_add_co_u32_e32 v14, vcc, 0x10000, v34
	s_nop 1
	v_addc_co_u32_e32 v15, vcc, 0, v35, vcc
	v_add_co_u32_e32 v18, vcc, 0x20000, v34
	global_load_dwordx4 v[10:13], v[34:35], off nt
	s_nop 0
	global_load_dwordx4 v[14:17], v[14:15], off nt
	v_addc_co_u32_e32 v19, vcc, 0, v35, vcc
	v_add_co_u32_e32 v22, vcc, 0x30000, v34
	s_nop 1
	v_addc_co_u32_e32 v23, vcc, 0, v35, vcc
	v_add_co_u32_e32 v26, vcc, 0x40000, v34
	global_load_dwordx4 v[18:21], v[18:19], off nt
	s_nop 0
	global_load_dwordx4 v[22:25], v[22:23], off nt
	v_addc_co_u32_e32 v27, vcc, 0, v35, vcc
	v_add_co_u32_e32 v30, vcc, 0x50000, v34
	s_nop 1
	v_addc_co_u32_e32 v31, vcc, 0, v35, vcc
	v_add_co_u32_e32 v36, vcc, 0x60000, v34
	global_load_dwordx4 v[26:29], v[26:27], off nt
	s_nop 0
	global_load_dwordx4 v[30:33], v[30:31], off nt
	v_addc_co_u32_e32 v37, vcc, 0, v35, vcc
	v_add_co_u32_e32 v38, vcc, 0x70000, v34
	s_nop 1
	v_addc_co_u32_e32 v39, vcc, 0, v35, vcc
	global_load_dwordx4 v[34:37], v[36:37], off nt
	s_nop 0
	global_load_dwordx4 v[38:41], v[38:39], off nt
	v_mul_u32_u24_e32 v5, 0x84, v8
	v_add3_u32 v2, s1, v2, v5
	v_add_u32_e32 v5, 0x420, v2
	s_waitcnt vmcnt(7)
	ds_write2_b32 v2, v10, v11 offset1:1
	ds_write2_b32 v2, v12, v13 offset0:2 offset1:3
	s_waitcnt vmcnt(6)
	ds_write2_b32 v5, v14, v15 offset1:1
	v_add_u32_e32 v5, 0x428, v2
	ds_write2_b32 v5, v16, v17 offset1:1
	v_add_u32_e32 v5, 0x840, v2
	s_waitcnt vmcnt(5)
	ds_write2_b32 v5, v18, v19 offset1:1
	v_add_u32_e32 v5, 0x848, v2
	ds_write2_b32 v5, v20, v21 offset1:1
	v_add_u32_e32 v5, 0xc60, v2
	s_waitcnt vmcnt(4)
	ds_write2_b32 v5, v22, v23 offset1:1
	v_add_u32_e32 v5, 0xc68, v2
	ds_write2_b32 v5, v24, v25 offset1:1
	v_add_u32_e32 v5, 0x1080, v2
	s_waitcnt vmcnt(3)
	ds_write2_b32 v5, v26, v27 offset1:1
	v_add_u32_e32 v5, 0x1088, v2
	ds_write2_b32 v5, v28, v29 offset1:1
	v_add_u32_e32 v5, 0x14a0, v2
	s_waitcnt vmcnt(2)
	ds_write2_b32 v5, v30, v31 offset1:1
	v_add_u32_e32 v5, 0x14a8, v2
	ds_write2_b32 v5, v32, v33 offset1:1
	v_add_u32_e32 v5, 0x18c0, v2
	s_waitcnt vmcnt(1)
	ds_write2_b32 v5, v34, v35 offset1:1
	v_add_u32_e32 v5, 0x18c8, v2
	ds_write2_b32 v5, v36, v37 offset1:1
	v_add_u32_e32 v5, 0x1ce0, v2
	v_add_u32_e32 v2, 0x1ce8, v2
	s_waitcnt vmcnt(0)
	ds_write2_b32 v5, v38, v39 offset1:1
	ds_write2_b32 v2, v40, v41 offset1:1
	v_mul_u32_u24_e32 v2, 0x420, v7
	s_waitcnt lgkmcnt(0)
	v_add3_u32 v28, s1, v2, v6
	s_lshl_b32 s4, s6, 1
	ds_read2_b32 v[8:9], v28 offset0:33 offset1:41
	ds_read2_b32 v[10:11], v28 offset1:8
	ds_read2_b32 v[12:13], v28 offset0:66 offset1:74
	ds_read2_b32 v[14:15], v28 offset0:99 offset1:107
	ds_read2_b32 v[16:17], v28 offset0:132 offset1:140
	ds_read2_b32 v[18:19], v28 offset0:165 offset1:173
	ds_read2_b32 v[20:21], v28 offset0:198 offset1:206
	ds_read2_b32 v[22:23], v28 offset0:231 offset1:239
	s_add_u32 s4, s50, s4
	s_addc_u32 s5, s51, 0
	v_mov_b32_e32 v5, v3
	v_lshl_add_u64 v[4:5], s[4:5], 0, v[4:5]
	s_mov_b64 s[4:5], 0x1400000
	v_lshl_add_u64 v[24:25], v[4:5], 0, s[4:5]
	v_lshlrev_b32_e32 v2, 12, v1
	s_waitcnt lgkmcnt(6)
	v_cvt_pk_bf16_f32 v4, v10, v8
	s_waitcnt lgkmcnt(4)
	v_cvt_pk_bf16_f32 v5, v12, v14
	s_waitcnt lgkmcnt(2)
	v_cvt_pk_bf16_f32 v6, v16, v18
	s_waitcnt lgkmcnt(0)
	v_cvt_pk_bf16_f32 v7, v20, v22
	v_lshl_add_u64 v[26:27], v[24:25], 0, v[2:3]
	global_store_dwordx4 v[26:27], v[4:7], off sc0 sc1
	v_or_b32_e32 v8, 0x8000, v2
	s_nop 0
	v_cvt_pk_bf16_f32 v4, v11, v9
	v_cvt_pk_bf16_f32 v5, v13, v15
	v_cvt_pk_bf16_f32 v6, v17, v19
	v_cvt_pk_bf16_f32 v7, v21, v23
	ds_read2_b32 v[10:11], v28 offset0:49 offset1:57
	ds_read2_b32 v[12:13], v28 offset0:16 offset1:24
	ds_read2_b32 v[14:15], v28 offset0:82 offset1:90
	ds_read2_b32 v[16:17], v28 offset0:115 offset1:123
	ds_read2_b32 v[18:19], v28 offset0:148 offset1:156
	ds_read2_b32 v[20:21], v28 offset0:181 offset1:189
	ds_read2_b32 v[22:23], v28 offset0:214 offset1:222
	ds_read2_b32 v[26:27], v28 offset0:247 offset1:255
	v_mov_b32_e32 v9, v3
	v_lshl_add_u64 v[8:9], v[24:25], 0, v[8:9]
	global_store_dwordx4 v[8:9], v[4:7], off sc0 sc1
	v_or_b32_e32 v8, 0x10000, v2
	v_mov_b32_e32 v9, v3
	s_waitcnt lgkmcnt(6)
	v_cvt_pk_bf16_f32 v4, v12, v10
	s_waitcnt lgkmcnt(4)
	v_cvt_pk_bf16_f32 v5, v14, v16
	s_waitcnt lgkmcnt(2)
	v_cvt_pk_bf16_f32 v6, v18, v20
	s_waitcnt lgkmcnt(0)
	v_cvt_pk_bf16_f32 v7, v22, v26
	v_lshl_add_u64 v[8:9], v[24:25], 0, v[8:9]
	v_or_b32_e32 v2, 0x18000, v2
	global_store_dwordx4 v[8:9], v[4:7], off sc0 sc1
	v_lshl_add_u64 v[2:3], v[24:25], 0, v[2:3]
	s_nop 0
	v_cvt_pk_bf16_f32 v4, v13, v11
	v_cvt_pk_bf16_f32 v5, v15, v17
	v_cvt_pk_bf16_f32 v6, v19, v21
	v_cvt_pk_bf16_f32 v7, v23, v27
	global_store_dwordx4 v[2:3], v[4:7], off sc0 sc1
	s_waitcnt lgkmcnt(0)

; #define LAS __attribute__((address_space(3)))
; __device__ __forceinline__ f32x4 ld_nt(const float* p) { return __builtin_nontemporal_load((const f32x4*)p); }
; __device__ __forceinline__ void transpose_item(const float* W, int K, int pitch, int ncols, f16* WT, LAS float* scr, int item, int lane) {
;     const int nblk = ncols / 32, kb = item / nblk, nb = item % nblk, k0 = 64 * kb, n0 = 32 * nb;
;     const int kr = lane >> 3, nq = (lane & 7) * 4;
;     f32x4 v[8];
; #pragma unroll
;     for (int i = 0; i < 8; ++i) v[i] = ld_nt(W + (size_t)(k0 + kr + 8 * i) * pitch + n0 + nq);
;     __builtin_amdgcn_sched_barrier(0);
; #pragma unroll
;     for (int i = 0; i < 8; ++i) { LAS float* sp = scr + (kr + 8 * i) * 33 + nq; sp[0] = v[i][0]; sp[1] = v[i][1]; sp[2] = v[i][2]; sp[3] = v[i][3]; }
;     asm volatile("s_waitcnt lgkmcnt(0)" ::: "memory");
;     const int c = lane & 7;
; #pragma unroll
;     for (int j = 0; j < 4; ++j) { const int n = (lane >> 3) + 8 * j; const LAS float* sp = scr + (8 * c) * 33 + n;
;         u32x4 o; o.x = pk_f16(sp[0 * 33], sp[1 * 33]); o.y = pk_f16(sp[2 * 33], sp[3 * 33]); o.z = pk_f16(sp[4 * 33], sp[5 * 33]); o.w = pk_f16(sp[6 * 33], sp[7 * 33]);
;         *(u32x4*)(WT + (size_t)(n0 + n) * K + k0 + 8 * c) = o; }
;     asm volatile("s_waitcnt lgkmcnt(0)" ::: "memory");
; }
.LBB0_34:
	s_andn2_b64 vcc, exec, s[4:5]
	s_cbranch_vccnz .LBB0_36
	s_add_i32 s4, s9, 0xfd80
	s_and_b32 s5, s4, 0xffff
	s_mul_i32 s5, s5, 0xaaab
	s_lshr_b32 s6, s5, 16
	s_lshr_b32 s5, s5, 22
	s_mulk_i32 s5, 0x60
	s_sub_i32 s4, s4, s5
	s_lshl_b32 s4, s4, 5
	s_and_b32 s7, s4, 0xffe0
	v_readlane_b32 s56, v254, 2
	s_and_b32 s6, s6, 0xffc0
	s_lshl_b32 s4, s7, 2
	v_readlane_b32 s70, v254, 16
	v_lshrrev_b32_e32 v1, 3, v212
	v_and_b32_e32 v36, 7, v0
	v_readlane_b32 s71, v254, 17
	s_add_u32 s4, s70, s4
	v_or_b32_e32 v4, s6, v1
	s_addc_u32 s5, s71, 0
	v_lshlrev_b32_e32 v34, 4, v36
	v_mov_b32_e32 v35, 0
	v_lshl_add_u64 v[2:3], s[4:5], 0, v[34:35]
	v_lshlrev_b32_e32 v4, 14, v4
	v_mov_b32_e32 v5, v35
	v_lshl_add_u64 v[26:27], v[2:3], 0, v[4:5]
	s_movk_i32 s4, 0x1000
	v_add_co_u32_e32 v2, vcc, s4, v26
	s_mov_b32 s4, 0x21000
	s_nop 0
	v_addc_co_u32_e32 v3, vcc, 0, v27, vcc
	v_add_co_u32_e32 v6, vcc, s4, v26
	s_mov_b32 s4, 0x41000
	s_nop 0
	v_addc_co_u32_e32 v7, vcc, 0, v27, vcc
	v_add_co_u32_e32 v10, vcc, s4, v26
	s_mov_b32 s4, 0x61000
	s_nop 0
	v_addc_co_u32_e32 v11, vcc, 0, v27, vcc
	v_add_co_u32_e32 v14, vcc, s4, v26
	s_mov_b32 s4, 0x81000
	s_nop 0
	v_addc_co_u32_e32 v15, vcc, 0, v27, vcc
	v_add_co_u32_e32 v18, vcc, s4, v26
	s_mov_b32 s4, 0xa1000
	s_nop 0
	v_addc_co_u32_e32 v19, vcc, 0, v27, vcc
	v_add_co_u32_e32 v22, vcc, s4, v26
	s_mov_b32 s4, 0xc1000
	s_nop 0
	v_addc_co_u32_e32 v23, vcc, 0, v27, vcc
	v_add_co_u32_e32 v28, vcc, s4, v26
	s_mov_b32 s4, 0xe1000
	s_nop 0
	v_addc_co_u32_e32 v29, vcc, 0, v27, vcc
	v_add_co_u32_e32 v30, vcc, s4, v26
	global_load_dwordx4 v[2:5], v[2:3], off nt
	s_nop 0
	global_load_dwordx4 v[6:9], v[6:7], off nt
	v_addc_co_u32_e32 v31, vcc, 0, v27, vcc
	global_load_dwordx4 v[10:13], v[10:11], off nt
	s_nop 0
	global_load_dwordx4 v[14:17], v[14:15], off nt
	s_nop 0
	global_load_dwordx4 v[18:21], v[18:19], off nt
	s_nop 0
	global_load_dwordx4 v[22:25], v[22:23], off nt
	s_nop 0
	global_load_dwordx4 v[26:29], v[28:29], off nt
	s_nop 0
	global_load_dwordx4 v[30:33], v[30:31], off nt
	v_readlane_b32 s57, v254, 3
	v_readlane_b32 s58, v254, 4
	v_readlane_b32 s59, v254, 5
	v_readlane_b32 s60, v254, 6
	v_readlane_b32 s61, v254, 7
	v_readlane_b32 s62, v254, 8
	v_readlane_b32 s63, v254, 9
	v_readlane_b32 s64, v254, 10
	v_readlane_b32 s65, v254, 11
	v_readlane_b32 s66, v254, 12
	v_readlane_b32 s67, v254, 13
	v_readlane_b32 s68, v254, 14
	v_readlane_b32 s69, v254, 15
	v_mul_u32_u24_e32 v37, 0x84, v1
	v_add3_u32 v37, s1, v34, v37
	s_waitcnt vmcnt(7)
	ds_write2_b32 v37, v2, v3 offset1:1
	ds_write2_b32 v37, v4, v5 offset0:2 offset1:3
	v_add_u32_e32 v2, 0x420, v37
	s_waitcnt vmcnt(6)
	ds_write2_b32 v2, v6, v7 offset1:1
	v_add_u32_e32 v2, 0x428, v37
	ds_write2_b32 v2, v8, v9 offset1:1
	v_add_u32_e32 v2, 0x840, v37
	s_waitcnt vmcnt(5)
	ds_write2_b32 v2, v10, v11 offset1:1
	v_add_u32_e32 v2, 0x848, v37
	ds_write2_b32 v2, v12, v13 offset1:1
	v_add_u32_e32 v2, 0xc60, v37
	s_waitcnt vmcnt(4)
	ds_write2_b32 v2, v14, v15 offset1:1
	v_add_u32_e32 v2, 0xc68, v37
	ds_write2_b32 v2, v16, v17 offset1:1
	v_add_u32_e32 v2, 0x1080, v37
	s_waitcnt vmcnt(3)
	ds_write2_b32 v2, v18, v19 offset1:1
	v_add_u32_e32 v2, 0x1088, v37
	ds_write2_b32 v2, v20, v21 offset1:1
	v_add_u32_e32 v2, 0x14a0, v37
	s_waitcnt vmcnt(2)
	ds_write2_b32 v2, v22, v23 offset1:1
	v_add_u32_e32 v2, 0x14a8, v37
	ds_write2_b32 v2, v24, v25 offset1:1
	v_add_u32_e32 v2, 0x18c0, v37
	s_waitcnt vmcnt(1)
	ds_write2_b32 v2, v26, v27 offset1:1
	v_add_u32_e32 v2, 0x18c8, v37
	ds_write2_b32 v2, v28, v29 offset1:1
	v_add_u32_e32 v2, 0x1ce0, v37
	s_waitcnt vmcnt(0)
	ds_write2_b32 v2, v30, v31 offset1:1
	v_add_u32_e32 v2, 0x1ce8, v37
	ds_write2_b32 v2, v32, v33 offset1:1
	v_mul_u32_u24_e32 v4, 0x420, v36
	v_lshlrev_b32_e32 v5, 2, v1
	s_waitcnt lgkmcnt(0)
	v_add3_u32 v26, s1, v4, v5
	s_lshl_b32 s4, s6, 1
	ds_read2_b32 v[6:7], v26 offset0:33 offset1:41
	ds_read2_b32 v[8:9], v26 offset1:8
	ds_read2_b32 v[10:11], v26 offset0:66 offset1:74
	ds_read2_b32 v[12:13], v26 offset0:99 offset1:107
	ds_read2_b32 v[14:15], v26 offset0:132 offset1:140
	ds_read2_b32 v[16:17], v26 offset0:165 offset1:173
	ds_read2_b32 v[18:19], v26 offset0:198 offset1:206
	ds_read2_b32 v[20:21], v26 offset0:231 offset1:239
	s_add_u32 s4, s50, s4
	s_addc_u32 s5, s51, 0
	v_lshl_add_u64 v[2:3], s[4:5], 0, v[34:35]
	s_mov_b64 s[4:5], 0x800000
	v_or_b32_e32 v1, s7, v1
	v_lshl_add_u64 v[22:23], v[2:3], 0, s[4:5]
	v_lshlrev_b32_e32 v34, 12, v1
	s_waitcnt lgkmcnt(6)
	v_cvt_pk_bf16_f32 v2, v8, v6
	s_waitcnt lgkmcnt(4)
	v_cvt_pk_bf16_f32 v3, v10, v12
	s_waitcnt lgkmcnt(2)
	v_cvt_pk_bf16_f32 v4, v14, v16
	s_waitcnt lgkmcnt(0)
	v_cvt_pk_bf16_f32 v5, v18, v20
	v_lshl_add_u64 v[24:25], v[22:23], 0, v[34:35]
	global_store_dwordx4 v[24:25], v[2:5], off sc0 sc1
	v_or_b32_e32 v6, 0x8000, v34
	s_nop 0
	v_cvt_pk_bf16_f32 v2, v9, v7
	v_cvt_pk_bf16_f32 v3, v11, v13
	v_cvt_pk_bf16_f32 v4, v15, v17
	v_cvt_pk_bf16_f32 v5, v19, v21
	ds_read2_b32 v[8:9], v26 offset0:49 offset1:57
	ds_read2_b32 v[10:11], v26 offset0:16 offset1:24
	ds_read2_b32 v[12:13], v26 offset0:82 offset1:90
	ds_read2_b32 v[14:15], v26 offset0:115 offset1:123
	ds_read2_b32 v[16:17], v26 offset0:148 offset1:156
	ds_read2_b32 v[18:19], v26 offset0:181 offset1:189
	ds_read2_b32 v[20:21], v26 offset0:214 offset1:222
	ds_read2_b32 v[24:25], v26 offset0:247 offset1:255
	v_mov_b32_e32 v7, v35
	v_lshl_add_u64 v[6:7], v[22:23], 0, v[6:7]
	global_store_dwordx4 v[6:7], v[2:5], off sc0 sc1
	v_or_b32_e32 v6, 0x10000, v34
	v_mov_b32_e32 v7, v35
	s_waitcnt lgkmcnt(6)
	v_cvt_pk_bf16_f32 v2, v10, v8
	s_waitcnt lgkmcnt(4)
	v_cvt_pk_bf16_f32 v3, v12, v14
	s_waitcnt lgkmcnt(2)
	v_cvt_pk_bf16_f32 v4, v16, v18
	s_waitcnt lgkmcnt(0)
	v_cvt_pk_bf16_f32 v5, v20, v24
	v_lshl_add_u64 v[6:7], v[22:23], 0, v[6:7]
	v_or_b32_e32 v34, 0x18000, v34
	global_store_dwordx4 v[6:7], v[2:5], off sc0 sc1
	v_lshl_add_u64 v[6:7], v[22:23], 0, v[34:35]
	s_nop 0
	v_cvt_pk_bf16_f32 v2, v11, v9
	v_cvt_pk_bf16_f32 v3, v13, v15
	v_cvt_pk_bf16_f32 v4, v17, v19
	v_cvt_pk_bf16_f32 v5, v21, v25
	global_store_dwordx4 v[6:7], v[2:5], off sc0 sc1
	s_waitcnt lgkmcnt(0)

; __device__ __forceinline__ f32x4 ld_nt(const float* p) { return __builtin_nontemporal_load((const f32x4*)p); }
; __device__ __forceinline__ u32x4 pack8(const f32x4 v0, const f32x4 v1) { u32x4 w; w.x = pk_f16(v0[0], v0[1]); w.y = pk_f16(v0[2], v0[3]); w.z = pk_f16(v1[0], v1[1]); w.w = pk_f16(v1[2], v1[3]); return w; }
; __device__ __forceinline__ void convert_item(const float* W, f16* O, int item, int lane) {
;     f32x4 v[4][4];
; #pragma unroll
;     for (int r = 0; r < 4; ++r)
; #pragma unroll
;         for (int q = 0; q < 4; ++q) v[r][q] = ld_nt(W + (size_t)(item * 4 + r) * 4096 + lane * 16 + q * 4);
;     __builtin_amdgcn_sched_barrier(0);
; #pragma unroll
;     for (int r = 0; r < 4; ++r) { f16* op = O + (size_t)(item * 4 + r) * 1024 + lane * 16; *(u32x4*)op = pack8(v[r][0], v[r][1]); *(u32x4*)(op + 8) = pack8(v[r][2], v[r][3]); }
; }
.LBB0_37:
	s_andn2_b64 vcc, exec, s[4:5]
	s_cbranch_vccnz .LBB0_39
	v_readlane_b32 s56, v254, 2
	s_add_i32 s10, s9, 0xffffff80
	v_lshlrev_b32_e32 v66, 6, v212
	v_mov_b32_e32 v67, 0
	v_readlane_b32 s70, v254, 16
	v_readlane_b32 s71, v254, 17
	s_lshl_b32 s4, s10, 14
	s_mov_b32 s5, 0
	v_lshl_add_u64 v[2:3], s[70:71], 0, v[66:67]
	v_lshl_add_u64 v[50:51], s[4:5], 2, v[2:3]
	v_add_co_u32_e32 v18, vcc, 0x4000, v50
	s_mov_b64 s[6:7], 0x4000
	s_nop 0
	v_addc_co_u32_e32 v19, vcc, 0, v51, vcc
	v_lshl_add_u64 v[30:31], v[50:51], 0, s[6:7]
	s_mov_b64 s[6:7], 0x8000
	v_add_co_u32_e32 v34, vcc, 0x8000, v50
	v_lshl_add_u64 v[46:47], v[50:51], 0, s[6:7]
	s_nop 0
	v_addc_co_u32_e32 v35, vcc, 0, v51, vcc
	s_mov_b64 s[6:7], 0xc000
	global_load_dwordx4 v[2:5], v[50:51], off offset:48 nt
	global_load_dwordx4 v[6:9], v[50:51], off offset:32 nt
	global_load_dwordx4 v[10:13], v[50:51], off offset:16 nt
	global_load_dwordx4 v[14:17], v[50:51], off nt
	v_lshl_add_u64 v[62:63], v[50:51], 0, s[6:7]
	v_add_co_u32_e32 v50, vcc, 0xc000, v50
	global_load_dwordx4 v[18:21], v[18:19], off nt
	s_nop 0
	global_load_dwordx4 v[22:25], v[30:31], off offset:48 nt
	global_load_dwordx4 v[26:29], v[30:31], off offset:32 nt
	s_nop 0
	global_load_dwordx4 v[30:33], v[30:31], off offset:16 nt
	v_addc_co_u32_e32 v51, vcc, 0, v51, vcc
	global_load_dwordx4 v[34:37], v[34:35], off nt
	s_nop 0
	global_load_dwordx4 v[38:41], v[46:47], off offset:48 nt
	global_load_dwordx4 v[42:45], v[46:47], off offset:32 nt
	s_nop 0
	global_load_dwordx4 v[46:49], v[46:47], off offset:16 nt
	s_nop 0
	global_load_dwordx4 v[50:53], v[50:51], off nt
	s_nop 0
	global_load_dwordx4 v[54:57], v[62:63], off offset:48 nt
	global_load_dwordx4 v[58:61], v[62:63], off offset:32 nt
	s_nop 0
	global_load_dwordx4 v[62:65], v[62:63], off offset:16 nt
	v_readlane_b32 s57, v254, 3
	v_readlane_b32 s58, v254, 4
	v_readlane_b32 s59, v254, 5
	v_readlane_b32 s60, v254, 6
	v_readlane_b32 s61, v254, 7
	v_readlane_b32 s62, v254, 8
	v_readlane_b32 s63, v254, 9
	v_readlane_b32 s64, v254, 10
	v_readlane_b32 s65, v254, 11
	v_readlane_b32 s66, v254, 12
	v_readlane_b32 s67, v254, 13
	v_readlane_b32 s68, v254, 14
	v_readlane_b32 s69, v254, 15
	v_lshlrev_b32_e32 v66, 5, v212
	v_lshl_add_u64 v[66:67], s[50:51], 0, v[66:67]
	s_lshl_b32 s4, s10, 13
	v_lshl_add_u64 v[66:67], v[66:67], 0, s[4:5]
	s_mov_b64 s[4:5], 0x13600000
	v_lshl_add_u64 v[68:69], v[66:67], 0, s[4:5]
	s_mov_b32 s4, 0x13601000
	s_waitcnt vmcnt(14)
	v_cvt_pk_bf16_f32 v6, v6, v7
	v_cvt_pk_bf16_f32 v7, v8, v9
	v_cvt_pk_bf16_f32 v8, v2, v3
	v_cvt_pk_bf16_f32 v9, v4, v5
	s_waitcnt vmcnt(11)
	v_cvt_pk_bf16_f32 v2, v18, v19
	v_cvt_pk_bf16_f32 v3, v20, v21
	s_waitcnt vmcnt(8)
	v_cvt_pk_bf16_f32 v4, v30, v31
	v_cvt_pk_bf16_f32 v5, v32, v33
	v_cvt_pk_bf16_f32 v14, v14, v15
	v_cvt_pk_bf16_f32 v15, v16, v17
	v_cvt_pk_bf16_f32 v16, v10, v11
	v_add_co_u32_e32 v10, vcc, s4, v66
	global_store_dwordx4 v[68:69], v[2:5], off offset:2048 sc0 sc1
	s_nop 0
	v_addc_co_u32_e32 v11, vcc, 0, v67, vcc
	v_cvt_pk_bf16_f32 v2, v26, v27
	v_cvt_pk_bf16_f32 v3, v28, v29
	v_cvt_pk_bf16_f32 v4, v22, v23
	v_cvt_pk_bf16_f32 v5, v24, v25
	global_store_dwordx4 v[68:69], v[2:5], off offset:2064 sc0 sc1
	v_cvt_pk_bf16_f32 v17, v12, v13
	global_store_dwordx4 v[10:11], v[14:17], off offset:-4096 sc0 sc1
	s_waitcnt vmcnt(10)
	v_cvt_pk_bf16_f32 v2, v34, v35
	v_cvt_pk_bf16_f32 v3, v36, v37
	s_waitcnt vmcnt(7)
	v_cvt_pk_bf16_f32 v4, v46, v47
	v_cvt_pk_bf16_f32 v5, v48, v49
	global_store_dwordx4 v[10:11], v[2:5], off sc0 sc1
	global_store_dwordx4 v[68:69], v[6:9], off offset:16 sc0 sc1
	s_nop 0
	v_cvt_pk_bf16_f32 v2, v42, v43
	v_cvt_pk_bf16_f32 v3, v44, v45
	v_cvt_pk_bf16_f32 v4, v38, v39
	v_cvt_pk_bf16_f32 v5, v40, v41
	global_store_dwordx4 v[10:11], v[2:5], off offset:16 sc0 sc1
	s_waitcnt vmcnt(9)
	s_nop 0
	v_cvt_pk_bf16_f32 v2, v50, v51
	v_cvt_pk_bf16_f32 v3, v52, v53
	s_waitcnt vmcnt(6)
	v_cvt_pk_bf16_f32 v4, v62, v63
	v_cvt_pk_bf16_f32 v5, v64, v65
	global_store_dwordx4 v[10:11], v[2:5], off offset:2048 sc0 sc1
	s_nop 1
	v_cvt_pk_bf16_f32 v2, v58, v59
	v_cvt_pk_bf16_f32 v3, v60, v61
	v_cvt_pk_bf16_f32 v4, v54, v55
	v_cvt_pk_bf16_f32 v5, v56, v57
	global_store_dwordx4 v[10:11], v[2:5], off offset:2064 sc0 sc1

; #define LAS __attribute__((address_space(3)))
; __device__ __forceinline__ f32x4 ld_nt(const float* p) { return __builtin_nontemporal_load((const f32x4*)p); }
; __device__ __forceinline__ void transpose_item(const float* W, int K, int pitch, int ncols, f16* WT, LAS float* scr, int item, int lane) {
;     const int nblk = ncols / 32, kb = item / nblk, nb = item % nblk, k0 = 64 * kb, n0 = 32 * nb;
;     const int kr = lane >> 3, nq = (lane & 7) * 4;
;     f32x4 v[8];
; #pragma unroll
;     for (int i = 0; i < 8; ++i) v[i] = ld_nt(W + (size_t)(k0 + kr + 8 * i) * pitch + n0 + nq);
;     __builtin_amdgcn_sched_barrier(0);
; #pragma unroll
;     for (int i = 0; i < 8; ++i) { LAS float* sp = scr + (kr + 8 * i) * 33 + nq; sp[0] = v[i][0]; sp[1] = v[i][1]; sp[2] = v[i][2]; sp[3] = v[i][3]; }
;     asm volatile("s_waitcnt lgkmcnt(0)" ::: "memory");
;     const int c = lane & 7;
; #pragma unroll
;     for (int j = 0; j < 4; ++j) { const int n = (lane >> 3) + 8 * j; const LAS float* sp = scr + (8 * c) * 33 + n;
;         u32x4 o; o.x = pk_f16(sp[0 * 33], sp[1 * 33]); o.y = pk_f16(sp[2 * 33], sp[3 * 33]); o.z = pk_f16(sp[4 * 33], sp[5 * 33]); o.w = pk_f16(sp[6 * 33], sp[7 * 33]);
;         *(u32x4*)(WT + (size_t)(n0 + n) * K + k0 + 8 * c) = o; }
;     asm volatile("s_waitcnt lgkmcnt(0)" ::: "memory");
; }
.LBB0_40:
	s_andn2_b64 vcc, exec, s[4:5]
	s_cbranch_vccnz .LBB0_42
	s_lshl_b32 s4, s9, 11
	s_and_b32 s4, s4, 0x30000
	s_lshl_b32 s5, s4, 2
	v_readlane_b32 s56, v254, 18
	v_readlane_b32 s57, v254, 19
	s_add_u32 s5, s56, s5
	s_addc_u32 s6, s57, 0
	s_lshl_b32 s4, s4, 1
	s_add_u32 s7, s50, s4
	s_addc_u32 s10, s51, 0
	s_lshl_b32 s4, s9, 3
	s_and_b32 s9, s4, 0xc0
	s_lshl_b32 s4, s53, 5
	s_and_b32 s11, s4, 0xe0
	s_lshl_b32 s4, s11, 2
	v_lshrrev_b32_e32 v1, 3, v212
	v_and_b32_e32 v36, 7, v0
	s_add_u32 s4, s5, s4
	v_or_b32_e32 v4, s9, v1
	s_addc_u32 s5, s6, 0
	v_lshlrev_b32_e32 v34, 4, v36
	v_mov_b32_e32 v35, 0
	v_lshl_add_u64 v[2:3], s[4:5], 0, v[34:35]
	v_lshlrev_b32_e32 v4, 10, v4
	v_mov_b32_e32 v5, v35
	v_lshl_add_u64 v[26:27], v[2:3], 0, v[4:5]
	s_movk_i32 s4, 0x2000
	v_add_co_u32_e32 v6, vcc, s4, v26
	s_movk_i32 s4, 0x4000
	s_nop 0
	v_addc_co_u32_e32 v7, vcc, 0, v27, vcc
	v_add_co_u32_e32 v10, vcc, s4, v26
	s_movk_i32 s4, 0x6000
	s_nop 0
	v_addc_co_u32_e32 v11, vcc, 0, v27, vcc
	v_add_co_u32_e32 v14, vcc, s4, v26
	s_mov_b32 s4, 0x8000
	s_nop 0
	v_addc_co_u32_e32 v15, vcc, 0, v27, vcc
	v_add_co_u32_e32 v18, vcc, s4, v26
	s_mov_b32 s4, 0xa000
	s_nop 0
	v_addc_co_u32_e32 v19, vcc, 0, v27, vcc
	v_add_co_u32_e32 v22, vcc, s4, v26
	s_mov_b32 s4, 0xc000
	s_nop 0
	v_addc_co_u32_e32 v23, vcc, 0, v27, vcc
	v_add_co_u32_e32 v28, vcc, s4, v26
	s_mov_b32 s4, 0xe000
	s_nop 0
	v_addc_co_u32_e32 v29, vcc, 0, v27, vcc
	v_add_co_u32_e32 v30, vcc, s4, v26
	global_load_dwordx4 v[2:5], v[26:27], off nt
	s_nop 0
	global_load_dwordx4 v[6:9], v[6:7], off nt
	v_addc_co_u32_e32 v31, vcc, 0, v27, vcc
	global_load_dwordx4 v[10:13], v[10:11], off nt
	s_nop 0
	global_load_dwordx4 v[14:17], v[14:15], off nt
	s_nop 0
	global_load_dwordx4 v[18:21], v[18:19], off nt
	s_nop 0
	global_load_dwordx4 v[22:25], v[22:23], off nt
	s_nop 0
	global_load_dwordx4 v[26:29], v[28:29], off nt
	s_nop 0
	global_load_dwordx4 v[30:33], v[30:31], off nt
	v_readlane_b32 s58, v254, 20
	v_readlane_b32 s59, v254, 21
	v_readlane_b32 s60, v254, 22
	v_readlane_b32 s61, v254, 23
	v_readlane_b32 s62, v254, 24
	v_readlane_b32 s63, v254, 25
	v_readlane_b32 s64, v254, 26
	v_readlane_b32 s65, v254, 27
	v_readlane_b32 s66, v254, 28
	v_readlane_b32 s67, v254, 29
	v_readlane_b32 s68, v254, 30
	v_readlane_b32 s69, v254, 31
	v_readlane_b32 s70, v254, 32
	v_readlane_b32 s71, v254, 33
	v_mul_u32_u24_e32 v37, 0x84, v1
	v_add3_u32 v37, s1, v34, v37
	s_waitcnt vmcnt(7)
	ds_write2_b32 v37, v2, v3 offset1:1
	ds_write2_b32 v37, v4, v5 offset0:2 offset1:3
	v_add_u32_e32 v2, 0x420, v37
	s_waitcnt vmcnt(6)
	ds_write2_b32 v2, v6, v7 offset1:1
	v_add_u32_e32 v2, 0x428, v37
	ds_write2_b32 v2, v8, v9 offset1:1
	v_add_u32_e32 v2, 0x840, v37
	s_waitcnt vmcnt(5)
	ds_write2_b32 v2, v10, v11 offset1:1
	v_add_u32_e32 v2, 0x848, v37
	ds_write2_b32 v2, v12, v13 offset1:1
	v_add_u32_e32 v2, 0xc60, v37
	s_waitcnt vmcnt(4)
	ds_write2_b32 v2, v14, v15 offset1:1
	v_add_u32_e32 v2, 0xc68, v37
	ds_write2_b32 v2, v16, v17 offset1:1
	v_add_u32_e32 v2, 0x1080, v37
	s_waitcnt vmcnt(3)
	ds_write2_b32 v2, v18, v19 offset1:1
	v_add_u32_e32 v2, 0x1088, v37
	ds_write2_b32 v2, v20, v21 offset1:1
	v_add_u32_e32 v2, 0x14a0, v37
	s_waitcnt vmcnt(2)
	ds_write2_b32 v2, v22, v23 offset1:1
	v_add_u32_e32 v2, 0x14a8, v37
	ds_write2_b32 v2, v24, v25 offset1:1
	v_add_u32_e32 v2, 0x18c0, v37
	s_waitcnt vmcnt(1)
	ds_write2_b32 v2, v26, v27 offset1:1
	v_add_u32_e32 v2, 0x18c8, v37
	ds_write2_b32 v2, v28, v29 offset1:1
	v_add_u32_e32 v2, 0x1ce0, v37
	s_waitcnt vmcnt(0)
	ds_write2_b32 v2, v30, v31 offset1:1
	v_add_u32_e32 v2, 0x1ce8, v37
	ds_write2_b32 v2, v32, v33 offset1:1
	v_mul_u32_u24_e32 v4, 0x420, v36
	v_lshlrev_b32_e32 v5, 2, v1
	s_waitcnt lgkmcnt(0)
	v_add3_u32 v26, s1, v4, v5
	s_lshl_b32 s4, s9, 1
	ds_read2_b32 v[6:7], v26 offset0:33 offset1:41
	ds_read2_b32 v[8:9], v26 offset1:8
	ds_read2_b32 v[10:11], v26 offset0:66 offset1:74
	ds_read2_b32 v[12:13], v26 offset0:99 offset1:107
	ds_read2_b32 v[14:15], v26 offset0:132 offset1:140
	ds_read2_b32 v[16:17], v26 offset0:165 offset1:173
	ds_read2_b32 v[18:19], v26 offset0:198 offset1:206
	ds_read2_b32 v[20:21], v26 offset0:231 offset1:239
	s_add_u32 s4, s7, s4
	s_addc_u32 s5, s10, 0
	v_lshl_add_u64 v[2:3], s[4:5], 0, v[34:35]
	s_mov_b64 s[4:5], 0x2000000
	v_or_b32_e32 v1, s11, v1
	v_lshl_add_u64 v[22:23], v[2:3], 0, s[4:5]
	v_lshlrev_b32_e32 v34, 9, v1
	s_waitcnt lgkmcnt(6)
	v_cvt_pk_bf16_f32 v2, v8, v6
	s_waitcnt lgkmcnt(4)
	v_cvt_pk_bf16_f32 v3, v10, v12
	s_waitcnt lgkmcnt(2)
	v_cvt_pk_bf16_f32 v4, v14, v16
	s_waitcnt lgkmcnt(0)
	v_cvt_pk_bf16_f32 v5, v18, v20
	v_lshl_add_u64 v[24:25], v[22:23], 0, v[34:35]
	global_store_dwordx4 v[24:25], v[2:5], off sc0 sc1
	v_or_b32_e32 v6, 0x1000, v34
	s_nop 0
	v_cvt_pk_bf16_f32 v2, v9, v7
	v_cvt_pk_bf16_f32 v3, v11, v13
	v_cvt_pk_bf16_f32 v4, v15, v17
	v_cvt_pk_bf16_f32 v5, v19, v21
	ds_read2_b32 v[8:9], v26 offset0:49 offset1:57
	ds_read2_b32 v[10:11], v26 offset0:16 offset1:24
	ds_read2_b32 v[12:13], v26 offset0:82 offset1:90
	ds_read2_b32 v[14:15], v26 offset0:115 offset1:123
	ds_read2_b32 v[16:17], v26 offset0:148 offset1:156
	ds_read2_b32 v[18:19], v26 offset0:181 offset1:189
	ds_read2_b32 v[20:21], v26 offset0:214 offset1:222
	ds_read2_b32 v[24:25], v26 offset0:247 offset1:255
	v_mov_b32_e32 v7, v35
	v_lshl_add_u64 v[6:7], v[22:23], 0, v[6:7]
	global_store_dwordx4 v[6:7], v[2:5], off sc0 sc1
	v_or_b32_e32 v6, 0x2000, v34
	v_mov_b32_e32 v7, v35
	s_waitcnt lgkmcnt(6)
	v_cvt_pk_bf16_f32 v2, v10, v8
	s_waitcnt lgkmcnt(4)
	v_cvt_pk_bf16_f32 v3, v12, v14
	s_waitcnt lgkmcnt(2)
	v_cvt_pk_bf16_f32 v4, v16, v18
	s_waitcnt lgkmcnt(0)
	v_cvt_pk_bf16_f32 v5, v20, v24
	v_lshl_add_u64 v[6:7], v[22:23], 0, v[6:7]
	v_or_b32_e32 v34, 0x3000, v34
	global_store_dwordx4 v[6:7], v[2:5], off sc0 sc1
	v_lshl_add_u64 v[6:7], v[22:23], 0, v[34:35]
	s_nop 0
	v_cvt_pk_bf16_f32 v2, v11, v9
	v_cvt_pk_bf16_f32 v3, v13, v15
	v_cvt_pk_bf16_f32 v4, v17, v19
	v_cvt_pk_bf16_f32 v5, v21, v25
	global_store_dwordx4 v[6:7], v[2:5], off sc0 sc1
	s_waitcnt lgkmcnt(0)

; #define LAS __attribute__((address_space(3)))
; __device__ __forceinline__ f32x4 ld_nt(const float* p) { return __builtin_nontemporal_load((const f32x4*)p); }
; __device__ __forceinline__ void transpose_item(const float* W, int K, int pitch, int ncols, f16* WT, LAS float* scr, int item, int lane) {
;     const int nblk = ncols / 32, kb = item / nblk, nb = item % nblk, k0 = 64 * kb, n0 = 32 * nb;
;     const int kr = lane >> 3, nq = (lane & 7) * 4;
;     f32x4 v[8];
; #pragma unroll
;     for (int i = 0; i < 8; ++i) v[i] = ld_nt(W + (size_t)(k0 + kr + 8 * i) * pitch + n0 + nq);
;     __builtin_amdgcn_sched_barrier(0);
; #pragma unroll
;     for (int i = 0; i < 8; ++i) { LAS float* sp = scr + (kr + 8 * i) * 33 + nq; sp[0] = v[i][0]; sp[1] = v[i][1]; sp[2] = v[i][2]; sp[3] = v[i][3]; }
;     asm volatile("s_waitcnt lgkmcnt(0)" ::: "memory");
;     const int c = lane & 7;
; #pragma unroll
;     for (int j = 0; j < 4; ++j) { const int n = (lane >> 3) + 8 * j; const LAS float* sp = scr + (8 * c) * 33 + n;
;         u32x4 o; o.x = pk_f16(sp[0 * 33], sp[1 * 33]); o.y = pk_f16(sp[2 * 33], sp[3 * 33]); o.z = pk_f16(sp[4 * 33], sp[5 * 33]); o.w = pk_f16(sp[6 * 33], sp[7 * 33]);
;         *(u32x4*)(WT + (size_t)(n0 + n) * K + k0 + 8 * c) = o; }
;     asm volatile("s_waitcnt lgkmcnt(0)" ::: "memory");
; }
.LBB0_44:
	s_cmpk_gt_u32 s19, 0xe7f
	s_mov_b64 s[14:15], -1
	s_cbranch_scc0 .LBB0_50
	s_and_b32 s28, s20, 0x7e0
	s_cmpk_gt_u32 s19, 0x167f
	v_or_b32_e32 v40, s28, v20
	v_or_b32_e32 v39, s28, v21
	v_or_b32_e32 v38, s28, v3
	v_or_b32_e32 v37, s28, v1
	s_cbranch_scc0 .LBB0_47
	s_and_b32 s12, s19, 0x7fffffc0
	s_add_i32 s14, s12, 0xffffe980
	v_or_b32_e32 v6, s14, v20
	s_lshl_b32 s12, s28, 2
	v_lshlrev_b64 v[42:43], 13, v[6:7]
	v_or_b32_e32 v44, 8, v6
	v_mov_b32_e32 v45, v7
	v_or_b32_e32 v50, 16, v6
	v_mov_b32_e32 v51, v7
	v_or_b32_e32 v52, 24, v6
	v_mov_b32_e32 v53, v7
	v_or_b32_e32 v58, 32, v6
	v_mov_b32_e32 v59, v7
	v_or_b32_e32 v60, 40, v6
	v_mov_b32_e32 v61, v7
	v_or_b32_e32 v68, 48, v6
	v_mov_b32_e32 v69, v7
	v_or_b32_e32 v6, 56, v6
	v_lshl_add_u64 v[66:67], v[8:9], 0, s[12:13]
	v_lshlrev_b64 v[44:45], 13, v[44:45]
	v_lshlrev_b64 v[50:51], 13, v[50:51]
	v_lshlrev_b64 v[52:53], 13, v[52:53]
	v_lshlrev_b64 v[58:59], 13, v[58:59]
	v_lshlrev_b64 v[60:61], 13, v[60:61]
	v_lshlrev_b64 v[68:69], 13, v[68:69]
	v_lshlrev_b64 v[70:71], 13, v[6:7]
	v_lshl_add_u64 v[42:43], v[66:67], 0, v[42:43]
	v_lshl_add_u64 v[46:47], v[66:67], 0, v[44:45]
	v_lshl_add_u64 v[50:51], v[66:67], 0, v[50:51]
	v_lshl_add_u64 v[54:55], v[66:67], 0, v[52:53]
	v_lshl_add_u64 v[58:59], v[66:67], 0, v[58:59]
	v_lshl_add_u64 v[62:63], v[66:67], 0, v[60:61]
	v_lshl_add_u64 v[68:69], v[66:67], 0, v[68:69]
	v_lshl_add_u64 v[70:71], v[66:67], 0, v[70:71]
	global_load_dwordx4 v[42:45], v[42:43], off nt
	s_nop 0
	global_load_dwordx4 v[46:49], v[46:47], off nt
	s_nop 0
	global_load_dwordx4 v[50:53], v[50:51], off nt
	s_nop 0
	global_load_dwordx4 v[54:57], v[54:55], off nt
	s_nop 0
	global_load_dwordx4 v[58:61], v[58:59], off nt
	s_nop 0
	global_load_dwordx4 v[62:65], v[62:63], off nt
	s_nop 0
	global_load_dwordx4 v[66:69], v[68:69], off nt
	s_nop 0
	global_load_dwordx4 v[70:73], v[70:71], off nt
	s_waitcnt vmcnt(7)
	ds_write2_b32 v22, v42, v43 offset1:1
	ds_write2_b32 v22, v44, v45 offset0:2 offset1:3
	s_waitcnt vmcnt(6)
	ds_write2_b32 v23, v46, v47 offset1:1
	ds_write2_b32 v24, v48, v49 offset1:1
	s_waitcnt vmcnt(5)
	ds_write2_b32 v25, v50, v51 offset1:1
	ds_write2_b32 v26, v52, v53 offset1:1
	s_waitcnt vmcnt(4)
	ds_write2_b32 v27, v54, v55 offset1:1
	ds_write2_b32 v28, v56, v57 offset1:1
	s_waitcnt vmcnt(3)
	ds_write2_b32 v29, v58, v59 offset1:1
	ds_write2_b32 v30, v60, v61 offset1:1
	s_waitcnt vmcnt(2)
	ds_write2_b32 v31, v62, v63 offset1:1
	ds_write2_b32 v32, v64, v65 offset1:1
	s_waitcnt vmcnt(1)
	ds_write2_b32 v33, v66, v67 offset1:1
	ds_write2_b32 v34, v68, v69 offset1:1
	s_waitcnt vmcnt(0)
	ds_write2_b32 v35, v70, v71 offset1:1
	ds_write2_b32 v36, v72, v73 offset1:1
	s_waitcnt lgkmcnt(0)
	ds_read2_b32 v[46:47], v5 offset0:33 offset1:41
	ds_read2_b32 v[48:49], v5 offset1:8
	ds_read2_b32 v[50:51], v5 offset0:66 offset1:74
	ds_read2_b32 v[52:53], v5 offset0:99 offset1:107
	ds_read2_b32 v[54:55], v5 offset0:132 offset1:140
	ds_read2_b32 v[56:57], v5 offset0:165 offset1:173
	ds_read2_b32 v[58:59], v5 offset0:198 offset1:206
	ds_read2_b32 v[60:61], v5 offset0:231 offset1:239
	s_mov_b32 s15, s13
	v_lshl_add_u64 v[62:63], s[14:15], 1, v[10:11]
	v_lshlrev_b32_e32 v6, 11, v40
	s_waitcnt lgkmcnt(6)
	v_cvt_pk_bf16_f32 v42, v48, v46
	s_waitcnt lgkmcnt(4)
	v_cvt_pk_bf16_f32 v43, v50, v52
	s_waitcnt lgkmcnt(2)
	v_cvt_pk_bf16_f32 v44, v54, v56
	s_waitcnt lgkmcnt(0)
	v_cvt_pk_bf16_f32 v45, v58, v60
	v_lshl_add_u64 v[64:65], v[62:63], 0, v[6:7]
	global_store_dwordx4 v[64:65], v[42:45], off sc0 sc1
	v_lshlrev_b32_e32 v6, 11, v39
	s_mov_b64 s[14:15], 0
	v_cvt_pk_bf16_f32 v42, v49, v47
	v_cvt_pk_bf16_f32 v43, v51, v53
	v_cvt_pk_bf16_f32 v44, v55, v57
	v_cvt_pk_bf16_f32 v45, v59, v61
	ds_read2_b32 v[48:49], v5 offset0:49 offset1:57
	ds_read2_b32 v[50:51], v5 offset0:16 offset1:24
	ds_read2_b32 v[52:53], v5 offset0:82 offset1:90
	ds_read2_b32 v[54:55], v5 offset0:115 offset1:123
	ds_read2_b32 v[56:57], v5 offset0:148 offset1:156
	ds_read2_b32 v[58:59], v5 offset0:181 offset1:189
	ds_read2_b32 v[60:61], v5 offset0:214 offset1:222
	ds_read2_b32 v[64:65], v5 offset0:247 offset1:255
	v_lshl_add_u64 v[46:47], v[62:63], 0, v[6:7]
	v_lshlrev_b32_e32 v6, 11, v38
	global_store_dwordx4 v[46:47], v[42:45], off sc0 sc1
	v_lshl_add_u64 v[46:47], v[62:63], 0, v[6:7]
	v_lshlrev_b32_e32 v6, 11, v37
	s_waitcnt lgkmcnt(6)
	v_cvt_pk_bf16_f32 v42, v50, v48
	s_waitcnt lgkmcnt(4)
	v_cvt_pk_bf16_f32 v43, v52, v54
	s_waitcnt lgkmcnt(2)
	v_cvt_pk_bf16_f32 v44, v56, v58
	s_waitcnt lgkmcnt(0)
	v_cvt_pk_bf16_f32 v45, v60, v64
	global_store_dwordx4 v[46:47], v[42:45], off sc0 sc1
	v_lshl_add_u64 v[46:47], v[62:63], 0, v[6:7]
	s_nop 0
	v_cvt_pk_bf16_f32 v42, v51, v49
	v_cvt_pk_bf16_f32 v43, v53, v55
	v_cvt_pk_bf16_f32 v44, v57, v59
	v_cvt_pk_bf16_f32 v45, v61, v65
	global_store_dwordx4 v[46:47], v[42:45], off sc0 sc1
	s_waitcnt lgkmcnt(0)
; #define LAS __attribute__((address_space(3)))
; __device__ __forceinline__ f32x4 ld_nt(const float* p) { return __builtin_nontemporal_load((const f32x4*)p); }
; __device__ __forceinline__ void transpose_item(const float* W, int K, int pitch, int ncols, f16* WT, LAS float* scr, int item, int lane) {
;     const int nblk = ncols / 32, kb = item / nblk, nb = item % nblk, k0 = 64 * kb, n0 = 32 * nb;
;     const int kr = lane >> 3, nq = (lane & 7) * 4;
;     f32x4 v[8];
; #pragma unroll
;     for (int i = 0; i < 8; ++i) v[i] = ld_nt(W + (size_t)(k0 + kr + 8 * i) * pitch + n0 + nq);
;     __builtin_amdgcn_sched_barrier(0);
; #pragma unroll
;     for (int i = 0; i < 8; ++i) { LAS float* sp = scr + (kr + 8 * i) * 33 + nq; sp[0] = v[i][0]; sp[1] = v[i][1]; sp[2] = v[i][2]; sp[3] = v[i][3]; }
;     asm volatile("s_waitcnt lgkmcnt(0)" ::: "memory");
;     const int c = lane & 7;
; #pragma unroll
;     for (int j = 0; j < 4; ++j) { const int n = (lane >> 3) + 8 * j; const LAS float* sp = scr + (8 * c) * 33 + n;
;         u32x4 o; o.x = pk_f16(sp[0 * 33], sp[1 * 33]); o.y = pk_f16(sp[2 * 33], sp[3 * 33]); o.z = pk_f16(sp[4 * 33], sp[5 * 33]); o.w = pk_f16(sp[6 * 33], sp[7 * 33]);
;         *(u32x4*)(WT + (size_t)(n0 + n) * K + k0 + 8 * c) = o; }
;     asm volatile("s_waitcnt lgkmcnt(0)" ::: "memory");
; }
.LBB0_47:
	s_andn2_b64 vcc, exec, s[14:15]
	s_cbranch_vccnz .LBB0_49
	s_add_i32 s12, s19, 0xf180
	s_and_b32 s14, s12, 0xffc0
	v_or_b32_e32 v6, s14, v20
	s_lshl_b32 s12, s28, 2
	v_lshl_add_u64 v[42:43], v[12:13], 0, s[12:13]
	v_lshlrev_b32_e32 v6, 13, v6
	v_lshl_add_u64 v[66:67], v[42:43], 0, v[6:7]
	v_add_co_u32_e32 v46, vcc, 0x10000, v66
	s_nop 1
	v_addc_co_u32_e32 v47, vcc, 0, v67, vcc
	v_add_co_u32_e32 v50, vcc, 0x20000, v66
	global_load_dwordx4 v[42:45], v[66:67], off nt
	s_nop 0
	global_load_dwordx4 v[46:49], v[46:47], off nt
	v_addc_co_u32_e32 v51, vcc, 0, v67, vcc
	v_add_co_u32_e32 v54, vcc, 0x30000, v66
	s_nop 1
	v_addc_co_u32_e32 v55, vcc, 0, v67, vcc
	v_add_co_u32_e32 v58, vcc, 0x40000, v66
	global_load_dwordx4 v[50:53], v[50:51], off nt
	s_nop 0
	global_load_dwordx4 v[54:57], v[54:55], off nt
	v_addc_co_u32_e32 v59, vcc, 0, v67, vcc
	v_add_co_u32_e32 v62, vcc, 0x50000, v66
	s_nop 1
	v_addc_co_u32_e32 v63, vcc, 0, v67, vcc
	v_add_co_u32_e32 v68, vcc, 0x60000, v66
	global_load_dwordx4 v[58:61], v[58:59], off nt
	s_nop 0
	global_load_dwordx4 v[62:65], v[62:63], off nt
	v_addc_co_u32_e32 v69, vcc, 0, v67, vcc
	v_add_co_u32_e32 v70, vcc, 0x70000, v66
	s_nop 1
	v_addc_co_u32_e32 v71, vcc, 0, v67, vcc
	global_load_dwordx4 v[66:69], v[68:69], off nt
	s_nop 0
	global_load_dwordx4 v[70:73], v[70:71], off nt
	s_waitcnt vmcnt(7)
	ds_write2_b32 v22, v42, v43 offset1:1
	ds_write2_b32 v22, v44, v45 offset0:2 offset1:3
	s_waitcnt vmcnt(6)
	ds_write2_b32 v23, v46, v47 offset1:1
	ds_write2_b32 v24, v48, v49 offset1:1
	s_waitcnt vmcnt(5)
	ds_write2_b32 v25, v50, v51 offset1:1
	ds_write2_b32 v26, v52, v53 offset1:1
	s_waitcnt vmcnt(4)
	ds_write2_b32 v27, v54, v55 offset1:1
	ds_write2_b32 v28, v56, v57 offset1:1
	s_waitcnt vmcnt(3)
	ds_write2_b32 v29, v58, v59 offset1:1
	ds_write2_b32 v30, v60, v61 offset1:1
	s_waitcnt vmcnt(2)
	ds_write2_b32 v31, v62, v63 offset1:1
	ds_write2_b32 v32, v64, v65 offset1:1
	s_waitcnt vmcnt(1)
	ds_write2_b32 v33, v66, v67 offset1:1
	ds_write2_b32 v34, v68, v69 offset1:1
	s_waitcnt vmcnt(0)
	ds_write2_b32 v35, v70, v71 offset1:1
	ds_write2_b32 v36, v72, v73 offset1:1
	s_waitcnt lgkmcnt(0)
	ds_read2_b32 v[46:47], v5 offset0:33 offset1:41
	ds_read2_b32 v[48:49], v5 offset1:8
	ds_read2_b32 v[50:51], v5 offset0:66 offset1:74
	ds_read2_b32 v[52:53], v5 offset0:99 offset1:107
	ds_read2_b32 v[54:55], v5 offset0:132 offset1:140
	ds_read2_b32 v[56:57], v5 offset0:165 offset1:173
	ds_read2_b32 v[58:59], v5 offset0:198 offset1:206
	ds_read2_b32 v[60:61], v5 offset0:231 offset1:239
	s_lshl_b32 s12, s14, 1
	v_lshl_add_u64 v[62:63], v[14:15], 0, s[12:13]
	v_lshlrev_b32_e32 v6, 12, v40
	s_waitcnt lgkmcnt(6)
	v_cvt_pk_bf16_f32 v42, v48, v46
	s_waitcnt lgkmcnt(4)
	v_cvt_pk_bf16_f32 v43, v50, v52
	s_waitcnt lgkmcnt(2)
	v_cvt_pk_bf16_f32 v44, v54, v56
	s_waitcnt lgkmcnt(0)
	v_cvt_pk_bf16_f32 v45, v58, v60
	v_lshl_add_u64 v[40:41], v[62:63], 0, v[6:7]
	global_store_dwordx4 v[40:41], v[42:45], off sc0 sc1
	v_cvt_pk_bf16_f32 v40, v49, v47
	v_cvt_pk_bf16_f32 v41, v51, v53
	v_cvt_pk_bf16_f32 v42, v55, v57
	v_cvt_pk_bf16_f32 v43, v59, v61
	ds_read2_b32 v[46:47], v5 offset0:49 offset1:57
	ds_read2_b32 v[48:49], v5 offset0:16 offset1:24
	ds_read2_b32 v[50:51], v5 offset0:82 offset1:90
	ds_read2_b32 v[52:53], v5 offset0:115 offset1:123
	ds_read2_b32 v[54:55], v5 offset0:148 offset1:156
	ds_read2_b32 v[56:57], v5 offset0:181 offset1:189
	ds_read2_b32 v[58:59], v5 offset0:214 offset1:222
	ds_read2_b32 v[60:61], v5 offset0:247 offset1:255
	v_lshlrev_b32_e32 v6, 12, v39
	v_lshl_add_u64 v[44:45], v[62:63], 0, v[6:7]
	v_lshlrev_b32_e32 v6, 12, v38
	global_store_dwordx4 v[44:45], v[40:43], off sc0 sc1
	v_lshl_add_u64 v[38:39], v[62:63], 0, v[6:7]
	v_lshlrev_b32_e32 v6, 12, v37
	s_waitcnt lgkmcnt(6)
	v_cvt_pk_bf16_f32 v40, v48, v46
	s_waitcnt lgkmcnt(4)
	v_cvt_pk_bf16_f32 v41, v50, v52
	s_waitcnt lgkmcnt(2)
	v_cvt_pk_bf16_f32 v42, v54, v56
	s_waitcnt lgkmcnt(0)
	v_cvt_pk_bf16_f32 v43, v58, v60
	global_store_dwordx4 v[38:39], v[40:43], off sc0 sc1
	v_cvt_pk_bf16_f32 v38, v49, v47
	v_cvt_pk_bf16_f32 v39, v51, v53
	v_cvt_pk_bf16_f32 v40, v55, v57
	v_cvt_pk_bf16_f32 v41, v59, v61
	v_lshl_add_u64 v[42:43], v[62:63], 0, v[6:7]
	global_store_dwordx4 v[42:43], v[38:41], off sc0 sc1
	s_waitcnt lgkmcnt(0)

; #define LAS __attribute__((address_space(3)))
; __device__ __forceinline__ f32x4 ld_nt(const float* p) { return __builtin_nontemporal_load((const f32x4*)p); }
; __device__ __forceinline__ void transpose_item(const float* W, int K, int pitch, int ncols, f16* WT, LAS float* scr, int item, int lane) {
;     const int nblk = ncols / 32, kb = item / nblk, nb = item % nblk, k0 = 64 * kb, n0 = 32 * nb;
;     const int kr = lane >> 3, nq = (lane & 7) * 4;
;     f32x4 v[8];
; #pragma unroll
;     for (int i = 0; i < 8; ++i) v[i] = ld_nt(W + (size_t)(k0 + kr + 8 * i) * pitch + n0 + nq);
;     __builtin_amdgcn_sched_barrier(0);
; #pragma unroll
;     for (int i = 0; i < 8; ++i) { LAS float* sp = scr + (kr + 8 * i) * 33 + nq; sp[0] = v[i][0]; sp[1] = v[i][1]; sp[2] = v[i][2]; sp[3] = v[i][3]; }
;     asm volatile("s_waitcnt lgkmcnt(0)" ::: "memory");
;     const int c = lane & 7;
; #pragma unroll
;     for (int j = 0; j < 4; ++j) { const int n = (lane >> 3) + 8 * j; const LAS float* sp = scr + (8 * c) * 33 + n;
;         u32x4 o; o.x = pk_f16(sp[0 * 33], sp[1 * 33]); o.y = pk_f16(sp[2 * 33], sp[3 * 33]); o.z = pk_f16(sp[4 * 33], sp[5 * 33]); o.w = pk_f16(sp[6 * 33], sp[7 * 33]);
;         *(u32x4*)(WT + (size_t)(n0 + n) * K + k0 + 8 * c) = o; }
;     asm volatile("s_waitcnt lgkmcnt(0)" ::: "memory");
; }
.LBB0_50:
	s_andn2_b64 vcc, exec, s[14:15]
	s_cbranch_vccnz .LBB0_43
	s_add_i32 s12, s19, 0xfd80
	s_and_b32 s14, s12, 0xffff
	s_mul_i32 s14, s14, 0xaaab
	s_lshr_b32 s15, s14, 16
	s_lshr_b32 s14, s14, 22
	s_mulk_i32 s14, 0x60
	s_sub_i32 s12, s12, s14
	s_lshl_b32 s12, s12, 5
	s_and_b32 s14, s15, 0xffc0
	s_and_b32 s15, s12, 0xffe0
	v_or_b32_e32 v6, s14, v20
	s_lshl_b32 s12, s15, 2
	v_lshl_add_u64 v[38:39], v[16:17], 0, s[12:13]
	v_lshlrev_b32_e32 v6, 14, v6
	v_lshl_add_u64 v[62:63], v[38:39], 0, v[6:7]
	v_add_co_u32_e32 v42, vcc, s21, v62
	s_nop 1
	v_addc_co_u32_e32 v43, vcc, 0, v63, vcc
	v_add_co_u32_e32 v46, vcc, s22, v62
	global_load_dwordx4 v[38:41], v[62:63], off nt
	s_nop 0
	global_load_dwordx4 v[42:45], v[42:43], off nt
	v_addc_co_u32_e32 v47, vcc, 0, v63, vcc
	v_add_co_u32_e32 v50, vcc, s23, v62
	s_nop 1
	v_addc_co_u32_e32 v51, vcc, 0, v63, vcc
	v_add_co_u32_e32 v54, vcc, s24, v62
	global_load_dwordx4 v[46:49], v[46:47], off nt
	s_nop 0
	global_load_dwordx4 v[50:53], v[50:51], off nt
	v_addc_co_u32_e32 v55, vcc, 0, v63, vcc
	v_add_co_u32_e32 v58, vcc, s25, v62
	s_nop 1
	v_addc_co_u32_e32 v59, vcc, 0, v63, vcc
	v_add_co_u32_e32 v64, vcc, s26, v62
	global_load_dwordx4 v[54:57], v[54:55], off nt
	s_nop 0
	global_load_dwordx4 v[58:61], v[58:59], off nt
	v_addc_co_u32_e32 v65, vcc, 0, v63, vcc
	v_add_co_u32_e32 v66, vcc, s27, v62
	s_nop 1
	v_addc_co_u32_e32 v67, vcc, 0, v63, vcc
	global_load_dwordx4 v[62:65], v[64:65], off nt
	s_nop 0
	global_load_dwordx4 v[66:69], v[66:67], off nt
	s_waitcnt vmcnt(7)
	ds_write2_b32 v22, v38, v39 offset1:1
	ds_write2_b32 v22, v40, v41 offset0:2 offset1:3
	s_waitcnt vmcnt(6)
	ds_write2_b32 v23, v42, v43 offset1:1
	ds_write2_b32 v24, v44, v45 offset1:1
	s_waitcnt vmcnt(5)
	ds_write2_b32 v25, v46, v47 offset1:1
	ds_write2_b32 v26, v48, v49 offset1:1
	s_waitcnt vmcnt(4)
	ds_write2_b32 v27, v50, v51 offset1:1
	ds_write2_b32 v28, v52, v53 offset1:1
	s_waitcnt vmcnt(3)
	ds_write2_b32 v29, v54, v55 offset1:1
	ds_write2_b32 v30, v56, v57 offset1:1
	s_waitcnt vmcnt(2)
	ds_write2_b32 v31, v58, v59 offset1:1
	ds_write2_b32 v32, v60, v61 offset1:1
	s_waitcnt vmcnt(1)
	ds_write2_b32 v33, v62, v63 offset1:1
	ds_write2_b32 v34, v64, v65 offset1:1
	s_waitcnt vmcnt(0)
	ds_write2_b32 v35, v66, v67 offset1:1
	ds_write2_b32 v36, v68, v69 offset1:1
	s_waitcnt lgkmcnt(0)
	ds_read2_b32 v[42:43], v5 offset0:33 offset1:41
	ds_read2_b32 v[44:45], v5 offset1:8
	ds_read2_b32 v[46:47], v5 offset0:66 offset1:74
	ds_read2_b32 v[48:49], v5 offset0:99 offset1:107
	ds_read2_b32 v[50:51], v5 offset0:132 offset1:140
	ds_read2_b32 v[52:53], v5 offset0:165 offset1:173
	ds_read2_b32 v[54:55], v5 offset0:198 offset1:206
	ds_read2_b32 v[56:57], v5 offset0:231 offset1:239
	s_lshl_b32 s12, s14, 1
	v_or_b32_e32 v6, s15, v20
	v_lshl_add_u64 v[58:59], v[18:19], 0, s[12:13]
	v_lshlrev_b32_e32 v6, 12, v6
	s_waitcnt lgkmcnt(6)
	v_cvt_pk_bf16_f32 v38, v44, v42
	s_waitcnt lgkmcnt(4)
	v_cvt_pk_bf16_f32 v39, v46, v48
	s_waitcnt lgkmcnt(2)
	v_cvt_pk_bf16_f32 v40, v50, v52
	s_waitcnt lgkmcnt(0)
	v_cvt_pk_bf16_f32 v41, v54, v56
	v_lshl_add_u64 v[60:61], v[58:59], 0, v[6:7]
	global_store_dwordx4 v[60:61], v[38:41], off sc0 sc1
	v_or_b32_e32 v6, s15, v21
	v_lshlrev_b32_e32 v6, 12, v6
	v_cvt_pk_bf16_f32 v38, v45, v43
	v_cvt_pk_bf16_f32 v39, v47, v49
	v_cvt_pk_bf16_f32 v40, v51, v53
	v_cvt_pk_bf16_f32 v41, v55, v57
	ds_read2_b32 v[44:45], v5 offset0:49 offset1:57
	ds_read2_b32 v[46:47], v5 offset0:16 offset1:24
	ds_read2_b32 v[48:49], v5 offset0:82 offset1:90
	ds_read2_b32 v[50:51], v5 offset0:115 offset1:123
	ds_read2_b32 v[52:53], v5 offset0:148 offset1:156
	ds_read2_b32 v[54:55], v5 offset0:181 offset1:189
	ds_read2_b32 v[56:57], v5 offset0:214 offset1:222
	ds_read2_b32 v[60:61], v5 offset0:247 offset1:255
	v_lshl_add_u64 v[42:43], v[58:59], 0, v[6:7]
	v_or_b32_e32 v6, s15, v3
	v_lshlrev_b32_e32 v6, 12, v6
	global_store_dwordx4 v[42:43], v[38:41], off sc0 sc1
	v_lshl_add_u64 v[42:43], v[58:59], 0, v[6:7]
	v_or_b32_e32 v6, s15, v1
	s_waitcnt lgkmcnt(6)
	v_cvt_pk_bf16_f32 v38, v46, v44
	s_waitcnt lgkmcnt(4)
	v_cvt_pk_bf16_f32 v39, v48, v50
	s_waitcnt lgkmcnt(2)
	v_cvt_pk_bf16_f32 v40, v52, v54
	s_waitcnt lgkmcnt(0)
	v_cvt_pk_bf16_f32 v41, v56, v60
	v_lshlrev_b32_e32 v6, 12, v6
	global_store_dwordx4 v[42:43], v[38:41], off sc0 sc1
	v_lshl_add_u64 v[42:43], v[58:59], 0, v[6:7]
	s_nop 0
	v_cvt_pk_bf16_f32 v38, v47, v45
	v_cvt_pk_bf16_f32 v39, v49, v51
	v_cvt_pk_bf16_f32 v40, v53, v55
	v_cvt_pk_bf16_f32 v41, v57, v61
	global_store_dwordx4 v[42:43], v[38:41], off sc0 sc1
	s_waitcnt lgkmcnt(0)
	s_branch .LBB0_43
; #define LAS __attribute__((address_space(3)))
; __device__ __forceinline__ f32x4 ld_nt(const float* p) { return __builtin_nontemporal_load((const f32x4*)p); }
; __device__ __forceinline__ void transpose_item(const float* W, int K, int pitch, int ncols, f16* WT, LAS float* scr, int item, int lane) {
;     const int nblk = ncols / 32, kb = item / nblk, nb = item % nblk, k0 = 64 * kb, n0 = 32 * nb;
;     const int kr = lane >> 3, nq = (lane & 7) * 4;
;     f32x4 v[8];
; #pragma unroll
;     for (int i = 0; i < 8; ++i) v[i] = ld_nt(W + (size_t)(k0 + kr + 8 * i) * pitch + n0 + nq);
;     __builtin_amdgcn_sched_barrier(0);
; #pragma unroll
;     for (int i = 0; i < 8; ++i) { LAS float* sp = scr + (kr + 8 * i) * 33 + nq; sp[0] = v[i][0]; sp[1] = v[i][1]; sp[2] = v[i][2]; sp[3] = v[i][3]; }
;     asm volatile("s_waitcnt lgkmcnt(0)" ::: "memory");
;     const int c = lane & 7;
; #pragma unroll
;     for (int j = 0; j < 4; ++j) { const int n = (lane >> 3) + 8 * j; const LAS float* sp = scr + (8 * c) * 33 + n;
;         u32x4 o; o.x = pk_f16(sp[0 * 33], sp[1 * 33]); o.y = pk_f16(sp[2 * 33], sp[3 * 33]); o.z = pk_f16(sp[4 * 33], sp[5 * 33]); o.w = pk_f16(sp[6 * 33], sp[7 * 33]);
;         *(u32x4*)(WT + (size_t)(n0 + n) * K + k0 + 8 * c) = o; }
;     asm volatile("s_waitcnt lgkmcnt(0)" ::: "memory");
; }
.LBB0_52:
	s_cmpk_gt_i32 s16, 0xcf
	s_cbranch_scc0 .LBB0_69
	s_addk_i32 s0, 0x200
	s_cmpk_gt_i32 s0, 0x7f
	s_mov_b64 s[12:13], -1
	s_cbranch_scc0 .LBB0_67
	s_cmpk_gt_u32 s0, 0x27f
	s_cbranch_scc0 .LBB0_64
	s_cmpk_gt_u32 s0, 0xe7f
	s_cbranch_scc0 .LBB0_61
	s_lshl_b32 s1, s0, 5
	s_and_b32 s1, s1, 0x7e0
	s_cmpk_gt_u32 s0, 0x167f
	s_mov_b32 s13, 0
	s_mov_b64 s[14:15], -1
	v_or_b32_e32 v9, s1, v20
	v_or_b32_e32 v8, s1, v21
	v_or_b32_e32 v7, s1, v3
	v_or_b32_e32 v6, s1, v1
	s_cbranch_scc0 .LBB0_58
	s_and_b32 s12, s0, 0x7fffffc0
	s_addk_i32 s12, 0xe980
	s_lshl_b32 s14, s1, 2
	s_add_u32 s14, s40, s14
	v_or_b32_e32 v18, s12, v20
	s_addc_u32 s15, s41, 0
	v_lshlrev_b32_e32 v48, 2, v4
	v_mov_b32_e32 v49, 0
	v_lshl_add_u64 v[40:41], s[14:15], 0, v[48:49]
	v_or_b32_e32 v48, 8, v18
	v_lshlrev_b64 v[12:13], 13, v[48:49]
	v_or_b32_e32 v48, 16, v18
	v_lshlrev_b64 v[24:25], 13, v[48:49]
	v_or_b32_e32 v48, 24, v18
	v_lshlrev_b64 v[26:27], 13, v[48:49]
	v_or_b32_e32 v48, 32, v18
	v_lshlrev_b64 v[32:33], 13, v[48:49]
	v_or_b32_e32 v48, 40, v18
	v_mov_b32_e32 v19, v49
	v_lshlrev_b64 v[34:35], 13, v[48:49]
	v_or_b32_e32 v48, 48, v18
	v_lshlrev_b64 v[10:11], 13, v[18:19]
	v_lshlrev_b64 v[42:43], 13, v[48:49]
	v_or_b32_e32 v48, 56, v18
	v_lshl_add_u64 v[10:11], v[40:41], 0, v[10:11]
	v_lshl_add_u64 v[14:15], v[40:41], 0, v[12:13]
	v_lshl_add_u64 v[24:25], v[40:41], 0, v[24:25]
	v_lshl_add_u64 v[28:29], v[40:41], 0, v[26:27]
	v_lshl_add_u64 v[32:33], v[40:41], 0, v[32:33]
	v_lshl_add_u64 v[36:37], v[40:41], 0, v[34:35]
	v_lshl_add_u64 v[42:43], v[40:41], 0, v[42:43]
	v_lshlrev_b64 v[18:19], 13, v[48:49]
	global_load_dwordx4 v[10:13], v[10:11], off nt
	s_nop 0
	global_load_dwordx4 v[14:17], v[14:15], off nt
	s_nop 0
	global_load_dwordx4 v[24:27], v[24:25], off nt
	s_nop 0
	global_load_dwordx4 v[28:31], v[28:29], off nt
	s_nop 0
	global_load_dwordx4 v[32:35], v[32:33], off nt
	s_nop 0
	global_load_dwordx4 v[36:39], v[36:37], off nt
	v_lshl_add_u64 v[18:19], v[40:41], 0, v[18:19]
	global_load_dwordx4 v[40:43], v[42:43], off nt
	s_nop 0
	global_load_dwordx4 v[44:47], v[18:19], off nt
	s_waitcnt vmcnt(7)
	ds_write2_b32 v22, v10, v11 offset1:1
	ds_write2_b32 v22, v12, v13 offset0:2 offset1:3
	v_add_u32_e32 v10, 0x420, v22
	s_waitcnt vmcnt(6)
	ds_write2_b32 v10, v14, v15 offset1:1
	v_add_u32_e32 v10, 0x428, v22
	ds_write2_b32 v10, v16, v17 offset1:1
	v_add_u32_e32 v10, 0x840, v22
	s_waitcnt vmcnt(5)
	ds_write2_b32 v10, v24, v25 offset1:1
	v_add_u32_e32 v10, 0x848, v22
	ds_write2_b32 v10, v26, v27 offset1:1
	v_add_u32_e32 v10, 0xc60, v22
	s_waitcnt vmcnt(4)
	ds_write2_b32 v10, v28, v29 offset1:1
	v_add_u32_e32 v10, 0xc68, v22
	ds_write2_b32 v10, v30, v31 offset1:1
	v_add_u32_e32 v10, 0x1080, v22
	s_waitcnt vmcnt(3)
	ds_write2_b32 v10, v32, v33 offset1:1
	v_add_u32_e32 v10, 0x1088, v22
	ds_write2_b32 v10, v34, v35 offset1:1
	v_add_u32_e32 v10, 0x14a0, v22
	s_waitcnt vmcnt(2)
	ds_write2_b32 v10, v36, v37 offset1:1
	v_add_u32_e32 v10, 0x14a8, v22
	ds_write2_b32 v10, v38, v39 offset1:1
	v_add_u32_e32 v10, 0x18c0, v22
	s_waitcnt vmcnt(1)
	ds_write2_b32 v10, v40, v41 offset1:1
	v_add_u32_e32 v10, 0x18c8, v22
	ds_write2_b32 v10, v42, v43 offset1:1
	v_add_u32_e32 v10, 0x1ce0, v22
	s_waitcnt vmcnt(0)
	ds_write2_b32 v10, v44, v45 offset1:1
	v_add_u32_e32 v10, 0x1ce8, v22
	ds_write2_b32 v10, v46, v47 offset1:1
	s_waitcnt lgkmcnt(0)
	ds_read2_b32 v[14:15], v5 offset0:33 offset1:41
	ds_read2_b32 v[16:17], v5 offset1:8
	ds_read2_b32 v[18:19], v5 offset0:66 offset1:74
	ds_read2_b32 v[24:25], v5 offset0:99 offset1:107
	ds_read2_b32 v[26:27], v5 offset0:132 offset1:140
	ds_read2_b32 v[28:29], v5 offset0:165 offset1:173
	ds_read2_b32 v[30:31], v5 offset0:198 offset1:206
	ds_read2_b32 v[32:33], v5 offset0:231 offset1:239
	s_lshl_b64 s[12:13], s[12:13], 1
	s_add_u32 s10, s10, s12
	s_addc_u32 s11, s11, s13
	v_lshlrev_b32_e32 v48, 1, v2
	v_lshl_add_u64 v[34:35], s[10:11], 0, v[48:49]
	v_lshlrev_b32_e32 v48, 11, v9
	s_waitcnt lgkmcnt(6)
	v_cvt_pk_bf16_f32 v10, v16, v14
	s_waitcnt lgkmcnt(4)
	v_cvt_pk_bf16_f32 v11, v18, v24
	s_waitcnt lgkmcnt(2)
	v_cvt_pk_bf16_f32 v12, v26, v28
	s_waitcnt lgkmcnt(0)
	v_cvt_pk_bf16_f32 v13, v30, v32
	v_lshl_add_u64 v[36:37], v[34:35], 0, v[48:49]
	global_store_dwordx4 v[36:37], v[10:13], off sc0 sc1
	v_lshlrev_b32_e32 v48, 11, v8
	s_mov_b64 s[14:15], 0
	v_cvt_pk_bf16_f32 v10, v17, v15
	v_cvt_pk_bf16_f32 v11, v19, v25
	v_cvt_pk_bf16_f32 v12, v27, v29
	v_cvt_pk_bf16_f32 v13, v31, v33
	ds_read2_b32 v[16:17], v5 offset0:49 offset1:57
	ds_read2_b32 v[18:19], v5 offset0:16 offset1:24
	ds_read2_b32 v[24:25], v5 offset0:82 offset1:90
	ds_read2_b32 v[26:27], v5 offset0:115 offset1:123
	ds_read2_b32 v[28:29], v5 offset0:148 offset1:156
	ds_read2_b32 v[30:31], v5 offset0:181 offset1:189
	ds_read2_b32 v[32:33], v5 offset0:214 offset1:222
	ds_read2_b32 v[36:37], v5 offset0:247 offset1:255
	v_lshl_add_u64 v[14:15], v[34:35], 0, v[48:49]
	v_lshlrev_b32_e32 v48, 11, v7
	global_store_dwordx4 v[14:15], v[10:13], off sc0 sc1
	v_lshl_add_u64 v[14:15], v[34:35], 0, v[48:49]
	v_lshlrev_b32_e32 v48, 11, v6
	s_waitcnt lgkmcnt(6)
	v_cvt_pk_bf16_f32 v10, v18, v16
	s_waitcnt lgkmcnt(4)
	v_cvt_pk_bf16_f32 v11, v24, v26
	s_waitcnt lgkmcnt(2)
	v_cvt_pk_bf16_f32 v12, v28, v30
	s_waitcnt lgkmcnt(0)
	v_cvt_pk_bf16_f32 v13, v32, v36
	global_store_dwordx4 v[14:15], v[10:13], off sc0 sc1
	v_lshl_add_u64 v[14:15], v[34:35], 0, v[48:49]
	s_nop 0
	v_cvt_pk_bf16_f32 v10, v19, v17
	v_cvt_pk_bf16_f32 v11, v25, v27
	v_cvt_pk_bf16_f32 v12, v29, v31
	v_cvt_pk_bf16_f32 v13, v33, v37
	global_store_dwordx4 v[14:15], v[10:13], off sc0 sc1
	s_waitcnt lgkmcnt(0)
; #define LAS __attribute__((address_space(3)))
; __device__ __forceinline__ f32x4 ld_nt(const float* p) { return __builtin_nontemporal_load((const f32x4*)p); }
; __device__ __forceinline__ void transpose_item(const float* W, int K, int pitch, int ncols, f16* WT, LAS float* scr, int item, int lane) {
;     const int nblk = ncols / 32, kb = item / nblk, nb = item % nblk, k0 = 64 * kb, n0 = 32 * nb;
;     const int kr = lane >> 3, nq = (lane & 7) * 4;
;     f32x4 v[8];
; #pragma unroll
;     for (int i = 0; i < 8; ++i) v[i] = ld_nt(W + (size_t)(k0 + kr + 8 * i) * pitch + n0 + nq);
;     __builtin_amdgcn_sched_barrier(0);
; #pragma unroll
;     for (int i = 0; i < 8; ++i) { LAS float* sp = scr + (kr + 8 * i) * 33 + nq; sp[0] = v[i][0]; sp[1] = v[i][1]; sp[2] = v[i][2]; sp[3] = v[i][3]; }
;     asm volatile("s_waitcnt lgkmcnt(0)" ::: "memory");
;     const int c = lane & 7;
; #pragma unroll
;     for (int j = 0; j < 4; ++j) { const int n = (lane >> 3) + 8 * j; const LAS float* sp = scr + (8 * c) * 33 + n;
;         u32x4 o; o.x = pk_f16(sp[0 * 33], sp[1 * 33]); o.y = pk_f16(sp[2 * 33], sp[3 * 33]); o.z = pk_f16(sp[4 * 33], sp[5 * 33]); o.w = pk_f16(sp[6 * 33], sp[7 * 33]);
;         *(u32x4*)(WT + (size_t)(n0 + n) * K + k0 + 8 * c) = o; }
;     asm volatile("s_waitcnt lgkmcnt(0)" ::: "memory");
; }
.LBB0_58:
	s_andn2_b64 vcc, exec, s[14:15]
	s_cbranch_vccnz .LBB0_60
	s_add_i32 s10, s0, 0xf180
	s_and_b32 s12, s10, 0xffc0
	s_lshl_b32 s1, s1, 2
	s_add_u32 s10, s44, s1
	v_or_b32_e32 v12, s12, v20
	s_addc_u32 s11, s45, 0
	v_lshlrev_b32_e32 v18, 2, v4
	v_mov_b32_e32 v19, 0
	v_lshl_add_u64 v[10:11], s[10:11], 0, v[18:19]
	v_lshlrev_b32_e32 v18, 13, v12
	v_lshl_add_u64 v[40:41], v[10:11], 0, v[18:19]
	v_add_co_u32_e32 v14, vcc, 0x10000, v40
	s_nop 1
	v_addc_co_u32_e32 v15, vcc, 0, v41, vcc
	v_add_co_u32_e32 v24, vcc, 0x20000, v40
	global_load_dwordx4 v[10:13], v[40:41], off nt
	s_nop 0
	global_load_dwordx4 v[14:17], v[14:15], off nt
	v_addc_co_u32_e32 v25, vcc, 0, v41, vcc
	v_add_co_u32_e32 v28, vcc, 0x30000, v40
	s_nop 1
	v_addc_co_u32_e32 v29, vcc, 0, v41, vcc
	v_add_co_u32_e32 v32, vcc, 0x40000, v40
	global_load_dwordx4 v[24:27], v[24:25], off nt
	s_nop 0
	global_load_dwordx4 v[28:31], v[28:29], off nt
	v_addc_co_u32_e32 v33, vcc, 0, v41, vcc
	v_add_co_u32_e32 v36, vcc, 0x50000, v40
	s_nop 1
	v_addc_co_u32_e32 v37, vcc, 0, v41, vcc
	v_add_co_u32_e32 v42, vcc, 0x60000, v40
	global_load_dwordx4 v[32:35], v[32:33], off nt
	s_nop 0
	global_load_dwordx4 v[36:39], v[36:37], off nt
	v_addc_co_u32_e32 v43, vcc, 0, v41, vcc
	v_add_co_u32_e32 v44, vcc, 0x70000, v40
	s_nop 1
	v_addc_co_u32_e32 v45, vcc, 0, v41, vcc
	global_load_dwordx4 v[40:43], v[42:43], off nt
	s_nop 0
	global_load_dwordx4 v[44:47], v[44:45], off nt
	s_waitcnt vmcnt(7)
	ds_write2_b32 v22, v10, v11 offset1:1
	ds_write2_b32 v22, v12, v13 offset0:2 offset1:3
	v_add_u32_e32 v10, 0x420, v22
	s_waitcnt vmcnt(6)
	ds_write2_b32 v10, v14, v15 offset1:1
	v_add_u32_e32 v10, 0x428, v22
	ds_write2_b32 v10, v16, v17 offset1:1
	v_add_u32_e32 v10, 0x840, v22
	s_waitcnt vmcnt(5)
	ds_write2_b32 v10, v24, v25 offset1:1
	v_add_u32_e32 v10, 0x848, v22
	ds_write2_b32 v10, v26, v27 offset1:1
	v_add_u32_e32 v10, 0xc60, v22
	s_waitcnt vmcnt(4)
	ds_write2_b32 v10, v28, v29 offset1:1
	v_add_u32_e32 v10, 0xc68, v22
	ds_write2_b32 v10, v30, v31 offset1:1
	v_add_u32_e32 v10, 0x1080, v22
	s_waitcnt vmcnt(3)
	ds_write2_b32 v10, v32, v33 offset1:1
	v_add_u32_e32 v10, 0x1088, v22
	ds_write2_b32 v10, v34, v35 offset1:1
	v_add_u32_e32 v10, 0x14a0, v22
	s_waitcnt vmcnt(2)
	ds_write2_b32 v10, v36, v37 offset1:1
	v_add_u32_e32 v10, 0x14a8, v22
	ds_write2_b32 v10, v38, v39 offset1:1
	v_add_u32_e32 v10, 0x18c0, v22
	s_waitcnt vmcnt(1)
	ds_write2_b32 v10, v40, v41 offset1:1
	v_add_u32_e32 v10, 0x18c8, v22
	ds_write2_b32 v10, v42, v43 offset1:1
	v_add_u32_e32 v10, 0x1ce0, v22
	s_waitcnt vmcnt(0)
	ds_write2_b32 v10, v44, v45 offset1:1
	v_add_u32_e32 v10, 0x1ce8, v22
	ds_write2_b32 v10, v46, v47 offset1:1
	s_waitcnt lgkmcnt(0)
	ds_read2_b32 v[14:15], v5 offset0:33 offset1:41
	ds_read2_b32 v[16:17], v5 offset1:8
	ds_read2_b32 v[24:25], v5 offset0:66 offset1:74
	ds_read2_b32 v[26:27], v5 offset0:99 offset1:107
	ds_read2_b32 v[28:29], v5 offset0:132 offset1:140
	ds_read2_b32 v[30:31], v5 offset0:165 offset1:173
	ds_read2_b32 v[32:33], v5 offset0:198 offset1:206
	ds_read2_b32 v[34:35], v5 offset0:231 offset1:239
	s_lshl_b32 s1, s12, 1
	s_add_u32 s8, s8, s1
	s_addc_u32 s9, s9, 0
	v_lshlrev_b32_e32 v18, 1, v2
	v_lshl_add_u64 v[36:37], s[8:9], 0, v[18:19]
	v_lshlrev_b32_e32 v18, 12, v9
	s_waitcnt lgkmcnt(6)
	v_cvt_pk_bf16_f32 v10, v16, v14
	s_waitcnt lgkmcnt(4)
	v_cvt_pk_bf16_f32 v11, v24, v26
	s_waitcnt lgkmcnt(2)
	v_cvt_pk_bf16_f32 v12, v28, v30
	s_waitcnt lgkmcnt(0)
	v_cvt_pk_bf16_f32 v13, v32, v34
	v_lshl_add_u64 v[38:39], v[36:37], 0, v[18:19]
	global_store_dwordx4 v[38:39], v[10:13], off sc0 sc1
	v_lshlrev_b32_e32 v18, 12, v8
	v_lshl_add_u64 v[8:9], v[36:37], 0, v[18:19]
	v_cvt_pk_bf16_f32 v10, v17, v15
	v_cvt_pk_bf16_f32 v11, v25, v27
	v_cvt_pk_bf16_f32 v12, v29, v31
	v_cvt_pk_bf16_f32 v13, v33, v35
	ds_read2_b32 v[14:15], v5 offset0:49 offset1:57
	ds_read2_b32 v[16:17], v5 offset0:16 offset1:24
	ds_read2_b32 v[24:25], v5 offset0:82 offset1:90
	ds_read2_b32 v[26:27], v5 offset0:115 offset1:123
	ds_read2_b32 v[28:29], v5 offset0:148 offset1:156
	ds_read2_b32 v[30:31], v5 offset0:181 offset1:189
	ds_read2_b32 v[32:33], v5 offset0:214 offset1:222
	ds_read2_b32 v[34:35], v5 offset0:247 offset1:255
	v_lshlrev_b32_e32 v18, 12, v7
	global_store_dwordx4 v[8:9], v[10:13], off sc0 sc1
	s_waitcnt lgkmcnt(6)
	v_cvt_pk_bf16_f32 v8, v16, v14
	s_waitcnt lgkmcnt(4)
	v_cvt_pk_bf16_f32 v9, v24, v26
	s_waitcnt lgkmcnt(2)
	v_cvt_pk_bf16_f32 v10, v28, v30
	s_waitcnt lgkmcnt(0)
	v_cvt_pk_bf16_f32 v11, v32, v34
	v_lshl_add_u64 v[12:13], v[36:37], 0, v[18:19]
	v_lshlrev_b32_e32 v18, 12, v6
	global_store_dwordx4 v[12:13], v[8:11], off sc0 sc1
	v_lshl_add_u64 v[6:7], v[36:37], 0, v[18:19]
	s_nop 0
	v_cvt_pk_bf16_f32 v8, v17, v15
	v_cvt_pk_bf16_f32 v9, v25, v27
	v_cvt_pk_bf16_f32 v10, v29, v31
	v_cvt_pk_bf16_f32 v11, v33, v35
	global_store_dwordx4 v[6:7], v[8:11], off sc0 sc1
	s_waitcnt lgkmcnt(0)

; #define LAS __attribute__((address_space(3)))
; __device__ __forceinline__ f32x4 ld_nt(const float* p) { return __builtin_nontemporal_load((const f32x4*)p); }
; __device__ __forceinline__ void transpose_item(const float* W, int K, int pitch, int ncols, f16* WT, LAS float* scr, int item, int lane) {
;     const int nblk = ncols / 32, kb = item / nblk, nb = item % nblk, k0 = 64 * kb, n0 = 32 * nb;
;     const int kr = lane >> 3, nq = (lane & 7) * 4;
;     f32x4 v[8];
; #pragma unroll
;     for (int i = 0; i < 8; ++i) v[i] = ld_nt(W + (size_t)(k0 + kr + 8 * i) * pitch + n0 + nq);
;     __builtin_amdgcn_sched_barrier(0);
; #pragma unroll
;     for (int i = 0; i < 8; ++i) { LAS float* sp = scr + (kr + 8 * i) * 33 + nq; sp[0] = v[i][0]; sp[1] = v[i][1]; sp[2] = v[i][2]; sp[3] = v[i][3]; }
;     asm volatile("s_waitcnt lgkmcnt(0)" ::: "memory");
;     const int c = lane & 7;
; #pragma unroll
;     for (int j = 0; j < 4; ++j) { const int n = (lane >> 3) + 8 * j; const LAS float* sp = scr + (8 * c) * 33 + n;
;         u32x4 o; o.x = pk_f16(sp[0 * 33], sp[1 * 33]); o.y = pk_f16(sp[2 * 33], sp[3 * 33]); o.z = pk_f16(sp[4 * 33], sp[5 * 33]); o.w = pk_f16(sp[6 * 33], sp[7 * 33]);
;         *(u32x4*)(WT + (size_t)(n0 + n) * K + k0 + 8 * c) = o; }
;     asm volatile("s_waitcnt lgkmcnt(0)" ::: "memory");
; }
.LBB0_61:
	s_andn2_b64 vcc, exec, s[12:13]
	s_cbranch_vccnz .LBB0_63
	s_add_i32 s1, s0, 0xfd80
	s_and_b32 s8, s1, 0xffff
	s_mul_i32 s8, s8, 0xaaab
	s_lshr_b32 s9, s8, 16
	s_lshr_b32 s8, s8, 22
	s_mulk_i32 s8, 0x60
	s_sub_i32 s1, s1, s8
	s_lshl_b32 s1, s1, 5
	s_and_b32 s1, s1, 0xffe0
	s_and_b32 s8, s9, 0xffc0
	s_lshl_b32 s9, s1, 2
	s_add_u32 s6, s6, s9
	v_or_b32_e32 v8, s8, v20
	s_addc_u32 s7, s7, 0
	v_lshlrev_b32_e32 v18, 2, v4
	v_mov_b32_e32 v19, 0
	v_lshl_add_u64 v[6:7], s[6:7], 0, v[18:19]
	v_lshlrev_b32_e32 v18, 14, v8
	v_lshl_add_u64 v[36:37], v[6:7], 0, v[18:19]
	s_mov_b32 s6, 0x20000
	v_add_co_u32_e32 v10, vcc, s6, v36
	s_mov_b32 s6, 0x40000
	s_nop 0
	v_addc_co_u32_e32 v11, vcc, 0, v37, vcc
	v_add_co_u32_e32 v14, vcc, s6, v36
	s_mov_b32 s6, 0x60000
	s_nop 0
	v_addc_co_u32_e32 v15, vcc, 0, v37, vcc
	v_add_co_u32_e32 v24, vcc, s6, v36
	s_mov_b32 s6, 0x80000
	s_nop 0
	v_addc_co_u32_e32 v25, vcc, 0, v37, vcc
	v_add_co_u32_e32 v28, vcc, s6, v36
	s_mov_b32 s6, 0xa0000
	s_nop 0
	v_addc_co_u32_e32 v29, vcc, 0, v37, vcc
	v_add_co_u32_e32 v32, vcc, s6, v36
	s_mov_b32 s6, 0xc0000
	s_nop 0
	v_addc_co_u32_e32 v33, vcc, 0, v37, vcc
	v_add_co_u32_e32 v38, vcc, s6, v36
	s_mov_b32 s6, 0xe0000
	s_nop 0
	v_addc_co_u32_e32 v39, vcc, 0, v37, vcc
	v_add_co_u32_e32 v40, vcc, s6, v36
	global_load_dwordx4 v[6:9], v[36:37], off nt
	s_nop 0
	global_load_dwordx4 v[10:13], v[10:11], off nt
	v_addc_co_u32_e32 v41, vcc, 0, v37, vcc
	global_load_dwordx4 v[14:17], v[14:15], off nt
	s_nop 0
	global_load_dwordx4 v[24:27], v[24:25], off nt
	s_nop 0
	global_load_dwordx4 v[28:31], v[28:29], off nt
	s_nop 0
	global_load_dwordx4 v[32:35], v[32:33], off nt
	s_nop 0
	global_load_dwordx4 v[36:39], v[38:39], off nt
	s_nop 0
	global_load_dwordx4 v[40:43], v[40:41], off nt
	s_waitcnt vmcnt(7)
	ds_write2_b32 v22, v6, v7 offset1:1
	ds_write2_b32 v22, v8, v9 offset0:2 offset1:3
	v_add_u32_e32 v6, 0x420, v22
	s_waitcnt vmcnt(6)
	ds_write2_b32 v6, v10, v11 offset1:1
	v_add_u32_e32 v6, 0x428, v22
	ds_write2_b32 v6, v12, v13 offset1:1
	v_add_u32_e32 v6, 0x840, v22
	s_waitcnt vmcnt(5)
	ds_write2_b32 v6, v14, v15 offset1:1
	v_add_u32_e32 v6, 0x848, v22
	ds_write2_b32 v6, v16, v17 offset1:1
	v_add_u32_e32 v6, 0xc60, v22
	s_waitcnt vmcnt(4)
	ds_write2_b32 v6, v24, v25 offset1:1
	v_add_u32_e32 v6, 0xc68, v22
	ds_write2_b32 v6, v26, v27 offset1:1
	v_add_u32_e32 v6, 0x1080, v22
	s_waitcnt vmcnt(3)
	ds_write2_b32 v6, v28, v29 offset1:1
	v_add_u32_e32 v6, 0x1088, v22
	ds_write2_b32 v6, v30, v31 offset1:1
	v_add_u32_e32 v6, 0x14a0, v22
	s_waitcnt vmcnt(2)
	ds_write2_b32 v6, v32, v33 offset1:1
	v_add_u32_e32 v6, 0x14a8, v22
	ds_write2_b32 v6, v34, v35 offset1:1
	v_add_u32_e32 v6, 0x18c0, v22
	s_waitcnt vmcnt(1)
	ds_write2_b32 v6, v36, v37 offset1:1
	v_add_u32_e32 v6, 0x18c8, v22
	ds_write2_b32 v6, v38, v39 offset1:1
	v_add_u32_e32 v6, 0x1ce0, v22
	s_waitcnt vmcnt(0)
	ds_write2_b32 v6, v40, v41 offset1:1
	v_add_u32_e32 v6, 0x1ce8, v22
	ds_write2_b32 v6, v42, v43 offset1:1
	s_waitcnt lgkmcnt(0)
	ds_read2_b32 v[10:11], v5 offset0:33 offset1:41
	ds_read2_b32 v[12:13], v5 offset1:8
	ds_read2_b32 v[14:15], v5 offset0:66 offset1:74
	ds_read2_b32 v[16:17], v5 offset0:99 offset1:107
	ds_read2_b32 v[24:25], v5 offset0:132 offset1:140
	ds_read2_b32 v[26:27], v5 offset0:165 offset1:173
	ds_read2_b32 v[28:29], v5 offset0:198 offset1:206
	ds_read2_b32 v[30:31], v5 offset0:231 offset1:239
	s_lshl_b32 s6, s8, 1
	s_add_u32 s4, s4, s6
	s_addc_u32 s5, s5, 0
	v_lshlrev_b32_e32 v18, 1, v2
	s_waitcnt lgkmcnt(6)
	v_cvt_pk_bf16_f32 v6, v12, v10
	v_or_b32_e32 v10, s1, v20
	v_lshl_add_u64 v[32:33], s[4:5], 0, v[18:19]
	v_lshlrev_b32_e32 v18, 12, v10
	s_waitcnt lgkmcnt(4)
	v_cvt_pk_bf16_f32 v7, v14, v16
	s_waitcnt lgkmcnt(2)
	v_cvt_pk_bf16_f32 v8, v24, v26
	s_waitcnt lgkmcnt(0)
	v_cvt_pk_bf16_f32 v9, v28, v30
	v_lshl_add_u64 v[34:35], v[32:33], 0, v[18:19]
	global_store_dwordx4 v[34:35], v[6:9], off sc0 sc1
	v_or_b32_e32 v10, s1, v21
	v_lshlrev_b32_e32 v18, 12, v10
	v_cvt_pk_bf16_f32 v6, v13, v11
	v_cvt_pk_bf16_f32 v7, v15, v17
	v_cvt_pk_bf16_f32 v8, v25, v27
	v_cvt_pk_bf16_f32 v9, v29, v31
	ds_read2_b32 v[12:13], v5 offset0:49 offset1:57
	ds_read2_b32 v[14:15], v5 offset0:16 offset1:24
	ds_read2_b32 v[16:17], v5 offset0:82 offset1:90
	ds_read2_b32 v[24:25], v5 offset0:115 offset1:123
	ds_read2_b32 v[26:27], v5 offset0:148 offset1:156
	ds_read2_b32 v[28:29], v5 offset0:181 offset1:189
	ds_read2_b32 v[30:31], v5 offset0:214 offset1:222
	ds_read2_b32 v[34:35], v5 offset0:247 offset1:255
	v_lshl_add_u64 v[10:11], v[32:33], 0, v[18:19]
	global_store_dwordx4 v[10:11], v[6:9], off sc0 sc1
	v_or_b32_e32 v10, s1, v3
	v_lshlrev_b32_e32 v18, 12, v10
	s_waitcnt lgkmcnt(6)
	v_cvt_pk_bf16_f32 v6, v14, v12
	s_waitcnt lgkmcnt(4)
	v_cvt_pk_bf16_f32 v7, v16, v24
	s_waitcnt lgkmcnt(2)
	v_cvt_pk_bf16_f32 v8, v26, v28
	s_waitcnt lgkmcnt(0)
	v_cvt_pk_bf16_f32 v9, v30, v34
	v_lshl_add_u64 v[10:11], v[32:33], 0, v[18:19]
	global_store_dwordx4 v[10:11], v[6:9], off sc0 sc1
	v_or_b32_e32 v10, s1, v1
	v_lshlrev_b32_e32 v18, 12, v10
	v_cvt_pk_bf16_f32 v6, v15, v13
	v_cvt_pk_bf16_f32 v7, v17, v25
	v_cvt_pk_bf16_f32 v8, v27, v29
	v_cvt_pk_bf16_f32 v9, v31, v35
	v_lshl_add_u64 v[10:11], v[32:33], 0, v[18:19]
	global_store_dwordx4 v[10:11], v[6:9], off sc0 sc1
	s_waitcnt lgkmcnt(0)

; __device__ __forceinline__ f32x4 ld_nt(const float* p) { return __builtin_nontemporal_load((const f32x4*)p); }
; __device__ __forceinline__ u32x4 pack8(const f32x4 v0, const f32x4 v1) { u32x4 w; w.x = pk_f16(v0[0], v0[1]); w.y = pk_f16(v0[2], v0[3]); w.z = pk_f16(v1[0], v1[1]); w.w = pk_f16(v1[2], v1[3]); return w; }
; __device__ __forceinline__ void convert_item(const float* W, f16* O, int item, int lane) {
;     f32x4 v[4][4];
; #pragma unroll
;     for (int r = 0; r < 4; ++r)
; #pragma unroll
;         for (int q = 0; q < 4; ++q) v[r][q] = ld_nt(W + (size_t)(item * 4 + r) * 4096 + lane * 16 + q * 4);
;     __builtin_amdgcn_sched_barrier(0);
; #pragma unroll
;     for (int r = 0; r < 4; ++r) { f16* op = O + (size_t)(item * 4 + r) * 1024 + lane * 16; *(u32x4*)op = pack8(v[r][0], v[r][1]); *(u32x4*)(op + 8) = pack8(v[r][2], v[r][3]); }
; }
.LBB0_64:
	s_andn2_b64 vcc, exec, s[12:13]
	s_cbranch_vccnz .LBB0_66
	v_readlane_b32 s56, v254, 2
	v_lshlrev_b32_e32 v18, 6, v212
	v_mov_b32_e32 v19, 0
	v_readlane_b32 s70, v254, 16
	v_readlane_b32 s71, v254, 17
	s_add_i32 s1, s0, 0xffffff80
	s_mov_b32 s5, 0
	v_lshl_add_u64 v[6:7], s[70:71], 0, v[18:19]
	s_lshl_b32 s4, s1, 14
	v_lshl_add_u64 v[60:61], s[4:5], 2, v[6:7]
	s_movk_i32 s4, 0x4000
	v_add_co_u32_e32 v28, vcc, s4, v60
	s_mov_b64 s[6:7], 0x4000
	s_nop 0
	v_addc_co_u32_e32 v29, vcc, 0, v61, vcc
	s_mov_b32 s4, 0x8000
	v_lshl_add_u64 v[40:41], v[60:61], 0, s[6:7]
	s_mov_b64 s[6:7], 0x8000
	v_add_co_u32_e32 v44, vcc, s4, v60
	v_lshl_add_u64 v[56:57], v[60:61], 0, s[6:7]
	s_nop 0
	v_addc_co_u32_e32 v45, vcc, 0, v61, vcc
	s_mov_b64 s[6:7], 0xc000
	s_mov_b32 s4, 0xc000
	global_load_dwordx4 v[6:9], v[60:61], off offset:48 nt
	global_load_dwordx4 v[10:13], v[60:61], off offset:32 nt
	global_load_dwordx4 v[14:17], v[60:61], off offset:16 nt
	global_load_dwordx4 v[24:27], v[60:61], off nt
	v_lshl_add_u64 v[72:73], v[60:61], 0, s[6:7]
	v_add_co_u32_e32 v60, vcc, s4, v60
	global_load_dwordx4 v[28:31], v[28:29], off nt
	s_nop 0
	global_load_dwordx4 v[32:35], v[40:41], off offset:48 nt
	global_load_dwordx4 v[36:39], v[40:41], off offset:32 nt
	s_nop 0
	global_load_dwordx4 v[40:43], v[40:41], off offset:16 nt
	v_addc_co_u32_e32 v61, vcc, 0, v61, vcc
	global_load_dwordx4 v[44:47], v[44:45], off nt
	s_nop 0
	global_load_dwordx4 v[48:51], v[56:57], off offset:48 nt
	global_load_dwordx4 v[52:55], v[56:57], off offset:32 nt
	s_nop 0
	global_load_dwordx4 v[56:59], v[56:57], off offset:16 nt
	s_nop 0
	global_load_dwordx4 v[60:63], v[60:61], off nt
	s_nop 0
	global_load_dwordx4 v[64:67], v[72:73], off offset:48 nt
	global_load_dwordx4 v[68:71], v[72:73], off offset:32 nt
	s_nop 0
	global_load_dwordx4 v[72:75], v[72:73], off offset:16 nt
	v_lshlrev_b32_e32 v18, 5, v212
	v_readlane_b32 s57, v254, 3
	v_readlane_b32 s58, v254, 4
	v_readlane_b32 s59, v254, 5
	v_readlane_b32 s60, v254, 6
	v_readlane_b32 s61, v254, 7
	v_readlane_b32 s62, v254, 8
	v_readlane_b32 s63, v254, 9
	v_readlane_b32 s64, v254, 10
	v_readlane_b32 s65, v254, 11
	v_readlane_b32 s66, v254, 12
	v_readlane_b32 s67, v254, 13
	v_readlane_b32 s68, v254, 14
	v_readlane_b32 s69, v254, 15
	v_lshl_add_u64 v[18:19], s[50:51], 0, v[18:19]
	s_lshl_b32 s4, s1, 13
	v_lshl_add_u64 v[18:19], v[18:19], 0, s[4:5]
	s_mov_b64 s[4:5], 0x13600000
	v_lshl_add_u64 v[76:77], v[18:19], 0, s[4:5]
	s_mov_b32 s1, 0x13601000
	s_waitcnt vmcnt(14)
	v_cvt_pk_bf16_f32 v10, v10, v11
	v_cvt_pk_bf16_f32 v11, v12, v13
	v_cvt_pk_bf16_f32 v12, v6, v7
	v_cvt_pk_bf16_f32 v13, v8, v9
	s_waitcnt vmcnt(11)
	v_cvt_pk_bf16_f32 v6, v28, v29
	v_cvt_pk_bf16_f32 v7, v30, v31
	s_waitcnt vmcnt(8)
	v_cvt_pk_bf16_f32 v8, v40, v41
	v_cvt_pk_bf16_f32 v9, v42, v43
	v_cvt_pk_bf16_f32 v24, v24, v25
	v_cvt_pk_bf16_f32 v25, v26, v27
	v_cvt_pk_bf16_f32 v26, v14, v15
	v_add_co_u32_e32 v14, vcc, s1, v18
	global_store_dwordx4 v[76:77], v[6:9], off offset:2048 sc0 sc1
	s_nop 0
	v_addc_co_u32_e32 v15, vcc, 0, v19, vcc
	v_cvt_pk_bf16_f32 v6, v36, v37
	v_cvt_pk_bf16_f32 v7, v38, v39
	v_cvt_pk_bf16_f32 v8, v32, v33
	v_cvt_pk_bf16_f32 v9, v34, v35
	global_store_dwordx4 v[76:77], v[6:9], off offset:2064 sc0 sc1
	v_cvt_pk_bf16_f32 v27, v16, v17
	global_store_dwordx4 v[14:15], v[24:27], off offset:-4096 sc0 sc1
	s_waitcnt vmcnt(10)
	v_cvt_pk_bf16_f32 v6, v44, v45
	v_cvt_pk_bf16_f32 v7, v46, v47
	s_waitcnt vmcnt(7)
	v_cvt_pk_bf16_f32 v8, v56, v57
	v_cvt_pk_bf16_f32 v9, v58, v59
	global_store_dwordx4 v[14:15], v[6:9], off sc0 sc1
	global_store_dwordx4 v[76:77], v[10:13], off offset:16 sc0 sc1
	s_nop 0
	v_cvt_pk_bf16_f32 v6, v52, v53
	v_cvt_pk_bf16_f32 v7, v54, v55
	v_cvt_pk_bf16_f32 v8, v48, v49
	v_cvt_pk_bf16_f32 v9, v50, v51
	global_store_dwordx4 v[14:15], v[6:9], off offset:16 sc0 sc1
	s_waitcnt vmcnt(9)
	s_nop 0
	v_cvt_pk_bf16_f32 v6, v60, v61
	v_cvt_pk_bf16_f32 v7, v62, v63
	s_waitcnt vmcnt(6)
	v_cvt_pk_bf16_f32 v8, v72, v73
	v_cvt_pk_bf16_f32 v9, v74, v75
	global_store_dwordx4 v[14:15], v[6:9], off offset:2048 sc0 sc1
	s_nop 1
	v_cvt_pk_bf16_f32 v6, v68, v69
	v_cvt_pk_bf16_f32 v7, v70, v71
	v_cvt_pk_bf16_f32 v8, v64, v65
	v_cvt_pk_bf16_f32 v9, v66, v67
	global_store_dwordx4 v[14:15], v[6:9], off offset:2064 sc0 sc1

; #define LAS __attribute__((address_space(3)))
; __device__ __forceinline__ f32x4 ld_nt(const float* p) { return __builtin_nontemporal_load((const f32x4*)p); }
; __device__ __forceinline__ void transpose_item(const float* W, int K, int pitch, int ncols, f16* WT, LAS float* scr, int item, int lane) {
;     const int nblk = ncols / 32, kb = item / nblk, nb = item % nblk, k0 = 64 * kb, n0 = 32 * nb;
;     const int kr = lane >> 3, nq = (lane & 7) * 4;
;     f32x4 v[8];
; #pragma unroll
;     for (int i = 0; i < 8; ++i) v[i] = ld_nt(W + (size_t)(k0 + kr + 8 * i) * pitch + n0 + nq);
;     __builtin_amdgcn_sched_barrier(0);
; #pragma unroll
;     for (int i = 0; i < 8; ++i) { LAS float* sp = scr + (kr + 8 * i) * 33 + nq; sp[0] = v[i][0]; sp[1] = v[i][1]; sp[2] = v[i][2]; sp[3] = v[i][3]; }
;     asm volatile("s_waitcnt lgkmcnt(0)" ::: "memory");
;     const int c = lane & 7;
; #pragma unroll
;     for (int j = 0; j < 4; ++j) { const int n = (lane >> 3) + 8 * j; const LAS float* sp = scr + (8 * c) * 33 + n;
;         u32x4 o; o.x = pk_f16(sp[0 * 33], sp[1 * 33]); o.y = pk_f16(sp[2 * 33], sp[3 * 33]); o.z = pk_f16(sp[4 * 33], sp[5 * 33]); o.w = pk_f16(sp[6 * 33], sp[7 * 33]);
;         *(u32x4*)(WT + (size_t)(n0 + n) * K + k0 + 8 * c) = o; }
;     asm volatile("s_waitcnt lgkmcnt(0)" ::: "memory");
; }
.LBB0_67:
	s_andn2_b64 vcc, exec, s[12:13]
	s_cbranch_vccnz .LBB0_69
	s_ashr_i32 s1, s0, 31
	s_lshr_b32 s1, s1, 27
	s_add_i32 s1, s0, s1
	s_lshl_b32 s4, s1, 11
	s_and_b32 s4, s4, 0xffff0000
	s_ashr_i32 s5, s4, 31
	s_lshl_b64 s[6:7], s[4:5], 2
	v_readlane_b32 s56, v254, 18
	v_readlane_b32 s57, v254, 19
	s_add_u32 s8, s56, s6
	s_addc_u32 s7, s57, s7
	s_lshl_b64 s[4:5], s[4:5], 1
	s_add_u32 s9, s50, s4
	s_addc_u32 s10, s51, s5
	s_and_b32 s1, s1, 0xffe0
	s_sub_i32 s0, s0, s1
	s_bfe_i32 s1, s0, 0x80000
	s_bfe_u32 s1, s1, 0x3000c
	s_add_i32 s1, s0, s1
	s_bfe_i32 s4, s1, 0x80000
	s_and_b32 s1, s1, 0xf8
	s_sub_i32 s0, s0, s1
	s_sext_i32_i16 s4, s4
	s_sext_i32_i8 s0, s0
	s_lshl_b32 s1, s4, 3
	s_lshl_b32 s4, s0, 5
	s_and_b32 s6, s1, 0xffffffc0
	s_ashr_i32 s5, s4, 31
	v_or_b32_e32 v18, s6, v20
	s_lshl_b64 s[0:1], s[4:5], 2
	s_add_u32 s0, s8, s0
	v_ashrrev_i32_e32 v19, 31, v18
	v_or_b32_e32 v8, 8, v18
	v_or_b32_e32 v14, 16, v18
	v_or_b32_e32 v16, 24, v18
	v_or_b32_e32 v28, 32, v18
	v_or_b32_e32 v30, 40, v18
	v_or_b32_e32 v38, 48, v18
	s_addc_u32 s1, s7, s1
	v_lshlrev_b32_e32 v44, 2, v4
	v_mov_b32_e32 v45, 0
	v_lshlrev_b64 v[6:7], 10, v[18:19]
	v_ashrrev_i32_e32 v9, 31, v8
	v_ashrrev_i32_e32 v15, 31, v14
	v_ashrrev_i32_e32 v17, 31, v16
	v_ashrrev_i32_e32 v29, 31, v28
	v_ashrrev_i32_e32 v31, 31, v30
	v_ashrrev_i32_e32 v39, 31, v38
	v_or_b32_e32 v18, 56, v18
	v_lshl_add_u64 v[36:37], s[0:1], 0, v[44:45]
	v_lshlrev_b64 v[8:9], 10, v[8:9]
	v_lshlrev_b64 v[14:15], 10, v[14:15]
	v_lshlrev_b64 v[16:17], 10, v[16:17]
	v_lshlrev_b64 v[28:29], 10, v[28:29]
	v_lshlrev_b64 v[30:31], 10, v[30:31]
	v_lshlrev_b64 v[38:39], 10, v[38:39]
	v_ashrrev_i32_e32 v19, 31, v18
	v_lshl_add_u64 v[6:7], v[36:37], 0, v[6:7]
	v_lshl_add_u64 v[10:11], v[36:37], 0, v[8:9]
	v_lshl_add_u64 v[14:15], v[36:37], 0, v[14:15]
	v_lshl_add_u64 v[24:25], v[36:37], 0, v[16:17]
	v_lshl_add_u64 v[28:29], v[36:37], 0, v[28:29]
	v_lshl_add_u64 v[32:33], v[36:37], 0, v[30:31]
	v_lshl_add_u64 v[38:39], v[36:37], 0, v[38:39]
	v_lshlrev_b64 v[18:19], 10, v[18:19]
	global_load_dwordx4 v[6:9], v[6:7], off nt
	s_nop 0
	global_load_dwordx4 v[10:13], v[10:11], off nt
	s_nop 0
	global_load_dwordx4 v[14:17], v[14:15], off nt
	s_nop 0
	global_load_dwordx4 v[24:27], v[24:25], off nt
	s_nop 0
	global_load_dwordx4 v[28:31], v[28:29], off nt
	s_nop 0
	global_load_dwordx4 v[32:35], v[32:33], off nt
	v_lshl_add_u64 v[18:19], v[36:37], 0, v[18:19]
	global_load_dwordx4 v[36:39], v[38:39], off nt
	s_nop 0
	global_load_dwordx4 v[40:43], v[18:19], off nt
	v_readlane_b32 s58, v254, 20
	v_readlane_b32 s59, v254, 21
	v_readlane_b32 s60, v254, 22
	v_readlane_b32 s61, v254, 23
	v_readlane_b32 s62, v254, 24
	v_readlane_b32 s63, v254, 25
	v_readlane_b32 s64, v254, 26
	v_readlane_b32 s65, v254, 27
	v_readlane_b32 s66, v254, 28
	v_readlane_b32 s67, v254, 29
	v_readlane_b32 s68, v254, 30
	v_readlane_b32 s69, v254, 31
	v_readlane_b32 s70, v254, 32
	v_readlane_b32 s71, v254, 33
	v_add_u32_e32 v4, 0x420, v22
	s_waitcnt vmcnt(7)
	ds_write2_b32 v22, v6, v7 offset1:1
	ds_write2_b32 v22, v8, v9 offset0:2 offset1:3
	s_waitcnt vmcnt(6)
	ds_write2_b32 v4, v10, v11 offset1:1
	v_add_u32_e32 v4, 0x428, v22
	ds_write2_b32 v4, v12, v13 offset1:1
	v_add_u32_e32 v4, 0x840, v22
	s_waitcnt vmcnt(5)
	ds_write2_b32 v4, v14, v15 offset1:1
	v_add_u32_e32 v4, 0x848, v22
	ds_write2_b32 v4, v16, v17 offset1:1
	v_add_u32_e32 v4, 0xc60, v22
	s_waitcnt vmcnt(4)
	ds_write2_b32 v4, v24, v25 offset1:1
	v_add_u32_e32 v4, 0xc68, v22
	ds_write2_b32 v4, v26, v27 offset1:1
	v_add_u32_e32 v4, 0x1080, v22
	s_waitcnt vmcnt(3)
	ds_write2_b32 v4, v28, v29 offset1:1
	v_add_u32_e32 v4, 0x1088, v22
	ds_write2_b32 v4, v30, v31 offset1:1
	v_add_u32_e32 v4, 0x14a0, v22
	s_waitcnt vmcnt(2)
	ds_write2_b32 v4, v32, v33 offset1:1
	v_add_u32_e32 v4, 0x14a8, v22
	ds_write2_b32 v4, v34, v35 offset1:1
	v_add_u32_e32 v4, 0x18c0, v22
	s_waitcnt vmcnt(1)
	ds_write2_b32 v4, v36, v37 offset1:1
	v_add_u32_e32 v4, 0x18c8, v22
	ds_write2_b32 v4, v38, v39 offset1:1
	v_add_u32_e32 v4, 0x1ce0, v22
	s_waitcnt vmcnt(0)
	ds_write2_b32 v4, v40, v41 offset1:1
	v_add_u32_e32 v4, 0x1ce8, v22
	ds_write2_b32 v4, v42, v43 offset1:1
	s_waitcnt lgkmcnt(0)
	s_ashr_i32 s7, s6, 31
	s_lshl_b64 s[0:1], s[6:7], 1
	ds_read2_b32 v[10:11], v5 offset0:33 offset1:41
	ds_read2_b32 v[12:13], v5 offset1:8
	ds_read2_b32 v[14:15], v5 offset0:66 offset1:74
	ds_read2_b32 v[16:17], v5 offset0:99 offset1:107
	ds_read2_b32 v[18:19], v5 offset0:132 offset1:140
	ds_read2_b32 v[22:23], v5 offset0:165 offset1:173
	ds_read2_b32 v[24:25], v5 offset0:198 offset1:206
	ds_read2_b32 v[26:27], v5 offset0:231 offset1:239
	s_add_u32 s0, s9, s0
	s_addc_u32 s1, s10, s1
	v_lshlrev_b32_e32 v44, 1, v2
	v_or_b32_e32 v30, s4, v20
	v_lshl_add_u64 v[6:7], s[0:1], 0, v[44:45]
	s_mov_b64 s[0:1], 0x2000000
	v_ashrrev_i32_e32 v31, 31, v30
	v_lshl_add_u64 v[28:29], v[6:7], 0, s[0:1]
	v_lshlrev_b64 v[30:31], 9, v[30:31]
	s_waitcnt lgkmcnt(6)
	v_cvt_pk_bf16_f32 v6, v12, v10
	s_waitcnt lgkmcnt(4)
	v_cvt_pk_bf16_f32 v7, v14, v16
	s_waitcnt lgkmcnt(2)
	v_cvt_pk_bf16_f32 v8, v18, v22
	s_waitcnt lgkmcnt(0)
	v_cvt_pk_bf16_f32 v9, v24, v26
	v_lshl_add_u64 v[30:31], v[28:29], 0, v[30:31]
	global_store_dwordx4 v[30:31], v[6:9], off sc0 sc1
	v_or_b32_e32 v10, s4, v21
	v_or_b32_e32 v2, s4, v3
	v_cvt_pk_bf16_f32 v6, v13, v11
	v_cvt_pk_bf16_f32 v7, v15, v17
	v_cvt_pk_bf16_f32 v8, v19, v23
	v_cvt_pk_bf16_f32 v9, v25, v27
	ds_read2_b32 v[12:13], v5 offset0:49 offset1:57
	ds_read2_b32 v[14:15], v5 offset0:16 offset1:24
	ds_read2_b32 v[16:17], v5 offset0:82 offset1:90
	ds_read2_b32 v[18:19], v5 offset0:115 offset1:123
	ds_read2_b32 v[20:21], v5 offset0:148 offset1:156
	ds_read2_b32 v[22:23], v5 offset0:181 offset1:189
	ds_read2_b32 v[24:25], v5 offset0:214 offset1:222
	ds_read2_b32 v[26:27], v5 offset0:247 offset1:255
	v_ashrrev_i32_e32 v11, 31, v10
	v_lshlrev_b64 v[10:11], 9, v[10:11]
	v_ashrrev_i32_e32 v3, 31, v2
	v_lshl_add_u64 v[10:11], v[28:29], 0, v[10:11]
	v_lshlrev_b64 v[2:3], 9, v[2:3]
	global_store_dwordx4 v[10:11], v[6:9], off sc0 sc1
	s_waitcnt lgkmcnt(6)
	v_cvt_pk_bf16_f32 v4, v14, v12
	s_waitcnt lgkmcnt(4)
	v_cvt_pk_bf16_f32 v5, v16, v18
	s_waitcnt lgkmcnt(2)
	v_cvt_pk_bf16_f32 v6, v20, v22
	s_waitcnt lgkmcnt(0)
	v_cvt_pk_bf16_f32 v7, v24, v26
	v_lshl_add_u64 v[2:3], v[28:29], 0, v[2:3]
	global_store_dwordx4 v[2:3], v[4:7], off sc0 sc1
	v_cvt_pk_bf16_f32 v2, v15, v13
	v_cvt_pk_bf16_f32 v3, v17, v19
	v_or_b32_e32 v6, s4, v1
	v_ashrrev_i32_e32 v7, 31, v6
	v_lshlrev_b64 v[6:7], 9, v[6:7]
	v_cvt_pk_bf16_f32 v4, v21, v23
	v_cvt_pk_bf16_f32 v5, v25, v27
	v_lshl_add_u64 v[6:7], v[28:29], 0, v[6:7]
	global_store_dwordx4 v[6:7], v[2:5], off sc0 sc1
	s_waitcnt lgkmcnt(0)

; #define LAS __attribute__((address_space(3)))
; __device__ __forceinline__ u32x4 pack8(const f32x4 v0, const f32x4 v1) { u32x4 w; w.x = pk_f16(v0[0], v0[1]); w.y = pk_f16(v0[2], v0[3]); w.z = pk_f16(v1[0], v1[1]); w.w = pk_f16(v1[2], v1[3]); return w; }
; __device__ __forceinline__ void ssm_tables(LAS float* L, int item, const float* lam_re, const float* lam_im, const float* log_dt, const float* b_re, const float* b_im,
;                                            const float* c_re, const float* c_im, f16* PG, f16* QG, f16* KTH) {
;     ...
;     { const int sp = lane >> 1, h0 = (lane & 1) * 8; const int e = dir == 0 ? TC - 1 - sp : sp;
;       for (int jr = wave; jr < 128; jr += NWAVES) { const int ri = jr >> 6, n = jr & 63;
;         const f32x2 p = *(const LAS f32x2*)(L + T_AP + e * APS + 2 * n);
;         const LAS f32x4* brp = (const LAS f32x4*)(L + T_BR + dir * 1024 + n * 16 + h0); const LAS f32x4* bip = (const LAS f32x4*)(L + T_BI + dir * 1024 + n * 16 + h0);
;         const f32x4 br0 = brp[0], br1 = brp[1], bi0 = bip[0], bi1 = bip[1];
;         const f32x4 v0 = ri == 0 ? p.x * br0 - p.y * bi0 : p.x * bi0 + p.y * br0, v1 = ri == 0 ? p.x * br1 - p.y * bi1 : p.x * bi1 + p.y * br1;
;         *(u32x4*)(PGg + (size_t)(dir * 128 + jr) * 512 + lane * 8) = pack8(v0, v1); } }
;     { const int k0 = (lane & 15) * 8, ri = k0 >> 6, n0 = k0 & 63;
;       for (int it = 0; it < 16; ++it) { const int nrow = wave * 64 + it * 4 + (lane >> 4), s = nrow >> 4, h = nrow & 15; const int e = dir == 0 ? s + 1 : TC - s;
;         const LAS f32x4* crp = (const LAS f32x4*)(L + T_CR + dir * 1024 + h * 64 + n0); const LAS f32x4* cip = (const LAS f32x4*)(L + T_CI + dir * 1024 + h * 64 + n0);
;         const LAS f32x4* app = (const LAS f32x4*)(L + T_AP + e * APS + 2 * n0);
;         const f32x4 cr0 = crp[0], cr1 = crp[1], ci0 = cip[0], ci1 = cip[1], a0 = app[0], a1 = app[1], a2 = app[2], a3 = app[3];
;         const f32x4 pr0 = {a0[0], a0[2], a1[0], a1[2]}, pi0 = {a0[1], a0[3], a1[1], a1[3]}, pr1 = {a2[0], a2[2], a3[0], a3[2]}, pi1 = {a2[1], a2[3], a3[1], a3[3]};
;         const f32x4 v0 = ri == 0 ? cr0 * pr0 - ci0 * pi0 : -(cr0 * pi0 + ci0 * pr0), v1 = ri == 0 ? cr1 * pr1 - ci1 * pi1 : -(cr1 * pi1 + ci1 * pr1);
;         *(u32x4*)(QGg + (size_t)nrow * 256 + dir * 128 + k0) = pack8(v0, v1); } }
.LBB0_163:
	v_and_b32_e32 v6, 63, v24
	v_lshl_add_u32 v7, v6, 3, v4
	v_lshl_add_u32 v18, v6, 6, v5
	ds_read_b64 v[28:29], v7
	ds_read_b128 v[6:9], v18 offset:26640
	ds_read_b128 v[10:13], v18 offset:18464
	ds_read_b128 v[14:17], v18 offset:18448
	ds_read_b128 v[18:21], v18 offset:26656
	v_cmp_lt_u32_e64 s[2:3], s8, v24
	s_waitcnt lgkmcnt(3)
	v_pk_mul_f32 v[30:31], v[28:29], v[6:7] op_sel:[1,0]
	v_pk_mul_f32 v[32:33], v[28:29], v[8:9] op_sel:[1,0]
	v_pk_mul_f32 v[6:7], v[28:29], v[6:7] op_sel_hi:[0,1]
	v_pk_mul_f32 v[8:9], v[28:29], v[8:9] op_sel_hi:[0,1]
	s_waitcnt lgkmcnt(0)
	v_pk_mul_f32 v[34:35], v[28:29], v[18:19] op_sel:[1,0]
	v_pk_mul_f32 v[36:37], v[28:29], v[20:21] op_sel:[1,0]
	v_pk_mul_f32 v[18:19], v[28:29], v[18:19] op_sel_hi:[0,1]
	v_pk_mul_f32 v[20:21], v[28:29], v[20:21] op_sel_hi:[0,1]
	s_or_b64 s[6:7], s[2:3], s[6:7]
	v_pk_fma_f32 v[32:33], v[28:29], v[16:17], v[32:33] op_sel_hi:[0,1,1] neg_lo:[0,0,1] neg_hi:[0,0,1]
	v_pk_fma_f32 v[8:9], v[28:29], v[16:17], v[8:9] op_sel:[1,0,0]
	v_cmp_gt_u32_e64 s[2:3], 64, v24
	v_pk_fma_f32 v[16:17], v[28:29], v[14:15], v[30:31] op_sel_hi:[0,1,1] neg_lo:[0,0,1] neg_hi:[0,0,1]
	v_pk_fma_f32 v[6:7], v[28:29], v[14:15], v[6:7] op_sel:[1,0,0]
	v_pk_fma_f32 v[14:15], v[28:29], v[12:13], v[36:37] op_sel_hi:[0,1,1] neg_lo:[0,0,1] neg_hi:[0,0,1]
	v_pk_fma_f32 v[30:31], v[28:29], v[10:11], v[34:35] op_sel_hi:[0,1,1] neg_lo:[0,0,1] neg_hi:[0,0,1]
	v_pk_fma_f32 v[12:13], v[28:29], v[12:13], v[20:21] op_sel:[1,0,0]
	v_pk_fma_f32 v[10:11], v[28:29], v[10:11], v[18:19] op_sel:[1,0,0]
	v_cndmask_b32_e64 v9, v9, v33, s[2:3]
	v_cndmask_b32_e64 v8, v8, v32, s[2:3]
	v_cndmask_b32_e64 v7, v7, v17, s[2:3]
	v_cndmask_b32_e64 v6, v6, v16, s[2:3]
	v_cndmask_b32_e64 v13, v13, v15, s[2:3]
	v_cndmask_b32_e64 v12, v12, v14, s[2:3]
	v_cndmask_b32_e64 v11, v11, v31, s[2:3]
	v_cndmask_b32_e64 v10, v10, v30, s[2:3]
	v_add_u32_e32 v25, 8, v24
	v_cvt_pk_bf16_f32 v6, v6, v7
	v_cvt_pk_bf16_f32 v7, v8, v9
	v_cvt_pk_bf16_f32 v8, v10, v11
	v_cvt_pk_bf16_f32 v9, v12, v13
	v_mov_b32_e32 v24, v25
	global_store_dwordx4 v[2:3], v[6:9], off sc0 sc1
	v_lshl_add_u64 v[2:3], v[2:3], 0, s[10:11]
	s_andn2_b64 exec, exec, s[6:7]
	s_cbranch_execnz .LBB0_163
	s_or_b64 exec, exec, s[6:7]
	s_add_u32 s2, s50, s4
	s_addc_u32 s3, s51, s5
	v_lshlrev_b32_e32 v2, 3, v22
	s_lshl_b32 s0, s0, 8
	v_and_b32_e32 v2, 56, v2
	s_add_u32 s0, s2, s0
	v_lshl_add_u32 v24, v2, 2, s1
	s_addc_u32 s1, s3, 0
	v_lshlrev_b32_e32 v18, 4, v22
	v_mov_b32_e32 v19, 0
	v_and_b32_e32 v26, 0x1c0, v0
	v_lshl_add_u32 v25, v2, 3, 0
	v_lshl_add_u64 v[2:3], s[0:1], 0, v[18:19]
	s_mov_b64 s[0:1], 0x3100000
	v_lshl_add_u64 v[20:21], v[2:3], 0, s[0:1]
	v_lshrrev_b32_e32 v2, 4, v26
	v_or_b32_e32 v3, 1, v2
	v_sub_u32_e32 v2, 32, v2
	v_cndmask_b32_e32 v2, v2, v3, vcc
	v_lshl_add_u32 v6, v27, 2, v24
	s_movk_i32 s0, 0x210
	v_mad_i32_i24 v18, v2, s0, v25
	ds_read_b128 v[10:13], v6 offset:34832
	ds_read_b128 v[2:5], v6 offset:34848
	ds_read_b128 v[28:31], v18
	ds_read_b128 v[32:35], v18 offset:16
	ds_read_b128 v[14:17], v6 offset:43024
	ds_read_b128 v[6:9], v6 offset:43040
	ds_read_b128 v[36:39], v18 offset:32
	ds_read_b128 v[40:43], v18 offset:48
	s_waitcnt lgkmcnt(4)
	v_mov_b32_e32 v58, v33
	v_mov_b32_e32 v59, v35
	v_mov_b32_e32 v60, v29
	v_mov_b32_e32 v61, v31
	s_waitcnt lgkmcnt(3)
	v_pk_mul_f32 v[44:45], v[16:17], v[58:59]
	v_pk_mul_f32 v[46:47], v[14:15], v[60:61]
	v_mov_b32_e32 v29, v30
	v_mov_b32_e32 v33, v34
	v_pk_fma_f32 v[30:31], v[10:11], v[28:29], v[46:47] neg_lo:[0,0,1] neg_hi:[0,0,1]
	v_pk_fma_f32 v[34:35], v[12:13], v[32:33], v[44:45] neg_lo:[0,0,1] neg_hi:[0,0,1]
	v_pk_mul_f32 v[44:45], v[14:15], v[28:29]
	v_pk_mul_f32 v[46:47], v[16:17], v[32:33]
	v_pk_fma_f32 v[44:45], v[10:11], v[60:61], v[44:45]
	v_pk_fma_f32 v[46:47], v[12:13], v[58:59], v[46:47]
	v_xor_b32_e32 v18, 0x80000000, v44
	v_xor_b32_e32 v27, 0x80000000, v45
	v_xor_b32_e32 v44, 0x80000000, v46
	v_xor_b32_e32 v45, 0x80000000, v47
	v_cmp_gt_u32_e64 s[2:3], 8, v22
	s_waitcnt lgkmcnt(1)
	v_mov_b32_e32 v62, v37
	v_mov_b32_e32 v63, v39
	v_cndmask_b32_e64 v46, v45, v35, s[2:3]
	v_cndmask_b32_e64 v47, v44, v34, s[2:3]
	v_cndmask_b32_e64 v18, v18, v30, s[2:3]
	s_waitcnt lgkmcnt(0)
	v_mov_b32_e32 v30, v41
	v_pk_mul_f32 v[44:45], v[6:7], v[62:63]
	v_mov_b32_e32 v37, v38
	v_mov_b32_e32 v41, v42
	v_cndmask_b32_e64 v27, v27, v31, s[2:3]
	v_mov_b32_e32 v31, v43
	v_pk_fma_f32 v[38:39], v[2:3], v[36:37], v[44:45] neg_lo:[0,0,1] neg_hi:[0,0,1]
	v_pk_mul_f32 v[42:43], v[6:7], v[36:37]
	v_pk_mul_f32 v[44:45], v[8:9], v[40:41]
	v_pk_mul_f32 v[34:35], v[8:9], v[30:31]
	v_pk_fma_f32 v[44:45], v[4:5], v[30:31], v[44:45]
	v_pk_fma_f32 v[42:43], v[2:3], v[62:63], v[42:43]
	v_or_b32_e32 v64, v23, v26
	v_pk_fma_f32 v[34:35], v[4:5], v[40:41], v[34:35] neg_lo:[0,0,1] neg_hi:[0,0,1]
	v_xor_b32_e32 v42, 0x80000000, v42
	v_xor_b32_e32 v44, 0x80000000, v44
	v_xor_b32_e32 v45, 0x80000000, v45
	v_cndmask_b32_e64 v35, v45, v35, s[2:3]
	v_cndmask_b32_e64 v34, v44, v34, s[2:3]
	v_cndmask_b32_e64 v38, v42, v38, s[2:3]
	v_cvt_pk_bf16_f32 v42, v18, v27
	v_lshlrev_b32_e32 v18, 9, v64
	v_cvt_pk_bf16_f32 v45, v34, v35
	v_lshl_add_u64 v[34:35], v[20:21], 0, v[18:19]
	v_or_b32_e32 v18, 4, v64
	v_lshlrev_b32_e32 v27, 8, v18
	v_and_b32_e32 v27, 0x700, v27
	v_xor_b32_e32 v43, 0x80000000, v43
	v_add_u32_e32 v27, v24, v27
	v_cndmask_b32_e64 v39, v43, v39, s[2:3]
	v_cvt_pk_bf16_f32 v43, v47, v46
	ds_read_b128 v[46:49], v27 offset:43024
	v_cvt_pk_bf16_f32 v44, v38, v39
	global_store_dwordx4 v[34:35], v[42:45], off sc0 sc1
	ds_read_b128 v[42:45], v27 offset:34832
	ds_read_b128 v[50:53], v27 offset:34848
	ds_read_b128 v[54:57], v27 offset:43040
	v_lshlrev_b32_e32 v18, 9, v18
	s_waitcnt lgkmcnt(3)
; #define LAS __attribute__((address_space(3)))
; __device__ __forceinline__ u32x4 pack8(const f32x4 v0, const f32x4 v1) { u32x4 w; w.x = pk_f16(v0[0], v0[1]); w.y = pk_f16(v0[2], v0[3]); w.z = pk_f16(v1[0], v1[1]); w.w = pk_f16(v1[2], v1[3]); return w; }
; __device__ __forceinline__ void ssm_tables(LAS float* L, int item, const float* lam_re, const float* lam_im, const float* log_dt, const float* b_re, const float* b_im,
;                                            const float* c_re, const float* c_im, f16* PG, f16* QG, f16* KTH) {
;     ...
;     { const int k0 = (lane & 15) * 8, ri = k0 >> 6, n0 = k0 & 63;
;       for (int it = 0; it < 16; ++it) { const int nrow = wave * 64 + it * 4 + (lane >> 4), s = nrow >> 4, h = nrow & 15; const int e = dir == 0 ? s + 1 : TC - s;
;         const LAS f32x4* crp = (const LAS f32x4*)(L + T_CR + dir * 1024 + h * 64 + n0); const LAS f32x4* cip = (const LAS f32x4*)(L + T_CI + dir * 1024 + h * 64 + n0);
;         const LAS f32x4* app = (const LAS f32x4*)(L + T_AP + e * APS + 2 * n0);
;         const f32x4 cr0 = crp[0], cr1 = crp[1], ci0 = cip[0], ci1 = cip[1], a0 = app[0], a1 = app[1], a2 = app[2], a3 = app[3];
;         const f32x4 pr0 = {a0[0], a0[2], a1[0], a1[2]}, pi0 = {a0[1], a0[3], a1[1], a1[3]}, pr1 = {a2[0], a2[2], a3[0], a3[2]}, pi1 = {a2[1], a2[3], a3[1], a3[3]};
;         const f32x4 v0 = ri == 0 ? cr0 * pr0 - ci0 * pi0 : -(cr0 * pi0 + ci0 * pr0), v1 = ri == 0 ? cr1 * pr1 - ci1 * pi1 : -(cr1 * pi1 + ci1 * pr1);
;         *(u32x4*)(QGg + (size_t)nrow * 256 + dir * 128 + k0) = pack8(v0, v1); } }
	v_pk_mul_f32 v[34:35], v[58:59], v[48:49]
	v_pk_mul_f32 v[38:39], v[60:61], v[46:47]
	v_pk_mul_f32 v[48:49], v[32:33], v[48:49]
	v_pk_mul_f32 v[46:47], v[28:29], v[46:47]
	s_waitcnt lgkmcnt(2)
	v_pk_fma_f32 v[38:39], v[28:29], v[42:43], v[38:39] neg_lo:[0,0,1] neg_hi:[0,0,1]
	v_pk_fma_f32 v[34:35], v[32:33], v[44:45], v[34:35] neg_lo:[0,0,1] neg_hi:[0,0,1]
	v_pk_fma_f32 v[44:45], v[58:59], v[44:45], v[48:49]
	v_pk_fma_f32 v[42:43], v[60:61], v[42:43], v[46:47]
	s_nop 0
	v_xor_b32_e32 v27, 0x80000000, v42
	v_xor_b32_e32 v42, 0x80000000, v43
	v_xor_b32_e32 v43, 0x80000000, v44
	v_xor_b32_e32 v44, 0x80000000, v45
	v_cndmask_b32_e64 v47, v43, v34, s[2:3]
	v_cndmask_b32_e64 v48, v42, v39, s[2:3]
	s_waitcnt lgkmcnt(0)
	v_pk_mul_f32 v[42:43], v[40:41], v[56:57]
	v_cndmask_b32_e64 v46, v44, v35, s[2:3]
	v_pk_mul_f32 v[34:35], v[30:31], v[56:57]
	v_pk_mul_f32 v[44:45], v[36:37], v[54:55]
	v_pk_fma_f32 v[42:43], v[30:31], v[52:53], v[42:43]
	v_cndmask_b32_e64 v27, v27, v38, s[2:3]
	v_pk_mul_f32 v[38:39], v[62:63], v[54:55]
	v_pk_fma_f32 v[34:35], v[40:41], v[52:53], v[34:35] neg_lo:[0,0,1] neg_hi:[0,0,1]
	v_pk_fma_f32 v[44:45], v[62:63], v[50:51], v[44:45]
	v_xor_b32_e32 v42, 0x80000000, v42
	v_xor_b32_e32 v43, 0x80000000, v43
	v_pk_fma_f32 v[38:39], v[36:37], v[50:51], v[38:39] neg_lo:[0,0,1] neg_hi:[0,0,1]
	v_xor_b32_e32 v45, 0x80000000, v45
	v_cndmask_b32_e64 v35, v43, v35, s[2:3]
	v_cndmask_b32_e64 v34, v42, v34, s[2:3]
	v_cndmask_b32_e64 v39, v45, v39, s[2:3]
	v_cvt_pk_bf16_f32 v45, v34, v35
	v_lshl_add_u64 v[34:35], v[20:21], 0, v[18:19]
	v_or_b32_e32 v18, 8, v64
	v_cvt_pk_bf16_f32 v42, v27, v48
	v_lshlrev_b32_e32 v27, 8, v18
	v_and_b32_e32 v27, 0xb00, v27
	v_xor_b32_e32 v44, 0x80000000, v44
	v_add_u32_e32 v27, v24, v27
	v_cndmask_b32_e64 v38, v44, v38, s[2:3]
	v_cvt_pk_bf16_f32 v43, v47, v46
	ds_read_b128 v[46:49], v27 offset:43024
	v_cvt_pk_bf16_f32 v44, v38, v39
	global_store_dwordx4 v[34:35], v[42:45], off sc0 sc1
	ds_read_b128 v[42:45], v27 offset:34832
	ds_read_b128 v[50:53], v27 offset:34848
	ds_read_b128 v[54:57], v27 offset:43040
	v_lshlrev_b32_e32 v18, 9, v18
	s_waitcnt lgkmcnt(3)
	v_pk_mul_f32 v[34:35], v[58:59], v[48:49]
	v_pk_mul_f32 v[38:39], v[60:61], v[46:47]
	v_pk_mul_f32 v[48:49], v[32:33], v[48:49]
	v_pk_mul_f32 v[46:47], v[28:29], v[46:47]
	s_waitcnt lgkmcnt(2)
	v_pk_fma_f32 v[38:39], v[28:29], v[42:43], v[38:39] neg_lo:[0,0,1] neg_hi:[0,0,1]
	v_pk_fma_f32 v[34:35], v[32:33], v[44:45], v[34:35] neg_lo:[0,0,1] neg_hi:[0,0,1]
	v_pk_fma_f32 v[44:45], v[58:59], v[44:45], v[48:49]
	v_pk_fma_f32 v[42:43], v[60:61], v[42:43], v[46:47]
	s_nop 0
	v_xor_b32_e32 v27, 0x80000000, v42
	v_xor_b32_e32 v42, 0x80000000, v43
	v_xor_b32_e32 v43, 0x80000000, v44
	v_xor_b32_e32 v44, 0x80000000, v45
	v_cndmask_b32_e64 v47, v43, v34, s[2:3]
	v_cndmask_b32_e64 v48, v42, v39, s[2:3]
	s_waitcnt lgkmcnt(0)
	v_pk_mul_f32 v[42:43], v[40:41], v[56:57]
	v_cndmask_b32_e64 v46, v44, v35, s[2:3]
	v_pk_mul_f32 v[34:35], v[30:31], v[56:57]
	v_pk_mul_f32 v[44:45], v[36:37], v[54:55]
	v_pk_fma_f32 v[42:43], v[30:31], v[52:53], v[42:43]
	v_cndmask_b32_e64 v27, v27, v38, s[2:3]
	v_pk_mul_f32 v[38:39], v[62:63], v[54:55]
	v_pk_fma_f32 v[34:35], v[40:41], v[52:53], v[34:35] neg_lo:[0,0,1] neg_hi:[0,0,1]
	v_pk_fma_f32 v[44:45], v[62:63], v[50:51], v[44:45]
	v_xor_b32_e32 v42, 0x80000000, v42
	v_xor_b32_e32 v43, 0x80000000, v43
	v_pk_fma_f32 v[38:39], v[36:37], v[50:51], v[38:39] neg_lo:[0,0,1] neg_hi:[0,0,1]
	v_xor_b32_e32 v45, 0x80000000, v45
	v_cndmask_b32_e64 v35, v43, v35, s[2:3]
	v_cndmask_b32_e64 v34, v42, v34, s[2:3]
	v_cndmask_b32_e64 v39, v45, v39, s[2:3]
	v_cvt_pk_bf16_f32 v45, v34, v35
	v_lshl_add_u64 v[34:35], v[20:21], 0, v[18:19]
	v_or_b32_e32 v18, 12, v64
	v_cvt_pk_bf16_f32 v42, v27, v48
	v_lshlrev_b32_e32 v27, 8, v18
	v_and_b32_e32 v27, 0xf00, v27
	v_xor_b32_e32 v44, 0x80000000, v44
	v_add_u32_e32 v27, v24, v27
	v_cndmask_b32_e64 v38, v44, v38, s[2:3]
	v_cvt_pk_bf16_f32 v43, v47, v46
	ds_read_b128 v[46:49], v27 offset:43024
	v_cvt_pk_bf16_f32 v44, v38, v39
	global_store_dwordx4 v[34:35], v[42:45], off sc0 sc1
	ds_read_b128 v[42:45], v27 offset:34832
	ds_read_b128 v[50:53], v27 offset:34848
	ds_read_b128 v[54:57], v27 offset:43040
	v_lshlrev_b32_e32 v18, 9, v18
	s_waitcnt lgkmcnt(3)
	v_pk_mul_f32 v[34:35], v[58:59], v[48:49]
	v_pk_mul_f32 v[38:39], v[60:61], v[46:47]
	s_waitcnt lgkmcnt(2)
	v_pk_fma_f32 v[34:35], v[32:33], v[44:45], v[34:35] neg_lo:[0,0,1] neg_hi:[0,0,1]
	v_pk_fma_f32 v[38:39], v[28:29], v[42:43], v[38:39] neg_lo:[0,0,1] neg_hi:[0,0,1]
	v_pk_mul_f32 v[32:33], v[32:33], v[48:49]
	v_pk_mul_f32 v[28:29], v[28:29], v[46:47]
	v_pk_fma_f32 v[32:33], v[58:59], v[44:45], v[32:33]
	v_pk_fma_f32 v[28:29], v[60:61], v[42:43], v[28:29]
	s_nop 0
	v_xor_b32_e32 v27, 0x80000000, v28
	v_xor_b32_e32 v28, 0x80000000, v29
	v_xor_b32_e32 v29, 0x80000000, v32
	v_xor_b32_e32 v32, 0x80000000, v33
	v_cndmask_b32_e64 v42, v32, v35, s[2:3]
	s_waitcnt lgkmcnt(0)
; #define LAS __attribute__((address_space(3)))
; __device__ __forceinline__ u32x4 pack8(const f32x4 v0, const f32x4 v1) { u32x4 w; w.x = pk_f16(v0[0], v0[1]); w.y = pk_f16(v0[2], v0[3]); w.z = pk_f16(v1[0], v1[1]); w.w = pk_f16(v1[2], v1[3]); return w; }
; __device__ __forceinline__ void ssm_tables(LAS float* L, int item, const float* lam_re, const float* lam_im, const float* log_dt, const float* b_re, const float* b_im,
;                                            const float* c_re, const float* c_im, f16* PG, f16* QG, f16* KTH) {
;     ...
;     { const int k0 = (lane & 15) * 8, ri = k0 >> 6, n0 = k0 & 63;
;       for (int it = 0; it < 16; ++it) { const int nrow = wave * 64 + it * 4 + (lane >> 4), s = nrow >> 4, h = nrow & 15; const int e = dir == 0 ? s + 1 : TC - s;
;         const LAS f32x4* crp = (const LAS f32x4*)(L + T_CR + dir * 1024 + h * 64 + n0); const LAS f32x4* cip = (const LAS f32x4*)(L + T_CI + dir * 1024 + h * 64 + n0);
;         const LAS f32x4* app = (const LAS f32x4*)(L + T_AP + e * APS + 2 * n0);
;         const f32x4 cr0 = crp[0], cr1 = crp[1], ci0 = cip[0], ci1 = cip[1], a0 = app[0], a1 = app[1], a2 = app[2], a3 = app[3];
;         const f32x4 pr0 = {a0[0], a0[2], a1[0], a1[2]}, pi0 = {a0[1], a0[3], a1[1], a1[3]}, pr1 = {a2[0], a2[2], a3[0], a3[2]}, pi1 = {a2[1], a2[3], a3[1], a3[3]};
;         const f32x4 v0 = ri == 0 ? cr0 * pr0 - ci0 * pi0 : -(cr0 * pi0 + ci0 * pr0), v1 = ri == 0 ? cr1 * pr1 - ci1 * pi1 : -(cr1 * pi1 + ci1 * pr1);
;         *(u32x4*)(QGg + (size_t)nrow * 256 + dir * 128 + k0) = pack8(v0, v1); } }
	v_pk_mul_f32 v[32:33], v[62:63], v[54:55]
	v_cndmask_b32_e64 v43, v29, v34, s[2:3]
	v_pk_fma_f32 v[32:33], v[36:37], v[50:51], v[32:33] neg_lo:[0,0,1] neg_hi:[0,0,1]
	v_pk_mul_f32 v[34:35], v[40:41], v[56:57]
	v_pk_mul_f32 v[36:37], v[36:37], v[54:55]
	v_cndmask_b32_e64 v39, v28, v39, s[2:3]
	v_pk_mul_f32 v[28:29], v[30:31], v[56:57]
	v_pk_fma_f32 v[30:31], v[30:31], v[52:53], v[34:35]
	v_pk_fma_f32 v[34:35], v[62:63], v[50:51], v[36:37]
	v_cndmask_b32_e64 v27, v27, v38, s[2:3]
	v_pk_fma_f32 v[28:29], v[40:41], v[52:53], v[28:29] neg_lo:[0,0,1] neg_hi:[0,0,1]
	v_xor_b32_e32 v34, 0x80000000, v34
	v_xor_b32_e32 v35, 0x80000000, v35
	v_xor_b32_e32 v30, 0x80000000, v30
	v_lshl_add_u64 v[40:41], v[20:21], 0, v[18:19]
	v_or_b32_e32 v18, 16, v26
	v_cndmask_b32_e64 v36, v30, v28, s[2:3]
	v_cndmask_b32_e64 v30, v35, v33, s[2:3]
	v_cndmask_b32_e64 v32, v34, v32, s[2:3]
	v_cvt_pk_bf16_f32 v28, v27, v39
	v_lshrrev_b32_e32 v27, 4, v18
	v_cvt_pk_bf16_f32 v30, v32, v30
	v_add_u32_e32 v32, 1, v27
	v_sub_u32_e32 v27, 32, v27
	v_xor_b32_e32 v31, 0x80000000, v31
	v_cndmask_b32_e32 v27, v27, v32, vcc
	v_cndmask_b32_e64 v31, v31, v29, s[2:3]
	v_mad_i32_i24 v27, v27, s0, v25
	v_cvt_pk_bf16_f32 v31, v36, v31
	ds_read_b128 v[32:35], v27
	ds_read_b128 v[36:39], v27 offset:16
	v_cvt_pk_bf16_f32 v29, v43, v42
	global_store_dwordx4 v[40:41], v[28:31], off sc0 sc1
	ds_read_b128 v[28:31], v27 offset:32
	ds_read_b128 v[40:43], v27 offset:48
	s_waitcnt lgkmcnt(3)
	v_mov_b32_e32 v48, v33
	s_waitcnt lgkmcnt(2)
	v_mov_b32_e32 v44, v37
	v_mov_b32_e32 v45, v39
	v_mov_b32_e32 v49, v35
	v_pk_mul_f32 v[46:47], v[16:17], v[44:45]
	v_pk_mul_f32 v[50:51], v[14:15], v[48:49]
	v_mov_b32_e32 v33, v34
	v_mov_b32_e32 v37, v38
	v_pk_fma_f32 v[34:35], v[10:11], v[32:33], v[50:51] neg_lo:[0,0,1] neg_hi:[0,0,1]
	v_pk_fma_f32 v[38:39], v[12:13], v[36:37], v[46:47] neg_lo:[0,0,1] neg_hi:[0,0,1]
	v_pk_mul_f32 v[32:33], v[14:15], v[32:33]
	v_pk_mul_f32 v[36:37], v[16:17], v[36:37]
	v_pk_fma_f32 v[32:33], v[10:11], v[48:49], v[32:33]
	v_pk_fma_f32 v[36:37], v[12:13], v[44:45], v[36:37]
	v_xor_b32_e32 v27, 0x80000000, v32
	v_xor_b32_e32 v32, 0x80000000, v33
	v_xor_b32_e32 v33, 0x80000000, v36
	v_xor_b32_e32 v36, 0x80000000, v37
	v_cndmask_b32_e64 v44, v36, v39, s[2:3]
	s_waitcnt lgkmcnt(1)
	v_mov_b32_e32 v36, v29
	v_mov_b32_e32 v37, v31
	v_cndmask_b32_e64 v45, v33, v38, s[2:3]
	v_cndmask_b32_e64 v46, v32, v35, s[2:3]
	s_waitcnt lgkmcnt(0)
	v_mov_b32_e32 v32, v41
	v_pk_mul_f32 v[38:39], v[6:7], v[36:37]
	v_mov_b32_e32 v29, v30
	v_mov_b32_e32 v41, v42
	v_mov_b32_e32 v33, v43
	v_pk_fma_f32 v[30:31], v[2:3], v[28:29], v[38:39] neg_lo:[0,0,1] neg_hi:[0,0,1]
	v_pk_mul_f32 v[28:29], v[6:7], v[28:29]
	v_pk_mul_f32 v[38:39], v[8:9], v[40:41]
	v_cndmask_b32_e64 v27, v27, v34, s[2:3]
	v_pk_mul_f32 v[34:35], v[8:9], v[32:33]
	v_pk_fma_f32 v[32:33], v[4:5], v[32:33], v[38:39]
	v_pk_fma_f32 v[28:29], v[2:3], v[36:37], v[28:29]
	v_or_b32_e32 v18, v18, v23
	v_pk_fma_f32 v[34:35], v[4:5], v[40:41], v[34:35] neg_lo:[0,0,1] neg_hi:[0,0,1]
	v_xor_b32_e32 v28, 0x80000000, v28
	v_xor_b32_e32 v29, 0x80000000, v29
	v_xor_b32_e32 v32, 0x80000000, v32
	v_xor_b32_e32 v33, 0x80000000, v33
	v_cndmask_b32_e64 v33, v33, v35, s[2:3]
	v_cndmask_b32_e64 v32, v32, v34, s[2:3]
	v_cndmask_b32_e64 v31, v29, v31, s[2:3]
	v_cndmask_b32_e64 v30, v28, v30, s[2:3]
	v_lshlrev_b32_e32 v18, 9, v18
	v_cvt_pk_bf16_f32 v30, v30, v31
	v_cvt_pk_bf16_f32 v31, v32, v33
	v_lshl_add_u64 v[32:33], v[20:21], 0, v[18:19]
	v_or_b32_e32 v18, 20, v26
	v_cvt_pk_bf16_f32 v28, v27, v46
	v_cvt_pk_bf16_f32 v29, v45, v44
	v_or_b32_e32 v27, v18, v23
	v_lshrrev_b32_e32 v18, 4, v18
	global_store_dwordx4 v[32:33], v[28:31], off sc0 sc1
	s_nop 1
	v_add_u32_e32 v28, 1, v18
	v_sub_u32_e32 v18, 32, v18
	v_cndmask_b32_e32 v18, v18, v28, vcc
	v_lshlrev_b32_e32 v28, 8, v27
	v_and_b32_e32 v28, 0x700, v28
	v_add_u32_e32 v48, v24, v28
	v_mad_i32_i24 v18, v18, s0, v25
	ds_read_b128 v[28:31], v48 offset:34832
	ds_read_b128 v[32:35], v48 offset:34848
	ds_read_b128 v[36:39], v18
	ds_read_b128 v[40:43], v18 offset:16
	ds_read_b128 v[44:47], v48 offset:43024
	ds_read_b128 v[48:51], v48 offset:43040
	ds_read_b128 v[52:55], v18 offset:32
	ds_read_b128 v[56:59], v18 offset:48
	s_waitcnt lgkmcnt(5)
	v_mov_b32_e32 v64, v37
	v_mov_b32_e32 v65, v39
	s_waitcnt lgkmcnt(4)
	v_mov_b32_e32 v60, v41
	v_mov_b32_e32 v61, v43
	s_waitcnt lgkmcnt(3)
	v_pk_mul_f32 v[66:67], v[44:45], v[64:65]
	v_mov_b32_e32 v37, v38
	v_pk_mul_f32 v[62:63], v[46:47], v[60:61]
	v_pk_fma_f32 v[38:39], v[28:29], v[36:37], v[66:67] neg_lo:[0,0,1] neg_hi:[0,0,1]
	v_mov_b32_e32 v41, v42
	v_pk_mul_f32 v[36:37], v[44:45], v[36:37]
	v_pk_fma_f32 v[42:43], v[30:31], v[40:41], v[62:63] neg_lo:[0,0,1] neg_hi:[0,0,1]
	v_pk_mul_f32 v[40:41], v[46:47], v[40:41]
	v_pk_fma_f32 v[28:29], v[28:29], v[64:65], v[36:37]
	v_pk_fma_f32 v[30:31], v[30:31], v[60:61], v[40:41]
	v_xor_b32_e32 v18, 0x80000000, v28
	v_xor_b32_e32 v28, 0x80000000, v29
	v_xor_b32_e32 v29, 0x80000000, v30
	v_xor_b32_e32 v30, 0x80000000, v31
	v_cndmask_b32_e64 v46, v28, v39, s[2:3]
	s_waitcnt lgkmcnt(0)
; #define LAS __attribute__((address_space(3)))
; __device__ __forceinline__ u32x4 pack8(const f32x4 v0, const f32x4 v1) { u32x4 w; w.x = pk_f16(v0[0], v0[1]); w.y = pk_f16(v0[2], v0[3]); w.z = pk_f16(v1[0], v1[1]); w.w = pk_f16(v1[2], v1[3]); return w; }
; __device__ __forceinline__ void ssm_tables(LAS float* L, int item, const float* lam_re, const float* lam_im, const float* log_dt, const float* b_re, const float* b_im,
;                                            const float* c_re, const float* c_im, f16* PG, f16* QG, f16* KTH) {
;     ...
;     { const int k0 = (lane & 15) * 8, ri = k0 >> 6, n0 = k0 & 63;
;       for (int it = 0; it < 16; ++it) { const int nrow = wave * 64 + it * 4 + (lane >> 4), s = nrow >> 4, h = nrow & 15; const int e = dir == 0 ? s + 1 : TC - s;
;         const LAS f32x4* crp = (const LAS f32x4*)(L + T_CR + dir * 1024 + h * 64 + n0); const LAS f32x4* cip = (const LAS f32x4*)(L + T_CI + dir * 1024 + h * 64 + n0);
;         const LAS f32x4* app = (const LAS f32x4*)(L + T_AP + e * APS + 2 * n0);
;         const f32x4 cr0 = crp[0], cr1 = crp[1], ci0 = cip[0], ci1 = cip[1], a0 = app[0], a1 = app[1], a2 = app[2], a3 = app[3];
;         const f32x4 pr0 = {a0[0], a0[2], a1[0], a1[2]}, pi0 = {a0[1], a0[3], a1[1], a1[3]}, pr1 = {a2[0], a2[2], a3[0], a3[2]}, pi1 = {a2[1], a2[3], a3[1], a3[3]};
;         const f32x4 v0 = ri == 0 ? cr0 * pr0 - ci0 * pi0 : -(cr0 * pi0 + ci0 * pr0), v1 = ri == 0 ? cr1 * pr1 - ci1 * pi1 : -(cr1 * pi1 + ci1 * pr1);
;         *(u32x4*)(QGg + (size_t)nrow * 256 + dir * 128 + k0) = pack8(v0, v1); } }
	v_mov_b32_e32 v28, v57
	v_mov_b32_e32 v36, v53
	v_mov_b32_e32 v37, v55
	v_mov_b32_e32 v53, v54
	v_mov_b32_e32 v57, v58
	v_cndmask_b32_e64 v44, v30, v43, s[2:3]
	v_cndmask_b32_e64 v45, v29, v42, s[2:3]
	v_cndmask_b32_e64 v18, v18, v38, s[2:3]
	v_mov_b32_e32 v29, v59
	v_pk_mul_f32 v[38:39], v[48:49], v[36:37]
	v_pk_mul_f32 v[40:41], v[50:51], v[56:57]
	v_pk_mul_f32 v[42:43], v[48:49], v[52:53]
	v_pk_mul_f32 v[30:31], v[50:51], v[28:29]
	v_pk_fma_f32 v[38:39], v[32:33], v[52:53], v[38:39] neg_lo:[0,0,1] neg_hi:[0,0,1]
	v_pk_fma_f32 v[28:29], v[34:35], v[28:29], v[40:41]
	v_pk_fma_f32 v[32:33], v[32:33], v[36:37], v[42:43]
	v_pk_fma_f32 v[30:31], v[34:35], v[56:57], v[30:31] neg_lo:[0,0,1] neg_hi:[0,0,1]
	v_xor_b32_e32 v32, 0x80000000, v32
	v_xor_b32_e32 v33, 0x80000000, v33
	v_xor_b32_e32 v28, 0x80000000, v28
	v_xor_b32_e32 v29, 0x80000000, v29
	v_cndmask_b32_e64 v34, v28, v30, s[2:3]
	v_cndmask_b32_e64 v30, v33, v39, s[2:3]
	v_cndmask_b32_e64 v32, v32, v38, s[2:3]
	v_cvt_pk_bf16_f32 v28, v18, v46
	v_lshlrev_b32_e32 v18, 9, v27
	v_cndmask_b32_e64 v31, v29, v31, s[2:3]
	v_cvt_pk_bf16_f32 v30, v32, v30
	v_lshl_add_u64 v[32:33], v[20:21], 0, v[18:19]
	v_or_b32_e32 v18, 24, v26
	v_cvt_pk_bf16_f32 v29, v45, v44
	v_cvt_pk_bf16_f32 v31, v34, v31
	v_or_b32_e32 v27, v18, v23
	v_lshrrev_b32_e32 v18, 4, v18
	global_store_dwordx4 v[32:33], v[28:31], off sc0 sc1
	s_nop 1
	v_add_u32_e32 v28, 1, v18
	v_sub_u32_e32 v18, 32, v18
	v_cndmask_b32_e32 v18, v18, v28, vcc
	v_lshlrev_b32_e32 v28, 8, v27
	v_and_b32_e32 v28, 0xb00, v28
	v_add_u32_e32 v48, v24, v28
	v_mad_i32_i24 v18, v18, s0, v25
	ds_read_b128 v[28:31], v48 offset:34832
	ds_read_b128 v[32:35], v48 offset:34848
	ds_read_b128 v[36:39], v18
	ds_read_b128 v[40:43], v18 offset:16
	ds_read_b128 v[44:47], v48 offset:43024
	ds_read_b128 v[48:51], v48 offset:43040
	ds_read_b128 v[52:55], v18 offset:32
	ds_read_b128 v[56:59], v18 offset:48
	s_waitcnt lgkmcnt(5)
	v_mov_b32_e32 v64, v37
	v_mov_b32_e32 v65, v39
	s_waitcnt lgkmcnt(4)
	v_mov_b32_e32 v60, v41
	v_mov_b32_e32 v61, v43
	s_waitcnt lgkmcnt(3)
	v_pk_mul_f32 v[66:67], v[44:45], v[64:65]
	v_mov_b32_e32 v37, v38
	v_pk_mul_f32 v[62:63], v[46:47], v[60:61]
	v_pk_fma_f32 v[38:39], v[28:29], v[36:37], v[66:67] neg_lo:[0,0,1] neg_hi:[0,0,1]
	v_mov_b32_e32 v41, v42
	v_pk_mul_f32 v[36:37], v[44:45], v[36:37]
	v_pk_fma_f32 v[42:43], v[30:31], v[40:41], v[62:63] neg_lo:[0,0,1] neg_hi:[0,0,1]
	v_pk_mul_f32 v[40:41], v[46:47], v[40:41]
	v_pk_fma_f32 v[28:29], v[28:29], v[64:65], v[36:37]
	v_pk_fma_f32 v[30:31], v[30:31], v[60:61], v[40:41]
	v_xor_b32_e32 v18, 0x80000000, v28
	v_xor_b32_e32 v28, 0x80000000, v29
	v_xor_b32_e32 v29, 0x80000000, v30
	v_xor_b32_e32 v30, 0x80000000, v31
	v_cndmask_b32_e64 v46, v28, v39, s[2:3]
	s_waitcnt lgkmcnt(0)
	v_mov_b32_e32 v28, v57
	v_mov_b32_e32 v36, v53
	v_mov_b32_e32 v37, v55
	v_mov_b32_e32 v53, v54
	v_mov_b32_e32 v57, v58
	v_cndmask_b32_e64 v44, v30, v43, s[2:3]
	v_cndmask_b32_e64 v45, v29, v42, s[2:3]
	v_cndmask_b32_e64 v18, v18, v38, s[2:3]
	v_mov_b32_e32 v29, v59
	v_pk_mul_f32 v[38:39], v[48:49], v[36:37]
	v_pk_mul_f32 v[40:41], v[50:51], v[56:57]
	v_pk_mul_f32 v[42:43], v[48:49], v[52:53]
	v_pk_mul_f32 v[30:31], v[50:51], v[28:29]
	v_pk_fma_f32 v[38:39], v[32:33], v[52:53], v[38:39] neg_lo:[0,0,1] neg_hi:[0,0,1]
	v_pk_fma_f32 v[28:29], v[34:35], v[28:29], v[40:41]
	v_pk_fma_f32 v[32:33], v[32:33], v[36:37], v[42:43]
	v_pk_fma_f32 v[30:31], v[34:35], v[56:57], v[30:31] neg_lo:[0,0,1] neg_hi:[0,0,1]
	v_xor_b32_e32 v32, 0x80000000, v32
	v_xor_b32_e32 v33, 0x80000000, v33
	v_xor_b32_e32 v28, 0x80000000, v28
	v_xor_b32_e32 v29, 0x80000000, v29
	v_cndmask_b32_e64 v34, v28, v30, s[2:3]
	v_cndmask_b32_e64 v30, v33, v39, s[2:3]
	v_cndmask_b32_e64 v32, v32, v38, s[2:3]
	v_cvt_pk_bf16_f32 v28, v18, v46
	v_lshlrev_b32_e32 v18, 9, v27
	v_cndmask_b32_e64 v31, v29, v31, s[2:3]
	v_cvt_pk_bf16_f32 v30, v32, v30
	v_lshl_add_u64 v[32:33], v[20:21], 0, v[18:19]
	v_or_b32_e32 v18, 28, v26
	v_cvt_pk_bf16_f32 v29, v45, v44
	v_cvt_pk_bf16_f32 v31, v34, v31
	v_or_b32_e32 v27, v18, v23
	v_lshrrev_b32_e32 v18, 4, v18
	global_store_dwordx4 v[32:33], v[28:31], off sc0 sc1
	s_nop 1
	v_add_u32_e32 v28, 1, v18
	v_sub_u32_e32 v18, 32, v18
	v_cndmask_b32_e32 v18, v18, v28, vcc
	v_lshlrev_b32_e32 v28, 8, v27
	v_and_b32_e32 v28, 0xf00, v28
	v_add_u32_e32 v48, v24, v28
	v_mad_i32_i24 v18, v18, s0, v25
	ds_read_b128 v[28:31], v48 offset:34832
	ds_read_b128 v[32:35], v48 offset:34848
	ds_read_b128 v[36:39], v18
	ds_read_b128 v[40:43], v18 offset:16
	ds_read_b128 v[44:47], v48 offset:43024
	ds_read_b128 v[48:51], v48 offset:43040
	ds_read_b128 v[52:55], v18 offset:32
	ds_read_b128 v[56:59], v18 offset:48
	s_waitcnt lgkmcnt(5)
	v_mov_b32_e32 v64, v37
	v_mov_b32_e32 v65, v39
	s_waitcnt lgkmcnt(4)
	v_mov_b32_e32 v60, v41
	v_mov_b32_e32 v61, v43
	s_waitcnt lgkmcnt(3)
	v_pk_mul_f32 v[66:67], v[44:45], v[64:65]
	v_mov_b32_e32 v37, v38
	v_pk_mul_f32 v[62:63], v[46:47], v[60:61]
	v_pk_fma_f32 v[38:39], v[28:29], v[36:37], v[66:67] neg_lo:[0,0,1] neg_hi:[0,0,1]
	v_mov_b32_e32 v41, v42
	v_pk_mul_f32 v[36:37], v[44:45], v[36:37]
	v_pk_fma_f32 v[42:43], v[30:31], v[40:41], v[62:63] neg_lo:[0,0,1] neg_hi:[0,0,1]
	v_pk_mul_f32 v[40:41], v[46:47], v[40:41]
	v_pk_fma_f32 v[28:29], v[28:29], v[64:65], v[36:37]
	v_pk_fma_f32 v[30:31], v[30:31], v[60:61], v[40:41]
	v_xor_b32_e32 v18, 0x80000000, v28
	v_xor_b32_e32 v28, 0x80000000, v29
	v_xor_b32_e32 v29, 0x80000000, v30
	v_cndmask_b32_e64 v46, v28, v39, s[2:3]
	s_waitcnt lgkmcnt(0)
; #define LAS __attribute__((address_space(3)))
; __device__ __forceinline__ u32x4 pack8(const f32x4 v0, const f32x4 v1) { u32x4 w; w.x = pk_f16(v0[0], v0[1]); w.y = pk_f16(v0[2], v0[3]); w.z = pk_f16(v1[0], v1[1]); w.w = pk_f16(v1[2], v1[3]); return w; }
; __device__ __forceinline__ void ssm_tables(LAS float* L, int item, const float* lam_re, const float* lam_im, const float* log_dt, const float* b_re, const float* b_im,
;                                            const float* c_re, const float* c_im, f16* PG, f16* QG, f16* KTH) {
;     ...
;     { const int k0 = (lane & 15) * 8, ri = k0 >> 6, n0 = k0 & 63;
;       for (int it = 0; it < 16; ++it) { const int nrow = wave * 64 + it * 4 + (lane >> 4), s = nrow >> 4, h = nrow & 15; const int e = dir == 0 ? s + 1 : TC - s;
;         const LAS f32x4* crp = (const LAS f32x4*)(L + T_CR + dir * 1024 + h * 64 + n0); const LAS f32x4* cip = (const LAS f32x4*)(L + T_CI + dir * 1024 + h * 64 + n0);
;         const LAS f32x4* app = (const LAS f32x4*)(L + T_AP + e * APS + 2 * n0);
;         const f32x4 cr0 = crp[0], cr1 = crp[1], ci0 = cip[0], ci1 = cip[1], a0 = app[0], a1 = app[1], a2 = app[2], a3 = app[3];
;         const f32x4 pr0 = {a0[0], a0[2], a1[0], a1[2]}, pi0 = {a0[1], a0[3], a1[1], a1[3]}, pr1 = {a2[0], a2[2], a3[0], a3[2]}, pi1 = {a2[1], a2[3], a3[1], a3[3]};
;         const f32x4 v0 = ri == 0 ? cr0 * pr0 - ci0 * pi0 : -(cr0 * pi0 + ci0 * pr0), v1 = ri == 0 ? cr1 * pr1 - ci1 * pi1 : -(cr1 * pi1 + ci1 * pr1);
;         *(u32x4*)(QGg + (size_t)nrow * 256 + dir * 128 + k0) = pack8(v0, v1); } }
	v_mov_b32_e32 v28, v57
	v_mov_b32_e32 v57, v58
	v_xor_b32_e32 v30, 0x80000000, v31
	v_cndmask_b32_e64 v45, v29, v42, s[2:3]
	v_mov_b32_e32 v29, v59
	v_pk_mul_f32 v[40:41], v[50:51], v[56:57]
	v_cndmask_b32_e64 v44, v30, v43, s[2:3]
	v_pk_mul_f32 v[30:31], v[50:51], v[28:29]
	v_mov_b32_e32 v36, v53
	v_mov_b32_e32 v37, v55
	v_mov_b32_e32 v53, v54
	v_pk_fma_f32 v[28:29], v[34:35], v[28:29], v[40:41]
	v_cndmask_b32_e64 v18, v18, v38, s[2:3]
	v_pk_mul_f32 v[38:39], v[48:49], v[36:37]
	v_pk_fma_f32 v[30:31], v[34:35], v[56:57], v[30:31] neg_lo:[0,0,1] neg_hi:[0,0,1]
	v_pk_mul_f32 v[42:43], v[48:49], v[52:53]
	v_xor_b32_e32 v28, 0x80000000, v28
	v_pk_fma_f32 v[38:39], v[32:33], v[52:53], v[38:39] neg_lo:[0,0,1] neg_hi:[0,0,1]
	v_pk_fma_f32 v[32:33], v[32:33], v[36:37], v[42:43]
	v_cndmask_b32_e64 v34, v28, v30, s[2:3]
	v_cvt_pk_bf16_f32 v28, v18, v46
	v_lshlrev_b32_e32 v18, 9, v27
	v_xor_b32_e32 v32, 0x80000000, v32
	v_xor_b32_e32 v33, 0x80000000, v33
	v_lshl_add_u64 v[40:41], v[20:21], 0, v[18:19]
	v_or_b32_e32 v18, 32, v26
	v_cndmask_b32_e64 v30, v33, v39, s[2:3]
	v_cndmask_b32_e64 v32, v32, v38, s[2:3]
	v_lshrrev_b32_e32 v27, 4, v18
	v_cvt_pk_bf16_f32 v30, v32, v30
	v_or_b32_e32 v32, 1, v27
	v_sub_u32_e32 v27, 32, v27
	v_xor_b32_e32 v29, 0x80000000, v29
	v_cndmask_b32_e32 v27, v27, v32, vcc
	v_cndmask_b32_e64 v31, v29, v31, s[2:3]
	v_mad_i32_i24 v27, v27, s0, v25
	v_cvt_pk_bf16_f32 v31, v34, v31
	ds_read_b128 v[32:35], v27
	ds_read_b128 v[36:39], v27 offset:16
	v_cvt_pk_bf16_f32 v29, v45, v44
	global_store_dwordx4 v[40:41], v[28:31], off sc0 sc1
	ds_read_b128 v[28:31], v27 offset:32
	ds_read_b128 v[40:43], v27 offset:48
	s_waitcnt lgkmcnt(3)
	v_mov_b32_e32 v48, v33
	s_waitcnt lgkmcnt(2)
	v_mov_b32_e32 v44, v37
	v_mov_b32_e32 v45, v39
	v_mov_b32_e32 v49, v35
	v_pk_mul_f32 v[46:47], v[16:17], v[44:45]
	v_pk_mul_f32 v[50:51], v[14:15], v[48:49]
	v_mov_b32_e32 v33, v34
	v_mov_b32_e32 v37, v38
	v_pk_fma_f32 v[34:35], v[10:11], v[32:33], v[50:51] neg_lo:[0,0,1] neg_hi:[0,0,1]
	v_pk_fma_f32 v[38:39], v[12:13], v[36:37], v[46:47] neg_lo:[0,0,1] neg_hi:[0,0,1]
	v_pk_mul_f32 v[32:33], v[14:15], v[32:33]
	v_pk_mul_f32 v[36:37], v[16:17], v[36:37]
	v_pk_fma_f32 v[32:33], v[10:11], v[48:49], v[32:33]
	v_pk_fma_f32 v[36:37], v[12:13], v[44:45], v[36:37]
	v_xor_b32_e32 v27, 0x80000000, v32
	v_xor_b32_e32 v32, 0x80000000, v33
	v_xor_b32_e32 v33, 0x80000000, v36
	v_xor_b32_e32 v36, 0x80000000, v37
	v_cndmask_b32_e64 v44, v36, v39, s[2:3]
	s_waitcnt lgkmcnt(1)
	v_mov_b32_e32 v36, v29
	v_mov_b32_e32 v37, v31
	v_cndmask_b32_e64 v45, v33, v38, s[2:3]
	v_cndmask_b32_e64 v46, v32, v35, s[2:3]
	s_waitcnt lgkmcnt(0)
	v_mov_b32_e32 v32, v41
	v_pk_mul_f32 v[38:39], v[6:7], v[36:37]
	v_mov_b32_e32 v29, v30
	v_mov_b32_e32 v41, v42
	v_mov_b32_e32 v33, v43
	v_pk_fma_f32 v[30:31], v[2:3], v[28:29], v[38:39] neg_lo:[0,0,1] neg_hi:[0,0,1]
	v_pk_mul_f32 v[28:29], v[6:7], v[28:29]
	v_pk_mul_f32 v[38:39], v[8:9], v[40:41]
	v_cndmask_b32_e64 v27, v27, v34, s[2:3]
	v_pk_mul_f32 v[34:35], v[8:9], v[32:33]
	v_pk_fma_f32 v[32:33], v[4:5], v[32:33], v[38:39]
	v_pk_fma_f32 v[28:29], v[2:3], v[36:37], v[28:29]
	v_or_b32_e32 v18, v18, v23
	v_pk_fma_f32 v[34:35], v[4:5], v[40:41], v[34:35] neg_lo:[0,0,1] neg_hi:[0,0,1]
	v_xor_b32_e32 v28, 0x80000000, v28
	v_xor_b32_e32 v29, 0x80000000, v29
	v_xor_b32_e32 v32, 0x80000000, v32
	v_xor_b32_e32 v33, 0x80000000, v33
	v_cndmask_b32_e64 v33, v33, v35, s[2:3]
	v_cndmask_b32_e64 v32, v32, v34, s[2:3]
	v_cndmask_b32_e64 v31, v29, v31, s[2:3]
	v_cndmask_b32_e64 v30, v28, v30, s[2:3]
	v_lshlrev_b32_e32 v18, 9, v18
	v_cvt_pk_bf16_f32 v30, v30, v31
	v_cvt_pk_bf16_f32 v31, v32, v33
	v_lshl_add_u64 v[32:33], v[20:21], 0, v[18:19]
	v_or_b32_e32 v18, 36, v26
	v_cvt_pk_bf16_f32 v28, v27, v46
	v_cvt_pk_bf16_f32 v29, v45, v44
	v_or_b32_e32 v27, v18, v23
	v_lshrrev_b32_e32 v18, 4, v18
	global_store_dwordx4 v[32:33], v[28:31], off sc0 sc1
	s_nop 1
	v_or_b32_e32 v28, 1, v18
	v_sub_u32_e32 v18, 32, v18
	v_cndmask_b32_e32 v18, v18, v28, vcc
	v_lshlrev_b32_e32 v28, 8, v27
	v_and_b32_e32 v28, 0x700, v28
	v_add_u32_e32 v48, v24, v28
	v_mad_i32_i24 v18, v18, s0, v25
	ds_read_b128 v[28:31], v48 offset:34832
	ds_read_b128 v[32:35], v48 offset:34848
	ds_read_b128 v[36:39], v18
	ds_read_b128 v[40:43], v18 offset:16
	ds_read_b128 v[44:47], v48 offset:43024
	ds_read_b128 v[48:51], v48 offset:43040
	ds_read_b128 v[52:55], v18 offset:32
	ds_read_b128 v[56:59], v18 offset:48
	s_waitcnt lgkmcnt(5)
	v_mov_b32_e32 v64, v37
	v_mov_b32_e32 v65, v39
	s_waitcnt lgkmcnt(4)
	v_mov_b32_e32 v60, v41
	v_mov_b32_e32 v61, v43
	s_waitcnt lgkmcnt(3)
	v_pk_mul_f32 v[66:67], v[44:45], v[64:65]
	v_mov_b32_e32 v37, v38
	v_pk_mul_f32 v[62:63], v[46:47], v[60:61]
	v_pk_fma_f32 v[38:39], v[28:29], v[36:37], v[66:67] neg_lo:[0,0,1] neg_hi:[0,0,1]
	v_mov_b32_e32 v41, v42
	v_pk_mul_f32 v[36:37], v[44:45], v[36:37]
	v_pk_fma_f32 v[42:43], v[30:31], v[40:41], v[62:63] neg_lo:[0,0,1] neg_hi:[0,0,1]
	v_pk_mul_f32 v[40:41], v[46:47], v[40:41]
	v_pk_fma_f32 v[28:29], v[28:29], v[64:65], v[36:37]
	v_pk_fma_f32 v[30:31], v[30:31], v[60:61], v[40:41]
	v_xor_b32_e32 v18, 0x80000000, v28
	v_xor_b32_e32 v28, 0x80000000, v29
	v_xor_b32_e32 v29, 0x80000000, v30
	v_xor_b32_e32 v30, 0x80000000, v31
	v_cndmask_b32_e64 v46, v28, v39, s[2:3]
	s_waitcnt lgkmcnt(0)
; #define LAS __attribute__((address_space(3)))
; __device__ __forceinline__ u32x4 pack8(const f32x4 v0, const f32x4 v1) { u32x4 w; w.x = pk_f16(v0[0], v0[1]); w.y = pk_f16(v0[2], v0[3]); w.z = pk_f16(v1[0], v1[1]); w.w = pk_f16(v1[2], v1[3]); return w; }
; __device__ __forceinline__ void ssm_tables(LAS float* L, int item, const float* lam_re, const float* lam_im, const float* log_dt, const float* b_re, const float* b_im,
;                                            const float* c_re, const float* c_im, f16* PG, f16* QG, f16* KTH) {
;     ...
;     { const int k0 = (lane & 15) * 8, ri = k0 >> 6, n0 = k0 & 63;
;       for (int it = 0; it < 16; ++it) { const int nrow = wave * 64 + it * 4 + (lane >> 4), s = nrow >> 4, h = nrow & 15; const int e = dir == 0 ? s + 1 : TC - s;
;         const LAS f32x4* crp = (const LAS f32x4*)(L + T_CR + dir * 1024 + h * 64 + n0); const LAS f32x4* cip = (const LAS f32x4*)(L + T_CI + dir * 1024 + h * 64 + n0);
;         const LAS f32x4* app = (const LAS f32x4*)(L + T_AP + e * APS + 2 * n0);
;         const f32x4 cr0 = crp[0], cr1 = crp[1], ci0 = cip[0], ci1 = cip[1], a0 = app[0], a1 = app[1], a2 = app[2], a3 = app[3];
;         const f32x4 pr0 = {a0[0], a0[2], a1[0], a1[2]}, pi0 = {a0[1], a0[3], a1[1], a1[3]}, pr1 = {a2[0], a2[2], a3[0], a3[2]}, pi1 = {a2[1], a2[3], a3[1], a3[3]};
;         const f32x4 v0 = ri == 0 ? cr0 * pr0 - ci0 * pi0 : -(cr0 * pi0 + ci0 * pr0), v1 = ri == 0 ? cr1 * pr1 - ci1 * pi1 : -(cr1 * pi1 + ci1 * pr1);
;         *(u32x4*)(QGg + (size_t)nrow * 256 + dir * 128 + k0) = pack8(v0, v1); } }
	v_mov_b32_e32 v28, v57
	v_mov_b32_e32 v36, v53
	v_mov_b32_e32 v37, v55
	v_mov_b32_e32 v53, v54
	v_mov_b32_e32 v57, v58
	v_cndmask_b32_e64 v44, v30, v43, s[2:3]
	v_cndmask_b32_e64 v45, v29, v42, s[2:3]
	v_cndmask_b32_e64 v18, v18, v38, s[2:3]
	v_mov_b32_e32 v29, v59
	v_pk_mul_f32 v[38:39], v[48:49], v[36:37]
	v_pk_mul_f32 v[40:41], v[50:51], v[56:57]
	v_pk_mul_f32 v[42:43], v[48:49], v[52:53]
	v_pk_mul_f32 v[30:31], v[50:51], v[28:29]
	v_pk_fma_f32 v[38:39], v[32:33], v[52:53], v[38:39] neg_lo:[0,0,1] neg_hi:[0,0,1]
	v_pk_fma_f32 v[28:29], v[34:35], v[28:29], v[40:41]
	v_pk_fma_f32 v[32:33], v[32:33], v[36:37], v[42:43]
	v_pk_fma_f32 v[30:31], v[34:35], v[56:57], v[30:31] neg_lo:[0,0,1] neg_hi:[0,0,1]
	v_xor_b32_e32 v32, 0x80000000, v32
	v_xor_b32_e32 v33, 0x80000000, v33
	v_xor_b32_e32 v28, 0x80000000, v28
	v_xor_b32_e32 v29, 0x80000000, v29
	v_cndmask_b32_e64 v34, v28, v30, s[2:3]
	v_cndmask_b32_e64 v30, v33, v39, s[2:3]
	v_cndmask_b32_e64 v32, v32, v38, s[2:3]
	v_cvt_pk_bf16_f32 v28, v18, v46
	v_lshlrev_b32_e32 v18, 9, v27
	v_cndmask_b32_e64 v31, v29, v31, s[2:3]
	v_cvt_pk_bf16_f32 v30, v32, v30
	v_lshl_add_u64 v[32:33], v[20:21], 0, v[18:19]
	v_or_b32_e32 v18, 40, v26
	v_cvt_pk_bf16_f32 v29, v45, v44
	v_cvt_pk_bf16_f32 v31, v34, v31
	v_or_b32_e32 v27, v18, v23
	v_lshrrev_b32_e32 v18, 4, v18
	global_store_dwordx4 v[32:33], v[28:31], off sc0 sc1
	s_nop 1
	v_or_b32_e32 v28, 1, v18
	v_sub_u32_e32 v18, 32, v18
	v_cndmask_b32_e32 v18, v18, v28, vcc
	v_lshlrev_b32_e32 v28, 8, v27
	v_and_b32_e32 v28, 0xb00, v28
	v_add_u32_e32 v48, v24, v28
	v_mad_i32_i24 v18, v18, s0, v25
	ds_read_b128 v[28:31], v48 offset:34832
	ds_read_b128 v[32:35], v48 offset:34848
	ds_read_b128 v[36:39], v18
	ds_read_b128 v[40:43], v18 offset:16
	ds_read_b128 v[44:47], v48 offset:43024
	ds_read_b128 v[48:51], v48 offset:43040
	ds_read_b128 v[52:55], v18 offset:32
	ds_read_b128 v[56:59], v18 offset:48
	s_waitcnt lgkmcnt(5)
	v_mov_b32_e32 v64, v37
	v_mov_b32_e32 v65, v39
	s_waitcnt lgkmcnt(4)
	v_mov_b32_e32 v60, v41
	v_mov_b32_e32 v61, v43
	s_waitcnt lgkmcnt(3)
	v_pk_mul_f32 v[66:67], v[44:45], v[64:65]
	v_mov_b32_e32 v37, v38
	v_pk_mul_f32 v[62:63], v[46:47], v[60:61]
	v_pk_fma_f32 v[38:39], v[28:29], v[36:37], v[66:67] neg_lo:[0,0,1] neg_hi:[0,0,1]
	v_mov_b32_e32 v41, v42
	v_pk_mul_f32 v[36:37], v[44:45], v[36:37]
	v_pk_fma_f32 v[42:43], v[30:31], v[40:41], v[62:63] neg_lo:[0,0,1] neg_hi:[0,0,1]
	v_pk_mul_f32 v[40:41], v[46:47], v[40:41]
	v_pk_fma_f32 v[28:29], v[28:29], v[64:65], v[36:37]
	v_pk_fma_f32 v[30:31], v[30:31], v[60:61], v[40:41]
	v_xor_b32_e32 v18, 0x80000000, v28
	v_xor_b32_e32 v28, 0x80000000, v29
	v_xor_b32_e32 v29, 0x80000000, v30
	v_xor_b32_e32 v30, 0x80000000, v31
	v_cndmask_b32_e64 v46, v28, v39, s[2:3]
	s_waitcnt lgkmcnt(0)
	v_mov_b32_e32 v28, v57
	v_mov_b32_e32 v36, v53
	v_mov_b32_e32 v37, v55
	v_mov_b32_e32 v53, v54
	v_mov_b32_e32 v57, v58
	v_cndmask_b32_e64 v44, v30, v43, s[2:3]
	v_cndmask_b32_e64 v45, v29, v42, s[2:3]
	v_cndmask_b32_e64 v18, v18, v38, s[2:3]
	v_mov_b32_e32 v29, v59
	v_pk_mul_f32 v[38:39], v[48:49], v[36:37]
	v_pk_mul_f32 v[40:41], v[50:51], v[56:57]
	v_pk_mul_f32 v[42:43], v[48:49], v[52:53]
	v_pk_mul_f32 v[30:31], v[50:51], v[28:29]
	v_pk_fma_f32 v[38:39], v[32:33], v[52:53], v[38:39] neg_lo:[0,0,1] neg_hi:[0,0,1]
	v_pk_fma_f32 v[28:29], v[34:35], v[28:29], v[40:41]
	v_pk_fma_f32 v[32:33], v[32:33], v[36:37], v[42:43]
	v_pk_fma_f32 v[30:31], v[34:35], v[56:57], v[30:31] neg_lo:[0,0,1] neg_hi:[0,0,1]
	v_xor_b32_e32 v32, 0x80000000, v32
	v_xor_b32_e32 v33, 0x80000000, v33
	v_xor_b32_e32 v28, 0x80000000, v28
	v_xor_b32_e32 v29, 0x80000000, v29
	v_cndmask_b32_e64 v34, v28, v30, s[2:3]
	v_cndmask_b32_e64 v30, v33, v39, s[2:3]
	v_cndmask_b32_e64 v32, v32, v38, s[2:3]
	v_cvt_pk_bf16_f32 v28, v18, v46
	v_lshlrev_b32_e32 v18, 9, v27
	v_cndmask_b32_e64 v31, v29, v31, s[2:3]
	v_cvt_pk_bf16_f32 v30, v32, v30
	v_lshl_add_u64 v[32:33], v[20:21], 0, v[18:19]
	v_or_b32_e32 v18, 44, v26
	v_cvt_pk_bf16_f32 v29, v45, v44
	v_cvt_pk_bf16_f32 v31, v34, v31
	v_or_b32_e32 v27, v18, v23
	v_lshrrev_b32_e32 v18, 4, v18
	global_store_dwordx4 v[32:33], v[28:31], off sc0 sc1
	s_nop 1
	v_or_b32_e32 v28, 1, v18
	v_sub_u32_e32 v18, 32, v18
	v_cndmask_b32_e32 v18, v18, v28, vcc
	v_lshlrev_b32_e32 v28, 8, v27
	v_and_b32_e32 v28, 0xf00, v28
	v_add_u32_e32 v48, v24, v28
	v_mad_i32_i24 v18, v18, s0, v25
	ds_read_b128 v[28:31], v48 offset:34832
	ds_read_b128 v[32:35], v48 offset:34848
	ds_read_b128 v[36:39], v18
	ds_read_b128 v[40:43], v18 offset:16
	ds_read_b128 v[44:47], v48 offset:43024
	ds_read_b128 v[48:51], v48 offset:43040
	ds_read_b128 v[52:55], v18 offset:32
	ds_read_b128 v[56:59], v18 offset:48
	s_waitcnt lgkmcnt(5)
	v_mov_b32_e32 v64, v37
	v_mov_b32_e32 v65, v39
	s_waitcnt lgkmcnt(4)
	v_mov_b32_e32 v60, v41
	v_mov_b32_e32 v61, v43
	s_waitcnt lgkmcnt(3)
	v_pk_mul_f32 v[66:67], v[44:45], v[64:65]
	v_mov_b32_e32 v37, v38
	v_pk_mul_f32 v[62:63], v[46:47], v[60:61]
	v_pk_fma_f32 v[38:39], v[28:29], v[36:37], v[66:67] neg_lo:[0,0,1] neg_hi:[0,0,1]
	v_mov_b32_e32 v41, v42
	v_pk_mul_f32 v[36:37], v[44:45], v[36:37]
	v_pk_fma_f32 v[42:43], v[30:31], v[40:41], v[62:63] neg_lo:[0,0,1] neg_hi:[0,0,1]
	v_pk_mul_f32 v[40:41], v[46:47], v[40:41]
	v_pk_fma_f32 v[28:29], v[28:29], v[64:65], v[36:37]
	v_pk_fma_f32 v[30:31], v[30:31], v[60:61], v[40:41]
	v_xor_b32_e32 v18, 0x80000000, v28
	v_xor_b32_e32 v28, 0x80000000, v29
	v_xor_b32_e32 v29, 0x80000000, v30
	v_cndmask_b32_e64 v46, v28, v39, s[2:3]
	s_waitcnt lgkmcnt(0)
; #define LAS __attribute__((address_space(3)))
; __device__ __forceinline__ u32x4 pack8(const f32x4 v0, const f32x4 v1) { u32x4 w; w.x = pk_f16(v0[0], v0[1]); w.y = pk_f16(v0[2], v0[3]); w.z = pk_f16(v1[0], v1[1]); w.w = pk_f16(v1[2], v1[3]); return w; }
; __device__ __forceinline__ void ssm_tables(LAS float* L, int item, const float* lam_re, const float* lam_im, const float* log_dt, const float* b_re, const float* b_im,
;                                            const float* c_re, const float* c_im, f16* PG, f16* QG, f16* KTH) {
;     ...
;     { const int k0 = (lane & 15) * 8, ri = k0 >> 6, n0 = k0 & 63;
;       for (int it = 0; it < 16; ++it) { const int nrow = wave * 64 + it * 4 + (lane >> 4), s = nrow >> 4, h = nrow & 15; const int e = dir == 0 ? s + 1 : TC - s;
;         const LAS f32x4* crp = (const LAS f32x4*)(L + T_CR + dir * 1024 + h * 64 + n0); const LAS f32x4* cip = (const LAS f32x4*)(L + T_CI + dir * 1024 + h * 64 + n0);
;         const LAS f32x4* app = (const LAS f32x4*)(L + T_AP + e * APS + 2 * n0);
;         const f32x4 cr0 = crp[0], cr1 = crp[1], ci0 = cip[0], ci1 = cip[1], a0 = app[0], a1 = app[1], a2 = app[2], a3 = app[3];
;         const f32x4 pr0 = {a0[0], a0[2], a1[0], a1[2]}, pi0 = {a0[1], a0[3], a1[1], a1[3]}, pr1 = {a2[0], a2[2], a3[0], a3[2]}, pi1 = {a2[1], a2[3], a3[1], a3[3]};
;         const f32x4 v0 = ri == 0 ? cr0 * pr0 - ci0 * pi0 : -(cr0 * pi0 + ci0 * pr0), v1 = ri == 0 ? cr1 * pr1 - ci1 * pi1 : -(cr1 * pi1 + ci1 * pr1);
;         *(u32x4*)(QGg + (size_t)nrow * 256 + dir * 128 + k0) = pack8(v0, v1); } }
	v_mov_b32_e32 v28, v57
	v_mov_b32_e32 v57, v58
	v_xor_b32_e32 v30, 0x80000000, v31
	v_cndmask_b32_e64 v45, v29, v42, s[2:3]
	v_mov_b32_e32 v29, v59
	v_pk_mul_f32 v[40:41], v[50:51], v[56:57]
	v_cndmask_b32_e64 v44, v30, v43, s[2:3]
	v_pk_mul_f32 v[30:31], v[50:51], v[28:29]
	v_mov_b32_e32 v36, v53
	v_mov_b32_e32 v37, v55
	v_mov_b32_e32 v53, v54
	v_pk_fma_f32 v[28:29], v[34:35], v[28:29], v[40:41]
	v_cndmask_b32_e64 v18, v18, v38, s[2:3]
	v_pk_mul_f32 v[38:39], v[48:49], v[36:37]
	v_pk_fma_f32 v[30:31], v[34:35], v[56:57], v[30:31] neg_lo:[0,0,1] neg_hi:[0,0,1]
	v_pk_mul_f32 v[42:43], v[48:49], v[52:53]
	v_xor_b32_e32 v28, 0x80000000, v28
	v_pk_fma_f32 v[38:39], v[32:33], v[52:53], v[38:39] neg_lo:[0,0,1] neg_hi:[0,0,1]
	v_pk_fma_f32 v[32:33], v[32:33], v[36:37], v[42:43]
	v_cndmask_b32_e64 v34, v28, v30, s[2:3]
	v_cvt_pk_bf16_f32 v28, v18, v46
	v_lshlrev_b32_e32 v18, 9, v27
	v_xor_b32_e32 v32, 0x80000000, v32
	v_xor_b32_e32 v33, 0x80000000, v33
	v_lshl_add_u64 v[40:41], v[20:21], 0, v[18:19]
	v_or_b32_e32 v18, 48, v26
	v_cndmask_b32_e64 v30, v33, v39, s[2:3]
	v_cndmask_b32_e64 v32, v32, v38, s[2:3]
	v_lshrrev_b32_e32 v27, 4, v18
	v_cvt_pk_bf16_f32 v30, v32, v30
	v_add_u32_e32 v32, 1, v27
	v_sub_u32_e32 v27, 32, v27
	v_xor_b32_e32 v29, 0x80000000, v29
	v_cndmask_b32_e32 v27, v27, v32, vcc
	v_cndmask_b32_e64 v31, v29, v31, s[2:3]
	v_mad_i32_i24 v27, v27, s0, v25
	v_cvt_pk_bf16_f32 v31, v34, v31
	ds_read_b128 v[32:35], v27
	ds_read_b128 v[36:39], v27 offset:16
	v_cvt_pk_bf16_f32 v29, v45, v44
	global_store_dwordx4 v[40:41], v[28:31], off sc0 sc1
	ds_read_b128 v[28:31], v27 offset:32
	ds_read_b128 v[40:43], v27 offset:48
	s_waitcnt lgkmcnt(3)
	v_mov_b32_e32 v48, v33
	v_mov_b32_e32 v49, v35
	v_mov_b32_e32 v33, v34
	s_waitcnt lgkmcnt(2)
	v_mov_b32_e32 v44, v37
	v_mov_b32_e32 v45, v39
	v_pk_mul_f32 v[50:51], v[14:15], v[48:49]
	v_mov_b32_e32 v37, v38
	v_pk_mul_f32 v[14:15], v[14:15], v[32:33]
	v_pk_mul_f32 v[46:47], v[16:17], v[44:45]
	v_pk_fma_f32 v[34:35], v[10:11], v[32:33], v[50:51] neg_lo:[0,0,1] neg_hi:[0,0,1]
	v_pk_mul_f32 v[16:17], v[16:17], v[36:37]
	v_pk_fma_f32 v[10:11], v[10:11], v[48:49], v[14:15]
	v_pk_fma_f32 v[38:39], v[12:13], v[36:37], v[46:47] neg_lo:[0,0,1] neg_hi:[0,0,1]
	v_pk_fma_f32 v[12:13], v[12:13], v[44:45], v[16:17]
	v_xor_b32_e32 v10, 0x80000000, v10
	v_xor_b32_e32 v11, 0x80000000, v11
	v_xor_b32_e32 v12, 0x80000000, v12
	v_xor_b32_e32 v13, 0x80000000, v13
	v_cndmask_b32_e64 v33, v11, v35, s[2:3]
	v_cndmask_b32_e64 v34, v10, v34, s[2:3]
	s_waitcnt lgkmcnt(0)
	v_mov_b32_e32 v10, v41
	v_mov_b32_e32 v11, v43
	v_mov_b32_e32 v14, v29
	v_mov_b32_e32 v15, v31
	v_mov_b32_e32 v29, v30
	v_mov_b32_e32 v41, v42
	v_cndmask_b32_e64 v27, v13, v39, s[2:3]
	v_cndmask_b32_e64 v32, v12, v38, s[2:3]
	v_pk_mul_f32 v[12:13], v[8:9], v[10:11]
	v_pk_mul_f32 v[16:17], v[6:7], v[14:15]
	v_pk_mul_f32 v[6:7], v[6:7], v[28:29]
	v_pk_mul_f32 v[8:9], v[8:9], v[40:41]
	v_pk_fma_f32 v[16:17], v[2:3], v[28:29], v[16:17] neg_lo:[0,0,1] neg_hi:[0,0,1]
	v_pk_fma_f32 v[12:13], v[4:5], v[40:41], v[12:13] neg_lo:[0,0,1] neg_hi:[0,0,1]
	v_pk_fma_f32 v[4:5], v[4:5], v[10:11], v[8:9]
	v_pk_fma_f32 v[2:3], v[2:3], v[14:15], v[6:7]
	v_or_b32_e32 v18, v18, v23
	v_xor_b32_e32 v2, 0x80000000, v2
	v_xor_b32_e32 v3, 0x80000000, v3
	v_xor_b32_e32 v4, 0x80000000, v4
	v_xor_b32_e32 v5, 0x80000000, v5
	v_cndmask_b32_e64 v5, v5, v13, s[2:3]
	v_cndmask_b32_e64 v6, v4, v12, s[2:3]
	v_cndmask_b32_e64 v4, v3, v17, s[2:3]
	v_cndmask_b32_e64 v7, v2, v16, s[2:3]
	v_lshlrev_b32_e32 v18, 9, v18
	v_cvt_pk_bf16_f32 v2, v34, v33
	v_cvt_pk_bf16_f32 v3, v32, v27
	v_cvt_pk_bf16_f32 v4, v7, v4
	v_cvt_pk_bf16_f32 v5, v6, v5
	v_lshl_add_u64 v[6:7], v[20:21], 0, v[18:19]
	global_store_dwordx4 v[6:7], v[2:5], off sc0 sc1
	s_nop 1
	v_or_b32_e32 v2, 52, v26
	v_or_b32_e32 v18, v2, v23
	v_lshrrev_b32_e32 v2, 4, v2
	v_add_u32_e32 v3, 1, v2
	v_sub_u32_e32 v2, 32, v2
	v_cndmask_b32_e32 v2, v2, v3, vcc
	v_lshlrev_b32_e32 v3, 8, v18
	v_and_b32_e32 v3, 0x700, v3
	v_add_u32_e32 v27, v24, v3
	v_mad_i32_i24 v40, v2, s0, v25
	ds_read_b128 v[2:5], v27 offset:34832
	ds_read_b128 v[6:9], v27 offset:34848
	ds_read_b128 v[10:13], v40
	ds_read_b128 v[14:17], v40 offset:16
	ds_read_b128 v[28:31], v27 offset:43024
	ds_read_b128 v[32:35], v27 offset:43040
	ds_read_b128 v[36:39], v40 offset:32
	ds_read_b128 v[40:43], v40 offset:48
	s_waitcnt lgkmcnt(5)
	v_mov_b32_e32 v48, v11
	v_mov_b32_e32 v49, v13
	s_waitcnt lgkmcnt(4)
	v_mov_b32_e32 v44, v15
	v_mov_b32_e32 v45, v17
	s_waitcnt lgkmcnt(3)
	v_pk_mul_f32 v[50:51], v[28:29], v[48:49]
	v_mov_b32_e32 v11, v12
	v_pk_mul_f32 v[46:47], v[30:31], v[44:45]
	v_pk_fma_f32 v[12:13], v[2:3], v[10:11], v[50:51] neg_lo:[0,0,1] neg_hi:[0,0,1]
	v_mov_b32_e32 v15, v16
	v_pk_mul_f32 v[10:11], v[28:29], v[10:11]
	v_pk_fma_f32 v[16:17], v[4:5], v[14:15], v[46:47] neg_lo:[0,0,1] neg_hi:[0,0,1]
	v_pk_mul_f32 v[14:15], v[30:31], v[14:15]
	v_pk_fma_f32 v[2:3], v[2:3], v[48:49], v[10:11]
	v_pk_fma_f32 v[4:5], v[4:5], v[44:45], v[14:15]
	v_xor_b32_e32 v2, 0x80000000, v2
	v_xor_b32_e32 v3, 0x80000000, v3
	v_xor_b32_e32 v4, 0x80000000, v4
	v_xor_b32_e32 v5, 0x80000000, v5
	v_cndmask_b32_e64 v30, v2, v12, s[2:3]
	s_waitcnt lgkmcnt(0)
; #define LAS __attribute__((address_space(3)))
; __device__ __forceinline__ u32x4 pack8(const f32x4 v0, const f32x4 v1) { u32x4 w; w.x = pk_f16(v0[0], v0[1]); w.y = pk_f16(v0[2], v0[3]); w.z = pk_f16(v1[0], v1[1]); w.w = pk_f16(v1[2], v1[3]); return w; }
; __device__ __forceinline__ void ssm_tables(LAS float* L, int item, const float* lam_re, const float* lam_im, const float* log_dt, const float* b_re, const float* b_im,
;                                            const float* c_re, const float* c_im, f16* PG, f16* QG, f16* KTH) {
;     ...
;     { const int k0 = (lane & 15) * 8, ri = k0 >> 6, n0 = k0 & 63;
;       for (int it = 0; it < 16; ++it) { const int nrow = wave * 64 + it * 4 + (lane >> 4), s = nrow >> 4, h = nrow & 15; const int e = dir == 0 ? s + 1 : TC - s;
;         const LAS f32x4* crp = (const LAS f32x4*)(L + T_CR + dir * 1024 + h * 64 + n0); const LAS f32x4* cip = (const LAS f32x4*)(L + T_CI + dir * 1024 + h * 64 + n0);
;         const LAS f32x4* app = (const LAS f32x4*)(L + T_AP + e * APS + 2 * n0);
;         const f32x4 cr0 = crp[0], cr1 = crp[1], ci0 = cip[0], ci1 = cip[1], a0 = app[0], a1 = app[1], a2 = app[2], a3 = app[3];
;         const f32x4 pr0 = {a0[0], a0[2], a1[0], a1[2]}, pi0 = {a0[1], a0[3], a1[1], a1[3]}, pr1 = {a2[0], a2[2], a3[0], a3[2]}, pi1 = {a2[1], a2[3], a3[1], a3[3]};
;         const f32x4 v0 = ri == 0 ? cr0 * pr0 - ci0 * pi0 : -(cr0 * pi0 + ci0 * pr0), v1 = ri == 0 ? cr1 * pr1 - ci1 * pi1 : -(cr1 * pi1 + ci1 * pr1);
;         *(u32x4*)(QGg + (size_t)nrow * 256 + dir * 128 + k0) = pack8(v0, v1); } }
;     __syncthreads();
	v_mov_b32_e32 v2, v41
	v_mov_b32_e32 v10, v37
	v_mov_b32_e32 v11, v39
	v_mov_b32_e32 v37, v38
	v_mov_b32_e32 v41, v42
	v_cndmask_b32_e64 v27, v5, v17, s[2:3]
	v_cndmask_b32_e64 v28, v4, v16, s[2:3]
	v_cndmask_b32_e64 v29, v3, v13, s[2:3]
	v_mov_b32_e32 v3, v43
	v_pk_mul_f32 v[12:13], v[32:33], v[10:11]
	v_pk_mul_f32 v[14:15], v[34:35], v[40:41]
	v_pk_mul_f32 v[16:17], v[32:33], v[36:37]
	v_pk_mul_f32 v[4:5], v[34:35], v[2:3]
	v_pk_fma_f32 v[12:13], v[6:7], v[36:37], v[12:13] neg_lo:[0,0,1] neg_hi:[0,0,1]
	v_pk_fma_f32 v[2:3], v[8:9], v[2:3], v[14:15]
	v_pk_fma_f32 v[6:7], v[6:7], v[10:11], v[16:17]
	v_pk_fma_f32 v[4:5], v[8:9], v[40:41], v[4:5] neg_lo:[0,0,1] neg_hi:[0,0,1]
	v_xor_b32_e32 v6, 0x80000000, v6
	v_xor_b32_e32 v7, 0x80000000, v7
	v_xor_b32_e32 v2, 0x80000000, v2
	v_xor_b32_e32 v3, 0x80000000, v3
	v_cndmask_b32_e64 v5, v3, v5, s[2:3]
	v_cndmask_b32_e64 v8, v2, v4, s[2:3]
	v_cndmask_b32_e64 v4, v7, v13, s[2:3]
	v_cndmask_b32_e64 v6, v6, v12, s[2:3]
	v_lshlrev_b32_e32 v18, 9, v18
	v_cvt_pk_bf16_f32 v2, v30, v29
	v_cvt_pk_bf16_f32 v3, v28, v27
	v_cvt_pk_bf16_f32 v4, v6, v4
	v_cvt_pk_bf16_f32 v5, v8, v5
	v_lshl_add_u64 v[6:7], v[20:21], 0, v[18:19]
	global_store_dwordx4 v[6:7], v[2:5], off sc0 sc1
	s_nop 1
	v_or_b32_e32 v2, 56, v26
	v_or_b32_e32 v18, v2, v23
	v_lshrrev_b32_e32 v2, 4, v2
	v_add_u32_e32 v3, 1, v2
	v_sub_u32_e32 v2, 32, v2
	v_cndmask_b32_e32 v2, v2, v3, vcc
	v_lshlrev_b32_e32 v3, 8, v18
	v_and_b32_e32 v3, 0xb00, v3
	v_add_u32_e32 v27, v24, v3
	v_mad_i32_i24 v40, v2, s0, v25
	ds_read_b128 v[2:5], v27 offset:34832
	ds_read_b128 v[6:9], v27 offset:34848
	ds_read_b128 v[10:13], v40
	ds_read_b128 v[14:17], v40 offset:16
	ds_read_b128 v[28:31], v27 offset:43024
	ds_read_b128 v[32:35], v27 offset:43040
	ds_read_b128 v[36:39], v40 offset:32
	ds_read_b128 v[40:43], v40 offset:48
	s_waitcnt lgkmcnt(5)
	v_mov_b32_e32 v48, v11
	v_mov_b32_e32 v49, v13
	s_waitcnt lgkmcnt(4)
	v_mov_b32_e32 v44, v15
	v_mov_b32_e32 v45, v17
	s_waitcnt lgkmcnt(3)
	v_pk_mul_f32 v[50:51], v[28:29], v[48:49]
	v_mov_b32_e32 v11, v12
	v_pk_mul_f32 v[46:47], v[30:31], v[44:45]
	v_pk_fma_f32 v[12:13], v[2:3], v[10:11], v[50:51] neg_lo:[0,0,1] neg_hi:[0,0,1]
	v_mov_b32_e32 v15, v16
	v_pk_mul_f32 v[10:11], v[28:29], v[10:11]
	v_pk_fma_f32 v[16:17], v[4:5], v[14:15], v[46:47] neg_lo:[0,0,1] neg_hi:[0,0,1]
	v_pk_mul_f32 v[14:15], v[30:31], v[14:15]
	v_pk_fma_f32 v[2:3], v[2:3], v[48:49], v[10:11]
	v_pk_fma_f32 v[4:5], v[4:5], v[44:45], v[14:15]
	v_xor_b32_e32 v2, 0x80000000, v2
	v_xor_b32_e32 v3, 0x80000000, v3
	v_xor_b32_e32 v4, 0x80000000, v4
	v_xor_b32_e32 v5, 0x80000000, v5
	v_cndmask_b32_e64 v30, v2, v12, s[2:3]
	s_waitcnt lgkmcnt(0)
	v_mov_b32_e32 v2, v41
	v_mov_b32_e32 v10, v37
	v_mov_b32_e32 v11, v39
	v_mov_b32_e32 v37, v38
	v_mov_b32_e32 v41, v42
	v_cndmask_b32_e64 v27, v5, v17, s[2:3]
	v_cndmask_b32_e64 v28, v4, v16, s[2:3]
	v_cndmask_b32_e64 v29, v3, v13, s[2:3]
	v_mov_b32_e32 v3, v43
	v_pk_mul_f32 v[12:13], v[32:33], v[10:11]
	v_pk_mul_f32 v[14:15], v[34:35], v[40:41]
	v_pk_mul_f32 v[16:17], v[32:33], v[36:37]
	v_pk_mul_f32 v[4:5], v[34:35], v[2:3]
	v_pk_fma_f32 v[12:13], v[6:7], v[36:37], v[12:13] neg_lo:[0,0,1] neg_hi:[0,0,1]
	v_pk_fma_f32 v[2:3], v[8:9], v[2:3], v[14:15]
	v_pk_fma_f32 v[6:7], v[6:7], v[10:11], v[16:17]
	v_pk_fma_f32 v[4:5], v[8:9], v[40:41], v[4:5] neg_lo:[0,0,1] neg_hi:[0,0,1]
	v_xor_b32_e32 v6, 0x80000000, v6
	v_xor_b32_e32 v7, 0x80000000, v7
	v_xor_b32_e32 v2, 0x80000000, v2
	v_xor_b32_e32 v3, 0x80000000, v3
	v_cndmask_b32_e64 v5, v3, v5, s[2:3]
	v_cndmask_b32_e64 v8, v2, v4, s[2:3]
	v_cndmask_b32_e64 v4, v7, v13, s[2:3]
	v_cndmask_b32_e64 v6, v6, v12, s[2:3]
	v_lshlrev_b32_e32 v18, 9, v18
	v_cvt_pk_bf16_f32 v2, v30, v29
	v_cvt_pk_bf16_f32 v3, v28, v27
	v_cvt_pk_bf16_f32 v4, v6, v4
	v_cvt_pk_bf16_f32 v5, v8, v5
	v_lshl_add_u64 v[6:7], v[20:21], 0, v[18:19]
	global_store_dwordx4 v[6:7], v[2:5], off sc0 sc1
	s_nop 1
	v_or_b32_e32 v2, 60, v26
	v_or_b32_e32 v18, v2, v23
	v_lshrrev_b32_e32 v2, 4, v2
	v_add_u32_e32 v3, 1, v2
	v_sub_u32_e32 v2, 32, v2
	v_cndmask_b32_e32 v2, v2, v3, vcc
	v_lshlrev_b32_e32 v3, 8, v18
	v_and_b32_e32 v3, 0xf00, v3
	v_add_u32_e32 v23, v24, v3
	v_mad_i32_i24 v36, v2, s0, v25
	ds_read_b128 v[2:5], v23 offset:34832
	ds_read_b128 v[6:9], v23 offset:34848
	ds_read_b128 v[10:13], v36
	ds_read_b128 v[14:17], v36 offset:16
	ds_read_b128 v[24:27], v23 offset:43024
	ds_read_b128 v[28:31], v23 offset:43040
	ds_read_b128 v[32:35], v36 offset:32
	ds_read_b128 v[36:39], v36 offset:48
	s_waitcnt lgkmcnt(5)
	v_mov_b32_e32 v44, v11
	v_mov_b32_e32 v45, v13
	s_waitcnt lgkmcnt(4)
	v_mov_b32_e32 v40, v15
	v_mov_b32_e32 v41, v17
	s_waitcnt lgkmcnt(3)
	v_pk_mul_f32 v[46:47], v[24:25], v[44:45]
	v_mov_b32_e32 v11, v12
	v_pk_mul_f32 v[42:43], v[26:27], v[40:41]
	v_pk_fma_f32 v[12:13], v[2:3], v[10:11], v[46:47] neg_lo:[0,0,1] neg_hi:[0,0,1]
	v_mov_b32_e32 v15, v16
	v_pk_mul_f32 v[10:11], v[24:25], v[10:11]
	v_pk_fma_f32 v[16:17], v[4:5], v[14:15], v[42:43] neg_lo:[0,0,1] neg_hi:[0,0,1]
	v_pk_mul_f32 v[14:15], v[26:27], v[14:15]
	v_pk_fma_f32 v[2:3], v[2:3], v[44:45], v[10:11]
	v_pk_fma_f32 v[4:5], v[4:5], v[40:41], v[14:15]
	v_xor_b32_e32 v2, 0x80000000, v2
	v_xor_b32_e32 v3, 0x80000000, v3
	v_xor_b32_e32 v4, 0x80000000, v4
	v_xor_b32_e32 v5, 0x80000000, v5
	v_cndmask_b32_e64 v26, v2, v12, s[2:3]
	s_waitcnt lgkmcnt(0)
	v_mov_b32_e32 v2, v37
	v_mov_b32_e32 v10, v33
	v_mov_b32_e32 v11, v35
	v_mov_b32_e32 v33, v34
	v_mov_b32_e32 v37, v38
	v_cndmask_b32_e64 v23, v5, v17, s[2:3]
	v_cndmask_b32_e64 v24, v4, v16, s[2:3]
	v_cndmask_b32_e64 v25, v3, v13, s[2:3]
	v_mov_b32_e32 v3, v39
	v_pk_mul_f32 v[12:13], v[28:29], v[10:11]
	v_pk_mul_f32 v[14:15], v[30:31], v[36:37]
	v_pk_mul_f32 v[16:17], v[28:29], v[32:33]
	v_pk_mul_f32 v[4:5], v[30:31], v[2:3]
	v_pk_fma_f32 v[12:13], v[6:7], v[32:33], v[12:13] neg_lo:[0,0,1] neg_hi:[0,0,1]
	v_pk_fma_f32 v[2:3], v[8:9], v[2:3], v[14:15]
	v_pk_fma_f32 v[6:7], v[6:7], v[10:11], v[16:17]
	v_pk_fma_f32 v[4:5], v[8:9], v[36:37], v[4:5] neg_lo:[0,0,1] neg_hi:[0,0,1]
	v_xor_b32_e32 v6, 0x80000000, v6
	v_xor_b32_e32 v7, 0x80000000, v7
	v_xor_b32_e32 v2, 0x80000000, v2
	v_xor_b32_e32 v3, 0x80000000, v3
	v_cndmask_b32_e64 v5, v3, v5, s[2:3]
	v_cndmask_b32_e64 v8, v2, v4, s[2:3]
	v_cndmask_b32_e64 v4, v7, v13, s[2:3]
	v_cndmask_b32_e64 v6, v6, v12, s[2:3]
	v_lshlrev_b32_e32 v18, 9, v18
	v_cvt_pk_bf16_f32 v2, v26, v25
	v_cvt_pk_bf16_f32 v3, v24, v23
	v_cvt_pk_bf16_f32 v4, v6, v4
	v_cvt_pk_bf16_f32 v5, v8, v5
	v_lshl_add_u64 v[6:7], v[20:21], 0, v[18:19]
	global_store_dwordx4 v[6:7], v[2:5], off sc0 sc1
	s_barrier

; __device__ __forceinline__ u32x4 pack8(const f32x4 v0, const f32x4 v1) { u32x4 w; w.x = pk_f16(v0[0], v0[1]); w.y = pk_f16(v0[2], v0[3]); w.z = pk_f16(v1[0], v1[1]); w.w = pk_f16(v1[2], v1[3]); return w; }
;     __device__ __forceinline__ void operator()(AccRef acc, const Unit& u, int wr, int wc, int fr, int fq) const {
;         int row0 = u.g * 256 + wr * 64 + fr; asm volatile("" : "+v"(row0)); int col0 = u.pn * 256 + wc * 32 + 8 * fq; asm volatile("" : "+v"(col0));
; #pragma unroll
;         for (int ai = 0; ai < 2; ++ai)
; #pragma unroll
;             for (int m = 0; m < 4; ++m)
; #pragma unroll
;                 for (int bj = 0; bj < 2; ++bj) *(u32x4*)(WinT + (size_t)(row0 + ai * HALF + m * 16) * D + col0 + bj * HALF) = pack8(acc[ai][bj][m][0], acc[ai][bj][m][1]);
.LBB0_175:
	v_lshl_add_u32 v140, s84, 8, v134
	v_lshl_or_b32 v142, s86, 8, v1
	v_ashrrev_i32_e32 v141, 31, v140
	v_lshlrev_b64 v[140:141], 12, v[140:141]
	v_cvt_pk_bf16_f32 v114, v114, v115
	v_ashrrev_i32_e32 v143, 31, v142
	v_cvt_pk_bf16_f32 v115, v116, v117
	v_cvt_pk_bf16_f32 v116, v118, v119
	v_lshl_add_u64 v[118:119], s[28:29], 0, v[140:141]
	v_lshl_add_u64 v[118:119], v[142:143], 1, v[118:119]
	s_mov_b32 s81, 0x10000
	v_cvt_pk_bf16_f32 v98, v98, v99
	v_cvt_pk_bf16_f32 v99, v100, v101
	v_cvt_pk_bf16_f32 v101, v104, v105
	v_add_co_u32_e32 v104, vcc, s81, v118
	s_mov_b32 s81, 0x20000
	s_nop 0
	v_addc_co_u32_e32 v105, vcc, 0, v119, vcc
	v_cvt_pk_bf16_f32 v66, v66, v67
	v_cvt_pk_bf16_f32 v67, v68, v69
	v_cvt_pk_bf16_f32 v69, v72, v73
	v_add_co_u32_e32 v72, vcc, s81, v118
	s_mov_b32 s81, 0x30000
	s_nop 0
	v_addc_co_u32_e32 v73, vcc, 0, v119, vcc
	v_cvt_pk_bf16_f32 v34, v34, v35
	v_cvt_pk_bf16_f32 v35, v36, v37
	v_cvt_pk_bf16_f32 v37, v40, v41
	v_add_co_u32_e32 v40, vcc, s81, v118
	v_cvt_pk_bf16_f32 v36, v38, v39
	s_mov_b64 s[84:85], 0x30000
	v_addc_co_u32_e32 v41, vcc, 0, v119, vcc
	s_mov_b32 s81, 0x80000
	v_lshl_add_u64 v[38:39], v[118:119], 0, s[84:85]
	global_store_dwordx4 v[40:41], v[34:37], off sc0 sc1
	v_add_co_u32_e32 v40, vcc, s81, v118
	s_nop 0
	v_cvt_pk_bf16_f32 v34, v42, v43
	v_cvt_pk_bf16_f32 v35, v44, v45
	v_cvt_pk_bf16_f32 v36, v46, v47
	v_cvt_pk_bf16_f32 v37, v48, v49
	global_store_dwordx4 v[38:39], v[34:37], off offset:256 sc0 sc1
	v_addc_co_u32_e32 v41, vcc, 0, v119, vcc
	s_nop 0
	v_cvt_pk_bf16_f32 v34, v82, v83
	v_cvt_pk_bf16_f32 v35, v84, v85
	v_cvt_pk_bf16_f32 v36, v86, v87
	v_cvt_pk_bf16_f32 v37, v88, v89
	s_mov_b32 s81, 0x90000
	global_store_dwordx4 v[40:41], v[34:37], off sc0 sc1
	v_add_co_u32_e32 v40, vcc, s81, v118
	s_mov_b32 s81, 0xa0000
	s_nop 0
	v_addc_co_u32_e32 v41, vcc, 0, v119, vcc
	s_mov_b64 s[84:85], 0x80000
	v_cvt_pk_bf16_f32 v18, v18, v19
	v_cvt_pk_bf16_f32 v19, v20, v21
	v_cvt_pk_bf16_f32 v21, v24, v25
	v_add_co_u32_e32 v24, vcc, s81, v118
	v_lshl_add_u64 v[38:39], v[118:119], 0, s[84:85]
	v_cvt_pk_bf16_f32 v34, v90, v91
	v_cvt_pk_bf16_f32 v35, v92, v93
	v_cvt_pk_bf16_f32 v36, v94, v95
	v_cvt_pk_bf16_f32 v37, v96, v97
	s_mov_b64 s[84:85], 0x90000
	v_addc_co_u32_e32 v25, vcc, 0, v119, vcc
	s_mov_b32 s81, 0xb0000
	global_store_dwordx4 v[38:39], v[34:37], off offset:256 sc0 sc1
	v_lshl_add_u64 v[38:39], v[118:119], 0, s[84:85]
	s_mov_b64 s[84:85], 0xa0000
	v_cvt_pk_bf16_f32 v2, v2, v3
	v_cvt_pk_bf16_f32 v3, v4, v5
	v_cvt_pk_bf16_f32 v5, v8, v9
	v_add_co_u32_e32 v8, vcc, s81, v118
	v_cvt_pk_bf16_f32 v117, v120, v121
	v_cvt_pk_bf16_f32 v100, v102, v103
	v_cvt_pk_bf16_f32 v68, v70, v71
	v_cvt_pk_bf16_f32 v34, v50, v51
	v_cvt_pk_bf16_f32 v35, v52, v53
	v_cvt_pk_bf16_f32 v36, v54, v55
	v_cvt_pk_bf16_f32 v37, v56, v57
	v_cvt_pk_bf16_f32 v20, v22, v23
	v_lshl_add_u64 v[22:23], v[118:119], 0, s[84:85]
	v_cvt_pk_bf16_f32 v4, v6, v7
	s_mov_b64 s[84:85], 0xb0000
	v_addc_co_u32_e32 v9, vcc, 0, v119, vcc
	global_store_dwordx4 v[118:119], v[114:117], off sc0 sc1
	v_lshl_add_u64 v[102:103], v[118:119], 0, s[22:23]
	global_store_dwordx4 v[104:105], v[98:101], off sc0 sc1
	v_cvt_pk_bf16_f32 v114, v122, v123
	v_cvt_pk_bf16_f32 v115, v124, v125
	v_cvt_pk_bf16_f32 v116, v126, v127
	v_cvt_pk_bf16_f32 v117, v128, v129
	v_cvt_pk_bf16_f32 v98, v106, v107
	v_cvt_pk_bf16_f32 v99, v108, v109
	v_cvt_pk_bf16_f32 v100, v110, v111
	v_cvt_pk_bf16_f32 v101, v112, v113
	v_lshl_add_u64 v[70:71], v[118:119], 0, s[2:3]
	global_store_dwordx4 v[72:73], v[66:69], off sc0 sc1
	global_store_dwordx4 v[40:41], v[34:37], off sc0 sc1
	global_store_dwordx4 v[24:25], v[18:21], off sc0 sc1
	v_cvt_pk_bf16_f32 v66, v74, v75
	v_cvt_pk_bf16_f32 v67, v76, v77
	v_cvt_pk_bf16_f32 v68, v78, v79
	v_cvt_pk_bf16_f32 v69, v80, v81
	v_cvt_pk_bf16_f32 v34, v58, v59
	v_cvt_pk_bf16_f32 v35, v60, v61
	v_cvt_pk_bf16_f32 v36, v62, v63
	v_cvt_pk_bf16_f32 v37, v64, v65
	v_cvt_pk_bf16_f32 v18, v26, v27
	v_cvt_pk_bf16_f32 v19, v28, v29
	v_cvt_pk_bf16_f32 v20, v30, v31
	v_cvt_pk_bf16_f32 v21, v32, v33
	v_lshl_add_u64 v[6:7], v[118:119], 0, s[84:85]
	global_store_dwordx4 v[8:9], v[2:5], off sc0 sc1
	s_andn2_b64 vcc, exec, s[90:91]
	s_mov_b64 s[84:85], -1
	v_cvt_pk_bf16_f32 v2, v10, v11
	v_cvt_pk_bf16_f32 v3, v12, v13
	v_cvt_pk_bf16_f32 v4, v14, v15
	v_cvt_pk_bf16_f32 v5, v16, v17
	global_store_dwordx4 v[118:119], v[114:117], off offset:256 sc0 sc1
	global_store_dwordx4 v[102:103], v[98:101], off offset:256 sc0 sc1
	global_store_dwordx4 v[70:71], v[66:69], off offset:256 sc0 sc1
	global_store_dwordx4 v[38:39], v[34:37], off offset:256 sc0 sc1
	global_store_dwordx4 v[22:23], v[18:21], off offset:256 sc0 sc1
	global_store_dwordx4 v[6:7], v[2:5], off offset:256 sc0 sc1
	s_cbranch_vccnz .LBB0_170
	s_andn2_b64 vcc, exec, s[26:27]
	s_cbranch_vccnz .LBB0_169
	s_barrier
	s_branch .LBB0_169

; __device__ __forceinline__ f32x4 ld_nt(const float* p) { return __builtin_nontemporal_load((const f32x4*)p); }
; __device__ __forceinline__ void norm_rows(int gw, int lane, const float* x, const float* ctx, const float* ng, const float* mod, f16* h) {
;     ...
;     auto finish_row = [&](const f32x4 (&v)[8], f16* dst) { float ss = 0.f;
; #pragma unroll
;         for (int j = 0; j < 8; ++j) ss += (v[j][0] * v[j][0] + v[j][1] * v[j][1]) + (v[j][2] * v[j][2] + v[j][3] * v[j][3]);
;     ...
;     if (r0 < M_LAT) { load_mod(r0 / SEQ);
; #pragma unroll 1
;         for (int rb = r0; rb < r0 + RPW; rb += 4) { f32x4 v[4][8];
; #pragma unroll
;             for (int rr = 0; rr < 4; ++rr)
; #pragma unroll
;                 for (int j = 0; j < 8; ++j) v[rr][j] = ld_nt(x + (size_t)(rb + rr) * D + 256 * j + 4 * lane);
;             __builtin_amdgcn_sched_barrier(0);
; #pragma unroll
;             for (int rr = 0; rr < 4; ++rr) finish_row(v[rr], h + (size_t)(rb + rr) * D); } }
.LBB0_181:
	v_add_co_u32_e32 v34, vcc, 0xffff9000, v198
	s_nop 1
	v_addc_co_u32_e32 v35, vcc, -1, v199, vcc
	global_load_dwordx4 v[158:161], v[34:35], off offset:-3072 nt
	global_load_dwordx4 v[154:157], v[34:35], off offset:-2048 nt
	global_load_dwordx4 v[150:153], v[34:35], off offset:-1024 nt
	global_load_dwordx4 v[142:145], v[34:35], off nt
	v_add_co_u32_e32 v34, vcc, 0xffffa000, v198
	s_nop 1
	v_addc_co_u32_e32 v35, vcc, -1, v199, vcc
	global_load_dwordx4 v[146:149], v[34:35], off offset:-3072 nt
	global_load_dwordx4 v[138:141], v[34:35], off offset:-2048 nt
	global_load_dwordx4 v[134:137], v[34:35], off offset:-1024 nt
	global_load_dwordx4 v[130:133], v[34:35], off nt
	v_add_co_u32_e32 v34, vcc, 0xffffb000, v198
	s_nop 1
	v_addc_co_u32_e32 v35, vcc, -1, v199, vcc
	global_load_dwordx4 v[126:129], v[34:35], off offset:-3072 nt
	global_load_dwordx4 v[122:125], v[34:35], off offset:-2048 nt
	global_load_dwordx4 v[118:121], v[34:35], off offset:-1024 nt
	global_load_dwordx4 v[110:113], v[34:35], off nt
	v_add_co_u32_e32 v34, vcc, 0xffffc000, v198
	s_nop 1
	v_addc_co_u32_e32 v35, vcc, -1, v199, vcc
	global_load_dwordx4 v[114:117], v[34:35], off offset:-3072 nt
	global_load_dwordx4 v[106:109], v[34:35], off offset:-2048 nt
	global_load_dwordx4 v[102:105], v[34:35], off offset:-1024 nt
	global_load_dwordx4 v[98:101], v[34:35], off nt
	v_add_co_u32_e32 v34, vcc, 0xffffd000, v198
	s_nop 1
	v_addc_co_u32_e32 v35, vcc, -1, v199, vcc
	global_load_dwordx4 v[94:97], v[34:35], off offset:-3072 nt
	global_load_dwordx4 v[90:93], v[34:35], off offset:-2048 nt
	global_load_dwordx4 v[86:89], v[34:35], off offset:-1024 nt
	global_load_dwordx4 v[78:81], v[34:35], off nt
	v_add_co_u32_e32 v34, vcc, 0xffffe000, v198
	s_nop 1
	v_addc_co_u32_e32 v35, vcc, -1, v199, vcc
	global_load_dwordx4 v[82:85], v[34:35], off offset:-3072 nt
	global_load_dwordx4 v[74:77], v[34:35], off offset:-2048 nt
	global_load_dwordx4 v[70:73], v[34:35], off offset:-1024 nt
	global_load_dwordx4 v[66:69], v[34:35], off nt
	v_add_co_u32_e32 v34, vcc, 0xfffff000, v198
	s_nop 1
	v_addc_co_u32_e32 v35, vcc, -1, v199, vcc
	global_load_dwordx4 v[62:65], v[34:35], off offset:-3072 nt
	global_load_dwordx4 v[58:61], v[34:35], off offset:-2048 nt
	global_load_dwordx4 v[54:57], v[34:35], off offset:-1024 nt
	global_load_dwordx4 v[50:53], v[198:199], off offset:-4096 nt
	global_load_dwordx4 v[46:49], v[198:199], off offset:-3072 nt
	global_load_dwordx4 v[42:45], v[198:199], off offset:-2048 nt
	global_load_dwordx4 v[38:41], v[198:199], off offset:-1024 nt
	s_nop 0
	global_load_dwordx4 v[34:37], v[198:199], off nt
	s_waitcnt vmcnt(31)
	v_mov_b32_e32 v208, v159
	s_waitcnt vmcnt(30)
	v_mov_b32_e32 v209, v155
	v_mov_b32_e32 v200, v158
	v_mov_b32_e32 v201, v154
	v_pk_mul_f32 v[208:209], v[208:209], v[208:209]
	v_mov_b32_e32 v210, v161
	v_mov_b32_e32 v211, v157
	v_pk_fma_f32 v[200:201], v[200:201], v[200:201], v[208:209]
	v_mov_b32_e32 v208, v160
	v_mov_b32_e32 v209, v156
	v_pk_mul_f32 v[210:211], v[210:211], v[210:211]
	s_waitcnt vmcnt(27)
	v_mul_f32_e32 v163, v146, v146
	v_pk_fma_f32 v[208:209], v[208:209], v[208:209], v[210:211]
	v_pk_mul_f32 v[210:211], v[150:151], v[150:151]
	v_pk_add_f32 v[200:201], v[200:201], v[208:209]
	v_pk_mul_f32 v[208:209], v[152:153], v[152:153]
	v_mul_f32_e32 v207, v147, v147
	v_pk_mov_b32 v[214:215], v[210:211], v[208:209] op_sel:[1,0]
	v_mov_b32_e32 v211, v209
	v_pk_add_f32 v[208:209], v[214:215], v[210:211]
	v_pk_add_f32 v[200:201], v[200:201], v[200:201] op_sel:[0,1] op_sel_hi:[1,0]
	v_pk_add_f32 v[208:209], v[208:209], v[208:209] op_sel:[0,1] op_sel_hi:[1,0]
	v_mov_b32_e32 v201, v163
	v_mov_b32_e32 v209, v207
	v_pk_add_f32 v[200:201], v[200:201], v[208:209]
	v_mul_f32_e32 v208, v143, v143
	v_mul_f32_e32 v210, v148, v148
	v_pk_fma_f32 v[208:209], v[142:143], v[142:143], v[208:209] op_sel_hi:[1,1,0]
	v_mul_f32_e32 v213, v149, v149
	v_mov_b32_e32 v209, v210
	v_mul_f32_e32 v210, v145, v145
	v_pk_fma_f32 v[210:211], v[144:145], v[144:145], v[210:211] op_sel_hi:[1,1,0]
	s_waitcnt vmcnt(24)
	v_mul_f32_e32 v163, v130, v130
	v_mov_b32_e32 v211, v213
	v_pk_add_f32 v[208:209], v[208:209], v[210:211]
	v_pk_mul_f32 v[210:211], v[138:139], v[138:139]
	v_pk_add_f32 v[200:201], v[200:201], v[208:209]
	v_pk_mul_f32 v[208:209], v[140:141], v[140:141]
	v_mul_f32_e32 v207, v131, v131
	v_pk_mov_b32 v[214:215], v[210:211], v[208:209] op_sel:[1,0]
	v_mov_b32_e32 v211, v209
	v_pk_add_f32 v[208:209], v[214:215], v[210:211]
	v_pk_add_f32 v[200:201], v[200:201], v[200:201] op_sel:[0,1] op_sel_hi:[1,0]
	v_pk_add_f32 v[208:209], v[208:209], v[208:209] op_sel:[0,1] op_sel_hi:[1,0]
	v_mov_b32_e32 v201, v163
	v_mov_b32_e32 v209, v207
	v_pk_add_f32 v[200:201], v[200:201], v[208:209]
	v_mul_f32_e32 v208, v135, v135
	v_mul_f32_e32 v210, v132, v132
	v_pk_fma_f32 v[208:209], v[134:135], v[134:135], v[208:209] op_sel_hi:[1,1,0]
	v_mul_f32_e32 v213, v133, v133
	v_mov_b32_e32 v209, v210
	v_mul_f32_e32 v210, v137, v137
	v_pk_fma_f32 v[210:211], v[136:137], v[136:137], v[210:211] op_sel_hi:[1,1,0]
	s_waitcnt vmcnt(23)
	v_mov_b32_e32 v214, v129
	v_mov_b32_e32 v211, v213
	v_pk_add_f32 v[208:209], v[208:209], v[210:211]
	v_mov_b32_e32 v210, v127
	s_waitcnt vmcnt(22)
	v_mov_b32_e32 v211, v123
	v_pk_add_f32 v[200:201], v[200:201], v[208:209]
	v_mov_b32_e32 v208, v126
	v_mov_b32_e32 v209, v122
	v_pk_mul_f32 v[210:211], v[210:211], v[210:211]
	v_mov_b32_e32 v215, v125
	v_pk_fma_f32 v[208:209], v[208:209], v[208:209], v[210:211]
	v_mov_b32_e32 v210, v128
	v_mov_b32_e32 v211, v124
	v_pk_mul_f32 v[214:215], v[214:215], v[214:215]
	s_waitcnt vmcnt(19)
; __device__ __forceinline__ void norm_rows(int gw, int lane, const float* x, const float* ctx, const float* ng, const float* mod, f16* h) {
;     ...
;     auto finish_row = [&](const f32x4 (&v)[8], f16* dst) { float ss = 0.f;
; #pragma unroll
;         for (int j = 0; j < 8; ++j) ss += (v[j][0] * v[j][0] + v[j][1] * v[j][1]) + (v[j][2] * v[j][2] + v[j][3] * v[j][3]);
;         const float rstd = rsqrtf(wave_sum(ss) * (1.f / D) + EPS);
; #pragma unroll
;         for (int j = 0; j < 8; ++j) { const f32x4 o = v[j] * rstd * gs[j] + sh[j]; u32x2 w; w.x = pk_f16(o[0], o[1]); w.y = pk_f16(o[2], o[3]); *(u32x2*)(dst + 256 * j + 4 * lane) = w; } };
	v_mul_f32_e32 v163, v114, v114
	v_pk_fma_f32 v[210:211], v[210:211], v[210:211], v[214:215]
	v_pk_mul_f32 v[214:215], v[118:119], v[118:119]
	v_pk_add_f32 v[208:209], v[208:209], v[210:211]
	v_pk_mul_f32 v[210:211], v[120:121], v[120:121]
	v_mul_f32_e32 v207, v115, v115
	v_pk_mov_b32 v[216:217], v[214:215], v[210:211] op_sel:[1,0]
	v_mov_b32_e32 v215, v211
	v_pk_add_f32 v[210:211], v[216:217], v[214:215]
	v_pk_add_f32 v[208:209], v[208:209], v[208:209] op_sel:[0,1] op_sel_hi:[1,0]
	v_pk_add_f32 v[210:211], v[210:211], v[210:211] op_sel:[0,1] op_sel_hi:[1,0]
	v_mov_b32_e32 v209, v163
	v_mov_b32_e32 v211, v207
	v_pk_add_f32 v[208:209], v[208:209], v[210:211]
	v_mul_f32_e32 v210, v111, v111
	v_mul_f32_e32 v214, v113, v113
	v_mul_f32_e32 v213, v116, v116
	v_mul_f32_e32 v216, v117, v117
	v_pk_fma_f32 v[210:211], v[110:111], v[110:111], v[210:211] op_sel_hi:[1,1,0]
	v_pk_fma_f32 v[214:215], v[112:113], v[112:113], v[214:215] op_sel_hi:[1,1,0]
	v_mov_b32_e32 v211, v213
	v_mov_b32_e32 v215, v216
	v_pk_add_f32 v[210:211], v[210:211], v[214:215]
	s_waitcnt vmcnt(18)
	v_pk_mul_f32 v[214:215], v[106:107], v[106:107]
	v_pk_add_f32 v[208:209], v[208:209], v[210:211]
	v_pk_mul_f32 v[210:211], v[108:109], v[108:109]
	s_waitcnt vmcnt(16)
	v_mul_f32_e32 v163, v98, v98
	v_pk_mov_b32 v[216:217], v[214:215], v[210:211] op_sel:[1,0]
	v_mov_b32_e32 v215, v211
	v_pk_add_f32 v[210:211], v[216:217], v[214:215]
	v_mul_f32_e32 v207, v99, v99
	v_pk_add_f32 v[208:209], v[208:209], v[208:209] op_sel:[0,1] op_sel_hi:[1,0]
	v_pk_add_f32 v[210:211], v[210:211], v[210:211] op_sel:[0,1] op_sel_hi:[1,0]
	v_mov_b32_e32 v209, v163
	v_mov_b32_e32 v211, v207
	v_pk_add_f32 v[208:209], v[208:209], v[210:211]
	v_mul_f32_e32 v210, v103, v103
	v_mul_f32_e32 v214, v105, v105
	v_mul_f32_e32 v213, v100, v100
	v_mul_f32_e32 v216, v101, v101
	v_pk_fma_f32 v[210:211], v[102:103], v[102:103], v[210:211] op_sel_hi:[1,1,0]
	v_pk_fma_f32 v[214:215], v[104:105], v[104:105], v[214:215] op_sel_hi:[1,1,0]
	v_mov_b32_e32 v211, v213
	v_mov_b32_e32 v215, v216
	v_pk_add_f32 v[210:211], v[210:211], v[214:215]
	s_add_i32 s7, s7, 4
	v_pk_add_f32 v[208:209], v[208:209], v[210:211]
	v_mov_b32_e32 v211, v200
	v_mov_b32_e32 v210, v208
	v_mov_b32_e32 v200, v209
	v_pk_add_f32 v[200:201], v[210:211], v[200:201]
	ds_bpermute_b32 v209, v1, v201
	ds_bpermute_b32 v208, v1, v200
	v_lshl_add_u64 v[198:199], v[198:199], 0, s[26:27]
	s_cmp_le_i32 s7, s12
	s_waitcnt lgkmcnt(0)
	v_pk_add_f32 v[200:201], v[200:201], v[208:209]
	ds_bpermute_b32 v209, v202, v201
	ds_bpermute_b32 v208, v202, v200
	s_waitcnt lgkmcnt(0)
	v_pk_add_f32 v[200:201], v[200:201], v[208:209]
	ds_bpermute_b32 v209, v203, v201
	ds_bpermute_b32 v208, v203, v200
	s_waitcnt lgkmcnt(0)
	v_pk_add_f32 v[200:201], v[200:201], v[208:209]
	ds_bpermute_b32 v209, v204, v201
	ds_bpermute_b32 v208, v204, v200
	s_waitcnt lgkmcnt(0)
	v_pk_add_f32 v[200:201], v[200:201], v[208:209]
	ds_bpermute_b32 v209, v205, v201
	ds_bpermute_b32 v208, v205, v200
	s_waitcnt lgkmcnt(0)
	v_pk_add_f32 v[200:201], v[200:201], v[208:209]
	ds_bpermute_b32 v209, v206, v201
	ds_bpermute_b32 v208, v206, v200
	s_waitcnt lgkmcnt(0)
	v_pk_add_f32 v[208:209], v[200:201], v[208:209]
	v_mov_b64_e32 v[200:201], s[22:23]
	v_pk_fma_f32 v[208:209], v[208:209], s[14:15], v[200:201] op_sel_hi:[1,0,0]
	s_nop 0
	v_mul_f32_e32 v163, 0x4b800000, v209
	v_cmp_gt_f32_e64 s[2:3], s15, v209
	v_cmp_gt_f32_e32 vcc, s15, v208
	s_nop 0
	v_cndmask_b32_e64 v163, v209, v163, s[2:3]
	v_rsq_f32_e32 v163, v163
	s_nop 0
	v_mul_f32_e32 v207, 0x45800000, v163
	v_cndmask_b32_e64 v210, v163, v207, s[2:3]
	v_pk_mul_f32 v[158:159], v[158:159], v[210:211] op_sel_hi:[1,0]
	v_pk_mul_f32 v[160:161], v[160:161], v[210:211] op_sel_hi:[1,0]
	v_pk_fma_f32 v[158:159], v[166:167], v[158:159], v[2:3]
	v_pk_fma_f32 v[160:161], v[164:165], v[160:161], v[4:5]
	v_cvt_pk_bf16_f32 v158, v158, v159
	v_cvt_pk_bf16_f32 v159, v160, v161
	v_add_co_u32_e64 v160, s[2:3], s10, v196
	v_pk_mul_f32 v[130:131], v[130:131], v[210:211] op_sel_hi:[1,0]
	v_pk_mul_f32 v[132:133], v[132:133], v[210:211] op_sel_hi:[1,0]
	v_addc_co_u32_e64 v161, s[2:3], -1, v197, s[2:3]
	v_pk_fma_f32 v[132:133], v[192:193], v[132:133], v[32:33]
	v_pk_fma_f32 v[130:131], v[194:195], v[130:131], v[30:31]
	v_pk_mul_f32 v[142:143], v[142:143], v[210:211] op_sel_hi:[1,0]
	v_cvt_pk_bf16_f32 v130, v130, v131
	v_cvt_pk_bf16_f32 v131, v132, v133
	v_add_co_u32_e64 v132, s[2:3], s11, v196
	v_pk_mul_f32 v[144:145], v[144:145], v[210:211] op_sel_hi:[1,0]
	s_nop 0
	v_addc_co_u32_e64 v133, s[2:3], -1, v197, s[2:3]
	global_store_dwordx2 v[132:133], v[130:131], off offset:-4096 sc0 sc1
	v_mul_f32_e32 v130, 0x4b800000, v208
	v_cndmask_b32_e32 v130, v208, v130, vcc
	v_rsq_f32_e32 v130, v130
	v_pk_fma_f32 v[144:145], v[176:177], v[144:145], v[16:17]
	v_pk_fma_f32 v[142:143], v[178:179], v[142:143], v[14:15]
	v_pk_mul_f32 v[154:155], v[154:155], v[210:211] op_sel_hi:[1,0]
	v_mul_f32_e32 v131, 0x45800000, v130
	v_cndmask_b32_e32 v130, v130, v131, vcc
	v_pk_mul_f32 v[102:103], v[102:103], v[130:131] op_sel_hi:[1,0]
	v_pk_mul_f32 v[104:105], v[104:105], v[130:131] op_sel_hi:[1,0]
	v_pk_mul_f32 v[98:99], v[98:99], v[130:131] op_sel_hi:[1,0]
	v_pk_mul_f32 v[100:101], v[100:101], v[130:131] op_sel_hi:[1,0]
	v_pk_fma_f32 v[104:105], v[188:189], v[104:105], v[28:29]
	v_pk_fma_f32 v[102:103], v[190:191], v[102:103], v[26:27]
	v_pk_fma_f32 v[100:101], v[192:193], v[100:101], v[32:33]
	v_pk_fma_f32 v[98:99], v[194:195], v[98:99], v[30:31]
	v_cvt_pk_bf16_f32 v102, v102, v103
	v_cvt_pk_bf16_f32 v103, v104, v105
	v_cvt_pk_bf16_f32 v98, v98, v99
	v_cvt_pk_bf16_f32 v99, v100, v101
	s_waitcnt vmcnt(16)
; __device__ __forceinline__ void norm_rows(int gw, int lane, const float* x, const float* ctx, const float* ng, const float* mod, f16* h) {
;     ...
;     auto finish_row = [&](const f32x4 (&v)[8], f16* dst) { float ss = 0.f;
; #pragma unroll
;         for (int j = 0; j < 8; ++j) ss += (v[j][0] * v[j][0] + v[j][1] * v[j][1]) + (v[j][2] * v[j][2] + v[j][3] * v[j][3]);
;         const float rstd = rsqrtf(wave_sum(ss) * (1.f / D) + EPS);
; #pragma unroll
;         for (int j = 0; j < 8; ++j) { const f32x4 o = v[j] * rstd * gs[j] + sh[j]; u32x2 w; w.x = pk_f16(o[0], o[1]); w.y = pk_f16(o[2], o[3]); *(u32x2*)(dst + 256 * j + 4 * lane) = w; } };
	v_mov_b32_e32 v100, v95
	s_waitcnt vmcnt(15)
	v_mov_b32_e32 v101, v91
	global_store_dwordx2 v[132:133], v[102:103], off offset:-512 sc0 sc1
	global_store_dwordx2 v[132:133], v[98:99], off sc0 sc1
	v_mov_b32_e32 v98, v94
	v_mov_b32_e32 v99, v90
	v_pk_mul_f32 v[100:101], v[100:101], v[100:101]
	v_mov_b32_e32 v102, v97
	v_mov_b32_e32 v103, v93
	v_pk_fma_f32 v[98:99], v[98:99], v[98:99], v[100:101]
	v_mov_b32_e32 v100, v96
	v_mov_b32_e32 v101, v92
	v_pk_mul_f32 v[102:103], v[102:103], v[102:103]
	v_pk_mul_f32 v[106:107], v[106:107], v[130:131] op_sel_hi:[1,0]
	v_pk_fma_f32 v[100:101], v[100:101], v[100:101], v[102:103]
	s_waitcnt vmcnt(16)
	v_pk_mul_f32 v[102:103], v[86:87], v[86:87]
	v_pk_add_f32 v[98:99], v[98:99], v[100:101]
	v_pk_mul_f32 v[100:101], v[88:89], v[88:89]
	v_pk_add_f32 v[98:99], v[98:99], v[98:99] op_sel:[0,1] op_sel_hi:[1,0]
	v_pk_mov_b32 v[104:105], v[102:103], v[100:101] op_sel:[1,0]
	v_mov_b32_e32 v103, v101
	v_pk_add_f32 v[100:101], v[104:105], v[102:103]
	s_waitcnt vmcnt(14)
	v_mul_f32_e32 v102, v82, v82
	v_mul_f32_e32 v103, v83, v83
	v_pk_add_f32 v[100:101], v[100:101], v[100:101] op_sel:[0,1] op_sel_hi:[1,0]
	v_mov_b32_e32 v99, v102
	v_mov_b32_e32 v101, v103
	v_pk_add_f32 v[98:99], v[98:99], v[100:101]
	v_mul_f32_e32 v100, v79, v79
	v_mul_f32_e32 v102, v81, v81
	v_mul_f32_e32 v104, v84, v84
	v_mul_f32_e32 v105, v85, v85
	v_pk_fma_f32 v[100:101], v[78:79], v[78:79], v[100:101] op_sel_hi:[1,1,0]
	v_pk_fma_f32 v[102:103], v[80:81], v[80:81], v[102:103] op_sel_hi:[1,1,0]
	v_mov_b32_e32 v101, v104
	v_mov_b32_e32 v103, v105
	v_pk_add_f32 v[100:101], v[100:101], v[102:103]
	s_waitcnt vmcnt(13)
	v_pk_mul_f32 v[102:103], v[74:75], v[74:75]
	v_pk_add_f32 v[98:99], v[98:99], v[100:101]
	v_pk_mul_f32 v[100:101], v[76:77], v[76:77]
	v_pk_add_f32 v[98:99], v[98:99], v[98:99] op_sel:[0,1] op_sel_hi:[1,0]
	v_pk_mov_b32 v[104:105], v[102:103], v[100:101] op_sel:[1,0]
	v_mov_b32_e32 v103, v101
	v_pk_add_f32 v[100:101], v[104:105], v[102:103]
	s_waitcnt vmcnt(11)
	v_mul_f32_e32 v102, v66, v66
	v_mul_f32_e32 v103, v67, v67
	v_pk_add_f32 v[100:101], v[100:101], v[100:101] op_sel:[0,1] op_sel_hi:[1,0]
	v_mov_b32_e32 v99, v102
	v_mov_b32_e32 v101, v103
	v_pk_add_f32 v[98:99], v[98:99], v[100:101]
	v_mul_f32_e32 v100, v71, v71
	v_mul_f32_e32 v102, v73, v73
	v_mul_f32_e32 v104, v68, v68
	v_mul_f32_e32 v105, v69, v69
	v_pk_fma_f32 v[100:101], v[70:71], v[70:71], v[100:101] op_sel_hi:[1,1,0]
	v_pk_fma_f32 v[102:103], v[72:73], v[72:73], v[102:103] op_sel_hi:[1,1,0]
	v_mov_b32_e32 v101, v104
	v_mov_b32_e32 v103, v105
	v_pk_add_f32 v[100:101], v[100:101], v[102:103]
	s_waitcnt vmcnt(10)
	v_mov_b32_e32 v102, v63
	s_waitcnt vmcnt(9)
	v_mov_b32_e32 v103, v59
	v_pk_add_f32 v[98:99], v[98:99], v[100:101]
	v_mov_b32_e32 v100, v62
	v_mov_b32_e32 v101, v58
	v_pk_mul_f32 v[102:103], v[102:103], v[102:103]
	v_mov_b32_e32 v104, v65
	v_mov_b32_e32 v105, v61
	v_pk_mul_f32 v[108:109], v[108:109], v[130:131] op_sel_hi:[1,0]
	v_pk_fma_f32 v[100:101], v[100:101], v[100:101], v[102:103]
	v_mov_b32_e32 v102, v64
	v_mov_b32_e32 v103, v60
	v_pk_mul_f32 v[104:105], v[104:105], v[104:105]
	v_pk_fma_f32 v[108:109], v[184:185], v[108:109], v[24:25]
	v_pk_fma_f32 v[106:107], v[186:187], v[106:107], v[22:23]
	v_pk_fma_f32 v[102:103], v[102:103], v[102:103], v[104:105]
	v_cvt_pk_bf16_f32 v106, v106, v107
	v_cvt_pk_bf16_f32 v107, v108, v109
	v_pk_add_f32 v[100:101], v[100:101], v[102:103]
	s_waitcnt vmcnt(8)
	v_pk_mul_f32 v[102:103], v[56:57], v[56:57]
	v_pk_mul_f32 v[104:105], v[54:55], v[54:55]
	global_store_dwordx2 v[132:133], v[106:107], off offset:-1024 sc0 sc1
	v_pk_mov_b32 v[106:107], v[104:105], v[102:103] op_sel:[1,0]
	v_mov_b32_e32 v105, v103
	v_pk_add_f32 v[102:103], v[106:107], v[104:105]
	s_waitcnt vmcnt(7)
	v_mul_f32_e32 v104, v46, v46
	v_mul_f32_e32 v105, v47, v47
	v_pk_add_f32 v[100:101], v[100:101], v[100:101] op_sel:[0,1] op_sel_hi:[1,0]
	v_pk_add_f32 v[102:103], v[102:103], v[102:103] op_sel:[0,1] op_sel_hi:[1,0]
	v_mov_b32_e32 v101, v104
	v_mov_b32_e32 v103, v105
	v_pk_add_f32 v[100:101], v[100:101], v[102:103]
	v_mul_f32_e32 v102, v51, v51
	v_mul_f32_e32 v104, v53, v53
	v_mul_f32_e32 v106, v48, v48
	v_mul_f32_e32 v107, v49, v49
	v_pk_fma_f32 v[102:103], v[50:51], v[50:51], v[102:103] op_sel_hi:[1,1,0]
	v_pk_fma_f32 v[104:105], v[52:53], v[52:53], v[104:105] op_sel_hi:[1,1,0]
	v_mov_b32_e32 v103, v106
	v_mov_b32_e32 v105, v107
	v_pk_add_f32 v[102:103], v[102:103], v[104:105]
	s_waitcnt vmcnt(6)
	v_pk_mul_f32 v[104:105], v[42:43], v[42:43]
	v_pk_add_f32 v[100:101], v[100:101], v[102:103]
	v_pk_mul_f32 v[102:103], v[44:45], v[44:45]
	v_pk_add_f32 v[100:101], v[100:101], v[100:101] op_sel:[0,1] op_sel_hi:[1,0]
	v_pk_mov_b32 v[106:107], v[104:105], v[102:103] op_sel:[1,0]
	v_mov_b32_e32 v105, v103
	v_pk_add_f32 v[102:103], v[106:107], v[104:105]
	s_waitcnt vmcnt(4)
	v_mul_f32_e32 v104, v34, v34
	v_mul_f32_e32 v105, v35, v35
	v_pk_add_f32 v[102:103], v[102:103], v[102:103] op_sel:[0,1] op_sel_hi:[1,0]
	v_mov_b32_e32 v101, v104
	v_mov_b32_e32 v103, v105
	v_pk_add_f32 v[100:101], v[100:101], v[102:103]
	v_mul_f32_e32 v102, v39, v39
	v_mul_f32_e32 v104, v41, v41
	v_mul_f32_e32 v106, v36, v36
	v_mul_f32_e32 v107, v37, v37
	v_pk_fma_f32 v[102:103], v[38:39], v[38:39], v[102:103] op_sel_hi:[1,1,0]
	v_pk_fma_f32 v[104:105], v[40:41], v[40:41], v[104:105] op_sel_hi:[1,1,0]
	v_mov_b32_e32 v103, v106
	v_mov_b32_e32 v105, v107
	v_pk_add_f32 v[102:103], v[102:103], v[104:105]
	v_pk_mul_f32 v[110:111], v[110:111], v[130:131] op_sel_hi:[1,0]
	v_pk_add_f32 v[100:101], v[100:101], v[102:103]
	v_mov_b32_e32 v103, v98
	v_mov_b32_e32 v102, v100
	v_mov_b32_e32 v98, v101
	v_pk_add_f32 v[98:99], v[102:103], v[98:99]
	ds_bpermute_b32 v101, v1, v99
	ds_bpermute_b32 v100, v1, v98
	v_pk_mul_f32 v[112:113], v[112:113], v[130:131] op_sel_hi:[1,0]
	v_pk_fma_f32 v[110:111], v[178:179], v[110:111], v[14:15]
	v_pk_fma_f32 v[112:113], v[176:177], v[112:113], v[16:17]
	v_cvt_pk_bf16_f32 v142, v142, v143
	s_waitcnt lgkmcnt(0)
; __device__ __forceinline__ void norm_rows(int gw, int lane, const float* x, const float* ctx, const float* ng, const float* mod, f16* h) {
;     ...
;     auto finish_row = [&](const f32x4 (&v)[8], f16* dst) { float ss = 0.f;
; #pragma unroll
;         for (int j = 0; j < 8; ++j) ss += (v[j][0] * v[j][0] + v[j][1] * v[j][1]) + (v[j][2] * v[j][2] + v[j][3] * v[j][3]);
;         const float rstd = rsqrtf(wave_sum(ss) * (1.f / D) + EPS);
; #pragma unroll
;         for (int j = 0; j < 8; ++j) { const f32x4 o = v[j] * rstd * gs[j] + sh[j]; u32x2 w; w.x = pk_f16(o[0], o[1]); w.y = pk_f16(o[2], o[3]); *(u32x2*)(dst + 256 * j + 4 * lane) = w; } };
	v_pk_add_f32 v[98:99], v[98:99], v[100:101]
	ds_bpermute_b32 v101, v202, v99
	ds_bpermute_b32 v100, v202, v98
	v_cvt_pk_bf16_f32 v143, v144, v145
	v_cvt_pk_bf16_f32 v110, v110, v111
	v_cvt_pk_bf16_f32 v111, v112, v113
	v_pk_mul_f32 v[156:157], v[156:157], v[210:211] op_sel_hi:[1,0]
	s_waitcnt lgkmcnt(0)
	v_pk_add_f32 v[98:99], v[98:99], v[100:101]
	ds_bpermute_b32 v101, v203, v99
	ds_bpermute_b32 v100, v203, v98
	v_pk_mul_f32 v[150:151], v[150:151], v[210:211] op_sel_hi:[1,0]
	v_pk_mul_f32 v[152:153], v[152:153], v[210:211] op_sel_hi:[1,0]
	global_store_dwordx2 v[160:161], v[142:143], off offset:-2048 sc0 sc1
	v_pk_mul_f32 v[142:143], v[146:147], v[210:211] op_sel_hi:[1,0]
	s_waitcnt lgkmcnt(0)
	v_pk_add_f32 v[98:99], v[98:99], v[100:101]
	ds_bpermute_b32 v101, v204, v99
	ds_bpermute_b32 v100, v204, v98
	v_pk_mul_f32 v[144:145], v[148:149], v[210:211] op_sel_hi:[1,0]
	v_pk_mul_f32 v[138:139], v[138:139], v[210:211] op_sel_hi:[1,0]
	v_pk_mul_f32 v[140:141], v[140:141], v[210:211] op_sel_hi:[1,0]
	v_pk_mul_f32 v[134:135], v[134:135], v[210:211] op_sel_hi:[1,0]
	s_waitcnt lgkmcnt(0)
	v_pk_add_f32 v[98:99], v[98:99], v[100:101]
	ds_bpermute_b32 v101, v205, v99
	ds_bpermute_b32 v100, v205, v98
	v_pk_mul_f32 v[136:137], v[136:137], v[210:211] op_sel_hi:[1,0]
	v_pk_mul_f32 v[126:127], v[126:127], v[130:131] op_sel_hi:[1,0]
	v_pk_mul_f32 v[128:129], v[128:129], v[130:131] op_sel_hi:[1,0]
	v_pk_mul_f32 v[122:123], v[122:123], v[130:131] op_sel_hi:[1,0]
	s_waitcnt lgkmcnt(0)
	v_pk_add_f32 v[98:99], v[98:99], v[100:101]
	ds_bpermute_b32 v101, v206, v99
	ds_bpermute_b32 v100, v206, v98
	v_pk_mul_f32 v[124:125], v[124:125], v[130:131] op_sel_hi:[1,0]
	v_pk_mul_f32 v[118:119], v[118:119], v[130:131] op_sel_hi:[1,0]
	v_pk_mul_f32 v[120:121], v[120:121], v[130:131] op_sel_hi:[1,0]
	global_store_dwordx2 v[132:133], v[110:111], off offset:-2048 sc0 sc1
	s_waitcnt lgkmcnt(0)
	v_pk_add_f32 v[98:99], v[98:99], v[100:101]
	v_pk_mul_f32 v[110:111], v[114:115], v[130:131] op_sel_hi:[1,0]
	v_pk_fma_f32 v[98:99], v[98:99], s[14:15], v[200:201] op_sel_hi:[1,0,0]
	v_pk_mul_f32 v[112:113], v[116:117], v[130:131] op_sel_hi:[1,0]
	v_mul_f32_e32 v100, 0x4b800000, v99
	v_cmp_gt_f32_e64 s[2:3], s15, v99
	v_cmp_gt_f32_e32 vcc, s15, v98
	v_pk_fma_f32 v[156:157], v[168:169], v[156:157], v[8:9]
	v_cndmask_b32_e64 v99, v99, v100, s[2:3]
	v_rsq_f32_e32 v99, v99
	v_pk_fma_f32 v[154:155], v[170:171], v[154:155], v[6:7]
	v_pk_fma_f32 v[152:153], v[172:173], v[152:153], v[12:13]
	v_pk_fma_f32 v[150:151], v[174:175], v[150:151], v[10:11]
	v_mul_f32_e32 v100, 0x45800000, v99
	v_cndmask_b32_e64 v100, v99, v100, s[2:3]
	v_pk_mul_f32 v[66:67], v[66:67], v[100:101] op_sel_hi:[1,0]
	v_pk_mul_f32 v[68:69], v[68:69], v[100:101] op_sel_hi:[1,0]
	v_pk_fma_f32 v[66:67], v[194:195], v[66:67], v[30:31]
	v_pk_fma_f32 v[68:69], v[192:193], v[68:69], v[32:33]
	v_cvt_pk_bf16_f32 v66, v66, v67
	v_cvt_pk_bf16_f32 v67, v68, v69
	global_store_dwordx2 v[196:197], v[66:67], off offset:-4096 sc0 sc1
	v_mul_f32_e32 v66, 0x4b800000, v98
	v_cndmask_b32_e32 v66, v98, v66, vcc
	v_rsq_f32_e32 v66, v66
	v_pk_mul_f32 v[94:95], v[94:95], v[100:101] op_sel_hi:[1,0]
	v_pk_mul_f32 v[96:97], v[96:97], v[100:101] op_sel_hi:[1,0]
	v_pk_fma_f32 v[94:95], v[166:167], v[94:95], v[2:3]
	v_pk_fma_f32 v[96:97], v[164:165], v[96:97], v[4:5]
	v_pk_mul_f32 v[78:79], v[78:79], v[100:101] op_sel_hi:[1,0]
	v_pk_mul_f32 v[80:81], v[80:81], v[100:101] op_sel_hi:[1,0]
	v_mul_f32_e32 v67, 0x45800000, v66
	v_cvt_pk_bf16_f32 v94, v94, v95
	v_cvt_pk_bf16_f32 v95, v96, v97
	v_add_co_u32_e64 v96, s[2:3], s13, v196
	v_pk_fma_f32 v[80:81], v[176:177], v[80:81], v[16:17]
	v_pk_fma_f32 v[78:79], v[178:179], v[78:79], v[14:15]
	v_cndmask_b32_e32 v66, v66, v67, vcc
	v_addc_co_u32_e64 v97, s[2:3], -1, v197, s[2:3]
	v_cvt_pk_bf16_f32 v78, v78, v79
	v_cvt_pk_bf16_f32 v79, v80, v81
	v_pk_mul_f32 v[62:63], v[62:63], v[66:67] op_sel_hi:[1,0]
	v_pk_mul_f32 v[64:65], v[64:65], v[66:67] op_sel_hi:[1,0]
	v_pk_mul_f32 v[58:59], v[58:59], v[66:67] op_sel_hi:[1,0]
	v_pk_mul_f32 v[60:61], v[60:61], v[66:67] op_sel_hi:[1,0]
	v_pk_mul_f32 v[54:55], v[54:55], v[66:67] op_sel_hi:[1,0]
	v_pk_mul_f32 v[56:57], v[56:57], v[66:67] op_sel_hi:[1,0]
	v_pk_mul_f32 v[50:51], v[50:51], v[66:67] op_sel_hi:[1,0]
	v_pk_mul_f32 v[52:53], v[52:53], v[66:67] op_sel_hi:[1,0]
	v_pk_mul_f32 v[46:47], v[46:47], v[66:67] op_sel_hi:[1,0]
	v_pk_mul_f32 v[48:49], v[48:49], v[66:67] op_sel_hi:[1,0]
	v_pk_mul_f32 v[42:43], v[42:43], v[66:67] op_sel_hi:[1,0]
	v_pk_mul_f32 v[44:45], v[44:45], v[66:67] op_sel_hi:[1,0]
	v_pk_mul_f32 v[38:39], v[38:39], v[66:67] op_sel_hi:[1,0]
	v_pk_mul_f32 v[40:41], v[40:41], v[66:67] op_sel_hi:[1,0]
	v_pk_mul_f32 v[34:35], v[34:35], v[66:67] op_sel_hi:[1,0]
	v_pk_mul_f32 v[36:37], v[36:37], v[66:67] op_sel_hi:[1,0]
	v_pk_mul_f32 v[90:91], v[90:91], v[100:101] op_sel_hi:[1,0]
	v_pk_mul_f32 v[92:93], v[92:93], v[100:101] op_sel_hi:[1,0]
	v_pk_mul_f32 v[86:87], v[86:87], v[100:101] op_sel_hi:[1,0]
	v_pk_mul_f32 v[88:89], v[88:89], v[100:101] op_sel_hi:[1,0]
	global_store_dwordx2 v[96:97], v[78:79], off offset:-2048 sc0 sc1
	v_pk_mul_f32 v[78:79], v[82:83], v[100:101] op_sel_hi:[1,0]
	v_pk_mul_f32 v[80:81], v[84:85], v[100:101] op_sel_hi:[1,0]
	v_pk_mul_f32 v[74:75], v[74:75], v[100:101] op_sel_hi:[1,0]
	v_pk_mul_f32 v[76:77], v[76:77], v[100:101] op_sel_hi:[1,0]
	v_pk_mul_f32 v[70:71], v[70:71], v[100:101] op_sel_hi:[1,0]
	v_pk_mul_f32 v[72:73], v[72:73], v[100:101] op_sel_hi:[1,0]
	v_pk_fma_f32 v[64:65], v[164:165], v[64:65], v[4:5]
	v_pk_fma_f32 v[62:63], v[166:167], v[62:63], v[2:3]
	v_pk_fma_f32 v[60:61], v[168:169], v[60:61], v[8:9]
; __device__ __forceinline__ void norm_rows(int gw, int lane, const float* x, const float* ctx, const float* ng, const float* mod, f16* h) {
;     ...
; #pragma unroll
;         for (int j = 0; j < 8; ++j) { const f32x4 o = v[j] * rstd * gs[j] + sh[j]; u32x2 w; w.x = pk_f16(o[0], o[1]); w.y = pk_f16(o[2], o[3]); *(u32x2*)(dst + 256 * j + 4 * lane) = w; } };
;     ...
;         for (int rb = r0; rb < r0 + RPW; rb += 4) { f32x4 v[4][8];
	v_pk_fma_f32 v[58:59], v[170:171], v[58:59], v[6:7]
	v_pk_fma_f32 v[56:57], v[172:173], v[56:57], v[12:13]
	v_pk_fma_f32 v[54:55], v[174:175], v[54:55], v[10:11]
	v_pk_fma_f32 v[52:53], v[176:177], v[52:53], v[16:17]
	v_pk_fma_f32 v[50:51], v[178:179], v[50:51], v[14:15]
	v_pk_fma_f32 v[48:49], v[180:181], v[48:49], v[20:21]
	v_pk_fma_f32 v[46:47], v[182:183], v[46:47], v[18:19]
	v_pk_fma_f32 v[44:45], v[184:185], v[44:45], v[24:25]
	v_pk_fma_f32 v[42:43], v[186:187], v[42:43], v[22:23]
	v_pk_fma_f32 v[40:41], v[188:189], v[40:41], v[28:29]
	v_pk_fma_f32 v[38:39], v[190:191], v[38:39], v[26:27]
	v_pk_fma_f32 v[36:37], v[192:193], v[36:37], v[32:33]
	v_pk_fma_f32 v[34:35], v[194:195], v[34:35], v[30:31]
	v_pk_fma_f32 v[144:145], v[180:181], v[144:145], v[20:21]
	v_pk_fma_f32 v[142:143], v[182:183], v[142:143], v[18:19]
	v_pk_fma_f32 v[140:141], v[184:185], v[140:141], v[24:25]
	v_pk_fma_f32 v[138:139], v[186:187], v[138:139], v[22:23]
	v_pk_fma_f32 v[136:137], v[188:189], v[136:137], v[28:29]
	v_pk_fma_f32 v[134:135], v[190:191], v[134:135], v[26:27]
	v_pk_fma_f32 v[128:129], v[164:165], v[128:129], v[4:5]
	v_pk_fma_f32 v[126:127], v[166:167], v[126:127], v[2:3]
	v_pk_fma_f32 v[124:125], v[168:169], v[124:125], v[8:9]
	v_pk_fma_f32 v[122:123], v[170:171], v[122:123], v[6:7]
	v_pk_fma_f32 v[120:121], v[172:173], v[120:121], v[12:13]
	v_pk_fma_f32 v[118:119], v[174:175], v[118:119], v[10:11]
	v_pk_fma_f32 v[112:113], v[180:181], v[112:113], v[20:21]
	v_pk_fma_f32 v[110:111], v[182:183], v[110:111], v[18:19]
	v_pk_fma_f32 v[92:93], v[168:169], v[92:93], v[8:9]
	v_pk_fma_f32 v[90:91], v[170:171], v[90:91], v[6:7]
	v_pk_fma_f32 v[88:89], v[172:173], v[88:89], v[12:13]
	v_pk_fma_f32 v[86:87], v[174:175], v[86:87], v[10:11]
	v_pk_fma_f32 v[80:81], v[180:181], v[80:81], v[20:21]
	v_pk_fma_f32 v[78:79], v[182:183], v[78:79], v[18:19]
	v_pk_fma_f32 v[76:77], v[184:185], v[76:77], v[24:25]
	v_pk_fma_f32 v[74:75], v[186:187], v[74:75], v[22:23]
	v_pk_fma_f32 v[72:73], v[188:189], v[72:73], v[28:29]
	v_pk_fma_f32 v[70:71], v[190:191], v[70:71], v[26:27]
	v_cvt_pk_bf16_f32 v62, v62, v63
	v_cvt_pk_bf16_f32 v63, v64, v65
	v_cvt_pk_bf16_f32 v58, v58, v59
	v_cvt_pk_bf16_f32 v59, v60, v61
	v_cvt_pk_bf16_f32 v54, v54, v55
	v_cvt_pk_bf16_f32 v55, v56, v57
	v_cvt_pk_bf16_f32 v50, v50, v51
	v_cvt_pk_bf16_f32 v51, v52, v53
	v_cvt_pk_bf16_f32 v46, v46, v47
	v_cvt_pk_bf16_f32 v47, v48, v49
	v_cvt_pk_bf16_f32 v42, v42, v43
	v_cvt_pk_bf16_f32 v43, v44, v45
	v_cvt_pk_bf16_f32 v38, v38, v39
	v_cvt_pk_bf16_f32 v39, v40, v41
	v_cvt_pk_bf16_f32 v34, v34, v35
	v_cvt_pk_bf16_f32 v35, v36, v37
	v_cvt_pk_bf16_f32 v154, v154, v155
	v_cvt_pk_bf16_f32 v155, v156, v157
	v_cvt_pk_bf16_f32 v150, v150, v151
	v_cvt_pk_bf16_f32 v151, v152, v153
	v_cvt_pk_bf16_f32 v142, v142, v143
	v_cvt_pk_bf16_f32 v143, v144, v145
	v_cvt_pk_bf16_f32 v138, v138, v139
	v_cvt_pk_bf16_f32 v139, v140, v141
	v_cvt_pk_bf16_f32 v134, v134, v135
	v_cvt_pk_bf16_f32 v135, v136, v137
	v_cvt_pk_bf16_f32 v126, v126, v127
	v_cvt_pk_bf16_f32 v127, v128, v129
	v_cvt_pk_bf16_f32 v122, v122, v123
	v_cvt_pk_bf16_f32 v123, v124, v125
	v_cvt_pk_bf16_f32 v118, v118, v119
	v_cvt_pk_bf16_f32 v119, v120, v121
	v_cvt_pk_bf16_f32 v110, v110, v111
	v_cvt_pk_bf16_f32 v111, v112, v113
	v_cvt_pk_bf16_f32 v90, v90, v91
	v_cvt_pk_bf16_f32 v91, v92, v93
	v_cvt_pk_bf16_f32 v86, v86, v87
	v_cvt_pk_bf16_f32 v87, v88, v89
	v_cvt_pk_bf16_f32 v78, v78, v79
	v_cvt_pk_bf16_f32 v79, v80, v81
	v_cvt_pk_bf16_f32 v74, v74, v75
	v_cvt_pk_bf16_f32 v75, v76, v77
	v_cvt_pk_bf16_f32 v70, v70, v71
	v_cvt_pk_bf16_f32 v71, v72, v73
	global_store_dwordx2 v[196:197], v[62:63], off offset:-3584 sc0 sc1
	global_store_dwordx2 v[196:197], v[58:59], off offset:-3072 sc0 sc1
	global_store_dwordx2 v[196:197], v[54:55], off offset:-2560 sc0 sc1
	global_store_dwordx2 v[196:197], v[50:51], off offset:-2048 sc0 sc1
	global_store_dwordx2 v[196:197], v[46:47], off offset:-1536 sc0 sc1
	global_store_dwordx2 v[196:197], v[42:43], off offset:-1024 sc0 sc1
	global_store_dwordx2 v[196:197], v[38:39], off offset:-512 sc0 sc1
	global_store_dwordx2 v[196:197], v[34:35], off sc0 sc1
	v_lshl_add_u64 v[196:197], v[196:197], 0, s[24:25]
	global_store_dwordx2 v[160:161], v[158:159], off offset:-3584 sc0 sc1
	global_store_dwordx2 v[160:161], v[154:155], off offset:-3072 sc0 sc1
	global_store_dwordx2 v[160:161], v[150:151], off offset:-2560 sc0 sc1
	global_store_dwordx2 v[160:161], v[142:143], off offset:-1536 sc0 sc1
	global_store_dwordx2 v[160:161], v[138:139], off offset:-1024 sc0 sc1
	global_store_dwordx2 v[160:161], v[134:135], off offset:-512 sc0 sc1
	global_store_dwordx2 v[132:133], v[126:127], off offset:-3584 sc0 sc1
	global_store_dwordx2 v[132:133], v[122:123], off offset:-3072 sc0 sc1
	global_store_dwordx2 v[132:133], v[118:119], off offset:-2560 sc0 sc1
	global_store_dwordx2 v[132:133], v[110:111], off offset:-1536 sc0 sc1
	global_store_dwordx2 v[96:97], v[94:95], off offset:-3584 sc0 sc1
	global_store_dwordx2 v[96:97], v[90:91], off offset:-3072 sc0 sc1
	global_store_dwordx2 v[96:97], v[86:87], off offset:-2560 sc0 sc1
	global_store_dwordx2 v[96:97], v[78:79], off offset:-1536 sc0 sc1
	global_store_dwordx2 v[96:97], v[74:75], off offset:-1024 sc0 sc1
	global_store_dwordx2 v[96:97], v[70:71], off offset:-512 sc0 sc1
	s_cbranch_scc1 .LBB0_181
; __device__ __forceinline__ f32x4 ld_nt(const float* p) { return __builtin_nontemporal_load((const f32x4*)p); }
; __device__ __forceinline__ void norm_rows(int gw, int lane, const float* x, const float* ctx, const float* ng, const float* mod, f16* h) {
;     ...
;     auto load_mod = [&](int mr) { const float* shp = mod + mr * 3 * D;
; #pragma unroll
;         for (int j = 0; j < 8; ++j) { const int cidx = 256 * j + 4 * lane; const f32x4 g4 = *(const f32x4*)(ng + cidx), s4 = *(const f32x4*)(shp + D + cidx); gs[j] = g4 * (1.f + s4); sh[j] = *(const f32x4*)(shp + cidx); } };
;     auto finish_row = [&](const f32x4 (&v)[8], f16* dst) { float ss = 0.f;
; #pragma unroll
;         for (int j = 0; j < 8; ++j) ss += (v[j][0] * v[j][0] + v[j][1] * v[j][1]) + (v[j][2] * v[j][2] + v[j][3] * v[j][3]);
;     ...
;     if (gw < M_CTX) { load_mod(2); f32x4 v[8];
; #pragma unroll
;         for (int j = 0; j < 8; ++j) v[j] = ld_nt(ctx + (size_t)gw * D + 256 * j + 4 * lane);
.LBB0_182:
	s_cmpk_gt_i32 s6, 0x1ff
	s_cbranch_scc1 .LBB0_184
	s_add_u32 s2, s50, 0x10c000
	s_addc_u32 s3, s51, 0
	s_add_u32 s10, s50, 0x10e000
	s_addc_u32 s11, s51, 0
	s_ashr_i32 s7, s6, 31
	v_readlane_b32 s56, v254, 2
	v_or_b32_e32 v1, 0x400, v162
	s_lshl_b64 s[8:9], s[6:7], 13
	v_readlane_b32 s60, v254, 6
	global_load_dwordx4 v[50:53], v162, s[10:11]
	global_load_dwordx4 v[54:57], v1, s[10:11]
	v_or_b32_e32 v34, 0x800, v162
	v_readlane_b32 s61, v254, 7
	s_add_u32 s8, s60, s8
	global_load_dwordx4 v[58:61], v34, s[10:11]
	v_or_b32_e32 v35, 0xc00, v162
	v_or_b32_e32 v22, 0x1000, v162
	v_or_b32_e32 v133, 0x1400, v162
	s_addc_u32 s9, s61, s9
	global_load_dwordx4 v[62:65], v35, s[10:11]
	global_load_dwordx4 v[66:69], v22, s[10:11]
	global_load_dwordx4 v[70:73], v133, s[10:11]
	global_load_dwordx4 v[42:45], v162, s[8:9] nt
	global_load_dwordx4 v[30:33], v162, s[8:9] offset:1024 nt
	global_load_dwordx4 v[26:29], v162, s[8:9] offset:2048 nt
	global_load_dwordx4 v[18:21], v162, s[8:9] offset:3072 nt
	v_mov_b32_e32 v163, 0
	s_movk_i32 s12, 0x1000
	v_lshl_add_u64 v[2:3], s[8:9], 0, v[162:163]
	v_add_co_u32_e32 v6, vcc, s12, v2
	v_readlane_b32 s68, v254, 14
	s_nop 0
	v_addc_co_u32_e32 v7, vcc, 0, v3, vcc
	v_readlane_b32 s69, v254, 15
	global_load_dwordx4 v[14:17], v[6:7], off nt
	global_load_dwordx4 v[10:13], v[6:7], off offset:1024 nt
	global_load_dwordx4 v[2:5], v[6:7], off offset:3072 nt
	s_nop 0
	global_load_dwordx4 v[6:9], v[6:7], off offset:2048 nt
	s_nop 0
	global_load_dwordx4 v[74:77], v162, s[68:69]
	global_load_dwordx4 v[78:81], v162, s[68:69] offset:1024
	global_load_dwordx4 v[82:85], v162, s[68:69] offset:2048
	global_load_dwordx4 v[86:89], v162, s[68:69] offset:3072
	v_or_b32_e32 v136, 0x1800, v162
	v_or_b32_e32 v137, 0x1c00, v162
	global_load_dwordx4 v[90:93], v133, s[68:69]
	global_load_dwordx4 v[94:97], v136, s[68:69]
	global_load_dwordx4 v[98:101], v137, s[68:69]
	global_load_dwordx4 v[102:105], v22, s[68:69]
	s_nop 0
	global_load_dwordx4 v[22:25], v22, s[2:3]
	s_nop 0
	global_load_dwordx4 v[106:109], v162, s[2:3]
	global_load_dwordx4 v[46:49], v1, s[2:3]
	global_load_dwordx4 v[38:41], v34, s[2:3]
	s_nop 0
	global_load_dwordx4 v[34:37], v35, s[2:3]
	s_nop 0
	global_load_dwordx4 v[110:113], v136, s[10:11]
	global_load_dwordx4 v[114:117], v137, s[10:11]
	v_lshlrev_b32_e32 v162, 3, v212
	v_readlane_b32 s57, v254, 3
	v_readlane_b32 s58, v254, 4
	v_readlane_b32 s59, v254, 5
	v_readlane_b32 s62, v254, 8
	v_readlane_b32 s63, v254, 9
	v_readlane_b32 s64, v254, 10
	v_readlane_b32 s65, v254, 11
	v_readlane_b32 s66, v254, 12
	v_readlane_b32 s67, v254, 13
	v_readlane_b32 s70, v254, 16
	v_readlane_b32 s71, v254, 17
	s_waitcnt vmcnt(0)
	v_pk_add_f32 v[118:119], v[52:53], 1.0 op_sel_hi:[1,0]
	v_pk_add_f32 v[122:123], v[56:57], 1.0 op_sel_hi:[1,0]
	v_pk_add_f32 v[120:121], v[50:51], 1.0 op_sel_hi:[1,0]
	v_pk_add_f32 v[124:125], v[54:55], 1.0 op_sel_hi:[1,0]
	v_pk_add_f32 v[126:127], v[60:61], 1.0 op_sel_hi:[1,0]
	v_pk_add_f32 v[128:129], v[58:59], 1.0 op_sel_hi:[1,0]
	v_mov_b32_e32 v52, v43
	v_mov_b32_e32 v53, v31
	v_mov_b32_e32 v56, v45
	v_mov_b32_e32 v57, v33
	v_mov_b32_e32 v50, v42
	v_mov_b32_e32 v51, v30
	v_mov_b32_e32 v54, v44
	v_mov_b32_e32 v55, v32
	v_pk_mul_f32 v[58:59], v[28:29], v[28:29]
	v_pk_mul_f32 v[60:61], v[26:27], v[26:27]
	v_pk_mul_f32 v[52:53], v[52:53], v[52:53]
	v_pk_mul_f32 v[56:57], v[56:57], v[56:57]
	v_pk_mov_b32 v[134:135], v[60:61], v[58:59] op_sel:[1,0]
	v_mov_b32_e32 v61, v59
	v_pk_fma_f32 v[50:51], v[50:51], v[50:51], v[52:53]
	v_pk_fma_f32 v[52:53], v[54:55], v[54:55], v[56:57]
	v_mul_f32_e32 v130, v19, v19
	v_mul_f32_e32 v132, v21, v21
	v_pk_add_f32 v[54:55], v[134:135], v[60:61]
	v_pk_add_f32 v[50:51], v[50:51], v[52:53]
	v_pk_fma_f32 v[58:59], v[18:19], v[18:19], v[130:131] op_sel_hi:[1,1,0]
	v_pk_fma_f32 v[130:131], v[20:21], v[20:21], v[132:133] op_sel_hi:[1,1,0]
	v_mul_f32_e32 v1, v14, v14
	v_mul_f32_e32 v56, v15, v15
	v_pk_add_f32 v[52:53], v[54:55], v[54:55] op_sel:[0,1] op_sel_hi:[1,0]
	v_pk_add_f32 v[50:51], v[50:51], v[50:51] op_sel:[0,1] op_sel_hi:[1,0]
	v_mul_f32_e32 v59, v16, v16
	v_mul_f32_e32 v131, v17, v17
	v_mov_b32_e32 v53, v56
	v_mov_b32_e32 v51, v1
	v_pk_add_f32 v[50:51], v[50:51], v[52:53]
	v_pk_add_f32 v[52:53], v[58:59], v[130:131]
	v_pk_mul_f32 v[54:55], v[10:11], v[10:11]
	v_pk_add_f32 v[50:51], v[50:51], v[52:53]
	v_pk_mul_f32 v[52:53], v[12:13], v[12:13]
	v_mul_f32_e32 v1, v2, v2
	v_pk_mov_b32 v[56:57], v[54:55], v[52:53] op_sel:[1,0]
	v_mov_b32_e32 v55, v53
	v_pk_add_f32 v[52:53], v[56:57], v[54:55]
	v_mul_f32_e32 v54, v3, v3
	v_pk_add_f32 v[50:51], v[50:51], v[50:51] op_sel:[0,1] op_sel_hi:[1,0]
	v_pk_add_f32 v[52:53], v[52:53], v[52:53] op_sel:[0,1] op_sel_hi:[1,0]
	v_mov_b32_e32 v51, v1
	v_mov_b32_e32 v53, v54
	v_pk_add_f32 v[50:51], v[50:51], v[52:53]
	v_mul_f32_e32 v52, v7, v7
	v_mul_f32_e32 v55, v4, v4
	v_pk_fma_f32 v[52:53], v[6:7], v[6:7], v[52:53] op_sel_hi:[1,1,0]
	v_mul_f32_e32 v54, v9, v9
	v_mul_f32_e32 v56, v5, v5
	v_mov_b32_e32 v53, v55
	v_pk_fma_f32 v[54:55], v[8:9], v[8:9], v[54:55] op_sel_hi:[1,1,0]
	global_load_dwordx4 v[58:61], v137, s[2:3]
	v_mov_b32_e32 v55, v56
	v_pk_add_f32 v[52:53], v[52:53], v[54:55]
	v_pk_mul_f32 v[76:77], v[76:77], v[118:119]
	v_pk_add_f32 v[50:51], v[50:51], v[52:53]
	v_pk_add_f32 v[62:63], v[62:63], 1.0 op_sel_hi:[1,0]
	v_add_f32_e32 v1, v50, v51
	v_mbcnt_lo_u32_b32 v50, -1, 0
	v_mbcnt_hi_u32_b32 v130, -1, v50
	v_and_b32_e32 v50, 64, v130
	v_add_u32_e32 v131, 64, v50
	v_xor_b32_e32 v50, 1, v130
	v_cmp_lt_i32_e32 vcc, v50, v131
	v_xor_b32_e32 v118, 8, v130
	v_pk_mul_f32 v[62:63], v[86:87], v[62:63]
	v_cndmask_b32_e32 v50, v130, v50, vcc
	v_lshlrev_b32_e32 v50, 2, v50
	ds_bpermute_b32 v54, v50, v1
	global_load_dwordx4 v[50:53], v133, s[2:3]
	v_xor_b32_e32 v86, 16, v130
	v_pk_add_f32 v[66:67], v[66:67], 1.0 op_sel_hi:[1,0]
	v_pk_add_f32 v[64:65], v[64:65], 1.0 op_sel_hi:[1,0]
	s_waitcnt lgkmcnt(0)
; __device__ __forceinline__ void norm_rows(int gw, int lane, const float* x, const float* ctx, const float* ng, const float* mod, f16* h) {
;     ...
;         const float rstd = rsqrtf(wave_sum(ss) * (1.f / D) + EPS);
; #pragma unroll
;         for (int j = 0; j < 8; ++j) { const f32x4 o = v[j] * rstd * gs[j] + sh[j]; u32x2 w; w.x = pk_f16(o[0], o[1]); w.y = pk_f16(o[2], o[3]); *(u32x2*)(dst + 256 * j + 4 * lane) = w; } };
;     ...
;         finish_row(v, h + (size_t)(M_LAT + gw) * D); }
	v_add_f32_e32 v1, v1, v54
	v_xor_b32_e32 v54, 2, v130
	v_cmp_lt_i32_e32 vcc, v54, v131
	v_pk_mul_f32 v[66:67], v[102:103], v[66:67]
	v_pk_add_f32 v[110:111], v[110:111], 1.0 op_sel_hi:[1,0]
	v_cndmask_b32_e32 v54, v130, v54, vcc
	v_lshlrev_b32_e32 v54, 2, v54
	ds_bpermute_b32 v132, v54, v1
	global_load_dwordx4 v[54:57], v136, s[2:3]
	v_pk_mul_f32 v[64:65], v[88:89], v[64:65]
	v_pk_mul_f32 v[88:89], v[94:95], v[110:111]
	v_mov_b32_e32 v94, 0x358637bd
	s_waitcnt lgkmcnt(0)
	v_add_f32_e32 v1, v1, v132
	v_xor_b32_e32 v132, 4, v130
	v_cmp_lt_i32_e32 vcc, v132, v131
	s_mov_b32 s2, 0x800000
	v_pk_mul_f32 v[74:75], v[74:75], v[120:121]
	v_cndmask_b32_e32 v132, v130, v132, vcc
	v_lshlrev_b32_e32 v132, 2, v132
	ds_bpermute_b32 v132, v132, v1
	v_cmp_lt_i32_e32 vcc, v118, v131
	v_pk_add_f32 v[68:69], v[68:69], 1.0 op_sel_hi:[1,0]
	v_pk_add_f32 v[72:73], v[72:73], 1.0 op_sel_hi:[1,0]
	v_cndmask_b32_e32 v118, v130, v118, vcc
	s_waitcnt lgkmcnt(0)
	v_add_f32_e32 v1, v1, v132
	v_lshlrev_b32_e32 v118, 2, v118
	ds_bpermute_b32 v118, v118, v1
	v_cmp_lt_i32_e32 vcc, v86, v131
	v_pk_add_f32 v[70:71], v[70:71], 1.0 op_sel_hi:[1,0]
	v_pk_add_f32 v[112:113], v[112:113], 1.0 op_sel_hi:[1,0]
	v_cndmask_b32_e32 v86, v130, v86, vcc
	s_waitcnt lgkmcnt(0)
	v_add_f32_e32 v1, v1, v118
	v_lshlrev_b32_e32 v86, 2, v86
	ds_bpermute_b32 v86, v86, v1
	v_pk_add_f32 v[116:117], v[116:117], 1.0 op_sel_hi:[1,0]
	v_pk_add_f32 v[114:115], v[114:115], 1.0 op_sel_hi:[1,0]
	v_pk_mul_f32 v[80:81], v[80:81], v[122:123]
	v_pk_mul_f32 v[78:79], v[78:79], v[124:125]
	s_waitcnt lgkmcnt(0)
	v_add_f32_e32 v1, v1, v86
	v_xor_b32_e32 v86, 32, v130
	v_cmp_lt_i32_e32 vcc, v86, v131
	v_pk_mul_f32 v[84:85], v[84:85], v[126:127]
	v_pk_mul_f32 v[82:83], v[82:83], v[128:129]
	v_cndmask_b32_e32 v86, v130, v86, vcc
	v_lshlrev_b32_e32 v86, 2, v86
	ds_bpermute_b32 v102, v86, v1
	v_pk_mul_f32 v[68:69], v[104:105], v[68:69]
	v_pk_mul_f32 v[72:73], v[92:93], v[72:73]
	v_pk_mul_f32 v[70:71], v[90:91], v[70:71]
	v_pk_mul_f32 v[86:87], v[96:97], v[112:113]
	s_waitcnt lgkmcnt(0)
	v_add_f32_e32 v1, v1, v102
	v_fmac_f32_e32 v94, 0x3a000000, v1
	v_mul_f32_e32 v1, 0x4b800000, v94
	v_cmp_gt_f32_e32 vcc, s2, v94
	s_lshl_b64 s[2:3], s[6:7], 12
	s_add_u32 s2, s50, s2
	v_cndmask_b32_e32 v1, v94, v1, vcc
	v_rsq_f32_e32 v1, v1
	s_addc_u32 s3, s51, s3
	v_pk_mul_f32 v[90:91], v[100:101], v[116:117]
	v_pk_mul_f32 v[92:93], v[98:99], v[114:115]
	v_mul_f32_e32 v94, 0x45800000, v1
	v_cndmask_b32_e32 v94, v1, v94, vcc
	v_pk_mul_f32 v[42:43], v[42:43], v[94:95] op_sel_hi:[1,0]
	v_pk_mul_f32 v[44:45], v[44:45], v[94:95] op_sel_hi:[1,0]
	v_pk_fma_f32 v[42:43], v[74:75], v[42:43], v[106:107]
	v_pk_fma_f32 v[44:45], v[76:77], v[44:45], v[108:109]
	v_cvt_pk_bf16_f32 v42, v42, v43
	v_cvt_pk_bf16_f32 v43, v44, v45
	v_lshl_add_u64 v[44:45], s[2:3], 0, v[162:163]
	s_mov_b64 s[2:3], 0xa100000
	v_lshl_add_u64 v[74:75], v[44:45], 0, s[2:3]
	s_mov_b32 s2, 0xa100000
	v_pk_mul_f32 v[30:31], v[30:31], v[94:95] op_sel_hi:[1,0]
	v_pk_mul_f32 v[32:33], v[32:33], v[94:95] op_sel_hi:[1,0]
	v_pk_mul_f32 v[26:27], v[26:27], v[94:95] op_sel_hi:[1,0]
	v_pk_mul_f32 v[28:29], v[28:29], v[94:95] op_sel_hi:[1,0]
	v_pk_mul_f32 v[18:19], v[18:19], v[94:95] op_sel_hi:[1,0]
	v_pk_mul_f32 v[20:21], v[20:21], v[94:95] op_sel_hi:[1,0]
	v_pk_mul_f32 v[14:15], v[14:15], v[94:95] op_sel_hi:[1,0]
	v_pk_mul_f32 v[16:17], v[16:17], v[94:95] op_sel_hi:[1,0]
	v_pk_mul_f32 v[10:11], v[10:11], v[94:95] op_sel_hi:[1,0]
	v_pk_mul_f32 v[12:13], v[12:13], v[94:95] op_sel_hi:[1,0]
	v_pk_mul_f32 v[6:7], v[6:7], v[94:95] op_sel_hi:[1,0]
	v_pk_mul_f32 v[8:9], v[8:9], v[94:95] op_sel_hi:[1,0]
	v_pk_mul_f32 v[2:3], v[2:3], v[94:95] op_sel_hi:[1,0]
	v_pk_mul_f32 v[4:5], v[4:5], v[94:95] op_sel_hi:[1,0]
	v_add_co_u32_e32 v44, vcc, s2, v44
	v_pk_fma_f32 v[32:33], v[80:81], v[32:33], v[48:49]
	v_pk_fma_f32 v[30:31], v[78:79], v[30:31], v[46:47]
	v_pk_fma_f32 v[28:29], v[84:85], v[28:29], v[40:41]
	v_pk_fma_f32 v[26:27], v[82:83], v[26:27], v[38:39]
	v_pk_fma_f32 v[20:21], v[64:65], v[20:21], v[36:37]
	v_pk_fma_f32 v[18:19], v[62:63], v[18:19], v[34:35]
	v_pk_fma_f32 v[16:17], v[68:69], v[16:17], v[24:25]
	v_pk_fma_f32 v[14:15], v[66:67], v[14:15], v[22:23]
	s_waitcnt vmcnt(1)
	v_pk_fma_f32 v[12:13], v[72:73], v[12:13], v[52:53]
	v_pk_fma_f32 v[10:11], v[70:71], v[10:11], v[50:51]
	s_waitcnt vmcnt(0)
	v_pk_fma_f32 v[8:9], v[86:87], v[8:9], v[56:57]
	v_pk_fma_f32 v[6:7], v[88:89], v[6:7], v[54:55]
	v_pk_fma_f32 v[4:5], v[90:91], v[4:5], v[60:61]
	v_pk_fma_f32 v[2:3], v[92:93], v[2:3], v[58:59]
	v_addc_co_u32_e32 v45, vcc, 0, v45, vcc
	v_cvt_pk_bf16_f32 v30, v30, v31
	v_cvt_pk_bf16_f32 v31, v32, v33
	v_cvt_pk_bf16_f32 v26, v26, v27
	v_cvt_pk_bf16_f32 v27, v28, v29
	v_cvt_pk_bf16_f32 v18, v18, v19
	v_cvt_pk_bf16_f32 v19, v20, v21
	v_cvt_pk_bf16_f32 v14, v14, v15
	v_cvt_pk_bf16_f32 v15, v16, v17
	v_cvt_pk_bf16_f32 v10, v10, v11
	v_cvt_pk_bf16_f32 v11, v12, v13
	v_cvt_pk_bf16_f32 v6, v6, v7
	v_cvt_pk_bf16_f32 v7, v8, v9
	v_cvt_pk_bf16_f32 v2, v2, v3
	v_cvt_pk_bf16_f32 v3, v4, v5
	global_store_dwordx2 v[44:45], v[42:43], off sc0 sc1
	global_store_dwordx2 v[74:75], v[30:31], off offset:512 sc0 sc1
	global_store_dwordx2 v[74:75], v[26:27], off offset:1024 sc0 sc1
	global_store_dwordx2 v[74:75], v[18:19], off offset:1536 sc0 sc1
	global_store_dwordx2 v[74:75], v[14:15], off offset:2048 sc0 sc1
	global_store_dwordx2 v[74:75], v[10:11], off offset:2560 sc0 sc1
	global_store_dwordx2 v[74:75], v[6:7], off offset:3072 sc0 sc1
	global_store_dwordx2 v[74:75], v[2:3], off offset:3584 sc0 sc1

; #define LAS __attribute__((address_space(3)))
; __device__ __forceinline__ f32x4 ld_nt(const float* p) { return __builtin_nontemporal_load((const f32x4*)p); }
; __device__ __forceinline__ void transpose_item(const float* W, int K, int pitch, int ncols, f16* WT, LAS float* scr, int item, int lane) {
;     const int nblk = ncols / 32, kb = item / nblk, nb = item % nblk, k0 = 64 * kb, n0 = 32 * nb;
;     const int kr = lane >> 3, nq = (lane & 7) * 4;
;     f32x4 v[8];
; #pragma unroll
;     for (int i = 0; i < 8; ++i) v[i] = ld_nt(W + (size_t)(k0 + kr + 8 * i) * pitch + n0 + nq);
;     __builtin_amdgcn_sched_barrier(0);
; #pragma unroll
;     for (int i = 0; i < 8; ++i) { LAS float* sp = scr + (kr + 8 * i) * 33 + nq; sp[0] = v[i][0]; sp[1] = v[i][1]; sp[2] = v[i][2]; sp[3] = v[i][3]; }
;     asm volatile("s_waitcnt lgkmcnt(0)" ::: "memory");
;     const int c = lane & 7;
; #pragma unroll
;     for (int j = 0; j < 4; ++j) { const int n = (lane >> 3) + 8 * j; const LAS float* sp = scr + (8 * c) * 33 + n;
;         u32x4 o; o.x = pk_f16(sp[0 * 33], sp[1 * 33]); o.y = pk_f16(sp[2 * 33], sp[3 * 33]); o.z = pk_f16(sp[4 * 33], sp[5 * 33]); o.w = pk_f16(sp[6 * 33], sp[7 * 33]);
;         *(u32x4*)(WT + (size_t)(n0 + n) * K + k0 + 8 * c) = o; }
;     asm volatile("s_waitcnt lgkmcnt(0)" ::: "memory");
; __device__ __forceinline__ void transpose_dispatch(int it, const float* in_w, const float* out_w, const float* glu_w, const float* pool_w, unsigned char* ws, LAS float* scr, int lane) {
;     if (it < 4 * TI_POOL1) { const int pg = it / TI_POOL1; transpose_item(pool_w + pg * 65536, 256, 256, 256, (f16*)(ws + WS_WPOOL) + pg * 65536, scr, it % TI_POOL1, lane); return; } it -= 4 * TI_POOL1;
;     if (it < TI_RAW) { convert_item(in_w, (f16*)(ws + WS_WRAW), it, lane); return; } it -= TI_RAW;
;     if (it < TI_IN) { transpose_item(in_w + 1024, D, 4096, 3072, (f16*)(ws + WS_WIN) + (size_t)1024 * D, scr, it, lane); return; } it -= TI_IN;
;     if (it < TI_OUT) { transpose_item(out_w, D, D, D, (f16*)(ws + WS_WOUT), scr, it, lane); return; } it -= TI_OUT;
;     transpose_item(glu_w, SW, 2 * SW, 2 * SW, (f16*)(ws + WS_WGLU), scr, it, lane);
.LBB0_187:
	s_add_i32 s56, s9, 0xffff0e80
	s_cmpk_gt_i32 s56, 0x7f
	s_mov_b64 s[20:21], -1
	s_cbranch_scc0 .LBB0_201
	s_cmpk_gt_u32 s56, 0x27f
	s_cbranch_scc0 .LBB0_198
	s_cmpk_gt_u32 s56, 0xe7f
	s_cbranch_scc0 .LBB0_195
	s_and_b32 s15, s19, 0x7e0
	s_cmpk_gt_u32 s56, 0x167f
	v_or_b32_e32 v44, s15, v24
	v_or_b32_e32 v43, s15, v25
	v_or_b32_e32 v42, s15, v3
	v_or_b32_e32 v41, s15, v1
	s_cbranch_scc0 .LBB0_192
	s_and_b32 s20, s56, 0x7fffffc0
	s_addk_i32 s20, 0xe980
	v_or_b32_e32 v6, s20, v24
	s_lshl_b32 s58, s15, 2
	s_mov_b32 s59, s13
	v_lshlrev_b64 v[46:47], 13, v[6:7]
	v_or_b32_e32 v48, 8, v6
	v_mov_b32_e32 v49, v7
	v_or_b32_e32 v54, 16, v6
	v_mov_b32_e32 v55, v7
	v_or_b32_e32 v56, 24, v6
	v_mov_b32_e32 v57, v7
	v_or_b32_e32 v62, 32, v6
	v_mov_b32_e32 v63, v7
	v_or_b32_e32 v64, 40, v6
	v_mov_b32_e32 v65, v7
	v_or_b32_e32 v72, 48, v6
	v_mov_b32_e32 v73, v7
	v_or_b32_e32 v6, 56, v6
	v_lshl_add_u64 v[70:71], v[8:9], 0, s[58:59]
	v_lshlrev_b64 v[48:49], 13, v[48:49]
	v_lshlrev_b64 v[54:55], 13, v[54:55]
	v_lshlrev_b64 v[56:57], 13, v[56:57]
	v_lshlrev_b64 v[62:63], 13, v[62:63]
	v_lshlrev_b64 v[64:65], 13, v[64:65]
	v_lshlrev_b64 v[72:73], 13, v[72:73]
	v_lshlrev_b64 v[74:75], 13, v[6:7]
	v_lshl_add_u64 v[46:47], v[70:71], 0, v[46:47]
	v_lshl_add_u64 v[50:51], v[70:71], 0, v[48:49]
	v_lshl_add_u64 v[54:55], v[70:71], 0, v[54:55]
	v_lshl_add_u64 v[58:59], v[70:71], 0, v[56:57]
	v_lshl_add_u64 v[62:63], v[70:71], 0, v[62:63]
	v_lshl_add_u64 v[66:67], v[70:71], 0, v[64:65]
	v_lshl_add_u64 v[72:73], v[70:71], 0, v[72:73]
	v_lshl_add_u64 v[74:75], v[70:71], 0, v[74:75]
	global_load_dwordx4 v[46:49], v[46:47], off nt
	s_nop 0
	global_load_dwordx4 v[50:53], v[50:51], off nt
	s_nop 0
	global_load_dwordx4 v[54:57], v[54:55], off nt
	s_nop 0
	global_load_dwordx4 v[58:61], v[58:59], off nt
	s_nop 0
	global_load_dwordx4 v[62:65], v[62:63], off nt
	s_nop 0
	global_load_dwordx4 v[66:69], v[66:67], off nt
	s_nop 0
	global_load_dwordx4 v[70:73], v[72:73], off nt
	s_nop 0
	global_load_dwordx4 v[74:77], v[74:75], off nt
	s_waitcnt vmcnt(0)
	ds_write2_b32 v26, v46, v47 offset1:1
	ds_write2_b32 v26, v48, v49 offset0:2 offset1:3
	ds_write2_b32 v27, v50, v51 offset1:1
	ds_write2_b32 v28, v52, v53 offset1:1
	ds_write2_b32 v29, v54, v55 offset1:1
	ds_write2_b32 v30, v56, v57 offset1:1
	ds_write2_b32 v31, v58, v59 offset1:1
	ds_write2_b32 v32, v60, v61 offset1:1
	ds_write2_b32 v33, v62, v63 offset1:1
	ds_write2_b32 v34, v64, v65 offset1:1
	ds_write2_b32 v35, v66, v67 offset1:1
	ds_write2_b32 v36, v68, v69 offset1:1
	ds_write2_b32 v37, v70, v71 offset1:1
	ds_write2_b32 v38, v72, v73 offset1:1
	ds_write2_b32 v39, v74, v75 offset1:1
	ds_write2_b32 v40, v76, v77 offset1:1
	s_waitcnt lgkmcnt(0)
	ds_read2_b32 v[50:51], v5 offset0:33 offset1:41
	ds_read2_b32 v[52:53], v5 offset1:8
	ds_read2_b32 v[54:55], v5 offset0:66 offset1:74
	ds_read2_b32 v[56:57], v5 offset0:99 offset1:107
	ds_read2_b32 v[58:59], v5 offset0:132 offset1:140
	ds_read2_b32 v[60:61], v5 offset0:165 offset1:173
	ds_read2_b32 v[62:63], v5 offset0:198 offset1:206
	ds_read2_b32 v[64:65], v5 offset0:231 offset1:239
	s_mov_b32 s21, s13
	v_lshl_add_u64 v[66:67], s[20:21], 1, v[10:11]
	v_lshlrev_b32_e32 v6, 11, v44
	s_waitcnt lgkmcnt(6)
	v_cvt_pk_bf16_f32 v46, v52, v50
	s_waitcnt lgkmcnt(4)
	v_cvt_pk_bf16_f32 v47, v54, v56
	s_waitcnt lgkmcnt(2)
	v_cvt_pk_bf16_f32 v48, v58, v60
	s_waitcnt lgkmcnt(0)
	v_cvt_pk_bf16_f32 v49, v62, v64
	v_lshl_add_u64 v[68:69], v[66:67], 0, v[6:7]
	global_store_dwordx4 v[68:69], v[46:49], off sc0 sc1
	v_lshlrev_b32_e32 v6, 11, v43
	s_mov_b64 s[20:21], 0
	v_cvt_pk_bf16_f32 v46, v53, v51
	v_cvt_pk_bf16_f32 v47, v55, v57
	v_cvt_pk_bf16_f32 v48, v59, v61
	v_cvt_pk_bf16_f32 v49, v63, v65
	ds_read2_b32 v[52:53], v5 offset0:49 offset1:57
	ds_read2_b32 v[54:55], v5 offset0:16 offset1:24
	ds_read2_b32 v[56:57], v5 offset0:82 offset1:90
	ds_read2_b32 v[58:59], v5 offset0:115 offset1:123
	ds_read2_b32 v[60:61], v5 offset0:148 offset1:156
	ds_read2_b32 v[62:63], v5 offset0:181 offset1:189
	ds_read2_b32 v[64:65], v5 offset0:214 offset1:222
	ds_read2_b32 v[68:69], v5 offset0:247 offset1:255
	v_lshl_add_u64 v[50:51], v[66:67], 0, v[6:7]
	v_lshlrev_b32_e32 v6, 11, v42
	global_store_dwordx4 v[50:51], v[46:49], off sc0 sc1
	v_lshl_add_u64 v[50:51], v[66:67], 0, v[6:7]
	v_lshlrev_b32_e32 v6, 11, v41
	s_waitcnt lgkmcnt(6)
	v_cvt_pk_bf16_f32 v46, v54, v52
	s_waitcnt lgkmcnt(4)
	v_cvt_pk_bf16_f32 v47, v56, v58
	s_waitcnt lgkmcnt(2)
	v_cvt_pk_bf16_f32 v48, v60, v62
	s_waitcnt lgkmcnt(0)
	v_cvt_pk_bf16_f32 v49, v64, v68
	global_store_dwordx4 v[50:51], v[46:49], off sc0 sc1
	v_lshl_add_u64 v[50:51], v[66:67], 0, v[6:7]
	s_nop 0
	v_cvt_pk_bf16_f32 v46, v55, v53
	v_cvt_pk_bf16_f32 v47, v57, v59
	v_cvt_pk_bf16_f32 v48, v61, v63
	v_cvt_pk_bf16_f32 v49, v65, v69
	global_store_dwordx4 v[50:51], v[46:49], off sc0 sc1
	s_waitcnt lgkmcnt(0)
; #define LAS __attribute__((address_space(3)))
; __device__ __forceinline__ f32x4 ld_nt(const float* p) { return __builtin_nontemporal_load((const f32x4*)p); }
; __device__ __forceinline__ void transpose_item(const float* W, int K, int pitch, int ncols, f16* WT, LAS float* scr, int item, int lane) {
;     const int nblk = ncols / 32, kb = item / nblk, nb = item % nblk, k0 = 64 * kb, n0 = 32 * nb;
;     const int kr = lane >> 3, nq = (lane & 7) * 4;
;     f32x4 v[8];
; #pragma unroll
;     for (int i = 0; i < 8; ++i) v[i] = ld_nt(W + (size_t)(k0 + kr + 8 * i) * pitch + n0 + nq);
;     __builtin_amdgcn_sched_barrier(0);
; #pragma unroll
;     for (int i = 0; i < 8; ++i) { LAS float* sp = scr + (kr + 8 * i) * 33 + nq; sp[0] = v[i][0]; sp[1] = v[i][1]; sp[2] = v[i][2]; sp[3] = v[i][3]; }
;     asm volatile("s_waitcnt lgkmcnt(0)" ::: "memory");
;     const int c = lane & 7;
; #pragma unroll
;     for (int j = 0; j < 4; ++j) { const int n = (lane >> 3) + 8 * j; const LAS float* sp = scr + (8 * c) * 33 + n;
;         u32x4 o; o.x = pk_f16(sp[0 * 33], sp[1 * 33]); o.y = pk_f16(sp[2 * 33], sp[3 * 33]); o.z = pk_f16(sp[4 * 33], sp[5 * 33]); o.w = pk_f16(sp[6 * 33], sp[7 * 33]);
;         *(u32x4*)(WT + (size_t)(n0 + n) * K + k0 + 8 * c) = o; }
;     asm volatile("s_waitcnt lgkmcnt(0)" ::: "memory");
; __device__ __forceinline__ void transpose_dispatch(int it, const float* in_w, const float* out_w, const float* glu_w, const float* pool_w, unsigned char* ws, LAS float* scr, int lane) {
;     ...
;     if (it < TI_OUT) { transpose_item(out_w, D, D, D, (f16*)(ws + WS_WOUT), scr, it, lane); return; } it -= TI_OUT;
.LBB0_192:
	s_andn2_b64 vcc, exec, s[20:21]
	s_cbranch_vccnz .LBB0_194
	s_and_b32 s57, s9, 0xffc0
	v_or_b32_e32 v6, s57, v24
	s_lshl_b32 s20, s15, 2
	s_mov_b32 s21, s13
	v_lshl_add_u64 v[46:47], v[12:13], 0, s[20:21]
	v_lshlrev_b32_e32 v6, 13, v6
	v_lshl_add_u64 v[70:71], v[46:47], 0, v[6:7]
	v_add_co_u32_e32 v50, vcc, 0x10000, v70
	s_nop 1
	v_addc_co_u32_e32 v51, vcc, 0, v71, vcc
	v_add_co_u32_e32 v54, vcc, 0x20000, v70
	global_load_dwordx4 v[46:49], v[70:71], off nt
	s_nop 0
	global_load_dwordx4 v[50:53], v[50:51], off nt
	v_addc_co_u32_e32 v55, vcc, 0, v71, vcc
	v_add_co_u32_e32 v58, vcc, 0x30000, v70
	s_nop 1
	v_addc_co_u32_e32 v59, vcc, 0, v71, vcc
	v_add_co_u32_e32 v62, vcc, 0x40000, v70
	global_load_dwordx4 v[54:57], v[54:55], off nt
	s_nop 0
	global_load_dwordx4 v[58:61], v[58:59], off nt
	v_addc_co_u32_e32 v63, vcc, 0, v71, vcc
	v_add_co_u32_e32 v66, vcc, 0x50000, v70
	s_nop 1
	v_addc_co_u32_e32 v67, vcc, 0, v71, vcc
	v_add_co_u32_e32 v72, vcc, 0x60000, v70
	global_load_dwordx4 v[62:65], v[62:63], off nt
	s_nop 0
	global_load_dwordx4 v[66:69], v[66:67], off nt
	v_addc_co_u32_e32 v73, vcc, 0, v71, vcc
	v_add_co_u32_e32 v74, vcc, 0x70000, v70
	s_nop 1
	v_addc_co_u32_e32 v75, vcc, 0, v71, vcc
	global_load_dwordx4 v[70:73], v[72:73], off nt
	s_nop 0
	global_load_dwordx4 v[74:77], v[74:75], off nt
	s_waitcnt vmcnt(0)
	ds_write2_b32 v26, v46, v47 offset1:1
	ds_write2_b32 v26, v48, v49 offset0:2 offset1:3
	ds_write2_b32 v27, v50, v51 offset1:1
	ds_write2_b32 v28, v52, v53 offset1:1
	ds_write2_b32 v29, v54, v55 offset1:1
	ds_write2_b32 v30, v56, v57 offset1:1
	ds_write2_b32 v31, v58, v59 offset1:1
	ds_write2_b32 v32, v60, v61 offset1:1
	ds_write2_b32 v33, v62, v63 offset1:1
	ds_write2_b32 v34, v64, v65 offset1:1
	ds_write2_b32 v35, v66, v67 offset1:1
	ds_write2_b32 v36, v68, v69 offset1:1
	ds_write2_b32 v37, v70, v71 offset1:1
	ds_write2_b32 v38, v72, v73 offset1:1
	ds_write2_b32 v39, v74, v75 offset1:1
	ds_write2_b32 v40, v76, v77 offset1:1
	s_waitcnt lgkmcnt(0)
	ds_read2_b32 v[50:51], v5 offset0:33 offset1:41
	ds_read2_b32 v[52:53], v5 offset1:8
	ds_read2_b32 v[54:55], v5 offset0:66 offset1:74
	ds_read2_b32 v[56:57], v5 offset0:99 offset1:107
	ds_read2_b32 v[58:59], v5 offset0:132 offset1:140
	ds_read2_b32 v[60:61], v5 offset0:165 offset1:173
	ds_read2_b32 v[62:63], v5 offset0:198 offset1:206
	ds_read2_b32 v[64:65], v5 offset0:231 offset1:239
	s_lshl_b32 s20, s57, 1
	v_lshl_add_u64 v[66:67], v[14:15], 0, s[20:21]
	v_lshlrev_b32_e32 v6, 12, v44
	s_waitcnt lgkmcnt(6)
	v_cvt_pk_bf16_f32 v46, v52, v50
	s_waitcnt lgkmcnt(4)
	v_cvt_pk_bf16_f32 v47, v54, v56
	s_waitcnt lgkmcnt(2)
	v_cvt_pk_bf16_f32 v48, v58, v60
	s_waitcnt lgkmcnt(0)
	v_cvt_pk_bf16_f32 v49, v62, v64
	v_lshl_add_u64 v[44:45], v[66:67], 0, v[6:7]
	global_store_dwordx4 v[44:45], v[46:49], off sc0 sc1
	v_cvt_pk_bf16_f32 v44, v53, v51
	v_cvt_pk_bf16_f32 v45, v55, v57
	v_cvt_pk_bf16_f32 v46, v59, v61
	v_cvt_pk_bf16_f32 v47, v63, v65
	ds_read2_b32 v[50:51], v5 offset0:49 offset1:57
	ds_read2_b32 v[52:53], v5 offset0:16 offset1:24
	ds_read2_b32 v[54:55], v5 offset0:82 offset1:90
	ds_read2_b32 v[56:57], v5 offset0:115 offset1:123
	ds_read2_b32 v[58:59], v5 offset0:148 offset1:156
	ds_read2_b32 v[60:61], v5 offset0:181 offset1:189
	ds_read2_b32 v[62:63], v5 offset0:214 offset1:222
	ds_read2_b32 v[64:65], v5 offset0:247 offset1:255
	v_lshlrev_b32_e32 v6, 12, v43
	v_lshl_add_u64 v[48:49], v[66:67], 0, v[6:7]
	v_lshlrev_b32_e32 v6, 12, v42
	global_store_dwordx4 v[48:49], v[44:47], off sc0 sc1
	v_lshl_add_u64 v[42:43], v[66:67], 0, v[6:7]
	v_lshlrev_b32_e32 v6, 12, v41
	s_waitcnt lgkmcnt(6)
	v_cvt_pk_bf16_f32 v44, v52, v50
	s_waitcnt lgkmcnt(4)
	v_cvt_pk_bf16_f32 v45, v54, v56
	s_waitcnt lgkmcnt(2)
	v_cvt_pk_bf16_f32 v46, v58, v60
	s_waitcnt lgkmcnt(0)
	v_cvt_pk_bf16_f32 v47, v62, v64
	global_store_dwordx4 v[42:43], v[44:47], off sc0 sc1
	v_cvt_pk_bf16_f32 v42, v53, v51
	v_cvt_pk_bf16_f32 v43, v55, v57
	v_cvt_pk_bf16_f32 v44, v59, v61
	v_cvt_pk_bf16_f32 v45, v63, v65
	v_lshl_add_u64 v[46:47], v[66:67], 0, v[6:7]
	global_store_dwordx4 v[46:47], v[42:45], off sc0 sc1
	s_waitcnt lgkmcnt(0)

; #define LAS __attribute__((address_space(3)))
; __device__ __forceinline__ f32x4 ld_nt(const float* p) { return __builtin_nontemporal_load((const f32x4*)p); }
; __device__ __forceinline__ void transpose_item(const float* W, int K, int pitch, int ncols, f16* WT, LAS float* scr, int item, int lane) {
;     const int nblk = ncols / 32, kb = item / nblk, nb = item % nblk, k0 = 64 * kb, n0 = 32 * nb;
;     const int kr = lane >> 3, nq = (lane & 7) * 4;
;     f32x4 v[8];
; #pragma unroll
;     for (int i = 0; i < 8; ++i) v[i] = ld_nt(W + (size_t)(k0 + kr + 8 * i) * pitch + n0 + nq);
;     __builtin_amdgcn_sched_barrier(0);
; #pragma unroll
;     for (int i = 0; i < 8; ++i) { LAS float* sp = scr + (kr + 8 * i) * 33 + nq; sp[0] = v[i][0]; sp[1] = v[i][1]; sp[2] = v[i][2]; sp[3] = v[i][3]; }
;     asm volatile("s_waitcnt lgkmcnt(0)" ::: "memory");
;     const int c = lane & 7;
; #pragma unroll
;     for (int j = 0; j < 4; ++j) { const int n = (lane >> 3) + 8 * j; const LAS float* sp = scr + (8 * c) * 33 + n;
;         u32x4 o; o.x = pk_f16(sp[0 * 33], sp[1 * 33]); o.y = pk_f16(sp[2 * 33], sp[3 * 33]); o.z = pk_f16(sp[4 * 33], sp[5 * 33]); o.w = pk_f16(sp[6 * 33], sp[7 * 33]);
;         *(u32x4*)(WT + (size_t)(n0 + n) * K + k0 + 8 * c) = o; }
;     asm volatile("s_waitcnt lgkmcnt(0)" ::: "memory");
; __device__ __forceinline__ void transpose_dispatch(int it, const float* in_w, const float* out_w, const float* glu_w, const float* pool_w, unsigned char* ws, LAS float* scr, int lane) {
;     ...
;     if (it < TI_IN) { transpose_item(in_w + 1024, D, 4096, 3072, (f16*)(ws + WS_WIN) + (size_t)1024 * D, scr, it, lane); return; } it -= TI_IN;
.LBB0_195:
	s_andn2_b64 vcc, exec, s[20:21]
	s_cbranch_vccnz .LBB0_197
	s_add_i32 s15, s56, 0xfd80
	s_and_b32 s20, s15, 0xffff
	s_mul_i32 s20, s20, 0xaaab
	s_lshr_b32 s21, s20, 16
	s_lshr_b32 s20, s20, 22
	s_mulk_i32 s20, 0x60
	s_sub_i32 s15, s15, s20
	s_lshl_b32 s15, s15, 5
	s_and_b32 s57, s21, 0xffc0
	s_and_b32 s15, s15, 0xffe0
	v_or_b32_e32 v6, s57, v24
	s_lshl_b32 s20, s15, 2
	s_mov_b32 s21, s13
	v_lshl_add_u64 v[42:43], v[16:17], 0, s[20:21]
	v_lshlrev_b32_e32 v6, 14, v6
	v_lshl_add_u64 v[66:67], v[42:43], 0, v[6:7]
	v_add_co_u32_e32 v46, vcc, s29, v66
	s_nop 1
	v_addc_co_u32_e32 v47, vcc, 0, v67, vcc
	v_add_co_u32_e32 v50, vcc, s30, v66
	global_load_dwordx4 v[42:45], v[66:67], off nt
	s_nop 0
	global_load_dwordx4 v[46:49], v[46:47], off nt
	v_addc_co_u32_e32 v51, vcc, 0, v67, vcc
	v_add_co_u32_e32 v54, vcc, s31, v66
	s_nop 1
	v_addc_co_u32_e32 v55, vcc, 0, v67, vcc
	v_add_co_u32_e32 v58, vcc, s33, v66
	global_load_dwordx4 v[50:53], v[50:51], off nt
	s_nop 0
	global_load_dwordx4 v[54:57], v[54:55], off nt
	v_addc_co_u32_e32 v59, vcc, 0, v67, vcc
	v_add_co_u32_e32 v62, vcc, s34, v66
	s_nop 1
	v_addc_co_u32_e32 v63, vcc, 0, v67, vcc
	v_add_co_u32_e32 v68, vcc, s35, v66
	global_load_dwordx4 v[58:61], v[58:59], off nt
	s_nop 0
	global_load_dwordx4 v[62:65], v[62:63], off nt
	v_addc_co_u32_e32 v69, vcc, 0, v67, vcc
	v_add_co_u32_e32 v70, vcc, s36, v66
	s_nop 1
	v_addc_co_u32_e32 v71, vcc, 0, v67, vcc
	global_load_dwordx4 v[66:69], v[68:69], off nt
	s_nop 0
	global_load_dwordx4 v[70:73], v[70:71], off nt
	s_waitcnt vmcnt(0)
	ds_write2_b32 v26, v42, v43 offset1:1
	ds_write2_b32 v26, v44, v45 offset0:2 offset1:3
	ds_write2_b32 v27, v46, v47 offset1:1
	ds_write2_b32 v28, v48, v49 offset1:1
	ds_write2_b32 v29, v50, v51 offset1:1
	ds_write2_b32 v30, v52, v53 offset1:1
	ds_write2_b32 v31, v54, v55 offset1:1
	ds_write2_b32 v32, v56, v57 offset1:1
	ds_write2_b32 v33, v58, v59 offset1:1
	ds_write2_b32 v34, v60, v61 offset1:1
	ds_write2_b32 v35, v62, v63 offset1:1
	ds_write2_b32 v36, v64, v65 offset1:1
	ds_write2_b32 v37, v66, v67 offset1:1
	ds_write2_b32 v38, v68, v69 offset1:1
	ds_write2_b32 v39, v70, v71 offset1:1
	ds_write2_b32 v40, v72, v73 offset1:1
	s_waitcnt lgkmcnt(0)
	ds_read2_b32 v[46:47], v5 offset0:33 offset1:41
	ds_read2_b32 v[48:49], v5 offset1:8
	ds_read2_b32 v[50:51], v5 offset0:66 offset1:74
	ds_read2_b32 v[52:53], v5 offset0:99 offset1:107
	ds_read2_b32 v[54:55], v5 offset0:132 offset1:140
	ds_read2_b32 v[56:57], v5 offset0:165 offset1:173
	ds_read2_b32 v[58:59], v5 offset0:198 offset1:206
	ds_read2_b32 v[60:61], v5 offset0:231 offset1:239
	s_lshl_b32 s20, s57, 1
	v_or_b32_e32 v6, s15, v24
	v_lshl_add_u64 v[62:63], v[18:19], 0, s[20:21]
	v_lshlrev_b32_e32 v6, 12, v6
	s_waitcnt lgkmcnt(6)
	v_cvt_pk_bf16_f32 v42, v48, v46
	s_waitcnt lgkmcnt(4)
	v_cvt_pk_bf16_f32 v43, v50, v52
	s_waitcnt lgkmcnt(2)
	v_cvt_pk_bf16_f32 v44, v54, v56
	s_waitcnt lgkmcnt(0)
	v_cvt_pk_bf16_f32 v45, v58, v60
	v_lshl_add_u64 v[64:65], v[62:63], 0, v[6:7]
	global_store_dwordx4 v[64:65], v[42:45], off sc0 sc1
	v_or_b32_e32 v6, s15, v25
	v_lshlrev_b32_e32 v6, 12, v6
	v_cvt_pk_bf16_f32 v42, v49, v47
	v_cvt_pk_bf16_f32 v43, v51, v53
	v_cvt_pk_bf16_f32 v44, v55, v57
	v_cvt_pk_bf16_f32 v45, v59, v61
	ds_read2_b32 v[48:49], v5 offset0:49 offset1:57
	ds_read2_b32 v[50:51], v5 offset0:16 offset1:24
	ds_read2_b32 v[52:53], v5 offset0:82 offset1:90
	ds_read2_b32 v[54:55], v5 offset0:115 offset1:123
	ds_read2_b32 v[56:57], v5 offset0:148 offset1:156
	ds_read2_b32 v[58:59], v5 offset0:181 offset1:189
	ds_read2_b32 v[60:61], v5 offset0:214 offset1:222
	ds_read2_b32 v[64:65], v5 offset0:247 offset1:255
	v_lshl_add_u64 v[46:47], v[62:63], 0, v[6:7]
	v_or_b32_e32 v6, s15, v3
	v_lshlrev_b32_e32 v6, 12, v6
	global_store_dwordx4 v[46:47], v[42:45], off sc0 sc1
	v_lshl_add_u64 v[46:47], v[62:63], 0, v[6:7]
	v_or_b32_e32 v6, s15, v1
	s_waitcnt lgkmcnt(6)
	v_cvt_pk_bf16_f32 v42, v50, v48
	s_waitcnt lgkmcnt(4)
	v_cvt_pk_bf16_f32 v43, v52, v54
	s_waitcnt lgkmcnt(2)
	v_cvt_pk_bf16_f32 v44, v56, v58
	s_waitcnt lgkmcnt(0)
	v_cvt_pk_bf16_f32 v45, v60, v64
	v_lshlrev_b32_e32 v6, 12, v6
	global_store_dwordx4 v[46:47], v[42:45], off sc0 sc1
	v_lshl_add_u64 v[46:47], v[62:63], 0, v[6:7]
	s_nop 0
	v_cvt_pk_bf16_f32 v42, v51, v49
	v_cvt_pk_bf16_f32 v43, v53, v55
	v_cvt_pk_bf16_f32 v44, v57, v59
	v_cvt_pk_bf16_f32 v45, v61, v65
	global_store_dwordx4 v[46:47], v[42:45], off sc0 sc1
	s_waitcnt lgkmcnt(0)

; __device__ __forceinline__ f32x4 ld_nt(const float* p) { return __builtin_nontemporal_load((const f32x4*)p); }
; __device__ __forceinline__ u32x4 pack8(const f32x4 v0, const f32x4 v1) { u32x4 w; w.x = pk_f16(v0[0], v0[1]); w.y = pk_f16(v0[2], v0[3]); w.z = pk_f16(v1[0], v1[1]); w.w = pk_f16(v1[2], v1[3]); return w; }
; __device__ __forceinline__ void convert_item(const float* W, f16* O, int item, int lane) {
;     f32x4 v[4][4];
; #pragma unroll
;     for (int r = 0; r < 4; ++r)
; #pragma unroll
;         for (int q = 0; q < 4; ++q) v[r][q] = ld_nt(W + (size_t)(item * 4 + r) * 4096 + lane * 16 + q * 4);
;     __builtin_amdgcn_sched_barrier(0);
; #pragma unroll
;     for (int r = 0; r < 4; ++r) { f16* op = O + (size_t)(item * 4 + r) * 1024 + lane * 16; *(u32x4*)op = pack8(v[r][0], v[r][1]); *(u32x4*)(op + 8) = pack8(v[r][2], v[r][3]); }
.LBB0_198:
	s_andn2_b64 vcc, exec, s[20:21]
	s_cbranch_vccnz .LBB0_200
	v_lshl_add_u64 v[90:91], s[12:13], 2, v[20:21]
	v_add_co_u32_e32 v58, vcc, s18, v90
	global_load_dwordx4 v[42:45], v[90:91], off offset:48 nt
	global_load_dwordx4 v[46:49], v[90:91], off offset:32 nt
	global_load_dwordx4 v[50:53], v[90:91], off offset:16 nt
	global_load_dwordx4 v[54:57], v[90:91], off nt
	v_addc_co_u32_e32 v59, vcc, 0, v91, vcc
	v_add_co_u32_e32 v74, vcc, s37, v90
	v_lshl_add_u64 v[70:71], v[90:91], 0, s[22:23]
	s_nop 0
	v_addc_co_u32_e32 v75, vcc, 0, v91, vcc
	v_lshl_add_u64 v[86:87], v[90:91], 0, s[24:25]
	v_lshl_add_u64 v[102:103], v[90:91], 0, s[26:27]
	v_add_co_u32_e32 v90, vcc, s54, v90
	global_load_dwordx4 v[58:61], v[58:59], off nt
	s_nop 0
	global_load_dwordx4 v[62:65], v[70:71], off offset:48 nt
	global_load_dwordx4 v[66:69], v[70:71], off offset:32 nt
	s_nop 0
	global_load_dwordx4 v[70:73], v[70:71], off offset:16 nt
	v_addc_co_u32_e32 v91, vcc, 0, v91, vcc
	global_load_dwordx4 v[74:77], v[74:75], off nt
	s_nop 0
	global_load_dwordx4 v[78:81], v[86:87], off offset:48 nt
	global_load_dwordx4 v[82:85], v[86:87], off offset:32 nt
	s_nop 0
	global_load_dwordx4 v[86:89], v[86:87], off offset:16 nt
	s_nop 0
	global_load_dwordx4 v[90:93], v[90:91], off nt
	s_nop 0
	global_load_dwordx4 v[94:97], v[102:103], off offset:48 nt
	global_load_dwordx4 v[98:101], v[102:103], off offset:32 nt
	s_nop 0
	global_load_dwordx4 v[102:105], v[102:103], off offset:16 nt
	s_mov_b32 s15, s13
	v_lshl_add_u64 v[106:107], s[14:15], 1, v[22:23]
	s_waitcnt vmcnt(0)
	v_cvt_pk_bf16_f32 v46, v46, v47
	v_cvt_pk_bf16_f32 v47, v48, v49
	v_cvt_pk_bf16_f32 v48, v42, v43
	v_cvt_pk_bf16_f32 v49, v44, v45
	v_cvt_pk_bf16_f32 v42, v58, v59
	v_cvt_pk_bf16_f32 v43, v60, v61
	v_cvt_pk_bf16_f32 v44, v70, v71
	v_cvt_pk_bf16_f32 v45, v72, v73
	global_store_dwordx4 v[106:107], v[46:49], off offset:16 sc0 sc1
	global_store_dwordx4 v[106:107], v[42:45], off offset:2048 sc0 sc1
	v_cvt_pk_bf16_f32 v54, v54, v55
	v_add_co_u32_e32 v46, vcc, s55, v106
	v_cvt_pk_bf16_f32 v42, v66, v67
	v_cvt_pk_bf16_f32 v43, v68, v69
	v_cvt_pk_bf16_f32 v44, v62, v63
	v_cvt_pk_bf16_f32 v45, v64, v65
	global_store_dwordx4 v[106:107], v[42:45], off offset:2064 sc0 sc1
	v_addc_co_u32_e32 v47, vcc, 0, v107, vcc
	s_nop 0
	v_cvt_pk_bf16_f32 v42, v74, v75
	v_cvt_pk_bf16_f32 v43, v76, v77
	v_cvt_pk_bf16_f32 v44, v86, v87
	v_cvt_pk_bf16_f32 v45, v88, v89
	global_store_dwordx4 v[46:47], v[42:45], off sc0 sc1
	v_cvt_pk_bf16_f32 v55, v56, v57
	v_cvt_pk_bf16_f32 v56, v50, v51
	v_cvt_pk_bf16_f32 v42, v82, v83
	v_cvt_pk_bf16_f32 v43, v84, v85
	v_cvt_pk_bf16_f32 v44, v78, v79
	v_cvt_pk_bf16_f32 v45, v80, v81
	global_store_dwordx4 v[46:47], v[42:45], off offset:16 sc0 sc1
	v_cvt_pk_bf16_f32 v57, v52, v53
	global_store_dwordx4 v[106:107], v[54:57], off sc0 sc1
	v_cvt_pk_bf16_f32 v42, v90, v91
	v_cvt_pk_bf16_f32 v43, v92, v93
	v_cvt_pk_bf16_f32 v44, v102, v103
	v_cvt_pk_bf16_f32 v45, v104, v105
	global_store_dwordx4 v[46:47], v[42:45], off offset:2048 sc0 sc1
	s_nop 1
	v_cvt_pk_bf16_f32 v42, v98, v99
	v_cvt_pk_bf16_f32 v43, v100, v101
	v_cvt_pk_bf16_f32 v44, v94, v95
	v_cvt_pk_bf16_f32 v45, v96, v97
	global_store_dwordx4 v[46:47], v[42:45], off offset:2064 sc0 sc1

; #define LAS __attribute__((address_space(3)))
; __device__ __forceinline__ f32x4 ld_nt(const float* p) { return __builtin_nontemporal_load((const f32x4*)p); }
; __device__ __forceinline__ void transpose_item(const float* W, int K, int pitch, int ncols, f16* WT, LAS float* scr, int item, int lane) {
;     const int nblk = ncols / 32, kb = item / nblk, nb = item % nblk, k0 = 64 * kb, n0 = 32 * nb;
;     const int kr = lane >> 3, nq = (lane & 7) * 4;
;     f32x4 v[8];
; #pragma unroll
;     for (int i = 0; i < 8; ++i) v[i] = ld_nt(W + (size_t)(k0 + kr + 8 * i) * pitch + n0 + nq);
;     __builtin_amdgcn_sched_barrier(0);
; #pragma unroll
;     for (int i = 0; i < 8; ++i) { LAS float* sp = scr + (kr + 8 * i) * 33 + nq; sp[0] = v[i][0]; sp[1] = v[i][1]; sp[2] = v[i][2]; sp[3] = v[i][3]; }
;     asm volatile("s_waitcnt lgkmcnt(0)" ::: "memory");
;     const int c = lane & 7;
; #pragma unroll
;     for (int j = 0; j < 4; ++j) { const int n = (lane >> 3) + 8 * j; const LAS float* sp = scr + (8 * c) * 33 + n;
;         u32x4 o; o.x = pk_f16(sp[0 * 33], sp[1 * 33]); o.y = pk_f16(sp[2 * 33], sp[3 * 33]); o.z = pk_f16(sp[4 * 33], sp[5 * 33]); o.w = pk_f16(sp[6 * 33], sp[7 * 33]);
;         *(u32x4*)(WT + (size_t)(n0 + n) * K + k0 + 8 * c) = o; }
;     asm volatile("s_waitcnt lgkmcnt(0)" ::: "memory");
; __device__ __forceinline__ void transpose_dispatch(int it, const float* in_w, const float* out_w, const float* glu_w, const float* pool_w, unsigned char* ws, LAS float* scr, int lane) {
;     if (it < 4 * TI_POOL1) { const int pg = it / TI_POOL1; transpose_item(pool_w + pg * 65536, 256, 256, 256, (f16*)(ws + WS_WPOOL) + pg * 65536, scr, it % TI_POOL1, lane); return; } it -= 4 * TI_POOL1;
.LBB0_201:
	s_andn2_b64 vcc, exec, s[20:21]
	s_cbranch_vccnz .LBB0_186
	s_ashr_i32 s15, s56, 31
	s_lshr_b32 s15, s15, 27
	s_add_i32 s15, s56, s15
	s_lshl_b32 s20, s15, 11
	s_and_b32 s20, s20, 0xffff0000
	s_ashr_i32 s21, s20, 31
	s_lshl_b64 s[58:59], s[20:21], 2
	v_readlane_b32 s60, v254, 18
	v_readlane_b32 s61, v254, 19
	s_add_u32 s57, s60, s58
	s_addc_u32 s60, s61, s59
	s_lshl_b64 s[20:21], s[20:21], 1
	v_readlane_b32 s62, v254, 20
	s_add_u32 s61, s0, s20
	s_addc_u32 s62, s1, s21
	s_and_b32 s15, s15, 0xffe0
	s_sub_i32 s15, s56, s15
	s_bfe_i32 s20, s15, 0x80000
	s_bfe_u32 s20, s20, 0x3000c
	s_add_i32 s20, s15, s20
	s_bfe_i32 s21, s20, 0x80000
	s_and_b32 s20, s20, 0xf8
	s_sext_i32_i16 s21, s21
	s_sub_i32 s15, s15, s20
	s_sext_i32_i8 s15, s15
	s_lshl_b32 s20, s21, 3
	s_and_b32 s56, s20, 0xffffffc0
	s_lshl_b32 s20, s15, 5
	v_or_b32_e32 v66, s56, v24
	s_ashr_i32 s21, s20, 31
	s_lshl_b64 s[58:59], s[20:21], 2
	v_ashrrev_i32_e32 v67, 31, v66
	s_add_u32 s58, s57, s58
	v_lshlrev_b64 v[42:43], 10, v[66:67]
	v_or_b32_e32 v44, 8, v66
	v_or_b32_e32 v50, 16, v66
	v_or_b32_e32 v52, 24, v66
	v_or_b32_e32 v58, 32, v66
	v_or_b32_e32 v60, 40, v66
	v_or_b32_e32 v70, 48, v66
	v_or_b32_e32 v66, 56, v66
	s_addc_u32 s59, s60, s59
	v_lshlrev_b32_e32 v6, 2, v4
	v_ashrrev_i32_e32 v45, 31, v44
	v_ashrrev_i32_e32 v51, 31, v50
	v_ashrrev_i32_e32 v53, 31, v52
	v_ashrrev_i32_e32 v59, 31, v58
	v_ashrrev_i32_e32 v61, 31, v60
	v_ashrrev_i32_e32 v71, 31, v70
	v_ashrrev_i32_e32 v67, 31, v66
	v_lshl_add_u64 v[68:69], s[58:59], 0, v[6:7]
	v_lshlrev_b64 v[44:45], 10, v[44:45]
	v_lshlrev_b64 v[50:51], 10, v[50:51]
	v_lshlrev_b64 v[52:53], 10, v[52:53]
	v_lshlrev_b64 v[58:59], 10, v[58:59]
	v_lshlrev_b64 v[60:61], 10, v[60:61]
	v_lshlrev_b64 v[70:71], 10, v[70:71]
	v_lshlrev_b64 v[66:67], 10, v[66:67]
	v_lshl_add_u64 v[42:43], v[68:69], 0, v[42:43]
	v_lshl_add_u64 v[46:47], v[68:69], 0, v[44:45]
	v_lshl_add_u64 v[50:51], v[68:69], 0, v[50:51]
	v_lshl_add_u64 v[54:55], v[68:69], 0, v[52:53]
	v_lshl_add_u64 v[58:59], v[68:69], 0, v[58:59]
	v_lshl_add_u64 v[62:63], v[68:69], 0, v[60:61]
	v_lshl_add_u64 v[70:71], v[68:69], 0, v[70:71]
	v_lshl_add_u64 v[72:73], v[68:69], 0, v[66:67]
	global_load_dwordx4 v[42:45], v[42:43], off nt
	s_nop 0
	global_load_dwordx4 v[46:49], v[46:47], off nt
	s_nop 0
	global_load_dwordx4 v[50:53], v[50:51], off nt
	s_nop 0
	global_load_dwordx4 v[54:57], v[54:55], off nt
	s_nop 0
	global_load_dwordx4 v[58:61], v[58:59], off nt
	s_nop 0
	global_load_dwordx4 v[62:65], v[62:63], off nt
	s_nop 0
	global_load_dwordx4 v[66:69], v[70:71], off nt
	s_nop 0
	global_load_dwordx4 v[70:73], v[72:73], off nt
	v_readlane_b32 s63, v254, 21
	v_readlane_b32 s64, v254, 22
	v_readlane_b32 s65, v254, 23
	v_readlane_b32 s66, v254, 24
	v_readlane_b32 s67, v254, 25
	v_readlane_b32 s68, v254, 26
	v_readlane_b32 s69, v254, 27
	v_readlane_b32 s70, v254, 28
	v_readlane_b32 s71, v254, 29
	v_readlane_b32 s72, v254, 30
	v_readlane_b32 s73, v254, 31
	v_readlane_b32 s74, v254, 32
	v_readlane_b32 s75, v254, 33
	s_waitcnt vmcnt(0)
	ds_write2_b32 v26, v42, v43 offset1:1
	ds_write2_b32 v26, v44, v45 offset0:2 offset1:3
	ds_write2_b32 v27, v46, v47 offset1:1
	ds_write2_b32 v28, v48, v49 offset1:1
	ds_write2_b32 v29, v50, v51 offset1:1
	ds_write2_b32 v30, v52, v53 offset1:1
	ds_write2_b32 v31, v54, v55 offset1:1
	ds_write2_b32 v32, v56, v57 offset1:1
	ds_write2_b32 v33, v58, v59 offset1:1
	ds_write2_b32 v34, v60, v61 offset1:1
	ds_write2_b32 v35, v62, v63 offset1:1
	ds_write2_b32 v36, v64, v65 offset1:1
	ds_write2_b32 v37, v66, v67 offset1:1
	ds_write2_b32 v38, v68, v69 offset1:1
	ds_write2_b32 v39, v70, v71 offset1:1
	ds_write2_b32 v40, v72, v73 offset1:1
	s_waitcnt lgkmcnt(0)
	s_ashr_i32 s57, s56, 31
	ds_read2_b32 v[46:47], v5 offset0:33 offset1:41
	ds_read2_b32 v[48:49], v5 offset1:8
	ds_read2_b32 v[50:51], v5 offset0:66 offset1:74
	ds_read2_b32 v[52:53], v5 offset0:99 offset1:107
	ds_read2_b32 v[54:55], v5 offset0:132 offset1:140
	ds_read2_b32 v[56:57], v5 offset0:165 offset1:173
	ds_read2_b32 v[58:59], v5 offset0:198 offset1:206
	ds_read2_b32 v[60:61], v5 offset0:231 offset1:239
	s_lshl_b64 s[56:57], s[56:57], 1
	s_add_u32 s56, s61, s56
	v_or_b32_e32 v64, s20, v24
	s_addc_u32 s57, s62, s57
	v_lshlrev_b32_e32 v6, 1, v2
	v_ashrrev_i32_e32 v65, 31, v64
	v_lshl_add_u64 v[62:63], s[56:57], 0, v[6:7]
	v_lshlrev_b64 v[64:65], 9, v[64:65]
	s_waitcnt lgkmcnt(6)
	v_cvt_pk_bf16_f32 v42, v48, v46
	s_waitcnt lgkmcnt(4)
	v_cvt_pk_bf16_f32 v43, v50, v52
	s_waitcnt lgkmcnt(2)
	v_cvt_pk_bf16_f32 v44, v54, v56
	s_waitcnt lgkmcnt(0)
	v_cvt_pk_bf16_f32 v45, v58, v60
	v_lshl_add_u64 v[64:65], v[62:63], 0, v[64:65]
	v_or_b32_e32 v46, s20, v25
	global_store_dwordx4 v[64:65], v[42:45], off sc0 sc1
	s_nop 1
	v_cvt_pk_bf16_f32 v42, v49, v47
	v_ashrrev_i32_e32 v47, 31, v46
	v_cvt_pk_bf16_f32 v43, v51, v53
	v_cvt_pk_bf16_f32 v44, v55, v57
	v_cvt_pk_bf16_f32 v45, v59, v61
	v_lshlrev_b64 v[46:47], 9, v[46:47]
	ds_read2_b32 v[48:49], v5 offset0:49 offset1:57
	ds_read2_b32 v[50:51], v5 offset0:16 offset1:24
	ds_read2_b32 v[52:53], v5 offset0:82 offset1:90
	ds_read2_b32 v[54:55], v5 offset0:115 offset1:123
	ds_read2_b32 v[56:57], v5 offset0:148 offset1:156
	ds_read2_b32 v[58:59], v5 offset0:181 offset1:189
	ds_read2_b32 v[60:61], v5 offset0:214 offset1:222
	ds_read2_b32 v[64:65], v5 offset0:247 offset1:255
	v_lshl_add_u64 v[46:47], v[62:63], 0, v[46:47]
	global_store_dwordx4 v[46:47], v[42:45], off sc0 sc1
	v_or_b32_e32 v46, s20, v3
	v_ashrrev_i32_e32 v47, 31, v46
	v_lshlrev_b64 v[46:47], 9, v[46:47]
	s_waitcnt lgkmcnt(6)
	v_cvt_pk_bf16_f32 v42, v50, v48
	s_waitcnt lgkmcnt(4)
	v_cvt_pk_bf16_f32 v43, v52, v54
	s_waitcnt lgkmcnt(2)
	v_cvt_pk_bf16_f32 v44, v56, v58
	s_waitcnt lgkmcnt(0)
	v_cvt_pk_bf16_f32 v45, v60, v64
	v_lshl_add_u64 v[46:47], v[62:63], 0, v[46:47]
	global_store_dwordx4 v[46:47], v[42:45], off sc0 sc1
	v_or_b32_e32 v46, s20, v1
	v_ashrrev_i32_e32 v47, 31, v46
	v_lshlrev_b64 v[46:47], 9, v[46:47]
	v_cvt_pk_bf16_f32 v42, v51, v49
	v_cvt_pk_bf16_f32 v43, v53, v55
	v_cvt_pk_bf16_f32 v44, v57, v59
	v_cvt_pk_bf16_f32 v45, v61, v65
	v_lshl_add_u64 v[46:47], v[62:63], 0, v[46:47]
	global_store_dwordx4 v[46:47], v[42:45], off sc0 sc1
	s_waitcnt lgkmcnt(0)
	s_branch .LBB0_186
; #define LAS __attribute__((address_space(3)))
; __device__ __forceinline__ f32x4 ld_nt(const float* p) { return __builtin_nontemporal_load((const f32x4*)p); }
; __device__ __forceinline__ void transpose_item(const float* W, int K, int pitch, int ncols, f16* WT, LAS float* scr, int item, int lane) {
;     const int nblk = ncols / 32, kb = item / nblk, nb = item % nblk, k0 = 64 * kb, n0 = 32 * nb;
;     const int kr = lane >> 3, nq = (lane & 7) * 4;
;     f32x4 v[8];
; #pragma unroll
;     for (int i = 0; i < 8; ++i) v[i] = ld_nt(W + (size_t)(k0 + kr + 8 * i) * pitch + n0 + nq);
;     __builtin_amdgcn_sched_barrier(0);
; #pragma unroll
;     for (int i = 0; i < 8; ++i) { LAS float* sp = scr + (kr + 8 * i) * 33 + nq; sp[0] = v[i][0]; sp[1] = v[i][1]; sp[2] = v[i][2]; sp[3] = v[i][3]; }
;     asm volatile("s_waitcnt lgkmcnt(0)" ::: "memory");
;     const int c = lane & 7;
; #pragma unroll
;     for (int j = 0; j < 4; ++j) { const int n = (lane >> 3) + 8 * j; const LAS float* sp = scr + (8 * c) * 33 + n;
;         u32x4 o; o.x = pk_f16(sp[0 * 33], sp[1 * 33]); o.y = pk_f16(sp[2 * 33], sp[3 * 33]); o.z = pk_f16(sp[4 * 33], sp[5 * 33]); o.w = pk_f16(sp[6 * 33], sp[7 * 33]);
;         *(u32x4*)(WT + (size_t)(n0 + n) * K + k0 + 8 * c) = o; }
;     asm volatile("s_waitcnt lgkmcnt(0)" ::: "memory");
; __device__ __forceinline__ void transpose_dispatch(int it, const float* in_w, const float* out_w, const float* glu_w, const float* pool_w, unsigned char* ws, LAS float* scr, int lane) {
;     ...
;     transpose_item(glu_w, SW, 2 * SW, 2 * SW, (f16*)(ws + WS_WGLU), scr, it, lane);
; __global__ void __launch_bounds__(NTHREADS, 2) mk_fwd(Args a) {
;     ...
;                    if (b2 < 16) transpose_dispatch((832 + b2) * 8 + wave, a.in[7], a.in[20], a.in[18], a.in[8], a.ws, scr, lane); } );
.LBB0_203:
	s_cmpk_lt_i32 s81, 0x90
	s_cbranch_scc0 .LBB0_212
	s_add_i32 s7, s6, 0x1600
	s_cmpk_gt_i32 s7, 0x7f
	s_mov_b64 s[12:13], -1
	s_cbranch_scc0 .LBB0_210
	s_lshl_b32 s8, s7, 5
	s_and_b32 s8, s8, 0x7e0
	s_cmpk_gt_u32 s7, 0x167f
	s_mov_b32 s13, 0
	s_mov_b64 s[14:15], -1
	v_or_b32_e32 v9, s8, v24
	v_or_b32_e32 v8, s8, v25
	v_or_b32_e32 v7, s8, v3
	v_or_b32_e32 v6, s8, v1
	s_cbranch_scc0 .LBB0_207
	s_and_b32 s9, s7, 0x7fffffc0
	s_add_i32 s12, s9, 0xffffe980
	s_lshl_b32 s9, s8, 2
	s_add_u32 s14, s40, s9
	v_or_b32_e32 v22, s12, v24
	s_addc_u32 s15, s41, 0
	v_lshlrev_b32_e32 v48, 2, v4
	v_mov_b32_e32 v49, 0
	v_lshl_add_u64 v[40:41], s[14:15], 0, v[48:49]
	v_or_b32_e32 v48, 8, v22
	v_lshlrev_b64 v[12:13], 13, v[48:49]
	v_or_b32_e32 v48, 16, v22
	v_lshlrev_b64 v[18:19], 13, v[48:49]
	v_or_b32_e32 v48, 24, v22
	v_lshlrev_b64 v[20:21], 13, v[48:49]
	v_or_b32_e32 v48, 32, v22
	v_lshlrev_b64 v[32:33], 13, v[48:49]
	v_or_b32_e32 v48, 40, v22
	v_mov_b32_e32 v23, v49
	v_lshlrev_b64 v[34:35], 13, v[48:49]
	v_or_b32_e32 v48, 48, v22
	v_lshlrev_b64 v[10:11], 13, v[22:23]
	v_lshlrev_b64 v[42:43], 13, v[48:49]
	v_or_b32_e32 v48, 56, v22
	v_lshl_add_u64 v[10:11], v[40:41], 0, v[10:11]
	v_lshl_add_u64 v[14:15], v[40:41], 0, v[12:13]
	v_lshl_add_u64 v[18:19], v[40:41], 0, v[18:19]
	v_lshl_add_u64 v[28:29], v[40:41], 0, v[20:21]
	v_lshl_add_u64 v[32:33], v[40:41], 0, v[32:33]
	v_lshl_add_u64 v[36:37], v[40:41], 0, v[34:35]
	v_lshl_add_u64 v[42:43], v[40:41], 0, v[42:43]
	v_lshlrev_b64 v[22:23], 13, v[48:49]
	global_load_dwordx4 v[10:13], v[10:11], off nt
	s_nop 0
	global_load_dwordx4 v[14:17], v[14:15], off nt
	s_nop 0
	global_load_dwordx4 v[18:21], v[18:19], off nt
	s_nop 0
	global_load_dwordx4 v[28:31], v[28:29], off nt
	s_nop 0
	global_load_dwordx4 v[32:35], v[32:33], off nt
	s_nop 0
	global_load_dwordx4 v[36:39], v[36:37], off nt
	v_lshl_add_u64 v[22:23], v[40:41], 0, v[22:23]
	global_load_dwordx4 v[40:43], v[42:43], off nt
	s_nop 0
	global_load_dwordx4 v[44:47], v[22:23], off nt
	s_waitcnt vmcnt(0)
	ds_write2_b32 v26, v10, v11 offset1:1
	ds_write2_b32 v26, v12, v13 offset0:2 offset1:3
	v_add_u32_e32 v10, 0x420, v26
	ds_write2_b32 v10, v14, v15 offset1:1
	v_add_u32_e32 v10, 0x428, v26
	ds_write2_b32 v10, v16, v17 offset1:1
	v_add_u32_e32 v10, 0x840, v26
	ds_write2_b32 v10, v18, v19 offset1:1
	v_add_u32_e32 v10, 0x848, v26
	ds_write2_b32 v10, v20, v21 offset1:1
	v_add_u32_e32 v10, 0xc60, v26
	ds_write2_b32 v10, v28, v29 offset1:1
	v_add_u32_e32 v10, 0xc68, v26
	ds_write2_b32 v10, v30, v31 offset1:1
	v_add_u32_e32 v10, 0x1080, v26
	ds_write2_b32 v10, v32, v33 offset1:1
	v_add_u32_e32 v10, 0x1088, v26
	ds_write2_b32 v10, v34, v35 offset1:1
	v_add_u32_e32 v10, 0x14a0, v26
	ds_write2_b32 v10, v36, v37 offset1:1
	v_add_u32_e32 v10, 0x14a8, v26
	ds_write2_b32 v10, v38, v39 offset1:1
	v_add_u32_e32 v10, 0x18c0, v26
	ds_write2_b32 v10, v40, v41 offset1:1
	v_add_u32_e32 v10, 0x18c8, v26
	ds_write2_b32 v10, v42, v43 offset1:1
	v_add_u32_e32 v10, 0x1ce0, v26
	ds_write2_b32 v10, v44, v45 offset1:1
	v_add_u32_e32 v10, 0x1ce8, v26
	ds_write2_b32 v10, v46, v47 offset1:1
	s_waitcnt lgkmcnt(0)
	ds_read2_b32 v[14:15], v5 offset0:33 offset1:41
	ds_read2_b32 v[16:17], v5 offset1:8
	ds_read2_b32 v[18:19], v5 offset0:66 offset1:74
	ds_read2_b32 v[20:21], v5 offset0:99 offset1:107
	ds_read2_b32 v[22:23], v5 offset0:132 offset1:140
	ds_read2_b32 v[28:29], v5 offset0:165 offset1:173
	ds_read2_b32 v[30:31], v5 offset0:198 offset1:206
	ds_read2_b32 v[32:33], v5 offset0:231 offset1:239
	s_lshl_b64 s[12:13], s[12:13], 1
	s_add_u32 s10, s10, s12
	s_addc_u32 s11, s11, s13
	v_lshlrev_b32_e32 v48, 1, v2
	v_lshl_add_u64 v[34:35], s[10:11], 0, v[48:49]
	v_lshlrev_b32_e32 v48, 11, v9
	s_waitcnt lgkmcnt(6)
	v_cvt_pk_bf16_f32 v10, v16, v14
	s_waitcnt lgkmcnt(4)
	v_cvt_pk_bf16_f32 v11, v18, v20
	s_waitcnt lgkmcnt(2)
	v_cvt_pk_bf16_f32 v12, v22, v28
	s_waitcnt lgkmcnt(0)
	v_cvt_pk_bf16_f32 v13, v30, v32
	v_lshl_add_u64 v[36:37], v[34:35], 0, v[48:49]
	global_store_dwordx4 v[36:37], v[10:13], off sc0 sc1
	v_lshlrev_b32_e32 v48, 11, v8
	s_mov_b64 s[14:15], 0
	v_cvt_pk_bf16_f32 v10, v17, v15
	v_cvt_pk_bf16_f32 v11, v19, v21
	v_cvt_pk_bf16_f32 v12, v23, v29
	v_cvt_pk_bf16_f32 v13, v31, v33
	ds_read2_b32 v[16:17], v5 offset0:49 offset1:57
	ds_read2_b32 v[18:19], v5 offset0:16 offset1:24
	ds_read2_b32 v[20:21], v5 offset0:82 offset1:90
	ds_read2_b32 v[22:23], v5 offset0:115 offset1:123
	ds_read2_b32 v[28:29], v5 offset0:148 offset1:156
	ds_read2_b32 v[30:31], v5 offset0:181 offset1:189
	ds_read2_b32 v[32:33], v5 offset0:214 offset1:222
	ds_read2_b32 v[36:37], v5 offset0:247 offset1:255
	v_lshl_add_u64 v[14:15], v[34:35], 0, v[48:49]
	v_lshlrev_b32_e32 v48, 11, v7
	global_store_dwordx4 v[14:15], v[10:13], off sc0 sc1
	v_lshl_add_u64 v[14:15], v[34:35], 0, v[48:49]
	v_lshlrev_b32_e32 v48, 11, v6
	s_waitcnt lgkmcnt(6)
	v_cvt_pk_bf16_f32 v10, v18, v16
	s_waitcnt lgkmcnt(4)
	v_cvt_pk_bf16_f32 v11, v20, v22
	s_waitcnt lgkmcnt(2)
	v_cvt_pk_bf16_f32 v12, v28, v30
	s_waitcnt lgkmcnt(0)
	v_cvt_pk_bf16_f32 v13, v32, v36
	global_store_dwordx4 v[14:15], v[10:13], off sc0 sc1
	v_lshl_add_u64 v[14:15], v[34:35], 0, v[48:49]
	s_nop 0
	v_cvt_pk_bf16_f32 v10, v19, v17
	v_cvt_pk_bf16_f32 v11, v21, v23
	v_cvt_pk_bf16_f32 v12, v29, v31
	v_cvt_pk_bf16_f32 v13, v33, v37
	global_store_dwordx4 v[14:15], v[10:13], off sc0 sc1
	s_waitcnt lgkmcnt(0)
; #define LAS __attribute__((address_space(3)))
; __device__ __forceinline__ f32x4 ld_nt(const float* p) { return __builtin_nontemporal_load((const f32x4*)p); }
; __device__ __forceinline__ void transpose_item(const float* W, int K, int pitch, int ncols, f16* WT, LAS float* scr, int item, int lane) {
;     const int nblk = ncols / 32, kb = item / nblk, nb = item % nblk, k0 = 64 * kb, n0 = 32 * nb;
;     const int kr = lane >> 3, nq = (lane & 7) * 4;
;     f32x4 v[8];
; #pragma unroll
;     for (int i = 0; i < 8; ++i) v[i] = ld_nt(W + (size_t)(k0 + kr + 8 * i) * pitch + n0 + nq);
;     __builtin_amdgcn_sched_barrier(0);
; #pragma unroll
;     for (int i = 0; i < 8; ++i) { LAS float* sp = scr + (kr + 8 * i) * 33 + nq; sp[0] = v[i][0]; sp[1] = v[i][1]; sp[2] = v[i][2]; sp[3] = v[i][3]; }
;     asm volatile("s_waitcnt lgkmcnt(0)" ::: "memory");
;     const int c = lane & 7;
; #pragma unroll
;     for (int j = 0; j < 4; ++j) { const int n = (lane >> 3) + 8 * j; const LAS float* sp = scr + (8 * c) * 33 + n;
;         u32x4 o; o.x = pk_f16(sp[0 * 33], sp[1 * 33]); o.y = pk_f16(sp[2 * 33], sp[3 * 33]); o.z = pk_f16(sp[4 * 33], sp[5 * 33]); o.w = pk_f16(sp[6 * 33], sp[7 * 33]);
;         *(u32x4*)(WT + (size_t)(n0 + n) * K + k0 + 8 * c) = o; }
;     asm volatile("s_waitcnt lgkmcnt(0)" ::: "memory");
; __device__ __forceinline__ void transpose_dispatch(int it, const float* in_w, const float* out_w, const float* glu_w, const float* pool_w, unsigned char* ws, LAS float* scr, int lane) {
;     ...
;     if (it < TI_OUT) { transpose_item(out_w, D, D, D, (f16*)(ws + WS_WOUT), scr, it, lane); return; } it -= TI_OUT;
.LBB0_207:
	s_andn2_b64 vcc, exec, s[14:15]
	s_cbranch_vccnz .LBB0_209
	s_add_i32 s9, s7, 0xf180
	s_and_b32 s10, s9, 0xffc0
	s_lshl_b32 s8, s8, 2
	s_add_u32 s8, s44, s8
	v_or_b32_e32 v12, s10, v24
	s_addc_u32 s9, s45, 0
	v_lshlrev_b32_e32 v22, 2, v4
	v_mov_b32_e32 v23, 0
	v_lshl_add_u64 v[10:11], s[8:9], 0, v[22:23]
	v_lshlrev_b32_e32 v22, 13, v12
	v_lshl_add_u64 v[40:41], v[10:11], 0, v[22:23]
	v_add_co_u32_e32 v14, vcc, 0x10000, v40
	s_nop 1
	v_addc_co_u32_e32 v15, vcc, 0, v41, vcc
	v_add_co_u32_e32 v18, vcc, 0x20000, v40
	global_load_dwordx4 v[10:13], v[40:41], off nt
	s_nop 0
	global_load_dwordx4 v[14:17], v[14:15], off nt
	v_addc_co_u32_e32 v19, vcc, 0, v41, vcc
	v_add_co_u32_e32 v28, vcc, 0x30000, v40
	s_nop 1
	v_addc_co_u32_e32 v29, vcc, 0, v41, vcc
	v_add_co_u32_e32 v32, vcc, 0x40000, v40
	global_load_dwordx4 v[18:21], v[18:19], off nt
	s_nop 0
	global_load_dwordx4 v[28:31], v[28:29], off nt
	v_addc_co_u32_e32 v33, vcc, 0, v41, vcc
	v_add_co_u32_e32 v36, vcc, 0x50000, v40
	s_nop 1
	v_addc_co_u32_e32 v37, vcc, 0, v41, vcc
	v_add_co_u32_e32 v42, vcc, 0x60000, v40
	global_load_dwordx4 v[32:35], v[32:33], off nt
	s_nop 0
	global_load_dwordx4 v[36:39], v[36:37], off nt
	v_addc_co_u32_e32 v43, vcc, 0, v41, vcc
	v_add_co_u32_e32 v44, vcc, 0x70000, v40
	s_nop 1
	v_addc_co_u32_e32 v45, vcc, 0, v41, vcc
	global_load_dwordx4 v[40:43], v[42:43], off nt
	s_nop 0
	global_load_dwordx4 v[44:47], v[44:45], off nt
	s_waitcnt vmcnt(0)
	ds_write2_b32 v26, v10, v11 offset1:1
	ds_write2_b32 v26, v12, v13 offset0:2 offset1:3
	v_add_u32_e32 v10, 0x420, v26
	ds_write2_b32 v10, v14, v15 offset1:1
	v_add_u32_e32 v10, 0x428, v26
	ds_write2_b32 v10, v16, v17 offset1:1
	v_add_u32_e32 v10, 0x840, v26
	ds_write2_b32 v10, v18, v19 offset1:1
	v_add_u32_e32 v10, 0x848, v26
	ds_write2_b32 v10, v20, v21 offset1:1
	v_add_u32_e32 v10, 0xc60, v26
	ds_write2_b32 v10, v28, v29 offset1:1
	v_add_u32_e32 v10, 0xc68, v26
	ds_write2_b32 v10, v30, v31 offset1:1
	v_add_u32_e32 v10, 0x1080, v26
	ds_write2_b32 v10, v32, v33 offset1:1
	v_add_u32_e32 v10, 0x1088, v26
	ds_write2_b32 v10, v34, v35 offset1:1
	v_add_u32_e32 v10, 0x14a0, v26
	ds_write2_b32 v10, v36, v37 offset1:1
	v_add_u32_e32 v10, 0x14a8, v26
	ds_write2_b32 v10, v38, v39 offset1:1
	v_add_u32_e32 v10, 0x18c0, v26
	ds_write2_b32 v10, v40, v41 offset1:1
	v_add_u32_e32 v10, 0x18c8, v26
	ds_write2_b32 v10, v42, v43 offset1:1
	v_add_u32_e32 v10, 0x1ce0, v26
	ds_write2_b32 v10, v44, v45 offset1:1
	v_add_u32_e32 v10, 0x1ce8, v26
	ds_write2_b32 v10, v46, v47 offset1:1
	s_waitcnt lgkmcnt(0)
	ds_read2_b32 v[14:15], v5 offset0:33 offset1:41
	ds_read2_b32 v[16:17], v5 offset1:8
	ds_read2_b32 v[18:19], v5 offset0:66 offset1:74
	ds_read2_b32 v[20:21], v5 offset0:99 offset1:107
	ds_read2_b32 v[28:29], v5 offset0:132 offset1:140
	ds_read2_b32 v[30:31], v5 offset0:165 offset1:173
	ds_read2_b32 v[32:33], v5 offset0:198 offset1:206
	ds_read2_b32 v[34:35], v5 offset0:231 offset1:239
	s_lshl_b32 s8, s10, 1
	s_add_u32 s2, s2, s8
	s_addc_u32 s3, s3, 0
	v_lshlrev_b32_e32 v22, 1, v2
	v_lshl_add_u64 v[36:37], s[2:3], 0, v[22:23]
	v_lshlrev_b32_e32 v22, 12, v9
	s_waitcnt lgkmcnt(6)
	v_cvt_pk_bf16_f32 v10, v16, v14
	s_waitcnt lgkmcnt(4)
	v_cvt_pk_bf16_f32 v11, v18, v20
	s_waitcnt lgkmcnt(2)
	v_cvt_pk_bf16_f32 v12, v28, v30
	s_waitcnt lgkmcnt(0)
	v_cvt_pk_bf16_f32 v13, v32, v34
	v_lshl_add_u64 v[38:39], v[36:37], 0, v[22:23]
	global_store_dwordx4 v[38:39], v[10:13], off sc0 sc1
	v_lshlrev_b32_e32 v22, 12, v8
	v_lshl_add_u64 v[8:9], v[36:37], 0, v[22:23]
	v_cvt_pk_bf16_f32 v10, v17, v15
	v_cvt_pk_bf16_f32 v11, v19, v21
	v_cvt_pk_bf16_f32 v12, v29, v31
	v_cvt_pk_bf16_f32 v13, v33, v35
	ds_read2_b32 v[14:15], v5 offset0:49 offset1:57
	ds_read2_b32 v[16:17], v5 offset0:16 offset1:24
	ds_read2_b32 v[18:19], v5 offset0:82 offset1:90
	ds_read2_b32 v[20:21], v5 offset0:115 offset1:123
	ds_read2_b32 v[28:29], v5 offset0:148 offset1:156
	ds_read2_b32 v[30:31], v5 offset0:181 offset1:189
	ds_read2_b32 v[32:33], v5 offset0:214 offset1:222
	ds_read2_b32 v[34:35], v5 offset0:247 offset1:255
	v_lshlrev_b32_e32 v22, 12, v7
	global_store_dwordx4 v[8:9], v[10:13], off sc0 sc1
	s_waitcnt lgkmcnt(6)
	v_cvt_pk_bf16_f32 v8, v16, v14
	s_waitcnt lgkmcnt(4)
	v_cvt_pk_bf16_f32 v9, v18, v20
	s_waitcnt lgkmcnt(2)
	v_cvt_pk_bf16_f32 v10, v28, v30
	s_waitcnt lgkmcnt(0)
	v_cvt_pk_bf16_f32 v11, v32, v34
	v_lshl_add_u64 v[12:13], v[36:37], 0, v[22:23]
	v_lshlrev_b32_e32 v22, 12, v6
	global_store_dwordx4 v[12:13], v[8:11], off sc0 sc1
	v_lshl_add_u64 v[6:7], v[36:37], 0, v[22:23]
	s_nop 0
	v_cvt_pk_bf16_f32 v8, v17, v15
	v_cvt_pk_bf16_f32 v9, v19, v21
	v_cvt_pk_bf16_f32 v10, v29, v31
	v_cvt_pk_bf16_f32 v11, v33, v35
	global_store_dwordx4 v[6:7], v[8:11], off sc0 sc1
	s_waitcnt lgkmcnt(0)

; #define LAS __attribute__((address_space(3)))
; __device__ __forceinline__ f32x4 ld_nt(const float* p) { return __builtin_nontemporal_load((const f32x4*)p); }
; __device__ __forceinline__ void transpose_item(const float* W, int K, int pitch, int ncols, f16* WT, LAS float* scr, int item, int lane) {
;     const int nblk = ncols / 32, kb = item / nblk, nb = item % nblk, k0 = 64 * kb, n0 = 32 * nb;
;     const int kr = lane >> 3, nq = (lane & 7) * 4;
;     f32x4 v[8];
; #pragma unroll
;     for (int i = 0; i < 8; ++i) v[i] = ld_nt(W + (size_t)(k0 + kr + 8 * i) * pitch + n0 + nq);
;     __builtin_amdgcn_sched_barrier(0);
; #pragma unroll
;     for (int i = 0; i < 8; ++i) { LAS float* sp = scr + (kr + 8 * i) * 33 + nq; sp[0] = v[i][0]; sp[1] = v[i][1]; sp[2] = v[i][2]; sp[3] = v[i][3]; }
;     asm volatile("s_waitcnt lgkmcnt(0)" ::: "memory");
;     const int c = lane & 7;
; #pragma unroll
;     for (int j = 0; j < 4; ++j) { const int n = (lane >> 3) + 8 * j; const LAS float* sp = scr + (8 * c) * 33 + n;
;         u32x4 o; o.x = pk_f16(sp[0 * 33], sp[1 * 33]); o.y = pk_f16(sp[2 * 33], sp[3 * 33]); o.z = pk_f16(sp[4 * 33], sp[5 * 33]); o.w = pk_f16(sp[6 * 33], sp[7 * 33]);
;         *(u32x4*)(WT + (size_t)(n0 + n) * K + k0 + 8 * c) = o; }
;     asm volatile("s_waitcnt lgkmcnt(0)" ::: "memory");
; __device__ __forceinline__ void transpose_dispatch(int it, const float* in_w, const float* out_w, const float* glu_w, const float* pool_w, unsigned char* ws, LAS float* scr, int lane) {
;     if (it < 4 * TI_POOL1) { const int pg = it / TI_POOL1; transpose_item(pool_w + pg * 65536, 256, 256, 256, (f16*)(ws + WS_WPOOL) + pg * 65536, scr, it % TI_POOL1, lane); return; } it -= 4 * TI_POOL1;
.LBB0_210:
	s_andn2_b64 vcc, exec, s[12:13]
	s_cbranch_vccnz .LBB0_212
	s_lshl_b32 s2, s7, 11
	s_sub_i32 s2, 0, s2
	s_and_b32 s2, s2, 0xffff0000
	s_sub_i32 s2, 0, s2
	s_ashr_i32 s3, s2, 31
	s_lshl_b64 s[8:9], s[2:3], 2
	v_readlane_b32 s56, v254, 18
	v_readlane_b32 s57, v254, 19
	s_add_u32 s11, s56, s8
	s_addc_u32 s12, s57, s9
	s_lshl_b64 s[2:3], s[2:3], 1
	s_add_u32 s13, s0, s2
	s_addc_u32 s14, s1, s3
	s_sub_i32 s2, 0, s7
	s_bfe_u32 s3, s2, 0x20003
	s_and_b32 s2, s2, 7
	s_sub_i32 s2, 0, s2
	s_sub_i32 s3, 0, s3
	s_sext_i32_i16 s2, s2
	s_sext_i32_i16 s3, s3
	s_lshl_b32 s2, s2, 5
	s_lshl_b32 s10, s3, 6
	s_ashr_i32 s3, s2, 31
	v_or_b32_e32 v22, s10, v24
	s_lshl_b64 s[8:9], s[2:3], 2
	s_add_u32 s8, s11, s8
	v_ashrrev_i32_e32 v23, 31, v22
	v_or_b32_e32 v8, 8, v22
	v_or_b32_e32 v14, 16, v22
	v_or_b32_e32 v16, 24, v22
	v_or_b32_e32 v28, 32, v22
	v_or_b32_e32 v30, 40, v22
	v_or_b32_e32 v38, 48, v22
	s_addc_u32 s9, s12, s9
	v_lshlrev_b32_e32 v44, 2, v4
	v_mov_b32_e32 v45, 0
	v_lshlrev_b64 v[6:7], 10, v[22:23]
	v_ashrrev_i32_e32 v9, 31, v8
	v_ashrrev_i32_e32 v15, 31, v14
	v_ashrrev_i32_e32 v17, 31, v16
	v_ashrrev_i32_e32 v29, 31, v28
	v_ashrrev_i32_e32 v31, 31, v30
	v_ashrrev_i32_e32 v39, 31, v38
	v_or_b32_e32 v22, 56, v22
	v_lshl_add_u64 v[36:37], s[8:9], 0, v[44:45]
	v_lshlrev_b64 v[8:9], 10, v[8:9]
	v_lshlrev_b64 v[14:15], 10, v[14:15]
	v_lshlrev_b64 v[16:17], 10, v[16:17]
	v_lshlrev_b64 v[28:29], 10, v[28:29]
	v_lshlrev_b64 v[30:31], 10, v[30:31]
	v_lshlrev_b64 v[38:39], 10, v[38:39]
	v_ashrrev_i32_e32 v23, 31, v22
	v_lshl_add_u64 v[6:7], v[36:37], 0, v[6:7]
	v_lshl_add_u64 v[10:11], v[36:37], 0, v[8:9]
	v_lshl_add_u64 v[14:15], v[36:37], 0, v[14:15]
	v_lshl_add_u64 v[18:19], v[36:37], 0, v[16:17]
	v_lshl_add_u64 v[28:29], v[36:37], 0, v[28:29]
	v_lshl_add_u64 v[32:33], v[36:37], 0, v[30:31]
	v_lshl_add_u64 v[38:39], v[36:37], 0, v[38:39]
	v_lshlrev_b64 v[22:23], 10, v[22:23]
	global_load_dwordx4 v[6:9], v[6:7], off nt
	s_nop 0
	global_load_dwordx4 v[10:13], v[10:11], off nt
	s_nop 0
	global_load_dwordx4 v[14:17], v[14:15], off nt
	s_nop 0
	global_load_dwordx4 v[18:21], v[18:19], off nt
	s_nop 0
	global_load_dwordx4 v[28:31], v[28:29], off nt
	s_nop 0
	global_load_dwordx4 v[32:35], v[32:33], off nt
	v_lshl_add_u64 v[22:23], v[36:37], 0, v[22:23]
	global_load_dwordx4 v[36:39], v[38:39], off nt
	s_nop 0
	global_load_dwordx4 v[40:43], v[22:23], off nt
	v_readlane_b32 s58, v254, 20
	v_readlane_b32 s59, v254, 21
	v_readlane_b32 s60, v254, 22
	v_readlane_b32 s61, v254, 23
	v_readlane_b32 s62, v254, 24
	v_readlane_b32 s63, v254, 25
	v_readlane_b32 s64, v254, 26
	v_readlane_b32 s65, v254, 27
	v_readlane_b32 s66, v254, 28
	v_readlane_b32 s67, v254, 29
	v_readlane_b32 s68, v254, 30
	v_readlane_b32 s69, v254, 31
	v_readlane_b32 s70, v254, 32
	v_readlane_b32 s71, v254, 33
	v_add_u32_e32 v4, 0x420, v26
	s_waitcnt vmcnt(0)
	ds_write2_b32 v26, v6, v7 offset1:1
	ds_write2_b32 v26, v8, v9 offset0:2 offset1:3
	ds_write2_b32 v4, v10, v11 offset1:1
	v_add_u32_e32 v4, 0x428, v26
	ds_write2_b32 v4, v12, v13 offset1:1
	v_add_u32_e32 v4, 0x840, v26
	ds_write2_b32 v4, v14, v15 offset1:1
	v_add_u32_e32 v4, 0x848, v26
	ds_write2_b32 v4, v16, v17 offset1:1
	v_add_u32_e32 v4, 0xc60, v26
	ds_write2_b32 v4, v18, v19 offset1:1
	v_add_u32_e32 v4, 0xc68, v26
	ds_write2_b32 v4, v20, v21 offset1:1
	v_add_u32_e32 v4, 0x1080, v26
	ds_write2_b32 v4, v28, v29 offset1:1
	v_add_u32_e32 v4, 0x1088, v26
	ds_write2_b32 v4, v30, v31 offset1:1
	v_add_u32_e32 v4, 0x14a0, v26
	ds_write2_b32 v4, v32, v33 offset1:1
	v_add_u32_e32 v4, 0x14a8, v26
	ds_write2_b32 v4, v34, v35 offset1:1
	v_add_u32_e32 v4, 0x18c0, v26
	ds_write2_b32 v4, v36, v37 offset1:1
	v_add_u32_e32 v4, 0x18c8, v26
	ds_write2_b32 v4, v38, v39 offset1:1
	v_add_u32_e32 v4, 0x1ce0, v26
	ds_write2_b32 v4, v40, v41 offset1:1
	v_add_u32_e32 v4, 0x1ce8, v26
	ds_write2_b32 v4, v42, v43 offset1:1
	s_waitcnt lgkmcnt(0)
	s_ashr_i32 s11, s10, 31
	ds_read2_b32 v[10:11], v5 offset0:33 offset1:41
	ds_read2_b32 v[12:13], v5 offset1:8
	ds_read2_b32 v[14:15], v5 offset0:66 offset1:74
	ds_read2_b32 v[16:17], v5 offset0:99 offset1:107
	ds_read2_b32 v[18:19], v5 offset0:132 offset1:140
	ds_read2_b32 v[20:21], v5 offset0:165 offset1:173
	ds_read2_b32 v[22:23], v5 offset0:198 offset1:206
	ds_read2_b32 v[26:27], v5 offset0:231 offset1:239
	s_lshl_b64 s[8:9], s[10:11], 1
	s_add_u32 s8, s13, s8
	v_or_b32_e32 v30, s2, v24
	s_addc_u32 s9, s14, s9
	v_lshlrev_b32_e32 v44, 1, v2
	v_ashrrev_i32_e32 v31, 31, v30
	v_lshl_add_u64 v[28:29], s[8:9], 0, v[44:45]
	v_lshlrev_b64 v[30:31], 9, v[30:31]
	s_waitcnt lgkmcnt(6)
	v_cvt_pk_bf16_f32 v6, v12, v10
	s_waitcnt lgkmcnt(4)
	v_cvt_pk_bf16_f32 v7, v14, v16
	s_waitcnt lgkmcnt(2)
	v_cvt_pk_bf16_f32 v8, v18, v20
	s_waitcnt lgkmcnt(0)
	v_cvt_pk_bf16_f32 v9, v22, v26
	v_lshl_add_u64 v[30:31], v[28:29], 0, v[30:31]
	global_store_dwordx4 v[30:31], v[6:9], off sc0 sc1
	v_or_b32_e32 v10, s2, v25
	v_or_b32_e32 v2, s2, v3
	v_cvt_pk_bf16_f32 v6, v13, v11
	v_cvt_pk_bf16_f32 v7, v15, v17
	v_cvt_pk_bf16_f32 v8, v19, v21
	v_cvt_pk_bf16_f32 v9, v23, v27
	ds_read2_b32 v[12:13], v5 offset0:49 offset1:57
	ds_read2_b32 v[14:15], v5 offset0:16 offset1:24
	ds_read2_b32 v[16:17], v5 offset0:82 offset1:90
	ds_read2_b32 v[18:19], v5 offset0:115 offset1:123
	ds_read2_b32 v[20:21], v5 offset0:148 offset1:156
	ds_read2_b32 v[22:23], v5 offset0:181 offset1:189
	ds_read2_b32 v[24:25], v5 offset0:214 offset1:222
	ds_read2_b32 v[26:27], v5 offset0:247 offset1:255
	v_ashrrev_i32_e32 v11, 31, v10
	v_lshlrev_b64 v[10:11], 9, v[10:11]
	v_ashrrev_i32_e32 v3, 31, v2
	v_lshl_add_u64 v[10:11], v[28:29], 0, v[10:11]
	v_lshlrev_b64 v[2:3], 9, v[2:3]
	global_store_dwordx4 v[10:11], v[6:9], off sc0 sc1
	s_waitcnt lgkmcnt(6)
	v_cvt_pk_bf16_f32 v4, v14, v12
	s_waitcnt lgkmcnt(4)
	v_cvt_pk_bf16_f32 v5, v16, v18
	s_waitcnt lgkmcnt(2)
	v_cvt_pk_bf16_f32 v6, v20, v22
	s_waitcnt lgkmcnt(0)
	v_cvt_pk_bf16_f32 v7, v24, v26
	v_lshl_add_u64 v[2:3], v[28:29], 0, v[2:3]
	global_store_dwordx4 v[2:3], v[4:7], off sc0 sc1
	v_cvt_pk_bf16_f32 v2, v15, v13
	v_cvt_pk_bf16_f32 v3, v17, v19
	v_or_b32_e32 v6, s2, v1
	v_ashrrev_i32_e32 v7, 31, v6
	v_lshlrev_b64 v[6:7], 9, v[6:7]
	v_cvt_pk_bf16_f32 v4, v21, v23
	v_cvt_pk_bf16_f32 v5, v25, v27
	v_lshl_add_u64 v[6:7], v[28:29], 0, v[6:7]
	global_store_dwordx4 v[6:7], v[2:5], off sc0 sc1
	s_waitcnt lgkmcnt(0)

; #define LAS __attribute__((address_space(3)))
; __device__ __forceinline__ f32x4 ld_nt(const float* p) { return __builtin_nontemporal_load((const f32x4*)p); }
; __device__ __forceinline__ void transpose_item(const float* W, int K, int pitch, int ncols, f16* WT, LAS float* scr, int item, int lane) {
;     const int nblk = ncols / 32, kb = item / nblk, nb = item % nblk, k0 = 64 * kb, n0 = 32 * nb;
;     const int kr = lane >> 3, nq = (lane & 7) * 4;
;     f32x4 v[8];
; #pragma unroll
;     for (int i = 0; i < 8; ++i) v[i] = ld_nt(W + (size_t)(k0 + kr + 8 * i) * pitch + n0 + nq);
;     __builtin_amdgcn_sched_barrier(0);
; #pragma unroll
;     for (int i = 0; i < 8; ++i) { LAS float* sp = scr + (kr + 8 * i) * 33 + nq; sp[0] = v[i][0]; sp[1] = v[i][1]; sp[2] = v[i][2]; sp[3] = v[i][3]; }
;     asm volatile("s_waitcnt lgkmcnt(0)" ::: "memory");
;     const int c = lane & 7;
; #pragma unroll
;     for (int j = 0; j < 4; ++j) { const int n = (lane >> 3) + 8 * j; const LAS float* sp = scr + (8 * c) * 33 + n;
;         u32x4 o; o.x = pk_f16(sp[0 * 33], sp[1 * 33]); o.y = pk_f16(sp[2 * 33], sp[3 * 33]); o.z = pk_f16(sp[4 * 33], sp[5 * 33]); o.w = pk_f16(sp[6 * 33], sp[7 * 33]);
;         *(u32x4*)(WT + (size_t)(n0 + n) * K + k0 + 8 * c) = o; }
;     asm volatile("s_waitcnt lgkmcnt(0)" ::: "memory");
; }
; __device__ __forceinline__ void transpose_dispatch(int it, const float* in_w, const float* out_w, const float* glu_w, const float* pool_w, unsigned char* ws, LAS float* scr, int lane) {
;     ...
;     transpose_item(glu_w, SW, 2 * SW, 2 * SW, (f16*)(ws + WS_WGLU), scr, it, lane);
.LBB0_213:
	s_and_b64 vcc, exec, s[2:3]
	s_cbranch_vccz .LBB0_230
	s_add_i32 s8, s6, 0xa00
	s_cmpk_gt_i32 s8, 0x7f
	s_mov_b64 s[2:3], -1
	s_cbranch_scc0 .LBB0_228
	s_cmpk_gt_u32 s8, 0x27f
	s_cbranch_scc0 .LBB0_225
	s_cmpk_gt_u32 s8, 0xe7f
	s_cbranch_scc0 .LBB0_222
	s_lshl_b32 s2, s8, 5
	v_and_b32_e32 v7, 7, v0
	s_and_b32 s9, s2, 0x7e0
	v_lshrrev_b32_e32 v8, 3, v212
	v_lshlrev_b32_e32 v1, 2, v7
	s_cmpk_gt_u32 s8, 0x167f
	s_mov_b32 s3, 0
	v_mov_b32_e32 v3, 0
	s_mov_b64 s[6:7], -1
	v_lshlrev_b32_e32 v2, 2, v1
	v_lshlrev_b32_e32 v4, 4, v7
	v_lshlrev_b32_e32 v6, 2, v8
	v_or_b32_e32 v1, s9, v8
	s_cbranch_scc0 .LBB0_219
	s_and_b32 s2, s8, 0x7fffffc0
	s_addk_i32 s2, 0xe980
	s_lshl_b32 s6, s9, 2
	s_add_u32 s6, s40, s6
	v_or_b32_e32 v34, s2, v8
	s_addc_u32 s7, s41, 0
	v_mov_b32_e32 v35, v3
	v_lshl_add_u64 v[36:37], s[6:7], 0, v[2:3]
	v_lshlrev_b64 v[10:11], 13, v[34:35]
	v_lshl_add_u64 v[18:19], v[36:37], 0, v[10:11]
	v_or_b32_e32 v10, 8, v34
	v_mov_b32_e32 v11, v3
	v_lshlrev_b64 v[10:11], 13, v[10:11]
	v_lshl_add_u64 v[20:21], v[36:37], 0, v[10:11]
	global_load_dwordx4 v[10:13], v[18:19], off nt
	global_load_dwordx4 v[14:17], v[20:21], off nt
	v_or_b32_e32 v18, 16, v34
	v_mov_b32_e32 v19, v3
	v_lshlrev_b64 v[18:19], 13, v[18:19]
	v_lshl_add_u64 v[26:27], v[36:37], 0, v[18:19]
	v_or_b32_e32 v18, 24, v34
	v_mov_b32_e32 v19, v3
	v_lshlrev_b64 v[18:19], 13, v[18:19]
	v_lshl_add_u64 v[28:29], v[36:37], 0, v[18:19]
	global_load_dwordx4 v[18:21], v[26:27], off nt
	global_load_dwordx4 v[22:25], v[28:29], off nt
	v_or_b32_e32 v26, 32, v34
	v_mov_b32_e32 v27, v3
	v_lshlrev_b64 v[26:27], 13, v[26:27]
	v_lshl_add_u64 v[38:39], v[36:37], 0, v[26:27]
	v_or_b32_e32 v26, 40, v34
	v_mov_b32_e32 v27, v3
	v_lshlrev_b64 v[26:27], 13, v[26:27]
	v_lshl_add_u64 v[40:41], v[36:37], 0, v[26:27]
	global_load_dwordx4 v[26:29], v[38:39], off nt
	global_load_dwordx4 v[30:33], v[40:41], off nt
	v_or_b32_e32 v38, 48, v34
	v_mov_b32_e32 v39, v3
	v_lshlrev_b64 v[38:39], 13, v[38:39]
	v_or_b32_e32 v34, 56, v34
	v_lshl_add_u64 v[42:43], v[36:37], 0, v[38:39]
	v_lshlrev_b64 v[34:35], 13, v[34:35]
	v_lshl_add_u64 v[44:45], v[36:37], 0, v[34:35]
	global_load_dwordx4 v[34:37], v[42:43], off nt
	global_load_dwordx4 v[38:41], v[44:45], off nt
	v_mul_u32_u24_e32 v5, 0x84, v8
	v_add3_u32 v5, s28, v2, v5
	v_add_u32_e32 v9, 0x420, v5
	s_waitcnt vmcnt(0)
	ds_write2_b32 v5, v10, v11 offset1:1
	ds_write2_b32 v5, v12, v13 offset0:2 offset1:3
	ds_write2_b32 v9, v14, v15 offset1:1
	v_add_u32_e32 v9, 0x428, v5
	ds_write2_b32 v9, v16, v17 offset1:1
	v_add_u32_e32 v9, 0x840, v5
	ds_write2_b32 v9, v18, v19 offset1:1
	v_add_u32_e32 v9, 0x848, v5
	ds_write2_b32 v9, v20, v21 offset1:1
	v_add_u32_e32 v9, 0xc60, v5
	ds_write2_b32 v9, v22, v23 offset1:1
	v_add_u32_e32 v9, 0xc68, v5
	ds_write2_b32 v9, v24, v25 offset1:1
	v_add_u32_e32 v9, 0x1080, v5
	ds_write2_b32 v9, v26, v27 offset1:1
	v_add_u32_e32 v9, 0x1088, v5
	ds_write2_b32 v9, v28, v29 offset1:1
	v_add_u32_e32 v9, 0x14a0, v5
	ds_write2_b32 v9, v30, v31 offset1:1
	v_add_u32_e32 v9, 0x14a8, v5
	ds_write2_b32 v9, v32, v33 offset1:1
	v_add_u32_e32 v9, 0x18c0, v5
	ds_write2_b32 v9, v34, v35 offset1:1
	v_add_u32_e32 v9, 0x18c8, v5
	s_lshl_b64 s[2:3], s[2:3], 1
	ds_write2_b32 v9, v36, v37 offset1:1
	v_add_u32_e32 v9, 0x1ce0, v5
	v_add_u32_e32 v5, 0x1ce8, v5
	s_add_u32 s2, s50, s2
	ds_write2_b32 v9, v38, v39 offset1:1
	ds_write2_b32 v5, v40, v41 offset1:1
	v_mul_u32_u24_e32 v9, 0x420, v7
	s_addc_u32 s3, s51, s3
	v_mov_b32_e32 v5, v3
	s_waitcnt lgkmcnt(0)
	v_lshl_add_u64 v[10:11], s[2:3], 0, v[4:5]
	v_add3_u32 v5, s28, v9, v6
	ds_read2_b32 v[14:15], v5 offset0:33 offset1:41
	ds_read2_b32 v[16:17], v5 offset1:8
	ds_read2_b32 v[18:19], v5 offset0:66 offset1:74
	ds_read2_b32 v[20:21], v5 offset0:99 offset1:107
	ds_read2_b32 v[22:23], v5 offset0:132 offset1:140
	ds_read2_b32 v[24:25], v5 offset0:165 offset1:173
	ds_read2_b32 v[26:27], v5 offset0:198 offset1:206
	ds_read2_b32 v[28:29], v5 offset0:231 offset1:239
	s_mov_b64 s[2:3], 0x1c00000
	v_lshl_add_u64 v[30:31], v[10:11], 0, s[2:3]
	v_lshlrev_b32_e32 v32, 11, v1
	v_mov_b32_e32 v33, v3
	s_waitcnt lgkmcnt(6)
	v_cvt_pk_bf16_f32 v10, v16, v14
	s_waitcnt lgkmcnt(4)
	v_cvt_pk_bf16_f32 v11, v18, v20
	s_waitcnt lgkmcnt(2)
	v_cvt_pk_bf16_f32 v12, v22, v24
	s_waitcnt lgkmcnt(0)
	v_cvt_pk_bf16_f32 v13, v26, v28
	v_lshl_add_u64 v[34:35], v[30:31], 0, v[32:33]
	global_store_dwordx4 v[34:35], v[10:13], off sc0 sc1
	v_or_b32_e32 v14, 0x4000, v32
	s_mov_b64 s[6:7], 0
	v_cvt_pk_bf16_f32 v10, v17, v15
	v_cvt_pk_bf16_f32 v11, v19, v21
	v_cvt_pk_bf16_f32 v12, v23, v25
	v_cvt_pk_bf16_f32 v13, v27, v29
	ds_read2_b32 v[16:17], v5 offset0:49 offset1:57
	ds_read2_b32 v[18:19], v5 offset0:16 offset1:24
	ds_read2_b32 v[20:21], v5 offset0:82 offset1:90
	ds_read2_b32 v[22:23], v5 offset0:115 offset1:123
	ds_read2_b32 v[24:25], v5 offset0:148 offset1:156
	ds_read2_b32 v[26:27], v5 offset0:181 offset1:189
	ds_read2_b32 v[28:29], v5 offset0:214 offset1:222
	ds_read2_b32 v[34:35], v5 offset0:247 offset1:255
	v_mov_b32_e32 v15, v3
	v_lshl_add_u64 v[14:15], v[30:31], 0, v[14:15]
	global_store_dwordx4 v[14:15], v[10:13], off sc0 sc1
	v_or_b32_e32 v14, 0x8000, v32
	v_mov_b32_e32 v15, v3
	s_waitcnt lgkmcnt(6)
	v_cvt_pk_bf16_f32 v10, v18, v16
	s_waitcnt lgkmcnt(4)
	v_cvt_pk_bf16_f32 v11, v20, v22
	s_waitcnt lgkmcnt(2)
	v_cvt_pk_bf16_f32 v12, v24, v26
	s_waitcnt lgkmcnt(0)
	v_cvt_pk_bf16_f32 v13, v28, v34
	v_lshl_add_u64 v[14:15], v[30:31], 0, v[14:15]
	global_store_dwordx4 v[14:15], v[10:13], off sc0 sc1
	v_or_b32_e32 v14, 0xc000, v32
	v_mov_b32_e32 v15, v3
	v_cvt_pk_bf16_f32 v10, v19, v17
	v_cvt_pk_bf16_f32 v11, v21, v23
	v_cvt_pk_bf16_f32 v12, v25, v27
	v_cvt_pk_bf16_f32 v13, v29, v35
	v_lshl_add_u64 v[14:15], v[30:31], 0, v[14:15]
	global_store_dwordx4 v[14:15], v[10:13], off sc0 sc1
	s_waitcnt lgkmcnt(0)
; #define LAS __attribute__((address_space(3)))
; __device__ __forceinline__ f32x4 ld_nt(const float* p) { return __builtin_nontemporal_load((const f32x4*)p); }
; __device__ __forceinline__ void transpose_item(const float* W, int K, int pitch, int ncols, f16* WT, LAS float* scr, int item, int lane) {
;     const int nblk = ncols / 32, kb = item / nblk, nb = item % nblk, k0 = 64 * kb, n0 = 32 * nb;
;     const int kr = lane >> 3, nq = (lane & 7) * 4;
;     f32x4 v[8];
; #pragma unroll
;     for (int i = 0; i < 8; ++i) v[i] = ld_nt(W + (size_t)(k0 + kr + 8 * i) * pitch + n0 + nq);
;     __builtin_amdgcn_sched_barrier(0);
; #pragma unroll
;     for (int i = 0; i < 8; ++i) { LAS float* sp = scr + (kr + 8 * i) * 33 + nq; sp[0] = v[i][0]; sp[1] = v[i][1]; sp[2] = v[i][2]; sp[3] = v[i][3]; }
;     asm volatile("s_waitcnt lgkmcnt(0)" ::: "memory");
;     const int c = lane & 7;
; #pragma unroll
;     for (int j = 0; j < 4; ++j) { const int n = (lane >> 3) + 8 * j; const LAS float* sp = scr + (8 * c) * 33 + n;
;         u32x4 o; o.x = pk_f16(sp[0 * 33], sp[1 * 33]); o.y = pk_f16(sp[2 * 33], sp[3 * 33]); o.z = pk_f16(sp[4 * 33], sp[5 * 33]); o.w = pk_f16(sp[6 * 33], sp[7 * 33]);
;         *(u32x4*)(WT + (size_t)(n0 + n) * K + k0 + 8 * c) = o; }
;     asm volatile("s_waitcnt lgkmcnt(0)" ::: "memory");
; }
; __device__ __forceinline__ void transpose_dispatch(int it, const float* in_w, const float* out_w, const float* glu_w, const float* pool_w, unsigned char* ws, LAS float* scr, int lane) {
;     ...
;     if (it < TI_OUT) { transpose_item(out_w, D, D, D, (f16*)(ws + WS_WOUT), scr, it, lane); return; } it -= TI_OUT;
.LBB0_219:
	s_andn2_b64 vcc, exec, s[6:7]
	s_cbranch_vccnz .LBB0_221
	s_add_i32 s2, s8, 0xf180
	s_and_b32 s6, s2, 0xffc0
	s_lshl_b32 s2, s9, 2
	s_add_u32 s2, s44, s2
	v_or_b32_e32 v5, s6, v8
	s_addc_u32 s3, s45, 0
	v_mov_b32_e32 v3, 0
	v_lshl_add_u64 v[10:11], s[2:3], 0, v[2:3]
	v_lshlrev_b32_e32 v12, 13, v5
	v_mov_b32_e32 v13, v3
	v_lshl_add_u64 v[34:35], v[10:11], 0, v[12:13]
	v_add_co_u32_e32 v18, vcc, 0x10000, v34
	s_nop 1
	v_addc_co_u32_e32 v19, vcc, 0, v35, vcc
	v_add_co_u32_e32 v26, vcc, 0x20000, v34
	global_load_dwordx4 v[10:13], v[34:35], off nt
	global_load_dwordx4 v[14:17], v[18:19], off nt
	v_addc_co_u32_e32 v27, vcc, 0, v35, vcc
	v_add_co_u32_e32 v28, vcc, 0x30000, v34
	s_nop 1
	v_addc_co_u32_e32 v29, vcc, 0, v35, vcc
	v_add_co_u32_e32 v36, vcc, 0x40000, v34
	global_load_dwordx4 v[18:21], v[26:27], off nt
	global_load_dwordx4 v[22:25], v[28:29], off nt
	v_addc_co_u32_e32 v37, vcc, 0, v35, vcc
	v_add_co_u32_e32 v38, vcc, 0x50000, v34
	s_nop 1
	v_addc_co_u32_e32 v39, vcc, 0, v35, vcc
	v_add_co_u32_e32 v42, vcc, 0x60000, v34
	global_load_dwordx4 v[26:29], v[36:37], off nt
	global_load_dwordx4 v[30:33], v[38:39], off nt
	v_addc_co_u32_e32 v43, vcc, 0, v35, vcc
	v_add_co_u32_e32 v44, vcc, 0x70000, v34
	s_nop 1
	v_addc_co_u32_e32 v45, vcc, 0, v35, vcc
	global_load_dwordx4 v[34:37], v[42:43], off nt
	global_load_dwordx4 v[38:41], v[44:45], off nt
	v_mul_u32_u24_e32 v5, 0x84, v8
	v_add3_u32 v2, s28, v2, v5
	v_add_u32_e32 v5, 0x420, v2
	s_waitcnt vmcnt(0)
	ds_write2_b32 v2, v10, v11 offset1:1
	ds_write2_b32 v2, v12, v13 offset0:2 offset1:3
	ds_write2_b32 v5, v14, v15 offset1:1
	v_add_u32_e32 v5, 0x428, v2
	ds_write2_b32 v5, v16, v17 offset1:1
	v_add_u32_e32 v5, 0x840, v2
	ds_write2_b32 v5, v18, v19 offset1:1
	v_add_u32_e32 v5, 0x848, v2
	ds_write2_b32 v5, v20, v21 offset1:1
	v_add_u32_e32 v5, 0xc60, v2
	ds_write2_b32 v5, v22, v23 offset1:1
	v_add_u32_e32 v5, 0xc68, v2
	ds_write2_b32 v5, v24, v25 offset1:1
	v_add_u32_e32 v5, 0x1080, v2
	ds_write2_b32 v5, v26, v27 offset1:1
	v_add_u32_e32 v5, 0x1088, v2
	ds_write2_b32 v5, v28, v29 offset1:1
	v_add_u32_e32 v5, 0x14a0, v2
	ds_write2_b32 v5, v30, v31 offset1:1
	v_add_u32_e32 v5, 0x14a8, v2
	ds_write2_b32 v5, v32, v33 offset1:1
	v_add_u32_e32 v5, 0x18c0, v2
	ds_write2_b32 v5, v34, v35 offset1:1
	v_add_u32_e32 v5, 0x18c8, v2
	ds_write2_b32 v5, v36, v37 offset1:1
	v_add_u32_e32 v5, 0x1ce0, v2
	v_add_u32_e32 v2, 0x1ce8, v2
	ds_write2_b32 v5, v38, v39 offset1:1
	ds_write2_b32 v2, v40, v41 offset1:1
	v_mul_u32_u24_e32 v2, 0x420, v7
	s_waitcnt lgkmcnt(0)
	v_add3_u32 v28, s28, v2, v6
	s_lshl_b32 s2, s6, 1
	ds_read2_b32 v[8:9], v28 offset0:33 offset1:41
	ds_read2_b32 v[10:11], v28 offset1:8
	ds_read2_b32 v[12:13], v28 offset0:66 offset1:74
	ds_read2_b32 v[14:15], v28 offset0:99 offset1:107
	ds_read2_b32 v[16:17], v28 offset0:132 offset1:140
	ds_read2_b32 v[18:19], v28 offset0:165 offset1:173
	ds_read2_b32 v[20:21], v28 offset0:198 offset1:206
	ds_read2_b32 v[22:23], v28 offset0:231 offset1:239
	s_add_u32 s2, s50, s2
	s_addc_u32 s3, s51, 0
	v_mov_b32_e32 v5, v3
	v_lshl_add_u64 v[4:5], s[2:3], 0, v[4:5]
	s_mov_b64 s[2:3], 0x1400000
	v_lshl_add_u64 v[24:25], v[4:5], 0, s[2:3]
	v_lshlrev_b32_e32 v2, 12, v1
	s_waitcnt lgkmcnt(6)
	v_cvt_pk_bf16_f32 v4, v10, v8
	s_waitcnt lgkmcnt(4)
	v_cvt_pk_bf16_f32 v5, v12, v14
	s_waitcnt lgkmcnt(2)
	v_cvt_pk_bf16_f32 v6, v16, v18
	s_waitcnt lgkmcnt(0)
	v_cvt_pk_bf16_f32 v7, v20, v22
	v_lshl_add_u64 v[26:27], v[24:25], 0, v[2:3]
	global_store_dwordx4 v[26:27], v[4:7], off sc0 sc1
	v_or_b32_e32 v8, 0x8000, v2
	s_nop 0
	v_cvt_pk_bf16_f32 v4, v11, v9
	v_cvt_pk_bf16_f32 v5, v13, v15
	v_cvt_pk_bf16_f32 v6, v17, v19
	v_cvt_pk_bf16_f32 v7, v21, v23
	ds_read2_b32 v[10:11], v28 offset0:49 offset1:57
	ds_read2_b32 v[12:13], v28 offset0:16 offset1:24
	ds_read2_b32 v[14:15], v28 offset0:82 offset1:90
	ds_read2_b32 v[16:17], v28 offset0:115 offset1:123
	ds_read2_b32 v[18:19], v28 offset0:148 offset1:156
	ds_read2_b32 v[20:21], v28 offset0:181 offset1:189
	ds_read2_b32 v[22:23], v28 offset0:214 offset1:222
	ds_read2_b32 v[26:27], v28 offset0:247 offset1:255
	v_mov_b32_e32 v9, v3
	v_lshl_add_u64 v[8:9], v[24:25], 0, v[8:9]
	global_store_dwordx4 v[8:9], v[4:7], off sc0 sc1
	v_or_b32_e32 v8, 0x10000, v2
	v_mov_b32_e32 v9, v3
	s_waitcnt lgkmcnt(6)
	v_cvt_pk_bf16_f32 v4, v12, v10
	s_waitcnt lgkmcnt(4)
	v_cvt_pk_bf16_f32 v5, v14, v16
	s_waitcnt lgkmcnt(2)
	v_cvt_pk_bf16_f32 v6, v18, v20
	s_waitcnt lgkmcnt(0)
	v_cvt_pk_bf16_f32 v7, v22, v26
	v_lshl_add_u64 v[8:9], v[24:25], 0, v[8:9]
	v_or_b32_e32 v2, 0x18000, v2
	global_store_dwordx4 v[8:9], v[4:7], off sc0 sc1
	v_lshl_add_u64 v[2:3], v[24:25], 0, v[2:3]
	s_nop 0
	v_cvt_pk_bf16_f32 v4, v13, v11
	v_cvt_pk_bf16_f32 v5, v15, v17
	v_cvt_pk_bf16_f32 v6, v19, v21
	v_cvt_pk_bf16_f32 v7, v23, v27
	global_store_dwordx4 v[2:3], v[4:7], off sc0 sc1
	s_waitcnt lgkmcnt(0)

; #define LAS __attribute__((address_space(3)))
; __device__ __forceinline__ f32x4 ld_nt(const float* p) { return __builtin_nontemporal_load((const f32x4*)p); }
; __device__ __forceinline__ void transpose_item(const float* W, int K, int pitch, int ncols, f16* WT, LAS float* scr, int item, int lane) {
;     const int nblk = ncols / 32, kb = item / nblk, nb = item % nblk, k0 = 64 * kb, n0 = 32 * nb;
;     const int kr = lane >> 3, nq = (lane & 7) * 4;
;     f32x4 v[8];
; #pragma unroll
;     for (int i = 0; i < 8; ++i) v[i] = ld_nt(W + (size_t)(k0 + kr + 8 * i) * pitch + n0 + nq);
;     __builtin_amdgcn_sched_barrier(0);
; #pragma unroll
;     for (int i = 0; i < 8; ++i) { LAS float* sp = scr + (kr + 8 * i) * 33 + nq; sp[0] = v[i][0]; sp[1] = v[i][1]; sp[2] = v[i][2]; sp[3] = v[i][3]; }
;     asm volatile("s_waitcnt lgkmcnt(0)" ::: "memory");
;     const int c = lane & 7;
; #pragma unroll
;     for (int j = 0; j < 4; ++j) { const int n = (lane >> 3) + 8 * j; const LAS float* sp = scr + (8 * c) * 33 + n;
;         u32x4 o; o.x = pk_f16(sp[0 * 33], sp[1 * 33]); o.y = pk_f16(sp[2 * 33], sp[3 * 33]); o.z = pk_f16(sp[4 * 33], sp[5 * 33]); o.w = pk_f16(sp[6 * 33], sp[7 * 33]);
;         *(u32x4*)(WT + (size_t)(n0 + n) * K + k0 + 8 * c) = o; }
;     asm volatile("s_waitcnt lgkmcnt(0)" ::: "memory");
; }
; __device__ __forceinline__ void transpose_dispatch(int it, const float* in_w, const float* out_w, const float* glu_w, const float* pool_w, unsigned char* ws, LAS float* scr, int lane) {
;     ...
;     if (it < TI_IN) { transpose_item(in_w + 1024, D, 4096, 3072, (f16*)(ws + WS_WIN) + (size_t)1024 * D, scr, it, lane); return; } it -= TI_IN;
.LBB0_222:
	s_andn2_b64 vcc, exec, s[2:3]
	s_cbranch_vccnz .LBB0_224
	s_add_i32 s2, s8, 0xfd80
	s_and_b32 s3, s2, 0xffff
	s_mul_i32 s3, s3, 0xaaab
	s_lshr_b32 s6, s3, 16
	s_lshr_b32 s3, s3, 22
	s_mulk_i32 s3, 0x60
	s_sub_i32 s2, s2, s3
	s_lshl_b32 s2, s2, 5
	v_readlane_b32 s56, v254, 2
	s_and_b32 s7, s2, 0xffe0
	v_readlane_b32 s70, v254, 16
	v_readlane_b32 s71, v254, 17
	s_and_b32 s6, s6, 0xffc0
	s_lshl_b32 s2, s7, 2
	s_mov_b64 s[26:27], s[70:71]
	v_lshrrev_b32_e32 v1, 3, v212
	v_and_b32_e32 v40, 7, v0
	s_add_u32 s2, s26, s2
	v_or_b32_e32 v4, s6, v1
	s_addc_u32 s3, s27, 0
	v_lshlrev_b32_e32 v34, 4, v40
	v_mov_b32_e32 v35, 0
	v_lshl_add_u64 v[2:3], s[2:3], 0, v[34:35]
	v_lshlrev_b32_e32 v4, 14, v4
	v_mov_b32_e32 v5, v35
	v_lshl_add_u64 v[26:27], v[2:3], 0, v[4:5]
	s_movk_i32 s2, 0x1000
	v_add_co_u32_e32 v10, vcc, s2, v26
	s_mov_b32 s2, 0x21000
	s_nop 0
	v_addc_co_u32_e32 v11, vcc, 0, v27, vcc
	v_add_co_u32_e32 v12, vcc, s2, v26
	s_mov_b32 s2, 0x41000
	s_nop 0
	v_addc_co_u32_e32 v13, vcc, 0, v27, vcc
	v_add_co_u32_e32 v18, vcc, s2, v26
	s_mov_b32 s2, 0x61000
	s_nop 0
	v_addc_co_u32_e32 v19, vcc, 0, v27, vcc
	v_add_co_u32_e32 v20, vcc, s2, v26
	s_mov_b32 s2, 0x81000
	s_nop 0
	v_addc_co_u32_e32 v21, vcc, 0, v27, vcc
	v_add_co_u32_e32 v28, vcc, s2, v26
	s_mov_b32 s2, 0xa1000
	s_nop 0
	v_addc_co_u32_e32 v29, vcc, 0, v27, vcc
	v_add_co_u32_e32 v30, vcc, s2, v26
	s_mov_b32 s2, 0xc1000
	s_nop 0
	v_addc_co_u32_e32 v31, vcc, 0, v27, vcc
	v_add_co_u32_e32 v36, vcc, s2, v26
	s_mov_b32 s2, 0xe1000
	s_nop 0
	v_addc_co_u32_e32 v37, vcc, 0, v27, vcc
	v_add_co_u32_e32 v38, vcc, s2, v26
	global_load_dwordx4 v[2:5], v[10:11], off nt
	global_load_dwordx4 v[6:9], v[12:13], off nt
	s_nop 0
	global_load_dwordx4 v[10:13], v[18:19], off nt
	global_load_dwordx4 v[14:17], v[20:21], off nt
	s_nop 0
	global_load_dwordx4 v[18:21], v[28:29], off nt
	global_load_dwordx4 v[22:25], v[30:31], off nt
	v_addc_co_u32_e32 v39, vcc, 0, v27, vcc
	global_load_dwordx4 v[26:29], v[36:37], off nt
	global_load_dwordx4 v[30:33], v[38:39], off nt
	v_readlane_b32 s57, v254, 3
	v_readlane_b32 s58, v254, 4
	v_readlane_b32 s59, v254, 5
	v_readlane_b32 s60, v254, 6
	v_readlane_b32 s61, v254, 7
	v_readlane_b32 s62, v254, 8
	v_readlane_b32 s63, v254, 9
	v_readlane_b32 s64, v254, 10
	v_readlane_b32 s65, v254, 11
	v_readlane_b32 s66, v254, 12
	v_readlane_b32 s67, v254, 13
	v_readlane_b32 s68, v254, 14
	v_readlane_b32 s69, v254, 15
	v_mul_u32_u24_e32 v36, 0x84, v1
	v_add3_u32 v36, s28, v34, v36
	s_waitcnt vmcnt(0)
	ds_write2_b32 v36, v2, v3 offset1:1
	ds_write2_b32 v36, v4, v5 offset0:2 offset1:3
	v_add_u32_e32 v2, 0x420, v36
	ds_write2_b32 v2, v6, v7 offset1:1
	v_add_u32_e32 v2, 0x428, v36
	ds_write2_b32 v2, v8, v9 offset1:1
	v_add_u32_e32 v2, 0x840, v36
	ds_write2_b32 v2, v10, v11 offset1:1
	v_add_u32_e32 v2, 0x848, v36
	ds_write2_b32 v2, v12, v13 offset1:1
	v_add_u32_e32 v2, 0xc60, v36
	ds_write2_b32 v2, v14, v15 offset1:1
	v_add_u32_e32 v2, 0xc68, v36
	ds_write2_b32 v2, v16, v17 offset1:1
	v_add_u32_e32 v2, 0x1080, v36
	ds_write2_b32 v2, v18, v19 offset1:1
	v_add_u32_e32 v2, 0x1088, v36
	ds_write2_b32 v2, v20, v21 offset1:1
	v_add_u32_e32 v2, 0x14a0, v36
	ds_write2_b32 v2, v22, v23 offset1:1
	v_add_u32_e32 v2, 0x14a8, v36
	ds_write2_b32 v2, v24, v25 offset1:1
	v_add_u32_e32 v2, 0x18c0, v36
	ds_write2_b32 v2, v26, v27 offset1:1
	v_add_u32_e32 v2, 0x18c8, v36
	ds_write2_b32 v2, v28, v29 offset1:1
	v_add_u32_e32 v2, 0x1ce0, v36
	ds_write2_b32 v2, v30, v31 offset1:1
	v_add_u32_e32 v2, 0x1ce8, v36
	ds_write2_b32 v2, v32, v33 offset1:1
	v_mul_u32_u24_e32 v4, 0x420, v40
	v_lshlrev_b32_e32 v5, 2, v1
	s_waitcnt lgkmcnt(0)
	v_add3_u32 v26, s28, v4, v5
	s_lshl_b32 s2, s6, 1
	ds_read2_b32 v[6:7], v26 offset0:33 offset1:41
	ds_read2_b32 v[8:9], v26 offset1:8
	ds_read2_b32 v[10:11], v26 offset0:66 offset1:74
	ds_read2_b32 v[12:13], v26 offset0:99 offset1:107
	ds_read2_b32 v[14:15], v26 offset0:132 offset1:140
	ds_read2_b32 v[16:17], v26 offset0:165 offset1:173
	ds_read2_b32 v[18:19], v26 offset0:198 offset1:206
	ds_read2_b32 v[20:21], v26 offset0:231 offset1:239
	s_add_u32 s2, s50, s2
	s_addc_u32 s3, s51, 0
	v_lshl_add_u64 v[2:3], s[2:3], 0, v[34:35]
	s_mov_b64 s[2:3], 0x800000
	v_or_b32_e32 v1, s7, v1
	v_lshl_add_u64 v[22:23], v[2:3], 0, s[2:3]
	v_lshlrev_b32_e32 v34, 12, v1
	s_waitcnt lgkmcnt(6)
	v_cvt_pk_bf16_f32 v2, v8, v6
	s_waitcnt lgkmcnt(4)
	v_cvt_pk_bf16_f32 v3, v10, v12
	s_waitcnt lgkmcnt(2)
	v_cvt_pk_bf16_f32 v4, v14, v16
	s_waitcnt lgkmcnt(0)
	v_cvt_pk_bf16_f32 v5, v18, v20
	v_lshl_add_u64 v[24:25], v[22:23], 0, v[34:35]
	global_store_dwordx4 v[24:25], v[2:5], off sc0 sc1
	v_or_b32_e32 v6, 0x8000, v34
	s_nop 0
	v_cvt_pk_bf16_f32 v2, v9, v7
	v_cvt_pk_bf16_f32 v3, v11, v13
	v_cvt_pk_bf16_f32 v4, v15, v17
	v_cvt_pk_bf16_f32 v5, v19, v21
	ds_read2_b32 v[8:9], v26 offset0:49 offset1:57
	ds_read2_b32 v[10:11], v26 offset0:16 offset1:24
	ds_read2_b32 v[12:13], v26 offset0:82 offset1:90
	ds_read2_b32 v[14:15], v26 offset0:115 offset1:123
	ds_read2_b32 v[16:17], v26 offset0:148 offset1:156
	ds_read2_b32 v[18:19], v26 offset0:181 offset1:189
	ds_read2_b32 v[20:21], v26 offset0:214 offset1:222
	ds_read2_b32 v[24:25], v26 offset0:247 offset1:255
	v_mov_b32_e32 v7, v35
	v_lshl_add_u64 v[6:7], v[22:23], 0, v[6:7]
	global_store_dwordx4 v[6:7], v[2:5], off sc0 sc1
	v_or_b32_e32 v6, 0x10000, v34
	v_mov_b32_e32 v7, v35
	s_waitcnt lgkmcnt(6)
	v_cvt_pk_bf16_f32 v2, v10, v8
	s_waitcnt lgkmcnt(4)
	v_cvt_pk_bf16_f32 v3, v12, v14
	s_waitcnt lgkmcnt(2)
	v_cvt_pk_bf16_f32 v4, v16, v18
	s_waitcnt lgkmcnt(0)
	v_cvt_pk_bf16_f32 v5, v20, v24
	v_lshl_add_u64 v[6:7], v[22:23], 0, v[6:7]
	v_or_b32_e32 v34, 0x18000, v34
	global_store_dwordx4 v[6:7], v[2:5], off sc0 sc1
	v_lshl_add_u64 v[6:7], v[22:23], 0, v[34:35]
	s_nop 0
	v_cvt_pk_bf16_f32 v2, v11, v9
	v_cvt_pk_bf16_f32 v3, v13, v15
	v_cvt_pk_bf16_f32 v4, v17, v19
	v_cvt_pk_bf16_f32 v5, v21, v25
	global_store_dwordx4 v[6:7], v[2:5], off sc0 sc1
	s_waitcnt lgkmcnt(0)

; __device__ __forceinline__ f32x4 ld_nt(const float* p) { return __builtin_nontemporal_load((const f32x4*)p); }
; __device__ __forceinline__ u32x4 pack8(const f32x4 v0, const f32x4 v1) { u32x4 w; w.x = pk_f16(v0[0], v0[1]); w.y = pk_f16(v0[2], v0[3]); w.z = pk_f16(v1[0], v1[1]); w.w = pk_f16(v1[2], v1[3]); return w; }
; __device__ __forceinline__ void convert_item(const float* W, f16* O, int item, int lane) {
;     f32x4 v[4][4];
; #pragma unroll
;     for (int r = 0; r < 4; ++r)
; #pragma unroll
;         for (int q = 0; q < 4; ++q) v[r][q] = ld_nt(W + (size_t)(item * 4 + r) * 4096 + lane * 16 + q * 4);
;     __builtin_amdgcn_sched_barrier(0);
; #pragma unroll
;     for (int r = 0; r < 4; ++r) { f16* op = O + (size_t)(item * 4 + r) * 1024 + lane * 16; *(u32x4*)op = pack8(v[r][0], v[r][1]); *(u32x4*)(op + 8) = pack8(v[r][2], v[r][3]); }
; }
; __device__ __forceinline__ void transpose_dispatch(int it, const float* in_w, const float* out_w, const float* glu_w, const float* pool_w, unsigned char* ws, LAS float* scr, int lane) {
;     ...
;     if (it < TI_RAW) { convert_item(in_w, (f16*)(ws + WS_WRAW), it, lane); return; } it -= TI_RAW;
.LBB0_225:
	s_andn2_b64 vcc, exec, s[2:3]
	s_cbranch_vccnz .LBB0_227
	v_readlane_b32 s56, v254, 2
	s_add_i32 s9, s8, 0xffffff80
	v_lshlrev_b32_e32 v66, 6, v212
	v_mov_b32_e32 v67, 0
	v_readlane_b32 s70, v254, 16
	v_readlane_b32 s71, v254, 17
	s_lshl_b32 s2, s9, 14
	s_mov_b32 s3, 0
	v_lshl_add_u64 v[2:3], s[70:71], 0, v[66:67]
	v_lshl_add_u64 v[50:51], s[2:3], 2, v[2:3]
	v_add_co_u32_e32 v36, vcc, 0x4000, v50
	s_mov_b64 s[6:7], 0x4000
	s_nop 0
	v_addc_co_u32_e32 v37, vcc, 0, v51, vcc
	v_add_co_u32_e32 v54, vcc, 0x8000, v50
	v_lshl_add_u64 v[34:35], v[50:51], 0, s[6:7]
	s_nop 0
	v_addc_co_u32_e32 v55, vcc, 0, v51, vcc
	s_mov_b64 s[6:7], 0x8000
	v_add_co_u32_e32 v70, vcc, 0xc000, v50
	v_lshl_add_u64 v[52:53], v[50:51], 0, s[6:7]
	s_mov_b64 s[6:7], 0xc000
	v_addc_co_u32_e32 v71, vcc, 0, v51, vcc
	global_load_dwordx4 v[2:5], v[50:51], off offset:48 nt
	global_load_dwordx4 v[6:9], v[50:51], off offset:32 nt
	global_load_dwordx4 v[10:13], v[50:51], off offset:16 nt
	global_load_dwordx4 v[14:17], v[50:51], off nt
	global_load_dwordx4 v[18:21], v[36:37], off nt
	global_load_dwordx4 v[22:25], v[34:35], off offset:48 nt
	global_load_dwordx4 v[26:29], v[34:35], off offset:32 nt
	global_load_dwordx4 v[30:33], v[34:35], off offset:16 nt
	s_nop 0
	global_load_dwordx4 v[34:37], v[54:55], off nt
	global_load_dwordx4 v[38:41], v[52:53], off offset:48 nt
	global_load_dwordx4 v[42:45], v[52:53], off offset:32 nt
	global_load_dwordx4 v[46:49], v[52:53], off offset:16 nt
	v_lshl_add_u64 v[68:69], v[50:51], 0, s[6:7]
	global_load_dwordx4 v[50:53], v[70:71], off nt
	global_load_dwordx4 v[54:57], v[68:69], off offset:48 nt
	global_load_dwordx4 v[58:61], v[68:69], off offset:32 nt
	global_load_dwordx4 v[62:65], v[68:69], off offset:16 nt
	v_readlane_b32 s57, v254, 3
	v_readlane_b32 s58, v254, 4
	v_readlane_b32 s59, v254, 5
	v_readlane_b32 s60, v254, 6
	v_readlane_b32 s61, v254, 7
	v_readlane_b32 s62, v254, 8
	v_readlane_b32 s63, v254, 9
	v_readlane_b32 s64, v254, 10
	v_readlane_b32 s65, v254, 11
	v_readlane_b32 s66, v254, 12
	v_readlane_b32 s67, v254, 13
	v_readlane_b32 s68, v254, 14
	v_readlane_b32 s69, v254, 15
	v_lshlrev_b32_e32 v66, 5, v212
	v_lshl_add_u64 v[66:67], s[4:5], 0, v[66:67]
	s_lshl_b32 s2, s9, 13
	v_lshl_add_u64 v[66:67], v[66:67], 0, s[2:3]
	s_waitcnt vmcnt(0)
	v_cvt_pk_bf16_f32 v6, v6, v7
	v_cvt_pk_bf16_f32 v7, v8, v9
	v_cvt_pk_bf16_f32 v8, v2, v3
	v_cvt_pk_bf16_f32 v9, v4, v5
	v_cvt_pk_bf16_f32 v2, v18, v19
	v_cvt_pk_bf16_f32 v3, v20, v21
	v_cvt_pk_bf16_f32 v4, v30, v31
	v_cvt_pk_bf16_f32 v5, v32, v33
	s_movk_i32 s2, 0x1000
	global_store_dwordx4 v[66:67], v[6:9], off offset:16 sc0 sc1
	global_store_dwordx4 v[66:67], v[2:5], off offset:2048 sc0 sc1
	v_cvt_pk_bf16_f32 v14, v14, v15
	v_add_co_u32_e32 v6, vcc, s2, v66
	v_cvt_pk_bf16_f32 v2, v26, v27
	v_cvt_pk_bf16_f32 v3, v28, v29
	v_cvt_pk_bf16_f32 v4, v22, v23
	v_cvt_pk_bf16_f32 v5, v24, v25
	global_store_dwordx4 v[66:67], v[2:5], off offset:2064 sc0 sc1
	v_addc_co_u32_e32 v7, vcc, 0, v67, vcc
	s_nop 0
	v_cvt_pk_bf16_f32 v2, v34, v35
	v_cvt_pk_bf16_f32 v3, v36, v37
	v_cvt_pk_bf16_f32 v4, v46, v47
	v_cvt_pk_bf16_f32 v5, v48, v49
	global_store_dwordx4 v[6:7], v[2:5], off sc0 sc1
	v_cvt_pk_bf16_f32 v15, v16, v17
	v_cvt_pk_bf16_f32 v16, v10, v11
	v_cvt_pk_bf16_f32 v2, v42, v43
	v_cvt_pk_bf16_f32 v3, v44, v45
	v_cvt_pk_bf16_f32 v4, v38, v39
	v_cvt_pk_bf16_f32 v5, v40, v41
	global_store_dwordx4 v[6:7], v[2:5], off offset:16 sc0 sc1
	v_cvt_pk_bf16_f32 v17, v12, v13
	global_store_dwordx4 v[66:67], v[14:17], off sc0 sc1
	v_cvt_pk_bf16_f32 v2, v50, v51
	v_cvt_pk_bf16_f32 v3, v52, v53
	v_cvt_pk_bf16_f32 v4, v62, v63
	v_cvt_pk_bf16_f32 v5, v64, v65
	global_store_dwordx4 v[6:7], v[2:5], off offset:2048 sc0 sc1
	s_nop 1
	v_cvt_pk_bf16_f32 v2, v58, v59
	v_cvt_pk_bf16_f32 v3, v60, v61
	v_cvt_pk_bf16_f32 v4, v54, v55
	v_cvt_pk_bf16_f32 v5, v56, v57
	global_store_dwordx4 v[6:7], v[2:5], off offset:2064 sc0 sc1

; #define LAS __attribute__((address_space(3)))
; __device__ __forceinline__ f32x4 ld_nt(const float* p) { return __builtin_nontemporal_load((const f32x4*)p); }
; __device__ __forceinline__ void transpose_item(const float* W, int K, int pitch, int ncols, f16* WT, LAS float* scr, int item, int lane) {
;     const int nblk = ncols / 32, kb = item / nblk, nb = item % nblk, k0 = 64 * kb, n0 = 32 * nb;
;     const int kr = lane >> 3, nq = (lane & 7) * 4;
;     f32x4 v[8];
; #pragma unroll
;     for (int i = 0; i < 8; ++i) v[i] = ld_nt(W + (size_t)(k0 + kr + 8 * i) * pitch + n0 + nq);
;     __builtin_amdgcn_sched_barrier(0);
; #pragma unroll
;     for (int i = 0; i < 8; ++i) { LAS float* sp = scr + (kr + 8 * i) * 33 + nq; sp[0] = v[i][0]; sp[1] = v[i][1]; sp[2] = v[i][2]; sp[3] = v[i][3]; }
;     asm volatile("s_waitcnt lgkmcnt(0)" ::: "memory");
;     const int c = lane & 7;
; #pragma unroll
;     for (int j = 0; j < 4; ++j) { const int n = (lane >> 3) + 8 * j; const LAS float* sp = scr + (8 * c) * 33 + n;
;         u32x4 o; o.x = pk_f16(sp[0 * 33], sp[1 * 33]); o.y = pk_f16(sp[2 * 33], sp[3 * 33]); o.z = pk_f16(sp[4 * 33], sp[5 * 33]); o.w = pk_f16(sp[6 * 33], sp[7 * 33]);
;         *(u32x4*)(WT + (size_t)(n0 + n) * K + k0 + 8 * c) = o; }
;     asm volatile("s_waitcnt lgkmcnt(0)" ::: "memory");
; }
; __device__ __forceinline__ void transpose_dispatch(int it, const float* in_w, const float* out_w, const float* glu_w, const float* pool_w, unsigned char* ws, LAS float* scr, int lane) {
;     if (it < 4 * TI_POOL1) { const int pg = it / TI_POOL1; transpose_item(pool_w + pg * 65536, 256, 256, 256, (f16*)(ws + WS_WPOOL) + pg * 65536, scr, it % TI_POOL1, lane); return; } it -= 4 * TI_POOL1;
.LBB0_228:
	s_andn2_b64 vcc, exec, s[2:3]
	s_cbranch_vccnz .LBB0_230
	s_ashr_i32 s2, s8, 31
	s_lshr_b32 s2, s2, 27
	s_add_i32 s6, s8, s2
	s_lshl_b32 s2, s6, 11
	s_and_b32 s2, s2, 0xffff0000
	s_ashr_i32 s3, s2, 31
	s_lshl_b64 s[4:5], s[2:3], 2
	v_readlane_b32 s56, v254, 18
	v_readlane_b32 s57, v254, 19
	s_add_u32 s7, s56, s4
	s_addc_u32 s5, s57, s5
	s_lshl_b64 s[2:3], s[2:3], 1
	s_add_u32 s9, s0, s2
	s_addc_u32 s10, s1, s3
	s_and_b32 s0, s6, 0xffe0
	s_sub_i32 s0, s8, s0
	s_bfe_i32 s1, s0, 0x80000
	s_bfe_u32 s1, s1, 0x3000c
	s_add_i32 s1, s0, s1
	s_bfe_i32 s2, s1, 0x80000
	s_and_b32 s1, s1, 0xf8
	s_sub_i32 s0, s0, s1
	s_sext_i32_i16 s2, s2
	s_sext_i32_i8 s0, s0
	s_lshl_b32 s1, s2, 3
	s_lshl_b32 s2, s0, 5
	s_ashr_i32 s3, s2, 31
	s_and_b32 s4, s1, 0xffffffc0
	v_lshrrev_b32_e32 v1, 3, v212
	s_lshl_b64 s[0:1], s[2:3], 2
	v_and_b32_e32 v40, 7, v0
	v_or_b32_e32 v26, s4, v1
	s_add_u32 s0, s7, s0
	s_addc_u32 s1, s5, s1
	v_lshlrev_b32_e32 v34, 4, v40
	v_mov_b32_e32 v35, 0
	v_ashrrev_i32_e32 v27, 31, v26
	v_lshl_add_u64 v[28:29], s[0:1], 0, v[34:35]
	v_lshlrev_b64 v[2:3], 10, v[26:27]
	v_lshl_add_u64 v[10:11], v[28:29], 0, v[2:3]
	v_or_b32_e32 v2, 8, v26
	v_ashrrev_i32_e32 v3, 31, v2
	v_lshlrev_b64 v[2:3], 10, v[2:3]
	v_lshl_add_u64 v[12:13], v[28:29], 0, v[2:3]
	global_load_dwordx4 v[2:5], v[10:11], off nt
	global_load_dwordx4 v[6:9], v[12:13], off nt
	v_or_b32_e32 v10, 16, v26
	v_ashrrev_i32_e32 v11, 31, v10
	v_lshlrev_b64 v[10:11], 10, v[10:11]
	v_lshl_add_u64 v[18:19], v[28:29], 0, v[10:11]
	v_or_b32_e32 v10, 24, v26
	v_ashrrev_i32_e32 v11, 31, v10
	v_lshlrev_b64 v[10:11], 10, v[10:11]
	v_lshl_add_u64 v[20:21], v[28:29], 0, v[10:11]
	global_load_dwordx4 v[10:13], v[18:19], off nt
	global_load_dwordx4 v[14:17], v[20:21], off nt
	v_or_b32_e32 v18, 32, v26
	v_ashrrev_i32_e32 v19, 31, v18
	v_lshlrev_b64 v[18:19], 10, v[18:19]
	v_lshl_add_u64 v[30:31], v[28:29], 0, v[18:19]
	v_or_b32_e32 v18, 40, v26
	v_ashrrev_i32_e32 v19, 31, v18
	v_lshlrev_b64 v[18:19], 10, v[18:19]
	v_lshl_add_u64 v[32:33], v[28:29], 0, v[18:19]
	global_load_dwordx4 v[18:21], v[30:31], off nt
	global_load_dwordx4 v[22:25], v[32:33], off nt
	v_or_b32_e32 v30, 48, v26
	v_ashrrev_i32_e32 v31, 31, v30
	v_or_b32_e32 v26, 56, v26
	v_lshlrev_b64 v[30:31], 10, v[30:31]
	v_ashrrev_i32_e32 v27, 31, v26
	v_lshl_add_u64 v[36:37], v[28:29], 0, v[30:31]
	v_lshlrev_b64 v[26:27], 10, v[26:27]
	v_lshl_add_u64 v[38:39], v[28:29], 0, v[26:27]
	global_load_dwordx4 v[26:29], v[36:37], off nt
	global_load_dwordx4 v[30:33], v[38:39], off nt
	v_readlane_b32 s58, v254, 20
	v_readlane_b32 s59, v254, 21
	v_readlane_b32 s60, v254, 22
	v_readlane_b32 s61, v254, 23
	v_readlane_b32 s62, v254, 24
	v_readlane_b32 s63, v254, 25
	v_readlane_b32 s64, v254, 26
	v_readlane_b32 s65, v254, 27
	v_readlane_b32 s66, v254, 28
	v_readlane_b32 s67, v254, 29
	v_readlane_b32 s68, v254, 30
	v_readlane_b32 s69, v254, 31
	v_readlane_b32 s70, v254, 32
	v_readlane_b32 s71, v254, 33
	v_mul_u32_u24_e32 v36, 0x84, v1
	v_add3_u32 v36, s28, v34, v36
	s_waitcnt vmcnt(0)
	ds_write2_b32 v36, v2, v3 offset1:1
	ds_write2_b32 v36, v4, v5 offset0:2 offset1:3
	v_add_u32_e32 v2, 0x420, v36
	ds_write2_b32 v2, v6, v7 offset1:1
	v_add_u32_e32 v2, 0x428, v36
	ds_write2_b32 v2, v8, v9 offset1:1
	v_add_u32_e32 v2, 0x840, v36
	ds_write2_b32 v2, v10, v11 offset1:1
	v_add_u32_e32 v2, 0x848, v36
	ds_write2_b32 v2, v12, v13 offset1:1
	v_add_u32_e32 v2, 0xc60, v36
	ds_write2_b32 v2, v14, v15 offset1:1
	v_add_u32_e32 v2, 0xc68, v36
	ds_write2_b32 v2, v16, v17 offset1:1
	v_add_u32_e32 v2, 0x1080, v36
	ds_write2_b32 v2, v18, v19 offset1:1
	v_add_u32_e32 v2, 0x1088, v36
	ds_write2_b32 v2, v20, v21 offset1:1
	v_add_u32_e32 v2, 0x14a0, v36
	ds_write2_b32 v2, v22, v23 offset1:1
	v_add_u32_e32 v2, 0x14a8, v36
	ds_write2_b32 v2, v24, v25 offset1:1
	v_add_u32_e32 v2, 0x18c0, v36
	ds_write2_b32 v2, v26, v27 offset1:1
	v_add_u32_e32 v2, 0x18c8, v36
	ds_write2_b32 v2, v28, v29 offset1:1
	v_add_u32_e32 v2, 0x1ce0, v36
	ds_write2_b32 v2, v30, v31 offset1:1
	v_add_u32_e32 v2, 0x1ce8, v36
	ds_write2_b32 v2, v32, v33 offset1:1
	v_mul_u32_u24_e32 v2, 0x420, v40
	v_lshlrev_b32_e32 v3, 2, v1
	s_waitcnt lgkmcnt(0)
	v_add3_u32 v28, s28, v2, v3
	s_ashr_i32 s5, s4, 31
	ds_read2_b32 v[6:7], v28 offset0:33 offset1:41
	ds_read2_b32 v[8:9], v28 offset1:8
	ds_read2_b32 v[10:11], v28 offset0:66 offset1:74
	ds_read2_b32 v[12:13], v28 offset0:99 offset1:107
	ds_read2_b32 v[14:15], v28 offset0:132 offset1:140
	ds_read2_b32 v[16:17], v28 offset0:165 offset1:173
	ds_read2_b32 v[18:19], v28 offset0:198 offset1:206
	ds_read2_b32 v[20:21], v28 offset0:231 offset1:239
	s_lshl_b64 s[0:1], s[4:5], 1
	s_add_u32 s0, s9, s0
	v_or_b32_e32 v24, s2, v1
	s_addc_u32 s1, s10, s1
	v_ashrrev_i32_e32 v25, 31, v24
	v_lshl_add_u64 v[22:23], s[0:1], 0, v[34:35]
	v_lshlrev_b64 v[26:27], 9, v[24:25]
	s_waitcnt lgkmcnt(6)
	v_cvt_pk_bf16_f32 v2, v8, v6
	s_waitcnt lgkmcnt(4)
	v_cvt_pk_bf16_f32 v3, v10, v12
	s_waitcnt lgkmcnt(2)
	v_cvt_pk_bf16_f32 v4, v14, v16
	s_waitcnt lgkmcnt(0)
	v_cvt_pk_bf16_f32 v5, v18, v20
	v_lshl_add_u64 v[26:27], v[22:23], 0, v[26:27]
	v_or_b32_e32 v6, 8, v24
	global_store_dwordx4 v[26:27], v[2:5], off sc0 sc1
	s_nop 1
	v_cvt_pk_bf16_f32 v2, v9, v7
	v_ashrrev_i32_e32 v7, 31, v6
	v_cvt_pk_bf16_f32 v3, v11, v13
	v_cvt_pk_bf16_f32 v4, v15, v17
	v_cvt_pk_bf16_f32 v5, v19, v21
	v_lshlrev_b64 v[6:7], 9, v[6:7]
	ds_read2_b32 v[8:9], v28 offset0:49 offset1:57
	ds_read2_b32 v[10:11], v28 offset0:16 offset1:24
	ds_read2_b32 v[12:13], v28 offset0:82 offset1:90
	ds_read2_b32 v[14:15], v28 offset0:115 offset1:123
	ds_read2_b32 v[16:17], v28 offset0:148 offset1:156
	ds_read2_b32 v[18:19], v28 offset0:181 offset1:189
	ds_read2_b32 v[20:21], v28 offset0:214 offset1:222
	ds_read2_b32 v[26:27], v28 offset0:247 offset1:255
	v_lshl_add_u64 v[6:7], v[22:23], 0, v[6:7]
	global_store_dwordx4 v[6:7], v[2:5], off sc0 sc1
	v_or_b32_e32 v6, 16, v24
	v_ashrrev_i32_e32 v7, 31, v6
	v_lshlrev_b64 v[6:7], 9, v[6:7]
	s_waitcnt lgkmcnt(6)
	v_cvt_pk_bf16_f32 v2, v10, v8
	s_waitcnt lgkmcnt(4)
	v_cvt_pk_bf16_f32 v3, v12, v14
	s_waitcnt lgkmcnt(2)
	v_cvt_pk_bf16_f32 v4, v16, v18
	s_waitcnt lgkmcnt(0)
	v_cvt_pk_bf16_f32 v5, v20, v26
	v_lshl_add_u64 v[6:7], v[22:23], 0, v[6:7]
	global_store_dwordx4 v[6:7], v[2:5], off sc0 sc1
	v_or_b32_e32 v6, 24, v24
	v_ashrrev_i32_e32 v7, 31, v6
	v_lshlrev_b64 v[6:7], 9, v[6:7]
	v_cvt_pk_bf16_f32 v2, v11, v9
	v_cvt_pk_bf16_f32 v3, v13, v15
	v_cvt_pk_bf16_f32 v4, v17, v19
	v_cvt_pk_bf16_f32 v5, v21, v27
	v_lshl_add_u64 v[6:7], v[22:23], 0, v[6:7]
	global_store_dwordx4 v[6:7], v[2:5], off sc0 sc1
	s_waitcnt lgkmcnt(0)

; __device__ __forceinline__ float silu_f(float v) { return v * fast_sigmoid(v); }
; __device__ __forceinline__ u32x4 pack8(const f32x4 v0, const f32x4 v1) { u32x4 w; w.x = pk_f16(v0[0], v0[1]); w.y = pk_f16(v0[2], v0[3]); w.z = pk_f16(v1[0], v1[1]); w.w = pk_f16(v1[2], v1[3]); return w; }
;     __device__ __forceinline__ void operator()(AccRef acc, const Unit& u, int wr, int wc, int fr, int fq) const {
;     ...
;             for (int m = 0; m < 4; ++m) { const int row = row0 + ai * HALF + m * 16;
; #pragma unroll
;                 for (int bj = 0; bj < 2; ++bj) { const int col = col0 + bj * HALF; f32x4 v0 = acc[ai][bj][m][0], v1 = acc[ai][bj][m][1];
;                     if (u.pn < 4) { *(u32x4*)(upool + (size_t)row * PW + col) = pack8(v0, v1); }
;                     else if (u.pn < 8) { const int cs = col - PW, gg = cs >> 4, hh = cs & 15, lc = row >> 5, s = row & 31;
;                         *(u32x4*)(X + (size_t)gg * XGS + (size_t)lc * XK + 256 + s * 16 + hh) = pack8(v0, v1); }
;                     else {
; #pragma unroll
;                         for (int j = 0; j < 4; ++j) { v0[j] = silu_f(v0[j]); v1[j] = silu_f(v1[j]); }
;                         *(u32x4*)(zs + (size_t)row * D + (col - PW - SW)) = pack8(v0, v1); } } }
.LBB0_299:
	v_lshl_add_u32 v146, s4, 8, v154
	s_cmp_gt_i32 s36, 3
	v_ashrrev_i32_e32 v136, 5, v146
	v_lshl_or_b32 v144, s36, 8, v156
	v_ashrrev_i32_e32 v147, 31, v146
	v_mad_i64_i32 v[148:149], s[4:5], v136, s87, 0
	v_lshlrev_b32_e32 v136, 4, v146
	s_cselect_b64 s[20:21], -1, 0
	v_lshlrev_b64 v[150:151], 12, v[146:147]
	v_and_b32_e32 v160, 15, v144
	v_and_b32_e32 v161, 0x1f0, v136
	s_mov_b64 s[4:5], -1
	s_and_b64 vcc, exec, s[20:21]
	s_cbranch_vccz .LBB0_305
	s_cmp_lt_u32 s36, 8
	s_cbranch_scc1 .LBB0_302
	v_mul_f32_e32 v136, 0xbfb8aa3b, v126
	v_mul_f32_e32 v145, 0xbfb8aa3b, v122
	v_mul_f32_e32 v152, 0xbfb8aa3b, v127
	v_mul_f32_e32 v153, 0xbfb8aa3b, v123
	v_exp_f32_e32 v136, v136
	v_exp_f32_e32 v145, v145
	v_exp_f32_e32 v152, v152
	v_exp_f32_e32 v153, v153
	v_mul_f32_e32 v162, 0xbfb8aa3b, v128
	v_mul_f32_e32 v163, 0xbfb8aa3b, v124
	v_mul_f32_e32 v164, 0xbfb8aa3b, v129
	v_mul_f32_e32 v165, 0xbfb8aa3b, v125
	v_exp_f32_e32 v162, v162
	v_exp_f32_e32 v163, v163
	v_exp_f32_e32 v164, v164
	v_exp_f32_e32 v165, v165
	v_add_f32_e32 v136, 1.0, v136
	v_add_f32_e32 v145, 1.0, v145
	v_add_f32_e32 v152, 1.0, v152
	v_add_f32_e32 v153, 1.0, v153
	v_rcp_f32_e32 v136, v136
	v_rcp_f32_e32 v145, v145
	v_rcp_f32_e32 v152, v152
	v_rcp_f32_e32 v153, v153
	v_add_f32_e32 v162, 1.0, v162
	v_add_f32_e32 v163, 1.0, v163
	v_add_f32_e32 v164, 1.0, v164
	v_add_f32_e32 v165, 1.0, v165
	v_rcp_f32_e32 v162, v162
	v_rcp_f32_e32 v163, v163
	v_rcp_f32_e32 v164, v164
	v_rcp_f32_e32 v165, v165
	v_mul_f32_e32 v136, v126, v136
	v_mul_f32_e32 v145, v122, v145
	v_mul_f32_e32 v152, v127, v152
	v_mul_f32_e32 v153, v123, v153
	v_mul_f32_e32 v166, v128, v162
	v_mul_f32_e32 v167, v124, v163
	v_mul_f32_e32 v163, v129, v164
	v_mul_f32_e32 v165, v125, v165
	v_cvt_pk_bf16_f32 v162, v136, v152
	v_cvt_pk_bf16_f32 v164, v145, v153
	v_lshl_add_u64 v[152:153], s[26:27], 0, v[150:151]
	v_ashrrev_i32_e32 v145, 31, v144
	v_cvt_pk_bf16_f32 v163, v166, v163
	v_cvt_pk_bf16_f32 v165, v167, v165
	v_lshl_add_u64 v[152:153], v[144:145], 1, v[152:153]
	s_mov_b64 s[4:5], 0
	global_store_dwordx4 v[152:153], v[162:165], off offset:-4096 sc0 sc1
.LBB0_302:
	s_andn2_b64 vcc, exec, s[4:5]
	s_cbranch_vccnz .LBB0_304
	v_add_u32_e32 v136, 0xfffffc00, v144
	v_ashrrev_i32_e32 v136, 4, v136
	v_mov_b64_e32 v[152:153], s[8:9]
	v_mad_i64_i32 v[152:153], s[4:5], v136, s88, v[152:153]
	v_lshl_add_u64 v[152:153], v[152:153], 0, v[148:149]
	v_lshlrev_b32_e32 v136, 1, v161
	v_lshl_add_u64 v[152:153], v[152:153], 0, v[136:137]
	v_lshlrev_b32_e32 v136, 1, v160
	v_cvt_pk_bf16_f32 v162, v126, v127
	v_cvt_pk_bf16_f32 v163, v128, v129
	v_cvt_pk_bf16_f32 v164, v122, v123
	v_cvt_pk_bf16_f32 v165, v124, v125
	v_lshl_add_u64 v[152:153], v[152:153], 0, v[136:137]
	global_store_dwordx4 v[152:153], v[162:165], off offset:512 sc0 sc1

; __device__ __forceinline__ float silu_f(float v) { return v * fast_sigmoid(v); }
; __device__ __forceinline__ u32x4 pack8(const f32x4 v0, const f32x4 v1) { u32x4 w; w.x = pk_f16(v0[0], v0[1]); w.y = pk_f16(v0[2], v0[3]); w.z = pk_f16(v1[0], v1[1]); w.w = pk_f16(v1[2], v1[3]); return w; }
;     __device__ __forceinline__ void operator()(AccRef acc, const Unit& u, int wr, int wc, int fr, int fq) const {
;     ...
;                 for (int bj = 0; bj < 2; ++bj) { const int col = col0 + bj * HALF; f32x4 v0 = acc[ai][bj][m][0], v1 = acc[ai][bj][m][1];
;                     if (u.pn < 4) { *(u32x4*)(upool + (size_t)row * PW + col) = pack8(v0, v1); }
;                     else if (u.pn < 8) { const int cs = col - PW, gg = cs >> 4, hh = cs & 15, lc = row >> 5, s = row & 31;
;                         *(u32x4*)(X + (size_t)gg * XGS + (size_t)lc * XK + 256 + s * 16 + hh) = pack8(v0, v1); }
;                     else {
; #pragma unroll
;                         for (int j = 0; j < 4; ++j) { v0[j] = silu_f(v0[j]); v1[j] = silu_f(v1[j]); }
;                         *(u32x4*)(zs + (size_t)row * D + (col - PW - SW)) = pack8(v0, v1); } } }
.LBB0_305:
	v_lshlrev_b64 v[152:153], 11, v[146:147]
	s_andn2_b64 vcc, exec, s[4:5]
	v_lshl_add_u64 v[152:153], s[24:25], 0, v[152:153]
	v_ashrrev_i32_e32 v145, 31, v144
	s_cbranch_vccnz .LBB0_307
	v_cvt_pk_bf16_f32 v126, v126, v127
	v_cvt_pk_bf16_f32 v127, v128, v129
	v_cvt_pk_bf16_f32 v128, v122, v123
	v_cvt_pk_bf16_f32 v129, v124, v125
	v_lshl_add_u64 v[122:123], v[144:145], 1, v[152:153]
	global_store_dwordx4 v[122:123], v[126:129], off sc0 sc1
.LBB0_307:
	v_cndmask_b32_e64 v122, 0, 1, s[20:21]
	v_cmp_ne_u32_e64 s[4:5], 1, v122
	s_andn2_b64 vcc, exec, s[20:21]
	s_mov_b64 s[20:21], -1
	s_cbranch_vccnz .LBB0_313
	s_cmp_lt_u32 s36, 8
	s_cbranch_scc1 .LBB0_310
	v_mul_f32_e32 v123, 0xbfb8aa3b, v114
	v_mul_f32_e32 v124, 0xbfb8aa3b, v119
	v_exp_f32_e32 v123, v123
	v_exp_f32_e32 v124, v124
	v_mul_f32_e32 v125, 0xbfb8aa3b, v115
	v_exp_f32_e32 v125, v125
	v_add_f32_e32 v123, 1.0, v123
	v_add_f32_e32 v124, 1.0, v124
	v_rcp_f32_e32 v123, v123
	v_rcp_f32_e32 v124, v124
	v_mul_f32_e32 v122, 0xbfb8aa3b, v118
	v_mul_f32_e32 v127, 0xbfb8aa3b, v116
	v_mul_f32_e32 v126, v114, v123
	v_mul_f32_e32 v123, v119, v124
	v_add_f32_e32 v124, 1.0, v125
	v_mul_f32_e32 v125, 0xbfb8aa3b, v120
	v_mul_f32_e32 v128, 0xbfb8aa3b, v121
	v_mul_f32_e32 v129, 0xbfb8aa3b, v117
	v_exp_f32_e32 v122, v122
	v_exp_f32_e32 v125, v125
	v_exp_f32_e32 v127, v127
	v_exp_f32_e32 v128, v128
	v_exp_f32_e32 v129, v129
	v_add_f32_e32 v122, 1.0, v122
	v_add_f32_e32 v125, 1.0, v125
	v_add_f32_e32 v127, 1.0, v127
	v_add_f32_e32 v128, 1.0, v128
	v_add_f32_e32 v129, 1.0, v129
	v_rcp_f32_e32 v122, v122
	v_rcp_f32_e32 v124, v124
	v_rcp_f32_e32 v125, v125
	v_rcp_f32_e32 v127, v127
	v_rcp_f32_e32 v128, v128
	v_rcp_f32_e32 v129, v129
	v_mul_f32_e32 v122, v118, v122
	v_mul_f32_e32 v124, v115, v124
	v_mul_f32_e32 v125, v120, v125
	v_mul_f32_e32 v127, v116, v127
	v_mul_f32_e32 v128, v121, v128
	v_mul_f32_e32 v129, v117, v129
	v_cvt_pk_bf16_f32 v122, v122, v123
	v_cvt_pk_bf16_f32 v123, v125, v128
	v_cvt_pk_bf16_f32 v124, v126, v124
	v_cvt_pk_bf16_f32 v125, v127, v129
	v_lshl_add_u64 v[126:127], s[26:27], 0, v[150:151]
	v_lshl_add_u64 v[126:127], v[144:145], 1, v[126:127]
	s_mov_b64 s[20:21], 0
	global_store_dwordx4 v[126:127], v[122:125], off offset:-3840 sc0 sc1
.LBB0_310:
	s_andn2_b64 vcc, exec, s[20:21]
	s_cbranch_vccnz .LBB0_312
	v_add_u32_e32 v122, 0xfffffc80, v144
	v_ashrrev_i32_e32 v128, 4, v122
	v_mov_b64_e32 v[126:127], s[8:9]
	v_mad_i64_i32 v[126:127], s[18:19], v128, s88, v[126:127]
	v_lshl_add_u64 v[126:127], v[126:127], 0, v[148:149]
	v_lshlrev_b32_e32 v136, 1, v161
	v_lshl_add_u64 v[126:127], v[126:127], 0, v[136:137]
	v_lshlrev_b32_e32 v136, 1, v160
	v_cvt_pk_bf16_f32 v122, v118, v119
	v_cvt_pk_bf16_f32 v123, v120, v121
	v_cvt_pk_bf16_f32 v124, v114, v115
	v_cvt_pk_bf16_f32 v125, v116, v117
	v_lshl_add_u64 v[126:127], v[126:127], 0, v[136:137]
	global_store_dwordx4 v[126:127], v[122:125], off offset:512 sc0 sc1

; __device__ __forceinline__ u32x4 pack8(const f32x4 v0, const f32x4 v1) { u32x4 w; w.x = pk_f16(v0[0], v0[1]); w.y = pk_f16(v0[2], v0[3]); w.z = pk_f16(v1[0], v1[1]); w.w = pk_f16(v1[2], v1[3]); return w; }
;     __device__ __forceinline__ void operator()(AccRef acc, const Unit& u, int wr, int wc, int fr, int fq) const {
;     ...
;                 for (int bj = 0; bj < 2; ++bj) { const int col = col0 + bj * HALF; f32x4 v0 = acc[ai][bj][m][0], v1 = acc[ai][bj][m][1];
;                     if (u.pn < 4) { *(u32x4*)(upool + (size_t)row * PW + col) = pack8(v0, v1); }
.LBB0_313:
	s_andn2_b64 vcc, exec, s[20:21]
	s_cbranch_vccnz .LBB0_315
	v_cvt_pk_bf16_f32 v118, v118, v119
	v_cvt_pk_bf16_f32 v119, v120, v121
	v_cvt_pk_bf16_f32 v120, v114, v115
	v_cvt_pk_bf16_f32 v121, v116, v117
	v_lshl_add_u64 v[114:115], v[144:145], 1, v[152:153]
	global_store_dwordx4 v[114:115], v[118:121], off offset:256 sc0 sc1

; __device__ __forceinline__ u32x4 pack8(const f32x4 v0, const f32x4 v1) { u32x4 w; w.x = pk_f16(v0[0], v0[1]); w.y = pk_f16(v0[2], v0[3]); w.z = pk_f16(v1[0], v1[1]); w.w = pk_f16(v1[2], v1[3]); return w; }
;     __device__ __forceinline__ void operator()(AccRef acc, const Unit& u, int wr, int wc, int fr, int fq) const {
;     ...
;                 for (int bj = 0; bj < 2; ++bj) { const int col = col0 + bj * HALF; f32x4 v0 = acc[ai][bj][m][0], v1 = acc[ai][bj][m][1];
;                     if (u.pn < 4) { *(u32x4*)(upool + (size_t)row * PW + col) = pack8(v0, v1); }
.LBB0_319:
	v_cvt_pk_bf16_f32 v102, v102, v103
	v_cvt_pk_bf16_f32 v103, v104, v105
	v_cvt_pk_bf16_f32 v104, v98, v99
	v_cvt_pk_bf16_f32 v105, v100, v101
	v_lshl_add_u64 v[98:99], v[144:145], 1, v[118:119]
	global_store_dwordx4 v[98:99], v[102:105], off offset:256 sc0 sc1

; __device__ __forceinline__ u32x4 pack8(const f32x4 v0, const f32x4 v1) { u32x4 w; w.x = pk_f16(v0[0], v0[1]); w.y = pk_f16(v0[2], v0[3]); w.z = pk_f16(v1[0], v1[1]); w.w = pk_f16(v1[2], v1[3]); return w; }
;     __device__ __forceinline__ void operator()(AccRef acc, const Unit& u, int wr, int wc, int fr, int fq) const {
;     ...
;                 for (int bj = 0; bj < 2; ++bj) { const int col = col0 + bj * HALF; f32x4 v0 = acc[ai][bj][m][0], v1 = acc[ai][bj][m][1];
;                     if (u.pn < 4) { *(u32x4*)(upool + (size_t)row * PW + col) = pack8(v0, v1); }
.LBB0_324:
	v_cvt_pk_bf16_f32 v86, v86, v87
	v_cvt_pk_bf16_f32 v87, v88, v89
	v_cvt_pk_bf16_f32 v88, v82, v83
	v_cvt_pk_bf16_f32 v89, v84, v85
	v_lshl_add_u64 v[82:83], v[144:145], 1, v[102:103]
	global_store_dwordx4 v[82:83], v[86:89], off offset:256 sc0 sc1

; __device__ __forceinline__ u32x4 pack8(const f32x4 v0, const f32x4 v1) { u32x4 w; w.x = pk_f16(v0[0], v0[1]); w.y = pk_f16(v0[2], v0[3]); w.z = pk_f16(v1[0], v1[1]); w.w = pk_f16(v1[2], v1[3]); return w; }
;     __device__ __forceinline__ void operator()(AccRef acc, const Unit& u, int wr, int wc, int fr, int fq) const {
;     ...
;                 for (int bj = 0; bj < 2; ++bj) { const int col = col0 + bj * HALF; f32x4 v0 = acc[ai][bj][m][0], v1 = acc[ai][bj][m][1];
;                     if (u.pn < 4) { *(u32x4*)(upool + (size_t)row * PW + col) = pack8(v0, v1); }
.LBB0_329:
	v_cvt_pk_bf16_f32 v70, v70, v71
	v_cvt_pk_bf16_f32 v71, v72, v73
	v_cvt_pk_bf16_f32 v72, v66, v67
	v_cvt_pk_bf16_f32 v73, v68, v69
	v_lshl_add_u64 v[66:67], v[144:145], 1, v[86:87]
	global_store_dwordx4 v[66:67], v[70:73], off offset:256 sc0 sc1

; __device__ __forceinline__ u32x4 pack8(const f32x4 v0, const f32x4 v1) { u32x4 w; w.x = pk_f16(v0[0], v0[1]); w.y = pk_f16(v0[2], v0[3]); w.z = pk_f16(v1[0], v1[1]); w.w = pk_f16(v1[2], v1[3]); return w; }
;     __device__ __forceinline__ void operator()(AccRef acc, const Unit& u, int wr, int wc, int fr, int fq) const {
;     ...
;                 for (int bj = 0; bj < 2; ++bj) { const int col = col0 + bj * HALF; f32x4 v0 = acc[ai][bj][m][0], v1 = acc[ai][bj][m][1];
;                     if (u.pn < 4) { *(u32x4*)(upool + (size_t)row * PW + col) = pack8(v0, v1); }
.LBB0_334:
	v_cvt_pk_bf16_f32 v54, v54, v55
	v_cvt_pk_bf16_f32 v55, v56, v57
	v_cvt_pk_bf16_f32 v56, v50, v51
	v_cvt_pk_bf16_f32 v57, v52, v53
	v_lshl_add_u64 v[50:51], v[144:145], 1, v[70:71]
	global_store_dwordx4 v[50:51], v[54:57], off offset:256 sc0 sc1

; __device__ __forceinline__ u32x4 pack8(const f32x4 v0, const f32x4 v1) { u32x4 w; w.x = pk_f16(v0[0], v0[1]); w.y = pk_f16(v0[2], v0[3]); w.z = pk_f16(v1[0], v1[1]); w.w = pk_f16(v1[2], v1[3]); return w; }
;     __device__ __forceinline__ void operator()(AccRef acc, const Unit& u, int wr, int wc, int fr, int fq) const {
;     ...
;                 for (int bj = 0; bj < 2; ++bj) { const int col = col0 + bj * HALF; f32x4 v0 = acc[ai][bj][m][0], v1 = acc[ai][bj][m][1];
;                     if (u.pn < 4) { *(u32x4*)(upool + (size_t)row * PW + col) = pack8(v0, v1); }
.LBB0_339:
	v_cvt_pk_bf16_f32 v38, v38, v39
	v_cvt_pk_bf16_f32 v39, v40, v41
	v_cvt_pk_bf16_f32 v40, v34, v35
	v_cvt_pk_bf16_f32 v41, v36, v37
	v_lshl_add_u64 v[34:35], v[144:145], 1, v[54:55]
	global_store_dwordx4 v[34:35], v[38:41], off offset:256 sc0 sc1

; __device__ __forceinline__ u32x4 pack8(const f32x4 v0, const f32x4 v1) { u32x4 w; w.x = pk_f16(v0[0], v0[1]); w.y = pk_f16(v0[2], v0[3]); w.z = pk_f16(v1[0], v1[1]); w.w = pk_f16(v1[2], v1[3]); return w; }
;     __device__ __forceinline__ void operator()(AccRef acc, const Unit& u, int wr, int wc, int fr, int fq) const {
;     ...
;                 for (int bj = 0; bj < 2; ++bj) { const int col = col0 + bj * HALF; f32x4 v0 = acc[ai][bj][m][0], v1 = acc[ai][bj][m][1];
;                     if (u.pn < 4) { *(u32x4*)(upool + (size_t)row * PW + col) = pack8(v0, v1); }
.LBB0_344:
	v_cvt_pk_bf16_f32 v22, v22, v23
	v_cvt_pk_bf16_f32 v23, v24, v25
	v_cvt_pk_bf16_f32 v24, v18, v19
	v_cvt_pk_bf16_f32 v25, v20, v21
	v_lshl_add_u64 v[18:19], v[144:145], 1, v[38:39]
	global_store_dwordx4 v[18:19], v[22:25], off offset:256 sc0 sc1

; __device__ __forceinline__ float silu_f(float v) { return v * fast_sigmoid(v); }
; __device__ __forceinline__ u32x4 pack8(const f32x4 v0, const f32x4 v1) { u32x4 w; w.x = pk_f16(v0[0], v0[1]); w.y = pk_f16(v0[2], v0[3]); w.z = pk_f16(v1[0], v1[1]); w.w = pk_f16(v1[2], v1[3]); return w; }
;     __device__ __forceinline__ void operator()(AccRef acc, const Unit& u, int wr, int wc, int fr, int fq) const {
;     ...
;                 for (int bj = 0; bj < 2; ++bj) { const int col = col0 + bj * HALF; f32x4 v0 = acc[ai][bj][m][0], v1 = acc[ai][bj][m][1];
;                     if (u.pn < 4) { *(u32x4*)(upool + (size_t)row * PW + col) = pack8(v0, v1); }
;                     else if (u.pn < 8) { const int cs = col - PW, gg = cs >> 4, hh = cs & 15, lc = row >> 5, s = row & 31;
;                         *(u32x4*)(X + (size_t)gg * XGS + (size_t)lc * XK + 256 + s * 16 + hh) = pack8(v0, v1); }
;                     else {
; #pragma unroll
;                         for (int j = 0; j < 4; ++j) { v0[j] = silu_f(v0[j]); v1[j] = silu_f(v1[j]); }
;                         *(u32x4*)(zs + (size_t)row * D + (col - PW - SW)) = pack8(v0, v1); } } }
.LBB0_350:
	s_cmp_lt_u32 s36, 8
	s_cbranch_scc1 .LBB0_352
	v_mul_f32_e32 v122, 0xbfb8aa3b, v106
	v_mul_f32_e32 v123, 0xbfb8aa3b, v111
	v_exp_f32_e32 v122, v122
	v_exp_f32_e32 v123, v123
	v_mul_f32_e32 v124, 0xbfb8aa3b, v107
	v_exp_f32_e32 v124, v124
	v_add_f32_e32 v122, 1.0, v122
	v_add_f32_e32 v123, 1.0, v123
	v_rcp_f32_e32 v122, v122
	v_rcp_f32_e32 v123, v123
	v_mul_f32_e32 v126, 0xbfb8aa3b, v108
	v_exp_f32_e32 v126, v126
	v_mul_f32_e32 v125, v106, v122
	v_mul_f32_e32 v122, v111, v123
	v_add_f32_e32 v123, 1.0, v124
	v_mul_f32_e32 v124, 0xbfb8aa3b, v112
	v_rcp_f32_e32 v123, v123
	v_exp_f32_e32 v124, v124
	v_mul_f32_e32 v128, 0xbfb8aa3b, v109
	v_mul_f32_e32 v121, 0xbfb8aa3b, v110
	v_mul_f32_e32 v127, v107, v123
	v_add_f32_e32 v123, 1.0, v124
	v_add_f32_e32 v124, 1.0, v126
	v_mul_f32_e32 v126, 0xbfb8aa3b, v113
	v_exp_f32_e32 v126, v126
	v_exp_f32_e32 v128, v128
	v_exp_f32_e32 v121, v121
	v_rcp_f32_e32 v123, v123
	v_add_f32_e32 v126, 1.0, v126
	v_add_f32_e32 v128, 1.0, v128
	v_add_f32_e32 v121, 1.0, v121
	v_rcp_f32_e32 v124, v124
	v_rcp_f32_e32 v126, v126
	v_rcp_f32_e32 v128, v128
	v_rcp_f32_e32 v121, v121
	v_mul_f32_e32 v123, v112, v123
	v_mul_f32_e32 v129, v108, v124
	v_mul_f32_e32 v124, v113, v126
	v_mul_f32_e32 v126, v109, v128
	v_mul_f32_e32 v121, v110, v121
	v_cvt_pk_bf16_f32 v123, v123, v124
	v_cvt_pk_bf16_f32 v124, v125, v127
	v_cvt_pk_bf16_f32 v125, v129, v126
	v_lshl_add_u64 v[126:127], s[26:27], 0, v[116:117]
	v_cvt_pk_bf16_f32 v122, v121, v122
	v_lshl_add_u64 v[126:127], v[144:145], 1, v[126:127]
	s_mov_b64 s[20:21], 0
	global_store_dwordx4 v[126:127], v[122:125], off offset:-4096 sc0 sc1
.LBB0_352:
	s_andn2_b64 vcc, exec, s[20:21]
	s_cbranch_vccnz .LBB0_354
	v_add_u32_e32 v121, 0xfffffc00, v144
	v_ashrrev_i32_e32 v121, 4, v121
	v_mov_b64_e32 v[126:127], s[8:9]
	v_mad_i64_i32 v[126:127], s[18:19], v121, s88, v[126:127]
	v_lshl_add_u64 v[126:127], v[126:127], 0, v[114:115]
	v_lshlrev_b32_e32 v136, 1, v120
	v_lshl_add_u64 v[126:127], v[126:127], 0, v[136:137]
	v_lshlrev_b32_e32 v136, 1, v160
	v_cvt_pk_bf16_f32 v122, v110, v111
	v_cvt_pk_bf16_f32 v123, v112, v113
	v_cvt_pk_bf16_f32 v124, v106, v107
	v_cvt_pk_bf16_f32 v125, v108, v109
	v_lshl_add_u64 v[126:127], v[126:127], 0, v[136:137]
	global_store_dwordx4 v[126:127], v[122:125], off offset:512 sc0 sc1

; __device__ __forceinline__ float silu_f(float v) { return v * fast_sigmoid(v); }
; __device__ __forceinline__ u32x4 pack8(const f32x4 v0, const f32x4 v1) { u32x4 w; w.x = pk_f16(v0[0], v0[1]); w.y = pk_f16(v0[2], v0[3]); w.z = pk_f16(v1[0], v1[1]); w.w = pk_f16(v1[2], v1[3]); return w; }
;     __device__ __forceinline__ void operator()(AccRef acc, const Unit& u, int wr, int wc, int fr, int fq) const {
;     ...
;                 for (int bj = 0; bj < 2; ++bj) { const int col = col0 + bj * HALF; f32x4 v0 = acc[ai][bj][m][0], v1 = acc[ai][bj][m][1];
;                     if (u.pn < 4) { *(u32x4*)(upool + (size_t)row * PW + col) = pack8(v0, v1); }
;                     else if (u.pn < 8) { const int cs = col - PW, gg = cs >> 4, hh = cs & 15, lc = row >> 5, s = row & 31;
;                         *(u32x4*)(X + (size_t)gg * XGS + (size_t)lc * XK + 256 + s * 16 + hh) = pack8(v0, v1); }
;                     else {
; #pragma unroll
;                         for (int j = 0; j < 4; ++j) { v0[j] = silu_f(v0[j]); v1[j] = silu_f(v1[j]); }
;                         *(u32x4*)(zs + (size_t)row * D + (col - PW - SW)) = pack8(v0, v1); } } }
.LBB0_355:
	v_cvt_pk_bf16_f32 v110, v110, v111
	v_cvt_pk_bf16_f32 v111, v112, v113
	v_cvt_pk_bf16_f32 v112, v106, v107
	v_cvt_pk_bf16_f32 v113, v108, v109
	v_lshl_add_u64 v[106:107], v[144:145], 1, v[118:119]
	global_store_dwordx4 v[106:107], v[110:113], off sc0 sc1
	s_and_b64 vcc, exec, s[4:5]
	s_mov_b64 s[20:21], -1
	s_cbranch_vccnz .LBB0_318
.LBB0_356:
	s_cmp_lt_u32 s36, 8
	s_cbranch_scc1 .LBB0_358
	v_mul_f32_e32 v107, 0xbfb8aa3b, v98
	v_mul_f32_e32 v108, 0xbfb8aa3b, v103
	v_exp_f32_e32 v107, v107
	v_exp_f32_e32 v108, v108
	v_mul_f32_e32 v109, 0xbfb8aa3b, v99
	v_exp_f32_e32 v109, v109
	v_add_f32_e32 v107, 1.0, v107
	v_add_f32_e32 v108, 1.0, v108
	v_rcp_f32_e32 v107, v107
	v_rcp_f32_e32 v108, v108
	v_mul_f32_e32 v106, 0xbfb8aa3b, v102
	v_mul_f32_e32 v111, 0xbfb8aa3b, v100
	v_mul_f32_e32 v110, v98, v107
	v_mul_f32_e32 v107, v103, v108
	v_add_f32_e32 v108, 1.0, v109
	v_mul_f32_e32 v109, 0xbfb8aa3b, v104
	v_mul_f32_e32 v112, 0xbfb8aa3b, v105
	v_mul_f32_e32 v113, 0xbfb8aa3b, v101
	v_exp_f32_e32 v106, v106
	v_exp_f32_e32 v109, v109
	v_exp_f32_e32 v111, v111
	v_exp_f32_e32 v112, v112
	v_exp_f32_e32 v113, v113
	v_add_f32_e32 v106, 1.0, v106
	v_add_f32_e32 v109, 1.0, v109
	v_add_f32_e32 v111, 1.0, v111
	v_add_f32_e32 v112, 1.0, v112
	v_add_f32_e32 v113, 1.0, v113
	v_rcp_f32_e32 v106, v106
	v_rcp_f32_e32 v108, v108
	v_rcp_f32_e32 v109, v109
	v_rcp_f32_e32 v111, v111
	v_rcp_f32_e32 v112, v112
	v_rcp_f32_e32 v113, v113
	v_mul_f32_e32 v106, v102, v106
	v_mul_f32_e32 v108, v99, v108
	v_mul_f32_e32 v109, v104, v109
	v_mul_f32_e32 v111, v100, v111
	v_mul_f32_e32 v112, v105, v112
	v_mul_f32_e32 v113, v101, v113
	v_cvt_pk_bf16_f32 v106, v106, v107
	v_cvt_pk_bf16_f32 v107, v109, v112
	v_cvt_pk_bf16_f32 v108, v110, v108
	v_cvt_pk_bf16_f32 v109, v111, v113
	v_lshl_add_u64 v[110:111], s[26:27], 0, v[116:117]
	v_lshl_add_u64 v[110:111], v[144:145], 1, v[110:111]
	s_mov_b64 s[20:21], 0
	global_store_dwordx4 v[110:111], v[106:109], off offset:-3840 sc0 sc1
.LBB0_358:
	s_andn2_b64 vcc, exec, s[20:21]
	s_cbranch_vccnz .LBB0_360
	v_add_u32_e32 v106, 0xfffffc80, v144
	v_ashrrev_i32_e32 v112, 4, v106
	v_mov_b64_e32 v[110:111], s[8:9]
	v_mad_i64_i32 v[110:111], s[18:19], v112, s88, v[110:111]
	v_lshl_add_u64 v[110:111], v[110:111], 0, v[114:115]
	v_lshlrev_b32_e32 v136, 1, v120
	v_lshl_add_u64 v[110:111], v[110:111], 0, v[136:137]
	v_lshlrev_b32_e32 v136, 1, v160
	v_cvt_pk_bf16_f32 v106, v102, v103
	v_cvt_pk_bf16_f32 v107, v104, v105
	v_cvt_pk_bf16_f32 v108, v98, v99
	v_cvt_pk_bf16_f32 v109, v100, v101
	v_lshl_add_u64 v[110:111], v[110:111], 0, v[136:137]
	global_store_dwordx4 v[110:111], v[106:109], off offset:512 sc0 sc1

; __device__ __forceinline__ float silu_f(float v) { return v * fast_sigmoid(v); }
; __device__ __forceinline__ u32x4 pack8(const f32x4 v0, const f32x4 v1) { u32x4 w; w.x = pk_f16(v0[0], v0[1]); w.y = pk_f16(v0[2], v0[3]); w.z = pk_f16(v1[0], v1[1]); w.w = pk_f16(v1[2], v1[3]); return w; }
;     __device__ __forceinline__ void operator()(AccRef acc, const Unit& u, int wr, int wc, int fr, int fq) const {
;     ...
;                 for (int bj = 0; bj < 2; ++bj) { const int col = col0 + bj * HALF; f32x4 v0 = acc[ai][bj][m][0], v1 = acc[ai][bj][m][1];
;                     if (u.pn < 4) { *(u32x4*)(upool + (size_t)row * PW + col) = pack8(v0, v1); }
;                     else if (u.pn < 8) { const int cs = col - PW, gg = cs >> 4, hh = cs & 15, lc = row >> 5, s = row & 31;
;                         *(u32x4*)(X + (size_t)gg * XGS + (size_t)lc * XK + 256 + s * 16 + hh) = pack8(v0, v1); }
;                     else {
; #pragma unroll
;                         for (int j = 0; j < 4; ++j) { v0[j] = silu_f(v0[j]); v1[j] = silu_f(v1[j]); }
;                         *(u32x4*)(zs + (size_t)row * D + (col - PW - SW)) = pack8(v0, v1); } } }
.LBB0_361:
	s_cmp_lt_u32 s36, 8
	s_cbranch_scc1 .LBB0_363
	v_mul_f32_e32 v105, 0xbfb8aa3b, v90
	v_mul_f32_e32 v106, 0xbfb8aa3b, v95
	v_exp_f32_e32 v105, v105
	v_exp_f32_e32 v106, v106
	v_mul_f32_e32 v107, 0xbfb8aa3b, v91
	v_exp_f32_e32 v107, v107
	v_add_f32_e32 v105, 1.0, v105
	v_add_f32_e32 v106, 1.0, v106
	v_rcp_f32_e32 v105, v105
	v_rcp_f32_e32 v106, v106
	v_mul_f32_e32 v104, 0xbfb8aa3b, v94
	v_mul_f32_e32 v109, 0xbfb8aa3b, v92
	v_mul_f32_e32 v108, v90, v105
	v_mul_f32_e32 v105, v95, v106
	v_add_f32_e32 v106, 1.0, v107
	v_mul_f32_e32 v107, 0xbfb8aa3b, v96
	v_mul_f32_e32 v110, 0xbfb8aa3b, v97
	v_mul_f32_e32 v111, 0xbfb8aa3b, v93
	v_exp_f32_e32 v104, v104
	v_exp_f32_e32 v107, v107
	v_exp_f32_e32 v109, v109
	v_exp_f32_e32 v110, v110
	v_exp_f32_e32 v111, v111
	v_add_f32_e32 v104, 1.0, v104
	v_add_f32_e32 v107, 1.0, v107
	v_add_f32_e32 v109, 1.0, v109
	v_add_f32_e32 v110, 1.0, v110
	v_add_f32_e32 v111, 1.0, v111
	v_rcp_f32_e32 v104, v104
	v_rcp_f32_e32 v106, v106
	v_rcp_f32_e32 v107, v107
	v_rcp_f32_e32 v109, v109
	v_rcp_f32_e32 v110, v110
	v_rcp_f32_e32 v111, v111
	v_mul_f32_e32 v104, v94, v104
	v_mul_f32_e32 v106, v91, v106
	v_mul_f32_e32 v107, v96, v107
	v_mul_f32_e32 v109, v92, v109
	v_mul_f32_e32 v110, v97, v110
	v_mul_f32_e32 v111, v93, v111
	v_cvt_pk_bf16_f32 v104, v104, v105
	v_cvt_pk_bf16_f32 v105, v107, v110
	v_cvt_pk_bf16_f32 v106, v108, v106
	v_cvt_pk_bf16_f32 v107, v109, v111
	v_lshl_add_u64 v[108:109], s[26:27], 0, v[100:101]
	v_lshl_add_u64 v[108:109], v[144:145], 1, v[108:109]
	s_mov_b64 s[20:21], 0
	global_store_dwordx4 v[108:109], v[104:107], off offset:-4096 sc0 sc1
.LBB0_363:
	s_andn2_b64 vcc, exec, s[20:21]
	s_cbranch_vccnz .LBB0_365
	v_add_u32_e32 v104, 0xfffffc00, v144
	v_ashrrev_i32_e32 v110, 4, v104
	v_mov_b64_e32 v[108:109], s[8:9]
	v_mad_i64_i32 v[108:109], s[18:19], v110, s88, v[108:109]
	v_lshl_add_u64 v[108:109], v[108:109], 0, v[98:99]
	v_lshlrev_b32_e32 v136, 1, v161
	v_lshl_add_u64 v[108:109], v[108:109], 0, v[136:137]
	v_lshlrev_b32_e32 v136, 1, v160
	v_cvt_pk_bf16_f32 v104, v94, v95
	v_cvt_pk_bf16_f32 v105, v96, v97
	v_cvt_pk_bf16_f32 v106, v90, v91
	v_cvt_pk_bf16_f32 v107, v92, v93
	v_lshl_add_u64 v[108:109], v[108:109], 0, v[136:137]
	global_store_dwordx4 v[108:109], v[104:107], off offset:512 sc0 sc1

; __device__ __forceinline__ float silu_f(float v) { return v * fast_sigmoid(v); }
; __device__ __forceinline__ u32x4 pack8(const f32x4 v0, const f32x4 v1) { u32x4 w; w.x = pk_f16(v0[0], v0[1]); w.y = pk_f16(v0[2], v0[3]); w.z = pk_f16(v1[0], v1[1]); w.w = pk_f16(v1[2], v1[3]); return w; }
;     __device__ __forceinline__ void operator()(AccRef acc, const Unit& u, int wr, int wc, int fr, int fq) const {
;     ...
;                 for (int bj = 0; bj < 2; ++bj) { const int col = col0 + bj * HALF; f32x4 v0 = acc[ai][bj][m][0], v1 = acc[ai][bj][m][1];
;                     if (u.pn < 4) { *(u32x4*)(upool + (size_t)row * PW + col) = pack8(v0, v1); }
;                     else if (u.pn < 8) { const int cs = col - PW, gg = cs >> 4, hh = cs & 15, lc = row >> 5, s = row & 31;
;                         *(u32x4*)(X + (size_t)gg * XGS + (size_t)lc * XK + 256 + s * 16 + hh) = pack8(v0, v1); }
;                     else {
; #pragma unroll
;                         for (int j = 0; j < 4; ++j) { v0[j] = silu_f(v0[j]); v1[j] = silu_f(v1[j]); }
;                         *(u32x4*)(zs + (size_t)row * D + (col - PW - SW)) = pack8(v0, v1); } } }
.LBB0_366:
	v_cvt_pk_bf16_f32 v94, v94, v95
	v_cvt_pk_bf16_f32 v95, v96, v97
	v_cvt_pk_bf16_f32 v96, v90, v91
	v_cvt_pk_bf16_f32 v97, v92, v93
	v_lshl_add_u64 v[90:91], v[144:145], 1, v[102:103]
	global_store_dwordx4 v[90:91], v[94:97], off sc0 sc1
	s_and_b64 vcc, exec, s[4:5]
	s_mov_b64 s[20:21], -1
	s_cbranch_vccnz .LBB0_323
.LBB0_367:
	s_cmp_lt_u32 s36, 8
	s_cbranch_scc1 .LBB0_369
	v_mul_f32_e32 v91, 0xbfb8aa3b, v82
	v_mul_f32_e32 v92, 0xbfb8aa3b, v87
	v_exp_f32_e32 v91, v91
	v_exp_f32_e32 v92, v92
	v_mul_f32_e32 v93, 0xbfb8aa3b, v83
	v_exp_f32_e32 v93, v93
	v_add_f32_e32 v91, 1.0, v91
	v_add_f32_e32 v92, 1.0, v92
	v_rcp_f32_e32 v91, v91
	v_rcp_f32_e32 v92, v92
	v_mul_f32_e32 v90, 0xbfb8aa3b, v86
	v_mul_f32_e32 v95, 0xbfb8aa3b, v84
	v_mul_f32_e32 v94, v82, v91
	v_mul_f32_e32 v91, v87, v92
	v_add_f32_e32 v92, 1.0, v93
	v_mul_f32_e32 v93, 0xbfb8aa3b, v88
	v_mul_f32_e32 v96, 0xbfb8aa3b, v89
	v_mul_f32_e32 v97, 0xbfb8aa3b, v85
	v_exp_f32_e32 v90, v90
	v_exp_f32_e32 v93, v93
	v_exp_f32_e32 v95, v95
	v_exp_f32_e32 v96, v96
	v_exp_f32_e32 v97, v97
	v_add_f32_e32 v90, 1.0, v90
	v_add_f32_e32 v93, 1.0, v93
	v_add_f32_e32 v95, 1.0, v95
	v_add_f32_e32 v96, 1.0, v96
	v_add_f32_e32 v97, 1.0, v97
	v_rcp_f32_e32 v90, v90
	v_rcp_f32_e32 v92, v92
	v_rcp_f32_e32 v93, v93
	v_rcp_f32_e32 v95, v95
	v_rcp_f32_e32 v96, v96
	v_rcp_f32_e32 v97, v97
	v_mul_f32_e32 v90, v86, v90
	v_mul_f32_e32 v92, v83, v92
	v_mul_f32_e32 v93, v88, v93
	v_mul_f32_e32 v95, v84, v95
	v_mul_f32_e32 v96, v89, v96
	v_mul_f32_e32 v97, v85, v97
	v_cvt_pk_bf16_f32 v90, v90, v91
	v_cvt_pk_bf16_f32 v91, v93, v96
	v_cvt_pk_bf16_f32 v92, v94, v92
	v_cvt_pk_bf16_f32 v93, v95, v97
	v_lshl_add_u64 v[94:95], s[26:27], 0, v[100:101]
	v_lshl_add_u64 v[94:95], v[144:145], 1, v[94:95]
	s_mov_b64 s[20:21], 0
	global_store_dwordx4 v[94:95], v[90:93], off offset:-3840 sc0 sc1
.LBB0_369:
	s_andn2_b64 vcc, exec, s[20:21]
	s_cbranch_vccnz .LBB0_371
	v_add_u32_e32 v90, 0xfffffc80, v144
	v_ashrrev_i32_e32 v96, 4, v90
	v_mov_b64_e32 v[94:95], s[8:9]
	v_mad_i64_i32 v[94:95], s[18:19], v96, s88, v[94:95]
	v_lshl_add_u64 v[94:95], v[94:95], 0, v[98:99]
	v_lshlrev_b32_e32 v136, 1, v161
	v_lshl_add_u64 v[94:95], v[94:95], 0, v[136:137]
	v_lshlrev_b32_e32 v136, 1, v160
	v_cvt_pk_bf16_f32 v90, v86, v87
	v_cvt_pk_bf16_f32 v91, v88, v89
	v_cvt_pk_bf16_f32 v92, v82, v83
	v_cvt_pk_bf16_f32 v93, v84, v85
	v_lshl_add_u64 v[94:95], v[94:95], 0, v[136:137]
	global_store_dwordx4 v[94:95], v[90:93], off offset:512 sc0 sc1

; __device__ __forceinline__ float silu_f(float v) { return v * fast_sigmoid(v); }
; __device__ __forceinline__ u32x4 pack8(const f32x4 v0, const f32x4 v1) { u32x4 w; w.x = pk_f16(v0[0], v0[1]); w.y = pk_f16(v0[2], v0[3]); w.z = pk_f16(v1[0], v1[1]); w.w = pk_f16(v1[2], v1[3]); return w; }
;     __device__ __forceinline__ void operator()(AccRef acc, const Unit& u, int wr, int wc, int fr, int fq) const {
;     ...
;                 for (int bj = 0; bj < 2; ++bj) { const int col = col0 + bj * HALF; f32x4 v0 = acc[ai][bj][m][0], v1 = acc[ai][bj][m][1];
;                     if (u.pn < 4) { *(u32x4*)(upool + (size_t)row * PW + col) = pack8(v0, v1); }
;                     else if (u.pn < 8) { const int cs = col - PW, gg = cs >> 4, hh = cs & 15, lc = row >> 5, s = row & 31;
;                         *(u32x4*)(X + (size_t)gg * XGS + (size_t)lc * XK + 256 + s * 16 + hh) = pack8(v0, v1); }
;                     else {
; #pragma unroll
;                         for (int j = 0; j < 4; ++j) { v0[j] = silu_f(v0[j]); v1[j] = silu_f(v1[j]); }
;                         *(u32x4*)(zs + (size_t)row * D + (col - PW - SW)) = pack8(v0, v1); } } }
.LBB0_372:
	s_cmp_lt_u32 s36, 8
	s_cbranch_scc1 .LBB0_374
	v_mul_f32_e32 v90, 0xbfb8aa3b, v74
	v_mul_f32_e32 v91, 0xbfb8aa3b, v79
	v_exp_f32_e32 v90, v90
	v_exp_f32_e32 v91, v91
	v_mul_f32_e32 v92, 0xbfb8aa3b, v75
	v_exp_f32_e32 v92, v92
	v_add_f32_e32 v90, 1.0, v90
	v_add_f32_e32 v91, 1.0, v91
	v_rcp_f32_e32 v90, v90
	v_rcp_f32_e32 v91, v91
	v_mul_f32_e32 v94, 0xbfb8aa3b, v76
	v_exp_f32_e32 v94, v94
	v_mul_f32_e32 v93, v74, v90
	v_mul_f32_e32 v90, v79, v91
	v_add_f32_e32 v91, 1.0, v92
	v_mul_f32_e32 v92, 0xbfb8aa3b, v80
	v_rcp_f32_e32 v91, v91
	v_exp_f32_e32 v92, v92
	v_mul_f32_e32 v96, 0xbfb8aa3b, v77
	v_mul_f32_e32 v89, 0xbfb8aa3b, v78
	v_mul_f32_e32 v95, v75, v91
	v_add_f32_e32 v91, 1.0, v92
	v_add_f32_e32 v92, 1.0, v94
	v_mul_f32_e32 v94, 0xbfb8aa3b, v81
	v_exp_f32_e32 v94, v94
	v_exp_f32_e32 v96, v96
	v_exp_f32_e32 v89, v89
	v_rcp_f32_e32 v91, v91
	v_add_f32_e32 v94, 1.0, v94
	v_add_f32_e32 v96, 1.0, v96
	v_add_f32_e32 v89, 1.0, v89
	v_rcp_f32_e32 v92, v92
	v_rcp_f32_e32 v94, v94
	v_rcp_f32_e32 v96, v96
	v_rcp_f32_e32 v89, v89
	v_mul_f32_e32 v91, v80, v91
	v_mul_f32_e32 v97, v76, v92
	v_mul_f32_e32 v92, v81, v94
	v_mul_f32_e32 v94, v77, v96
	v_mul_f32_e32 v89, v78, v89
	v_cvt_pk_bf16_f32 v91, v91, v92
	v_cvt_pk_bf16_f32 v92, v93, v95
	v_cvt_pk_bf16_f32 v93, v97, v94
	v_lshl_add_u64 v[94:95], s[26:27], 0, v[84:85]
	v_cvt_pk_bf16_f32 v90, v89, v90
	v_lshl_add_u64 v[94:95], v[144:145], 1, v[94:95]
	s_mov_b64 s[20:21], 0
	global_store_dwordx4 v[94:95], v[90:93], off offset:-4096 sc0 sc1
.LBB0_374:
	s_andn2_b64 vcc, exec, s[20:21]
	s_cbranch_vccnz .LBB0_376
	v_add_u32_e32 v89, 0xfffffc00, v144
	v_ashrrev_i32_e32 v89, 4, v89
	v_mov_b64_e32 v[94:95], s[8:9]
	v_mad_i64_i32 v[94:95], s[18:19], v89, s88, v[94:95]
	v_lshl_add_u64 v[94:95], v[94:95], 0, v[82:83]
	v_lshlrev_b32_e32 v136, 1, v88
	v_lshl_add_u64 v[94:95], v[94:95], 0, v[136:137]
	v_lshlrev_b32_e32 v136, 1, v160
	v_cvt_pk_bf16_f32 v90, v78, v79
	v_cvt_pk_bf16_f32 v91, v80, v81
	v_cvt_pk_bf16_f32 v92, v74, v75
	v_cvt_pk_bf16_f32 v93, v76, v77
	v_lshl_add_u64 v[94:95], v[94:95], 0, v[136:137]
	global_store_dwordx4 v[94:95], v[90:93], off offset:512 sc0 sc1

; __device__ __forceinline__ float silu_f(float v) { return v * fast_sigmoid(v); }
; __device__ __forceinline__ u32x4 pack8(const f32x4 v0, const f32x4 v1) { u32x4 w; w.x = pk_f16(v0[0], v0[1]); w.y = pk_f16(v0[2], v0[3]); w.z = pk_f16(v1[0], v1[1]); w.w = pk_f16(v1[2], v1[3]); return w; }
;     __device__ __forceinline__ void operator()(AccRef acc, const Unit& u, int wr, int wc, int fr, int fq) const {
;     ...
;                 for (int bj = 0; bj < 2; ++bj) { const int col = col0 + bj * HALF; f32x4 v0 = acc[ai][bj][m][0], v1 = acc[ai][bj][m][1];
;                     if (u.pn < 4) { *(u32x4*)(upool + (size_t)row * PW + col) = pack8(v0, v1); }
;                     else if (u.pn < 8) { const int cs = col - PW, gg = cs >> 4, hh = cs & 15, lc = row >> 5, s = row & 31;
;                         *(u32x4*)(X + (size_t)gg * XGS + (size_t)lc * XK + 256 + s * 16 + hh) = pack8(v0, v1); }
;                     else {
; #pragma unroll
;                         for (int j = 0; j < 4; ++j) { v0[j] = silu_f(v0[j]); v1[j] = silu_f(v1[j]); }
;                         *(u32x4*)(zs + (size_t)row * D + (col - PW - SW)) = pack8(v0, v1); } } }
.LBB0_377:
	v_cvt_pk_bf16_f32 v78, v78, v79
	v_cvt_pk_bf16_f32 v79, v80, v81
	v_cvt_pk_bf16_f32 v80, v74, v75
	v_cvt_pk_bf16_f32 v81, v76, v77
	v_lshl_add_u64 v[74:75], v[144:145], 1, v[86:87]
	global_store_dwordx4 v[74:75], v[78:81], off sc0 sc1
	s_and_b64 vcc, exec, s[4:5]
	s_mov_b64 s[20:21], -1
	s_cbranch_vccnz .LBB0_328
.LBB0_378:
	s_cmp_lt_u32 s36, 8
	s_cbranch_scc1 .LBB0_380
	v_mul_f32_e32 v75, 0xbfb8aa3b, v66
	v_mul_f32_e32 v76, 0xbfb8aa3b, v71
	v_exp_f32_e32 v75, v75
	v_exp_f32_e32 v76, v76
	v_mul_f32_e32 v77, 0xbfb8aa3b, v67
	v_exp_f32_e32 v77, v77
	v_add_f32_e32 v75, 1.0, v75
	v_add_f32_e32 v76, 1.0, v76
	v_rcp_f32_e32 v75, v75
	v_rcp_f32_e32 v76, v76
	v_mul_f32_e32 v74, 0xbfb8aa3b, v70
	v_mul_f32_e32 v79, 0xbfb8aa3b, v68
	v_mul_f32_e32 v78, v66, v75
	v_mul_f32_e32 v75, v71, v76
	v_add_f32_e32 v76, 1.0, v77
	v_mul_f32_e32 v77, 0xbfb8aa3b, v72
	v_mul_f32_e32 v80, 0xbfb8aa3b, v73
	v_mul_f32_e32 v81, 0xbfb8aa3b, v69
	v_exp_f32_e32 v74, v74
	v_exp_f32_e32 v77, v77
	v_exp_f32_e32 v79, v79
	v_exp_f32_e32 v80, v80
	v_exp_f32_e32 v81, v81
	v_add_f32_e32 v74, 1.0, v74
	v_add_f32_e32 v77, 1.0, v77
	v_add_f32_e32 v79, 1.0, v79
	v_add_f32_e32 v80, 1.0, v80
	v_add_f32_e32 v81, 1.0, v81
	v_rcp_f32_e32 v74, v74
	v_rcp_f32_e32 v76, v76
	v_rcp_f32_e32 v77, v77
	v_rcp_f32_e32 v79, v79
	v_rcp_f32_e32 v80, v80
	v_rcp_f32_e32 v81, v81
	v_mul_f32_e32 v74, v70, v74
	v_mul_f32_e32 v76, v67, v76
	v_mul_f32_e32 v77, v72, v77
	v_mul_f32_e32 v79, v68, v79
	v_mul_f32_e32 v80, v73, v80
	v_mul_f32_e32 v81, v69, v81
	v_cvt_pk_bf16_f32 v74, v74, v75
	v_cvt_pk_bf16_f32 v75, v77, v80
	v_cvt_pk_bf16_f32 v76, v78, v76
	v_cvt_pk_bf16_f32 v77, v79, v81
	v_lshl_add_u64 v[78:79], s[26:27], 0, v[84:85]
	v_lshl_add_u64 v[78:79], v[144:145], 1, v[78:79]
	s_mov_b64 s[20:21], 0
	global_store_dwordx4 v[78:79], v[74:77], off offset:-3840 sc0 sc1
.LBB0_380:
	s_andn2_b64 vcc, exec, s[20:21]
	s_cbranch_vccnz .LBB0_382
	v_add_u32_e32 v74, 0xfffffc80, v144
	v_ashrrev_i32_e32 v80, 4, v74
	v_mov_b64_e32 v[78:79], s[8:9]
	v_mad_i64_i32 v[78:79], s[18:19], v80, s88, v[78:79]
	v_lshl_add_u64 v[78:79], v[78:79], 0, v[82:83]
	v_lshlrev_b32_e32 v136, 1, v88
	v_lshl_add_u64 v[78:79], v[78:79], 0, v[136:137]
	v_lshlrev_b32_e32 v136, 1, v160
	v_cvt_pk_bf16_f32 v74, v70, v71
	v_cvt_pk_bf16_f32 v75, v72, v73
	v_cvt_pk_bf16_f32 v76, v66, v67
	v_cvt_pk_bf16_f32 v77, v68, v69
	v_lshl_add_u64 v[78:79], v[78:79], 0, v[136:137]
	global_store_dwordx4 v[78:79], v[74:77], off offset:512 sc0 sc1

; __device__ __forceinline__ float silu_f(float v) { return v * fast_sigmoid(v); }
; __device__ __forceinline__ u32x4 pack8(const f32x4 v0, const f32x4 v1) { u32x4 w; w.x = pk_f16(v0[0], v0[1]); w.y = pk_f16(v0[2], v0[3]); w.z = pk_f16(v1[0], v1[1]); w.w = pk_f16(v1[2], v1[3]); return w; }
;     __device__ __forceinline__ void operator()(AccRef acc, const Unit& u, int wr, int wc, int fr, int fq) const {
;     ...
;                 for (int bj = 0; bj < 2; ++bj) { const int col = col0 + bj * HALF; f32x4 v0 = acc[ai][bj][m][0], v1 = acc[ai][bj][m][1];
;                     if (u.pn < 4) { *(u32x4*)(upool + (size_t)row * PW + col) = pack8(v0, v1); }
;                     else if (u.pn < 8) { const int cs = col - PW, gg = cs >> 4, hh = cs & 15, lc = row >> 5, s = row & 31;
;                         *(u32x4*)(X + (size_t)gg * XGS + (size_t)lc * XK + 256 + s * 16 + hh) = pack8(v0, v1); }
;                     else {
; #pragma unroll
;                         for (int j = 0; j < 4; ++j) { v0[j] = silu_f(v0[j]); v1[j] = silu_f(v1[j]); }
;                         *(u32x4*)(zs + (size_t)row * D + (col - PW - SW)) = pack8(v0, v1); } } }
.LBB0_383:
	s_cmp_lt_u32 s36, 8
	s_cbranch_scc1 .LBB0_385
	v_mul_f32_e32 v73, 0xbfb8aa3b, v58
	v_mul_f32_e32 v74, 0xbfb8aa3b, v63
	v_exp_f32_e32 v73, v73
	v_exp_f32_e32 v74, v74
	v_mul_f32_e32 v75, 0xbfb8aa3b, v59
	v_exp_f32_e32 v75, v75
	v_add_f32_e32 v73, 1.0, v73
	v_add_f32_e32 v74, 1.0, v74
	v_rcp_f32_e32 v73, v73
	v_rcp_f32_e32 v74, v74
	v_mul_f32_e32 v72, 0xbfb8aa3b, v62
	v_mul_f32_e32 v77, 0xbfb8aa3b, v60
	v_mul_f32_e32 v76, v58, v73
	v_mul_f32_e32 v73, v63, v74
	v_add_f32_e32 v74, 1.0, v75
	v_mul_f32_e32 v75, 0xbfb8aa3b, v64
	v_mul_f32_e32 v78, 0xbfb8aa3b, v65
	v_mul_f32_e32 v79, 0xbfb8aa3b, v61
	v_exp_f32_e32 v72, v72
	v_exp_f32_e32 v75, v75
	v_exp_f32_e32 v77, v77
	v_exp_f32_e32 v78, v78
	v_exp_f32_e32 v79, v79
	v_add_f32_e32 v72, 1.0, v72
	v_add_f32_e32 v75, 1.0, v75
	v_add_f32_e32 v77, 1.0, v77
	v_add_f32_e32 v78, 1.0, v78
	v_add_f32_e32 v79, 1.0, v79
	v_rcp_f32_e32 v72, v72
	v_rcp_f32_e32 v74, v74
	v_rcp_f32_e32 v75, v75
	v_rcp_f32_e32 v77, v77
	v_rcp_f32_e32 v78, v78
	v_rcp_f32_e32 v79, v79
	v_mul_f32_e32 v72, v62, v72
	v_mul_f32_e32 v74, v59, v74
	v_mul_f32_e32 v75, v64, v75
	v_mul_f32_e32 v77, v60, v77
	v_mul_f32_e32 v78, v65, v78
	v_mul_f32_e32 v79, v61, v79
	v_cvt_pk_bf16_f32 v72, v72, v73
	v_cvt_pk_bf16_f32 v73, v75, v78
	v_cvt_pk_bf16_f32 v74, v76, v74
	v_cvt_pk_bf16_f32 v75, v77, v79
	v_lshl_add_u64 v[76:77], s[26:27], 0, v[68:69]
	v_lshl_add_u64 v[76:77], v[144:145], 1, v[76:77]
	s_mov_b64 s[20:21], 0
	global_store_dwordx4 v[76:77], v[72:75], off offset:-4096 sc0 sc1
.LBB0_385:
	s_andn2_b64 vcc, exec, s[20:21]
	s_cbranch_vccnz .LBB0_387
	v_add_u32_e32 v72, 0xfffffc00, v144
	v_ashrrev_i32_e32 v78, 4, v72
	v_mov_b64_e32 v[76:77], s[8:9]
	v_mad_i64_i32 v[76:77], s[18:19], v78, s88, v[76:77]
	v_lshl_add_u64 v[76:77], v[76:77], 0, v[66:67]
	v_lshlrev_b32_e32 v136, 1, v161
	v_lshl_add_u64 v[76:77], v[76:77], 0, v[136:137]
	v_lshlrev_b32_e32 v136, 1, v160
	v_cvt_pk_bf16_f32 v72, v62, v63
	v_cvt_pk_bf16_f32 v73, v64, v65
	v_cvt_pk_bf16_f32 v74, v58, v59
	v_cvt_pk_bf16_f32 v75, v60, v61
	v_lshl_add_u64 v[76:77], v[76:77], 0, v[136:137]
	global_store_dwordx4 v[76:77], v[72:75], off offset:512 sc0 sc1

; __device__ __forceinline__ float silu_f(float v) { return v * fast_sigmoid(v); }
; __device__ __forceinline__ u32x4 pack8(const f32x4 v0, const f32x4 v1) { u32x4 w; w.x = pk_f16(v0[0], v0[1]); w.y = pk_f16(v0[2], v0[3]); w.z = pk_f16(v1[0], v1[1]); w.w = pk_f16(v1[2], v1[3]); return w; }
;     __device__ __forceinline__ void operator()(AccRef acc, const Unit& u, int wr, int wc, int fr, int fq) const {
;     ...
;                 for (int bj = 0; bj < 2; ++bj) { const int col = col0 + bj * HALF; f32x4 v0 = acc[ai][bj][m][0], v1 = acc[ai][bj][m][1];
;                     if (u.pn < 4) { *(u32x4*)(upool + (size_t)row * PW + col) = pack8(v0, v1); }
;                     else if (u.pn < 8) { const int cs = col - PW, gg = cs >> 4, hh = cs & 15, lc = row >> 5, s = row & 31;
;                         *(u32x4*)(X + (size_t)gg * XGS + (size_t)lc * XK + 256 + s * 16 + hh) = pack8(v0, v1); }
;                     else {
; #pragma unroll
;                         for (int j = 0; j < 4; ++j) { v0[j] = silu_f(v0[j]); v1[j] = silu_f(v1[j]); }
;                         *(u32x4*)(zs + (size_t)row * D + (col - PW - SW)) = pack8(v0, v1); } } }
.LBB0_388:
	v_cvt_pk_bf16_f32 v62, v62, v63
	v_cvt_pk_bf16_f32 v63, v64, v65
	v_cvt_pk_bf16_f32 v64, v58, v59
	v_cvt_pk_bf16_f32 v65, v60, v61
	v_lshl_add_u64 v[58:59], v[144:145], 1, v[70:71]
	global_store_dwordx4 v[58:59], v[62:65], off sc0 sc1
	s_and_b64 vcc, exec, s[4:5]
	s_mov_b64 s[20:21], -1
	s_cbranch_vccnz .LBB0_333
.LBB0_389:
	s_cmp_lt_u32 s36, 8
	s_cbranch_scc1 .LBB0_391
	v_mul_f32_e32 v59, 0xbfb8aa3b, v50
	v_mul_f32_e32 v60, 0xbfb8aa3b, v55
	v_exp_f32_e32 v59, v59
	v_exp_f32_e32 v60, v60
	v_mul_f32_e32 v61, 0xbfb8aa3b, v51
	v_exp_f32_e32 v61, v61
	v_add_f32_e32 v59, 1.0, v59
	v_add_f32_e32 v60, 1.0, v60
	v_rcp_f32_e32 v59, v59
	v_rcp_f32_e32 v60, v60
	v_mul_f32_e32 v58, 0xbfb8aa3b, v54
	v_mul_f32_e32 v63, 0xbfb8aa3b, v52
	v_mul_f32_e32 v62, v50, v59
	v_mul_f32_e32 v59, v55, v60
	v_add_f32_e32 v60, 1.0, v61
	v_mul_f32_e32 v61, 0xbfb8aa3b, v56
	v_mul_f32_e32 v64, 0xbfb8aa3b, v57
	v_mul_f32_e32 v65, 0xbfb8aa3b, v53
	v_exp_f32_e32 v58, v58
	v_exp_f32_e32 v61, v61
	v_exp_f32_e32 v63, v63
	v_exp_f32_e32 v64, v64
	v_exp_f32_e32 v65, v65
	v_add_f32_e32 v58, 1.0, v58
	v_add_f32_e32 v61, 1.0, v61
	v_add_f32_e32 v63, 1.0, v63
	v_add_f32_e32 v64, 1.0, v64
	v_add_f32_e32 v65, 1.0, v65
	v_rcp_f32_e32 v58, v58
	v_rcp_f32_e32 v60, v60
	v_rcp_f32_e32 v61, v61
	v_rcp_f32_e32 v63, v63
	v_rcp_f32_e32 v64, v64
	v_rcp_f32_e32 v65, v65
	v_mul_f32_e32 v58, v54, v58
	v_mul_f32_e32 v60, v51, v60
	v_mul_f32_e32 v61, v56, v61
	v_mul_f32_e32 v63, v52, v63
	v_mul_f32_e32 v64, v57, v64
	v_mul_f32_e32 v65, v53, v65
	v_cvt_pk_bf16_f32 v58, v58, v59
	v_cvt_pk_bf16_f32 v59, v61, v64
	v_cvt_pk_bf16_f32 v60, v62, v60
	v_cvt_pk_bf16_f32 v61, v63, v65
	v_lshl_add_u64 v[62:63], s[26:27], 0, v[68:69]
	v_lshl_add_u64 v[62:63], v[144:145], 1, v[62:63]
	s_mov_b64 s[20:21], 0
	global_store_dwordx4 v[62:63], v[58:61], off offset:-3840 sc0 sc1
.LBB0_391:
	s_andn2_b64 vcc, exec, s[20:21]
	s_cbranch_vccnz .LBB0_393
	v_add_u32_e32 v58, 0xfffffc80, v144
	v_ashrrev_i32_e32 v64, 4, v58
	v_mov_b64_e32 v[62:63], s[8:9]
	v_mad_i64_i32 v[62:63], s[18:19], v64, s88, v[62:63]
	v_lshl_add_u64 v[62:63], v[62:63], 0, v[66:67]
	v_lshlrev_b32_e32 v136, 1, v161
	v_lshl_add_u64 v[62:63], v[62:63], 0, v[136:137]
	v_lshlrev_b32_e32 v136, 1, v160
	v_cvt_pk_bf16_f32 v58, v54, v55
	v_cvt_pk_bf16_f32 v59, v56, v57
	v_cvt_pk_bf16_f32 v60, v50, v51
	v_cvt_pk_bf16_f32 v61, v52, v53
	v_lshl_add_u64 v[62:63], v[62:63], 0, v[136:137]
	global_store_dwordx4 v[62:63], v[58:61], off offset:512 sc0 sc1

; __device__ __forceinline__ float silu_f(float v) { return v * fast_sigmoid(v); }
; __device__ __forceinline__ u32x4 pack8(const f32x4 v0, const f32x4 v1) { u32x4 w; w.x = pk_f16(v0[0], v0[1]); w.y = pk_f16(v0[2], v0[3]); w.z = pk_f16(v1[0], v1[1]); w.w = pk_f16(v1[2], v1[3]); return w; }
;     __device__ __forceinline__ void operator()(AccRef acc, const Unit& u, int wr, int wc, int fr, int fq) const {
;     ...
;                 for (int bj = 0; bj < 2; ++bj) { const int col = col0 + bj * HALF; f32x4 v0 = acc[ai][bj][m][0], v1 = acc[ai][bj][m][1];
;                     if (u.pn < 4) { *(u32x4*)(upool + (size_t)row * PW + col) = pack8(v0, v1); }
;                     else if (u.pn < 8) { const int cs = col - PW, gg = cs >> 4, hh = cs & 15, lc = row >> 5, s = row & 31;
;                         *(u32x4*)(X + (size_t)gg * XGS + (size_t)lc * XK + 256 + s * 16 + hh) = pack8(v0, v1); }
;                     else {
; #pragma unroll
;                         for (int j = 0; j < 4; ++j) { v0[j] = silu_f(v0[j]); v1[j] = silu_f(v1[j]); }
;                         *(u32x4*)(zs + (size_t)row * D + (col - PW - SW)) = pack8(v0, v1); } } }
.LBB0_394:
	s_cmp_lt_u32 s36, 8
	s_cbranch_scc1 .LBB0_396
	v_mul_f32_e32 v58, 0xbfb8aa3b, v42
	v_mul_f32_e32 v59, 0xbfb8aa3b, v47
	v_exp_f32_e32 v58, v58
	v_exp_f32_e32 v59, v59
	v_mul_f32_e32 v60, 0xbfb8aa3b, v43
	v_exp_f32_e32 v60, v60
	v_add_f32_e32 v58, 1.0, v58
	v_add_f32_e32 v59, 1.0, v59
	v_rcp_f32_e32 v58, v58
	v_rcp_f32_e32 v59, v59
	v_mul_f32_e32 v62, 0xbfb8aa3b, v44
	v_exp_f32_e32 v62, v62
	v_mul_f32_e32 v61, v42, v58
	v_mul_f32_e32 v58, v47, v59
	v_add_f32_e32 v59, 1.0, v60
	v_mul_f32_e32 v60, 0xbfb8aa3b, v48
	v_rcp_f32_e32 v59, v59
	v_exp_f32_e32 v60, v60
	v_mul_f32_e32 v64, 0xbfb8aa3b, v45
	v_mul_f32_e32 v57, 0xbfb8aa3b, v46
	v_mul_f32_e32 v63, v43, v59
	v_add_f32_e32 v59, 1.0, v60
	v_add_f32_e32 v60, 1.0, v62
	v_mul_f32_e32 v62, 0xbfb8aa3b, v49
	v_exp_f32_e32 v62, v62
	v_exp_f32_e32 v64, v64
	v_exp_f32_e32 v57, v57
	v_rcp_f32_e32 v59, v59
	v_add_f32_e32 v62, 1.0, v62
	v_add_f32_e32 v64, 1.0, v64
	v_add_f32_e32 v57, 1.0, v57
	v_rcp_f32_e32 v60, v60
	v_rcp_f32_e32 v62, v62
	v_rcp_f32_e32 v64, v64
	v_rcp_f32_e32 v57, v57
	v_mul_f32_e32 v59, v48, v59
	v_mul_f32_e32 v65, v44, v60
	v_mul_f32_e32 v60, v49, v62
	v_mul_f32_e32 v62, v45, v64
	v_mul_f32_e32 v57, v46, v57
	v_cvt_pk_bf16_f32 v59, v59, v60
	v_cvt_pk_bf16_f32 v60, v61, v63
	v_cvt_pk_bf16_f32 v61, v65, v62
	v_lshl_add_u64 v[62:63], s[26:27], 0, v[52:53]
	v_cvt_pk_bf16_f32 v58, v57, v58
	v_lshl_add_u64 v[62:63], v[144:145], 1, v[62:63]
	s_mov_b64 s[20:21], 0
	global_store_dwordx4 v[62:63], v[58:61], off offset:-4096 sc0 sc1
.LBB0_396:
	s_andn2_b64 vcc, exec, s[20:21]
	s_cbranch_vccnz .LBB0_398
	v_add_u32_e32 v57, 0xfffffc00, v144
	v_ashrrev_i32_e32 v57, 4, v57
	v_mov_b64_e32 v[62:63], s[8:9]
	v_mad_i64_i32 v[62:63], s[18:19], v57, s88, v[62:63]
	v_lshl_add_u64 v[62:63], v[62:63], 0, v[50:51]
	v_lshlrev_b32_e32 v136, 1, v56
	v_lshl_add_u64 v[62:63], v[62:63], 0, v[136:137]
	v_lshlrev_b32_e32 v136, 1, v160
	v_cvt_pk_bf16_f32 v58, v46, v47
	v_cvt_pk_bf16_f32 v59, v48, v49
	v_cvt_pk_bf16_f32 v60, v42, v43
	v_cvt_pk_bf16_f32 v61, v44, v45
	v_lshl_add_u64 v[62:63], v[62:63], 0, v[136:137]
	global_store_dwordx4 v[62:63], v[58:61], off offset:512 sc0 sc1

; __device__ __forceinline__ float silu_f(float v) { return v * fast_sigmoid(v); }
; __device__ __forceinline__ u32x4 pack8(const f32x4 v0, const f32x4 v1) { u32x4 w; w.x = pk_f16(v0[0], v0[1]); w.y = pk_f16(v0[2], v0[3]); w.z = pk_f16(v1[0], v1[1]); w.w = pk_f16(v1[2], v1[3]); return w; }
;     __device__ __forceinline__ void operator()(AccRef acc, const Unit& u, int wr, int wc, int fr, int fq) const {
;     ...
;                 for (int bj = 0; bj < 2; ++bj) { const int col = col0 + bj * HALF; f32x4 v0 = acc[ai][bj][m][0], v1 = acc[ai][bj][m][1];
;                     if (u.pn < 4) { *(u32x4*)(upool + (size_t)row * PW + col) = pack8(v0, v1); }
;                     else if (u.pn < 8) { const int cs = col - PW, gg = cs >> 4, hh = cs & 15, lc = row >> 5, s = row & 31;
;                         *(u32x4*)(X + (size_t)gg * XGS + (size_t)lc * XK + 256 + s * 16 + hh) = pack8(v0, v1); }
;                     else {
; #pragma unroll
;                         for (int j = 0; j < 4; ++j) { v0[j] = silu_f(v0[j]); v1[j] = silu_f(v1[j]); }
;                         *(u32x4*)(zs + (size_t)row * D + (col - PW - SW)) = pack8(v0, v1); } } }
.LBB0_399:
	v_cvt_pk_bf16_f32 v46, v46, v47
	v_cvt_pk_bf16_f32 v47, v48, v49
	v_cvt_pk_bf16_f32 v48, v42, v43
	v_cvt_pk_bf16_f32 v49, v44, v45
	v_lshl_add_u64 v[42:43], v[144:145], 1, v[54:55]
	global_store_dwordx4 v[42:43], v[46:49], off sc0 sc1
	s_and_b64 vcc, exec, s[4:5]
	s_mov_b64 s[20:21], -1
	s_cbranch_vccnz .LBB0_338
.LBB0_400:
	s_cmp_lt_u32 s36, 8
	s_cbranch_scc1 .LBB0_402
	v_mul_f32_e32 v43, 0xbfb8aa3b, v34
	v_mul_f32_e32 v44, 0xbfb8aa3b, v39
	v_exp_f32_e32 v43, v43
	v_exp_f32_e32 v44, v44
	v_mul_f32_e32 v45, 0xbfb8aa3b, v35
	v_exp_f32_e32 v45, v45
	v_add_f32_e32 v43, 1.0, v43
	v_add_f32_e32 v44, 1.0, v44
	v_rcp_f32_e32 v43, v43
	v_rcp_f32_e32 v44, v44
	v_mul_f32_e32 v42, 0xbfb8aa3b, v38
	v_mul_f32_e32 v47, 0xbfb8aa3b, v36
	v_mul_f32_e32 v46, v34, v43
	v_mul_f32_e32 v43, v39, v44
	v_add_f32_e32 v44, 1.0, v45
	v_mul_f32_e32 v45, 0xbfb8aa3b, v40
	v_mul_f32_e32 v48, 0xbfb8aa3b, v41
	v_mul_f32_e32 v49, 0xbfb8aa3b, v37
	v_exp_f32_e32 v42, v42
	v_exp_f32_e32 v45, v45
	v_exp_f32_e32 v47, v47
	v_exp_f32_e32 v48, v48
	v_exp_f32_e32 v49, v49
	v_add_f32_e32 v42, 1.0, v42
	v_add_f32_e32 v45, 1.0, v45
	v_add_f32_e32 v47, 1.0, v47
	v_add_f32_e32 v48, 1.0, v48
	v_add_f32_e32 v49, 1.0, v49
	v_rcp_f32_e32 v42, v42
	v_rcp_f32_e32 v44, v44
	v_rcp_f32_e32 v45, v45
	v_rcp_f32_e32 v47, v47
	v_rcp_f32_e32 v48, v48
	v_rcp_f32_e32 v49, v49
	v_mul_f32_e32 v42, v38, v42
	v_mul_f32_e32 v44, v35, v44
	v_mul_f32_e32 v45, v40, v45
	v_mul_f32_e32 v47, v36, v47
	v_mul_f32_e32 v48, v41, v48
	v_mul_f32_e32 v49, v37, v49
	v_cvt_pk_bf16_f32 v42, v42, v43
	v_cvt_pk_bf16_f32 v43, v45, v48
	v_cvt_pk_bf16_f32 v44, v46, v44
	v_cvt_pk_bf16_f32 v45, v47, v49
	v_lshl_add_u64 v[46:47], s[26:27], 0, v[52:53]
	v_lshl_add_u64 v[46:47], v[144:145], 1, v[46:47]
	s_mov_b64 s[20:21], 0
	global_store_dwordx4 v[46:47], v[42:45], off offset:-3840 sc0 sc1
.LBB0_402:
	s_andn2_b64 vcc, exec, s[20:21]
	s_cbranch_vccnz .LBB0_404
	v_add_u32_e32 v42, 0xfffffc80, v144
	v_ashrrev_i32_e32 v48, 4, v42
	v_mov_b64_e32 v[46:47], s[8:9]
	v_mad_i64_i32 v[46:47], s[18:19], v48, s88, v[46:47]
	v_lshl_add_u64 v[46:47], v[46:47], 0, v[50:51]
	v_lshlrev_b32_e32 v136, 1, v56
	v_lshl_add_u64 v[46:47], v[46:47], 0, v[136:137]
	v_lshlrev_b32_e32 v136, 1, v160
	v_cvt_pk_bf16_f32 v42, v38, v39
	v_cvt_pk_bf16_f32 v43, v40, v41
	v_cvt_pk_bf16_f32 v44, v34, v35
	v_cvt_pk_bf16_f32 v45, v36, v37
	v_lshl_add_u64 v[46:47], v[46:47], 0, v[136:137]
	global_store_dwordx4 v[46:47], v[42:45], off offset:512 sc0 sc1

; __device__ __forceinline__ float silu_f(float v) { return v * fast_sigmoid(v); }
; __device__ __forceinline__ u32x4 pack8(const f32x4 v0, const f32x4 v1) { u32x4 w; w.x = pk_f16(v0[0], v0[1]); w.y = pk_f16(v0[2], v0[3]); w.z = pk_f16(v1[0], v1[1]); w.w = pk_f16(v1[2], v1[3]); return w; }
;     __device__ __forceinline__ void operator()(AccRef acc, const Unit& u, int wr, int wc, int fr, int fq) const {
;     ...
;                 for (int bj = 0; bj < 2; ++bj) { const int col = col0 + bj * HALF; f32x4 v0 = acc[ai][bj][m][0], v1 = acc[ai][bj][m][1];
;                     if (u.pn < 4) { *(u32x4*)(upool + (size_t)row * PW + col) = pack8(v0, v1); }
;                     else if (u.pn < 8) { const int cs = col - PW, gg = cs >> 4, hh = cs & 15, lc = row >> 5, s = row & 31;
;                         *(u32x4*)(X + (size_t)gg * XGS + (size_t)lc * XK + 256 + s * 16 + hh) = pack8(v0, v1); }
;                     else {
; #pragma unroll
;                         for (int j = 0; j < 4; ++j) { v0[j] = silu_f(v0[j]); v1[j] = silu_f(v1[j]); }
;                         *(u32x4*)(zs + (size_t)row * D + (col - PW - SW)) = pack8(v0, v1); } } }
.LBB0_405:
	s_cmp_lt_u32 s36, 8
	s_cbranch_scc1 .LBB0_407
	v_mul_f32_e32 v41, 0xbfb8aa3b, v26
	v_mul_f32_e32 v42, 0xbfb8aa3b, v31
	v_exp_f32_e32 v41, v41
	v_exp_f32_e32 v42, v42
	v_mul_f32_e32 v43, 0xbfb8aa3b, v27
	v_exp_f32_e32 v43, v43
	v_add_f32_e32 v41, 1.0, v41
	v_add_f32_e32 v42, 1.0, v42
	v_rcp_f32_e32 v41, v41
	v_rcp_f32_e32 v42, v42
	v_mul_f32_e32 v40, 0xbfb8aa3b, v30
	v_mul_f32_e32 v45, 0xbfb8aa3b, v28
	v_mul_f32_e32 v44, v26, v41
	v_mul_f32_e32 v41, v31, v42
	v_add_f32_e32 v42, 1.0, v43
	v_mul_f32_e32 v43, 0xbfb8aa3b, v32
	v_mul_f32_e32 v46, 0xbfb8aa3b, v33
	v_mul_f32_e32 v47, 0xbfb8aa3b, v29
	v_exp_f32_e32 v40, v40
	v_exp_f32_e32 v43, v43
	v_exp_f32_e32 v45, v45
	v_exp_f32_e32 v46, v46
	v_exp_f32_e32 v47, v47
	v_add_f32_e32 v40, 1.0, v40
	v_add_f32_e32 v43, 1.0, v43
	v_add_f32_e32 v45, 1.0, v45
	v_add_f32_e32 v46, 1.0, v46
	v_add_f32_e32 v47, 1.0, v47
	v_rcp_f32_e32 v40, v40
	v_rcp_f32_e32 v42, v42
	v_rcp_f32_e32 v43, v43
	v_rcp_f32_e32 v45, v45
	v_rcp_f32_e32 v46, v46
	v_rcp_f32_e32 v47, v47
	v_mul_f32_e32 v40, v30, v40
	v_mul_f32_e32 v42, v27, v42
	v_mul_f32_e32 v43, v32, v43
	v_mul_f32_e32 v45, v28, v45
	v_mul_f32_e32 v46, v33, v46
	v_mul_f32_e32 v47, v29, v47
	v_cvt_pk_bf16_f32 v40, v40, v41
	v_cvt_pk_bf16_f32 v41, v43, v46
	v_cvt_pk_bf16_f32 v42, v44, v42
	v_cvt_pk_bf16_f32 v43, v45, v47
	v_lshl_add_u64 v[44:45], s[26:27], 0, v[36:37]
	v_lshl_add_u64 v[44:45], v[144:145], 1, v[44:45]
	s_mov_b64 s[20:21], 0
	global_store_dwordx4 v[44:45], v[40:43], off offset:-4096 sc0 sc1
.LBB0_407:
	s_andn2_b64 vcc, exec, s[20:21]
	s_cbranch_vccnz .LBB0_409
	v_add_u32_e32 v40, 0xfffffc00, v144
	v_ashrrev_i32_e32 v46, 4, v40
	v_mov_b64_e32 v[44:45], s[8:9]
	v_mad_i64_i32 v[44:45], s[18:19], v46, s88, v[44:45]
	v_lshl_add_u64 v[44:45], v[44:45], 0, v[34:35]
	v_lshlrev_b32_e32 v136, 1, v161
	v_lshl_add_u64 v[44:45], v[44:45], 0, v[136:137]
	v_lshlrev_b32_e32 v136, 1, v160
	v_cvt_pk_bf16_f32 v40, v30, v31
	v_cvt_pk_bf16_f32 v41, v32, v33
	v_cvt_pk_bf16_f32 v42, v26, v27
	v_cvt_pk_bf16_f32 v43, v28, v29
	v_lshl_add_u64 v[44:45], v[44:45], 0, v[136:137]
	global_store_dwordx4 v[44:45], v[40:43], off offset:512 sc0 sc1

; __device__ __forceinline__ float silu_f(float v) { return v * fast_sigmoid(v); }
; __device__ __forceinline__ u32x4 pack8(const f32x4 v0, const f32x4 v1) { u32x4 w; w.x = pk_f16(v0[0], v0[1]); w.y = pk_f16(v0[2], v0[3]); w.z = pk_f16(v1[0], v1[1]); w.w = pk_f16(v1[2], v1[3]); return w; }
;     __device__ __forceinline__ void operator()(AccRef acc, const Unit& u, int wr, int wc, int fr, int fq) const {
;     ...
;                 for (int bj = 0; bj < 2; ++bj) { const int col = col0 + bj * HALF; f32x4 v0 = acc[ai][bj][m][0], v1 = acc[ai][bj][m][1];
;                     if (u.pn < 4) { *(u32x4*)(upool + (size_t)row * PW + col) = pack8(v0, v1); }
;                     else if (u.pn < 8) { const int cs = col - PW, gg = cs >> 4, hh = cs & 15, lc = row >> 5, s = row & 31;
;                         *(u32x4*)(X + (size_t)gg * XGS + (size_t)lc * XK + 256 + s * 16 + hh) = pack8(v0, v1); }
;                     else {
; #pragma unroll
;                         for (int j = 0; j < 4; ++j) { v0[j] = silu_f(v0[j]); v1[j] = silu_f(v1[j]); }
;                         *(u32x4*)(zs + (size_t)row * D + (col - PW - SW)) = pack8(v0, v1); } } }
.LBB0_410:
	v_cvt_pk_bf16_f32 v30, v30, v31
	v_cvt_pk_bf16_f32 v31, v32, v33
	v_cvt_pk_bf16_f32 v32, v26, v27
	v_cvt_pk_bf16_f32 v33, v28, v29
	v_lshl_add_u64 v[26:27], v[144:145], 1, v[38:39]
	global_store_dwordx4 v[26:27], v[30:33], off sc0 sc1
	s_and_b64 vcc, exec, s[4:5]
	s_mov_b64 s[20:21], -1
	s_cbranch_vccnz .LBB0_343
.LBB0_411:
	s_cmp_lt_u32 s36, 8
	s_cbranch_scc1 .LBB0_413
	v_mul_f32_e32 v27, 0xbfb8aa3b, v18
	v_mul_f32_e32 v28, 0xbfb8aa3b, v23
	v_exp_f32_e32 v27, v27
	v_exp_f32_e32 v28, v28
	v_mul_f32_e32 v29, 0xbfb8aa3b, v19
	v_exp_f32_e32 v29, v29
	v_add_f32_e32 v27, 1.0, v27
	v_add_f32_e32 v28, 1.0, v28
	v_rcp_f32_e32 v27, v27
	v_rcp_f32_e32 v28, v28
	v_mul_f32_e32 v26, 0xbfb8aa3b, v22
	v_mul_f32_e32 v31, 0xbfb8aa3b, v20
	v_mul_f32_e32 v30, v18, v27
	v_mul_f32_e32 v27, v23, v28
	v_add_f32_e32 v28, 1.0, v29
	v_mul_f32_e32 v29, 0xbfb8aa3b, v24
	v_mul_f32_e32 v32, 0xbfb8aa3b, v25
	v_mul_f32_e32 v33, 0xbfb8aa3b, v21
	v_exp_f32_e32 v26, v26
	v_exp_f32_e32 v29, v29
	v_exp_f32_e32 v31, v31
	v_exp_f32_e32 v32, v32
	v_exp_f32_e32 v33, v33
	v_add_f32_e32 v26, 1.0, v26
	v_add_f32_e32 v29, 1.0, v29
	v_add_f32_e32 v31, 1.0, v31
	v_add_f32_e32 v32, 1.0, v32
	v_add_f32_e32 v33, 1.0, v33
	v_rcp_f32_e32 v26, v26
	v_rcp_f32_e32 v28, v28
	v_rcp_f32_e32 v29, v29
	v_rcp_f32_e32 v31, v31
	v_rcp_f32_e32 v32, v32
	v_rcp_f32_e32 v33, v33
	v_mul_f32_e32 v26, v22, v26
	v_mul_f32_e32 v28, v19, v28
	v_mul_f32_e32 v29, v24, v29
	v_mul_f32_e32 v31, v20, v31
	v_mul_f32_e32 v32, v25, v32
	v_mul_f32_e32 v33, v21, v33
	v_cvt_pk_bf16_f32 v26, v26, v27
	v_cvt_pk_bf16_f32 v27, v29, v32
	v_cvt_pk_bf16_f32 v28, v30, v28
	v_cvt_pk_bf16_f32 v29, v31, v33
	v_lshl_add_u64 v[30:31], s[26:27], 0, v[36:37]
	v_lshl_add_u64 v[30:31], v[144:145], 1, v[30:31]
	s_mov_b64 s[20:21], 0
	global_store_dwordx4 v[30:31], v[26:29], off offset:-3840 sc0 sc1
.LBB0_413:
	s_andn2_b64 vcc, exec, s[20:21]
	s_cbranch_vccnz .LBB0_415
	v_add_u32_e32 v26, 0xfffffc80, v144
	v_ashrrev_i32_e32 v32, 4, v26
	v_mov_b64_e32 v[30:31], s[8:9]
	v_mad_i64_i32 v[30:31], s[18:19], v32, s88, v[30:31]
	v_lshl_add_u64 v[30:31], v[30:31], 0, v[34:35]
	v_lshlrev_b32_e32 v136, 1, v161
	v_lshl_add_u64 v[30:31], v[30:31], 0, v[136:137]
	v_lshlrev_b32_e32 v136, 1, v160
	v_cvt_pk_bf16_f32 v26, v22, v23
	v_cvt_pk_bf16_f32 v27, v24, v25
	v_cvt_pk_bf16_f32 v28, v18, v19
	v_cvt_pk_bf16_f32 v29, v20, v21
	v_lshl_add_u64 v[30:31], v[30:31], 0, v[136:137]
	global_store_dwordx4 v[30:31], v[26:29], off offset:512 sc0 sc1

; __device__ __forceinline__ float silu_f(float v) { return v * fast_sigmoid(v); }
; __device__ __forceinline__ u32x4 pack8(const f32x4 v0, const f32x4 v1) { u32x4 w; w.x = pk_f16(v0[0], v0[1]); w.y = pk_f16(v0[2], v0[3]); w.z = pk_f16(v1[0], v1[1]); w.w = pk_f16(v1[2], v1[3]); return w; }
;     __device__ __forceinline__ void operator()(AccRef acc, const Unit& u, int wr, int wc, int fr, int fq) const {
;     ...
;                 for (int bj = 0; bj < 2; ++bj) { const int col = col0 + bj * HALF; f32x4 v0 = acc[ai][bj][m][0], v1 = acc[ai][bj][m][1];
;                     if (u.pn < 4) { *(u32x4*)(upool + (size_t)row * PW + col) = pack8(v0, v1); }
;                     else if (u.pn < 8) { const int cs = col - PW, gg = cs >> 4, hh = cs & 15, lc = row >> 5, s = row & 31;
;                         *(u32x4*)(X + (size_t)gg * XGS + (size_t)lc * XK + 256 + s * 16 + hh) = pack8(v0, v1); }
;                     else {
; #pragma unroll
;                         for (int j = 0; j < 4; ++j) { v0[j] = silu_f(v0[j]); v1[j] = silu_f(v1[j]); }
;                         *(u32x4*)(zs + (size_t)row * D + (col - PW - SW)) = pack8(v0, v1); } } }
.LBB0_416:
	s_cmp_lt_u32 s36, 8
	s_cbranch_scc1 .LBB0_418
	v_mul_f32_e32 v26, 0xbfb8aa3b, v10
	v_mul_f32_e32 v27, 0xbfb8aa3b, v15
	v_exp_f32_e32 v26, v26
	v_exp_f32_e32 v27, v27
	v_mul_f32_e32 v28, 0xbfb8aa3b, v11
	v_exp_f32_e32 v28, v28
	v_add_f32_e32 v26, 1.0, v26
	v_add_f32_e32 v27, 1.0, v27
	v_rcp_f32_e32 v26, v26
	v_rcp_f32_e32 v27, v27
	v_mul_f32_e32 v30, 0xbfb8aa3b, v12
	v_exp_f32_e32 v30, v30
	v_mul_f32_e32 v29, v10, v26
	v_mul_f32_e32 v26, v15, v27
	v_add_f32_e32 v27, 1.0, v28
	v_mul_f32_e32 v28, 0xbfb8aa3b, v16
	v_rcp_f32_e32 v27, v27
	v_exp_f32_e32 v28, v28
	v_mul_f32_e32 v32, 0xbfb8aa3b, v13
	v_mul_f32_e32 v25, 0xbfb8aa3b, v14
	v_mul_f32_e32 v31, v11, v27
	v_add_f32_e32 v27, 1.0, v28
	v_add_f32_e32 v28, 1.0, v30
	v_mul_f32_e32 v30, 0xbfb8aa3b, v17
	v_exp_f32_e32 v30, v30
	v_exp_f32_e32 v32, v32
	v_exp_f32_e32 v25, v25
	v_rcp_f32_e32 v27, v27
	v_add_f32_e32 v30, 1.0, v30
	v_add_f32_e32 v32, 1.0, v32
	v_add_f32_e32 v25, 1.0, v25
	v_rcp_f32_e32 v28, v28
	v_rcp_f32_e32 v30, v30
	v_rcp_f32_e32 v32, v32
	v_rcp_f32_e32 v25, v25
	v_mul_f32_e32 v27, v16, v27
	v_mul_f32_e32 v33, v12, v28
	v_mul_f32_e32 v28, v17, v30
	v_mul_f32_e32 v30, v13, v32
	v_mul_f32_e32 v25, v14, v25
	v_cvt_pk_bf16_f32 v27, v27, v28
	v_cvt_pk_bf16_f32 v28, v29, v31
	v_cvt_pk_bf16_f32 v29, v33, v30
	v_lshl_add_u64 v[30:31], s[26:27], 0, v[20:21]
	v_cvt_pk_bf16_f32 v26, v25, v26
	v_lshl_add_u64 v[30:31], v[144:145], 1, v[30:31]
	s_mov_b64 s[20:21], 0
	global_store_dwordx4 v[30:31], v[26:29], off offset:-4096 sc0 sc1
.LBB0_418:
	s_andn2_b64 vcc, exec, s[20:21]
	s_cbranch_vccnz .LBB0_420
	v_add_u32_e32 v25, 0xfffffc00, v144
	v_ashrrev_i32_e32 v25, 4, v25
	v_mov_b64_e32 v[30:31], s[8:9]
	v_mad_i64_i32 v[30:31], s[18:19], v25, s88, v[30:31]
	v_lshl_add_u64 v[30:31], v[30:31], 0, v[18:19]
	v_lshlrev_b32_e32 v136, 1, v24
	v_lshl_add_u64 v[30:31], v[30:31], 0, v[136:137]
	v_lshlrev_b32_e32 v136, 1, v160
	v_cvt_pk_bf16_f32 v26, v14, v15
	v_cvt_pk_bf16_f32 v27, v16, v17
	v_cvt_pk_bf16_f32 v28, v10, v11
	v_cvt_pk_bf16_f32 v29, v12, v13
	v_lshl_add_u64 v[30:31], v[30:31], 0, v[136:137]
	global_store_dwordx4 v[30:31], v[26:29], off offset:512 sc0 sc1

; __device__ __forceinline__ float silu_f(float v) { return v * fast_sigmoid(v); }
; __device__ __forceinline__ u32x4 pack8(const f32x4 v0, const f32x4 v1) { u32x4 w; w.x = pk_f16(v0[0], v0[1]); w.y = pk_f16(v0[2], v0[3]); w.z = pk_f16(v1[0], v1[1]); w.w = pk_f16(v1[2], v1[3]); return w; }
;     __device__ __forceinline__ void operator()(AccRef acc, const Unit& u, int wr, int wc, int fr, int fq) const {
;     ...
;                 for (int bj = 0; bj < 2; ++bj) { const int col = col0 + bj * HALF; f32x4 v0 = acc[ai][bj][m][0], v1 = acc[ai][bj][m][1];
;                     if (u.pn < 4) { *(u32x4*)(upool + (size_t)row * PW + col) = pack8(v0, v1); }
;                     else if (u.pn < 8) { const int cs = col - PW, gg = cs >> 4, hh = cs & 15, lc = row >> 5, s = row & 31;
;                         *(u32x4*)(X + (size_t)gg * XGS + (size_t)lc * XK + 256 + s * 16 + hh) = pack8(v0, v1); }
;                     else {
; #pragma unroll
;                         for (int j = 0; j < 4; ++j) { v0[j] = silu_f(v0[j]); v1[j] = silu_f(v1[j]); }
;                         *(u32x4*)(zs + (size_t)row * D + (col - PW - SW)) = pack8(v0, v1); } } }
.LBB0_421:
	v_cvt_pk_bf16_f32 v14, v14, v15
	v_cvt_pk_bf16_f32 v15, v16, v17
	v_cvt_pk_bf16_f32 v16, v10, v11
	v_cvt_pk_bf16_f32 v17, v12, v13
	v_lshl_add_u64 v[10:11], v[144:145], 1, v[22:23]
	global_store_dwordx4 v[10:11], v[14:17], off sc0 sc1
	s_and_b64 vcc, exec, s[4:5]
	s_mov_b64 s[4:5], -1
	s_cbranch_vccnz .LBB0_348
.LBB0_422:
	s_cmp_lt_u32 s36, 8
	s_cbranch_scc1 .LBB0_424
	v_mul_f32_e32 v11, 0xbfb8aa3b, v2
	v_mul_f32_e32 v12, 0xbfb8aa3b, v7
	v_exp_f32_e32 v11, v11
	v_exp_f32_e32 v12, v12
	v_mul_f32_e32 v13, 0xbfb8aa3b, v3
	v_exp_f32_e32 v13, v13
	v_add_f32_e32 v11, 1.0, v11
	v_add_f32_e32 v12, 1.0, v12
	v_rcp_f32_e32 v11, v11
	v_rcp_f32_e32 v12, v12
	v_mul_f32_e32 v10, 0xbfb8aa3b, v6
	v_mul_f32_e32 v15, 0xbfb8aa3b, v4
	v_mul_f32_e32 v14, v2, v11
	v_mul_f32_e32 v11, v7, v12
	v_add_f32_e32 v12, 1.0, v13
	v_mul_f32_e32 v13, 0xbfb8aa3b, v8
	v_mul_f32_e32 v16, 0xbfb8aa3b, v9
	v_mul_f32_e32 v17, 0xbfb8aa3b, v5
	v_exp_f32_e32 v10, v10
	v_exp_f32_e32 v13, v13
	v_exp_f32_e32 v15, v15
	v_exp_f32_e32 v16, v16
	v_exp_f32_e32 v17, v17
	v_add_f32_e32 v10, 1.0, v10
	v_add_f32_e32 v13, 1.0, v13
	v_add_f32_e32 v15, 1.0, v15
	v_add_f32_e32 v16, 1.0, v16
	v_add_f32_e32 v17, 1.0, v17
	v_rcp_f32_e32 v10, v10
	v_rcp_f32_e32 v12, v12
	v_rcp_f32_e32 v13, v13
	v_rcp_f32_e32 v15, v15
	v_rcp_f32_e32 v16, v16
	v_rcp_f32_e32 v17, v17
	v_mul_f32_e32 v10, v6, v10
	v_mul_f32_e32 v12, v3, v12
	v_mul_f32_e32 v13, v8, v13
	v_mul_f32_e32 v15, v4, v15
	v_mul_f32_e32 v16, v9, v16
	v_mul_f32_e32 v17, v5, v17
	v_cvt_pk_bf16_f32 v10, v10, v11
	v_cvt_pk_bf16_f32 v11, v13, v16
	v_cvt_pk_bf16_f32 v12, v14, v12
	v_cvt_pk_bf16_f32 v13, v15, v17
	v_lshl_add_u64 v[14:15], s[26:27], 0, v[20:21]
	v_lshl_add_u64 v[14:15], v[144:145], 1, v[14:15]
	s_mov_b64 s[4:5], 0
	global_store_dwordx4 v[14:15], v[10:13], off offset:-3840 sc0 sc1
.LBB0_424:
	s_andn2_b64 vcc, exec, s[4:5]
	s_cbranch_vccnz .LBB0_426
	v_add_u32_e32 v10, 0xfffffc80, v144
	v_ashrrev_i32_e32 v16, 4, v10
	v_mov_b64_e32 v[14:15], s[8:9]
	v_mad_i64_i32 v[14:15], s[4:5], v16, s88, v[14:15]
	v_lshl_add_u64 v[14:15], v[14:15], 0, v[18:19]
	v_lshlrev_b32_e32 v136, 1, v24
	v_lshl_add_u64 v[14:15], v[14:15], 0, v[136:137]
	v_lshlrev_b32_e32 v136, 1, v160
	v_cvt_pk_bf16_f32 v10, v6, v7
	v_cvt_pk_bf16_f32 v11, v8, v9
	v_cvt_pk_bf16_f32 v12, v2, v3
	v_cvt_pk_bf16_f32 v13, v4, v5
	v_lshl_add_u64 v[14:15], v[14:15], 0, v[136:137]
	global_store_dwordx4 v[14:15], v[10:13], off offset:512 sc0 sc1

; __device__ __forceinline__ u32x4 pack8(const f32x4 v0, const f32x4 v1) { u32x4 w; w.x = pk_f16(v0[0], v0[1]); w.y = pk_f16(v0[2], v0[3]); w.z = pk_f16(v1[0], v1[1]); w.w = pk_f16(v1[2], v1[3]); return w; }
;     __device__ __forceinline__ void operator()(AccRef acc, const Unit& u, int wr, int wc, int fr, int fq) const {
;     ...
;                 for (int bj = 0; bj < 2; ++bj) { const int col = col0 + bj * HALF; f32x4 v0 = acc[ai][bj][m][0], v1 = acc[ai][bj][m][1];
;                     if (u.pn < 4) { *(u32x4*)(upool + (size_t)row * PW + col) = pack8(v0, v1); }
.LBB0_427:
	v_cvt_pk_bf16_f32 v6, v6, v7
	v_cvt_pk_bf16_f32 v7, v8, v9
	v_cvt_pk_bf16_f32 v8, v2, v3
	v_cvt_pk_bf16_f32 v9, v4, v5
	v_lshl_add_u64 v[2:3], v[144:145], 1, v[22:23]
	global_store_dwordx4 v[2:3], v[6:9], off offset:256 sc0 sc1
	s_andn2_b64 vcc, exec, s[2:3]
	s_mov_b64 s[2:3], -1
	s_cbranch_vccnz .LBB0_292

; __device__ __forceinline__ float silu_f(float v) { return v * fast_sigmoid(v); }
; __device__ __forceinline__ u32x4 pack8(const f32x4 v0, const f32x4 v1) { u32x4 w; w.x = pk_f16(v0[0], v0[1]); w.y = pk_f16(v0[2], v0[3]); w.z = pk_f16(v1[0], v1[1]); w.w = pk_f16(v1[2], v1[3]); return w; }
;     __device__ __forceinline__ void operator()(AccRef acc, const Unit& u, int wr, int wc, int fr, int fq) const {
;     ...
;             for (int m = 0; m < 4; ++m) { const int row = row0 + ai * HALF + m * 16;
; #pragma unroll
;                 for (int bj = 0; bj < 2; ++bj) { const int col = col0 + bj * HALF; f32x4 v0 = acc[ai][bj][m][0], v1 = acc[ai][bj][m][1];
;                     if (u.pn < 4) { *(u32x4*)(upool + (size_t)row * PW + col) = pack8(v0, v1); }
;                     else if (u.pn < 8) { const int cs = col - PW, gg = cs >> 4, hh = cs & 15, lc = row >> 5, s = row & 31;
;                         *(u32x4*)(X + (size_t)gg * XGS + (size_t)lc * XK + 256 + s * 16 + hh) = pack8(v0, v1); }
;                     else {
; #pragma unroll
;                         for (int j = 0; j < 4; ++j) { v0[j] = silu_f(v0[j]); v1[j] = silu_f(v1[j]); }
;                         *(u32x4*)(zs + (size_t)row * D + (col - PW - SW)) = pack8(v0, v1); } } }
.LBB0_498:
	v_lshl_or_b32 v131, s29, 8, v215
	v_or_b32_e32 v132, s60, v131
	v_mul_f32_e32 v131, 0xbfb8aa3b, v126
	v_mul_f32_e32 v134, 0xbfb8aa3b, v122
	v_mul_f32_e32 v135, 0xbfb8aa3b, v127
	v_exp_f32_e32 v133, v131
	v_exp_f32_e32 v134, v134
	v_exp_f32_e32 v135, v135
	v_lshl_add_u32 v130, s30, 8, v136
	v_add_f32_e32 v133, 1.0, v133
	v_add_f32_e32 v134, 1.0, v134
	v_add_f32_e32 v135, 1.0, v135
	v_mul_f32_e32 v136, 0xbfb8aa3b, v123
	v_rcp_f32_e32 v133, v133
	v_rcp_f32_e32 v134, v134
	v_rcp_f32_e32 v135, v135
	v_exp_f32_e32 v136, v136
	v_mul_f32_e32 v126, v126, v133
	v_mul_f32_e32 v122, v122, v134
	v_mul_f32_e32 v127, v127, v135
	v_add_f32_e32 v133, 1.0, v136
	v_mul_f32_e32 v134, 0xbfb8aa3b, v128
	v_mul_f32_e32 v135, 0xbfb8aa3b, v124
	v_rcp_f32_e32 v133, v133
	v_exp_f32_e32 v134, v134
	v_exp_f32_e32 v135, v135
	v_mul_f32_e32 v136, 0xbfb8aa3b, v125
	v_mul_f32_e32 v123, v123, v133
	v_add_f32_e32 v133, 1.0, v134
	v_add_f32_e32 v134, 1.0, v135
	v_mul_f32_e32 v135, 0xbfb8aa3b, v129
	v_exp_f32_e32 v136, v136
	v_exp_f32_e32 v135, v135
	v_rcp_f32_e32 v133, v133
	v_rcp_f32_e32 v134, v134
	v_add_f32_e32 v136, 1.0, v136
	v_add_f32_e32 v135, 1.0, v135
	v_rcp_f32_e32 v136, v136
	v_rcp_f32_e32 v135, v135
	v_mul_f32_e32 v128, v128, v133
	v_ashrrev_i32_e32 v131, 31, v130
	v_lshlrev_b64 v[130:131], 12, v[130:131]
	v_mul_f32_e32 v133, v124, v134
	v_mul_f32_e32 v134, v125, v136
	v_mul_f32_e32 v129, v129, v135
	v_cvt_pk_bf16_f32 v124, v126, v127
	v_cvt_pk_bf16_f32 v126, v122, v123
	v_cvt_pk_bf16_f32 v127, v133, v134
	v_lshl_add_u64 v[122:123], s[92:93], 0, v[130:131]
	v_ashrrev_i32_e32 v133, 31, v132
	v_cvt_pk_bf16_f32 v125, v128, v129
	v_lshl_add_u64 v[122:123], v[132:133], 1, v[122:123]
	v_mul_f32_e32 v128, 0xbfb8aa3b, v118
	global_store_dwordx4 v[122:123], v[124:127], off offset:-4096 sc0 sc1
	v_exp_f32_e32 v128, v128
	s_mov_b32 s2, s30
	v_mul_f32_e32 v125, 0xbfb8aa3b, v114
	v_mul_f32_e32 v126, 0xbfb8aa3b, v119
	v_exp_f32_e32 v125, v125
	v_exp_f32_e32 v126, v126
	v_add_f32_e32 v124, 1.0, v128
	v_mul_f32_e32 v127, 0xbfb8aa3b, v115
	v_add_f32_e32 v125, 1.0, v125
	v_add_f32_e32 v126, 1.0, v126
	v_rcp_f32_e32 v124, v124
	v_rcp_f32_e32 v125, v125
	v_rcp_f32_e32 v126, v126
	v_exp_f32_e32 v127, v127
	v_mul_f32_e32 v118, v118, v124
	v_mul_f32_e32 v124, v114, v125
	v_mul_f32_e32 v114, v119, v126
	v_add_f32_e32 v119, 1.0, v127
	v_mul_f32_e32 v125, 0xbfb8aa3b, v120
	v_mul_f32_e32 v126, 0xbfb8aa3b, v116
	v_rcp_f32_e32 v119, v119
	v_exp_f32_e32 v125, v125
	v_exp_f32_e32 v126, v126
	v_mul_f32_e32 v127, 0xbfb8aa3b, v117
	v_mul_f32_e32 v119, v115, v119
	v_add_f32_e32 v115, 1.0, v125
	v_add_f32_e32 v125, 1.0, v126
	v_mul_f32_e32 v126, 0xbfb8aa3b, v121
	v_exp_f32_e32 v126, v126
	v_exp_f32_e32 v127, v127
	v_rcp_f32_e32 v115, v115
	v_rcp_f32_e32 v125, v125
	v_add_f32_e32 v126, 1.0, v126
	v_rcp_f32_e32 v126, v126
	v_add_f32_e32 v127, 1.0, v127
	v_rcp_f32_e32 v127, v127
	v_mul_f32_e32 v115, v120, v115
	v_mul_f32_e32 v120, v116, v125
	v_mul_f32_e32 v116, v121, v126
	v_mul_f32_e32 v117, v117, v127
	v_cvt_pk_bf16_f32 v115, v115, v116
	v_mul_f32_e32 v116, 0xbfb8aa3b, v110
	v_cvt_pk_bf16_f32 v114, v118, v114
	v_exp_f32_e32 v118, v116
	v_cvt_pk_bf16_f32 v116, v124, v119
	v_cvt_pk_bf16_f32 v117, v120, v117
	global_store_dwordx4 v[122:123], v[114:117], off offset:-3840 sc0 sc1
	v_writelane_b32 v254, s2, 36
	s_add_u32 s0, s50, 0xa300000
	v_mul_f32_e32 v115, 0xbfb8aa3b, v106
	v_mul_f32_e32 v116, 0xbfb8aa3b, v111
	v_exp_f32_e32 v115, v115
	v_exp_f32_e32 v116, v116
	v_add_f32_e32 v114, 1.0, v118
	v_mul_f32_e32 v117, 0xbfb8aa3b, v107
	v_add_f32_e32 v115, 1.0, v115
	v_add_f32_e32 v116, 1.0, v116
	v_rcp_f32_e32 v114, v114
	v_rcp_f32_e32 v115, v115
	v_rcp_f32_e32 v116, v116
	v_exp_f32_e32 v117, v117
	v_mul_f32_e32 v110, v110, v114
	v_mul_f32_e32 v114, v106, v115
	v_mul_f32_e32 v106, v111, v116
	v_add_f32_e32 v111, 1.0, v117
	v_mul_f32_e32 v115, 0xbfb8aa3b, v112
	v_mul_f32_e32 v116, 0xbfb8aa3b, v108
	v_rcp_f32_e32 v111, v111
	v_exp_f32_e32 v115, v115
	v_exp_f32_e32 v116, v116
	v_mul_f32_e32 v117, 0xbfb8aa3b, v109
	v_mul_f32_e32 v111, v107, v111
	v_add_f32_e32 v107, 1.0, v115
	v_add_f32_e32 v115, 1.0, v116
	v_mul_f32_e32 v116, 0xbfb8aa3b, v113
	v_exp_f32_e32 v116, v116
	v_exp_f32_e32 v117, v117
	v_rcp_f32_e32 v107, v107
	v_rcp_f32_e32 v115, v115
	v_add_f32_e32 v116, 1.0, v116
	v_add_f32_e32 v117, 1.0, v117
	v_rcp_f32_e32 v116, v116
	v_rcp_f32_e32 v117, v117
	v_writelane_b32 v254, s3, 37
	v_mul_f32_e32 v107, v112, v107
	v_mul_f32_e32 v112, v108, v115
	v_mul_f32_e32 v108, v113, v116
	v_mul_f32_e32 v109, v109, v117
	v_cvt_pk_bf16_f32 v106, v110, v106
	v_mul_f32_e32 v110, 0xbfb8aa3b, v102
	s_mov_b64 s[2:3], 0x10000
	v_cvt_pk_bf16_f32 v107, v107, v108
	v_cvt_pk_bf16_f32 v108, v114, v111
	v_cvt_pk_bf16_f32 v109, v112, v109
	v_exp_f32_e32 v112, v110
	v_lshl_add_u64 v[110:111], v[122:123], 0, s[2:3]
	global_store_dwordx4 v[110:111], v[106:109], off offset:-4096 sc0 sc1
	s_mov_b64 s[2:3], 0x20000
	s_addc_u32 s1, s51, 0
	v_mul_f32_e32 v107, 0xbfb8aa3b, v98
	v_mul_f32_e32 v108, 0xbfb8aa3b, v103
	v_exp_f32_e32 v107, v107
	v_exp_f32_e32 v108, v108
	v_add_f32_e32 v106, 1.0, v112
	v_mul_f32_e32 v109, 0xbfb8aa3b, v99
	v_add_f32_e32 v107, 1.0, v107
	v_add_f32_e32 v108, 1.0, v108
	v_rcp_f32_e32 v106, v106
	v_rcp_f32_e32 v107, v107
	v_rcp_f32_e32 v108, v108
	v_exp_f32_e32 v109, v109
	v_mul_f32_e32 v102, v102, v106
	v_mul_f32_e32 v106, v98, v107
	v_mul_f32_e32 v98, v103, v108
	v_add_f32_e32 v103, 1.0, v109
	v_mul_f32_e32 v107, 0xbfb8aa3b, v104
	v_mul_f32_e32 v108, 0xbfb8aa3b, v100
	v_rcp_f32_e32 v103, v103
	v_exp_f32_e32 v107, v107
	v_exp_f32_e32 v108, v108
	v_mul_f32_e32 v109, 0xbfb8aa3b, v101
	v_mul_f32_e32 v103, v99, v103
; __device__ __forceinline__ float silu_f(float v) { return v * fast_sigmoid(v); }
; __device__ __forceinline__ u32x4 pack8(const f32x4 v0, const f32x4 v1) { u32x4 w; w.x = pk_f16(v0[0], v0[1]); w.y = pk_f16(v0[2], v0[3]); w.z = pk_f16(v1[0], v1[1]); w.w = pk_f16(v1[2], v1[3]); return w; }
;     __device__ __forceinline__ void operator()(AccRef acc, const Unit& u, int wr, int wc, int fr, int fq) const {
;     ...
; #pragma unroll
;                         for (int j = 0; j < 4; ++j) { v0[j] = silu_f(v0[j]); v1[j] = silu_f(v1[j]); }
;                         *(u32x4*)(zs + (size_t)row * D + (col - PW - SW)) = pack8(v0, v1); } } }
	v_add_f32_e32 v99, 1.0, v107
	v_add_f32_e32 v107, 1.0, v108
	v_mul_f32_e32 v108, 0xbfb8aa3b, v105
	v_exp_f32_e32 v108, v108
	v_exp_f32_e32 v109, v109
	v_rcp_f32_e32 v99, v99
	v_rcp_f32_e32 v107, v107
	v_add_f32_e32 v108, 1.0, v108
	v_rcp_f32_e32 v108, v108
	v_add_f32_e32 v109, 1.0, v109
	v_rcp_f32_e32 v109, v109
	v_mul_f32_e32 v99, v104, v99
	v_mul_f32_e32 v104, v100, v107
	v_mul_f32_e32 v100, v105, v108
	v_mul_f32_e32 v101, v101, v109
	v_cvt_pk_bf16_f32 v99, v99, v100
	v_mul_f32_e32 v100, 0xbfb8aa3b, v94
	v_cvt_pk_bf16_f32 v98, v102, v98
	v_exp_f32_e32 v102, v100
	v_cvt_pk_bf16_f32 v100, v106, v103
	v_cvt_pk_bf16_f32 v101, v104, v101
	global_store_dwordx4 v[110:111], v[98:101], off offset:-3840 sc0 sc1
	s_lshl_b32 s31, s34, 2
	s_and_b32 s35, s31, 0x80
	v_mul_f32_e32 v99, 0xbfb8aa3b, v90
	v_mul_f32_e32 v100, 0xbfb8aa3b, v95
	v_exp_f32_e32 v99, v99
	v_exp_f32_e32 v100, v100
	v_add_f32_e32 v98, 1.0, v102
	v_mul_f32_e32 v101, 0xbfb8aa3b, v91
	v_add_f32_e32 v99, 1.0, v99
	v_add_f32_e32 v100, 1.0, v100
	v_rcp_f32_e32 v98, v98
	v_rcp_f32_e32 v99, v99
	v_rcp_f32_e32 v100, v100
	v_exp_f32_e32 v101, v101
	v_mul_f32_e32 v94, v94, v98
	v_mul_f32_e32 v98, v90, v99
	v_mul_f32_e32 v90, v95, v100
	v_add_f32_e32 v95, 1.0, v101
	v_mul_f32_e32 v99, 0xbfb8aa3b, v96
	v_mul_f32_e32 v100, 0xbfb8aa3b, v92
	v_rcp_f32_e32 v95, v95
	v_exp_f32_e32 v99, v99
	v_exp_f32_e32 v100, v100
	v_mul_f32_e32 v101, 0xbfb8aa3b, v93
	v_mul_f32_e32 v95, v91, v95
	v_add_f32_e32 v91, 1.0, v99
	v_add_f32_e32 v99, 1.0, v100
	v_mul_f32_e32 v100, 0xbfb8aa3b, v97
	v_exp_f32_e32 v100, v100
	v_exp_f32_e32 v101, v101
	v_rcp_f32_e32 v91, v91
	v_rcp_f32_e32 v99, v99
	v_add_f32_e32 v100, 1.0, v100
	v_add_f32_e32 v101, 1.0, v101
	v_rcp_f32_e32 v100, v100
	v_rcp_f32_e32 v101, v101
	v_mul_f32_e32 v91, v96, v91
	v_mul_f32_e32 v96, v92, v99
	v_mul_f32_e32 v92, v97, v100
	v_mul_f32_e32 v93, v93, v101
	v_cvt_pk_bf16_f32 v90, v94, v90
	v_mul_f32_e32 v94, 0xbfb8aa3b, v86
	v_cvt_pk_bf16_f32 v91, v91, v92
	v_cvt_pk_bf16_f32 v92, v98, v95
	v_cvt_pk_bf16_f32 v93, v96, v93
	v_exp_f32_e32 v96, v94
	v_lshl_add_u64 v[94:95], v[122:123], 0, s[2:3]
	global_store_dwordx4 v[94:95], v[90:93], off offset:-4096 sc0 sc1
	s_mov_b64 s[2:3], 0x30000
	s_bfe_u32 s4, s24, 0x20005
	v_mul_f32_e32 v91, 0xbfb8aa3b, v82
	v_mul_f32_e32 v92, 0xbfb8aa3b, v87
	v_exp_f32_e32 v91, v91
	v_exp_f32_e32 v92, v92
	v_add_f32_e32 v90, 1.0, v96
	v_mul_f32_e32 v93, 0xbfb8aa3b, v83
	v_add_f32_e32 v91, 1.0, v91
	v_add_f32_e32 v92, 1.0, v92
	v_rcp_f32_e32 v90, v90
	v_rcp_f32_e32 v91, v91
	v_rcp_f32_e32 v92, v92
	v_exp_f32_e32 v93, v93
	v_mul_f32_e32 v86, v86, v90
	v_mul_f32_e32 v90, v82, v91
	v_mul_f32_e32 v82, v87, v92
	v_add_f32_e32 v87, 1.0, v93
	v_mul_f32_e32 v91, 0xbfb8aa3b, v88
	v_mul_f32_e32 v92, 0xbfb8aa3b, v84
	v_rcp_f32_e32 v87, v87
	v_exp_f32_e32 v91, v91
	v_exp_f32_e32 v92, v92
	v_mul_f32_e32 v93, 0xbfb8aa3b, v85
	v_mul_f32_e32 v87, v83, v87
	v_add_f32_e32 v83, 1.0, v91
	v_add_f32_e32 v91, 1.0, v92
	v_mul_f32_e32 v92, 0xbfb8aa3b, v89
	v_exp_f32_e32 v92, v92
	v_exp_f32_e32 v93, v93
	v_rcp_f32_e32 v83, v83
	v_rcp_f32_e32 v91, v91
	v_add_f32_e32 v92, 1.0, v92
	v_rcp_f32_e32 v92, v92
	v_add_f32_e32 v93, 1.0, v93
	v_rcp_f32_e32 v93, v93
	v_mul_f32_e32 v83, v88, v83
	v_mul_f32_e32 v88, v84, v91
	v_mul_f32_e32 v84, v89, v92
	v_mul_f32_e32 v85, v85, v93
	v_cvt_pk_bf16_f32 v83, v83, v84
	v_mul_f32_e32 v84, 0xbfb8aa3b, v78
	v_cvt_pk_bf16_f32 v82, v86, v82
	v_exp_f32_e32 v86, v84
	v_cvt_pk_bf16_f32 v84, v90, v87
	v_cvt_pk_bf16_f32 v85, v88, v85
	global_store_dwordx4 v[94:95], v[82:85], off offset:-3840 sc0 sc1
	v_readlane_b32 s56, v254, 18
	s_lshl_b32 s9, 2, s4
	v_mul_f32_e32 v83, 0xbfb8aa3b, v74
	v_mul_f32_e32 v84, 0xbfb8aa3b, v79
	v_exp_f32_e32 v83, v83
	v_exp_f32_e32 v84, v84
	v_add_f32_e32 v82, 1.0, v86
	v_mul_f32_e32 v85, 0xbfb8aa3b, v75
	v_add_f32_e32 v83, 1.0, v83
	v_add_f32_e32 v84, 1.0, v84
	v_rcp_f32_e32 v82, v82
	v_rcp_f32_e32 v83, v83
	v_rcp_f32_e32 v84, v84
	v_exp_f32_e32 v85, v85
	v_mul_f32_e32 v78, v78, v82
	v_mul_f32_e32 v82, v74, v83
	v_mul_f32_e32 v74, v79, v84
	v_add_f32_e32 v79, 1.0, v85
	v_mul_f32_e32 v83, 0xbfb8aa3b, v80
	v_mul_f32_e32 v84, 0xbfb8aa3b, v76
	v_rcp_f32_e32 v79, v79
	v_exp_f32_e32 v83, v83
	v_exp_f32_e32 v84, v84
	v_mul_f32_e32 v85, 0xbfb8aa3b, v77
	v_mul_f32_e32 v79, v75, v79
	v_add_f32_e32 v75, 1.0, v83
	v_add_f32_e32 v83, 1.0, v84
	v_mul_f32_e32 v84, 0xbfb8aa3b, v81
	v_exp_f32_e32 v84, v84
	v_exp_f32_e32 v85, v85
	v_rcp_f32_e32 v75, v75
	v_rcp_f32_e32 v83, v83
	v_add_f32_e32 v84, 1.0, v84
	v_add_f32_e32 v85, 1.0, v85
	v_rcp_f32_e32 v84, v84
	v_rcp_f32_e32 v85, v85
	v_mul_f32_e32 v75, v80, v75
	v_mul_f32_e32 v80, v76, v83
	v_mul_f32_e32 v76, v81, v84
	v_mul_f32_e32 v77, v77, v85
	v_cvt_pk_bf16_f32 v74, v78, v74
	v_mul_f32_e32 v78, 0xbfb8aa3b, v70
	v_cvt_pk_bf16_f32 v75, v75, v76
	v_cvt_pk_bf16_f32 v76, v82, v79
	v_cvt_pk_bf16_f32 v77, v80, v77
	v_exp_f32_e32 v80, v78
	v_lshl_add_u64 v[78:79], v[122:123], 0, s[2:3]
	global_store_dwordx4 v[78:79], v[74:77], off offset:-4096 sc0 sc1
	s_mov_b64 s[2:3], 0x80000
	s_lshl_b32 s5, s4, 8
	v_mul_f32_e32 v75, 0xbfb8aa3b, v66
	v_mul_f32_e32 v76, 0xbfb8aa3b, v71
	v_exp_f32_e32 v75, v75
	v_exp_f32_e32 v76, v76
	v_add_f32_e32 v74, 1.0, v80
	v_mul_f32_e32 v77, 0xbfb8aa3b, v67
	v_add_f32_e32 v75, 1.0, v75
	v_add_f32_e32 v76, 1.0, v76
	v_rcp_f32_e32 v74, v74
	v_rcp_f32_e32 v75, v75
	v_rcp_f32_e32 v76, v76
	v_exp_f32_e32 v77, v77
	v_mul_f32_e32 v70, v70, v74
	v_mul_f32_e32 v74, v66, v75
	v_mul_f32_e32 v66, v71, v76
	v_add_f32_e32 v71, 1.0, v77
	v_mul_f32_e32 v75, 0xbfb8aa3b, v72
	v_mul_f32_e32 v76, 0xbfb8aa3b, v68
	v_rcp_f32_e32 v71, v71
	v_exp_f32_e32 v75, v75
; __device__ __forceinline__ float silu_f(float v) { return v * fast_sigmoid(v); }
; __device__ __forceinline__ u32x4 pack8(const f32x4 v0, const f32x4 v1) { u32x4 w; w.x = pk_f16(v0[0], v0[1]); w.y = pk_f16(v0[2], v0[3]); w.z = pk_f16(v1[0], v1[1]); w.w = pk_f16(v1[2], v1[3]); return w; }
;     __device__ __forceinline__ void operator()(AccRef acc, const Unit& u, int wr, int wc, int fr, int fq) const {
;     ...
; #pragma unroll
;                         for (int j = 0; j < 4; ++j) { v0[j] = silu_f(v0[j]); v1[j] = silu_f(v1[j]); }
;                         *(u32x4*)(zs + (size_t)row * D + (col - PW - SW)) = pack8(v0, v1); } } }
	v_exp_f32_e32 v76, v76
	v_mul_f32_e32 v77, 0xbfb8aa3b, v69
	v_mul_f32_e32 v71, v67, v71
	v_add_f32_e32 v67, 1.0, v75
	v_add_f32_e32 v75, 1.0, v76
	v_mul_f32_e32 v76, 0xbfb8aa3b, v73
	v_exp_f32_e32 v76, v76
	v_exp_f32_e32 v77, v77
	v_rcp_f32_e32 v67, v67
	v_rcp_f32_e32 v75, v75
	v_add_f32_e32 v76, 1.0, v76
	v_rcp_f32_e32 v76, v76
	v_add_f32_e32 v77, 1.0, v77
	v_rcp_f32_e32 v77, v77
	v_mul_f32_e32 v67, v72, v67
	v_mul_f32_e32 v72, v68, v75
	v_mul_f32_e32 v68, v73, v76
	v_mul_f32_e32 v69, v69, v77
	v_cvt_pk_bf16_f32 v67, v67, v68
	v_mul_f32_e32 v68, 0xbfb8aa3b, v62
	v_cvt_pk_bf16_f32 v66, v70, v66
	v_exp_f32_e32 v70, v68
	v_cvt_pk_bf16_f32 v68, v74, v71
	v_cvt_pk_bf16_f32 v69, v72, v69
	global_store_dwordx4 v[78:79], v[66:69], off offset:-3840 sc0 sc1
	v_readlane_b32 s58, v254, 20
	v_readlane_b32 s59, v254, 21
	v_mul_f32_e32 v67, 0xbfb8aa3b, v58
	v_mul_f32_e32 v68, 0xbfb8aa3b, v63
	v_exp_f32_e32 v67, v67
	v_exp_f32_e32 v68, v68
	v_add_f32_e32 v66, 1.0, v70
	v_mul_f32_e32 v69, 0xbfb8aa3b, v59
	v_add_f32_e32 v67, 1.0, v67
	v_add_f32_e32 v68, 1.0, v68
	v_rcp_f32_e32 v66, v66
	v_rcp_f32_e32 v67, v67
	v_rcp_f32_e32 v68, v68
	v_exp_f32_e32 v69, v69
	v_mul_f32_e32 v62, v62, v66
	v_mul_f32_e32 v66, v58, v67
	v_mul_f32_e32 v58, v63, v68
	v_add_f32_e32 v63, 1.0, v69
	v_mul_f32_e32 v67, 0xbfb8aa3b, v64
	v_mul_f32_e32 v68, 0xbfb8aa3b, v60
	v_rcp_f32_e32 v63, v63
	v_exp_f32_e32 v67, v67
	v_exp_f32_e32 v68, v68
	v_mul_f32_e32 v69, 0xbfb8aa3b, v61
	v_mul_f32_e32 v63, v59, v63
	v_add_f32_e32 v59, 1.0, v67
	v_add_f32_e32 v67, 1.0, v68
	v_mul_f32_e32 v68, 0xbfb8aa3b, v65
	v_exp_f32_e32 v68, v68
	v_exp_f32_e32 v69, v69
	v_rcp_f32_e32 v59, v59
	v_rcp_f32_e32 v67, v67
	v_add_f32_e32 v68, 1.0, v68
	v_add_f32_e32 v69, 1.0, v69
	v_rcp_f32_e32 v68, v68
	v_rcp_f32_e32 v69, v69
	v_mul_f32_e32 v59, v64, v59
	v_mul_f32_e32 v64, v60, v67
	v_mul_f32_e32 v60, v65, v68
	v_mul_f32_e32 v61, v61, v69
	v_cvt_pk_bf16_f32 v58, v62, v58
	v_mul_f32_e32 v62, 0xbfb8aa3b, v54
	v_cvt_pk_bf16_f32 v59, v59, v60
	v_cvt_pk_bf16_f32 v60, v66, v63
	v_cvt_pk_bf16_f32 v61, v64, v61
	v_exp_f32_e32 v64, v62
	v_lshl_add_u64 v[62:63], v[122:123], 0, s[2:3]
	global_store_dwordx4 v[62:63], v[58:61], off offset:-4096 sc0 sc1
	s_mov_b64 s[2:3], 0x90000
	s_lshl_b32 s8, s28, 1
	v_mul_f32_e32 v59, 0xbfb8aa3b, v50
	v_mul_f32_e32 v60, 0xbfb8aa3b, v55
	v_exp_f32_e32 v59, v59
	v_exp_f32_e32 v60, v60
	v_add_f32_e32 v58, 1.0, v64
	v_mul_f32_e32 v61, 0xbfb8aa3b, v51
	v_add_f32_e32 v59, 1.0, v59
	v_add_f32_e32 v60, 1.0, v60
	v_rcp_f32_e32 v58, v58
	v_rcp_f32_e32 v59, v59
	v_rcp_f32_e32 v60, v60
	v_exp_f32_e32 v61, v61
	v_mul_f32_e32 v54, v54, v58
	v_mul_f32_e32 v58, v50, v59
	v_mul_f32_e32 v50, v55, v60
	v_add_f32_e32 v55, 1.0, v61
	v_mul_f32_e32 v59, 0xbfb8aa3b, v56
	v_mul_f32_e32 v60, 0xbfb8aa3b, v52
	v_rcp_f32_e32 v55, v55
	v_exp_f32_e32 v59, v59
	v_exp_f32_e32 v60, v60
	v_mul_f32_e32 v61, 0xbfb8aa3b, v53
	v_mul_f32_e32 v55, v51, v55
	v_add_f32_e32 v51, 1.0, v59
	v_add_f32_e32 v59, 1.0, v60
	v_mul_f32_e32 v60, 0xbfb8aa3b, v57
	v_exp_f32_e32 v60, v60
	v_exp_f32_e32 v61, v61
	v_rcp_f32_e32 v51, v51
	v_rcp_f32_e32 v59, v59
	v_add_f32_e32 v60, 1.0, v60
	v_rcp_f32_e32 v60, v60
	v_add_f32_e32 v61, 1.0, v61
	v_rcp_f32_e32 v61, v61
	v_mul_f32_e32 v51, v56, v51
	v_mul_f32_e32 v56, v52, v59
	v_mul_f32_e32 v52, v57, v60
	v_mul_f32_e32 v53, v53, v61
	v_cvt_pk_bf16_f32 v51, v51, v52
	v_mul_f32_e32 v52, 0xbfb8aa3b, v46
	v_cvt_pk_bf16_f32 v50, v54, v50
	v_exp_f32_e32 v54, v52
	v_cvt_pk_bf16_f32 v52, v58, v55
	v_cvt_pk_bf16_f32 v53, v56, v53
	global_store_dwordx4 v[62:63], v[50:53], off offset:-3840 sc0 sc1
	s_lshr_b32 s33, s9, 1
	s_lshl_b32 s6, s4, 10
	v_mul_f32_e32 v51, 0xbfb8aa3b, v42
	v_mul_f32_e32 v52, 0xbfb8aa3b, v47
	v_exp_f32_e32 v51, v51
	v_exp_f32_e32 v52, v52
	v_add_f32_e32 v50, 1.0, v54
	v_mul_f32_e32 v53, 0xbfb8aa3b, v43
	v_add_f32_e32 v51, 1.0, v51
	v_add_f32_e32 v52, 1.0, v52
	v_rcp_f32_e32 v50, v50
	v_rcp_f32_e32 v51, v51
	v_rcp_f32_e32 v52, v52
	v_exp_f32_e32 v53, v53
	v_mul_f32_e32 v46, v46, v50
	v_mul_f32_e32 v50, v42, v51
	v_mul_f32_e32 v42, v47, v52
	v_add_f32_e32 v47, 1.0, v53
	v_mul_f32_e32 v51, 0xbfb8aa3b, v48
	v_mul_f32_e32 v52, 0xbfb8aa3b, v44
	v_rcp_f32_e32 v47, v47
	v_exp_f32_e32 v51, v51
	v_exp_f32_e32 v52, v52
	v_mul_f32_e32 v53, 0xbfb8aa3b, v45
	v_mul_f32_e32 v47, v43, v47
	v_add_f32_e32 v43, 1.0, v51
	v_add_f32_e32 v51, 1.0, v52
	v_mul_f32_e32 v52, 0xbfb8aa3b, v49
	v_exp_f32_e32 v52, v52
	v_exp_f32_e32 v53, v53
	v_rcp_f32_e32 v43, v43
	v_rcp_f32_e32 v51, v51
	v_add_f32_e32 v52, 1.0, v52
	v_add_f32_e32 v53, 1.0, v53
	v_rcp_f32_e32 v52, v52
	v_rcp_f32_e32 v53, v53
	v_mul_f32_e32 v43, v48, v43
	v_mul_f32_e32 v48, v44, v51
	v_mul_f32_e32 v44, v49, v52
	v_mul_f32_e32 v45, v45, v53
	v_cvt_pk_bf16_f32 v42, v46, v42
	v_mul_f32_e32 v46, 0xbfb8aa3b, v38
	v_cvt_pk_bf16_f32 v43, v43, v44
	v_cvt_pk_bf16_f32 v44, v50, v47
	v_cvt_pk_bf16_f32 v45, v48, v45
	v_exp_f32_e32 v48, v46
	v_lshl_add_u64 v[46:47], v[122:123], 0, s[2:3]
	global_store_dwordx4 v[46:47], v[42:45], off offset:-4096 sc0 sc1
	s_mov_b64 s[2:3], 0xa0000
	s_mov_b64 s[54:55], s[58:59]
	v_mul_f32_e32 v43, 0xbfb8aa3b, v34
	v_mul_f32_e32 v44, 0xbfb8aa3b, v39
	v_exp_f32_e32 v43, v43
	v_exp_f32_e32 v44, v44
	v_add_f32_e32 v42, 1.0, v48
	v_mul_f32_e32 v45, 0xbfb8aa3b, v35
	v_add_f32_e32 v43, 1.0, v43
	v_add_f32_e32 v44, 1.0, v44
	v_rcp_f32_e32 v42, v42
	v_rcp_f32_e32 v43, v43
	v_rcp_f32_e32 v44, v44
	v_exp_f32_e32 v45, v45
	v_mul_f32_e32 v38, v38, v42
	v_mul_f32_e32 v42, v34, v43
	v_mul_f32_e32 v34, v39, v44
	v_add_f32_e32 v39, 1.0, v45
	v_mul_f32_e32 v43, 0xbfb8aa3b, v40
	v_mul_f32_e32 v44, 0xbfb8aa3b, v36
	v_rcp_f32_e32 v39, v39
	v_exp_f32_e32 v43, v43
; __device__ __forceinline__ float silu_f(float v) { return v * fast_sigmoid(v); }
; __device__ __forceinline__ u32x4 pack8(const f32x4 v0, const f32x4 v1) { u32x4 w; w.x = pk_f16(v0[0], v0[1]); w.y = pk_f16(v0[2], v0[3]); w.z = pk_f16(v1[0], v1[1]); w.w = pk_f16(v1[2], v1[3]); return w; }
;     __device__ __forceinline__ void operator()(AccRef acc, const Unit& u, int wr, int wc, int fr, int fq) const {
;     ...
; #pragma unroll
;                         for (int j = 0; j < 4; ++j) { v0[j] = silu_f(v0[j]); v1[j] = silu_f(v1[j]); }
;                         *(u32x4*)(zs + (size_t)row * D + (col - PW - SW)) = pack8(v0, v1); } } }
	v_exp_f32_e32 v44, v44
	v_mul_f32_e32 v45, 0xbfb8aa3b, v37
	v_mul_f32_e32 v39, v35, v39
	v_add_f32_e32 v35, 1.0, v43
	v_add_f32_e32 v43, 1.0, v44
	v_mul_f32_e32 v44, 0xbfb8aa3b, v41
	v_exp_f32_e32 v44, v44
	v_exp_f32_e32 v45, v45
	v_rcp_f32_e32 v35, v35
	v_rcp_f32_e32 v43, v43
	v_add_f32_e32 v44, 1.0, v44
	v_rcp_f32_e32 v44, v44
	v_add_f32_e32 v45, 1.0, v45
	v_rcp_f32_e32 v45, v45
	v_mul_f32_e32 v35, v40, v35
	v_mul_f32_e32 v40, v36, v43
	v_mul_f32_e32 v36, v41, v44
	v_mul_f32_e32 v37, v37, v45
	v_cvt_pk_bf16_f32 v35, v35, v36
	v_mul_f32_e32 v36, 0xbfb8aa3b, v30
	v_cvt_pk_bf16_f32 v34, v38, v34
	v_exp_f32_e32 v38, v36
	v_cvt_pk_bf16_f32 v36, v42, v39
	v_cvt_pk_bf16_f32 v37, v40, v37
	global_store_dwordx4 v[46:47], v[34:37], off offset:-3840 sc0 sc1
	v_mov_b32_e32 v171, 0
	v_readlane_b32 s57, v254, 19
	v_mul_f32_e32 v35, 0xbfb8aa3b, v26
	v_mul_f32_e32 v36, 0xbfb8aa3b, v31
	v_exp_f32_e32 v35, v35
	v_exp_f32_e32 v36, v36
	v_add_f32_e32 v34, 1.0, v38
	v_mul_f32_e32 v37, 0xbfb8aa3b, v27
	v_add_f32_e32 v35, 1.0, v35
	v_add_f32_e32 v36, 1.0, v36
	v_rcp_f32_e32 v34, v34
	v_rcp_f32_e32 v35, v35
	v_rcp_f32_e32 v36, v36
	v_exp_f32_e32 v37, v37
	v_mul_f32_e32 v30, v30, v34
	v_mul_f32_e32 v34, v26, v35
	v_mul_f32_e32 v26, v31, v36
	v_add_f32_e32 v31, 1.0, v37
	v_mul_f32_e32 v35, 0xbfb8aa3b, v32
	v_mul_f32_e32 v36, 0xbfb8aa3b, v28
	v_rcp_f32_e32 v31, v31
	v_exp_f32_e32 v35, v35
	v_exp_f32_e32 v36, v36
	v_mul_f32_e32 v37, 0xbfb8aa3b, v29
	v_mul_f32_e32 v31, v27, v31
	v_add_f32_e32 v27, 1.0, v35
	v_add_f32_e32 v35, 1.0, v36
	v_mul_f32_e32 v36, 0xbfb8aa3b, v33
	v_exp_f32_e32 v36, v36
	v_exp_f32_e32 v37, v37
	v_rcp_f32_e32 v27, v27
	v_rcp_f32_e32 v35, v35
	v_add_f32_e32 v36, 1.0, v36
	v_add_f32_e32 v37, 1.0, v37
	v_rcp_f32_e32 v36, v36
	v_rcp_f32_e32 v37, v37
	v_mul_f32_e32 v27, v32, v27
	v_mul_f32_e32 v32, v28, v35
	v_mul_f32_e32 v28, v33, v36
	v_mul_f32_e32 v29, v29, v37
	v_cvt_pk_bf16_f32 v26, v30, v26
	v_mul_f32_e32 v30, 0xbfb8aa3b, v22
	v_cvt_pk_bf16_f32 v27, v27, v28
	v_cvt_pk_bf16_f32 v28, v34, v31
	v_cvt_pk_bf16_f32 v29, v32, v29
	v_exp_f32_e32 v32, v30
	v_lshl_add_u64 v[30:31], v[122:123], 0, s[2:3]
	global_store_dwordx4 v[30:31], v[26:29], off offset:-4096 sc0 sc1
	s_mov_b64 s[2:3], 0xb0000
	v_readlane_b32 s60, v254, 22
	v_mul_f32_e32 v27, 0xbfb8aa3b, v18
	v_mul_f32_e32 v28, 0xbfb8aa3b, v23
	v_exp_f32_e32 v27, v27
	v_exp_f32_e32 v28, v28
	v_add_f32_e32 v26, 1.0, v32
	v_mul_f32_e32 v29, 0xbfb8aa3b, v19
	v_add_f32_e32 v27, 1.0, v27
	v_add_f32_e32 v28, 1.0, v28
	v_rcp_f32_e32 v26, v26
	v_rcp_f32_e32 v27, v27
	v_rcp_f32_e32 v28, v28
	v_exp_f32_e32 v29, v29
	v_mul_f32_e32 v22, v22, v26
	v_mul_f32_e32 v26, v18, v27
	v_mul_f32_e32 v18, v23, v28
	v_add_f32_e32 v23, 1.0, v29
	v_mul_f32_e32 v27, 0xbfb8aa3b, v24
	v_mul_f32_e32 v28, 0xbfb8aa3b, v20
	v_rcp_f32_e32 v23, v23
	v_exp_f32_e32 v27, v27
	v_exp_f32_e32 v28, v28
	v_mul_f32_e32 v29, 0xbfb8aa3b, v21
	v_mul_f32_e32 v23, v19, v23
	v_add_f32_e32 v19, 1.0, v27
	v_add_f32_e32 v27, 1.0, v28
	v_mul_f32_e32 v28, 0xbfb8aa3b, v25
	v_exp_f32_e32 v28, v28
	v_exp_f32_e32 v29, v29
	v_rcp_f32_e32 v19, v19
	v_rcp_f32_e32 v27, v27
	v_add_f32_e32 v28, 1.0, v28
	v_rcp_f32_e32 v28, v28
	v_add_f32_e32 v29, 1.0, v29
	v_rcp_f32_e32 v29, v29
	v_mul_f32_e32 v19, v24, v19
	v_mul_f32_e32 v24, v20, v27
	v_mul_f32_e32 v20, v25, v28
	v_mul_f32_e32 v21, v21, v29
	v_cvt_pk_bf16_f32 v19, v19, v20
	v_mul_f32_e32 v20, 0xbfb8aa3b, v14
	v_cvt_pk_bf16_f32 v18, v22, v18
	v_exp_f32_e32 v22, v20
	v_cvt_pk_bf16_f32 v20, v26, v23
	v_cvt_pk_bf16_f32 v21, v24, v21
	global_store_dwordx4 v[30:31], v[18:21], off offset:-3840 sc0 sc1
	v_readlane_b32 s61, v254, 23
	v_readlane_b32 s62, v254, 24
	v_mul_f32_e32 v19, 0xbfb8aa3b, v10
	v_mul_f32_e32 v20, 0xbfb8aa3b, v15
	v_exp_f32_e32 v19, v19
	v_exp_f32_e32 v20, v20
	v_add_f32_e32 v18, 1.0, v22
	v_mul_f32_e32 v21, 0xbfb8aa3b, v11
	v_add_f32_e32 v19, 1.0, v19
	v_add_f32_e32 v20, 1.0, v20
	v_rcp_f32_e32 v18, v18
	v_rcp_f32_e32 v19, v19
	v_rcp_f32_e32 v20, v20
	v_exp_f32_e32 v21, v21
	v_mul_f32_e32 v14, v14, v18
	v_mul_f32_e32 v18, v10, v19
	v_mul_f32_e32 v10, v15, v20
	v_add_f32_e32 v15, 1.0, v21
	v_mul_f32_e32 v19, 0xbfb8aa3b, v16
	v_mul_f32_e32 v20, 0xbfb8aa3b, v12
	v_rcp_f32_e32 v15, v15
	v_exp_f32_e32 v19, v19
	v_exp_f32_e32 v20, v20
	v_mul_f32_e32 v21, 0xbfb8aa3b, v13
	v_mul_f32_e32 v15, v11, v15
	v_add_f32_e32 v11, 1.0, v19
	v_add_f32_e32 v19, 1.0, v20
	v_mul_f32_e32 v20, 0xbfb8aa3b, v17
	v_exp_f32_e32 v20, v20
	v_exp_f32_e32 v21, v21
	v_rcp_f32_e32 v11, v11
	v_rcp_f32_e32 v19, v19
	v_add_f32_e32 v20, 1.0, v20
	v_add_f32_e32 v21, 1.0, v21
	v_rcp_f32_e32 v20, v20
	v_rcp_f32_e32 v21, v21
	v_mul_f32_e32 v11, v16, v11
	v_mul_f32_e32 v16, v12, v19
	v_mul_f32_e32 v12, v17, v20
	v_mul_f32_e32 v13, v13, v21
	v_cvt_pk_bf16_f32 v10, v14, v10
	v_mul_f32_e32 v14, 0xbfb8aa3b, v6
	v_cvt_pk_bf16_f32 v11, v11, v12
	v_cvt_pk_bf16_f32 v12, v18, v15
	v_cvt_pk_bf16_f32 v13, v16, v13
	v_exp_f32_e32 v16, v14
	v_lshl_add_u64 v[14:15], v[122:123], 0, s[2:3]
	global_store_dwordx4 v[14:15], v[10:13], off offset:-4096 sc0 sc1
	s_or_b32 s2, s35, s24
	s_ashr_i32 s2, s2, 7
	v_mul_f32_e32 v11, 0xbfb8aa3b, v2
	v_mul_f32_e32 v12, 0xbfb8aa3b, v7
	v_exp_f32_e32 v11, v11
	v_exp_f32_e32 v12, v12
	v_add_f32_e32 v10, 1.0, v16
	v_mul_f32_e32 v13, 0xbfb8aa3b, v3
	v_add_f32_e32 v11, 1.0, v11
	v_add_f32_e32 v12, 1.0, v12
	v_rcp_f32_e32 v10, v10
	v_rcp_f32_e32 v11, v11
	v_rcp_f32_e32 v12, v12
	v_exp_f32_e32 v13, v13
	v_mul_f32_e32 v6, v6, v10
	v_mul_f32_e32 v10, v2, v11
	v_mul_f32_e32 v2, v7, v12
	v_add_f32_e32 v7, 1.0, v13
	v_mul_f32_e32 v11, 0xbfb8aa3b, v8
	v_mul_f32_e32 v12, 0xbfb8aa3b, v4
	v_rcp_f32_e32 v7, v7
	v_exp_f32_e32 v11, v11
	v_exp_f32_e32 v12, v12
	v_mul_f32_e32 v13, 0xbfb8aa3b, v5
	v_mul_f32_e32 v7, v3, v7
	v_add_f32_e32 v3, 1.0, v11
	v_add_f32_e32 v11, 1.0, v12
	v_mul_f32_e32 v12, 0xbfb8aa3b, v9
	v_exp_f32_e32 v12, v12
	v_exp_f32_e32 v13, v13
	v_rcp_f32_e32 v3, v3
	v_rcp_f32_e32 v11, v11
	v_add_f32_e32 v12, 1.0, v12
	v_add_f32_e32 v13, 1.0, v13
	v_rcp_f32_e32 v12, v12
	v_rcp_f32_e32 v13, v13
	v_mul_f32_e32 v3, v8, v3
	v_mul_f32_e32 v8, v4, v11
	v_mul_f32_e32 v4, v9, v12
	v_mul_f32_e32 v5, v5, v13
	v_cvt_pk_bf16_f32 v2, v6, v2
	v_cvt_pk_bf16_f32 v3, v3, v4
	v_cvt_pk_bf16_f32 v4, v10, v7
	v_cvt_pk_bf16_f32 v5, v8, v5
	global_store_dwordx4 v[14:15], v[2:5], off offset:-3840 sc0 sc1
	v_mov_b32_e32 v16, v0
	s_ashr_i32 s3, s2, 31
	s_waitcnt vmcnt(0)
	s_barrier
; __device__ __forceinline__ void pm_item(LAS float* Vs0, int item, const f16* up, const f16* zs, const float* pscale, f16* branch) {
;     ...
;     const int w = 2 << g, lo_off = w >> 1, hi_off = w - lo_off;
;     const int o = tid & 31, cs = tid >> 5;
;     const f16* ub = up + (size_t)b * SEQ * PW + g * 256 + o * 8 + (size_t)(4 * cs) * PW;
;     const size_t zoff = (size_t)b * SEQ * D + g * 256 + o * 8 + (size_t)(4 * cs) * D;
;     const f32x4 sc0 = *(const f32x4*)(pscale + g * 256 + o * 8), sc1 = *(const f32x4*)(pscale + g * 256 + o * 8 + 4);
;     float rs[4][8];
; #pragma unroll
;     for (int q = 0; q < 4; ++q)
; #pragma unroll
;         for (int e = 0; e < 8; ++e) rs[q][e] = 0.f;
;     u32x4 cen[2][4], zz[2][4], hi[2][4], lo[2][4];
; #pragma unroll
;     for (int q = 0; q < 4; ++q) { cen[0][q] = *(const u32x4*)(ub + (size_t)(r0 * GW + q) * PW); zz[0][q] = *(const u32x4*)(zs + zoff + (size_t)(r0 * GW + q) * D); }
;     { const int rlo0 = r0 - lo_off < 0 ? 0 : r0 - lo_off, rhi0 = r0 + hi_off > ROWS ? ROWS : r0 + hi_off;
; #pragma unroll 1
;       for (int fb = rlo0; fb < rhi0; fb += 8) { u32x4 t[8][4];
	s_lshl_b64 s[2:3], s[2:3], 24
	v_ashrrev_i32_e32 v222, 3, v16
	v_lshlrev_b32_e32 v2, 3, v16
	v_and_b32_e32 v206, -4, v222
	s_or_b32 s5, s2, s5
	v_and_b32_e32 v221, 0xf8, v2
	v_ashrrev_i32_e32 v207, 31, v206
	s_add_u32 s6, s54, s6
	v_lshlrev_b64 v[10:11], 11, v[206:207]
	s_addc_u32 s7, s55, 0
	v_lshlrev_b32_e32 v207, 2, v221
	s_and_b32 s45, s8, 0x7c
	global_load_dwordx4 v[2:5], v207, s[6:7] offset:16
	global_load_dwordx4 v[6:9], v207, s[6:7]
	s_add_u32 s6, s0, s2
	s_addc_u32 s7, s1, s3
	s_lshl_b32 s4, s4, 9
	s_add_u32 s6, s6, s4
	s_addc_u32 s7, s7, 0
	v_lshlrev_b32_e32 v170, 1, v221
	v_or_b32_e32 v12, s5, v221
	v_mov_b32_e32 v13, s3
	v_lshl_add_u64 v[14:15], s[6:7], 0, v[170:171]
	s_lshl_b32 s55, s45, 6
	s_mov_b32 s5, 0
	v_lshl_add_u64 v[202:203], v[14:15], 0, v[10:11]
	v_lshl_add_u64 v[208:209], v[12:13], 0, v[10:11]
	s_lshl_b32 s4, s45, 17
	s_or_b32 s8, s55, 1
	v_lshl_add_u64 v[204:205], v[208:209], 1, s[92:93]
	v_lshl_add_u64 v[12:13], v[202:203], 0, s[4:5]
	s_lshl_b32 s4, s45, 18
	s_lshl_b32 s6, s8, 11
	s_mov_b32 s7, s5
	v_lshl_add_u64 v[14:15], v[204:205], 0, s[4:5]
	global_load_dwordx4 v[78:81], v[12:13], off
	global_load_dwordx4 v[86:89], v[14:15], off
	v_lshl_add_u64 v[12:13], v[202:203], 0, s[6:7]
	s_lshl_b32 s6, s8, 12
	s_or_b32 s8, s55, 2
	v_lshl_add_u64 v[14:15], v[204:205], 0, s[6:7]
	s_lshl_b32 s6, s8, 11
	global_load_dwordx4 v[58:61], v[12:13], off
	global_load_dwordx4 v[66:69], v[14:15], off
	v_lshl_add_u64 v[12:13], v[202:203], 0, s[6:7]
	s_lshl_b32 s6, s8, 12
	s_or_b32 s8, s55, 3
	v_lshl_add_u64 v[14:15], v[204:205], 0, s[6:7]
	s_lshl_b32 s6, s8, 11
	global_load_dwordx4 v[50:53], v[12:13], off
	global_load_dwordx4 v[54:57], v[14:15], off
	v_lshl_add_u64 v[12:13], v[202:203], 0, s[6:7]
	s_lshl_b32 s6, s8, 12
	v_lshl_add_u64 v[14:15], v[204:205], 0, s[6:7]
	global_load_dwordx4 v[42:45], v[12:13], off
	global_load_dwordx4 v[46:49], v[14:15], off
	v_readlane_b32 s63, v254, 25
	v_readlane_b32 s64, v254, 26
	v_readlane_b32 s65, v254, 27
	s_mov_b64 s[56:57], s[60:61]
	s_sub_i32 s44, s9, s33
	s_sub_i32 s41, s45, s33
	s_add_i32 s56, s44, s45
	s_max_i32 s5, s41, 0
	s_min_i32 s40, s56, 0x80
	s_mov_b32 s81, s28
	s_cmp_le_i32 s40, s5
	v_and_b32_e32 v220, 31, v16
	v_readlane_b32 s66, v254, 28
	v_readlane_b32 s67, v254, 29
	v_readlane_b32 s68, v254, 30
	v_readlane_b32 s69, v254, 31
	v_readlane_b32 s70, v254, 32
	v_readlane_b32 s71, v254, 33
	s_mov_b64 s[58:59], s[62:63]
	s_mov_b64 s[60:61], s[64:65]
	s_cbranch_scc1 .LBB0_530
	s_lshl_b32 s6, s5, 17
	s_add_u32 s2, s2, s6
	s_addc_u32 s3, s3, 0
	s_lshl_b32 s6, s24, 4
	s_and_b32 s6, s6, 0x600
	s_add_u32 s2, s6, s2
	s_addc_u32 s3, 0, s3
	v_lshl_add_u64 v[10:11], s[2:3], 0, v[10:11]
	v_lshlrev_b32_e32 v170, 4, v220
	v_lshl_add_u64 v[10:11], v[10:11], 0, v[170:171]
	v_lshl_add_u64 v[10:11], s[50:51], 0, v[10:11]
	s_mov_b64 s[2:3], 0xa3e1800
	v_mov_b32_e32 v170, v171
	v_lshl_add_u64 v[210:211], v[10:11], 0, s[2:3]
	s_mov_b32 s54, 0xfff1f000
	s_mov_b64 s[2:3], 0x100000
	s_mov_b32 s57, s5
	v_mov_b64_e32 v[200:201], v[170:171]
	v_mov_b64_e32 v[196:197], v[170:171]
	v_mov_b64_e32 v[198:199], v[170:171]
	v_mov_b64_e32 v[192:193], v[170:171]
	v_mov_b64_e32 v[194:195], v[170:171]
	v_mov_b64_e32 v[188:189], v[170:171]
	v_mov_b64_e32 v[190:191], v[170:171]
	v_mov_b64_e32 v[184:185], v[170:171]
	v_mov_b64_e32 v[186:187], v[170:171]
	v_mov_b64_e32 v[180:181], v[170:171]
	v_mov_b64_e32 v[182:183], v[170:171]
	v_mov_b64_e32 v[176:177], v[170:171]
	v_mov_b64_e32 v[178:179], v[170:171]
	v_mov_b64_e32 v[172:173], v[170:171]
	v_mov_b64_e32 v[174:175], v[170:171]
	s_branch .LBB0_501

; #define LAS __attribute__((address_space(3)))
; __device__ __forceinline__ u32x4 pack8(const f32x4 v0, const f32x4 v1) { u32x4 w; w.x = pk_f16(v0[0], v0[1]); w.y = pk_f16(v0[2], v0[3]); w.z = pk_f16(v1[0], v1[1]); w.w = pk_f16(v1[2], v1[3]); return w; }
; __device__ __forceinline__ void unpack8(const u32x4 w, f32x4& v0, f32x4& v1) { v0 = (f32x4){f16lo(w.x), f16hi(w.x), f16lo(w.y), f16hi(w.y)}; v1 = (f32x4){f16lo(w.z), f16hi(w.z), f16lo(w.w), f16hi(w.w)}; }
; __device__ __forceinline__ void pm_item(LAS float* Vs0, int item, const f16* up, const f16* zs, const float* pscale, f16* branch) {
;     ...
;           for (int q = 0; q < 4; ++q) { const int cc = 4 * cs + q;
;             if (q > 0) { const int cin = cc + hi_off - 1, cout = cc - 1 - lo_off;
;                 if (cin < GW) { const LAS f32x4* vp = (const LAS f32x4*)(Vs + cin * 256 + o * 8); s0 += vp[0]; s1 += vp[1]; }
;                 if (cout >= 0) { const LAS f32x4* vp = (const LAS f32x4*)(Vs + cout * 256 + o * 8); s0 -= vp[0]; s1 -= vp[1]; } }
;             const int clo = cc - lo_off < 0 ? 0 : cc - lo_off, chi = cc + hi_off > GW ? GW : cc + hi_off;
;             const float ic = 1.f / (float)(chi - clo);
;             f32x4 u0, u1, z0, z1; unpack8(cen[cur][q], u0, u1); unpack8(zz[cur][q], z0, z1);
;             *(u32x4*)(branch + zoff + (size_t)(r * GW + q) * D) = pack8((s0 * ic - u0) * sc0 * z0, (s1 * ic - u1) * sc1 * z1); } }
.LBB0_540:
	s_or_b64 exec, exec, s[6:7]
	v_sub_u32_e32 v115, v157, v156
	v_cvt_f32_i32_e32 v115, v115
	s_mov_b32 s5, 0x8000
	v_and_b32_e32 v121, 0xffff0000, v89
	v_xor_b32_sdwa v122, s5, v78 dst_sel:WORD_1 dst_unused:UNUSED_PAD src0_sel:DWORD src1_sel:DWORD
	v_div_scale_f32 v116, s[6:7], v115, v115, 1.0
	v_rcp_f32_e32 v117, v116
	v_div_scale_f32 v118, vcc, 1.0, v115, 1.0
	v_xor_b32_sdwa v123, s5, v78 dst_sel:WORD_1 dst_unused:UNUSED_PAD src0_sel:DWORD src1_sel:WORD_1
	v_fma_f32 v119, -v116, v117, 1.0
	v_fmac_f32_e32 v117, v119, v117
	v_mul_f32_e32 v119, v118, v117
	v_fma_f32 v120, -v116, v119, v118
	v_fmac_f32_e32 v119, v120, v117
	v_fma_f32 v116, -v116, v119, v118
	v_div_fmas_f32 v116, v116, v117, v119
	v_div_fixup_f32 v148, v116, v115, 1.0
	v_and_b32_e32 v117, 0xffff0000, v86
	v_lshlrev_b32_e32 v116, 16, v86
	v_and_b32_e32 v119, 0xffff0000, v87
	v_lshlrev_b32_e32 v118, 16, v87
	v_and_b32_e32 v87, 0xffff0000, v88
	v_lshlrev_b32_e32 v86, 16, v88
	v_lshlrev_b32_e32 v120, 16, v89
	v_xor_b32_sdwa v88, s5, v79 dst_sel:WORD_1 dst_unused:UNUSED_PAD src0_sel:DWORD src1_sel:DWORD
	v_xor_b32_sdwa v89, s5, v79 dst_sel:WORD_1 dst_unused:UNUSED_PAD src0_sel:DWORD src1_sel:WORD_1
	v_pk_fma_f32 v[78:79], v[148:149], v[110:111], v[122:123] op_sel_hi:[0,1,1]
	v_pk_fma_f32 v[88:89], v[148:149], v[112:113], v[88:89] op_sel_hi:[0,1,1]
	v_pk_mul_f32 v[88:89], v[8:9], v[88:89]
	v_pk_mul_f32 v[78:79], v[6:7], v[78:79]
	v_pk_mul_f32 v[88:89], v[118:119], v[88:89]
	v_xor_b32_sdwa v118, s5, v80 dst_sel:WORD_1 dst_unused:UNUSED_PAD src0_sel:DWORD src1_sel:DWORD
	v_xor_b32_sdwa v119, s5, v80 dst_sel:WORD_1 dst_unused:UNUSED_PAD src0_sel:DWORD src1_sel:WORD_1
	v_pk_mul_f32 v[78:79], v[116:117], v[78:79]
	v_xor_b32_sdwa v116, s5, v81 dst_sel:WORD_1 dst_unused:UNUSED_PAD src0_sel:DWORD src1_sel:DWORD
	v_xor_b32_sdwa v117, s5, v81 dst_sel:WORD_1 dst_unused:UNUSED_PAD src0_sel:DWORD src1_sel:WORD_1
	v_pk_fma_f32 v[80:81], v[148:149], v[106:107], v[118:119] op_sel_hi:[0,1,1]
	s_add_u32 s36, s50, 0x19800000
	v_pk_mul_f32 v[80:81], v[2:3], v[80:81]
	s_addc_u32 s37, s51, 0
	v_pk_fma_f32 v[116:117], v[148:149], v[108:109], v[116:117] op_sel_hi:[0,1,1]
	v_pk_mul_f32 v[80:81], v[86:87], v[80:81]
	v_lshl_add_u64 v[146:147], v[208:209], 1, s[36:37]
	v_pk_mul_f32 v[116:117], v[4:5], v[116:117]
	v_cvt_pk_bf16_f32 v87, v88, v89
	v_cvt_pk_bf16_f32 v88, v80, v81
	s_mov_b32 s5, 0
	v_or_b32_e32 v80, 1, v206
	v_pk_mul_f32 v[116:117], v[120:121], v[116:117]
	v_cvt_pk_bf16_f32 v86, v78, v79
	v_lshl_add_u64 v[78:79], v[146:147], 0, s[4:5]
	v_add_u32_e32 v158, s44, v80
	s_movk_i32 s4, 0x41
	v_cvt_pk_bf16_f32 v89, v116, v117
	v_cmp_gt_i32_e64 s[4:5], s4, v158
	v_lshl_add_u32 v163, v158, 10, 0
	global_store_dwordx4 v[78:79], v[86:89], off sc0 sc1
	s_and_saveexec_b64 s[6:7], s[4:5]
	s_cbranch_execz .LBB0_542
	s_movk_i32 s8, 0xfc00
	v_add3_u32 v81, v163, v207, s8
	ds_read_b128 v[86:89], v81
	ds_read_b128 v[116:119], v81 offset:16
	s_waitcnt lgkmcnt(1)
	v_pk_add_f32 v[112:113], v[112:113], v[88:89]
	v_pk_add_f32 v[110:111], v[110:111], v[86:87]
	s_waitcnt lgkmcnt(0)
	v_pk_add_f32 v[108:109], v[108:109], v[118:119]
	v_pk_add_f32 v[106:107], v[106:107], v[116:117]

; #define LAS __attribute__((address_space(3)))
; __device__ __forceinline__ u32x4 pack8(const f32x4 v0, const f32x4 v1) { u32x4 w; w.x = pk_f16(v0[0], v0[1]); w.y = pk_f16(v0[2], v0[3]); w.z = pk_f16(v1[0], v1[1]); w.w = pk_f16(v1[2], v1[3]); return w; }
; __device__ __forceinline__ void unpack8(const u32x4 w, f32x4& v0, f32x4& v1) { v0 = (f32x4){f16lo(w.x), f16hi(w.x), f16lo(w.y), f16hi(w.y)}; v1 = (f32x4){f16lo(w.z), f16hi(w.z), f16lo(w.w), f16hi(w.w)}; }
; __device__ __forceinline__ void pm_item(LAS float* Vs0, int item, const f16* up, const f16* zs, const float* pscale, f16* branch) {
;     ...
;           for (int q = 0; q < 4; ++q) { const int cc = 4 * cs + q;
;             if (q > 0) { const int cin = cc + hi_off - 1, cout = cc - 1 - lo_off;
;                 if (cin < GW) { const LAS f32x4* vp = (const LAS f32x4*)(Vs + cin * 256 + o * 8); s0 += vp[0]; s1 += vp[1]; }
;                 if (cout >= 0) { const LAS f32x4* vp = (const LAS f32x4*)(Vs + cout * 256 + o * 8); s0 -= vp[0]; s1 -= vp[1]; } }
;             const int clo = cc - lo_off < 0 ? 0 : cc - lo_off, chi = cc + hi_off > GW ? GW : cc + hi_off;
;             const float ic = 1.f / (float)(chi - clo);
;             f32x4 u0, u1, z0, z1; unpack8(cen[cur][q], u0, u1); unpack8(zz[cur][q], z0, z1);
;             *(u32x4*)(branch + zoff + (size_t)(r * GW + q) * D) = pack8((s0 * ic - u0) * sc0 * z0, (s1 * ic - u1) * sc1 * z1); } }
.LBB0_544:
	s_or_b64 exec, exec, s[8:9]
	v_subrev_u32_e32 v80, s33, v80
	v_max_i32_e32 v80, 0, v80
	v_min_i32_e32 v81, 64, v158
	v_sub_u32_e32 v80, v81, v80
	v_cvt_f32_i32_e32 v80, v80
	v_and_b32_e32 v81, 0xffff0000, v66
	v_div_scale_f32 v86, s[8:9], v80, v80, 1.0
	v_rcp_f32_e32 v87, v86
	v_div_scale_f32 v88, vcc, 1.0, v80, 1.0
	s_mov_b32 s8, 0x8000
	v_fma_f32 v89, -v86, v87, 1.0
	v_fmac_f32_e32 v87, v89, v87
	v_mul_f32_e32 v89, v88, v87
	v_fma_f32 v115, -v86, v89, v88
	v_fmac_f32_e32 v89, v115, v87
	v_fma_f32 v86, -v86, v89, v88
	v_div_fmas_f32 v86, v86, v87, v89
	v_div_fixup_f32 v150, v86, v80, 1.0
	v_lshlrev_b32_e32 v80, 16, v66
	v_and_b32_e32 v87, 0xffff0000, v67
	v_lshlrev_b32_e32 v86, 16, v67
	v_and_b32_e32 v67, 0xffff0000, v68
	v_lshlrev_b32_e32 v66, 16, v68
	v_and_b32_e32 v89, 0xffff0000, v69
	v_lshlrev_b32_e32 v88, 16, v69
	v_xor_b32_sdwa v68, s8, v59 dst_sel:WORD_1 dst_unused:UNUSED_PAD src0_sel:DWORD src1_sel:DWORD
	v_xor_b32_sdwa v69, s8, v59 dst_sel:WORD_1 dst_unused:UNUSED_PAD src0_sel:DWORD src1_sel:WORD_1
	v_xor_b32_sdwa v116, s8, v58 dst_sel:WORD_1 dst_unused:UNUSED_PAD src0_sel:DWORD src1_sel:DWORD
	v_xor_b32_sdwa v117, s8, v58 dst_sel:WORD_1 dst_unused:UNUSED_PAD src0_sel:DWORD src1_sel:WORD_1
	v_pk_fma_f32 v[68:69], v[150:151], v[112:113], v[68:69] op_sel_hi:[0,1,1]
	v_pk_fma_f32 v[58:59], v[150:151], v[110:111], v[116:117] op_sel_hi:[0,1,1]
	v_pk_mul_f32 v[58:59], v[6:7], v[58:59]
	v_pk_mul_f32 v[68:69], v[8:9], v[68:69]
	v_pk_mul_f32 v[58:59], v[80:81], v[58:59]
	v_pk_mul_f32 v[68:69], v[86:87], v[68:69]
	v_xor_b32_sdwa v80, s8, v61 dst_sel:WORD_1 dst_unused:UNUSED_PAD src0_sel:DWORD src1_sel:DWORD
	v_xor_b32_sdwa v81, s8, v61 dst_sel:WORD_1 dst_unused:UNUSED_PAD src0_sel:DWORD src1_sel:WORD_1
	v_xor_b32_sdwa v86, s8, v60 dst_sel:WORD_1 dst_unused:UNUSED_PAD src0_sel:DWORD src1_sel:DWORD
	v_xor_b32_sdwa v87, s8, v60 dst_sel:WORD_1 dst_unused:UNUSED_PAD src0_sel:DWORD src1_sel:WORD_1
	v_pk_fma_f32 v[80:81], v[150:151], v[108:109], v[80:81] op_sel_hi:[0,1,1]
	v_pk_fma_f32 v[60:61], v[150:151], v[106:107], v[86:87] op_sel_hi:[0,1,1]
	v_pk_mul_f32 v[60:61], v[2:3], v[60:61]
	v_pk_mul_f32 v[80:81], v[4:5], v[80:81]
	v_pk_mul_f32 v[60:61], v[66:67], v[60:61]
	v_pk_mul_f32 v[80:81], v[88:89], v[80:81]
	v_add_co_u32_e32 v66, vcc, 0x1000, v78
	v_cvt_pk_bf16_f32 v58, v58, v59
	v_cvt_pk_bf16_f32 v59, v68, v69
	v_cvt_pk_bf16_f32 v60, v60, v61
	v_cvt_pk_bf16_f32 v61, v80, v81
	v_addc_co_u32_e32 v67, vcc, 0, v79, vcc
	global_store_dwordx4 v[66:67], v[58:61], off sc0 sc1
	s_movk_i32 s8, 0x41
	s_nop 0
	v_or_b32_e32 v58, 2, v206
	v_add_u32_e32 v159, s44, v58
	v_cmp_gt_i32_e64 s[8:9], s8, v159
	v_lshl_add_u32 v165, v159, 10, 0
	s_and_saveexec_b64 s[10:11], s[8:9]
	s_cbranch_execz .LBB0_546
	s_movk_i32 s12, 0xfc00
	v_add3_u32 v59, v165, v207, s12
	ds_read_b128 v[66:69], v59
	ds_read_b128 v[86:89], v59 offset:16
	s_waitcnt lgkmcnt(1)
	v_pk_add_f32 v[112:113], v[112:113], v[68:69]
	v_pk_add_f32 v[110:111], v[110:111], v[66:67]
	s_waitcnt lgkmcnt(0)
	v_pk_add_f32 v[108:109], v[108:109], v[88:89]
	v_pk_add_f32 v[106:107], v[106:107], v[86:87]

; #define LAS __attribute__((address_space(3)))
; __device__ __forceinline__ u32x4 pack8(const f32x4 v0, const f32x4 v1) { u32x4 w; w.x = pk_f16(v0[0], v0[1]); w.y = pk_f16(v0[2], v0[3]); w.z = pk_f16(v1[0], v1[1]); w.w = pk_f16(v1[2], v1[3]); return w; }
; __device__ __forceinline__ void unpack8(const u32x4 w, f32x4& v0, f32x4& v1) { v0 = (f32x4){f16lo(w.x), f16hi(w.x), f16lo(w.y), f16hi(w.y)}; v1 = (f32x4){f16lo(w.z), f16hi(w.z), f16lo(w.w), f16hi(w.w)}; }
; __device__ __forceinline__ void pm_item(LAS float* Vs0, int item, const f16* up, const f16* zs, const float* pscale, f16* branch) {
;     ...
;           for (int q = 0; q < 4; ++q) { const int cc = 4 * cs + q;
;             if (q > 0) { const int cin = cc + hi_off - 1, cout = cc - 1 - lo_off;
;                 if (cin < GW) { const LAS f32x4* vp = (const LAS f32x4*)(Vs + cin * 256 + o * 8); s0 += vp[0]; s1 += vp[1]; }
;                 if (cout >= 0) { const LAS f32x4* vp = (const LAS f32x4*)(Vs + cout * 256 + o * 8); s0 -= vp[0]; s1 -= vp[1]; } }
;             const int clo = cc - lo_off < 0 ? 0 : cc - lo_off, chi = cc + hi_off > GW ? GW : cc + hi_off;
;             const float ic = 1.f / (float)(chi - clo);
;             f32x4 u0, u1, z0, z1; unpack8(cen[cur][q], u0, u1); unpack8(zz[cur][q], z0, z1);
;             *(u32x4*)(branch + zoff + (size_t)(r * GW + q) * D) = pack8((s0 * ic - u0) * sc0 * z0, (s1 * ic - u1) * sc1 * z1); } }
.LBB0_548:
	s_or_b64 exec, exec, s[12:13]
	v_subrev_u32_e32 v58, s33, v58
	v_max_i32_e32 v58, 0, v58
	v_min_i32_e32 v59, 64, v159
	v_sub_u32_e32 v58, v59, v58
	v_cvt_f32_i32_e32 v58, v58
	v_and_b32_e32 v59, 0xffff0000, v54
	v_div_scale_f32 v60, s[12:13], v58, v58, 1.0
	v_rcp_f32_e32 v61, v60
	v_div_scale_f32 v66, vcc, 1.0, v58, 1.0
	s_mov_b32 s12, 0x8000
	v_fma_f32 v67, -v60, v61, 1.0
	v_fmac_f32_e32 v61, v67, v61
	v_mul_f32_e32 v67, v66, v61
	v_fma_f32 v68, -v60, v67, v66
	v_fmac_f32_e32 v67, v68, v61
	v_fma_f32 v60, -v60, v67, v66
	v_div_fmas_f32 v60, v60, v61, v67
	v_div_fixup_f32 v152, v60, v58, 1.0
	v_lshlrev_b32_e32 v58, 16, v54
	v_and_b32_e32 v61, 0xffff0000, v55
	v_lshlrev_b32_e32 v60, 16, v55
	v_and_b32_e32 v55, 0xffff0000, v56
	v_lshlrev_b32_e32 v54, 16, v56
	v_and_b32_e32 v67, 0xffff0000, v57
	v_lshlrev_b32_e32 v66, 16, v57
	v_xor_b32_sdwa v56, s12, v51 dst_sel:WORD_1 dst_unused:UNUSED_PAD src0_sel:DWORD src1_sel:DWORD
	v_xor_b32_sdwa v57, s12, v51 dst_sel:WORD_1 dst_unused:UNUSED_PAD src0_sel:DWORD src1_sel:WORD_1
	v_xor_b32_sdwa v68, s12, v50 dst_sel:WORD_1 dst_unused:UNUSED_PAD src0_sel:DWORD src1_sel:DWORD
	v_xor_b32_sdwa v69, s12, v50 dst_sel:WORD_1 dst_unused:UNUSED_PAD src0_sel:DWORD src1_sel:WORD_1
	v_pk_fma_f32 v[56:57], v[152:153], v[112:113], v[56:57] op_sel_hi:[0,1,1]
	v_pk_fma_f32 v[50:51], v[152:153], v[110:111], v[68:69] op_sel_hi:[0,1,1]
	v_pk_mul_f32 v[50:51], v[6:7], v[50:51]
	v_pk_mul_f32 v[56:57], v[8:9], v[56:57]
	v_pk_mul_f32 v[50:51], v[58:59], v[50:51]
	v_pk_mul_f32 v[56:57], v[60:61], v[56:57]
	v_xor_b32_sdwa v58, s12, v53 dst_sel:WORD_1 dst_unused:UNUSED_PAD src0_sel:DWORD src1_sel:DWORD
	v_xor_b32_sdwa v59, s12, v53 dst_sel:WORD_1 dst_unused:UNUSED_PAD src0_sel:DWORD src1_sel:WORD_1
	v_xor_b32_sdwa v60, s12, v52 dst_sel:WORD_1 dst_unused:UNUSED_PAD src0_sel:DWORD src1_sel:DWORD
	v_xor_b32_sdwa v61, s12, v52 dst_sel:WORD_1 dst_unused:UNUSED_PAD src0_sel:DWORD src1_sel:WORD_1
	v_pk_fma_f32 v[58:59], v[152:153], v[108:109], v[58:59] op_sel_hi:[0,1,1]
	v_pk_fma_f32 v[52:53], v[152:153], v[106:107], v[60:61] op_sel_hi:[0,1,1]
	v_pk_mul_f32 v[52:53], v[2:3], v[52:53]
	v_pk_mul_f32 v[58:59], v[4:5], v[58:59]
	v_pk_mul_f32 v[52:53], v[54:55], v[52:53]
	v_pk_mul_f32 v[58:59], v[66:67], v[58:59]
	v_add_co_u32_e32 v54, vcc, 0x2000, v78
	v_cvt_pk_bf16_f32 v50, v50, v51
	v_cvt_pk_bf16_f32 v51, v56, v57
	v_cvt_pk_bf16_f32 v52, v52, v53
	v_cvt_pk_bf16_f32 v53, v58, v59
	v_addc_co_u32_e32 v55, vcc, 0, v79, vcc
	global_store_dwordx4 v[54:55], v[50:53], off sc0 sc1
	s_movk_i32 s12, 0x41
	s_nop 0
	v_or_b32_e32 v50, 3, v222
	v_add_u32_e32 v160, s44, v50
	v_cmp_gt_i32_e64 s[12:13], s12, v160
	v_lshl_add_u32 v167, v160, 10, 0
	s_and_saveexec_b64 s[14:15], s[12:13]
	s_cbranch_execz .LBB0_550
	s_movk_i32 s19, 0xfc00
	v_add3_u32 v51, v167, v207, s19
	ds_read_b128 v[52:55], v51
	ds_read_b128 v[56:59], v51 offset:16
	s_waitcnt lgkmcnt(1)
	v_pk_add_f32 v[112:113], v[112:113], v[54:55]
	v_pk_add_f32 v[110:111], v[110:111], v[52:53]
	s_waitcnt lgkmcnt(0)
	v_pk_add_f32 v[108:109], v[108:109], v[58:59]
	v_pk_add_f32 v[106:107], v[106:107], v[56:57]

; #define LAS __attribute__((address_space(3)))
; __device__ __forceinline__ u32x4 pack8(const f32x4 v0, const f32x4 v1) { u32x4 w; w.x = pk_f16(v0[0], v0[1]); w.y = pk_f16(v0[2], v0[3]); w.z = pk_f16(v1[0], v1[1]); w.w = pk_f16(v1[2], v1[3]); return w; }
; __device__ __forceinline__ void unpack8(const u32x4 w, f32x4& v0, f32x4& v1) { v0 = (f32x4){f16lo(w.x), f16hi(w.x), f16lo(w.y), f16hi(w.y)}; v1 = (f32x4){f16lo(w.z), f16hi(w.z), f16lo(w.w), f16hi(w.w)}; }
; __device__ __forceinline__ void pm_item(LAS float* Vs0, int item, const f16* up, const f16* zs, const float* pscale, f16* branch) {
;     ...
;         if (rr >= 1) {
;             if (r + hi_off - 1 < ROWS) {
; #pragma unroll
;                 for (int q = 0; q < 4; ++q) { f32x4 v0, v1; unpack8(hi[cur][q], v0, v1);
; #pragma unroll
;                     for (int e = 0; e < 4; ++e) { rs[q][e] += v0[e]; rs[q][4 + e] += v1[e]; } } }
;     ...
;           for (int q = 0; q < 4; ++q) { const int cc = 4 * cs + q;
;             if (q > 0) { const int cin = cc + hi_off - 1, cout = cc - 1 - lo_off;
;                 if (cin < GW) { const LAS f32x4* vp = (const LAS f32x4*)(Vs + cin * 256 + o * 8); s0 += vp[0]; s1 += vp[1]; }
;                 if (cout >= 0) { const LAS f32x4* vp = (const LAS f32x4*)(Vs + cout * 256 + o * 8); s0 -= vp[0]; s1 -= vp[1]; } }
;             const int clo = cc - lo_off < 0 ? 0 : cc - lo_off, chi = cc + hi_off > GW ? GW : cc + hi_off;
;             const float ic = 1.f / (float)(chi - clo);
;             f32x4 u0, u1, z0, z1; unpack8(cen[cur][q], u0, u1); unpack8(zz[cur][q], z0, z1);
;             *(u32x4*)(branch + zoff + (size_t)(r * GW + q) * D) = pack8((s0 * ic - u0) * sc0 * z0, (s1 * ic - u1) * sc1 * z1); } }
.LBB0_552:
	s_or_b64 exec, exec, s[20:21]
	v_subrev_u32_e32 v50, s33, v50
	v_max_i32_e32 v50, 0, v50
	v_min_i32_e32 v51, 64, v160
	v_sub_u32_e32 v50, v51, v50
	v_cvt_f32_i32_e32 v50, v50
	s_sub_i32 s55, 0x81, s44
	v_div_scale_f32 v51, s[18:19], v50, v50, 1.0
	v_rcp_f32_e32 v52, v51
	v_div_scale_f32 v53, vcc, 1.0, v50, 1.0
	s_mov_b32 s18, 0x8000
	v_fma_f32 v54, -v51, v52, 1.0
	v_fmac_f32_e32 v52, v54, v52
	v_mul_f32_e32 v54, v53, v52
	v_fma_f32 v55, -v51, v54, v53
	v_fmac_f32_e32 v54, v55, v52
	v_fma_f32 v51, -v51, v54, v53
	v_div_fmas_f32 v51, v51, v52, v54
	v_div_fixup_f32 v154, v51, v50, 1.0
	v_and_b32_e32 v51, 0xffff0000, v46
	v_lshlrev_b32_e32 v50, 16, v46
	v_and_b32_e32 v53, 0xffff0000, v47
	v_lshlrev_b32_e32 v52, 16, v47
	v_and_b32_e32 v47, 0xffff0000, v48
	v_lshlrev_b32_e32 v46, 16, v48
	v_and_b32_e32 v55, 0xffff0000, v49
	v_lshlrev_b32_e32 v54, 16, v49
	v_xor_b32_sdwa v48, s18, v43 dst_sel:WORD_1 dst_unused:UNUSED_PAD src0_sel:DWORD src1_sel:DWORD
	v_xor_b32_sdwa v49, s18, v43 dst_sel:WORD_1 dst_unused:UNUSED_PAD src0_sel:DWORD src1_sel:WORD_1
	v_xor_b32_sdwa v56, s18, v42 dst_sel:WORD_1 dst_unused:UNUSED_PAD src0_sel:DWORD src1_sel:DWORD
	v_xor_b32_sdwa v57, s18, v42 dst_sel:WORD_1 dst_unused:UNUSED_PAD src0_sel:DWORD src1_sel:WORD_1
	v_pk_fma_f32 v[48:49], v[154:155], v[112:113], v[48:49] op_sel_hi:[0,1,1]
	v_pk_fma_f32 v[42:43], v[154:155], v[110:111], v[56:57] op_sel_hi:[0,1,1]
	v_pk_mul_f32 v[42:43], v[6:7], v[42:43]
	v_pk_mul_f32 v[48:49], v[8:9], v[48:49]
	v_pk_mul_f32 v[42:43], v[50:51], v[42:43]
	v_pk_mul_f32 v[48:49], v[52:53], v[48:49]
	v_xor_b32_sdwa v50, s18, v45 dst_sel:WORD_1 dst_unused:UNUSED_PAD src0_sel:DWORD src1_sel:DWORD
	v_xor_b32_sdwa v51, s18, v45 dst_sel:WORD_1 dst_unused:UNUSED_PAD src0_sel:DWORD src1_sel:WORD_1
	v_xor_b32_sdwa v52, s18, v44 dst_sel:WORD_1 dst_unused:UNUSED_PAD src0_sel:DWORD src1_sel:DWORD
	v_xor_b32_sdwa v53, s18, v44 dst_sel:WORD_1 dst_unused:UNUSED_PAD src0_sel:DWORD src1_sel:WORD_1
	v_pk_fma_f32 v[50:51], v[154:155], v[108:109], v[50:51] op_sel_hi:[0,1,1]
	v_pk_fma_f32 v[44:45], v[154:155], v[106:107], v[52:53] op_sel_hi:[0,1,1]
	v_pk_mul_f32 v[44:45], v[2:3], v[44:45]
	v_pk_mul_f32 v[50:51], v[4:5], v[50:51]
	v_pk_mul_f32 v[44:45], v[46:47], v[44:45]
	v_pk_mul_f32 v[50:51], v[54:55], v[50:51]
	v_add_co_u32_e32 v46, vcc, 0x3000, v78
	s_or_b32 s18, s45, 1
	v_cvt_pk_bf16_f32 v42, v42, v43
	v_cvt_pk_bf16_f32 v43, v48, v49
	v_cvt_pk_bf16_f32 v44, v44, v45
	v_cvt_pk_bf16_f32 v45, v50, v51
	v_addc_co_u32_e32 v47, vcc, 0, v79, vcc
	s_cmp_ge_u32 s18, s55
	global_store_dwordx4 v[46:47], v[42:45], off sc0 sc1
	s_cbranch_scc1 .LBB0_554
	s_nop 0
	v_and_b32_e32 v43, 0xffff0000, v38
	v_lshlrev_b32_e32 v42, 16, v38
	v_and_b32_e32 v45, 0xffff0000, v39
	v_lshlrev_b32_e32 v44, 16, v39
	v_and_b32_e32 v47, 0xffff0000, v40
	v_lshlrev_b32_e32 v46, 16, v40
	v_and_b32_e32 v49, 0xffff0000, v41
	v_lshlrev_b32_e32 v48, 16, v41
	v_pk_add_f32 v[170:171], v[170:171], v[42:43]
	v_pk_add_f32 v[196:197], v[196:197], v[46:47]
	v_pk_add_f32 v[200:201], v[200:201], v[44:45]
	v_pk_add_f32 v[198:199], v[198:199], v[48:49]
	v_and_b32_e32 v43, 0xffff0000, v30
	v_lshlrev_b32_e32 v42, 16, v30
	v_and_b32_e32 v45, 0xffff0000, v31
	v_lshlrev_b32_e32 v44, 16, v31
	v_and_b32_e32 v47, 0xffff0000, v32
	v_lshlrev_b32_e32 v46, 16, v32
	v_and_b32_e32 v49, 0xffff0000, v33
	v_lshlrev_b32_e32 v48, 16, v33
	v_pk_add_f32 v[192:193], v[192:193], v[42:43]
	v_pk_add_f32 v[188:189], v[188:189], v[46:47]
	v_pk_add_f32 v[194:195], v[194:195], v[44:45]
	v_pk_add_f32 v[190:191], v[190:191], v[48:49]
	v_and_b32_e32 v43, 0xffff0000, v34
	v_lshlrev_b32_e32 v42, 16, v34
	v_and_b32_e32 v45, 0xffff0000, v35
	v_lshlrev_b32_e32 v44, 16, v35
	v_and_b32_e32 v47, 0xffff0000, v36
	v_lshlrev_b32_e32 v46, 16, v36
	v_and_b32_e32 v49, 0xffff0000, v37
	v_lshlrev_b32_e32 v48, 16, v37
	v_pk_add_f32 v[184:185], v[184:185], v[42:43]
	v_pk_add_f32 v[180:181], v[180:181], v[46:47]
	v_pk_add_f32 v[186:187], v[186:187], v[44:45]
	v_pk_add_f32 v[182:183], v[182:183], v[48:49]
	v_and_b32_e32 v43, 0xffff0000, v26
	v_lshlrev_b32_e32 v42, 16, v26
	v_and_b32_e32 v45, 0xffff0000, v27
	v_lshlrev_b32_e32 v44, 16, v27
	v_and_b32_e32 v47, 0xffff0000, v28
	v_lshlrev_b32_e32 v46, 16, v28
	v_and_b32_e32 v49, 0xffff0000, v29
	v_lshlrev_b32_e32 v48, 16, v29
	v_pk_add_f32 v[176:177], v[176:177], v[42:43]
	v_pk_add_f32 v[172:173], v[172:173], v[46:47]
	v_pk_add_f32 v[178:179], v[178:179], v[44:45]
	v_pk_add_f32 v[174:175], v[174:175], v[48:49]

; #define LAS __attribute__((address_space(3)))
; __device__ __forceinline__ u32x4 pack8(const f32x4 v0, const f32x4 v1) { u32x4 w; w.x = pk_f16(v0[0], v0[1]); w.y = pk_f16(v0[2], v0[3]); w.z = pk_f16(v1[0], v1[1]); w.w = pk_f16(v1[2], v1[3]); return w; }
; __device__ __forceinline__ void unpack8(const u32x4 w, f32x4& v0, f32x4& v1) { v0 = (f32x4){f16lo(w.x), f16hi(w.x), f16lo(w.y), f16hi(w.y)}; v1 = (f32x4){f16lo(w.z), f16hi(w.z), f16lo(w.w), f16hi(w.w)}; }
; __device__ __forceinline__ void pm_item(LAS float* Vs0, int item, const f16* up, const f16* zs, const float* pscale, f16* branch) {
;     ...
;           for (int q = 0; q < 4; ++q) { const int cc = 4 * cs + q;
;             if (q > 0) { const int cin = cc + hi_off - 1, cout = cc - 1 - lo_off;
;                 if (cin < GW) { const LAS f32x4* vp = (const LAS f32x4*)(Vs + cin * 256 + o * 8); s0 += vp[0]; s1 += vp[1]; }
;                 if (cout >= 0) { const LAS f32x4* vp = (const LAS f32x4*)(Vs + cout * 256 + o * 8); s0 -= vp[0]; s1 -= vp[1]; } }
;             const int clo = cc - lo_off < 0 ? 0 : cc - lo_off, chi = cc + hi_off > GW ? GW : cc + hi_off;
;             const float ic = 1.f / (float)(chi - clo);
;             f32x4 u0, u1, z0, z1; unpack8(cen[cur][q], u0, u1); unpack8(zz[cur][q], z0, z1);
;             *(u32x4*)(branch + zoff + (size_t)(r * GW + q) * D) = pack8((s0 * ic - u0) * sc0 * z0, (s1 * ic - u1) * sc1 * z1); } }
.LBB0_565:
	s_or_b64 exec, exec, s[20:21]
	s_mov_b32 s19, 0x8000
	v_mov_b32_e32 v149, v148
	v_and_b32_e32 v223, 0xffff0000, v102
	v_lshlrev_b32_e32 v222, 16, v102
	v_and_b32_e32 v225, 0xffff0000, v103
	v_lshlrev_b32_e32 v224, 16, v103
	v_and_b32_e32 v103, 0xffff0000, v104
	v_lshlrev_b32_e32 v102, 16, v104
	v_and_b32_e32 v227, 0xffff0000, v105
	v_lshlrev_b32_e32 v226, 16, v105
	v_xor_b32_sdwa v104, s19, v99 dst_sel:WORD_1 dst_unused:UNUSED_PAD src0_sel:DWORD src1_sel:DWORD
	v_xor_b32_sdwa v105, s19, v99 dst_sel:WORD_1 dst_unused:UNUSED_PAD src0_sel:DWORD src1_sel:WORD_1
	v_mov_b32_e32 v228, v148
	v_mov_b32_e32 v229, v148
	v_xor_b32_sdwa v230, s19, v98 dst_sel:WORD_1 dst_unused:UNUSED_PAD src0_sel:DWORD src1_sel:DWORD
	v_xor_b32_sdwa v231, s19, v98 dst_sel:WORD_1 dst_unused:UNUSED_PAD src0_sel:DWORD src1_sel:WORD_1
	v_pk_fma_f32 v[104:105], v[228:229], v[144:145], v[104:105]
	v_pk_fma_f32 v[98:99], v[148:149], v[142:143], v[230:231]
	v_pk_mul_f32 v[104:105], v[8:9], v[104:105]
	v_pk_mul_f32 v[98:99], v[6:7], v[98:99]
	v_pk_mul_f32 v[104:105], v[224:225], v[104:105]
	v_pk_mul_f32 v[98:99], v[222:223], v[98:99]
	v_xor_b32_sdwa v222, s19, v101 dst_sel:WORD_1 dst_unused:UNUSED_PAD src0_sel:DWORD src1_sel:DWORD
	v_xor_b32_sdwa v223, s19, v101 dst_sel:WORD_1 dst_unused:UNUSED_PAD src0_sel:DWORD src1_sel:WORD_1
	v_xor_b32_sdwa v224, s19, v100 dst_sel:WORD_1 dst_unused:UNUSED_PAD src0_sel:DWORD src1_sel:DWORD
	v_xor_b32_sdwa v225, s19, v100 dst_sel:WORD_1 dst_unused:UNUSED_PAD src0_sel:DWORD src1_sel:WORD_1
	v_pk_fma_f32 v[222:223], v[228:229], v[140:141], v[222:223]
	v_pk_fma_f32 v[100:101], v[148:149], v[138:139], v[224:225]
	v_pk_mul_f32 v[222:223], v[4:5], v[222:223]
	v_pk_mul_f32 v[100:101], v[2:3], v[100:101]
	v_pk_mul_f32 v[222:223], v[226:227], v[222:223]
	v_pk_mul_f32 v[102:103], v[102:103], v[100:101]
	s_lshl_b32 s18, s18, 18
	s_mov_b32 s19, 0
	v_mov_b32_e32 v151, v150
	v_mov_b32_e32 v153, v152
	v_mov_b32_e32 v155, v154
	v_cvt_pk_bf16_f32 v100, v98, v99
	v_cvt_pk_bf16_f32 v101, v104, v105
	v_cvt_pk_bf16_f32 v102, v102, v103
	v_cvt_pk_bf16_f32 v103, v222, v223
	v_lshl_add_u64 v[98:99], v[146:147], 0, s[18:19]
	global_store_dwordx4 v[98:99], v[100:103], off sc0 sc1
	s_and_saveexec_b64 s[20:21], s[4:5]
	s_cbranch_execz .LBB0_567
	v_lshl_add_u32 v100, v158, 10, s25
	s_movk_i32 s18, 0xfc00
	v_add3_u32 v104, v100, v207, s18
	ds_read_b128 v[100:103], v104
	ds_read_b128 v[222:225], v104 offset:16
	s_waitcnt lgkmcnt(1)
	v_pk_add_f32 v[144:145], v[144:145], v[102:103]
	v_pk_add_f32 v[142:143], v[142:143], v[100:101]
	s_waitcnt lgkmcnt(0)
	v_pk_add_f32 v[140:141], v[140:141], v[224:225]
	v_pk_add_f32 v[138:139], v[138:139], v[222:223]

; #define LAS __attribute__((address_space(3)))
; __device__ __forceinline__ u32x4 pack8(const f32x4 v0, const f32x4 v1) { u32x4 w; w.x = pk_f16(v0[0], v0[1]); w.y = pk_f16(v0[2], v0[3]); w.z = pk_f16(v1[0], v1[1]); w.w = pk_f16(v1[2], v1[3]); return w; }
; __device__ __forceinline__ void unpack8(const u32x4 w, f32x4& v0, f32x4& v1) { v0 = (f32x4){f16lo(w.x), f16hi(w.x), f16lo(w.y), f16hi(w.y)}; v1 = (f32x4){f16lo(w.z), f16hi(w.z), f16lo(w.w), f16hi(w.w)}; }
; __device__ __forceinline__ void pm_item(LAS float* Vs0, int item, const f16* up, const f16* zs, const float* pscale, f16* branch) {
;     ...
;           for (int q = 0; q < 4; ++q) { const int cc = 4 * cs + q;
;             if (q > 0) { const int cin = cc + hi_off - 1, cout = cc - 1 - lo_off;
;                 if (cin < GW) { const LAS f32x4* vp = (const LAS f32x4*)(Vs + cin * 256 + o * 8); s0 += vp[0]; s1 += vp[1]; }
;                 if (cout >= 0) { const LAS f32x4* vp = (const LAS f32x4*)(Vs + cout * 256 + o * 8); s0 -= vp[0]; s1 -= vp[1]; } }
;             const int clo = cc - lo_off < 0 ? 0 : cc - lo_off, chi = cc + hi_off > GW ? GW : cc + hi_off;
;             const float ic = 1.f / (float)(chi - clo);
;             f32x4 u0, u1, z0, z1; unpack8(cen[cur][q], u0, u1); unpack8(zz[cur][q], z0, z1);
;             *(u32x4*)(branch + zoff + (size_t)(r * GW + q) * D) = pack8((s0 * ic - u0) * sc0 * z0, (s1 * ic - u1) * sc1 * z1); } }
.LBB0_569:
	s_or_b64 exec, exec, s[20:21]
	s_mov_b32 s18, 0x8000
	v_and_b32_e32 v101, 0xffff0000, v94
	v_lshlrev_b32_e32 v100, 16, v94
	v_and_b32_e32 v103, 0xffff0000, v95
	v_lshlrev_b32_e32 v102, 16, v95
	v_and_b32_e32 v95, 0xffff0000, v96
	v_lshlrev_b32_e32 v94, 16, v96
	v_and_b32_e32 v105, 0xffff0000, v97
	v_lshlrev_b32_e32 v104, 16, v97
	v_xor_b32_sdwa v96, s18, v91 dst_sel:WORD_1 dst_unused:UNUSED_PAD src0_sel:DWORD src1_sel:DWORD
	v_xor_b32_sdwa v97, s18, v91 dst_sel:WORD_1 dst_unused:UNUSED_PAD src0_sel:DWORD src1_sel:WORD_1
	v_mov_b32_e32 v222, v150
	v_mov_b32_e32 v223, v150
	v_xor_b32_sdwa v224, s18, v90 dst_sel:WORD_1 dst_unused:UNUSED_PAD src0_sel:DWORD src1_sel:DWORD
	v_xor_b32_sdwa v225, s18, v90 dst_sel:WORD_1 dst_unused:UNUSED_PAD src0_sel:DWORD src1_sel:WORD_1
	v_pk_fma_f32 v[96:97], v[222:223], v[144:145], v[96:97]
	v_pk_fma_f32 v[90:91], v[150:151], v[142:143], v[224:225]
	v_pk_mul_f32 v[96:97], v[8:9], v[96:97]
	v_pk_mul_f32 v[90:91], v[6:7], v[90:91]
	v_pk_mul_f32 v[96:97], v[102:103], v[96:97]
	v_pk_mul_f32 v[90:91], v[100:101], v[90:91]
	v_xor_b32_sdwa v100, s18, v93 dst_sel:WORD_1 dst_unused:UNUSED_PAD src0_sel:DWORD src1_sel:DWORD
	v_xor_b32_sdwa v101, s18, v93 dst_sel:WORD_1 dst_unused:UNUSED_PAD src0_sel:DWORD src1_sel:WORD_1
	v_xor_b32_sdwa v102, s18, v92 dst_sel:WORD_1 dst_unused:UNUSED_PAD src0_sel:DWORD src1_sel:DWORD
	v_xor_b32_sdwa v103, s18, v92 dst_sel:WORD_1 dst_unused:UNUSED_PAD src0_sel:DWORD src1_sel:WORD_1
	v_pk_fma_f32 v[100:101], v[222:223], v[140:141], v[100:101]
	v_pk_fma_f32 v[92:93], v[150:151], v[138:139], v[102:103]
	v_pk_mul_f32 v[100:101], v[4:5], v[100:101]
	v_pk_mul_f32 v[92:93], v[2:3], v[92:93]
	v_pk_mul_f32 v[100:101], v[104:105], v[100:101]
	v_pk_mul_f32 v[92:93], v[94:95], v[92:93]
	v_add_co_u32_e32 v94, vcc, 0x1000, v98
	v_cvt_pk_bf16_f32 v90, v90, v91
	v_cvt_pk_bf16_f32 v91, v96, v97
	v_cvt_pk_bf16_f32 v92, v92, v93
	v_cvt_pk_bf16_f32 v93, v100, v101
	v_addc_co_u32_e32 v95, vcc, 0, v99, vcc
	global_store_dwordx4 v[94:95], v[90:93], off sc0 sc1
	s_and_saveexec_b64 s[20:21], s[8:9]
	s_cbranch_execz .LBB0_571
	v_lshl_add_u32 v90, v159, 10, s25
	s_movk_i32 s18, 0xfc00
	v_add3_u32 v94, v90, v207, s18
	ds_read_b128 v[90:93], v94
	ds_read_b128 v[94:97], v94 offset:16
	s_waitcnt lgkmcnt(1)
	v_pk_add_f32 v[144:145], v[144:145], v[92:93]
	v_pk_add_f32 v[142:143], v[142:143], v[90:91]
	s_waitcnt lgkmcnt(0)
	v_pk_add_f32 v[140:141], v[140:141], v[96:97]
	v_pk_add_f32 v[138:139], v[138:139], v[94:95]

; #define LAS __attribute__((address_space(3)))
; __device__ __forceinline__ u32x4 pack8(const f32x4 v0, const f32x4 v1) { u32x4 w; w.x = pk_f16(v0[0], v0[1]); w.y = pk_f16(v0[2], v0[3]); w.z = pk_f16(v1[0], v1[1]); w.w = pk_f16(v1[2], v1[3]); return w; }
; __device__ __forceinline__ void unpack8(const u32x4 w, f32x4& v0, f32x4& v1) { v0 = (f32x4){f16lo(w.x), f16hi(w.x), f16lo(w.y), f16hi(w.y)}; v1 = (f32x4){f16lo(w.z), f16hi(w.z), f16lo(w.w), f16hi(w.w)}; }
; __device__ __forceinline__ void pm_item(LAS float* Vs0, int item, const f16* up, const f16* zs, const float* pscale, f16* branch) {
;     ...
;           for (int q = 0; q < 4; ++q) { const int cc = 4 * cs + q;
;             if (q > 0) { const int cin = cc + hi_off - 1, cout = cc - 1 - lo_off;
;                 if (cin < GW) { const LAS f32x4* vp = (const LAS f32x4*)(Vs + cin * 256 + o * 8); s0 += vp[0]; s1 += vp[1]; }
;                 if (cout >= 0) { const LAS f32x4* vp = (const LAS f32x4*)(Vs + cout * 256 + o * 8); s0 -= vp[0]; s1 -= vp[1]; } }
;             const int clo = cc - lo_off < 0 ? 0 : cc - lo_off, chi = cc + hi_off > GW ? GW : cc + hi_off;
;             const float ic = 1.f / (float)(chi - clo);
;             f32x4 u0, u1, z0, z1; unpack8(cen[cur][q], u0, u1); unpack8(zz[cur][q], z0, z1);
;             *(u32x4*)(branch + zoff + (size_t)(r * GW + q) * D) = pack8((s0 * ic - u0) * sc0 * z0, (s1 * ic - u1) * sc1 * z1); } }
.LBB0_573:
	s_or_b64 exec, exec, s[20:21]
	s_mov_b32 s18, 0x8000
	v_and_b32_e32 v91, 0xffff0000, v82
	v_lshlrev_b32_e32 v90, 16, v82
	v_and_b32_e32 v93, 0xffff0000, v83
	v_lshlrev_b32_e32 v92, 16, v83
	v_and_b32_e32 v83, 0xffff0000, v84
	v_lshlrev_b32_e32 v82, 16, v84
	v_and_b32_e32 v95, 0xffff0000, v85
	v_lshlrev_b32_e32 v94, 16, v85
	v_xor_b32_sdwa v84, s18, v75 dst_sel:WORD_1 dst_unused:UNUSED_PAD src0_sel:DWORD src1_sel:DWORD
	v_xor_b32_sdwa v85, s18, v75 dst_sel:WORD_1 dst_unused:UNUSED_PAD src0_sel:DWORD src1_sel:WORD_1
	v_mov_b32_e32 v96, v152
	v_mov_b32_e32 v97, v152
	v_xor_b32_sdwa v100, s18, v74 dst_sel:WORD_1 dst_unused:UNUSED_PAD src0_sel:DWORD src1_sel:DWORD
	v_xor_b32_sdwa v101, s18, v74 dst_sel:WORD_1 dst_unused:UNUSED_PAD src0_sel:DWORD src1_sel:WORD_1
	v_pk_fma_f32 v[84:85], v[96:97], v[144:145], v[84:85]
	v_pk_fma_f32 v[74:75], v[152:153], v[142:143], v[100:101]
	v_pk_mul_f32 v[84:85], v[8:9], v[84:85]
	v_pk_mul_f32 v[74:75], v[6:7], v[74:75]
	v_pk_mul_f32 v[84:85], v[92:93], v[84:85]
	v_pk_mul_f32 v[74:75], v[90:91], v[74:75]
	v_xor_b32_sdwa v90, s18, v77 dst_sel:WORD_1 dst_unused:UNUSED_PAD src0_sel:DWORD src1_sel:DWORD
	v_xor_b32_sdwa v91, s18, v77 dst_sel:WORD_1 dst_unused:UNUSED_PAD src0_sel:DWORD src1_sel:WORD_1
	v_xor_b32_sdwa v92, s18, v76 dst_sel:WORD_1 dst_unused:UNUSED_PAD src0_sel:DWORD src1_sel:DWORD
	v_xor_b32_sdwa v93, s18, v76 dst_sel:WORD_1 dst_unused:UNUSED_PAD src0_sel:DWORD src1_sel:WORD_1
	v_pk_fma_f32 v[90:91], v[96:97], v[140:141], v[90:91]
	v_pk_fma_f32 v[76:77], v[152:153], v[138:139], v[92:93]
	v_pk_mul_f32 v[90:91], v[4:5], v[90:91]
	v_pk_mul_f32 v[76:77], v[2:3], v[76:77]
	v_pk_mul_f32 v[90:91], v[94:95], v[90:91]
	v_pk_mul_f32 v[76:77], v[82:83], v[76:77]
	v_add_co_u32_e32 v82, vcc, 0x2000, v98
	v_cvt_pk_bf16_f32 v74, v74, v75
	v_cvt_pk_bf16_f32 v75, v84, v85
	v_cvt_pk_bf16_f32 v76, v76, v77
	v_cvt_pk_bf16_f32 v77, v90, v91
	v_addc_co_u32_e32 v83, vcc, 0, v99, vcc
	global_store_dwordx4 v[82:83], v[74:77], off sc0 sc1
	s_and_saveexec_b64 s[20:21], s[12:13]
	s_cbranch_execz .LBB0_575
	v_lshl_add_u32 v74, v160, 10, s25
	s_movk_i32 s18, 0xfc00
	v_add3_u32 v82, v74, v207, s18
	ds_read_b128 v[74:77], v82
	ds_read_b128 v[82:85], v82 offset:16
	s_waitcnt lgkmcnt(1)
	v_pk_add_f32 v[144:145], v[144:145], v[76:77]
	v_pk_add_f32 v[142:143], v[142:143], v[74:75]
	s_waitcnt lgkmcnt(0)
	v_pk_add_f32 v[140:141], v[140:141], v[84:85]
	v_pk_add_f32 v[138:139], v[138:139], v[82:83]

; #define LAS __attribute__((address_space(3)))
; __device__ __forceinline__ u32x4 pack8(const f32x4 v0, const f32x4 v1) { u32x4 w; w.x = pk_f16(v0[0], v0[1]); w.y = pk_f16(v0[2], v0[3]); w.z = pk_f16(v1[0], v1[1]); w.w = pk_f16(v1[2], v1[3]); return w; }
; __device__ __forceinline__ void unpack8(const u32x4 w, f32x4& v0, f32x4& v1) { v0 = (f32x4){f16lo(w.x), f16hi(w.x), f16lo(w.y), f16hi(w.y)}; v1 = (f32x4){f16lo(w.z), f16hi(w.z), f16lo(w.w), f16hi(w.w)}; }
; __device__ __forceinline__ void pm_item(LAS float* Vs0, int item, const f16* up, const f16* zs, const float* pscale, f16* branch) {
;     ...
;         if (rr >= 1) {
;             if (r + hi_off - 1 < ROWS) {
; #pragma unroll
;                 for (int q = 0; q < 4; ++q) { f32x4 v0, v1; unpack8(hi[cur][q], v0, v1);
; #pragma unroll
;                     for (int e = 0; e < 4; ++e) { rs[q][e] += v0[e]; rs[q][4 + e] += v1[e]; } } }
;     ...
;           for (int q = 0; q < 4; ++q) { const int cc = 4 * cs + q;
;             if (q > 0) { const int cin = cc + hi_off - 1, cout = cc - 1 - lo_off;
;                 if (cin < GW) { const LAS f32x4* vp = (const LAS f32x4*)(Vs + cin * 256 + o * 8); s0 += vp[0]; s1 += vp[1]; }
;                 if (cout >= 0) { const LAS f32x4* vp = (const LAS f32x4*)(Vs + cout * 256 + o * 8); s0 -= vp[0]; s1 -= vp[1]; } }
;             const int clo = cc - lo_off < 0 ? 0 : cc - lo_off, chi = cc + hi_off > GW ? GW : cc + hi_off;
;             const float ic = 1.f / (float)(chi - clo);
;             f32x4 u0, u1, z0, z1; unpack8(cen[cur][q], u0, u1); unpack8(zz[cur][q], z0, z1);
;             *(u32x4*)(branch + zoff + (size_t)(r * GW + q) * D) = pack8((s0 * ic - u0) * sc0 * z0, (s1 * ic - u1) * sc1 * z1); } }
.LBB0_577:
	s_or_b64 exec, exec, s[20:21]
	s_mov_b32 s18, 0x8000
	v_and_b32_e32 v75, 0xffff0000, v70
	v_lshlrev_b32_e32 v74, 16, v70
	v_and_b32_e32 v77, 0xffff0000, v71
	v_lshlrev_b32_e32 v76, 16, v71
	v_and_b32_e32 v71, 0xffff0000, v72
	v_lshlrev_b32_e32 v70, 16, v72
	v_and_b32_e32 v83, 0xffff0000, v73
	v_lshlrev_b32_e32 v82, 16, v73
	v_xor_b32_sdwa v72, s18, v63 dst_sel:WORD_1 dst_unused:UNUSED_PAD src0_sel:DWORD src1_sel:DWORD
	v_xor_b32_sdwa v73, s18, v63 dst_sel:WORD_1 dst_unused:UNUSED_PAD src0_sel:DWORD src1_sel:WORD_1
	v_mov_b32_e32 v84, v154
	v_mov_b32_e32 v85, v154
	v_xor_b32_sdwa v90, s18, v62 dst_sel:WORD_1 dst_unused:UNUSED_PAD src0_sel:DWORD src1_sel:DWORD
	v_xor_b32_sdwa v91, s18, v62 dst_sel:WORD_1 dst_unused:UNUSED_PAD src0_sel:DWORD src1_sel:WORD_1
	v_pk_fma_f32 v[72:73], v[84:85], v[144:145], v[72:73]
	v_pk_fma_f32 v[62:63], v[154:155], v[142:143], v[90:91]
	v_pk_mul_f32 v[72:73], v[8:9], v[72:73]
	v_pk_mul_f32 v[62:63], v[6:7], v[62:63]
	v_pk_mul_f32 v[72:73], v[76:77], v[72:73]
	v_pk_mul_f32 v[62:63], v[74:75], v[62:63]
	v_xor_b32_sdwa v74, s18, v65 dst_sel:WORD_1 dst_unused:UNUSED_PAD src0_sel:DWORD src1_sel:DWORD
	v_xor_b32_sdwa v75, s18, v65 dst_sel:WORD_1 dst_unused:UNUSED_PAD src0_sel:DWORD src1_sel:WORD_1
	v_xor_b32_sdwa v76, s18, v64 dst_sel:WORD_1 dst_unused:UNUSED_PAD src0_sel:DWORD src1_sel:DWORD
	v_xor_b32_sdwa v77, s18, v64 dst_sel:WORD_1 dst_unused:UNUSED_PAD src0_sel:DWORD src1_sel:WORD_1
	v_pk_fma_f32 v[74:75], v[84:85], v[140:141], v[74:75]
	v_pk_fma_f32 v[64:65], v[154:155], v[138:139], v[76:77]
	v_pk_mul_f32 v[74:75], v[4:5], v[74:75]
	v_pk_mul_f32 v[64:65], v[2:3], v[64:65]
	v_pk_mul_f32 v[74:75], v[82:83], v[74:75]
	v_pk_mul_f32 v[64:65], v[70:71], v[64:65]
	v_add_co_u32_e32 v70, vcc, 0x3000, v98
	s_or_b32 s18, s45, 2
	v_cvt_pk_bf16_f32 v62, v62, v63
	v_cvt_pk_bf16_f32 v63, v72, v73
	v_cvt_pk_bf16_f32 v64, v64, v65
	v_cvt_pk_bf16_f32 v65, v74, v75
	v_addc_co_u32_e32 v71, vcc, 0, v99, vcc
	s_cmp_ge_u32 s18, s55
	global_store_dwordx4 v[70:71], v[62:65], off sc0 sc1
	s_cbranch_scc1 .LBB0_579
	s_waitcnt vmcnt(7)
	v_and_b32_e32 v63, 0xffff0000, v134
	v_lshlrev_b32_e32 v62, 16, v134
	v_and_b32_e32 v65, 0xffff0000, v135
	v_lshlrev_b32_e32 v64, 16, v135
	v_and_b32_e32 v71, 0xffff0000, v136
	v_lshlrev_b32_e32 v70, 16, v136
	v_and_b32_e32 v73, 0xffff0000, v137
	v_lshlrev_b32_e32 v72, 16, v137
	v_pk_add_f32 v[170:171], v[170:171], v[62:63]
	v_pk_add_f32 v[196:197], v[196:197], v[70:71]
	v_pk_add_f32 v[200:201], v[200:201], v[64:65]
	v_pk_add_f32 v[198:199], v[198:199], v[72:73]
	s_waitcnt vmcnt(6)
	v_and_b32_e32 v63, 0xffff0000, v130
	v_lshlrev_b32_e32 v62, 16, v130
	v_and_b32_e32 v65, 0xffff0000, v131
	v_lshlrev_b32_e32 v64, 16, v131
	v_and_b32_e32 v71, 0xffff0000, v132
	v_lshlrev_b32_e32 v70, 16, v132
	v_and_b32_e32 v73, 0xffff0000, v133
	v_lshlrev_b32_e32 v72, 16, v133
	v_pk_add_f32 v[192:193], v[192:193], v[62:63]
	v_pk_add_f32 v[188:189], v[188:189], v[70:71]
	v_pk_add_f32 v[194:195], v[194:195], v[64:65]
	v_pk_add_f32 v[190:191], v[190:191], v[72:73]
	s_waitcnt vmcnt(5)
	v_and_b32_e32 v63, 0xffff0000, v122
	v_lshlrev_b32_e32 v62, 16, v122
	v_and_b32_e32 v65, 0xffff0000, v123
	v_lshlrev_b32_e32 v64, 16, v123
	v_and_b32_e32 v71, 0xffff0000, v124
	v_lshlrev_b32_e32 v70, 16, v124
	v_and_b32_e32 v73, 0xffff0000, v125
	v_lshlrev_b32_e32 v72, 16, v125
	v_pk_add_f32 v[184:185], v[184:185], v[62:63]
	v_pk_add_f32 v[180:181], v[180:181], v[70:71]
	v_pk_add_f32 v[186:187], v[186:187], v[64:65]
	v_pk_add_f32 v[182:183], v[182:183], v[72:73]
	s_waitcnt vmcnt(4)
	v_and_b32_e32 v63, 0xffff0000, v114
	v_lshlrev_b32_e32 v62, 16, v114
	v_and_b32_e32 v65, 0xffff0000, v115
	v_lshlrev_b32_e32 v64, 16, v115
	v_and_b32_e32 v71, 0xffff0000, v116
	v_lshlrev_b32_e32 v70, 16, v116
	v_and_b32_e32 v73, 0xffff0000, v117
	v_lshlrev_b32_e32 v72, 16, v117
	v_pk_add_f32 v[176:177], v[176:177], v[62:63]
	v_pk_add_f32 v[172:173], v[172:173], v[70:71]
	v_pk_add_f32 v[178:179], v[178:179], v[64:65]
	v_pk_add_f32 v[174:175], v[174:175], v[72:73]

; #define LAS __attribute__((address_space(3)))
; __device__ __forceinline__ u32x4 pack8(const f32x4 v0, const f32x4 v1) { u32x4 w; w.x = pk_f16(v0[0], v0[1]); w.y = pk_f16(v0[2], v0[3]); w.z = pk_f16(v1[0], v1[1]); w.w = pk_f16(v1[2], v1[3]); return w; }
; __device__ __forceinline__ void unpack8(const u32x4 w, f32x4& v0, f32x4& v1) { v0 = (f32x4){f16lo(w.x), f16hi(w.x), f16lo(w.y), f16hi(w.y)}; v1 = (f32x4){f16lo(w.z), f16hi(w.z), f16lo(w.w), f16hi(w.w)}; }
; __device__ __forceinline__ void pm_item(LAS float* Vs0, int item, const f16* up, const f16* zs, const float* pscale, f16* branch) {
;     ...
;           for (int q = 0; q < 4; ++q) { const int cc = 4 * cs + q;
;             if (q > 0) { const int cin = cc + hi_off - 1, cout = cc - 1 - lo_off;
;                 if (cin < GW) { const LAS f32x4* vp = (const LAS f32x4*)(Vs + cin * 256 + o * 8); s0 += vp[0]; s1 += vp[1]; }
;                 if (cout >= 0) { const LAS f32x4* vp = (const LAS f32x4*)(Vs + cout * 256 + o * 8); s0 -= vp[0]; s1 -= vp[1]; } }
;             const int clo = cc - lo_off < 0 ? 0 : cc - lo_off, chi = cc + hi_off > GW ? GW : cc + hi_off;
;             const float ic = 1.f / (float)(chi - clo);
;             f32x4 u0, u1, z0, z1; unpack8(cen[cur][q], u0, u1); unpack8(zz[cur][q], z0, z1);
;             *(u32x4*)(branch + zoff + (size_t)(r * GW + q) * D) = pack8((s0 * ic - u0) * sc0 * z0, (s1 * ic - u1) * sc1 * z1); } }
.LBB0_589:
	s_or_b64 exec, exec, s[20:21]
	s_mov_b32 s19, 0x8000
	v_and_b32_e32 v115, 0xffff0000, v86
	v_lshlrev_b32_e32 v114, 16, v86
	v_and_b32_e32 v117, 0xffff0000, v87
	v_lshlrev_b32_e32 v116, 16, v87
	v_and_b32_e32 v87, 0xffff0000, v88
	v_lshlrev_b32_e32 v86, 16, v88
	v_and_b32_e32 v119, 0xffff0000, v89
	v_lshlrev_b32_e32 v118, 16, v89
	v_xor_b32_sdwa v88, s19, v79 dst_sel:WORD_1 dst_unused:UNUSED_PAD src0_sel:DWORD src1_sel:DWORD
	v_xor_b32_sdwa v89, s19, v79 dst_sel:WORD_1 dst_unused:UNUSED_PAD src0_sel:DWORD src1_sel:WORD_1
	v_mov_b32_e32 v120, v148
	v_mov_b32_e32 v121, v148
	v_xor_b32_sdwa v122, s19, v78 dst_sel:WORD_1 dst_unused:UNUSED_PAD src0_sel:DWORD src1_sel:DWORD
	v_xor_b32_sdwa v123, s19, v78 dst_sel:WORD_1 dst_unused:UNUSED_PAD src0_sel:DWORD src1_sel:WORD_1
	v_pk_fma_f32 v[88:89], v[120:121], v[112:113], v[88:89]
	v_pk_fma_f32 v[78:79], v[148:149], v[110:111], v[122:123]
	v_pk_mul_f32 v[88:89], v[8:9], v[88:89]
	v_pk_mul_f32 v[78:79], v[6:7], v[78:79]
	v_pk_mul_f32 v[88:89], v[116:117], v[88:89]
	v_pk_mul_f32 v[78:79], v[114:115], v[78:79]
	v_xor_b32_sdwa v114, s19, v81 dst_sel:WORD_1 dst_unused:UNUSED_PAD src0_sel:DWORD src1_sel:DWORD
	v_xor_b32_sdwa v115, s19, v81 dst_sel:WORD_1 dst_unused:UNUSED_PAD src0_sel:DWORD src1_sel:WORD_1
	v_xor_b32_sdwa v116, s19, v80 dst_sel:WORD_1 dst_unused:UNUSED_PAD src0_sel:DWORD src1_sel:DWORD
	v_xor_b32_sdwa v117, s19, v80 dst_sel:WORD_1 dst_unused:UNUSED_PAD src0_sel:DWORD src1_sel:WORD_1
	v_pk_fma_f32 v[114:115], v[120:121], v[108:109], v[114:115]
	v_pk_fma_f32 v[80:81], v[148:149], v[106:107], v[116:117]
	v_pk_mul_f32 v[114:115], v[4:5], v[114:115]
	v_pk_mul_f32 v[80:81], v[2:3], v[80:81]
	v_pk_mul_f32 v[114:115], v[118:119], v[114:115]
	v_pk_mul_f32 v[80:81], v[86:87], v[80:81]
	s_lshl_b32 s18, s18, 18
	s_mov_b32 s19, 0
	v_cvt_pk_bf16_f32 v86, v78, v79
	v_cvt_pk_bf16_f32 v87, v88, v89
	v_cvt_pk_bf16_f32 v88, v80, v81
	v_cvt_pk_bf16_f32 v89, v114, v115
	v_lshl_add_u64 v[78:79], v[146:147], 0, s[18:19]
	global_store_dwordx4 v[78:79], v[86:89], off sc0 sc1
	s_and_saveexec_b64 s[20:21], s[4:5]
	s_cbranch_execz .LBB0_591
	s_movk_i32 s18, 0xfc00
	v_add3_u32 v80, v163, v207, s18
	ds_read_b128 v[86:89], v80
	ds_read_b128 v[114:117], v80 offset:16
	s_waitcnt lgkmcnt(1)
	v_pk_add_f32 v[112:113], v[112:113], v[88:89]
	v_pk_add_f32 v[110:111], v[110:111], v[86:87]
	s_waitcnt lgkmcnt(0)
	v_pk_add_f32 v[108:109], v[108:109], v[116:117]
	v_pk_add_f32 v[106:107], v[106:107], v[114:115]

; #define LAS __attribute__((address_space(3)))
; __device__ __forceinline__ u32x4 pack8(const f32x4 v0, const f32x4 v1) { u32x4 w; w.x = pk_f16(v0[0], v0[1]); w.y = pk_f16(v0[2], v0[3]); w.z = pk_f16(v1[0], v1[1]); w.w = pk_f16(v1[2], v1[3]); return w; }
; __device__ __forceinline__ void unpack8(const u32x4 w, f32x4& v0, f32x4& v1) { v0 = (f32x4){f16lo(w.x), f16hi(w.x), f16lo(w.y), f16hi(w.y)}; v1 = (f32x4){f16lo(w.z), f16hi(w.z), f16lo(w.w), f16hi(w.w)}; }
; __device__ __forceinline__ void pm_item(LAS float* Vs0, int item, const f16* up, const f16* zs, const float* pscale, f16* branch) {
;     ...
;           for (int q = 0; q < 4; ++q) { const int cc = 4 * cs + q;
;             if (q > 0) { const int cin = cc + hi_off - 1, cout = cc - 1 - lo_off;
;                 if (cin < GW) { const LAS f32x4* vp = (const LAS f32x4*)(Vs + cin * 256 + o * 8); s0 += vp[0]; s1 += vp[1]; }
;                 if (cout >= 0) { const LAS f32x4* vp = (const LAS f32x4*)(Vs + cout * 256 + o * 8); s0 -= vp[0]; s1 -= vp[1]; } }
;             const int clo = cc - lo_off < 0 ? 0 : cc - lo_off, chi = cc + hi_off > GW ? GW : cc + hi_off;
;             const float ic = 1.f / (float)(chi - clo);
;             f32x4 u0, u1, z0, z1; unpack8(cen[cur][q], u0, u1); unpack8(zz[cur][q], z0, z1);
;             *(u32x4*)(branch + zoff + (size_t)(r * GW + q) * D) = pack8((s0 * ic - u0) * sc0 * z0, (s1 * ic - u1) * sc1 * z1); } }
.LBB0_593:
	s_or_b64 exec, exec, s[20:21]
	s_mov_b32 s18, 0x8000
	v_and_b32_e32 v81, 0xffff0000, v66
	v_lshlrev_b32_e32 v80, 16, v66
	v_and_b32_e32 v87, 0xffff0000, v67
	v_lshlrev_b32_e32 v86, 16, v67
	v_and_b32_e32 v67, 0xffff0000, v68
	v_lshlrev_b32_e32 v66, 16, v68
	v_and_b32_e32 v89, 0xffff0000, v69
	v_lshlrev_b32_e32 v88, 16, v69
	v_xor_b32_sdwa v68, s18, v59 dst_sel:WORD_1 dst_unused:UNUSED_PAD src0_sel:DWORD src1_sel:DWORD
	v_xor_b32_sdwa v69, s18, v59 dst_sel:WORD_1 dst_unused:UNUSED_PAD src0_sel:DWORD src1_sel:WORD_1
	v_mov_b32_e32 v114, v150
	v_mov_b32_e32 v115, v150
	v_xor_b32_sdwa v116, s18, v58 dst_sel:WORD_1 dst_unused:UNUSED_PAD src0_sel:DWORD src1_sel:DWORD
	v_xor_b32_sdwa v117, s18, v58 dst_sel:WORD_1 dst_unused:UNUSED_PAD src0_sel:DWORD src1_sel:WORD_1
	v_pk_fma_f32 v[68:69], v[114:115], v[112:113], v[68:69]
	v_pk_fma_f32 v[58:59], v[150:151], v[110:111], v[116:117]
	v_pk_mul_f32 v[68:69], v[8:9], v[68:69]
	v_pk_mul_f32 v[58:59], v[6:7], v[58:59]
	v_pk_mul_f32 v[68:69], v[86:87], v[68:69]
	v_pk_mul_f32 v[58:59], v[80:81], v[58:59]
	v_xor_b32_sdwa v80, s18, v61 dst_sel:WORD_1 dst_unused:UNUSED_PAD src0_sel:DWORD src1_sel:DWORD
	v_xor_b32_sdwa v81, s18, v61 dst_sel:WORD_1 dst_unused:UNUSED_PAD src0_sel:DWORD src1_sel:WORD_1
	v_xor_b32_sdwa v86, s18, v60 dst_sel:WORD_1 dst_unused:UNUSED_PAD src0_sel:DWORD src1_sel:DWORD
	v_xor_b32_sdwa v87, s18, v60 dst_sel:WORD_1 dst_unused:UNUSED_PAD src0_sel:DWORD src1_sel:WORD_1
	v_pk_fma_f32 v[80:81], v[114:115], v[108:109], v[80:81]
	v_pk_fma_f32 v[60:61], v[150:151], v[106:107], v[86:87]
	v_pk_mul_f32 v[80:81], v[4:5], v[80:81]
	v_pk_mul_f32 v[60:61], v[2:3], v[60:61]
	v_pk_mul_f32 v[80:81], v[88:89], v[80:81]
	v_pk_mul_f32 v[60:61], v[66:67], v[60:61]
	v_add_co_u32_e32 v66, vcc, 0x1000, v78
	v_cvt_pk_bf16_f32 v58, v58, v59
	v_cvt_pk_bf16_f32 v59, v68, v69
	v_cvt_pk_bf16_f32 v60, v60, v61
	v_cvt_pk_bf16_f32 v61, v80, v81
	v_addc_co_u32_e32 v67, vcc, 0, v79, vcc
	global_store_dwordx4 v[66:67], v[58:61], off sc0 sc1
	s_and_saveexec_b64 s[20:21], s[8:9]
	s_cbranch_execz .LBB0_595
	s_movk_i32 s18, 0xfc00
	v_add3_u32 v66, v165, v207, s18
	ds_read_b128 v[58:61], v66
	ds_read_b128 v[66:69], v66 offset:16
	s_waitcnt lgkmcnt(1)
	v_pk_add_f32 v[112:113], v[112:113], v[60:61]
	v_pk_add_f32 v[110:111], v[110:111], v[58:59]
	s_waitcnt lgkmcnt(0)
	v_pk_add_f32 v[108:109], v[108:109], v[68:69]
	v_pk_add_f32 v[106:107], v[106:107], v[66:67]

; #define LAS __attribute__((address_space(3)))
; __device__ __forceinline__ u32x4 pack8(const f32x4 v0, const f32x4 v1) { u32x4 w; w.x = pk_f16(v0[0], v0[1]); w.y = pk_f16(v0[2], v0[3]); w.z = pk_f16(v1[0], v1[1]); w.w = pk_f16(v1[2], v1[3]); return w; }
; __device__ __forceinline__ void unpack8(const u32x4 w, f32x4& v0, f32x4& v1) { v0 = (f32x4){f16lo(w.x), f16hi(w.x), f16lo(w.y), f16hi(w.y)}; v1 = (f32x4){f16lo(w.z), f16hi(w.z), f16lo(w.w), f16hi(w.w)}; }
; __device__ __forceinline__ void pm_item(LAS float* Vs0, int item, const f16* up, const f16* zs, const float* pscale, f16* branch) {
;     ...
;           for (int q = 0; q < 4; ++q) { const int cc = 4 * cs + q;
;             if (q > 0) { const int cin = cc + hi_off - 1, cout = cc - 1 - lo_off;
;                 if (cin < GW) { const LAS f32x4* vp = (const LAS f32x4*)(Vs + cin * 256 + o * 8); s0 += vp[0]; s1 += vp[1]; }
;                 if (cout >= 0) { const LAS f32x4* vp = (const LAS f32x4*)(Vs + cout * 256 + o * 8); s0 -= vp[0]; s1 -= vp[1]; } }
;             const int clo = cc - lo_off < 0 ? 0 : cc - lo_off, chi = cc + hi_off > GW ? GW : cc + hi_off;
;             const float ic = 1.f / (float)(chi - clo);
;             f32x4 u0, u1, z0, z1; unpack8(cen[cur][q], u0, u1); unpack8(zz[cur][q], z0, z1);
;             *(u32x4*)(branch + zoff + (size_t)(r * GW + q) * D) = pack8((s0 * ic - u0) * sc0 * z0, (s1 * ic - u1) * sc1 * z1); } }
.LBB0_597:
	s_or_b64 exec, exec, s[20:21]
	s_mov_b32 s18, 0x8000
	v_and_b32_e32 v59, 0xffff0000, v54
	v_lshlrev_b32_e32 v58, 16, v54
	v_and_b32_e32 v61, 0xffff0000, v55
	v_lshlrev_b32_e32 v60, 16, v55
	v_and_b32_e32 v55, 0xffff0000, v56
	v_lshlrev_b32_e32 v54, 16, v56
	v_and_b32_e32 v67, 0xffff0000, v57
	v_lshlrev_b32_e32 v66, 16, v57
	v_xor_b32_sdwa v56, s18, v51 dst_sel:WORD_1 dst_unused:UNUSED_PAD src0_sel:DWORD src1_sel:DWORD
	v_xor_b32_sdwa v57, s18, v51 dst_sel:WORD_1 dst_unused:UNUSED_PAD src0_sel:DWORD src1_sel:WORD_1
	v_mov_b32_e32 v68, v152
	v_mov_b32_e32 v69, v152
	v_xor_b32_sdwa v80, s18, v50 dst_sel:WORD_1 dst_unused:UNUSED_PAD src0_sel:DWORD src1_sel:DWORD
	v_xor_b32_sdwa v81, s18, v50 dst_sel:WORD_1 dst_unused:UNUSED_PAD src0_sel:DWORD src1_sel:WORD_1
	v_pk_fma_f32 v[56:57], v[68:69], v[112:113], v[56:57]
	v_pk_fma_f32 v[50:51], v[152:153], v[110:111], v[80:81]
	v_pk_mul_f32 v[56:57], v[8:9], v[56:57]
	v_pk_mul_f32 v[50:51], v[6:7], v[50:51]
	v_pk_mul_f32 v[56:57], v[60:61], v[56:57]
	v_pk_mul_f32 v[50:51], v[58:59], v[50:51]
	v_xor_b32_sdwa v58, s18, v53 dst_sel:WORD_1 dst_unused:UNUSED_PAD src0_sel:DWORD src1_sel:DWORD
	v_xor_b32_sdwa v59, s18, v53 dst_sel:WORD_1 dst_unused:UNUSED_PAD src0_sel:DWORD src1_sel:WORD_1
	v_xor_b32_sdwa v60, s18, v52 dst_sel:WORD_1 dst_unused:UNUSED_PAD src0_sel:DWORD src1_sel:DWORD
	v_xor_b32_sdwa v61, s18, v52 dst_sel:WORD_1 dst_unused:UNUSED_PAD src0_sel:DWORD src1_sel:WORD_1
	v_pk_fma_f32 v[58:59], v[68:69], v[108:109], v[58:59]
	v_pk_fma_f32 v[52:53], v[152:153], v[106:107], v[60:61]
	v_pk_mul_f32 v[58:59], v[4:5], v[58:59]
	v_pk_mul_f32 v[52:53], v[2:3], v[52:53]
	v_pk_mul_f32 v[58:59], v[66:67], v[58:59]
	v_pk_mul_f32 v[52:53], v[54:55], v[52:53]
	v_add_co_u32_e32 v54, vcc, 0x2000, v78
	v_cvt_pk_bf16_f32 v50, v50, v51
	v_cvt_pk_bf16_f32 v51, v56, v57
	v_cvt_pk_bf16_f32 v52, v52, v53
	v_cvt_pk_bf16_f32 v53, v58, v59
	v_addc_co_u32_e32 v55, vcc, 0, v79, vcc
	global_store_dwordx4 v[54:55], v[50:53], off sc0 sc1
	s_and_saveexec_b64 s[20:21], s[12:13]
	s_cbranch_execz .LBB0_599
	s_movk_i32 s18, 0xfc00
	v_add3_u32 v54, v167, v207, s18
	ds_read_b128 v[50:53], v54
	ds_read_b128 v[54:57], v54 offset:16
	s_waitcnt lgkmcnt(1)
	v_pk_add_f32 v[112:113], v[112:113], v[52:53]
	v_pk_add_f32 v[110:111], v[110:111], v[50:51]
	s_waitcnt lgkmcnt(0)
	v_pk_add_f32 v[108:109], v[108:109], v[56:57]
	v_pk_add_f32 v[106:107], v[106:107], v[54:55]

; #define LAS __attribute__((address_space(3)))
; __device__ __forceinline__ u32x4 pack8(const f32x4 v0, const f32x4 v1) { u32x4 w; w.x = pk_f16(v0[0], v0[1]); w.y = pk_f16(v0[2], v0[3]); w.z = pk_f16(v1[0], v1[1]); w.w = pk_f16(v1[2], v1[3]); return w; }
; __device__ __forceinline__ void unpack8(const u32x4 w, f32x4& v0, f32x4& v1) { v0 = (f32x4){f16lo(w.x), f16hi(w.x), f16lo(w.y), f16hi(w.y)}; v1 = (f32x4){f16lo(w.z), f16hi(w.z), f16lo(w.w), f16hi(w.w)}; }
; __device__ __forceinline__ void pm_item(LAS float* Vs0, int item, const f16* up, const f16* zs, const float* pscale, f16* branch) {
;     ...
;         if (rr >= 1) {
;             if (r + hi_off - 1 < ROWS) {
; #pragma unroll
;                 for (int q = 0; q < 4; ++q) { f32x4 v0, v1; unpack8(hi[cur][q], v0, v1);
; #pragma unroll
;                     for (int e = 0; e < 4; ++e) { rs[q][e] += v0[e]; rs[q][4 + e] += v1[e]; } } }
;     ...
;           for (int q = 0; q < 4; ++q) { const int cc = 4 * cs + q;
;             if (q > 0) { const int cin = cc + hi_off - 1, cout = cc - 1 - lo_off;
;                 if (cin < GW) { const LAS f32x4* vp = (const LAS f32x4*)(Vs + cin * 256 + o * 8); s0 += vp[0]; s1 += vp[1]; }
;                 if (cout >= 0) { const LAS f32x4* vp = (const LAS f32x4*)(Vs + cout * 256 + o * 8); s0 -= vp[0]; s1 -= vp[1]; } }
;             const int clo = cc - lo_off < 0 ? 0 : cc - lo_off, chi = cc + hi_off > GW ? GW : cc + hi_off;
;             const float ic = 1.f / (float)(chi - clo);
;             f32x4 u0, u1, z0, z1; unpack8(cen[cur][q], u0, u1); unpack8(zz[cur][q], z0, z1);
;             *(u32x4*)(branch + zoff + (size_t)(r * GW + q) * D) = pack8((s0 * ic - u0) * sc0 * z0, (s1 * ic - u1) * sc1 * z1); } }
.LBB0_601:
	s_or_b64 exec, exec, s[20:21]
	s_mov_b32 s18, 0x8000
	v_and_b32_e32 v51, 0xffff0000, v46
	v_lshlrev_b32_e32 v50, 16, v46
	v_and_b32_e32 v53, 0xffff0000, v47
	v_lshlrev_b32_e32 v52, 16, v47
	v_and_b32_e32 v47, 0xffff0000, v48
	v_lshlrev_b32_e32 v46, 16, v48
	v_and_b32_e32 v55, 0xffff0000, v49
	v_lshlrev_b32_e32 v54, 16, v49
	v_xor_b32_sdwa v48, s18, v43 dst_sel:WORD_1 dst_unused:UNUSED_PAD src0_sel:DWORD src1_sel:DWORD
	v_xor_b32_sdwa v49, s18, v43 dst_sel:WORD_1 dst_unused:UNUSED_PAD src0_sel:DWORD src1_sel:WORD_1
	v_mov_b32_e32 v56, v154
	v_mov_b32_e32 v57, v154
	v_xor_b32_sdwa v58, s18, v42 dst_sel:WORD_1 dst_unused:UNUSED_PAD src0_sel:DWORD src1_sel:DWORD
	v_xor_b32_sdwa v59, s18, v42 dst_sel:WORD_1 dst_unused:UNUSED_PAD src0_sel:DWORD src1_sel:WORD_1
	v_pk_fma_f32 v[48:49], v[56:57], v[112:113], v[48:49]
	v_pk_fma_f32 v[42:43], v[154:155], v[110:111], v[58:59]
	v_pk_mul_f32 v[48:49], v[8:9], v[48:49]
	v_pk_mul_f32 v[42:43], v[6:7], v[42:43]
	v_pk_mul_f32 v[48:49], v[52:53], v[48:49]
	v_pk_mul_f32 v[42:43], v[50:51], v[42:43]
	v_xor_b32_sdwa v50, s18, v45 dst_sel:WORD_1 dst_unused:UNUSED_PAD src0_sel:DWORD src1_sel:DWORD
	v_xor_b32_sdwa v51, s18, v45 dst_sel:WORD_1 dst_unused:UNUSED_PAD src0_sel:DWORD src1_sel:WORD_1
	v_xor_b32_sdwa v52, s18, v44 dst_sel:WORD_1 dst_unused:UNUSED_PAD src0_sel:DWORD src1_sel:DWORD
	v_xor_b32_sdwa v53, s18, v44 dst_sel:WORD_1 dst_unused:UNUSED_PAD src0_sel:DWORD src1_sel:WORD_1
	v_pk_fma_f32 v[50:51], v[56:57], v[108:109], v[50:51]
	v_pk_fma_f32 v[44:45], v[154:155], v[106:107], v[52:53]
	v_pk_mul_f32 v[50:51], v[4:5], v[50:51]
	v_pk_mul_f32 v[44:45], v[2:3], v[44:45]
	v_pk_mul_f32 v[50:51], v[54:55], v[50:51]
	v_pk_mul_f32 v[44:45], v[46:47], v[44:45]
	v_add_co_u32_e32 v46, vcc, 0x3000, v78
	s_or_b32 s18, s45, 3
	v_cvt_pk_bf16_f32 v42, v42, v43
	v_cvt_pk_bf16_f32 v43, v48, v49
	v_cvt_pk_bf16_f32 v44, v44, v45
	v_cvt_pk_bf16_f32 v45, v50, v51
	v_addc_co_u32_e32 v47, vcc, 0, v79, vcc
	s_cmp_ge_u32 s18, s55
	global_store_dwordx4 v[46:47], v[42:45], off sc0 sc1
	s_cbranch_scc1 .LBB0_603
	s_waitcnt vmcnt(7)
	v_and_b32_e32 v43, 0xffff0000, v38
	v_lshlrev_b32_e32 v42, 16, v38
	v_and_b32_e32 v45, 0xffff0000, v39
	v_lshlrev_b32_e32 v44, 16, v39
	v_and_b32_e32 v39, 0xffff0000, v40
	v_lshlrev_b32_e32 v38, 16, v40
	v_and_b32_e32 v47, 0xffff0000, v41
	v_lshlrev_b32_e32 v46, 16, v41
	v_pk_add_f32 v[196:197], v[196:197], v[38:39]
	s_waitcnt vmcnt(6)
	v_and_b32_e32 v39, 0xffff0000, v30
	v_lshlrev_b32_e32 v38, 16, v30
	v_and_b32_e32 v41, 0xffff0000, v31
	v_lshlrev_b32_e32 v40, 16, v31
	v_and_b32_e32 v31, 0xffff0000, v32
	v_lshlrev_b32_e32 v30, 16, v32
	v_pk_add_f32 v[170:171], v[170:171], v[42:43]
	v_and_b32_e32 v43, 0xffff0000, v33
	v_lshlrev_b32_e32 v42, 16, v33
	v_pk_add_f32 v[188:189], v[188:189], v[30:31]
	s_waitcnt vmcnt(5)
	v_and_b32_e32 v31, 0xffff0000, v34
	v_lshlrev_b32_e32 v30, 16, v34
	v_and_b32_e32 v33, 0xffff0000, v35
	v_lshlrev_b32_e32 v32, 16, v35
	v_and_b32_e32 v35, 0xffff0000, v36
	v_lshlrev_b32_e32 v34, 16, v36
	v_pk_add_f32 v[192:193], v[192:193], v[38:39]
	v_and_b32_e32 v39, 0xffff0000, v37
	v_lshlrev_b32_e32 v38, 16, v37
	v_pk_add_f32 v[184:185], v[184:185], v[30:31]
	v_pk_add_f32 v[180:181], v[180:181], v[34:35]
	v_pk_add_f32 v[186:187], v[186:187], v[32:33]
	s_waitcnt vmcnt(4)
	v_and_b32_e32 v31, 0xffff0000, v26
	v_lshlrev_b32_e32 v30, 16, v26
	v_and_b32_e32 v33, 0xffff0000, v27
	v_lshlrev_b32_e32 v32, 16, v27
	v_and_b32_e32 v27, 0xffff0000, v28
	v_lshlrev_b32_e32 v26, 16, v28
	v_and_b32_e32 v35, 0xffff0000, v29
	v_lshlrev_b32_e32 v34, 16, v29
	v_pk_add_f32 v[200:201], v[200:201], v[44:45]
	v_pk_add_f32 v[198:199], v[198:199], v[46:47]
	v_pk_add_f32 v[194:195], v[194:195], v[40:41]
	v_pk_add_f32 v[190:191], v[190:191], v[42:43]
	v_pk_add_f32 v[182:183], v[182:183], v[38:39]
	v_pk_add_f32 v[176:177], v[176:177], v[30:31]
	v_pk_add_f32 v[172:173], v[172:173], v[26:27]
	v_pk_add_f32 v[178:179], v[178:179], v[32:33]
	v_pk_add_f32 v[174:175], v[174:175], v[34:35]

; #define LAS __attribute__((address_space(3)))
; __device__ __forceinline__ u32x4 pack8(const f32x4 v0, const f32x4 v1) { u32x4 w; w.x = pk_f16(v0[0], v0[1]); w.y = pk_f16(v0[2], v0[3]); w.z = pk_f16(v1[0], v1[1]); w.w = pk_f16(v1[2], v1[3]); return w; }
; __device__ __forceinline__ void unpack8(const u32x4 w, f32x4& v0, f32x4& v1) { v0 = (f32x4){f16lo(w.x), f16hi(w.x), f16lo(w.y), f16hi(w.y)}; v1 = (f32x4){f16lo(w.z), f16hi(w.z), f16lo(w.w), f16hi(w.w)}; }
; __device__ __forceinline__ void pm_item(LAS float* Vs0, int item, const f16* up, const f16* zs, const float* pscale, f16* branch) {
;     ...
;           for (int q = 0; q < 4; ++q) { const int cc = 4 * cs + q;
;             if (q > 0) { const int cin = cc + hi_off - 1, cout = cc - 1 - lo_off;
;                 if (cin < GW) { const LAS f32x4* vp = (const LAS f32x4*)(Vs + cin * 256 + o * 8); s0 += vp[0]; s1 += vp[1]; }
;                 if (cout >= 0) { const LAS f32x4* vp = (const LAS f32x4*)(Vs + cout * 256 + o * 8); s0 -= vp[0]; s1 -= vp[1]; } }
;             const int clo = cc - lo_off < 0 ? 0 : cc - lo_off, chi = cc + hi_off > GW ? GW : cc + hi_off;
;             const float ic = 1.f / (float)(chi - clo);
;             f32x4 u0, u1, z0, z1; unpack8(cen[cur][q], u0, u1); unpack8(zz[cur][q], z0, z1);
;             *(u32x4*)(branch + zoff + (size_t)(r * GW + q) * D) = pack8((s0 * ic - u0) * sc0 * z0, (s1 * ic - u1) * sc1 * z1); } }
.LBB0_609:
	s_or_b64 exec, exec, s[20:21]
	s_mov_b32 s2, 0x8000
	v_xor_b32_sdwa v26, s2, v99 dst_sel:WORD_1 dst_unused:UNUSED_PAD src0_sel:DWORD src1_sel:DWORD
	v_xor_b32_sdwa v27, s2, v99 dst_sel:WORD_1 dst_unused:UNUSED_PAD src0_sel:DWORD src1_sel:WORD_1
	v_mov_b32_e32 v28, v148
	v_mov_b32_e32 v29, v148
	v_pk_fma_f32 v[26:27], v[28:29], v[16:17], v[26:27]
	v_and_b32_e32 v21, 0xffff0000, v103
	v_lshlrev_b32_e32 v20, 16, v103
	v_pk_mul_f32 v[26:27], v[8:9], v[26:27]
	v_xor_b32_sdwa v30, s2, v98 dst_sel:WORD_1 dst_unused:UNUSED_PAD src0_sel:DWORD src1_sel:DWORD
	v_pk_mul_f32 v[26:27], v[20:21], v[26:27]
	v_xor_b32_sdwa v20, s2, v101 dst_sel:WORD_1 dst_unused:UNUSED_PAD src0_sel:DWORD src1_sel:DWORD
	v_xor_b32_sdwa v21, s2, v101 dst_sel:WORD_1 dst_unused:UNUSED_PAD src0_sel:DWORD src1_sel:WORD_1
	v_xor_b32_sdwa v31, s2, v98 dst_sel:WORD_1 dst_unused:UNUSED_PAD src0_sel:DWORD src1_sel:WORD_1
	v_pk_fma_f32 v[20:21], v[28:29], v[12:13], v[20:21]
	v_xor_b32_sdwa v28, s2, v100 dst_sel:WORD_1 dst_unused:UNUSED_PAD src0_sel:DWORD src1_sel:DWORD
	v_xor_b32_sdwa v29, s2, v100 dst_sel:WORD_1 dst_unused:UNUSED_PAD src0_sel:DWORD src1_sel:WORD_1
	v_pk_fma_f32 v[30:31], v[148:149], v[14:15], v[30:31]
	v_pk_fma_f32 v[28:29], v[148:149], v[10:11], v[28:29]
	v_and_b32_e32 v19, 0xffff0000, v102
	v_lshlrev_b32_e32 v18, 16, v102
	v_and_b32_e32 v23, 0xffff0000, v104
	v_lshlrev_b32_e32 v22, 16, v104
	v_and_b32_e32 v25, 0xffff0000, v105
	v_lshlrev_b32_e32 v24, 16, v105
	v_pk_mul_f32 v[30:31], v[6:7], v[30:31]
	v_pk_mul_f32 v[28:29], v[2:3], v[28:29]
	v_pk_mul_f32 v[20:21], v[4:5], v[20:21]
	v_pk_mul_f32 v[18:19], v[18:19], v[30:31]
	v_pk_mul_f32 v[24:25], v[24:25], v[20:21]
	v_pk_mul_f32 v[22:23], v[22:23], v[28:29]
	s_lshl_b32 s2, s18, 18
	s_mov_b32 s3, 0
	v_cvt_pk_bf16_f32 v20, v18, v19
	v_cvt_pk_bf16_f32 v21, v26, v27
	v_cvt_pk_bf16_f32 v22, v22, v23
	v_cvt_pk_bf16_f32 v23, v24, v25
	v_lshl_add_u64 v[18:19], v[146:147], 0, s[2:3]
	global_store_dwordx4 v[18:19], v[20:23], off sc0 sc1
	s_and_saveexec_b64 s[2:3], s[4:5]
	s_cbranch_execz .LBB0_611
	v_lshl_add_u32 v20, v158, 10, s25
	s_movk_i32 s4, 0xfc00
	v_add3_u32 v24, v20, v207, s4
	ds_read_b128 v[20:23], v24
	ds_read_b128 v[24:27], v24 offset:16
	s_waitcnt lgkmcnt(1)
	v_pk_add_f32 v[16:17], v[16:17], v[22:23]
	v_pk_add_f32 v[14:15], v[14:15], v[20:21]
	s_waitcnt lgkmcnt(0)
	v_pk_add_f32 v[12:13], v[12:13], v[26:27]
	v_pk_add_f32 v[10:11], v[10:11], v[24:25]

; #define LAS __attribute__((address_space(3)))
; __device__ __forceinline__ u32x4 pack8(const f32x4 v0, const f32x4 v1) { u32x4 w; w.x = pk_f16(v0[0], v0[1]); w.y = pk_f16(v0[2], v0[3]); w.z = pk_f16(v1[0], v1[1]); w.w = pk_f16(v1[2], v1[3]); return w; }
; __device__ __forceinline__ void unpack8(const u32x4 w, f32x4& v0, f32x4& v1) { v0 = (f32x4){f16lo(w.x), f16hi(w.x), f16lo(w.y), f16hi(w.y)}; v1 = (f32x4){f16lo(w.z), f16hi(w.z), f16lo(w.w), f16hi(w.w)}; }
; __device__ __forceinline__ void pm_item(LAS float* Vs0, int item, const f16* up, const f16* zs, const float* pscale, f16* branch) {
;     ...
;           for (int q = 0; q < 4; ++q) { const int cc = 4 * cs + q;
;             if (q > 0) { const int cin = cc + hi_off - 1, cout = cc - 1 - lo_off;
;                 if (cin < GW) { const LAS f32x4* vp = (const LAS f32x4*)(Vs + cin * 256 + o * 8); s0 += vp[0]; s1 += vp[1]; }
;                 if (cout >= 0) { const LAS f32x4* vp = (const LAS f32x4*)(Vs + cout * 256 + o * 8); s0 -= vp[0]; s1 -= vp[1]; } }
;             const int clo = cc - lo_off < 0 ? 0 : cc - lo_off, chi = cc + hi_off > GW ? GW : cc + hi_off;
;             const float ic = 1.f / (float)(chi - clo);
;             f32x4 u0, u1, z0, z1; unpack8(cen[cur][q], u0, u1); unpack8(zz[cur][q], z0, z1);
;             *(u32x4*)(branch + zoff + (size_t)(r * GW + q) * D) = pack8((s0 * ic - u0) * sc0 * z0, (s1 * ic - u1) * sc1 * z1); } }
.LBB0_613:
	s_or_b64 exec, exec, s[2:3]
	s_mov_b32 s2, 0x8000
	v_xor_b32_sdwa v28, s2, v91 dst_sel:WORD_1 dst_unused:UNUSED_PAD src0_sel:DWORD src1_sel:DWORD
	v_xor_b32_sdwa v29, s2, v91 dst_sel:WORD_1 dst_unused:UNUSED_PAD src0_sel:DWORD src1_sel:WORD_1
	v_mov_b32_e32 v30, v150
	v_mov_b32_e32 v31, v150
	v_pk_fma_f32 v[28:29], v[30:31], v[16:17], v[28:29]
	v_and_b32_e32 v23, 0xffff0000, v95
	v_lshlrev_b32_e32 v22, 16, v95
	v_pk_mul_f32 v[28:29], v[8:9], v[28:29]
	v_xor_b32_sdwa v32, s2, v90 dst_sel:WORD_1 dst_unused:UNUSED_PAD src0_sel:DWORD src1_sel:DWORD
	v_pk_mul_f32 v[22:23], v[22:23], v[28:29]
	v_xor_b32_sdwa v28, s2, v93 dst_sel:WORD_1 dst_unused:UNUSED_PAD src0_sel:DWORD src1_sel:DWORD
	v_xor_b32_sdwa v29, s2, v93 dst_sel:WORD_1 dst_unused:UNUSED_PAD src0_sel:DWORD src1_sel:WORD_1
	v_xor_b32_sdwa v33, s2, v90 dst_sel:WORD_1 dst_unused:UNUSED_PAD src0_sel:DWORD src1_sel:WORD_1
	v_pk_fma_f32 v[28:29], v[30:31], v[12:13], v[28:29]
	v_xor_b32_sdwa v30, s2, v92 dst_sel:WORD_1 dst_unused:UNUSED_PAD src0_sel:DWORD src1_sel:DWORD
	v_xor_b32_sdwa v31, s2, v92 dst_sel:WORD_1 dst_unused:UNUSED_PAD src0_sel:DWORD src1_sel:WORD_1
	v_pk_fma_f32 v[32:33], v[150:151], v[14:15], v[32:33]
	v_pk_fma_f32 v[30:31], v[150:151], v[10:11], v[30:31]
	v_and_b32_e32 v21, 0xffff0000, v94
	v_lshlrev_b32_e32 v20, 16, v94
	v_and_b32_e32 v25, 0xffff0000, v96
	v_lshlrev_b32_e32 v24, 16, v96
	v_pk_mul_f32 v[32:33], v[6:7], v[32:33]
	v_pk_mul_f32 v[30:31], v[2:3], v[30:31]
	v_and_b32_e32 v27, 0xffff0000, v97
	v_lshlrev_b32_e32 v26, 16, v97
	v_pk_mul_f32 v[20:21], v[20:21], v[32:33]
	v_pk_mul_f32 v[28:29], v[4:5], v[28:29]
	v_pk_mul_f32 v[24:25], v[24:25], v[30:31]
	v_pk_mul_f32 v[26:27], v[26:27], v[28:29]
	v_cvt_pk_bf16_f32 v20, v20, v21
	v_cvt_pk_bf16_f32 v21, v22, v23
	v_cvt_pk_bf16_f32 v22, v24, v25
	v_add_co_u32_e32 v24, vcc, 0x1000, v18
	v_cvt_pk_bf16_f32 v23, v26, v27
	s_nop 0
	v_addc_co_u32_e32 v25, vcc, 0, v19, vcc
	global_store_dwordx4 v[24:25], v[20:23], off sc0 sc1
	s_and_saveexec_b64 s[2:3], s[8:9]
	s_cbranch_execz .LBB0_615
	v_lshl_add_u32 v20, v159, 10, s25
	s_movk_i32 s4, 0xfc00
	v_add3_u32 v24, v20, v207, s4
	ds_read_b128 v[20:23], v24
	ds_read_b128 v[24:27], v24 offset:16
	s_waitcnt lgkmcnt(1)
	v_pk_add_f32 v[16:17], v[16:17], v[22:23]
	v_pk_add_f32 v[14:15], v[14:15], v[20:21]
	s_waitcnt lgkmcnt(0)
	v_pk_add_f32 v[12:13], v[12:13], v[26:27]
	v_pk_add_f32 v[10:11], v[10:11], v[24:25]

; #define LAS __attribute__((address_space(3)))
; __device__ __forceinline__ u32x4 pack8(const f32x4 v0, const f32x4 v1) { u32x4 w; w.x = pk_f16(v0[0], v0[1]); w.y = pk_f16(v0[2], v0[3]); w.z = pk_f16(v1[0], v1[1]); w.w = pk_f16(v1[2], v1[3]); return w; }
; __device__ __forceinline__ void unpack8(const u32x4 w, f32x4& v0, f32x4& v1) { v0 = (f32x4){f16lo(w.x), f16hi(w.x), f16lo(w.y), f16hi(w.y)}; v1 = (f32x4){f16lo(w.z), f16hi(w.z), f16lo(w.w), f16hi(w.w)}; }
; __device__ __forceinline__ void pm_item(LAS float* Vs0, int item, const f16* up, const f16* zs, const float* pscale, f16* branch) {
;     ...
;           for (int q = 0; q < 4; ++q) { const int cc = 4 * cs + q;
;             if (q > 0) { const int cin = cc + hi_off - 1, cout = cc - 1 - lo_off;
;                 if (cin < GW) { const LAS f32x4* vp = (const LAS f32x4*)(Vs + cin * 256 + o * 8); s0 += vp[0]; s1 += vp[1]; }
;                 if (cout >= 0) { const LAS f32x4* vp = (const LAS f32x4*)(Vs + cout * 256 + o * 8); s0 -= vp[0]; s1 -= vp[1]; } }
;             const int clo = cc - lo_off < 0 ? 0 : cc - lo_off, chi = cc + hi_off > GW ? GW : cc + hi_off;
;             const float ic = 1.f / (float)(chi - clo);
;             f32x4 u0, u1, z0, z1; unpack8(cen[cur][q], u0, u1); unpack8(zz[cur][q], z0, z1);
;             *(u32x4*)(branch + zoff + (size_t)(r * GW + q) * D) = pack8((s0 * ic - u0) * sc0 * z0, (s1 * ic - u1) * sc1 * z1); } }
.LBB0_617:
	s_or_b64 exec, exec, s[2:3]
	s_mov_b32 s2, 0x8000
	v_xor_b32_sdwa v28, s2, v75 dst_sel:WORD_1 dst_unused:UNUSED_PAD src0_sel:DWORD src1_sel:DWORD
	v_xor_b32_sdwa v29, s2, v75 dst_sel:WORD_1 dst_unused:UNUSED_PAD src0_sel:DWORD src1_sel:WORD_1
	v_mov_b32_e32 v30, v152
	v_mov_b32_e32 v31, v152
	v_pk_fma_f32 v[28:29], v[30:31], v[16:17], v[28:29]
	v_and_b32_e32 v23, 0xffff0000, v83
	v_lshlrev_b32_e32 v22, 16, v83
	v_pk_mul_f32 v[28:29], v[8:9], v[28:29]
	v_xor_b32_sdwa v32, s2, v74 dst_sel:WORD_1 dst_unused:UNUSED_PAD src0_sel:DWORD src1_sel:DWORD
	v_pk_mul_f32 v[22:23], v[22:23], v[28:29]
	v_xor_b32_sdwa v28, s2, v77 dst_sel:WORD_1 dst_unused:UNUSED_PAD src0_sel:DWORD src1_sel:DWORD
	v_xor_b32_sdwa v29, s2, v77 dst_sel:WORD_1 dst_unused:UNUSED_PAD src0_sel:DWORD src1_sel:WORD_1
	v_xor_b32_sdwa v33, s2, v74 dst_sel:WORD_1 dst_unused:UNUSED_PAD src0_sel:DWORD src1_sel:WORD_1
	v_pk_fma_f32 v[28:29], v[30:31], v[12:13], v[28:29]
	v_xor_b32_sdwa v30, s2, v76 dst_sel:WORD_1 dst_unused:UNUSED_PAD src0_sel:DWORD src1_sel:DWORD
	v_xor_b32_sdwa v31, s2, v76 dst_sel:WORD_1 dst_unused:UNUSED_PAD src0_sel:DWORD src1_sel:WORD_1
	v_pk_fma_f32 v[32:33], v[152:153], v[14:15], v[32:33]
	v_pk_fma_f32 v[30:31], v[152:153], v[10:11], v[30:31]
	v_and_b32_e32 v21, 0xffff0000, v82
	v_lshlrev_b32_e32 v20, 16, v82
	v_and_b32_e32 v25, 0xffff0000, v84
	v_lshlrev_b32_e32 v24, 16, v84
	v_pk_mul_f32 v[32:33], v[6:7], v[32:33]
	v_pk_mul_f32 v[30:31], v[2:3], v[30:31]
	v_and_b32_e32 v27, 0xffff0000, v85
	v_lshlrev_b32_e32 v26, 16, v85
	v_pk_mul_f32 v[20:21], v[20:21], v[32:33]
	v_pk_mul_f32 v[28:29], v[4:5], v[28:29]
	v_pk_mul_f32 v[24:25], v[24:25], v[30:31]
	v_pk_mul_f32 v[26:27], v[26:27], v[28:29]
	v_cvt_pk_bf16_f32 v20, v20, v21
	v_cvt_pk_bf16_f32 v21, v22, v23
	v_cvt_pk_bf16_f32 v22, v24, v25
	v_add_co_u32_e32 v24, vcc, 0x2000, v18
	v_cvt_pk_bf16_f32 v23, v26, v27
	s_nop 0
	v_addc_co_u32_e32 v25, vcc, 0, v19, vcc
	global_store_dwordx4 v[24:25], v[20:23], off sc0 sc1
	s_and_saveexec_b64 s[2:3], s[12:13]
	s_cbranch_execz .LBB0_619
	v_lshl_add_u32 v20, v160, 10, s25
	s_movk_i32 s4, 0xfc00
	v_add3_u32 v24, v20, v207, s4
	ds_read_b128 v[20:23], v24
	ds_read_b128 v[24:27], v24 offset:16
	s_waitcnt lgkmcnt(1)
	v_pk_add_f32 v[16:17], v[16:17], v[22:23]
	v_pk_add_f32 v[14:15], v[14:15], v[20:21]
	s_waitcnt lgkmcnt(0)
	v_pk_add_f32 v[12:13], v[12:13], v[26:27]
	v_pk_add_f32 v[10:11], v[10:11], v[24:25]

; __device__ __forceinline__ u32x4 pack8(const f32x4 v0, const f32x4 v1) { u32x4 w; w.x = pk_f16(v0[0], v0[1]); w.y = pk_f16(v0[2], v0[3]); w.z = pk_f16(v1[0], v1[1]); w.w = pk_f16(v1[2], v1[3]); return w; }
; __device__ __forceinline__ void unpack8(const u32x4 w, f32x4& v0, f32x4& v1) { v0 = (f32x4){f16lo(w.x), f16hi(w.x), f16lo(w.y), f16hi(w.y)}; v1 = (f32x4){f16lo(w.z), f16hi(w.z), f16lo(w.w), f16hi(w.w)}; }
; __device__ __forceinline__ void pm_item(LAS float* Vs0, int item, const f16* up, const f16* zs, const float* pscale, f16* branch) {
;     int tid = threadIdx.x; asm volatile("" : "+v"(tid));
;     const int b = item >> 7, g = (item >> 5) & 3, band = item & 31, r0 = band * 4;
;     const int w = 2 << g, lo_off = w >> 1, hi_off = w - lo_off;
;     const int o = tid & 31, cs = tid >> 5;
;     const f16* ub = up + (size_t)b * SEQ * PW + g * 256 + o * 8 + (size_t)(4 * cs) * PW;
;     const size_t zoff = (size_t)b * SEQ * D + g * 256 + o * 8 + (size_t)(4 * cs) * D;
;     const f32x4 sc0 = *(const f32x4*)(pscale + g * 256 + o * 8), sc1 = *(const f32x4*)(pscale + g * 256 + o * 8 + 4);
;     float rs[4][8];
; #pragma unroll
;     for (int q = 0; q < 4; ++q)
; #pragma unroll
;         for (int e = 0; e < 8; ++e) rs[q][e] = 0.f;
;     u32x4 cen[2][4], zz[2][4], hi[2][4], lo[2][4];
; #pragma unroll
;     for (int q = 0; q < 4; ++q) { cen[0][q] = *(const u32x4*)(ub + (size_t)(r0 * GW + q) * PW); zz[0][q] = *(const u32x4*)(zs + zoff + (size_t)(r0 * GW + q) * D); }
;     { const int rlo0 = r0 - lo_off < 0 ? 0 : r0 - lo_off, rhi0 = r0 + hi_off > ROWS ? ROWS : r0 + hi_off;
; #pragma unroll 1
;       for (int fb = rlo0; fb < rhi0; fb += 8) { u32x4 t[8][4];
;     ...
;             f32x4 u0, u1, z0, z1; unpack8(cen[cur][q], u0, u1); unpack8(zz[cur][q], z0, z1);
;             *(u32x4*)(branch + zoff + (size_t)(r * GW + q) * D) = pack8((s0 * ic - u0) * sc0 * z0, (s1 * ic - u1) * sc1 * z1); } }
;     }
;     __syncthreads();
.LBB0_621:
	s_or_b64 exec, exec, s[2:3]
	s_mov_b32 s2, 0x8000
	v_xor_b32_sdwa v28, s2, v63 dst_sel:WORD_1 dst_unused:UNUSED_PAD src0_sel:DWORD src1_sel:DWORD
	v_xor_b32_sdwa v29, s2, v63 dst_sel:WORD_1 dst_unused:UNUSED_PAD src0_sel:DWORD src1_sel:WORD_1
	v_mov_b32_e32 v30, v154
	v_mov_b32_e32 v31, v154
	v_pk_fma_f32 v[16:17], v[30:31], v[16:17], v[28:29]
	v_xor_b32_sdwa v28, s2, v62 dst_sel:WORD_1 dst_unused:UNUSED_PAD src0_sel:DWORD src1_sel:DWORD
	v_xor_b32_sdwa v29, s2, v62 dst_sel:WORD_1 dst_unused:UNUSED_PAD src0_sel:DWORD src1_sel:WORD_1
	v_and_b32_e32 v21, 0xffff0000, v70
	v_pk_fma_f32 v[14:15], v[154:155], v[14:15], v[28:29]
	v_lshlrev_b32_e32 v20, 16, v70
	v_pk_mul_f32 v[6:7], v[6:7], v[14:15]
	v_xor_b32_sdwa v14, s2, v65 dst_sel:WORD_1 dst_unused:UNUSED_PAD src0_sel:DWORD src1_sel:DWORD
	v_xor_b32_sdwa v15, s2, v65 dst_sel:WORD_1 dst_unused:UNUSED_PAD src0_sel:DWORD src1_sel:WORD_1
	v_and_b32_e32 v25, 0xffff0000, v72
	v_pk_fma_f32 v[12:13], v[30:31], v[12:13], v[14:15]
	v_xor_b32_sdwa v14, s2, v64 dst_sel:WORD_1 dst_unused:UNUSED_PAD src0_sel:DWORD src1_sel:DWORD
	v_xor_b32_sdwa v15, s2, v64 dst_sel:WORD_1 dst_unused:UNUSED_PAD src0_sel:DWORD src1_sel:WORD_1
	v_lshlrev_b32_e32 v24, 16, v72
	v_pk_fma_f32 v[10:11], v[154:155], v[10:11], v[14:15]
	v_and_b32_e32 v27, 0xffff0000, v73
	v_lshlrev_b32_e32 v26, 16, v73
	v_pk_mul_f32 v[6:7], v[20:21], v[6:7]
	v_pk_mul_f32 v[2:3], v[2:3], v[10:11]
	v_pk_mul_f32 v[4:5], v[4:5], v[12:13]
	s_movk_i32 s2, 0x3000
	s_sub_i32 s6, 0x60, s54
	v_and_b32_e32 v23, 0xffff0000, v71
	v_lshlrev_b32_e32 v22, 16, v71
	v_pk_mul_f32 v[8:9], v[8:9], v[16:17]
	v_pk_mul_f32 v[10:11], v[26:27], v[4:5]
	v_pk_mul_f32 v[4:5], v[24:25], v[2:3]
	v_cvt_pk_bf16_f32 v2, v6, v7
	v_add_co_u32_e32 v6, vcc, s2, v18
	s_or_b32 s2, s35, s6
	v_pk_mul_f32 v[8:9], v[22:23], v[8:9]
	s_ashr_i32 s2, s2, 7
	v_cvt_pk_bf16_f32 v3, v8, v9
	v_cvt_pk_bf16_f32 v4, v4, v5
	v_cvt_pk_bf16_f32 v5, v10, v11
	v_addc_co_u32_e32 v7, vcc, 0, v19, vcc
	v_mov_b32_e32 v16, v0
	s_bfe_u32 s4, s6, 0x20005
	s_ashr_i32 s3, s2, 31
	global_store_dwordx4 v[6:7], v[2:5], off sc0 sc1
	s_barrier
	s_lshl_b64 s[2:3], s[2:3], 24
	s_lshl_b32 s8, s4, 8
	v_lshlrev_b32_e32 v2, 3, v16
	v_readlane_b32 s56, v254, 18
	s_lshl_b32 s7, 2, s4
	v_and_b32_e32 v221, 0xf8, v2
	s_or_b32 s8, s2, s8
	v_readlane_b32 s58, v254, 20
	v_readlane_b32 s59, v254, 21
	s_lshr_b32 s33, s7, 1
	v_or_b32_e32 v12, s8, v221
	s_lshl_b32 s8, s4, 10
	s_mov_b64 s[54:55], s[58:59]
	s_add_u32 s8, s54, s8
	s_addc_u32 s9, s55, 0
	s_and_b32 s31, s31, 0x7c
	s_add_u32 s0, s0, s2
	v_ashrrev_i32_e32 v222, 3, v16
	s_addc_u32 s1, s1, s3
	s_lshl_b32 s4, s4, 9
	v_and_b32_e32 v206, -4, v222
	s_add_u32 s0, s0, s4
	v_ashrrev_i32_e32 v207, 31, v206
	s_addc_u32 s1, s1, 0
	v_lshlrev_b32_e32 v170, 1, v221
	v_mov_b32_e32 v171, 0
	v_lshlrev_b64 v[10:11], 11, v[206:207]
	v_mov_b32_e32 v13, s3
	v_lshlrev_b32_e32 v207, 2, v221
	v_lshl_add_u64 v[14:15], s[0:1], 0, v[170:171]
	s_lshl_b32 s44, s31, 6
	s_mov_b32 s5, 0
	global_load_dwordx4 v[2:5], v207, s[8:9] offset:16
	global_load_dwordx4 v[6:9], v207, s[8:9]
	v_lshl_add_u64 v[202:203], v[14:15], 0, v[10:11]
	v_lshl_add_u64 v[208:209], v[12:13], 0, v[10:11]
	s_lshl_b32 s4, s31, 17
	s_or_b32 s8, s44, 1
	v_lshl_add_u64 v[204:205], v[208:209], 1, s[92:93]
	v_lshl_add_u64 v[12:13], v[202:203], 0, s[4:5]
	s_lshl_b32 s4, s31, 18
	s_lshl_b32 s0, s8, 11
	s_mov_b32 s1, s5
	v_lshl_add_u64 v[14:15], v[204:205], 0, s[4:5]
	global_load_dwordx4 v[78:81], v[12:13], off
	global_load_dwordx4 v[86:89], v[14:15], off
	v_lshl_add_u64 v[12:13], v[202:203], 0, s[0:1]
	s_lshl_b32 s0, s8, 12
	s_or_b32 s8, s44, 2
	v_lshl_add_u64 v[14:15], v[204:205], 0, s[0:1]
	s_lshl_b32 s0, s8, 11
	global_load_dwordx4 v[58:61], v[12:13], off
	global_load_dwordx4 v[66:69], v[14:15], off
	v_lshl_add_u64 v[12:13], v[202:203], 0, s[0:1]
	s_lshl_b32 s0, s8, 12
	s_or_b32 s8, s44, 3
	v_lshl_add_u64 v[14:15], v[204:205], 0, s[0:1]
	s_lshl_b32 s0, s8, 11
	global_load_dwordx4 v[50:53], v[12:13], off
	global_load_dwordx4 v[54:57], v[14:15], off
	v_lshl_add_u64 v[12:13], v[202:203], 0, s[0:1]
	s_lshl_b32 s0, s8, 12
	v_lshl_add_u64 v[14:15], v[204:205], 0, s[0:1]
	global_load_dwordx4 v[42:45], v[12:13], off
	global_load_dwordx4 v[46:49], v[14:15], off
	s_sub_i32 s0, s7, s33
	s_sub_i32 s35, s31, s33
	s_add_i32 s45, s0, s31
	v_readlane_b32 s57, v254, 19
	v_readlane_b32 s60, v254, 22
	v_readlane_b32 s61, v254, 23
	s_max_i32 s1, s35, 0
	s_min_i32 s5, s45, 0x80
	v_readlane_b32 s62, v254, 24
	v_readlane_b32 s63, v254, 25
	v_readlane_b32 s64, v254, 26
	v_readlane_b32 s65, v254, 27
	s_mov_b64 s[56:57], s[60:61]
	s_cmp_le_i32 s5, s1
	v_and_b32_e32 v220, 31, v16
	v_readlane_b32 s66, v254, 28
	v_readlane_b32 s67, v254, 29
	v_readlane_b32 s68, v254, 30
	v_readlane_b32 s69, v254, 31
	v_readlane_b32 s70, v254, 32
	v_readlane_b32 s71, v254, 33
	s_mov_b64 s[58:59], s[62:63]
	s_mov_b64 s[60:61], s[64:65]
	s_cbranch_scc1 .LBB0_652
	s_lshl_b32 s7, s1, 17
	s_add_u32 s2, s2, s7
	s_addc_u32 s3, s3, 0
	s_lshl_b32 s6, s6, 4
	s_and_b32 s6, s6, 0x600
	s_add_u32 s2, s6, s2
	s_addc_u32 s3, 0, s3
	v_lshl_add_u64 v[10:11], s[2:3], 0, v[10:11]
	v_lshlrev_b32_e32 v170, 4, v220
	v_lshl_add_u64 v[10:11], v[10:11], 0, v[170:171]
	v_lshl_add_u64 v[10:11], s[50:51], 0, v[10:11]
	s_mov_b64 s[2:3], 0xa3e1800
	v_mov_b32_e32 v170, v171
	v_lshl_add_u64 v[210:211], v[10:11], 0, s[2:3]
	s_mov_b32 s54, 0xfff1f000
	s_mov_b64 s[2:3], 0x100000
	s_mov_b32 s55, s1
	v_mov_b64_e32 v[200:201], v[170:171]
	v_mov_b64_e32 v[196:197], v[170:171]
	v_mov_b64_e32 v[198:199], v[170:171]
	v_mov_b64_e32 v[192:193], v[170:171]
	v_mov_b64_e32 v[194:195], v[170:171]
	v_mov_b64_e32 v[188:189], v[170:171]
	v_mov_b64_e32 v[190:191], v[170:171]
	v_mov_b64_e32 v[184:185], v[170:171]
	v_mov_b64_e32 v[186:187], v[170:171]
	v_mov_b64_e32 v[180:181], v[170:171]
	v_mov_b64_e32 v[182:183], v[170:171]
	v_mov_b64_e32 v[176:177], v[170:171]
	v_mov_b64_e32 v[178:179], v[170:171]
	v_mov_b64_e32 v[172:173], v[170:171]
	v_mov_b64_e32 v[174:175], v[170:171]
	s_branch .LBB0_624

; #define LAS __attribute__((address_space(3)))
; __device__ __forceinline__ u32x4 pack8(const f32x4 v0, const f32x4 v1) { u32x4 w; w.x = pk_f16(v0[0], v0[1]); w.y = pk_f16(v0[2], v0[3]); w.z = pk_f16(v1[0], v1[1]); w.w = pk_f16(v1[2], v1[3]); return w; }
; __device__ __forceinline__ void unpack8(const u32x4 w, f32x4& v0, f32x4& v1) { v0 = (f32x4){f16lo(w.x), f16hi(w.x), f16lo(w.y), f16hi(w.y)}; v1 = (f32x4){f16lo(w.z), f16hi(w.z), f16lo(w.w), f16hi(w.w)}; }
; __device__ __forceinline__ void pm_item(LAS float* Vs0, int item, const f16* up, const f16* zs, const float* pscale, f16* branch) {
;     ...
;             if (q > 0) { const int cin = cc + hi_off - 1, cout = cc - 1 - lo_off;
;                 if (cin < GW) { const LAS f32x4* vp = (const LAS f32x4*)(Vs + cin * 256 + o * 8); s0 += vp[0]; s1 += vp[1]; }
;                 if (cout >= 0) { const LAS f32x4* vp = (const LAS f32x4*)(Vs + cout * 256 + o * 8); s0 -= vp[0]; s1 -= vp[1]; } }
;             const int clo = cc - lo_off < 0 ? 0 : cc - lo_off, chi = cc + hi_off > GW ? GW : cc + hi_off;
;             const float ic = 1.f / (float)(chi - clo);
;             f32x4 u0, u1, z0, z1; unpack8(cen[cur][q], u0, u1); unpack8(zz[cur][q], z0, z1);
;             *(u32x4*)(branch + zoff + (size_t)(r * GW + q) * D) = pack8((s0 * ic - u0) * sc0 * z0, (s1 * ic - u1) * sc1 * z1); } }
.LBB0_662:
	s_or_b64 exec, exec, s[6:7]
	v_sub_u32_e32 v115, v157, v156
	v_cvt_f32_i32_e32 v115, v115
	s_mov_b32 s1, 0x8000
	s_waitcnt vmcnt(14)
	v_and_b32_e32 v117, 0xffff0000, v86
	v_xor_b32_sdwa v122, s1, v78 dst_sel:WORD_1 dst_unused:UNUSED_PAD src0_sel:DWORD src1_sel:DWORD
	v_div_scale_f32 v116, s[6:7], v115, v115, 1.0
	v_rcp_f32_e32 v118, v116
	v_div_scale_f32 v119, vcc, 1.0, v115, 1.0
	v_xor_b32_sdwa v123, s1, v78 dst_sel:WORD_1 dst_unused:UNUSED_PAD src0_sel:DWORD src1_sel:WORD_1
	v_fma_f32 v120, -v116, v118, 1.0
	v_fmac_f32_e32 v118, v120, v118
	v_mul_f32_e32 v120, v119, v118
	v_fma_f32 v121, -v116, v120, v119
	v_fmac_f32_e32 v120, v121, v118
	v_fma_f32 v116, -v116, v120, v119
	v_div_fmas_f32 v116, v116, v118, v120
	v_div_fixup_f32 v148, v116, v115, 1.0
	v_lshlrev_b32_e32 v116, 16, v86
	v_and_b32_e32 v119, 0xffff0000, v87
	v_lshlrev_b32_e32 v118, 16, v87
	v_and_b32_e32 v87, 0xffff0000, v88
	v_lshlrev_b32_e32 v86, 16, v88
	v_and_b32_e32 v121, 0xffff0000, v89
	v_lshlrev_b32_e32 v120, 16, v89
	v_xor_b32_sdwa v88, s1, v79 dst_sel:WORD_1 dst_unused:UNUSED_PAD src0_sel:DWORD src1_sel:DWORD
	v_xor_b32_sdwa v89, s1, v79 dst_sel:WORD_1 dst_unused:UNUSED_PAD src0_sel:DWORD src1_sel:WORD_1
	v_pk_fma_f32 v[78:79], v[148:149], v[110:111], v[122:123] op_sel_hi:[0,1,1]
	v_pk_fma_f32 v[88:89], v[148:149], v[112:113], v[88:89] op_sel_hi:[0,1,1]
	v_pk_mul_f32 v[88:89], v[8:9], v[88:89]
	v_pk_mul_f32 v[78:79], v[6:7], v[78:79]
	v_pk_mul_f32 v[88:89], v[118:119], v[88:89]
	v_xor_b32_sdwa v118, s1, v80 dst_sel:WORD_1 dst_unused:UNUSED_PAD src0_sel:DWORD src1_sel:DWORD
	v_xor_b32_sdwa v119, s1, v80 dst_sel:WORD_1 dst_unused:UNUSED_PAD src0_sel:DWORD src1_sel:WORD_1
	v_pk_mul_f32 v[78:79], v[116:117], v[78:79]
	v_xor_b32_sdwa v116, s1, v81 dst_sel:WORD_1 dst_unused:UNUSED_PAD src0_sel:DWORD src1_sel:DWORD
	v_xor_b32_sdwa v117, s1, v81 dst_sel:WORD_1 dst_unused:UNUSED_PAD src0_sel:DWORD src1_sel:WORD_1
	v_pk_fma_f32 v[80:81], v[148:149], v[106:107], v[118:119] op_sel_hi:[0,1,1]
	v_pk_mul_f32 v[80:81], v[2:3], v[80:81]
	v_pk_fma_f32 v[116:117], v[148:149], v[108:109], v[116:117] op_sel_hi:[0,1,1]
	v_pk_mul_f32 v[80:81], v[86:87], v[80:81]
	v_pk_mul_f32 v[116:117], v[4:5], v[116:117]
	v_cvt_pk_bf16_f32 v87, v88, v89
	v_cvt_pk_bf16_f32 v88, v80, v81
	v_or_b32_e32 v80, 1, v206
	v_lshl_add_u64 v[146:147], v[208:209], 1, s[36:37]
	v_pk_mul_f32 v[116:117], v[120:121], v[116:117]
	s_mov_b32 s5, 0
	v_add_u32_e32 v158, s0, v80
	s_movk_i32 s1, 0x41
	v_cvt_pk_bf16_f32 v86, v78, v79
	v_cvt_pk_bf16_f32 v89, v116, v117
	v_lshl_add_u64 v[78:79], v[146:147], 0, s[4:5]
	v_cmp_gt_i32_e64 s[4:5], s1, v158
	v_lshl_add_u32 v163, v158, 10, 0
	global_store_dwordx4 v[78:79], v[86:89], off sc0 sc1
	s_and_saveexec_b64 s[6:7], s[4:5]
	s_cbranch_execz .LBB0_664
	s_movk_i32 s1, 0xfc00
	v_add3_u32 v81, v163, v207, s1
	ds_read_b128 v[86:89], v81
	ds_read_b128 v[116:119], v81 offset:16
	s_waitcnt lgkmcnt(1)
	v_pk_add_f32 v[112:113], v[112:113], v[88:89]
	v_pk_add_f32 v[110:111], v[110:111], v[86:87]
	s_waitcnt lgkmcnt(0)
	v_pk_add_f32 v[108:109], v[108:109], v[118:119]
	v_pk_add_f32 v[106:107], v[106:107], v[116:117]

; #define LAS __attribute__((address_space(3)))
; __device__ __forceinline__ u32x4 pack8(const f32x4 v0, const f32x4 v1) { u32x4 w; w.x = pk_f16(v0[0], v0[1]); w.y = pk_f16(v0[2], v0[3]); w.z = pk_f16(v1[0], v1[1]); w.w = pk_f16(v1[2], v1[3]); return w; }
; __device__ __forceinline__ void unpack8(const u32x4 w, f32x4& v0, f32x4& v1) { v0 = (f32x4){f16lo(w.x), f16hi(w.x), f16lo(w.y), f16hi(w.y)}; v1 = (f32x4){f16lo(w.z), f16hi(w.z), f16lo(w.w), f16hi(w.w)}; }
; __device__ __forceinline__ void pm_item(LAS float* Vs0, int item, const f16* up, const f16* zs, const float* pscale, f16* branch) {
;     ...
;             if (q > 0) { const int cin = cc + hi_off - 1, cout = cc - 1 - lo_off;
;                 if (cin < GW) { const LAS f32x4* vp = (const LAS f32x4*)(Vs + cin * 256 + o * 8); s0 += vp[0]; s1 += vp[1]; }
;                 if (cout >= 0) { const LAS f32x4* vp = (const LAS f32x4*)(Vs + cout * 256 + o * 8); s0 -= vp[0]; s1 -= vp[1]; } }
;             const int clo = cc - lo_off < 0 ? 0 : cc - lo_off, chi = cc + hi_off > GW ? GW : cc + hi_off;
;             const float ic = 1.f / (float)(chi - clo);
;             f32x4 u0, u1, z0, z1; unpack8(cen[cur][q], u0, u1); unpack8(zz[cur][q], z0, z1);
;             *(u32x4*)(branch + zoff + (size_t)(r * GW + q) * D) = pack8((s0 * ic - u0) * sc0 * z0, (s1 * ic - u1) * sc1 * z1); } }
.LBB0_666:
	s_or_b64 exec, exec, s[8:9]
	v_subrev_u32_e32 v80, s33, v80
	v_max_i32_e32 v80, 0, v80
	v_min_i32_e32 v81, 64, v158
	v_sub_u32_e32 v80, v81, v80
	v_cvt_f32_i32_e32 v80, v80
	s_waitcnt vmcnt(13)
	v_and_b32_e32 v81, 0xffff0000, v66
	v_div_scale_f32 v86, s[8:9], v80, v80, 1.0
	v_rcp_f32_e32 v87, v86
	v_div_scale_f32 v88, vcc, 1.0, v80, 1.0
	s_mov_b32 s8, 0x8000
	v_fma_f32 v89, -v86, v87, 1.0
	v_fmac_f32_e32 v87, v89, v87
	v_mul_f32_e32 v89, v88, v87
	v_fma_f32 v115, -v86, v89, v88
	v_fmac_f32_e32 v89, v115, v87
	v_fma_f32 v86, -v86, v89, v88
	v_div_fmas_f32 v86, v86, v87, v89
	v_div_fixup_f32 v150, v86, v80, 1.0
	v_lshlrev_b32_e32 v80, 16, v66
	v_and_b32_e32 v87, 0xffff0000, v67
	v_lshlrev_b32_e32 v86, 16, v67
	v_and_b32_e32 v67, 0xffff0000, v68
	v_lshlrev_b32_e32 v66, 16, v68
	v_and_b32_e32 v89, 0xffff0000, v69
	v_lshlrev_b32_e32 v88, 16, v69
	v_xor_b32_sdwa v68, s8, v59 dst_sel:WORD_1 dst_unused:UNUSED_PAD src0_sel:DWORD src1_sel:DWORD
	v_xor_b32_sdwa v69, s8, v59 dst_sel:WORD_1 dst_unused:UNUSED_PAD src0_sel:DWORD src1_sel:WORD_1
	v_xor_b32_sdwa v116, s8, v58 dst_sel:WORD_1 dst_unused:UNUSED_PAD src0_sel:DWORD src1_sel:DWORD
	v_xor_b32_sdwa v117, s8, v58 dst_sel:WORD_1 dst_unused:UNUSED_PAD src0_sel:DWORD src1_sel:WORD_1
	v_pk_fma_f32 v[68:69], v[150:151], v[112:113], v[68:69] op_sel_hi:[0,1,1]
	v_pk_fma_f32 v[58:59], v[150:151], v[110:111], v[116:117] op_sel_hi:[0,1,1]
	v_pk_mul_f32 v[58:59], v[6:7], v[58:59]
	v_pk_mul_f32 v[68:69], v[8:9], v[68:69]
	v_pk_mul_f32 v[58:59], v[80:81], v[58:59]
	v_pk_mul_f32 v[68:69], v[86:87], v[68:69]
	v_xor_b32_sdwa v80, s8, v61 dst_sel:WORD_1 dst_unused:UNUSED_PAD src0_sel:DWORD src1_sel:DWORD
	v_xor_b32_sdwa v81, s8, v61 dst_sel:WORD_1 dst_unused:UNUSED_PAD src0_sel:DWORD src1_sel:WORD_1
	v_xor_b32_sdwa v86, s8, v60 dst_sel:WORD_1 dst_unused:UNUSED_PAD src0_sel:DWORD src1_sel:DWORD
	v_xor_b32_sdwa v87, s8, v60 dst_sel:WORD_1 dst_unused:UNUSED_PAD src0_sel:DWORD src1_sel:WORD_1
	v_pk_fma_f32 v[80:81], v[150:151], v[108:109], v[80:81] op_sel_hi:[0,1,1]
	v_pk_fma_f32 v[60:61], v[150:151], v[106:107], v[86:87] op_sel_hi:[0,1,1]
	v_pk_mul_f32 v[60:61], v[2:3], v[60:61]
	v_pk_mul_f32 v[80:81], v[4:5], v[80:81]
	v_pk_mul_f32 v[60:61], v[66:67], v[60:61]
	v_pk_mul_f32 v[80:81], v[88:89], v[80:81]
	v_add_co_u32_e32 v66, vcc, 0x1000, v78
	v_cvt_pk_bf16_f32 v58, v58, v59
	v_cvt_pk_bf16_f32 v59, v68, v69
	v_cvt_pk_bf16_f32 v60, v60, v61
	v_cvt_pk_bf16_f32 v61, v80, v81
	v_addc_co_u32_e32 v67, vcc, 0, v79, vcc
	global_store_dwordx4 v[66:67], v[58:61], off sc0 sc1
	s_movk_i32 s8, 0x41
	s_nop 0
	v_or_b32_e32 v58, 2, v206
	v_add_u32_e32 v159, s0, v58
	v_cmp_gt_i32_e64 s[8:9], s8, v159
	v_lshl_add_u32 v165, v159, 10, 0
	s_and_saveexec_b64 s[10:11], s[8:9]
	s_cbranch_execz .LBB0_668
	s_movk_i32 s12, 0xfc00
	v_add3_u32 v59, v165, v207, s12
	ds_read_b128 v[66:69], v59
	ds_read_b128 v[86:89], v59 offset:16
	s_waitcnt lgkmcnt(1)
	v_pk_add_f32 v[112:113], v[112:113], v[68:69]
	v_pk_add_f32 v[110:111], v[110:111], v[66:67]
	s_waitcnt lgkmcnt(0)
	v_pk_add_f32 v[108:109], v[108:109], v[88:89]
	v_pk_add_f32 v[106:107], v[106:107], v[86:87]

; #define LAS __attribute__((address_space(3)))
; __device__ __forceinline__ u32x4 pack8(const f32x4 v0, const f32x4 v1) { u32x4 w; w.x = pk_f16(v0[0], v0[1]); w.y = pk_f16(v0[2], v0[3]); w.z = pk_f16(v1[0], v1[1]); w.w = pk_f16(v1[2], v1[3]); return w; }
; __device__ __forceinline__ void unpack8(const u32x4 w, f32x4& v0, f32x4& v1) { v0 = (f32x4){f16lo(w.x), f16hi(w.x), f16lo(w.y), f16hi(w.y)}; v1 = (f32x4){f16lo(w.z), f16hi(w.z), f16lo(w.w), f16hi(w.w)}; }
; __device__ __forceinline__ void pm_item(LAS float* Vs0, int item, const f16* up, const f16* zs, const float* pscale, f16* branch) {
;     ...
;             if (q > 0) { const int cin = cc + hi_off - 1, cout = cc - 1 - lo_off;
;                 if (cin < GW) { const LAS f32x4* vp = (const LAS f32x4*)(Vs + cin * 256 + o * 8); s0 += vp[0]; s1 += vp[1]; }
;                 if (cout >= 0) { const LAS f32x4* vp = (const LAS f32x4*)(Vs + cout * 256 + o * 8); s0 -= vp[0]; s1 -= vp[1]; } }
;             const int clo = cc - lo_off < 0 ? 0 : cc - lo_off, chi = cc + hi_off > GW ? GW : cc + hi_off;
;             const float ic = 1.f / (float)(chi - clo);
;             f32x4 u0, u1, z0, z1; unpack8(cen[cur][q], u0, u1); unpack8(zz[cur][q], z0, z1);
;             *(u32x4*)(branch + zoff + (size_t)(r * GW + q) * D) = pack8((s0 * ic - u0) * sc0 * z0, (s1 * ic - u1) * sc1 * z1); } }
.LBB0_670:
	s_or_b64 exec, exec, s[12:13]
	v_subrev_u32_e32 v58, s33, v58
	v_max_i32_e32 v58, 0, v58
	v_min_i32_e32 v59, 64, v159
	v_sub_u32_e32 v58, v59, v58
	v_cvt_f32_i32_e32 v58, v58
	s_waitcnt vmcnt(12)
	v_and_b32_e32 v59, 0xffff0000, v54
	v_div_scale_f32 v60, s[12:13], v58, v58, 1.0
	v_rcp_f32_e32 v61, v60
	v_div_scale_f32 v66, vcc, 1.0, v58, 1.0
	s_mov_b32 s12, 0x8000
	v_fma_f32 v67, -v60, v61, 1.0
	v_fmac_f32_e32 v61, v67, v61
	v_mul_f32_e32 v67, v66, v61
	v_fma_f32 v68, -v60, v67, v66
	v_fmac_f32_e32 v67, v68, v61
	v_fma_f32 v60, -v60, v67, v66
	v_div_fmas_f32 v60, v60, v61, v67
	v_div_fixup_f32 v152, v60, v58, 1.0
	v_lshlrev_b32_e32 v58, 16, v54
	v_and_b32_e32 v61, 0xffff0000, v55
	v_lshlrev_b32_e32 v60, 16, v55
	v_and_b32_e32 v55, 0xffff0000, v56
	v_lshlrev_b32_e32 v54, 16, v56
	v_and_b32_e32 v67, 0xffff0000, v57
	v_lshlrev_b32_e32 v66, 16, v57
	v_xor_b32_sdwa v56, s12, v51 dst_sel:WORD_1 dst_unused:UNUSED_PAD src0_sel:DWORD src1_sel:DWORD
	v_xor_b32_sdwa v57, s12, v51 dst_sel:WORD_1 dst_unused:UNUSED_PAD src0_sel:DWORD src1_sel:WORD_1
	v_xor_b32_sdwa v68, s12, v50 dst_sel:WORD_1 dst_unused:UNUSED_PAD src0_sel:DWORD src1_sel:DWORD
	v_xor_b32_sdwa v69, s12, v50 dst_sel:WORD_1 dst_unused:UNUSED_PAD src0_sel:DWORD src1_sel:WORD_1
	v_pk_fma_f32 v[56:57], v[152:153], v[112:113], v[56:57] op_sel_hi:[0,1,1]
	v_pk_fma_f32 v[50:51], v[152:153], v[110:111], v[68:69] op_sel_hi:[0,1,1]
	v_pk_mul_f32 v[50:51], v[6:7], v[50:51]
	v_pk_mul_f32 v[56:57], v[8:9], v[56:57]
	v_pk_mul_f32 v[50:51], v[58:59], v[50:51]
	v_pk_mul_f32 v[56:57], v[60:61], v[56:57]
	v_xor_b32_sdwa v58, s12, v53 dst_sel:WORD_1 dst_unused:UNUSED_PAD src0_sel:DWORD src1_sel:DWORD
	v_xor_b32_sdwa v59, s12, v53 dst_sel:WORD_1 dst_unused:UNUSED_PAD src0_sel:DWORD src1_sel:WORD_1
	v_xor_b32_sdwa v60, s12, v52 dst_sel:WORD_1 dst_unused:UNUSED_PAD src0_sel:DWORD src1_sel:DWORD
	v_xor_b32_sdwa v61, s12, v52 dst_sel:WORD_1 dst_unused:UNUSED_PAD src0_sel:DWORD src1_sel:WORD_1
	v_pk_fma_f32 v[58:59], v[152:153], v[108:109], v[58:59] op_sel_hi:[0,1,1]
	v_pk_fma_f32 v[52:53], v[152:153], v[106:107], v[60:61] op_sel_hi:[0,1,1]
	v_pk_mul_f32 v[52:53], v[2:3], v[52:53]
	v_pk_mul_f32 v[58:59], v[4:5], v[58:59]
	v_pk_mul_f32 v[52:53], v[54:55], v[52:53]
	v_pk_mul_f32 v[58:59], v[66:67], v[58:59]
	v_add_co_u32_e32 v54, vcc, 0x2000, v78
	v_cvt_pk_bf16_f32 v50, v50, v51
	v_cvt_pk_bf16_f32 v51, v56, v57
	v_cvt_pk_bf16_f32 v52, v52, v53
	v_cvt_pk_bf16_f32 v53, v58, v59
	v_addc_co_u32_e32 v55, vcc, 0, v79, vcc
	global_store_dwordx4 v[54:55], v[50:53], off sc0 sc1
	s_movk_i32 s12, 0x41
	s_nop 0
	v_or_b32_e32 v50, 3, v222
	v_add_u32_e32 v160, s0, v50
	v_cmp_gt_i32_e64 s[12:13], s12, v160
	v_lshl_add_u32 v167, v160, 10, 0
	s_and_saveexec_b64 s[14:15], s[12:13]
	s_cbranch_execz .LBB0_672
	s_movk_i32 s18, 0xfc00
	v_add3_u32 v51, v167, v207, s18
	ds_read_b128 v[52:55], v51
	ds_read_b128 v[56:59], v51 offset:16
	s_waitcnt lgkmcnt(1)
	v_pk_add_f32 v[112:113], v[112:113], v[54:55]
	v_pk_add_f32 v[110:111], v[110:111], v[52:53]
	s_waitcnt lgkmcnt(0)
	v_pk_add_f32 v[108:109], v[108:109], v[58:59]
	v_pk_add_f32 v[106:107], v[106:107], v[56:57]

; __device__ __forceinline__ u32x4 pack8(const f32x4 v0, const f32x4 v1) { u32x4 w; w.x = pk_f16(v0[0], v0[1]); w.y = pk_f16(v0[2], v0[3]); w.z = pk_f16(v1[0], v1[1]); w.w = pk_f16(v1[2], v1[3]); return w; }
; __device__ __forceinline__ void unpack8(const u32x4 w, f32x4& v0, f32x4& v1) { v0 = (f32x4){f16lo(w.x), f16hi(w.x), f16lo(w.y), f16hi(w.y)}; v1 = (f32x4){f16lo(w.z), f16hi(w.z), f16lo(w.w), f16hi(w.w)}; }
; __device__ __forceinline__ void pm_item(LAS float* Vs0, int item, const f16* up, const f16* zs, const float* pscale, f16* branch) {
;     ...
;         if (rr >= 1) {
;             if (r + hi_off - 1 < ROWS) {
; #pragma unroll
;                 for (int q = 0; q < 4; ++q) { f32x4 v0, v1; unpack8(hi[cur][q], v0, v1);
; #pragma unroll
;                     for (int e = 0; e < 4; ++e) { rs[q][e] += v0[e]; rs[q][4 + e] += v1[e]; } } }
;     ...
;             const int clo = cc - lo_off < 0 ? 0 : cc - lo_off, chi = cc + hi_off > GW ? GW : cc + hi_off;
;             const float ic = 1.f / (float)(chi - clo);
;             f32x4 u0, u1, z0, z1; unpack8(cen[cur][q], u0, u1); unpack8(zz[cur][q], z0, z1);
;             *(u32x4*)(branch + zoff + (size_t)(r * GW + q) * D) = pack8((s0 * ic - u0) * sc0 * z0, (s1 * ic - u1) * sc1 * z1); } }
.LBB0_674:
	s_or_b64 exec, exec, s[20:21]
	v_subrev_u32_e32 v50, s33, v50
	v_max_i32_e32 v50, 0, v50
	v_min_i32_e32 v51, 64, v160
	v_sub_u32_e32 v50, v51, v50
	v_cvt_f32_i32_e32 v50, v50
	s_sub_i32 s1, 0x81, s0
	v_div_scale_f32 v51, s[18:19], v50, v50, 1.0
	v_rcp_f32_e32 v52, v51
	v_div_scale_f32 v53, vcc, 1.0, v50, 1.0
	s_mov_b32 s18, 0x8000
	v_fma_f32 v54, -v51, v52, 1.0
	v_fmac_f32_e32 v52, v54, v52
	v_mul_f32_e32 v54, v53, v52
	v_fma_f32 v55, -v51, v54, v53
	v_fmac_f32_e32 v54, v55, v52
	v_fma_f32 v51, -v51, v54, v53
	v_div_fmas_f32 v51, v51, v52, v54
	v_div_fixup_f32 v154, v51, v50, 1.0
	s_waitcnt vmcnt(11)
	v_and_b32_e32 v51, 0xffff0000, v46
	v_lshlrev_b32_e32 v50, 16, v46
	v_and_b32_e32 v53, 0xffff0000, v47
	v_lshlrev_b32_e32 v52, 16, v47
	v_and_b32_e32 v47, 0xffff0000, v48
	v_lshlrev_b32_e32 v46, 16, v48
	v_and_b32_e32 v55, 0xffff0000, v49
	v_lshlrev_b32_e32 v54, 16, v49
	v_xor_b32_sdwa v48, s18, v43 dst_sel:WORD_1 dst_unused:UNUSED_PAD src0_sel:DWORD src1_sel:DWORD
	v_xor_b32_sdwa v49, s18, v43 dst_sel:WORD_1 dst_unused:UNUSED_PAD src0_sel:DWORD src1_sel:WORD_1
	v_xor_b32_sdwa v56, s18, v42 dst_sel:WORD_1 dst_unused:UNUSED_PAD src0_sel:DWORD src1_sel:DWORD
	v_xor_b32_sdwa v57, s18, v42 dst_sel:WORD_1 dst_unused:UNUSED_PAD src0_sel:DWORD src1_sel:WORD_1
	v_pk_fma_f32 v[48:49], v[154:155], v[112:113], v[48:49] op_sel_hi:[0,1,1]
	v_pk_fma_f32 v[42:43], v[154:155], v[110:111], v[56:57] op_sel_hi:[0,1,1]
	v_pk_mul_f32 v[42:43], v[6:7], v[42:43]
	v_pk_mul_f32 v[48:49], v[8:9], v[48:49]
	v_pk_mul_f32 v[42:43], v[50:51], v[42:43]
	v_pk_mul_f32 v[48:49], v[52:53], v[48:49]
	v_xor_b32_sdwa v50, s18, v45 dst_sel:WORD_1 dst_unused:UNUSED_PAD src0_sel:DWORD src1_sel:DWORD
	v_xor_b32_sdwa v51, s18, v45 dst_sel:WORD_1 dst_unused:UNUSED_PAD src0_sel:DWORD src1_sel:WORD_1
	v_xor_b32_sdwa v52, s18, v44 dst_sel:WORD_1 dst_unused:UNUSED_PAD src0_sel:DWORD src1_sel:DWORD
	v_xor_b32_sdwa v53, s18, v44 dst_sel:WORD_1 dst_unused:UNUSED_PAD src0_sel:DWORD src1_sel:WORD_1
	v_pk_fma_f32 v[50:51], v[154:155], v[108:109], v[50:51] op_sel_hi:[0,1,1]
	v_pk_fma_f32 v[44:45], v[154:155], v[106:107], v[52:53] op_sel_hi:[0,1,1]
	v_pk_mul_f32 v[44:45], v[2:3], v[44:45]
	v_pk_mul_f32 v[50:51], v[4:5], v[50:51]
	v_pk_mul_f32 v[44:45], v[46:47], v[44:45]
	v_pk_mul_f32 v[50:51], v[54:55], v[50:51]
	v_add_co_u32_e32 v46, vcc, 0x3000, v78
	s_or_b32 s18, s31, 1
	v_cvt_pk_bf16_f32 v42, v42, v43
	v_cvt_pk_bf16_f32 v43, v48, v49
	v_cvt_pk_bf16_f32 v44, v44, v45
	v_cvt_pk_bf16_f32 v45, v50, v51
	v_addc_co_u32_e32 v47, vcc, 0, v79, vcc
	s_cmp_ge_u32 s18, s1
	global_store_dwordx4 v[46:47], v[42:45], off sc0 sc1
	s_cbranch_scc1 .LBB0_676
	s_waitcnt vmcnt(7)
	v_and_b32_e32 v43, 0xffff0000, v38
	v_lshlrev_b32_e32 v42, 16, v38
	v_and_b32_e32 v45, 0xffff0000, v39
	v_lshlrev_b32_e32 v44, 16, v39
	v_and_b32_e32 v47, 0xffff0000, v40
	v_lshlrev_b32_e32 v46, 16, v40
	v_and_b32_e32 v49, 0xffff0000, v41
	v_lshlrev_b32_e32 v48, 16, v41
	v_pk_add_f32 v[170:171], v[170:171], v[42:43]
	v_pk_add_f32 v[196:197], v[196:197], v[46:47]
	v_pk_add_f32 v[200:201], v[200:201], v[44:45]
	v_pk_add_f32 v[198:199], v[198:199], v[48:49]
	s_waitcnt vmcnt(6)
	v_and_b32_e32 v43, 0xffff0000, v30
	v_lshlrev_b32_e32 v42, 16, v30
	v_and_b32_e32 v45, 0xffff0000, v31
	v_lshlrev_b32_e32 v44, 16, v31
	v_and_b32_e32 v47, 0xffff0000, v32
	v_lshlrev_b32_e32 v46, 16, v32
	v_and_b32_e32 v49, 0xffff0000, v33
	v_lshlrev_b32_e32 v48, 16, v33
	v_pk_add_f32 v[192:193], v[192:193], v[42:43]
	v_pk_add_f32 v[188:189], v[188:189], v[46:47]
	v_pk_add_f32 v[194:195], v[194:195], v[44:45]
	v_pk_add_f32 v[190:191], v[190:191], v[48:49]
	s_waitcnt vmcnt(5)
	v_and_b32_e32 v43, 0xffff0000, v34
	v_lshlrev_b32_e32 v42, 16, v34
	v_and_b32_e32 v45, 0xffff0000, v35
	v_lshlrev_b32_e32 v44, 16, v35
	v_and_b32_e32 v47, 0xffff0000, v36
	v_lshlrev_b32_e32 v46, 16, v36
	v_and_b32_e32 v49, 0xffff0000, v37
	v_lshlrev_b32_e32 v48, 16, v37
	v_pk_add_f32 v[184:185], v[184:185], v[42:43]
	v_pk_add_f32 v[180:181], v[180:181], v[46:47]
	v_pk_add_f32 v[186:187], v[186:187], v[44:45]
	v_pk_add_f32 v[182:183], v[182:183], v[48:49]
	s_waitcnt vmcnt(4)
	v_and_b32_e32 v43, 0xffff0000, v26
	v_lshlrev_b32_e32 v42, 16, v26
	v_and_b32_e32 v45, 0xffff0000, v27
	v_lshlrev_b32_e32 v44, 16, v27
	v_and_b32_e32 v47, 0xffff0000, v28
	v_lshlrev_b32_e32 v46, 16, v28
	v_and_b32_e32 v49, 0xffff0000, v29
	v_lshlrev_b32_e32 v48, 16, v29
	v_pk_add_f32 v[176:177], v[176:177], v[42:43]
	v_pk_add_f32 v[172:173], v[172:173], v[46:47]
	v_pk_add_f32 v[178:179], v[178:179], v[44:45]
	v_pk_add_f32 v[174:175], v[174:175], v[48:49]

; #define LAS __attribute__((address_space(3)))
; __device__ __forceinline__ u32x4 pack8(const f32x4 v0, const f32x4 v1) { u32x4 w; w.x = pk_f16(v0[0], v0[1]); w.y = pk_f16(v0[2], v0[3]); w.z = pk_f16(v1[0], v1[1]); w.w = pk_f16(v1[2], v1[3]); return w; }
; __device__ __forceinline__ void unpack8(const u32x4 w, f32x4& v0, f32x4& v1) { v0 = (f32x4){f16lo(w.x), f16hi(w.x), f16lo(w.y), f16hi(w.y)}; v1 = (f32x4){f16lo(w.z), f16hi(w.z), f16lo(w.w), f16hi(w.w)}; }
; __device__ __forceinline__ void pm_item(LAS float* Vs0, int item, const f16* up, const f16* zs, const float* pscale, f16* branch) {
;     ...
;           for (int q = 0; q < 4; ++q) { const int cc = 4 * cs + q;
;             if (q > 0) { const int cin = cc + hi_off - 1, cout = cc - 1 - lo_off;
;                 if (cin < GW) { const LAS f32x4* vp = (const LAS f32x4*)(Vs + cin * 256 + o * 8); s0 += vp[0]; s1 += vp[1]; }
;                 if (cout >= 0) { const LAS f32x4* vp = (const LAS f32x4*)(Vs + cout * 256 + o * 8); s0 -= vp[0]; s1 -= vp[1]; } }
;             const int clo = cc - lo_off < 0 ? 0 : cc - lo_off, chi = cc + hi_off > GW ? GW : cc + hi_off;
;             const float ic = 1.f / (float)(chi - clo);
;             f32x4 u0, u1, z0, z1; unpack8(cen[cur][q], u0, u1); unpack8(zz[cur][q], z0, z1);
;             *(u32x4*)(branch + zoff + (size_t)(r * GW + q) * D) = pack8((s0 * ic - u0) * sc0 * z0, (s1 * ic - u1) * sc1 * z1); } }
.LBB0_687:
	s_or_b64 exec, exec, s[20:21]
	s_mov_b32 s19, 0x8000
	v_mov_b32_e32 v149, v148
	s_waitcnt vmcnt(18)
	v_and_b32_e32 v223, 0xffff0000, v102
	v_lshlrev_b32_e32 v222, 16, v102
	v_and_b32_e32 v225, 0xffff0000, v103
	v_lshlrev_b32_e32 v224, 16, v103
	v_and_b32_e32 v103, 0xffff0000, v104
	v_lshlrev_b32_e32 v102, 16, v104
	v_and_b32_e32 v227, 0xffff0000, v105
	v_lshlrev_b32_e32 v226, 16, v105
	v_xor_b32_sdwa v104, s19, v99 dst_sel:WORD_1 dst_unused:UNUSED_PAD src0_sel:DWORD src1_sel:DWORD
	v_xor_b32_sdwa v105, s19, v99 dst_sel:WORD_1 dst_unused:UNUSED_PAD src0_sel:DWORD src1_sel:WORD_1
	v_mov_b32_e32 v228, v148
	v_mov_b32_e32 v229, v148
	v_xor_b32_sdwa v230, s19, v98 dst_sel:WORD_1 dst_unused:UNUSED_PAD src0_sel:DWORD src1_sel:DWORD
	v_xor_b32_sdwa v231, s19, v98 dst_sel:WORD_1 dst_unused:UNUSED_PAD src0_sel:DWORD src1_sel:WORD_1
	v_pk_fma_f32 v[104:105], v[228:229], v[144:145], v[104:105]
	v_pk_fma_f32 v[98:99], v[148:149], v[142:143], v[230:231]
	v_pk_mul_f32 v[104:105], v[8:9], v[104:105]
	v_pk_mul_f32 v[98:99], v[6:7], v[98:99]
	v_pk_mul_f32 v[104:105], v[224:225], v[104:105]
	v_pk_mul_f32 v[98:99], v[222:223], v[98:99]
	v_xor_b32_sdwa v222, s19, v101 dst_sel:WORD_1 dst_unused:UNUSED_PAD src0_sel:DWORD src1_sel:DWORD
	v_xor_b32_sdwa v223, s19, v101 dst_sel:WORD_1 dst_unused:UNUSED_PAD src0_sel:DWORD src1_sel:WORD_1
	v_xor_b32_sdwa v224, s19, v100 dst_sel:WORD_1 dst_unused:UNUSED_PAD src0_sel:DWORD src1_sel:DWORD
	v_xor_b32_sdwa v225, s19, v100 dst_sel:WORD_1 dst_unused:UNUSED_PAD src0_sel:DWORD src1_sel:WORD_1
	v_pk_fma_f32 v[222:223], v[228:229], v[140:141], v[222:223]
	v_pk_fma_f32 v[100:101], v[148:149], v[138:139], v[224:225]
	v_pk_mul_f32 v[222:223], v[4:5], v[222:223]
	v_pk_mul_f32 v[100:101], v[2:3], v[100:101]
	v_pk_mul_f32 v[222:223], v[226:227], v[222:223]
	v_pk_mul_f32 v[102:103], v[102:103], v[100:101]
	s_lshl_b32 s18, s18, 18
	s_mov_b32 s19, 0
	v_mov_b32_e32 v151, v150
	v_mov_b32_e32 v153, v152
	v_mov_b32_e32 v155, v154
	v_cvt_pk_bf16_f32 v100, v98, v99
	v_cvt_pk_bf16_f32 v101, v104, v105
	v_cvt_pk_bf16_f32 v102, v102, v103
	v_cvt_pk_bf16_f32 v103, v222, v223
	v_lshl_add_u64 v[98:99], v[146:147], 0, s[18:19]
	global_store_dwordx4 v[98:99], v[100:103], off sc0 sc1
	s_and_saveexec_b64 s[20:21], s[4:5]
	s_cbranch_execz .LBB0_689
	v_lshl_add_u32 v100, v158, 10, s25
	s_movk_i32 s18, 0xfc00
	v_add3_u32 v104, v100, v207, s18
	ds_read_b128 v[100:103], v104
	ds_read_b128 v[222:225], v104 offset:16
	s_waitcnt lgkmcnt(1)
	v_pk_add_f32 v[144:145], v[144:145], v[102:103]
	v_pk_add_f32 v[142:143], v[142:143], v[100:101]
	s_waitcnt lgkmcnt(0)
	v_pk_add_f32 v[140:141], v[140:141], v[224:225]
	v_pk_add_f32 v[138:139], v[138:139], v[222:223]

; #define LAS __attribute__((address_space(3)))
; __device__ __forceinline__ u32x4 pack8(const f32x4 v0, const f32x4 v1) { u32x4 w; w.x = pk_f16(v0[0], v0[1]); w.y = pk_f16(v0[2], v0[3]); w.z = pk_f16(v1[0], v1[1]); w.w = pk_f16(v1[2], v1[3]); return w; }
; __device__ __forceinline__ void unpack8(const u32x4 w, f32x4& v0, f32x4& v1) { v0 = (f32x4){f16lo(w.x), f16hi(w.x), f16lo(w.y), f16hi(w.y)}; v1 = (f32x4){f16lo(w.z), f16hi(w.z), f16lo(w.w), f16hi(w.w)}; }
; __device__ __forceinline__ void pm_item(LAS float* Vs0, int item, const f16* up, const f16* zs, const float* pscale, f16* branch) {
;     ...
;           for (int q = 0; q < 4; ++q) { const int cc = 4 * cs + q;
;             if (q > 0) { const int cin = cc + hi_off - 1, cout = cc - 1 - lo_off;
;                 if (cin < GW) { const LAS f32x4* vp = (const LAS f32x4*)(Vs + cin * 256 + o * 8); s0 += vp[0]; s1 += vp[1]; }
;                 if (cout >= 0) { const LAS f32x4* vp = (const LAS f32x4*)(Vs + cout * 256 + o * 8); s0 -= vp[0]; s1 -= vp[1]; } }
;             const int clo = cc - lo_off < 0 ? 0 : cc - lo_off, chi = cc + hi_off > GW ? GW : cc + hi_off;
;             const float ic = 1.f / (float)(chi - clo);
;             f32x4 u0, u1, z0, z1; unpack8(cen[cur][q], u0, u1); unpack8(zz[cur][q], z0, z1);
;             *(u32x4*)(branch + zoff + (size_t)(r * GW + q) * D) = pack8((s0 * ic - u0) * sc0 * z0, (s1 * ic - u1) * sc1 * z1); } }
.LBB0_691:
	s_or_b64 exec, exec, s[20:21]
	s_mov_b32 s18, 0x8000
	s_waitcnt vmcnt(17)
	v_and_b32_e32 v101, 0xffff0000, v94
	v_lshlrev_b32_e32 v100, 16, v94
	v_and_b32_e32 v103, 0xffff0000, v95
	v_lshlrev_b32_e32 v102, 16, v95
	v_and_b32_e32 v95, 0xffff0000, v96
	v_lshlrev_b32_e32 v94, 16, v96
	v_and_b32_e32 v105, 0xffff0000, v97
	v_lshlrev_b32_e32 v104, 16, v97
	v_xor_b32_sdwa v96, s18, v91 dst_sel:WORD_1 dst_unused:UNUSED_PAD src0_sel:DWORD src1_sel:DWORD
	v_xor_b32_sdwa v97, s18, v91 dst_sel:WORD_1 dst_unused:UNUSED_PAD src0_sel:DWORD src1_sel:WORD_1
	v_mov_b32_e32 v222, v150
	v_mov_b32_e32 v223, v150
	v_xor_b32_sdwa v224, s18, v90 dst_sel:WORD_1 dst_unused:UNUSED_PAD src0_sel:DWORD src1_sel:DWORD
	v_xor_b32_sdwa v225, s18, v90 dst_sel:WORD_1 dst_unused:UNUSED_PAD src0_sel:DWORD src1_sel:WORD_1
	v_pk_fma_f32 v[96:97], v[222:223], v[144:145], v[96:97]
	v_pk_fma_f32 v[90:91], v[150:151], v[142:143], v[224:225]
	v_pk_mul_f32 v[96:97], v[8:9], v[96:97]
	v_pk_mul_f32 v[90:91], v[6:7], v[90:91]
	v_pk_mul_f32 v[96:97], v[102:103], v[96:97]
	v_pk_mul_f32 v[90:91], v[100:101], v[90:91]
	v_xor_b32_sdwa v100, s18, v93 dst_sel:WORD_1 dst_unused:UNUSED_PAD src0_sel:DWORD src1_sel:DWORD
	v_xor_b32_sdwa v101, s18, v93 dst_sel:WORD_1 dst_unused:UNUSED_PAD src0_sel:DWORD src1_sel:WORD_1
	v_xor_b32_sdwa v102, s18, v92 dst_sel:WORD_1 dst_unused:UNUSED_PAD src0_sel:DWORD src1_sel:DWORD
	v_xor_b32_sdwa v103, s18, v92 dst_sel:WORD_1 dst_unused:UNUSED_PAD src0_sel:DWORD src1_sel:WORD_1
	v_pk_fma_f32 v[100:101], v[222:223], v[140:141], v[100:101]
	v_pk_fma_f32 v[92:93], v[150:151], v[138:139], v[102:103]
	v_pk_mul_f32 v[100:101], v[4:5], v[100:101]
	v_pk_mul_f32 v[92:93], v[2:3], v[92:93]
	v_pk_mul_f32 v[100:101], v[104:105], v[100:101]
	v_pk_mul_f32 v[92:93], v[94:95], v[92:93]
	v_add_co_u32_e32 v94, vcc, 0x1000, v98
	v_cvt_pk_bf16_f32 v90, v90, v91
	v_cvt_pk_bf16_f32 v91, v96, v97
	v_cvt_pk_bf16_f32 v92, v92, v93
	v_cvt_pk_bf16_f32 v93, v100, v101
	v_addc_co_u32_e32 v95, vcc, 0, v99, vcc
	global_store_dwordx4 v[94:95], v[90:93], off sc0 sc1
	s_and_saveexec_b64 s[20:21], s[8:9]
	s_cbranch_execz .LBB0_693
	v_lshl_add_u32 v90, v159, 10, s25
	s_movk_i32 s18, 0xfc00
	v_add3_u32 v94, v90, v207, s18
	ds_read_b128 v[90:93], v94
	ds_read_b128 v[94:97], v94 offset:16
	s_waitcnt lgkmcnt(1)
	v_pk_add_f32 v[144:145], v[144:145], v[92:93]
	v_pk_add_f32 v[142:143], v[142:143], v[90:91]
	s_waitcnt lgkmcnt(0)
	v_pk_add_f32 v[140:141], v[140:141], v[96:97]
	v_pk_add_f32 v[138:139], v[138:139], v[94:95]

; #define LAS __attribute__((address_space(3)))
; __device__ __forceinline__ u32x4 pack8(const f32x4 v0, const f32x4 v1) { u32x4 w; w.x = pk_f16(v0[0], v0[1]); w.y = pk_f16(v0[2], v0[3]); w.z = pk_f16(v1[0], v1[1]); w.w = pk_f16(v1[2], v1[3]); return w; }
; __device__ __forceinline__ void unpack8(const u32x4 w, f32x4& v0, f32x4& v1) { v0 = (f32x4){f16lo(w.x), f16hi(w.x), f16lo(w.y), f16hi(w.y)}; v1 = (f32x4){f16lo(w.z), f16hi(w.z), f16lo(w.w), f16hi(w.w)}; }
; __device__ __forceinline__ void pm_item(LAS float* Vs0, int item, const f16* up, const f16* zs, const float* pscale, f16* branch) {
;     ...
;           for (int q = 0; q < 4; ++q) { const int cc = 4 * cs + q;
;             if (q > 0) { const int cin = cc + hi_off - 1, cout = cc - 1 - lo_off;
;                 if (cin < GW) { const LAS f32x4* vp = (const LAS f32x4*)(Vs + cin * 256 + o * 8); s0 += vp[0]; s1 += vp[1]; }
;                 if (cout >= 0) { const LAS f32x4* vp = (const LAS f32x4*)(Vs + cout * 256 + o * 8); s0 -= vp[0]; s1 -= vp[1]; } }
;             const int clo = cc - lo_off < 0 ? 0 : cc - lo_off, chi = cc + hi_off > GW ? GW : cc + hi_off;
;             const float ic = 1.f / (float)(chi - clo);
;             f32x4 u0, u1, z0, z1; unpack8(cen[cur][q], u0, u1); unpack8(zz[cur][q], z0, z1);
;             *(u32x4*)(branch + zoff + (size_t)(r * GW + q) * D) = pack8((s0 * ic - u0) * sc0 * z0, (s1 * ic - u1) * sc1 * z1); } }
.LBB0_695:
	s_or_b64 exec, exec, s[20:21]
	s_mov_b32 s18, 0x8000
	s_waitcnt vmcnt(16)
	v_and_b32_e32 v91, 0xffff0000, v82
	v_lshlrev_b32_e32 v90, 16, v82
	v_and_b32_e32 v93, 0xffff0000, v83
	v_lshlrev_b32_e32 v92, 16, v83
	v_and_b32_e32 v83, 0xffff0000, v84
	v_lshlrev_b32_e32 v82, 16, v84
	v_and_b32_e32 v95, 0xffff0000, v85
	v_lshlrev_b32_e32 v94, 16, v85
	v_xor_b32_sdwa v84, s18, v75 dst_sel:WORD_1 dst_unused:UNUSED_PAD src0_sel:DWORD src1_sel:DWORD
	v_xor_b32_sdwa v85, s18, v75 dst_sel:WORD_1 dst_unused:UNUSED_PAD src0_sel:DWORD src1_sel:WORD_1
	v_mov_b32_e32 v96, v152
	v_mov_b32_e32 v97, v152
	v_xor_b32_sdwa v100, s18, v74 dst_sel:WORD_1 dst_unused:UNUSED_PAD src0_sel:DWORD src1_sel:DWORD
	v_xor_b32_sdwa v101, s18, v74 dst_sel:WORD_1 dst_unused:UNUSED_PAD src0_sel:DWORD src1_sel:WORD_1
	v_pk_fma_f32 v[84:85], v[96:97], v[144:145], v[84:85]
	v_pk_fma_f32 v[74:75], v[152:153], v[142:143], v[100:101]
	v_pk_mul_f32 v[84:85], v[8:9], v[84:85]
	v_pk_mul_f32 v[74:75], v[6:7], v[74:75]
	v_pk_mul_f32 v[84:85], v[92:93], v[84:85]
	v_pk_mul_f32 v[74:75], v[90:91], v[74:75]
	v_xor_b32_sdwa v90, s18, v77 dst_sel:WORD_1 dst_unused:UNUSED_PAD src0_sel:DWORD src1_sel:DWORD
	v_xor_b32_sdwa v91, s18, v77 dst_sel:WORD_1 dst_unused:UNUSED_PAD src0_sel:DWORD src1_sel:WORD_1
	v_xor_b32_sdwa v92, s18, v76 dst_sel:WORD_1 dst_unused:UNUSED_PAD src0_sel:DWORD src1_sel:DWORD
	v_xor_b32_sdwa v93, s18, v76 dst_sel:WORD_1 dst_unused:UNUSED_PAD src0_sel:DWORD src1_sel:WORD_1
	v_pk_fma_f32 v[90:91], v[96:97], v[140:141], v[90:91]
	v_pk_fma_f32 v[76:77], v[152:153], v[138:139], v[92:93]
	v_pk_mul_f32 v[90:91], v[4:5], v[90:91]
	v_pk_mul_f32 v[76:77], v[2:3], v[76:77]
	v_pk_mul_f32 v[90:91], v[94:95], v[90:91]
	v_pk_mul_f32 v[76:77], v[82:83], v[76:77]
	v_add_co_u32_e32 v82, vcc, 0x2000, v98
	v_cvt_pk_bf16_f32 v74, v74, v75
	v_cvt_pk_bf16_f32 v75, v84, v85
	v_cvt_pk_bf16_f32 v76, v76, v77
	v_cvt_pk_bf16_f32 v77, v90, v91
	v_addc_co_u32_e32 v83, vcc, 0, v99, vcc
	global_store_dwordx4 v[82:83], v[74:77], off sc0 sc1
	s_and_saveexec_b64 s[20:21], s[12:13]
	s_cbranch_execz .LBB0_697
	v_lshl_add_u32 v74, v160, 10, s25
	s_movk_i32 s18, 0xfc00
	v_add3_u32 v82, v74, v207, s18
	ds_read_b128 v[74:77], v82
	ds_read_b128 v[82:85], v82 offset:16
	s_waitcnt lgkmcnt(1)
	v_pk_add_f32 v[144:145], v[144:145], v[76:77]
	v_pk_add_f32 v[142:143], v[142:143], v[74:75]
	s_waitcnt lgkmcnt(0)
	v_pk_add_f32 v[140:141], v[140:141], v[84:85]
	v_pk_add_f32 v[138:139], v[138:139], v[82:83]

; #define LAS __attribute__((address_space(3)))
; __device__ __forceinline__ u32x4 pack8(const f32x4 v0, const f32x4 v1) { u32x4 w; w.x = pk_f16(v0[0], v0[1]); w.y = pk_f16(v0[2], v0[3]); w.z = pk_f16(v1[0], v1[1]); w.w = pk_f16(v1[2], v1[3]); return w; }
; __device__ __forceinline__ void unpack8(const u32x4 w, f32x4& v0, f32x4& v1) { v0 = (f32x4){f16lo(w.x), f16hi(w.x), f16lo(w.y), f16hi(w.y)}; v1 = (f32x4){f16lo(w.z), f16hi(w.z), f16lo(w.w), f16hi(w.w)}; }
; __device__ __forceinline__ void pm_item(LAS float* Vs0, int item, const f16* up, const f16* zs, const float* pscale, f16* branch) {
;     ...
;         if (rr >= 1) {
;             if (r + hi_off - 1 < ROWS) {
; #pragma unroll
;                 for (int q = 0; q < 4; ++q) { f32x4 v0, v1; unpack8(hi[cur][q], v0, v1);
; #pragma unroll
;                     for (int e = 0; e < 4; ++e) { rs[q][e] += v0[e]; rs[q][4 + e] += v1[e]; } } }
;     ...
;           for (int q = 0; q < 4; ++q) { const int cc = 4 * cs + q;
;             if (q > 0) { const int cin = cc + hi_off - 1, cout = cc - 1 - lo_off;
;                 if (cin < GW) { const LAS f32x4* vp = (const LAS f32x4*)(Vs + cin * 256 + o * 8); s0 += vp[0]; s1 += vp[1]; }
;                 if (cout >= 0) { const LAS f32x4* vp = (const LAS f32x4*)(Vs + cout * 256 + o * 8); s0 -= vp[0]; s1 -= vp[1]; } }
;             const int clo = cc - lo_off < 0 ? 0 : cc - lo_off, chi = cc + hi_off > GW ? GW : cc + hi_off;
;             const float ic = 1.f / (float)(chi - clo);
;             f32x4 u0, u1, z0, z1; unpack8(cen[cur][q], u0, u1); unpack8(zz[cur][q], z0, z1);
;             *(u32x4*)(branch + zoff + (size_t)(r * GW + q) * D) = pack8((s0 * ic - u0) * sc0 * z0, (s1 * ic - u1) * sc1 * z1); } }
.LBB0_699:
	s_or_b64 exec, exec, s[20:21]
	s_mov_b32 s18, 0x8000
	s_waitcnt vmcnt(15)
	v_and_b32_e32 v75, 0xffff0000, v70
	v_lshlrev_b32_e32 v74, 16, v70
	v_and_b32_e32 v77, 0xffff0000, v71
	v_lshlrev_b32_e32 v76, 16, v71
	v_and_b32_e32 v71, 0xffff0000, v72
	v_lshlrev_b32_e32 v70, 16, v72
	v_and_b32_e32 v83, 0xffff0000, v73
	v_lshlrev_b32_e32 v82, 16, v73
	v_xor_b32_sdwa v72, s18, v63 dst_sel:WORD_1 dst_unused:UNUSED_PAD src0_sel:DWORD src1_sel:DWORD
	v_xor_b32_sdwa v73, s18, v63 dst_sel:WORD_1 dst_unused:UNUSED_PAD src0_sel:DWORD src1_sel:WORD_1
	v_mov_b32_e32 v84, v154
	v_mov_b32_e32 v85, v154
	v_xor_b32_sdwa v90, s18, v62 dst_sel:WORD_1 dst_unused:UNUSED_PAD src0_sel:DWORD src1_sel:DWORD
	v_xor_b32_sdwa v91, s18, v62 dst_sel:WORD_1 dst_unused:UNUSED_PAD src0_sel:DWORD src1_sel:WORD_1
	v_pk_fma_f32 v[72:73], v[84:85], v[144:145], v[72:73]
	v_pk_fma_f32 v[62:63], v[154:155], v[142:143], v[90:91]
	v_pk_mul_f32 v[72:73], v[8:9], v[72:73]
	v_pk_mul_f32 v[62:63], v[6:7], v[62:63]
	v_pk_mul_f32 v[72:73], v[76:77], v[72:73]
	v_pk_mul_f32 v[62:63], v[74:75], v[62:63]
	v_xor_b32_sdwa v74, s18, v65 dst_sel:WORD_1 dst_unused:UNUSED_PAD src0_sel:DWORD src1_sel:DWORD
	v_xor_b32_sdwa v75, s18, v65 dst_sel:WORD_1 dst_unused:UNUSED_PAD src0_sel:DWORD src1_sel:WORD_1
	v_xor_b32_sdwa v76, s18, v64 dst_sel:WORD_1 dst_unused:UNUSED_PAD src0_sel:DWORD src1_sel:DWORD
	v_xor_b32_sdwa v77, s18, v64 dst_sel:WORD_1 dst_unused:UNUSED_PAD src0_sel:DWORD src1_sel:WORD_1
	v_pk_fma_f32 v[74:75], v[84:85], v[140:141], v[74:75]
	v_pk_fma_f32 v[64:65], v[154:155], v[138:139], v[76:77]
	v_pk_mul_f32 v[74:75], v[4:5], v[74:75]
	v_pk_mul_f32 v[64:65], v[2:3], v[64:65]
	v_pk_mul_f32 v[74:75], v[82:83], v[74:75]
	v_pk_mul_f32 v[64:65], v[70:71], v[64:65]
	v_add_co_u32_e32 v70, vcc, 0x3000, v98
	s_or_b32 s18, s31, 2
	v_cvt_pk_bf16_f32 v62, v62, v63
	v_cvt_pk_bf16_f32 v63, v72, v73
	v_cvt_pk_bf16_f32 v64, v64, v65
	v_cvt_pk_bf16_f32 v65, v74, v75
	v_addc_co_u32_e32 v71, vcc, 0, v99, vcc
	s_cmp_ge_u32 s18, s1
	global_store_dwordx4 v[70:71], v[62:65], off sc0 sc1
	s_cbranch_scc1 .LBB0_701
	s_waitcnt vmcnt(7)
	v_and_b32_e32 v63, 0xffff0000, v134
	v_lshlrev_b32_e32 v62, 16, v134
	v_and_b32_e32 v65, 0xffff0000, v135
	v_lshlrev_b32_e32 v64, 16, v135
	v_and_b32_e32 v71, 0xffff0000, v136
	v_lshlrev_b32_e32 v70, 16, v136
	v_and_b32_e32 v73, 0xffff0000, v137
	v_lshlrev_b32_e32 v72, 16, v137
	v_pk_add_f32 v[170:171], v[170:171], v[62:63]
	v_pk_add_f32 v[196:197], v[196:197], v[70:71]
	v_pk_add_f32 v[200:201], v[200:201], v[64:65]
	v_pk_add_f32 v[198:199], v[198:199], v[72:73]
	s_waitcnt vmcnt(6)
	v_and_b32_e32 v63, 0xffff0000, v130
	v_lshlrev_b32_e32 v62, 16, v130
	v_and_b32_e32 v65, 0xffff0000, v131
	v_lshlrev_b32_e32 v64, 16, v131
	v_and_b32_e32 v71, 0xffff0000, v132
	v_lshlrev_b32_e32 v70, 16, v132
	v_and_b32_e32 v73, 0xffff0000, v133
	v_lshlrev_b32_e32 v72, 16, v133
	v_pk_add_f32 v[192:193], v[192:193], v[62:63]
	v_pk_add_f32 v[188:189], v[188:189], v[70:71]
	v_pk_add_f32 v[194:195], v[194:195], v[64:65]
	v_pk_add_f32 v[190:191], v[190:191], v[72:73]
	s_waitcnt vmcnt(5)
	v_and_b32_e32 v63, 0xffff0000, v122
	v_lshlrev_b32_e32 v62, 16, v122
	v_and_b32_e32 v65, 0xffff0000, v123
	v_lshlrev_b32_e32 v64, 16, v123
	v_and_b32_e32 v71, 0xffff0000, v124
	v_lshlrev_b32_e32 v70, 16, v124
	v_and_b32_e32 v73, 0xffff0000, v125
	v_lshlrev_b32_e32 v72, 16, v125
	v_pk_add_f32 v[184:185], v[184:185], v[62:63]
	v_pk_add_f32 v[180:181], v[180:181], v[70:71]
	v_pk_add_f32 v[186:187], v[186:187], v[64:65]
	v_pk_add_f32 v[182:183], v[182:183], v[72:73]
	s_waitcnt vmcnt(4)
	v_and_b32_e32 v63, 0xffff0000, v114
	v_lshlrev_b32_e32 v62, 16, v114
	v_and_b32_e32 v65, 0xffff0000, v115
	v_lshlrev_b32_e32 v64, 16, v115
	v_and_b32_e32 v71, 0xffff0000, v116
	v_lshlrev_b32_e32 v70, 16, v116
	v_and_b32_e32 v73, 0xffff0000, v117
	v_lshlrev_b32_e32 v72, 16, v117
	v_pk_add_f32 v[176:177], v[176:177], v[62:63]
	v_pk_add_f32 v[172:173], v[172:173], v[70:71]
	v_pk_add_f32 v[178:179], v[178:179], v[64:65]
	v_pk_add_f32 v[174:175], v[174:175], v[72:73]

; #define LAS __attribute__((address_space(3)))
; __device__ __forceinline__ u32x4 pack8(const f32x4 v0, const f32x4 v1) { u32x4 w; w.x = pk_f16(v0[0], v0[1]); w.y = pk_f16(v0[2], v0[3]); w.z = pk_f16(v1[0], v1[1]); w.w = pk_f16(v1[2], v1[3]); return w; }
; __device__ __forceinline__ void unpack8(const u32x4 w, f32x4& v0, f32x4& v1) { v0 = (f32x4){f16lo(w.x), f16hi(w.x), f16lo(w.y), f16hi(w.y)}; v1 = (f32x4){f16lo(w.z), f16hi(w.z), f16lo(w.w), f16hi(w.w)}; }
; __device__ __forceinline__ void pm_item(LAS float* Vs0, int item, const f16* up, const f16* zs, const float* pscale, f16* branch) {
;     ...
;         if (rr >= 1) {
;             if (r + hi_off - 1 < ROWS) {
; #pragma unroll
;                 for (int q = 0; q < 4; ++q) { f32x4 v0, v1; unpack8(hi[cur][q], v0, v1);
; #pragma unroll
;                     for (int e = 0; e < 4; ++e) { rs[q][e] += v0[e]; rs[q][4 + e] += v1[e]; } } }
;     ...
;           for (int q = 0; q < 4; ++q) { const int cc = 4 * cs + q;
;             if (q > 0) { const int cin = cc + hi_off - 1, cout = cc - 1 - lo_off;
;                 if (cin < GW) { const LAS f32x4* vp = (const LAS f32x4*)(Vs + cin * 256 + o * 8); s0 += vp[0]; s1 += vp[1]; }
;                 if (cout >= 0) { const LAS f32x4* vp = (const LAS f32x4*)(Vs + cout * 256 + o * 8); s0 -= vp[0]; s1 -= vp[1]; } }
;             const int clo = cc - lo_off < 0 ? 0 : cc - lo_off, chi = cc + hi_off > GW ? GW : cc + hi_off;
;             const float ic = 1.f / (float)(chi - clo);
;             f32x4 u0, u1, z0, z1; unpack8(cen[cur][q], u0, u1); unpack8(zz[cur][q], z0, z1);
;             *(u32x4*)(branch + zoff + (size_t)(r * GW + q) * D) = pack8((s0 * ic - u0) * sc0 * z0, (s1 * ic - u1) * sc1 * z1); } }
.LBB0_723:
	s_or_b64 exec, exec, s[20:21]
	s_mov_b32 s18, 0x8000
	v_and_b32_e32 v51, 0xffff0000, v46
	v_lshlrev_b32_e32 v50, 16, v46
	v_and_b32_e32 v53, 0xffff0000, v47
	v_lshlrev_b32_e32 v52, 16, v47
	v_and_b32_e32 v47, 0xffff0000, v48
	v_lshlrev_b32_e32 v46, 16, v48
	v_and_b32_e32 v55, 0xffff0000, v49
	v_lshlrev_b32_e32 v54, 16, v49
	v_xor_b32_sdwa v48, s18, v43 dst_sel:WORD_1 dst_unused:UNUSED_PAD src0_sel:DWORD src1_sel:DWORD
	v_xor_b32_sdwa v49, s18, v43 dst_sel:WORD_1 dst_unused:UNUSED_PAD src0_sel:DWORD src1_sel:WORD_1
	v_mov_b32_e32 v56, v154
	v_mov_b32_e32 v57, v154
	v_xor_b32_sdwa v58, s18, v42 dst_sel:WORD_1 dst_unused:UNUSED_PAD src0_sel:DWORD src1_sel:DWORD
	v_xor_b32_sdwa v59, s18, v42 dst_sel:WORD_1 dst_unused:UNUSED_PAD src0_sel:DWORD src1_sel:WORD_1
	v_pk_fma_f32 v[48:49], v[56:57], v[112:113], v[48:49]
	v_pk_fma_f32 v[42:43], v[154:155], v[110:111], v[58:59]
	v_pk_mul_f32 v[48:49], v[8:9], v[48:49]
	v_pk_mul_f32 v[42:43], v[6:7], v[42:43]
	v_pk_mul_f32 v[48:49], v[52:53], v[48:49]
	v_pk_mul_f32 v[42:43], v[50:51], v[42:43]
	v_xor_b32_sdwa v50, s18, v45 dst_sel:WORD_1 dst_unused:UNUSED_PAD src0_sel:DWORD src1_sel:DWORD
	v_xor_b32_sdwa v51, s18, v45 dst_sel:WORD_1 dst_unused:UNUSED_PAD src0_sel:DWORD src1_sel:WORD_1
	v_xor_b32_sdwa v52, s18, v44 dst_sel:WORD_1 dst_unused:UNUSED_PAD src0_sel:DWORD src1_sel:DWORD
	v_xor_b32_sdwa v53, s18, v44 dst_sel:WORD_1 dst_unused:UNUSED_PAD src0_sel:DWORD src1_sel:WORD_1
	v_pk_fma_f32 v[50:51], v[56:57], v[108:109], v[50:51]
	v_pk_fma_f32 v[44:45], v[154:155], v[106:107], v[52:53]
	v_pk_mul_f32 v[50:51], v[4:5], v[50:51]
	v_pk_mul_f32 v[44:45], v[2:3], v[44:45]
	v_pk_mul_f32 v[50:51], v[54:55], v[50:51]
	v_pk_mul_f32 v[44:45], v[46:47], v[44:45]
	v_add_co_u32_e32 v46, vcc, 0x3000, v78
	s_or_b32 s18, s31, 3
	v_cvt_pk_bf16_f32 v42, v42, v43
	v_cvt_pk_bf16_f32 v43, v48, v49
	v_cvt_pk_bf16_f32 v44, v44, v45
	v_cvt_pk_bf16_f32 v45, v50, v51
	v_addc_co_u32_e32 v47, vcc, 0, v79, vcc
	s_cmp_ge_u32 s18, s1
	global_store_dwordx4 v[46:47], v[42:45], off sc0 sc1
	s_cbranch_scc1 .LBB0_725
	s_waitcnt vmcnt(7)
	v_and_b32_e32 v43, 0xffff0000, v38
	v_lshlrev_b32_e32 v42, 16, v38
	v_and_b32_e32 v45, 0xffff0000, v39
	v_lshlrev_b32_e32 v44, 16, v39
	v_and_b32_e32 v39, 0xffff0000, v40
	v_lshlrev_b32_e32 v38, 16, v40
	v_and_b32_e32 v47, 0xffff0000, v41
	v_lshlrev_b32_e32 v46, 16, v41
	v_pk_add_f32 v[196:197], v[196:197], v[38:39]
	s_waitcnt vmcnt(6)
	v_and_b32_e32 v39, 0xffff0000, v30
	v_lshlrev_b32_e32 v38, 16, v30
	v_and_b32_e32 v41, 0xffff0000, v31
	v_lshlrev_b32_e32 v40, 16, v31
	v_and_b32_e32 v31, 0xffff0000, v32
	v_lshlrev_b32_e32 v30, 16, v32
	v_pk_add_f32 v[170:171], v[170:171], v[42:43]
	v_and_b32_e32 v43, 0xffff0000, v33
	v_lshlrev_b32_e32 v42, 16, v33
	v_pk_add_f32 v[188:189], v[188:189], v[30:31]
	s_waitcnt vmcnt(5)
	v_and_b32_e32 v31, 0xffff0000, v34
	v_lshlrev_b32_e32 v30, 16, v34
	v_and_b32_e32 v33, 0xffff0000, v35
	v_lshlrev_b32_e32 v32, 16, v35
	v_and_b32_e32 v35, 0xffff0000, v36
	v_lshlrev_b32_e32 v34, 16, v36
	v_pk_add_f32 v[192:193], v[192:193], v[38:39]
	v_and_b32_e32 v39, 0xffff0000, v37
	v_lshlrev_b32_e32 v38, 16, v37
	v_pk_add_f32 v[184:185], v[184:185], v[30:31]
	v_pk_add_f32 v[180:181], v[180:181], v[34:35]
	v_pk_add_f32 v[186:187], v[186:187], v[32:33]
	s_waitcnt vmcnt(4)
	v_and_b32_e32 v31, 0xffff0000, v26
	v_lshlrev_b32_e32 v30, 16, v26
	v_and_b32_e32 v33, 0xffff0000, v27
	v_lshlrev_b32_e32 v32, 16, v27
	v_and_b32_e32 v27, 0xffff0000, v28
	v_lshlrev_b32_e32 v26, 16, v28
	v_and_b32_e32 v35, 0xffff0000, v29
	v_lshlrev_b32_e32 v34, 16, v29
	v_pk_add_f32 v[200:201], v[200:201], v[44:45]
	v_pk_add_f32 v[198:199], v[198:199], v[46:47]
	v_pk_add_f32 v[194:195], v[194:195], v[40:41]
	v_pk_add_f32 v[190:191], v[190:191], v[42:43]
	v_pk_add_f32 v[182:183], v[182:183], v[38:39]
	v_pk_add_f32 v[176:177], v[176:177], v[30:31]
	v_pk_add_f32 v[172:173], v[172:173], v[26:27]
	v_pk_add_f32 v[178:179], v[178:179], v[32:33]
	v_pk_add_f32 v[174:175], v[174:175], v[34:35]

; #define LAS __attribute__((address_space(3)))
; __device__ __forceinline__ u32x4 pack8(const f32x4 v0, const f32x4 v1) { u32x4 w; w.x = pk_f16(v0[0], v0[1]); w.y = pk_f16(v0[2], v0[3]); w.z = pk_f16(v1[0], v1[1]); w.w = pk_f16(v1[2], v1[3]); return w; }
; __device__ __forceinline__ void unpack8(const u32x4 w, f32x4& v0, f32x4& v1) { v0 = (f32x4){f16lo(w.x), f16hi(w.x), f16lo(w.y), f16hi(w.y)}; v1 = (f32x4){f16lo(w.z), f16hi(w.z), f16lo(w.w), f16hi(w.w)}; }
; __device__ __forceinline__ void pm_item(LAS float* Vs0, int item, const f16* up, const f16* zs, const float* pscale, f16* branch) {
;     ...
;           for (int q = 0; q < 4; ++q) { const int cc = 4 * cs + q;
;             if (q > 0) { const int cin = cc + hi_off - 1, cout = cc - 1 - lo_off;
;                 if (cin < GW) { const LAS f32x4* vp = (const LAS f32x4*)(Vs + cin * 256 + o * 8); s0 += vp[0]; s1 += vp[1]; }
;                 if (cout >= 0) { const LAS f32x4* vp = (const LAS f32x4*)(Vs + cout * 256 + o * 8); s0 -= vp[0]; s1 -= vp[1]; } }
;             const int clo = cc - lo_off < 0 ? 0 : cc - lo_off, chi = cc + hi_off > GW ? GW : cc + hi_off;
;             const float ic = 1.f / (float)(chi - clo);
;             f32x4 u0, u1, z0, z1; unpack8(cen[cur][q], u0, u1); unpack8(zz[cur][q], z0, z1);
;             *(u32x4*)(branch + zoff + (size_t)(r * GW + q) * D) = pack8((s0 * ic - u0) * sc0 * z0, (s1 * ic - u1) * sc1 * z1); } }
.LBB0_731:
	s_or_b64 exec, exec, s[20:21]
	s_mov_b32 s0, 0x8000
	v_xor_b32_sdwa v26, s0, v99 dst_sel:WORD_1 dst_unused:UNUSED_PAD src0_sel:DWORD src1_sel:DWORD
	v_xor_b32_sdwa v27, s0, v99 dst_sel:WORD_1 dst_unused:UNUSED_PAD src0_sel:DWORD src1_sel:WORD_1
	v_mov_b32_e32 v28, v148
	v_mov_b32_e32 v29, v148
	v_pk_fma_f32 v[26:27], v[28:29], v[16:17], v[26:27]
	v_and_b32_e32 v21, 0xffff0000, v103
	v_lshlrev_b32_e32 v20, 16, v103
	v_pk_mul_f32 v[26:27], v[8:9], v[26:27]
	v_xor_b32_sdwa v30, s0, v98 dst_sel:WORD_1 dst_unused:UNUSED_PAD src0_sel:DWORD src1_sel:DWORD
	v_pk_mul_f32 v[26:27], v[20:21], v[26:27]
	v_xor_b32_sdwa v20, s0, v101 dst_sel:WORD_1 dst_unused:UNUSED_PAD src0_sel:DWORD src1_sel:DWORD
	v_xor_b32_sdwa v21, s0, v101 dst_sel:WORD_1 dst_unused:UNUSED_PAD src0_sel:DWORD src1_sel:WORD_1
	v_xor_b32_sdwa v31, s0, v98 dst_sel:WORD_1 dst_unused:UNUSED_PAD src0_sel:DWORD src1_sel:WORD_1
	v_pk_fma_f32 v[20:21], v[28:29], v[12:13], v[20:21]
	v_xor_b32_sdwa v28, s0, v100 dst_sel:WORD_1 dst_unused:UNUSED_PAD src0_sel:DWORD src1_sel:DWORD
	v_xor_b32_sdwa v29, s0, v100 dst_sel:WORD_1 dst_unused:UNUSED_PAD src0_sel:DWORD src1_sel:WORD_1
	v_pk_fma_f32 v[30:31], v[148:149], v[14:15], v[30:31]
	v_pk_fma_f32 v[28:29], v[148:149], v[10:11], v[28:29]
	v_and_b32_e32 v19, 0xffff0000, v102
	v_lshlrev_b32_e32 v18, 16, v102
	v_and_b32_e32 v23, 0xffff0000, v104
	v_lshlrev_b32_e32 v22, 16, v104
	v_and_b32_e32 v25, 0xffff0000, v105
	v_lshlrev_b32_e32 v24, 16, v105
	v_pk_mul_f32 v[30:31], v[6:7], v[30:31]
	v_pk_mul_f32 v[28:29], v[2:3], v[28:29]
	v_pk_mul_f32 v[20:21], v[4:5], v[20:21]
	v_pk_mul_f32 v[18:19], v[18:19], v[30:31]
	v_pk_mul_f32 v[24:25], v[24:25], v[20:21]
	v_pk_mul_f32 v[22:23], v[22:23], v[28:29]
	s_lshl_b32 s0, s18, 18
	s_mov_b32 s1, 0
	v_cvt_pk_bf16_f32 v20, v18, v19
	v_cvt_pk_bf16_f32 v21, v26, v27
	v_cvt_pk_bf16_f32 v22, v22, v23
	v_cvt_pk_bf16_f32 v23, v24, v25
	v_lshl_add_u64 v[18:19], v[146:147], 0, s[0:1]
	global_store_dwordx4 v[18:19], v[20:23], off sc0 sc1
	s_and_saveexec_b64 s[2:3], s[4:5]
	s_cbranch_execz .LBB0_733
	v_lshl_add_u32 v20, v158, 10, s25
	s_movk_i32 s0, 0xfc00
	v_add3_u32 v24, v20, v207, s0
	ds_read_b128 v[20:23], v24
	ds_read_b128 v[24:27], v24 offset:16
	s_waitcnt lgkmcnt(1)
	v_pk_add_f32 v[16:17], v[16:17], v[22:23]
	v_pk_add_f32 v[14:15], v[14:15], v[20:21]
	s_waitcnt lgkmcnt(0)
	v_pk_add_f32 v[12:13], v[12:13], v[26:27]
	v_pk_add_f32 v[10:11], v[10:11], v[24:25]

; #define LAS __attribute__((address_space(3)))
; __device__ __forceinline__ u32x4 pack8(const f32x4 v0, const f32x4 v1) { u32x4 w; w.x = pk_f16(v0[0], v0[1]); w.y = pk_f16(v0[2], v0[3]); w.z = pk_f16(v1[0], v1[1]); w.w = pk_f16(v1[2], v1[3]); return w; }
; __device__ __forceinline__ void unpack8(const u32x4 w, f32x4& v0, f32x4& v1) { v0 = (f32x4){f16lo(w.x), f16hi(w.x), f16lo(w.y), f16hi(w.y)}; v1 = (f32x4){f16lo(w.z), f16hi(w.z), f16lo(w.w), f16hi(w.w)}; }
; __device__ __forceinline__ void pm_item(LAS float* Vs0, int item, const f16* up, const f16* zs, const float* pscale, f16* branch) {
;     ...
;           for (int q = 0; q < 4; ++q) { const int cc = 4 * cs + q;
;             if (q > 0) { const int cin = cc + hi_off - 1, cout = cc - 1 - lo_off;
;                 if (cin < GW) { const LAS f32x4* vp = (const LAS f32x4*)(Vs + cin * 256 + o * 8); s0 += vp[0]; s1 += vp[1]; }
;                 if (cout >= 0) { const LAS f32x4* vp = (const LAS f32x4*)(Vs + cout * 256 + o * 8); s0 -= vp[0]; s1 -= vp[1]; } }
;             const int clo = cc - lo_off < 0 ? 0 : cc - lo_off, chi = cc + hi_off > GW ? GW : cc + hi_off;
;             const float ic = 1.f / (float)(chi - clo);
;             f32x4 u0, u1, z0, z1; unpack8(cen[cur][q], u0, u1); unpack8(zz[cur][q], z0, z1);
;             *(u32x4*)(branch + zoff + (size_t)(r * GW + q) * D) = pack8((s0 * ic - u0) * sc0 * z0, (s1 * ic - u1) * sc1 * z1); } }
.LBB0_735:
	s_or_b64 exec, exec, s[2:3]
	s_mov_b32 s0, 0x8000
	v_xor_b32_sdwa v28, s0, v91 dst_sel:WORD_1 dst_unused:UNUSED_PAD src0_sel:DWORD src1_sel:DWORD
	v_xor_b32_sdwa v29, s0, v91 dst_sel:WORD_1 dst_unused:UNUSED_PAD src0_sel:DWORD src1_sel:WORD_1
	v_mov_b32_e32 v30, v150
	v_mov_b32_e32 v31, v150
	v_pk_fma_f32 v[28:29], v[30:31], v[16:17], v[28:29]
	v_and_b32_e32 v23, 0xffff0000, v95
	v_lshlrev_b32_e32 v22, 16, v95
	v_pk_mul_f32 v[28:29], v[8:9], v[28:29]
	v_xor_b32_sdwa v32, s0, v90 dst_sel:WORD_1 dst_unused:UNUSED_PAD src0_sel:DWORD src1_sel:DWORD
	v_pk_mul_f32 v[22:23], v[22:23], v[28:29]
	v_xor_b32_sdwa v28, s0, v93 dst_sel:WORD_1 dst_unused:UNUSED_PAD src0_sel:DWORD src1_sel:DWORD
	v_xor_b32_sdwa v29, s0, v93 dst_sel:WORD_1 dst_unused:UNUSED_PAD src0_sel:DWORD src1_sel:WORD_1
	v_xor_b32_sdwa v33, s0, v90 dst_sel:WORD_1 dst_unused:UNUSED_PAD src0_sel:DWORD src1_sel:WORD_1
	v_pk_fma_f32 v[28:29], v[30:31], v[12:13], v[28:29]
	v_xor_b32_sdwa v30, s0, v92 dst_sel:WORD_1 dst_unused:UNUSED_PAD src0_sel:DWORD src1_sel:DWORD
	v_xor_b32_sdwa v31, s0, v92 dst_sel:WORD_1 dst_unused:UNUSED_PAD src0_sel:DWORD src1_sel:WORD_1
	v_pk_fma_f32 v[32:33], v[150:151], v[14:15], v[32:33]
	v_pk_fma_f32 v[30:31], v[150:151], v[10:11], v[30:31]
	v_and_b32_e32 v21, 0xffff0000, v94
	v_lshlrev_b32_e32 v20, 16, v94
	v_and_b32_e32 v25, 0xffff0000, v96
	v_lshlrev_b32_e32 v24, 16, v96
	v_pk_mul_f32 v[32:33], v[6:7], v[32:33]
	v_pk_mul_f32 v[30:31], v[2:3], v[30:31]
	v_and_b32_e32 v27, 0xffff0000, v97
	v_lshlrev_b32_e32 v26, 16, v97
	v_pk_mul_f32 v[20:21], v[20:21], v[32:33]
	v_pk_mul_f32 v[28:29], v[4:5], v[28:29]
	v_pk_mul_f32 v[24:25], v[24:25], v[30:31]
	v_pk_mul_f32 v[26:27], v[26:27], v[28:29]
	v_cvt_pk_bf16_f32 v20, v20, v21
	v_cvt_pk_bf16_f32 v21, v22, v23
	v_cvt_pk_bf16_f32 v22, v24, v25
	v_add_co_u32_e32 v24, vcc, 0x1000, v18
	v_cvt_pk_bf16_f32 v23, v26, v27
	s_nop 0
	v_addc_co_u32_e32 v25, vcc, 0, v19, vcc
	global_store_dwordx4 v[24:25], v[20:23], off sc0 sc1
	s_and_saveexec_b64 s[2:3], s[8:9]
	s_cbranch_execz .LBB0_737
	v_lshl_add_u32 v20, v159, 10, s25
	s_movk_i32 s0, 0xfc00
	v_add3_u32 v24, v20, v207, s0
	ds_read_b128 v[20:23], v24
	ds_read_b128 v[24:27], v24 offset:16
	s_waitcnt lgkmcnt(1)
	v_pk_add_f32 v[16:17], v[16:17], v[22:23]
	v_pk_add_f32 v[14:15], v[14:15], v[20:21]
	s_waitcnt lgkmcnt(0)
	v_pk_add_f32 v[12:13], v[12:13], v[26:27]
	v_pk_add_f32 v[10:11], v[10:11], v[24:25]

; #define LAS __attribute__((address_space(3)))
; __device__ __forceinline__ u32x4 pack8(const f32x4 v0, const f32x4 v1) { u32x4 w; w.x = pk_f16(v0[0], v0[1]); w.y = pk_f16(v0[2], v0[3]); w.z = pk_f16(v1[0], v1[1]); w.w = pk_f16(v1[2], v1[3]); return w; }
; __device__ __forceinline__ void unpack8(const u32x4 w, f32x4& v0, f32x4& v1) { v0 = (f32x4){f16lo(w.x), f16hi(w.x), f16lo(w.y), f16hi(w.y)}; v1 = (f32x4){f16lo(w.z), f16hi(w.z), f16lo(w.w), f16hi(w.w)}; }
; __device__ __forceinline__ void pm_item(LAS float* Vs0, int item, const f16* up, const f16* zs, const float* pscale, f16* branch) {
;     ...
;           for (int q = 0; q < 4; ++q) { const int cc = 4 * cs + q;
;             if (q > 0) { const int cin = cc + hi_off - 1, cout = cc - 1 - lo_off;
;                 if (cin < GW) { const LAS f32x4* vp = (const LAS f32x4*)(Vs + cin * 256 + o * 8); s0 += vp[0]; s1 += vp[1]; }
;                 if (cout >= 0) { const LAS f32x4* vp = (const LAS f32x4*)(Vs + cout * 256 + o * 8); s0 -= vp[0]; s1 -= vp[1]; } }
;             const int clo = cc - lo_off < 0 ? 0 : cc - lo_off, chi = cc + hi_off > GW ? GW : cc + hi_off;
;             const float ic = 1.f / (float)(chi - clo);
;             f32x4 u0, u1, z0, z1; unpack8(cen[cur][q], u0, u1); unpack8(zz[cur][q], z0, z1);
;             *(u32x4*)(branch + zoff + (size_t)(r * GW + q) * D) = pack8((s0 * ic - u0) * sc0 * z0, (s1 * ic - u1) * sc1 * z1); } }
.LBB0_739:
	s_or_b64 exec, exec, s[2:3]
	s_mov_b32 s0, 0x8000
	v_xor_b32_sdwa v28, s0, v75 dst_sel:WORD_1 dst_unused:UNUSED_PAD src0_sel:DWORD src1_sel:DWORD
	v_xor_b32_sdwa v29, s0, v75 dst_sel:WORD_1 dst_unused:UNUSED_PAD src0_sel:DWORD src1_sel:WORD_1
	v_mov_b32_e32 v30, v152
	v_mov_b32_e32 v31, v152
	v_pk_fma_f32 v[28:29], v[30:31], v[16:17], v[28:29]
	v_and_b32_e32 v23, 0xffff0000, v83
	v_lshlrev_b32_e32 v22, 16, v83
	v_pk_mul_f32 v[28:29], v[8:9], v[28:29]
	v_xor_b32_sdwa v32, s0, v74 dst_sel:WORD_1 dst_unused:UNUSED_PAD src0_sel:DWORD src1_sel:DWORD
	v_pk_mul_f32 v[22:23], v[22:23], v[28:29]
	v_xor_b32_sdwa v28, s0, v77 dst_sel:WORD_1 dst_unused:UNUSED_PAD src0_sel:DWORD src1_sel:DWORD
	v_xor_b32_sdwa v29, s0, v77 dst_sel:WORD_1 dst_unused:UNUSED_PAD src0_sel:DWORD src1_sel:WORD_1
	v_xor_b32_sdwa v33, s0, v74 dst_sel:WORD_1 dst_unused:UNUSED_PAD src0_sel:DWORD src1_sel:WORD_1
	v_pk_fma_f32 v[28:29], v[30:31], v[12:13], v[28:29]
	v_xor_b32_sdwa v30, s0, v76 dst_sel:WORD_1 dst_unused:UNUSED_PAD src0_sel:DWORD src1_sel:DWORD
	v_xor_b32_sdwa v31, s0, v76 dst_sel:WORD_1 dst_unused:UNUSED_PAD src0_sel:DWORD src1_sel:WORD_1
	v_pk_fma_f32 v[32:33], v[152:153], v[14:15], v[32:33]
	v_pk_fma_f32 v[30:31], v[152:153], v[10:11], v[30:31]
	v_and_b32_e32 v21, 0xffff0000, v82
	v_lshlrev_b32_e32 v20, 16, v82
	v_and_b32_e32 v25, 0xffff0000, v84
	v_lshlrev_b32_e32 v24, 16, v84
	v_pk_mul_f32 v[32:33], v[6:7], v[32:33]
	v_pk_mul_f32 v[30:31], v[2:3], v[30:31]
	v_and_b32_e32 v27, 0xffff0000, v85
	v_lshlrev_b32_e32 v26, 16, v85
	v_pk_mul_f32 v[20:21], v[20:21], v[32:33]
	v_pk_mul_f32 v[28:29], v[4:5], v[28:29]
	v_pk_mul_f32 v[24:25], v[24:25], v[30:31]
	v_pk_mul_f32 v[26:27], v[26:27], v[28:29]
	v_cvt_pk_bf16_f32 v20, v20, v21
	v_cvt_pk_bf16_f32 v21, v22, v23
	v_cvt_pk_bf16_f32 v22, v24, v25
	v_add_co_u32_e32 v24, vcc, 0x2000, v18
	v_cvt_pk_bf16_f32 v23, v26, v27
	s_nop 0
	v_addc_co_u32_e32 v25, vcc, 0, v19, vcc
	global_store_dwordx4 v[24:25], v[20:23], off sc0 sc1
	s_and_saveexec_b64 s[2:3], s[12:13]
	s_cbranch_execz .LBB0_741
	v_lshl_add_u32 v20, v160, 10, s25
	s_movk_i32 s0, 0xfc00
	v_add3_u32 v24, v20, v207, s0
	ds_read_b128 v[20:23], v24
	ds_read_b128 v[24:27], v24 offset:16
	s_waitcnt lgkmcnt(1)
	v_pk_add_f32 v[16:17], v[16:17], v[22:23]
	v_pk_add_f32 v[14:15], v[14:15], v[20:21]
	s_waitcnt lgkmcnt(0)
	v_pk_add_f32 v[12:13], v[12:13], v[26:27]
	v_pk_add_f32 v[10:11], v[10:11], v[24:25]

; #define LAS __attribute__((address_space(3)))
; __device__ __forceinline__ u32x4 pack8(const f32x4 v0, const f32x4 v1) { u32x4 w; w.x = pk_f16(v0[0], v0[1]); w.y = pk_f16(v0[2], v0[3]); w.z = pk_f16(v1[0], v1[1]); w.w = pk_f16(v1[2], v1[3]); return w; }
; __device__ __forceinline__ void unpack8(const u32x4 w, f32x4& v0, f32x4& v1) { v0 = (f32x4){f16lo(w.x), f16hi(w.x), f16lo(w.y), f16hi(w.y)}; v1 = (f32x4){f16lo(w.z), f16hi(w.z), f16lo(w.w), f16hi(w.w)}; }
; __device__ __forceinline__ unsigned xb_ld(unsigned* p)              { return __hip_atomic_load(p, __ATOMIC_RELAXED, __HIP_MEMORY_SCOPE_AGENT); }
; #define XB_SPIN(cond, bar) do { unsigned _sp = 0; while (cond) { __builtin_amdgcn_s_sleep(1); \
;     if ((++_sp & 255u) == 0u) { if (xb_ld(&(bar)[XB_TMO])) break; if (_sp > XB_SPIN_CAP) { atomicAdd(&(bar)[XB_TMO], 1u); break; } } } } while (0)
; __device__ __forceinline__ void pm_item(LAS float* Vs0, int item, const f16* up, const f16* zs, const float* pscale, f16* branch) {
;     ...
;           for (int q = 0; q < 4; ++q) { const int cc = 4 * cs + q;
;             if (q > 0) { const int cin = cc + hi_off - 1, cout = cc - 1 - lo_off;
;                 if (cin < GW) { const LAS f32x4* vp = (const LAS f32x4*)(Vs + cin * 256 + o * 8); s0 += vp[0]; s1 += vp[1]; }
;                 if (cout >= 0) { const LAS f32x4* vp = (const LAS f32x4*)(Vs + cout * 256 + o * 8); s0 -= vp[0]; s1 -= vp[1]; } }
;             const int clo = cc - lo_off < 0 ? 0 : cc - lo_off, chi = cc + hi_off > GW ? GW : cc + hi_off;
;             const float ic = 1.f / (float)(chi - clo);
;             f32x4 u0, u1, z0, z1; unpack8(cen[cur][q], u0, u1); unpack8(zz[cur][q], z0, z1);
;             *(u32x4*)(branch + zoff + (size_t)(r * GW + q) * D) = pack8((s0 * ic - u0) * sc0 * z0, (s1 * ic - u1) * sc1 * z1); } }
;     }
;     __syncthreads();
; __global__ void __launch_bounds__(NTHREADS, 2) mk_fwd(Args a) {
;     ...
;             if (tid == 0) { XB_SPIN(xb_ld(f1) == 0u, (ctl + CW_BAR)); __builtin_amdgcn_fence(__ATOMIC_ACQUIRE, "agent"); asm volatile("s_waitcnt vmcnt(0)" ::: "memory"); }
.LBB0_743:
	s_or_b64 exec, exec, s[2:3]
	s_mov_b32 s0, 0x8000
	v_xor_b32_sdwa v28, s0, v63 dst_sel:WORD_1 dst_unused:UNUSED_PAD src0_sel:DWORD src1_sel:DWORD
	v_xor_b32_sdwa v29, s0, v63 dst_sel:WORD_1 dst_unused:UNUSED_PAD src0_sel:DWORD src1_sel:WORD_1
	v_mov_b32_e32 v30, v154
	v_mov_b32_e32 v31, v154
	v_pk_fma_f32 v[16:17], v[30:31], v[16:17], v[28:29]
	v_xor_b32_sdwa v28, s0, v62 dst_sel:WORD_1 dst_unused:UNUSED_PAD src0_sel:DWORD src1_sel:DWORD
	v_xor_b32_sdwa v29, s0, v62 dst_sel:WORD_1 dst_unused:UNUSED_PAD src0_sel:DWORD src1_sel:WORD_1
	v_and_b32_e32 v21, 0xffff0000, v70
	v_pk_fma_f32 v[14:15], v[154:155], v[14:15], v[28:29]
	v_lshlrev_b32_e32 v20, 16, v70
	v_pk_mul_f32 v[6:7], v[6:7], v[14:15]
	v_xor_b32_sdwa v14, s0, v65 dst_sel:WORD_1 dst_unused:UNUSED_PAD src0_sel:DWORD src1_sel:DWORD
	v_xor_b32_sdwa v15, s0, v65 dst_sel:WORD_1 dst_unused:UNUSED_PAD src0_sel:DWORD src1_sel:WORD_1
	v_and_b32_e32 v23, 0xffff0000, v71
	v_pk_fma_f32 v[12:13], v[30:31], v[12:13], v[14:15]
	v_xor_b32_sdwa v14, s0, v64 dst_sel:WORD_1 dst_unused:UNUSED_PAD src0_sel:DWORD src1_sel:DWORD
	v_xor_b32_sdwa v15, s0, v64 dst_sel:WORD_1 dst_unused:UNUSED_PAD src0_sel:DWORD src1_sel:WORD_1
	v_lshlrev_b32_e32 v22, 16, v71
	v_pk_fma_f32 v[10:11], v[154:155], v[10:11], v[14:15]
	v_and_b32_e32 v25, 0xffff0000, v72
	v_lshlrev_b32_e32 v24, 16, v72
	v_and_b32_e32 v27, 0xffff0000, v73
	v_lshlrev_b32_e32 v26, 16, v73
	v_pk_mul_f32 v[8:9], v[8:9], v[16:17]
	v_pk_mul_f32 v[6:7], v[20:21], v[6:7]
	v_pk_mul_f32 v[2:3], v[2:3], v[10:11]
	v_pk_mul_f32 v[4:5], v[4:5], v[12:13]
	v_pk_mul_f32 v[8:9], v[22:23], v[8:9]
	v_pk_mul_f32 v[10:11], v[26:27], v[4:5]
	v_pk_mul_f32 v[4:5], v[24:25], v[2:3]
	v_cvt_pk_bf16_f32 v2, v6, v7
	v_add_co_u32_e32 v6, vcc, 0x3000, v18
	v_cvt_pk_bf16_f32 v3, v8, v9
	v_cvt_pk_bf16_f32 v4, v4, v5
	v_cvt_pk_bf16_f32 v5, v10, v11
	v_addc_co_u32_e32 v7, vcc, 0, v19, vcc
	global_store_dwordx4 v[6:7], v[2:5], off sc0 sc1
	s_barrier
	s_and_saveexec_b64 s[2:3], s[82:83]
	s_cbranch_execz .LBB0_758
	v_mov_b32_e32 v2, 0
	global_load_dword v3, v2, s[26:27] sc1
	s_waitcnt vmcnt(0)
	v_cmp_ne_u32_e32 vcc, 0, v3
	s_cbranch_vccnz .LBB0_757
	s_mov_b32 s0, 1
	s_branch .LBB0_747

; __device__ __forceinline__ void st_wt_x4(void* p, f32x4 v) { asm volatile("global_store_dwordx4 %0, %1, off sc0 sc1" :: "v"(p), "v"(v) : "memory"); }
;     __device__ __forceinline__ void operator()(AccRef acc, const Unit& u, int wr, int wc, int fr, int fq) const {
;         int row0 = u.pm * 256 + wr * 64 + fr; asm volatile("" : "+v"(row0)); int col0 = wc * 32 + 4 * fq; asm volatile("" : "+v"(col0));
; #pragma unroll
;         for (int ai = 0; ai < 2; ++ai)
; #pragma unroll
;             for (int m = 0; m < 4; ++m) { const int row = row0 + ai * HALF + m * 16;
;                 if (row < NCH) { float* rp = S + ((size_t)u.g * NCH + row) * 256 + col0;
; #pragma unroll
;                     for (int bj = 0; bj < 2; ++bj)
; #pragma unroll
;                         for (int n = 0; n < 2; ++n) { if (bj == 0) *(f32x4*)(rp + n * 16) = acc[ai][0][m][n]; else st_wt_x4(rp + HALF + n * 16, acc[ai][1][m][n]); } } }
;     }
.LBB0_867:
	v_lshl_add_u32 v140, s89, 8, v149
	v_mov_b32_e32 v138, v151
	s_movk_i32 s18, 0x210
	s_mul_hi_i32 s21, s64, 0x210
	s_mul_i32 s20, s64, 0x210
	v_ashrrev_i32_e32 v139, 31, v138
	v_cmp_gt_i32_e32 vcc, s18, v140
	s_and_saveexec_b64 s[64:65], vcc
	s_cbranch_execz .LBB0_869
	v_ashrrev_i32_e32 v141, 31, v140
	v_lshl_add_u64 v[156:157], s[20:21], 0, v[140:141]
	v_lshlrev_b64 v[156:157], 10, v[156:157]
	v_lshl_add_u64 v[156:157], s[10:11], 0, v[156:157]
	v_lshl_add_u64 v[156:157], v[138:139], 2, v[156:157]
	global_store_dwordx4 v[156:157], v[126:129], off sc0 sc1
	global_store_dwordx4 v[156:157], v[122:125], off offset:64 sc0 sc1
	v_lshl_add_u64 v[160:161], v[156:157], 0, s[68:69]
	global_store_dwordx4 v[160:161], v[114:117], off sc0 sc1
	v_lshl_add_u64 v[158:159], v[156:157], 0, s[66:67]
	global_store_dwordx4 v[158:159], v[106:109], off sc0 sc1
.LBB0_869:
	s_or_b64 exec, exec, s[64:65]
	s_movk_i32 s18, 0x200
	v_cmp_gt_i32_e32 vcc, s18, v140
	s_and_saveexec_b64 s[64:65], vcc
	s_cbranch_execz .LBB0_871
	v_add_u32_e32 v106, 16, v140
	v_ashrrev_i32_e32 v107, 31, v106
	v_lshl_add_u64 v[106:107], s[20:21], 0, v[106:107]
	v_lshlrev_b64 v[106:107], 10, v[106:107]
	v_lshl_add_u64 v[106:107], s[10:11], 0, v[106:107]
	v_lshl_add_u64 v[106:107], v[138:139], 2, v[106:107]
	global_store_dwordx4 v[106:107], v[118:121], off sc0 sc1
	global_store_dwordx4 v[106:107], v[110:113], off offset:64 sc0 sc1
	v_lshl_add_u64 v[114:115], v[106:107], 0, s[68:69]
	global_store_dwordx4 v[114:115], v[98:101], off sc0 sc1
	v_lshl_add_u64 v[108:109], v[106:107], 0, s[66:67]
	global_store_dwordx4 v[108:109], v[90:93], off sc0 sc1
.LBB0_871:
	s_or_b64 exec, exec, s[64:65]
	s_movk_i32 s18, 0x1f0
	v_cmp_gt_i32_e32 vcc, s18, v140
	s_and_saveexec_b64 s[64:65], vcc
	s_cbranch_execz .LBB0_873
	v_add_u32_e32 v90, 32, v140
	v_ashrrev_i32_e32 v91, 31, v90
	v_lshl_add_u64 v[90:91], s[20:21], 0, v[90:91]
	v_lshlrev_b64 v[90:91], 10, v[90:91]
	v_lshl_add_u64 v[90:91], s[10:11], 0, v[90:91]
	v_lshl_add_u64 v[90:91], v[138:139], 2, v[90:91]
	global_store_dwordx4 v[90:91], v[102:105], off sc0 sc1
	global_store_dwordx4 v[90:91], v[94:97], off offset:64 sc0 sc1
	v_lshl_add_u64 v[98:99], v[90:91], 0, s[68:69]
	global_store_dwordx4 v[98:99], v[82:85], off sc0 sc1
	v_lshl_add_u64 v[92:93], v[90:91], 0, s[66:67]
	global_store_dwordx4 v[92:93], v[74:77], off sc0 sc1
.LBB0_873:
	s_or_b64 exec, exec, s[64:65]
	s_movk_i32 s18, 0x1e0
	v_cmp_gt_i32_e32 vcc, s18, v140
	s_and_saveexec_b64 s[64:65], vcc
	s_cbranch_execz .LBB0_875
	v_add_u32_e32 v74, 48, v140
	v_ashrrev_i32_e32 v75, 31, v74
	v_lshl_add_u64 v[74:75], s[20:21], 0, v[74:75]
	v_lshlrev_b64 v[74:75], 10, v[74:75]
	v_lshl_add_u64 v[74:75], s[10:11], 0, v[74:75]
	v_lshl_add_u64 v[74:75], v[138:139], 2, v[74:75]
	global_store_dwordx4 v[74:75], v[86:89], off sc0 sc1
	global_store_dwordx4 v[74:75], v[78:81], off offset:64 sc0 sc1
	v_lshl_add_u64 v[82:83], v[74:75], 0, s[68:69]
	global_store_dwordx4 v[82:83], v[70:73], off sc0 sc1
	v_lshl_add_u64 v[76:77], v[74:75], 0, s[66:67]
	global_store_dwordx4 v[76:77], v[66:69], off sc0 sc1
.LBB0_875:
	s_or_b64 exec, exec, s[64:65]
	s_movk_i32 s18, 0x190
	v_cmp_gt_i32_e32 vcc, s18, v140
	s_and_saveexec_b64 s[64:65], vcc
	s_cbranch_execz .LBB0_877
	v_add_u32_e32 v66, 0x80, v140
	v_ashrrev_i32_e32 v67, 31, v66
	v_lshl_add_u64 v[66:67], s[20:21], 0, v[66:67]
	v_lshlrev_b64 v[66:67], 10, v[66:67]
	v_lshl_add_u64 v[66:67], s[10:11], 0, v[66:67]
	v_lshl_add_u64 v[66:67], v[138:139], 2, v[66:67]
	global_store_dwordx4 v[66:67], v[62:65], off sc0 sc1
	global_store_dwordx4 v[66:67], v[58:61], off offset:64 sc0 sc1
	v_lshl_add_u64 v[70:71], v[66:67], 0, s[68:69]
	global_store_dwordx4 v[70:71], v[50:53], off sc0 sc1
	v_lshl_add_u64 v[68:69], v[66:67], 0, s[66:67]
	global_store_dwordx4 v[68:69], v[42:45], off sc0 sc1
.LBB0_877:
	s_or_b64 exec, exec, s[64:65]
	s_movk_i32 s18, 0x180
	v_cmp_gt_i32_e32 vcc, s18, v140
	s_and_saveexec_b64 s[64:65], vcc
	s_cbranch_execz .LBB0_879
	v_add_u32_e32 v42, 0x90, v140
	v_ashrrev_i32_e32 v43, 31, v42
	v_lshl_add_u64 v[42:43], s[20:21], 0, v[42:43]
	v_lshlrev_b64 v[42:43], 10, v[42:43]
	v_lshl_add_u64 v[42:43], s[10:11], 0, v[42:43]
	v_lshl_add_u64 v[42:43], v[138:139], 2, v[42:43]
	global_store_dwordx4 v[42:43], v[54:57], off sc0 sc1
	global_store_dwordx4 v[42:43], v[46:49], off offset:64 sc0 sc1
	v_lshl_add_u64 v[50:51], v[42:43], 0, s[68:69]
	global_store_dwordx4 v[50:51], v[34:37], off sc0 sc1
	v_lshl_add_u64 v[44:45], v[42:43], 0, s[66:67]
	global_store_dwordx4 v[44:45], v[26:29], off sc0 sc1
.LBB0_879:
	s_or_b64 exec, exec, s[64:65]
	s_movk_i32 s18, 0x170
	v_cmp_gt_i32_e32 vcc, s18, v140
	s_and_saveexec_b64 s[64:65], vcc
	s_cbranch_execz .LBB0_881
	v_add_u32_e32 v26, 0xa0, v140
	v_ashrrev_i32_e32 v27, 31, v26
	v_lshl_add_u64 v[26:27], s[20:21], 0, v[26:27]
	v_lshlrev_b64 v[26:27], 10, v[26:27]
	v_lshl_add_u64 v[26:27], s[10:11], 0, v[26:27]
	v_lshl_add_u64 v[26:27], v[138:139], 2, v[26:27]
	global_store_dwordx4 v[26:27], v[38:41], off sc0 sc1
	global_store_dwordx4 v[26:27], v[30:33], off offset:64 sc0 sc1
	v_lshl_add_u64 v[34:35], v[26:27], 0, s[68:69]
	global_store_dwordx4 v[34:35], v[18:21], off sc0 sc1
	v_lshl_add_u64 v[28:29], v[26:27], 0, s[66:67]
	global_store_dwordx4 v[28:29], v[10:13], off sc0 sc1
.LBB0_881:
	s_or_b64 exec, exec, s[64:65]
	s_movk_i32 s18, 0x160
	v_cmp_gt_i32_e32 vcc, s18, v140
	s_and_saveexec_b64 s[64:65], vcc
	s_cbranch_execz .LBB0_883
	v_add_u32_e32 v10, 0xb0, v140
	v_ashrrev_i32_e32 v11, 31, v10
	v_lshl_add_u64 v[10:11], s[20:21], 0, v[10:11]
	v_lshlrev_b64 v[10:11], 10, v[10:11]
	v_lshl_add_u64 v[10:11], s[10:11], 0, v[10:11]
	v_lshl_add_u64 v[10:11], v[138:139], 2, v[10:11]
	global_store_dwordx4 v[10:11], v[22:25], off sc0 sc1
	global_store_dwordx4 v[10:11], v[14:17], off offset:64 sc0 sc1
	v_lshl_add_u64 v[18:19], v[10:11], 0, s[68:69]
	global_store_dwordx4 v[18:19], v[6:9], off sc0 sc1
	v_lshl_add_u64 v[12:13], v[10:11], 0, s[66:67]
	global_store_dwordx4 v[12:13], v[2:5], off sc0 sc1

; __device__ __forceinline__ float silu_f(float v) { return v * fast_sigmoid(v); }
; __device__ __forceinline__ u32x4 pack8(const f32x4 v0, const f32x4 v1) { u32x4 w; w.x = pk_f16(v0[0], v0[1]); w.y = pk_f16(v0[2], v0[3]); w.z = pk_f16(v1[0], v1[1]); w.w = pk_f16(v1[2], v1[3]); return w; }
;     __device__ __forceinline__ void operator()(AccRef acc, const Unit& u, int wr, int wc, int fr, int fq) const {
;     ...
;                     else {
; #pragma unroll
;                         for (int j = 0; j < 4; ++j) { v0[j] = silu_f(v0[j]); v1[j] = silu_f(v1[j]); }
;                         *(u32x4*)(zs + (size_t)row * D + (col - PW - SW)) = pack8(v0, v1); } } }
.LBB0_972:
	v_lshl_add_u32 v132, s30, 8, v131
	v_lshl_or_b32 v131, s29, 8, v215
	v_or_b32_e32 v134, s61, v131
	v_mul_f32_e32 v131, 0xbfb8aa3b, v126
	v_mul_f32_e32 v135, 0xbfb8aa3b, v122
	v_mul_f32_e32 v136, 0xbfb8aa3b, v127
	v_exp_f32_e32 v131, v131
	v_exp_f32_e32 v135, v135
	v_exp_f32_e32 v136, v136
	v_mul_f32_e32 v137, 0xbfb8aa3b, v123
	v_add_f32_e32 v131, 1.0, v131
	v_add_f32_e32 v135, 1.0, v135
	v_add_f32_e32 v136, 1.0, v136
	v_rcp_f32_e32 v131, v131
	v_rcp_f32_e32 v135, v135
	v_rcp_f32_e32 v136, v136
	v_exp_f32_e32 v137, v137
	v_mul_f32_e32 v126, v126, v131
	v_mul_f32_e32 v122, v122, v135
	v_mul_f32_e32 v127, v127, v136
	v_add_f32_e32 v131, 1.0, v137
	v_mul_f32_e32 v135, 0xbfb8aa3b, v128
	v_mul_f32_e32 v136, 0xbfb8aa3b, v124
	v_rcp_f32_e32 v131, v131
	v_exp_f32_e32 v135, v135
	v_exp_f32_e32 v136, v136
	v_mul_f32_e32 v137, 0xbfb8aa3b, v125
	v_mul_f32_e32 v123, v123, v131
	v_add_f32_e32 v131, 1.0, v135
	v_add_f32_e32 v135, 1.0, v136
	v_mul_f32_e32 v136, 0xbfb8aa3b, v129
	v_exp_f32_e32 v137, v137
	v_exp_f32_e32 v136, v136
	v_rcp_f32_e32 v131, v131
	v_rcp_f32_e32 v135, v135
	v_add_f32_e32 v137, 1.0, v137
	v_add_f32_e32 v136, 1.0, v136
	v_rcp_f32_e32 v137, v137
	v_rcp_f32_e32 v136, v136
	v_mul_f32_e32 v128, v128, v131
	v_ashrrev_i32_e32 v133, 31, v132
	v_lshlrev_b64 v[132:133], 12, v[132:133]
	v_mul_f32_e32 v131, v124, v135
	v_mul_f32_e32 v135, v125, v137
	v_mul_f32_e32 v129, v129, v136
	v_cvt_pk_bf16_f32 v124, v126, v127
	v_cvt_pk_bf16_f32 v126, v122, v123
	v_cvt_pk_bf16_f32 v127, v131, v135
	v_lshl_add_u64 v[122:123], s[92:93], 0, v[132:133]
	v_ashrrev_i32_e32 v135, 31, v134
	v_cvt_pk_bf16_f32 v125, v128, v129
	v_lshl_add_u64 v[122:123], v[134:135], 1, v[122:123]
	v_mul_f32_e32 v128, 0xbfb8aa3b, v118
	global_store_dwordx4 v[122:123], v[124:127], off offset:-4096 sc0 sc1
	v_exp_f32_e32 v128, v128
	s_mov_b64 s[0:1], 0x10000
	v_mul_f32_e32 v125, 0xbfb8aa3b, v114
	v_mul_f32_e32 v126, 0xbfb8aa3b, v119
	v_exp_f32_e32 v125, v125
	v_exp_f32_e32 v126, v126
	v_add_f32_e32 v124, 1.0, v128
	v_mul_f32_e32 v127, 0xbfb8aa3b, v115
	v_add_f32_e32 v125, 1.0, v125
	v_add_f32_e32 v126, 1.0, v126
	v_rcp_f32_e32 v124, v124
	v_rcp_f32_e32 v125, v125
	v_rcp_f32_e32 v126, v126
	v_exp_f32_e32 v127, v127
	v_mul_f32_e32 v118, v118, v124
	v_mul_f32_e32 v124, v114, v125
	v_mul_f32_e32 v114, v119, v126
	v_add_f32_e32 v119, 1.0, v127
	v_mul_f32_e32 v125, 0xbfb8aa3b, v120
	v_mul_f32_e32 v126, 0xbfb8aa3b, v116
	v_rcp_f32_e32 v119, v119
	v_exp_f32_e32 v125, v125
	v_exp_f32_e32 v126, v126
	v_mul_f32_e32 v127, 0xbfb8aa3b, v117
	v_mul_f32_e32 v119, v115, v119
	v_add_f32_e32 v115, 1.0, v125
	v_add_f32_e32 v125, 1.0, v126
	v_mul_f32_e32 v126, 0xbfb8aa3b, v121
	v_exp_f32_e32 v126, v126
	v_exp_f32_e32 v127, v127
	v_rcp_f32_e32 v115, v115
	v_rcp_f32_e32 v125, v125
	v_add_f32_e32 v126, 1.0, v126
	v_rcp_f32_e32 v126, v126
	v_add_f32_e32 v127, 1.0, v127
	v_rcp_f32_e32 v127, v127
	v_mul_f32_e32 v115, v120, v115
	v_mul_f32_e32 v120, v116, v125
	v_mul_f32_e32 v116, v121, v126
	v_mul_f32_e32 v117, v117, v127
	v_cvt_pk_bf16_f32 v115, v115, v116
	v_mul_f32_e32 v116, 0xbfb8aa3b, v110
	v_cvt_pk_bf16_f32 v114, v118, v114
	v_exp_f32_e32 v118, v116
	v_cvt_pk_bf16_f32 v116, v124, v119
	v_cvt_pk_bf16_f32 v117, v120, v117
	global_store_dwordx4 v[122:123], v[114:117], off offset:-3840 sc0 sc1
	s_nop 1
	v_mul_f32_e32 v115, 0xbfb8aa3b, v106
	v_mul_f32_e32 v116, 0xbfb8aa3b, v111
	v_exp_f32_e32 v115, v115
	v_exp_f32_e32 v116, v116
	v_add_f32_e32 v114, 1.0, v118
	v_mul_f32_e32 v117, 0xbfb8aa3b, v107
	v_add_f32_e32 v115, 1.0, v115
	v_add_f32_e32 v116, 1.0, v116
	v_rcp_f32_e32 v114, v114
	v_rcp_f32_e32 v115, v115
	v_rcp_f32_e32 v116, v116
	v_exp_f32_e32 v117, v117
	v_mul_f32_e32 v110, v110, v114
	v_mul_f32_e32 v114, v106, v115
	v_mul_f32_e32 v106, v111, v116
	v_add_f32_e32 v111, 1.0, v117
	v_mul_f32_e32 v115, 0xbfb8aa3b, v112
	v_mul_f32_e32 v116, 0xbfb8aa3b, v108
	v_rcp_f32_e32 v111, v111
	v_exp_f32_e32 v115, v115
	v_exp_f32_e32 v116, v116
	v_mul_f32_e32 v117, 0xbfb8aa3b, v109
	v_mul_f32_e32 v111, v107, v111
	v_add_f32_e32 v107, 1.0, v115
	v_add_f32_e32 v115, 1.0, v116
	v_mul_f32_e32 v116, 0xbfb8aa3b, v113
	v_exp_f32_e32 v116, v116
	v_exp_f32_e32 v117, v117
	v_rcp_f32_e32 v107, v107
	v_rcp_f32_e32 v115, v115
	v_add_f32_e32 v116, 1.0, v116
	v_add_f32_e32 v117, 1.0, v117
	v_rcp_f32_e32 v116, v116
	v_rcp_f32_e32 v117, v117
	v_mul_f32_e32 v107, v112, v107
	v_mul_f32_e32 v112, v108, v115
	v_mul_f32_e32 v108, v113, v116
	v_mul_f32_e32 v109, v109, v117
	v_cvt_pk_bf16_f32 v106, v110, v106
	v_mul_f32_e32 v110, 0xbfb8aa3b, v102
	v_cvt_pk_bf16_f32 v107, v107, v108
	v_cvt_pk_bf16_f32 v108, v114, v111
	v_cvt_pk_bf16_f32 v109, v112, v109
	v_exp_f32_e32 v112, v110
	v_lshl_add_u64 v[110:111], v[122:123], 0, s[0:1]
	global_store_dwordx4 v[110:111], v[106:109], off offset:-4096 sc0 sc1
	s_mov_b64 s[0:1], 0x20000
	s_nop 0
	v_mul_f32_e32 v107, 0xbfb8aa3b, v98
	v_mul_f32_e32 v108, 0xbfb8aa3b, v103
	v_exp_f32_e32 v107, v107
	v_exp_f32_e32 v108, v108
	v_add_f32_e32 v106, 1.0, v112
	v_mul_f32_e32 v109, 0xbfb8aa3b, v99
	v_add_f32_e32 v107, 1.0, v107
	v_add_f32_e32 v108, 1.0, v108
	v_rcp_f32_e32 v106, v106
	v_rcp_f32_e32 v107, v107
	v_rcp_f32_e32 v108, v108
	v_exp_f32_e32 v109, v109
	v_mul_f32_e32 v102, v102, v106
	v_mul_f32_e32 v106, v98, v107
	v_mul_f32_e32 v98, v103, v108
	v_add_f32_e32 v103, 1.0, v109
	v_mul_f32_e32 v107, 0xbfb8aa3b, v104
	v_mul_f32_e32 v108, 0xbfb8aa3b, v100
	v_rcp_f32_e32 v103, v103
	v_exp_f32_e32 v107, v107
	v_exp_f32_e32 v108, v108
	v_mul_f32_e32 v109, 0xbfb8aa3b, v101
	v_mul_f32_e32 v103, v99, v103
	v_add_f32_e32 v99, 1.0, v107
	v_add_f32_e32 v107, 1.0, v108
	v_mul_f32_e32 v108, 0xbfb8aa3b, v105
; __device__ __forceinline__ float silu_f(float v) { return v * fast_sigmoid(v); }
; __device__ __forceinline__ u32x4 pack8(const f32x4 v0, const f32x4 v1) { u32x4 w; w.x = pk_f16(v0[0], v0[1]); w.y = pk_f16(v0[2], v0[3]); w.z = pk_f16(v1[0], v1[1]); w.w = pk_f16(v1[2], v1[3]); return w; }
;     __device__ __forceinline__ void operator()(AccRef acc, const Unit& u, int wr, int wc, int fr, int fq) const {
;     ...
;                     else {
; #pragma unroll
;                         for (int j = 0; j < 4; ++j) { v0[j] = silu_f(v0[j]); v1[j] = silu_f(v1[j]); }
;                         *(u32x4*)(zs + (size_t)row * D + (col - PW - SW)) = pack8(v0, v1); } } }
	v_exp_f32_e32 v108, v108
	v_exp_f32_e32 v109, v109
	v_rcp_f32_e32 v99, v99
	v_rcp_f32_e32 v107, v107
	v_add_f32_e32 v108, 1.0, v108
	v_rcp_f32_e32 v108, v108
	v_add_f32_e32 v109, 1.0, v109
	v_rcp_f32_e32 v109, v109
	v_mul_f32_e32 v99, v104, v99
	v_mul_f32_e32 v104, v100, v107
	v_mul_f32_e32 v100, v105, v108
	v_mul_f32_e32 v101, v101, v109
	v_cvt_pk_bf16_f32 v99, v99, v100
	v_mul_f32_e32 v100, 0xbfb8aa3b, v94
	v_cvt_pk_bf16_f32 v98, v102, v98
	v_exp_f32_e32 v102, v100
	v_cvt_pk_bf16_f32 v100, v106, v103
	v_cvt_pk_bf16_f32 v101, v104, v101
	global_store_dwordx4 v[110:111], v[98:101], off offset:-3840 sc0 sc1
	s_nop 1
	v_mul_f32_e32 v99, 0xbfb8aa3b, v90
	v_mul_f32_e32 v100, 0xbfb8aa3b, v95
	v_exp_f32_e32 v99, v99
	v_exp_f32_e32 v100, v100
	v_add_f32_e32 v98, 1.0, v102
	v_mul_f32_e32 v101, 0xbfb8aa3b, v91
	v_add_f32_e32 v99, 1.0, v99
	v_add_f32_e32 v100, 1.0, v100
	v_rcp_f32_e32 v98, v98
	v_rcp_f32_e32 v99, v99
	v_rcp_f32_e32 v100, v100
	v_exp_f32_e32 v101, v101
	v_mul_f32_e32 v94, v94, v98
	v_mul_f32_e32 v98, v90, v99
	v_mul_f32_e32 v90, v95, v100
	v_add_f32_e32 v95, 1.0, v101
	v_mul_f32_e32 v99, 0xbfb8aa3b, v96
	v_mul_f32_e32 v100, 0xbfb8aa3b, v92
	v_rcp_f32_e32 v95, v95
	v_exp_f32_e32 v99, v99
	v_exp_f32_e32 v100, v100
	v_mul_f32_e32 v101, 0xbfb8aa3b, v93
	v_mul_f32_e32 v95, v91, v95
	v_add_f32_e32 v91, 1.0, v99
	v_add_f32_e32 v99, 1.0, v100
	v_mul_f32_e32 v100, 0xbfb8aa3b, v97
	v_exp_f32_e32 v100, v100
	v_exp_f32_e32 v101, v101
	v_rcp_f32_e32 v91, v91
	v_rcp_f32_e32 v99, v99
	v_add_f32_e32 v100, 1.0, v100
	v_add_f32_e32 v101, 1.0, v101
	v_rcp_f32_e32 v100, v100
	v_rcp_f32_e32 v101, v101
	v_mul_f32_e32 v91, v96, v91
	v_mul_f32_e32 v96, v92, v99
	v_mul_f32_e32 v92, v97, v100
	v_mul_f32_e32 v93, v93, v101
	v_cvt_pk_bf16_f32 v90, v94, v90
	v_mul_f32_e32 v94, 0xbfb8aa3b, v86
	v_cvt_pk_bf16_f32 v91, v91, v92
	v_cvt_pk_bf16_f32 v92, v98, v95
	v_cvt_pk_bf16_f32 v93, v96, v93
	v_exp_f32_e32 v96, v94
	v_lshl_add_u64 v[94:95], v[122:123], 0, s[0:1]
	global_store_dwordx4 v[94:95], v[90:93], off offset:-4096 sc0 sc1
	s_mov_b64 s[0:1], 0x30000
	s_nop 0
	v_mul_f32_e32 v91, 0xbfb8aa3b, v82
	v_mul_f32_e32 v92, 0xbfb8aa3b, v87
	v_exp_f32_e32 v91, v91
	v_exp_f32_e32 v92, v92
	v_add_f32_e32 v90, 1.0, v96
	v_mul_f32_e32 v93, 0xbfb8aa3b, v83
	v_add_f32_e32 v91, 1.0, v91
	v_add_f32_e32 v92, 1.0, v92
	v_rcp_f32_e32 v90, v90
	v_rcp_f32_e32 v91, v91
	v_rcp_f32_e32 v92, v92
	v_exp_f32_e32 v93, v93
	v_mul_f32_e32 v86, v86, v90
	v_mul_f32_e32 v90, v82, v91
	v_mul_f32_e32 v82, v87, v92
	v_add_f32_e32 v87, 1.0, v93
	v_mul_f32_e32 v91, 0xbfb8aa3b, v88
	v_mul_f32_e32 v92, 0xbfb8aa3b, v84
	v_rcp_f32_e32 v87, v87
	v_exp_f32_e32 v91, v91
	v_exp_f32_e32 v92, v92
	v_mul_f32_e32 v93, 0xbfb8aa3b, v85
	v_mul_f32_e32 v87, v83, v87
	v_add_f32_e32 v83, 1.0, v91
	v_add_f32_e32 v91, 1.0, v92
	v_mul_f32_e32 v92, 0xbfb8aa3b, v89
	v_exp_f32_e32 v92, v92
	v_exp_f32_e32 v93, v93
	v_rcp_f32_e32 v83, v83
	v_rcp_f32_e32 v91, v91
	v_add_f32_e32 v92, 1.0, v92
	v_rcp_f32_e32 v92, v92
	v_add_f32_e32 v93, 1.0, v93
	v_rcp_f32_e32 v93, v93
	v_mul_f32_e32 v83, v88, v83
	v_mul_f32_e32 v88, v84, v91
	v_mul_f32_e32 v84, v89, v92
	v_mul_f32_e32 v85, v85, v93
	v_cvt_pk_bf16_f32 v83, v83, v84
	v_mul_f32_e32 v84, 0xbfb8aa3b, v78
	v_cvt_pk_bf16_f32 v82, v86, v82
	v_exp_f32_e32 v86, v84
	v_cvt_pk_bf16_f32 v84, v90, v87
	v_cvt_pk_bf16_f32 v85, v88, v85
	global_store_dwordx4 v[94:95], v[82:85], off offset:-3840 sc0 sc1
	s_nop 1
	v_mul_f32_e32 v83, 0xbfb8aa3b, v74
	v_mul_f32_e32 v84, 0xbfb8aa3b, v79
	v_exp_f32_e32 v83, v83
	v_exp_f32_e32 v84, v84
	v_add_f32_e32 v82, 1.0, v86
	v_mul_f32_e32 v85, 0xbfb8aa3b, v75
	v_add_f32_e32 v83, 1.0, v83
	v_add_f32_e32 v84, 1.0, v84
	v_rcp_f32_e32 v82, v82
	v_rcp_f32_e32 v83, v83
	v_rcp_f32_e32 v84, v84
	v_exp_f32_e32 v85, v85
	v_mul_f32_e32 v78, v78, v82
	v_mul_f32_e32 v82, v74, v83
	v_mul_f32_e32 v74, v79, v84
	v_add_f32_e32 v79, 1.0, v85
	v_mul_f32_e32 v83, 0xbfb8aa3b, v80
	v_mul_f32_e32 v84, 0xbfb8aa3b, v76
	v_rcp_f32_e32 v79, v79
	v_exp_f32_e32 v83, v83
	v_exp_f32_e32 v84, v84
	v_mul_f32_e32 v85, 0xbfb8aa3b, v77
	v_mul_f32_e32 v79, v75, v79
	v_add_f32_e32 v75, 1.0, v83
	v_add_f32_e32 v83, 1.0, v84
	v_mul_f32_e32 v84, 0xbfb8aa3b, v81
	v_exp_f32_e32 v84, v84
	v_exp_f32_e32 v85, v85
	v_rcp_f32_e32 v75, v75
	v_rcp_f32_e32 v83, v83
	v_add_f32_e32 v84, 1.0, v84
	v_add_f32_e32 v85, 1.0, v85
	v_rcp_f32_e32 v84, v84
	v_rcp_f32_e32 v85, v85
	v_mul_f32_e32 v75, v80, v75
	v_mul_f32_e32 v80, v76, v83
	v_mul_f32_e32 v76, v81, v84
	v_mul_f32_e32 v77, v77, v85
	v_cvt_pk_bf16_f32 v74, v78, v74
	v_mul_f32_e32 v78, 0xbfb8aa3b, v70
	v_cvt_pk_bf16_f32 v75, v75, v76
	v_cvt_pk_bf16_f32 v76, v82, v79
	v_cvt_pk_bf16_f32 v77, v80, v77
	v_exp_f32_e32 v80, v78
	v_lshl_add_u64 v[78:79], v[122:123], 0, s[0:1]
	global_store_dwordx4 v[78:79], v[74:77], off offset:-4096 sc0 sc1
	s_mov_b64 s[0:1], 0x80000
	s_nop 0
	v_mul_f32_e32 v75, 0xbfb8aa3b, v66
	v_mul_f32_e32 v76, 0xbfb8aa3b, v71
	v_exp_f32_e32 v75, v75
	v_exp_f32_e32 v76, v76
	v_add_f32_e32 v74, 1.0, v80
	v_mul_f32_e32 v77, 0xbfb8aa3b, v67
	v_add_f32_e32 v75, 1.0, v75
	v_add_f32_e32 v76, 1.0, v76
	v_rcp_f32_e32 v74, v74
	v_rcp_f32_e32 v75, v75
	v_rcp_f32_e32 v76, v76
	v_exp_f32_e32 v77, v77
	v_mul_f32_e32 v70, v70, v74
	v_mul_f32_e32 v74, v66, v75
	v_mul_f32_e32 v66, v71, v76
	v_add_f32_e32 v71, 1.0, v77
	v_mul_f32_e32 v75, 0xbfb8aa3b, v72
	v_mul_f32_e32 v76, 0xbfb8aa3b, v68
	v_rcp_f32_e32 v71, v71
	v_exp_f32_e32 v75, v75
	v_exp_f32_e32 v76, v76
	v_mul_f32_e32 v77, 0xbfb8aa3b, v69
	v_mul_f32_e32 v71, v67, v71
	v_add_f32_e32 v67, 1.0, v75
	v_add_f32_e32 v75, 1.0, v76
	v_mul_f32_e32 v76, 0xbfb8aa3b, v73
	v_exp_f32_e32 v76, v76
	v_exp_f32_e32 v77, v77
; __device__ __forceinline__ float silu_f(float v) { return v * fast_sigmoid(v); }
; __device__ __forceinline__ u32x4 pack8(const f32x4 v0, const f32x4 v1) { u32x4 w; w.x = pk_f16(v0[0], v0[1]); w.y = pk_f16(v0[2], v0[3]); w.z = pk_f16(v1[0], v1[1]); w.w = pk_f16(v1[2], v1[3]); return w; }
;     __device__ __forceinline__ void operator()(AccRef acc, const Unit& u, int wr, int wc, int fr, int fq) const {
;     ...
;                     else {
; #pragma unroll
;                         for (int j = 0; j < 4; ++j) { v0[j] = silu_f(v0[j]); v1[j] = silu_f(v1[j]); }
;                         *(u32x4*)(zs + (size_t)row * D + (col - PW - SW)) = pack8(v0, v1); } } }
	v_rcp_f32_e32 v67, v67
	v_rcp_f32_e32 v75, v75
	v_add_f32_e32 v76, 1.0, v76
	v_rcp_f32_e32 v76, v76
	v_add_f32_e32 v77, 1.0, v77
	v_rcp_f32_e32 v77, v77
	v_mul_f32_e32 v67, v72, v67
	v_mul_f32_e32 v72, v68, v75
	v_mul_f32_e32 v68, v73, v76
	v_mul_f32_e32 v69, v69, v77
	v_cvt_pk_bf16_f32 v67, v67, v68
	v_mul_f32_e32 v68, 0xbfb8aa3b, v62
	v_cvt_pk_bf16_f32 v66, v70, v66
	v_exp_f32_e32 v70, v68
	v_cvt_pk_bf16_f32 v68, v74, v71
	v_cvt_pk_bf16_f32 v69, v72, v69
	global_store_dwordx4 v[78:79], v[66:69], off offset:-3840 sc0 sc1
	s_nop 1
	v_mul_f32_e32 v67, 0xbfb8aa3b, v58
	v_mul_f32_e32 v68, 0xbfb8aa3b, v63
	v_exp_f32_e32 v67, v67
	v_exp_f32_e32 v68, v68
	v_add_f32_e32 v66, 1.0, v70
	v_mul_f32_e32 v69, 0xbfb8aa3b, v59
	v_add_f32_e32 v67, 1.0, v67
	v_add_f32_e32 v68, 1.0, v68
	v_rcp_f32_e32 v66, v66
	v_rcp_f32_e32 v67, v67
	v_rcp_f32_e32 v68, v68
	v_exp_f32_e32 v69, v69
	v_mul_f32_e32 v62, v62, v66
	v_mul_f32_e32 v66, v58, v67
	v_mul_f32_e32 v58, v63, v68
	v_add_f32_e32 v63, 1.0, v69
	v_mul_f32_e32 v67, 0xbfb8aa3b, v64
	v_mul_f32_e32 v68, 0xbfb8aa3b, v60
	v_rcp_f32_e32 v63, v63
	v_exp_f32_e32 v67, v67
	v_exp_f32_e32 v68, v68
	v_mul_f32_e32 v69, 0xbfb8aa3b, v61
	v_mul_f32_e32 v63, v59, v63
	v_add_f32_e32 v59, 1.0, v67
	v_add_f32_e32 v67, 1.0, v68
	v_mul_f32_e32 v68, 0xbfb8aa3b, v65
	v_exp_f32_e32 v68, v68
	v_exp_f32_e32 v69, v69
	v_rcp_f32_e32 v59, v59
	v_rcp_f32_e32 v67, v67
	v_add_f32_e32 v68, 1.0, v68
	v_add_f32_e32 v69, 1.0, v69
	v_rcp_f32_e32 v68, v68
	v_rcp_f32_e32 v69, v69
	v_mul_f32_e32 v59, v64, v59
	v_mul_f32_e32 v64, v60, v67
	v_mul_f32_e32 v60, v65, v68
	v_mul_f32_e32 v61, v61, v69
	v_cvt_pk_bf16_f32 v58, v62, v58
	v_mul_f32_e32 v62, 0xbfb8aa3b, v54
	v_cvt_pk_bf16_f32 v59, v59, v60
	v_cvt_pk_bf16_f32 v60, v66, v63
	v_cvt_pk_bf16_f32 v61, v64, v61
	v_exp_f32_e32 v64, v62
	v_lshl_add_u64 v[62:63], v[122:123], 0, s[0:1]
	global_store_dwordx4 v[62:63], v[58:61], off offset:-4096 sc0 sc1
	s_mov_b64 s[0:1], 0x90000
	s_nop 0
	v_mul_f32_e32 v59, 0xbfb8aa3b, v50
	v_mul_f32_e32 v60, 0xbfb8aa3b, v55
	v_exp_f32_e32 v59, v59
	v_exp_f32_e32 v60, v60
	v_add_f32_e32 v58, 1.0, v64
	v_mul_f32_e32 v61, 0xbfb8aa3b, v51
	v_add_f32_e32 v59, 1.0, v59
	v_add_f32_e32 v60, 1.0, v60
	v_rcp_f32_e32 v58, v58
	v_rcp_f32_e32 v59, v59
	v_rcp_f32_e32 v60, v60
	v_exp_f32_e32 v61, v61
	v_mul_f32_e32 v54, v54, v58
	v_mul_f32_e32 v58, v50, v59
	v_mul_f32_e32 v50, v55, v60
	v_add_f32_e32 v55, 1.0, v61
	v_mul_f32_e32 v59, 0xbfb8aa3b, v56
	v_mul_f32_e32 v60, 0xbfb8aa3b, v52
	v_rcp_f32_e32 v55, v55
	v_exp_f32_e32 v59, v59
	v_exp_f32_e32 v60, v60
	v_mul_f32_e32 v61, 0xbfb8aa3b, v53
	v_mul_f32_e32 v55, v51, v55
	v_add_f32_e32 v51, 1.0, v59
	v_add_f32_e32 v59, 1.0, v60
	v_mul_f32_e32 v60, 0xbfb8aa3b, v57
	v_exp_f32_e32 v60, v60
	v_exp_f32_e32 v61, v61
	v_rcp_f32_e32 v51, v51
	v_rcp_f32_e32 v59, v59
	v_add_f32_e32 v60, 1.0, v60
	v_rcp_f32_e32 v60, v60
	v_add_f32_e32 v61, 1.0, v61
	v_rcp_f32_e32 v61, v61
	v_mul_f32_e32 v51, v56, v51
	v_mul_f32_e32 v56, v52, v59
	v_mul_f32_e32 v52, v57, v60
	v_mul_f32_e32 v53, v53, v61
	v_cvt_pk_bf16_f32 v51, v51, v52
	v_mul_f32_e32 v52, 0xbfb8aa3b, v46
	v_cvt_pk_bf16_f32 v50, v54, v50
	v_exp_f32_e32 v54, v52
	v_cvt_pk_bf16_f32 v52, v58, v55
	v_cvt_pk_bf16_f32 v53, v56, v53
	global_store_dwordx4 v[62:63], v[50:53], off offset:-3840 sc0 sc1
	s_nop 1
	v_mul_f32_e32 v51, 0xbfb8aa3b, v42
	v_mul_f32_e32 v52, 0xbfb8aa3b, v47
	v_exp_f32_e32 v51, v51
	v_exp_f32_e32 v52, v52
	v_add_f32_e32 v50, 1.0, v54
	v_mul_f32_e32 v53, 0xbfb8aa3b, v43
	v_add_f32_e32 v51, 1.0, v51
	v_add_f32_e32 v52, 1.0, v52
	v_rcp_f32_e32 v50, v50
	v_rcp_f32_e32 v51, v51
	v_rcp_f32_e32 v52, v52
	v_exp_f32_e32 v53, v53
	v_mul_f32_e32 v46, v46, v50
	v_mul_f32_e32 v50, v42, v51
	v_mul_f32_e32 v42, v47, v52
	v_add_f32_e32 v47, 1.0, v53
	v_mul_f32_e32 v51, 0xbfb8aa3b, v48
	v_mul_f32_e32 v52, 0xbfb8aa3b, v44
	v_rcp_f32_e32 v47, v47
	v_exp_f32_e32 v51, v51
	v_exp_f32_e32 v52, v52
	v_mul_f32_e32 v53, 0xbfb8aa3b, v45
	v_mul_f32_e32 v47, v43, v47
	v_add_f32_e32 v43, 1.0, v51
	v_add_f32_e32 v51, 1.0, v52
	v_mul_f32_e32 v52, 0xbfb8aa3b, v49
	v_exp_f32_e32 v52, v52
	v_exp_f32_e32 v53, v53
	v_rcp_f32_e32 v43, v43
	v_rcp_f32_e32 v51, v51
	v_add_f32_e32 v52, 1.0, v52
	v_add_f32_e32 v53, 1.0, v53
	v_rcp_f32_e32 v52, v52
	v_rcp_f32_e32 v53, v53
	v_mul_f32_e32 v43, v48, v43
	v_mul_f32_e32 v48, v44, v51
	v_mul_f32_e32 v44, v49, v52
	v_mul_f32_e32 v45, v45, v53
	v_cvt_pk_bf16_f32 v42, v46, v42
	v_mul_f32_e32 v46, 0xbfb8aa3b, v38
	v_cvt_pk_bf16_f32 v43, v43, v44
	v_cvt_pk_bf16_f32 v44, v50, v47
	v_cvt_pk_bf16_f32 v45, v48, v45
	v_exp_f32_e32 v48, v46
	v_lshl_add_u64 v[46:47], v[122:123], 0, s[0:1]
	global_store_dwordx4 v[46:47], v[42:45], off offset:-4096 sc0 sc1
	s_mov_b64 s[0:1], 0xa0000
	s_nop 0
	v_mul_f32_e32 v43, 0xbfb8aa3b, v34
	v_mul_f32_e32 v44, 0xbfb8aa3b, v39
	v_exp_f32_e32 v43, v43
	v_exp_f32_e32 v44, v44
	v_add_f32_e32 v42, 1.0, v48
	v_mul_f32_e32 v45, 0xbfb8aa3b, v35
	v_add_f32_e32 v43, 1.0, v43
	v_add_f32_e32 v44, 1.0, v44
	v_rcp_f32_e32 v42, v42
	v_rcp_f32_e32 v43, v43
	v_rcp_f32_e32 v44, v44
	v_exp_f32_e32 v45, v45
	v_mul_f32_e32 v38, v38, v42
	v_mul_f32_e32 v42, v34, v43
	v_mul_f32_e32 v34, v39, v44
	v_add_f32_e32 v39, 1.0, v45
	v_mul_f32_e32 v43, 0xbfb8aa3b, v40
	v_mul_f32_e32 v44, 0xbfb8aa3b, v36
	v_rcp_f32_e32 v39, v39
	v_exp_f32_e32 v43, v43
	v_exp_f32_e32 v44, v44
	v_mul_f32_e32 v45, 0xbfb8aa3b, v37
	v_mul_f32_e32 v39, v35, v39
	v_add_f32_e32 v35, 1.0, v43
	v_add_f32_e32 v43, 1.0, v44
	v_mul_f32_e32 v44, 0xbfb8aa3b, v41
	v_exp_f32_e32 v44, v44
	v_exp_f32_e32 v45, v45
	v_rcp_f32_e32 v35, v35
	v_rcp_f32_e32 v43, v43
	v_add_f32_e32 v44, 1.0, v44
	v_rcp_f32_e32 v44, v44
; __device__ __forceinline__ float silu_f(float v) { return v * fast_sigmoid(v); }
; __device__ __forceinline__ u32x4 pack8(const f32x4 v0, const f32x4 v1) { u32x4 w; w.x = pk_f16(v0[0], v0[1]); w.y = pk_f16(v0[2], v0[3]); w.z = pk_f16(v1[0], v1[1]); w.w = pk_f16(v1[2], v1[3]); return w; }
; __device__ __forceinline__ unsigned xb_ld(unsigned* p)              { return __hip_atomic_load(p, __ATOMIC_RELAXED, __HIP_MEMORY_SCOPE_AGENT); }
; #define XB_SPIN(cond, bar) do { unsigned _sp = 0; while (cond) { __builtin_amdgcn_s_sleep(1); \
;     if ((++_sp & 255u) == 0u) { if (xb_ld(&(bar)[XB_TMO])) break; if (_sp > XB_SPIN_CAP) { atomicAdd(&(bar)[XB_TMO], 1u); break; } } } } while (0)
; #define SUB(i, ...) do { if (PROBE_PH == phk && PROBE_SUB == (i)) { __syncthreads(); tp0 = __builtin_amdgcn_s_memrealtime(); } __VA_ARGS__ if (PROBE_PH == phk && PROBE_SUB == (i)) { asm volatile("s_waitcnt vmcnt(0)" ::: "memory"); __syncthreads(); tp1 = __builtin_amdgcn_s_memrealtime(); } } while (0)
;     __device__ __forceinline__ void operator()(AccRef acc, const Unit& u, int wr, int wc, int fr, int fq) const {
;     ...
;                     else {
; #pragma unroll
;                         for (int j = 0; j < 4; ++j) { v0[j] = silu_f(v0[j]); v1[j] = silu_f(v1[j]); }
;                         *(u32x4*)(zs + (size_t)row * D + (col - PW - SW)) = pack8(v0, v1); } } }
; __global__ void __launch_bounds__(NTHREADS, 2) mk_fwd(Args a) {
;     ...
;             asm volatile("s_waitcnt vmcnt(0)" ::: "memory"); __syncthreads();
;             if (tid == 0) __hip_atomic_store(f2, 1u, __ATOMIC_RELAXED, __HIP_MEMORY_SCOPE_AGENT);
;             SUB(6, pg8::gemm_phase<CfgDense2048, EpiInProj, pg8::OneUnit, true, true>(lds, (const char*)(a.ws + WS_H), (const char*)(a.ws + WS_WIN), SZ, EZ); );
;             if (tid == 0) { XB_SPIN(xb_ld(f3) == 0u, (ctl + CW_BAR)); __builtin_amdgcn_fence(__ATOMIC_ACQUIRE, "agent"); asm volatile("s_waitcnt vmcnt(0)" ::: "memory"); }
	v_add_f32_e32 v45, 1.0, v45
	v_rcp_f32_e32 v45, v45
	v_mul_f32_e32 v35, v40, v35
	v_mul_f32_e32 v40, v36, v43
	v_mul_f32_e32 v36, v41, v44
	v_mul_f32_e32 v37, v37, v45
	v_cvt_pk_bf16_f32 v35, v35, v36
	v_mul_f32_e32 v36, 0xbfb8aa3b, v30
	v_cvt_pk_bf16_f32 v34, v38, v34
	v_exp_f32_e32 v38, v36
	v_cvt_pk_bf16_f32 v36, v42, v39
	v_cvt_pk_bf16_f32 v37, v40, v37
	global_store_dwordx4 v[46:47], v[34:37], off offset:-3840 sc0 sc1
	s_nop 1
	v_mul_f32_e32 v35, 0xbfb8aa3b, v26
	v_mul_f32_e32 v36, 0xbfb8aa3b, v31
	v_exp_f32_e32 v35, v35
	v_exp_f32_e32 v36, v36
	v_add_f32_e32 v34, 1.0, v38
	v_mul_f32_e32 v37, 0xbfb8aa3b, v27
	v_add_f32_e32 v35, 1.0, v35
	v_add_f32_e32 v36, 1.0, v36
	v_rcp_f32_e32 v34, v34
	v_rcp_f32_e32 v35, v35
	v_rcp_f32_e32 v36, v36
	v_exp_f32_e32 v37, v37
	v_mul_f32_e32 v30, v30, v34
	v_mul_f32_e32 v34, v26, v35
	v_mul_f32_e32 v26, v31, v36
	v_add_f32_e32 v31, 1.0, v37
	v_mul_f32_e32 v35, 0xbfb8aa3b, v32
	v_mul_f32_e32 v36, 0xbfb8aa3b, v28
	v_rcp_f32_e32 v31, v31
	v_exp_f32_e32 v35, v35
	v_exp_f32_e32 v36, v36
	v_mul_f32_e32 v37, 0xbfb8aa3b, v29
	v_mul_f32_e32 v31, v27, v31
	v_add_f32_e32 v27, 1.0, v35
	v_add_f32_e32 v35, 1.0, v36
	v_mul_f32_e32 v36, 0xbfb8aa3b, v33
	v_exp_f32_e32 v36, v36
	v_exp_f32_e32 v37, v37
	v_rcp_f32_e32 v27, v27
	v_rcp_f32_e32 v35, v35
	v_add_f32_e32 v36, 1.0, v36
	v_add_f32_e32 v37, 1.0, v37
	v_rcp_f32_e32 v36, v36
	v_rcp_f32_e32 v37, v37
	v_mul_f32_e32 v27, v32, v27
	v_mul_f32_e32 v32, v28, v35
	v_mul_f32_e32 v28, v33, v36
	v_mul_f32_e32 v29, v29, v37
	v_cvt_pk_bf16_f32 v26, v30, v26
	v_mul_f32_e32 v30, 0xbfb8aa3b, v22
	v_cvt_pk_bf16_f32 v27, v27, v28
	v_cvt_pk_bf16_f32 v28, v34, v31
	v_cvt_pk_bf16_f32 v29, v32, v29
	v_exp_f32_e32 v32, v30
	v_lshl_add_u64 v[30:31], v[122:123], 0, s[0:1]
	global_store_dwordx4 v[30:31], v[26:29], off offset:-4096 sc0 sc1
	s_mov_b64 s[0:1], 0xb0000
	s_nop 0
	v_mul_f32_e32 v27, 0xbfb8aa3b, v18
	v_mul_f32_e32 v28, 0xbfb8aa3b, v23
	v_exp_f32_e32 v27, v27
	v_exp_f32_e32 v28, v28
	v_add_f32_e32 v26, 1.0, v32
	v_mul_f32_e32 v29, 0xbfb8aa3b, v19
	v_add_f32_e32 v27, 1.0, v27
	v_add_f32_e32 v28, 1.0, v28
	v_rcp_f32_e32 v26, v26
	v_rcp_f32_e32 v27, v27
	v_rcp_f32_e32 v28, v28
	v_exp_f32_e32 v29, v29
	v_mul_f32_e32 v22, v22, v26
	v_mul_f32_e32 v26, v18, v27
	v_mul_f32_e32 v18, v23, v28
	v_add_f32_e32 v23, 1.0, v29
	v_mul_f32_e32 v27, 0xbfb8aa3b, v24
	v_mul_f32_e32 v28, 0xbfb8aa3b, v20
	v_rcp_f32_e32 v23, v23
	v_exp_f32_e32 v27, v27
	v_exp_f32_e32 v28, v28
	v_mul_f32_e32 v29, 0xbfb8aa3b, v21
	v_mul_f32_e32 v23, v19, v23
	v_add_f32_e32 v19, 1.0, v27
	v_add_f32_e32 v27, 1.0, v28
	v_mul_f32_e32 v28, 0xbfb8aa3b, v25
	v_exp_f32_e32 v28, v28
	v_exp_f32_e32 v29, v29
	v_rcp_f32_e32 v19, v19
	v_rcp_f32_e32 v27, v27
	v_add_f32_e32 v28, 1.0, v28
	v_rcp_f32_e32 v28, v28
	v_add_f32_e32 v29, 1.0, v29
	v_rcp_f32_e32 v29, v29
	v_mul_f32_e32 v19, v24, v19
	v_mul_f32_e32 v24, v20, v27
	v_mul_f32_e32 v20, v25, v28
	v_mul_f32_e32 v21, v21, v29
	v_cvt_pk_bf16_f32 v19, v19, v20
	v_mul_f32_e32 v20, 0xbfb8aa3b, v14
	v_cvt_pk_bf16_f32 v18, v22, v18
	v_exp_f32_e32 v22, v20
	v_cvt_pk_bf16_f32 v20, v26, v23
	v_cvt_pk_bf16_f32 v21, v24, v21
	global_store_dwordx4 v[30:31], v[18:21], off offset:-3840 sc0 sc1
	s_nop 1
	v_mul_f32_e32 v19, 0xbfb8aa3b, v10
	v_mul_f32_e32 v20, 0xbfb8aa3b, v15
	v_exp_f32_e32 v19, v19
	v_exp_f32_e32 v20, v20
	v_add_f32_e32 v18, 1.0, v22
	v_mul_f32_e32 v21, 0xbfb8aa3b, v11
	v_add_f32_e32 v19, 1.0, v19
	v_add_f32_e32 v20, 1.0, v20
	v_rcp_f32_e32 v18, v18
	v_rcp_f32_e32 v19, v19
	v_rcp_f32_e32 v20, v20
	v_exp_f32_e32 v21, v21
	v_mul_f32_e32 v14, v14, v18
	v_mul_f32_e32 v18, v10, v19
	v_mul_f32_e32 v10, v15, v20
	v_add_f32_e32 v15, 1.0, v21
	v_mul_f32_e32 v19, 0xbfb8aa3b, v16
	v_mul_f32_e32 v20, 0xbfb8aa3b, v12
	v_rcp_f32_e32 v15, v15
	v_exp_f32_e32 v19, v19
	v_exp_f32_e32 v20, v20
	v_mul_f32_e32 v21, 0xbfb8aa3b, v13
	v_mul_f32_e32 v15, v11, v15
	v_add_f32_e32 v11, 1.0, v19
	v_add_f32_e32 v19, 1.0, v20
	v_mul_f32_e32 v20, 0xbfb8aa3b, v17
	v_exp_f32_e32 v20, v20
	v_exp_f32_e32 v21, v21
	v_rcp_f32_e32 v11, v11
	v_rcp_f32_e32 v19, v19
	v_add_f32_e32 v20, 1.0, v20
	v_add_f32_e32 v21, 1.0, v21
	v_rcp_f32_e32 v20, v20
	v_rcp_f32_e32 v21, v21
	v_mul_f32_e32 v11, v16, v11
	v_mul_f32_e32 v16, v12, v19
	v_mul_f32_e32 v12, v17, v20
	v_mul_f32_e32 v13, v13, v21
	v_cvt_pk_bf16_f32 v10, v14, v10
	v_mul_f32_e32 v14, 0xbfb8aa3b, v6
	v_cvt_pk_bf16_f32 v11, v11, v12
	v_cvt_pk_bf16_f32 v12, v18, v15
	v_cvt_pk_bf16_f32 v13, v16, v13
	v_exp_f32_e32 v16, v14
	v_lshl_add_u64 v[14:15], v[122:123], 0, s[0:1]
	global_store_dwordx4 v[14:15], v[10:13], off offset:-4096 sc0 sc1
	s_nop 1
	v_mul_f32_e32 v11, 0xbfb8aa3b, v2
	v_mul_f32_e32 v12, 0xbfb8aa3b, v7
	v_exp_f32_e32 v11, v11
	v_exp_f32_e32 v12, v12
	v_add_f32_e32 v10, 1.0, v16
	v_mul_f32_e32 v13, 0xbfb8aa3b, v3
	v_add_f32_e32 v11, 1.0, v11
	v_add_f32_e32 v12, 1.0, v12
	v_rcp_f32_e32 v10, v10
	v_rcp_f32_e32 v11, v11
	v_rcp_f32_e32 v12, v12
	v_exp_f32_e32 v13, v13
	v_mul_f32_e32 v6, v6, v10
	v_mul_f32_e32 v10, v2, v11
	v_mul_f32_e32 v2, v7, v12
	v_add_f32_e32 v7, 1.0, v13
	v_mul_f32_e32 v11, 0xbfb8aa3b, v8
	v_mul_f32_e32 v12, 0xbfb8aa3b, v4
	v_rcp_f32_e32 v7, v7
	v_exp_f32_e32 v11, v11
	v_exp_f32_e32 v12, v12
	v_mul_f32_e32 v13, 0xbfb8aa3b, v5
	v_mul_f32_e32 v7, v3, v7
	v_add_f32_e32 v3, 1.0, v11
	v_add_f32_e32 v11, 1.0, v12
	v_mul_f32_e32 v12, 0xbfb8aa3b, v9
	v_exp_f32_e32 v12, v12
	v_exp_f32_e32 v13, v13
	v_rcp_f32_e32 v3, v3
	v_rcp_f32_e32 v11, v11
	v_add_f32_e32 v12, 1.0, v12
	v_add_f32_e32 v13, 1.0, v13
	v_rcp_f32_e32 v12, v12
	v_rcp_f32_e32 v13, v13
	v_mul_f32_e32 v3, v8, v3
	v_mul_f32_e32 v8, v4, v11
	v_mul_f32_e32 v4, v9, v12
	v_mul_f32_e32 v5, v5, v13
	v_cvt_pk_bf16_f32 v2, v6, v2
	v_cvt_pk_bf16_f32 v3, v3, v4
	v_cvt_pk_bf16_f32 v4, v10, v7
	v_cvt_pk_bf16_f32 v5, v8, v5
	global_store_dwordx4 v[14:15], v[2:5], off offset:-3840 sc0 sc1
	s_waitcnt vmcnt(0)
	s_barrier
	s_and_saveexec_b64 s[2:3], s[82:83]
	s_mov_b32 s81, s28
	s_cbranch_execz .LBB0_989
	v_mov_b32_e32 v2, 0
	global_load_dword v3, v2, s[26:27] offset:1024 sc1
	s_waitcnt vmcnt(0)
	v_cmp_ne_u32_e32 vcc, 0, v3
	s_cbranch_vccnz .LBB0_988
	s_mov_b32 s0, 1
	s_branch .LBB0_976

; __device__ __forceinline__ float gelu_tanh_f(float y) { const float t = 0.7978845608028654f * (y + 0.044715f * y * y * y); return y * fast_sigmoid(2.f * t); }
; __device__ __forceinline__ u32x4 pack8(const f32x4 v0, const f32x4 v1) { u32x4 w; w.x = pk_f16(v0[0], v0[1]); w.y = pk_f16(v0[2], v0[3]); w.z = pk_f16(v1[0], v1[1]); w.w = pk_f16(v1[2], v1[3]); return w; }
; __device__ __forceinline__ void unpack8(const u32x4 w, f32x4& v0, f32x4& v1) { v0 = (f32x4){f16lo(w.x), f16hi(w.x), f16lo(w.y), f16hi(w.y)}; v1 = (f32x4){f16lo(w.z), f16hi(w.z), f16lo(w.w), f16hi(w.w)}; }
;     __device__ __forceinline__ void operator()(AccRef acc, const Unit& u, int wr, int wc, int fr, int fq) const {
;         int row0 = u.pm * 256 + wr * 64 + fr; asm volatile("" : "+v"(row0)); int col0 = u.pn * 256 + wc * 32 + 8 * fq; asm volatile("" : "+v"(col0));
;         const float* dp = dskip + u.g * GH + (col0 & 15);
;         const f32x4 d0 = *(const f32x4*)dp, d1 = *(const f32x4*)(dp + 4);
;         const f16* Xg = X + (size_t)u.g * XGS + 256 + col0; f16* Yg = YG + (size_t)u.g * YGS + col0;
; #pragma unroll
;         for (int ai = 0; ai < 2; ++ai) { u32x4 uv[4][2];
; #pragma unroll
;             for (int m = 0; m < 4; ++m)
; #pragma unroll
;                 for (int bj = 0; bj < 2; ++bj) uv[m][bj] = *(const u32x4*)(Xg + (size_t)(row0 + ai * HALF + m * 16) * XK + bj * HALF);
;             __builtin_amdgcn_sched_barrier(0);
; #pragma unroll
;             for (int m = 0; m < 4; ++m)
; #pragma unroll
;                 for (int bj = 0; bj < 2; ++bj) { f32x4 u0, u1; unpack8(uv[m][bj], u0, u1);
;                     f32x4 v0 = acc[ai][bj][m][0] + d0 * u0, v1 = acc[ai][bj][m][1] + d1 * u1;
; #pragma unroll
;                     for (int j = 0; j < 4; ++j) { v0[j] = gelu_tanh_f(v0[j]); v1[j] = gelu_tanh_f(v1[j]); }
;                     *(u32x4*)(Yg + (size_t)(row0 + ai * HALF + m * 16) * 512 + bj * HALF) = pack8(v0, v1); } }
.LBB0_996:
	v_lshl_or_b32 v1, s0, 8, v215
	s_lshl_b32 s0, s24, 4
	s_ashr_i32 s1, s0, 31
	v_lshl_add_u32 v164, s84, 8, v27
	v_or_b32_e32 v106, s54, v1
	s_lshl_b64 s[0:1], s[0:1], 2
	s_add_u32 s0, s38, s0
	v_and_b32_e32 v1, 15, v106
	v_ashrrev_i32_e32 v107, 31, v106
	s_addc_u32 s1, s39, s1
	v_lshlrev_b32_e32 v1, 2, v1
	v_lshlrev_b64 v[162:163], 1, v[106:107]
	global_load_dwordx4 v[26:29], v1, s[0:1] offset:16
	global_load_dwordx4 v[30:33], v1, s[0:1]
	v_lshl_add_u64 v[166:167], s[2:3], 0, v[162:163]
	s_movk_i32 s0, 0x600
	v_mad_i64_i32 v[106:107], s[2:3], v164, s0, v[166:167]
	v_add_u32_e32 v172, 16, v164
	global_load_dwordx4 v[176:179], v[106:107], off offset:512
	global_load_dwordx4 v[180:183], v[106:107], off offset:768
	v_mad_i64_i32 v[106:107], s[2:3], v172, s0, v[166:167]
	v_add_u32_e32 v170, 32, v164
	global_load_dwordx4 v[158:161], v[106:107], off offset:512
	global_load_dwordx4 v[154:157], v[106:107], off offset:768
	v_mad_i64_i32 v[106:107], s[2:3], v170, s0, v[166:167]
	v_add_u32_e32 v168, 48, v164
	global_load_dwordx4 v[142:145], v[106:107], off offset:512
	global_load_dwordx4 v[130:133], v[106:107], off offset:768
	v_mad_i64_i32 v[106:107], s[2:3], v168, s0, v[166:167]
	global_load_dwordx4 v[118:121], v[106:107], off offset:512
	s_nop 0
	global_load_dwordx4 v[106:109], v[106:107], off offset:768
	s_lshl_b64 s[2:3], s[24:25], 19
	s_add_u32 s2, s50, s2
	s_addc_u32 s3, s51, s3
	v_lshl_add_u64 v[162:163], s[2:3], 0, v[162:163]
	s_mov_b64 s[2:3], 0x17800000
	v_lshl_add_u64 v[162:163], v[162:163], 0, s[2:3]
	v_ashrrev_i32_e32 v165, 31, v164
	v_ashrrev_i32_e32 v173, 31, v172
	v_ashrrev_i32_e32 v171, 31, v170
	v_ashrrev_i32_e32 v169, 31, v168
	s_waitcnt vmcnt(0)
	v_and_b32_e32 v185, 0xffff0000, v176
	v_lshlrev_b32_e32 v184, 16, v176
	v_and_b32_e32 v187, 0xffff0000, v177
	v_lshlrev_b32_e32 v186, 16, v177
	v_and_b32_e32 v177, 0xffff0000, v178
	v_lshlrev_b32_e32 v176, 16, v178
	v_pk_fma_f32 v[150:151], v[30:31], v[184:185], v[150:151]
	v_pk_fma_f32 v[146:147], v[26:27], v[176:177], v[146:147]
	v_lshlrev_b64 v[174:175], 10, v[164:165]
	v_mul_f32_e32 v1, 0x3d372713, v150
	v_mul_f32_e32 v165, 0x3d372713, v146
	v_mul_f32_e32 v176, 0x3d372713, v151
	v_mul_f32_e32 v1, v150, v1
	v_mul_f32_e32 v165, v146, v165
	v_mul_f32_e32 v176, v151, v176
	v_fma_f32 v1, v150, v1, v150
	v_fma_f32 v165, v146, v165, v146
	v_fma_f32 v176, v151, v176, v151
	v_mul_f32_e32 v1, 0x3f4c422a, v1
	v_mul_f32_e32 v165, 0x3f4c422a, v165
	v_mul_f32_e32 v176, 0x3f4c422a, v176
	v_add_f32_e32 v1, v1, v1
	v_add_f32_e32 v165, v165, v165
	v_add_f32_e32 v176, v176, v176
	v_mul_f32_e32 v1, 0xbfb8aa3b, v1
	v_mul_f32_e32 v165, 0xbfb8aa3b, v165
	v_mul_f32_e32 v176, 0xbfb8aa3b, v176
	v_exp_f32_e32 v1, v1
	v_exp_f32_e32 v165, v165
	v_exp_f32_e32 v176, v176
	v_mul_f32_e32 v177, 0x3d372713, v147
	v_add_f32_e32 v1, 1.0, v1
	v_add_f32_e32 v165, 1.0, v165
	v_add_f32_e32 v176, 1.0, v176
	v_rcp_f32_e32 v1, v1
	v_rcp_f32_e32 v165, v165
	v_rcp_f32_e32 v176, v176
	v_mul_f32_e32 v177, v147, v177
	v_fma_f32 v177, v147, v177, v147
	v_and_b32_e32 v189, 0xffff0000, v179
	v_lshlrev_b32_e32 v188, 16, v179
	v_mul_f32_e32 v177, 0x3f4c422a, v177
	v_pk_fma_f32 v[152:153], v[32:33], v[186:187], v[152:153]
	v_pk_fma_f32 v[148:149], v[28:29], v[188:189], v[148:149]
	v_add_f32_e32 v177, v177, v177
	v_mul_f32_e32 v177, 0xbfb8aa3b, v177
	v_mul_f32_e32 v1, v150, v1
	v_mul_f32_e32 v150, v146, v165
	v_mul_f32_e32 v146, v151, v176
	v_mul_f32_e32 v165, 0x3d372713, v152
	v_mul_f32_e32 v176, 0x3d372713, v148
	v_exp_f32_e32 v177, v177
	v_mul_f32_e32 v165, v152, v165
	v_mul_f32_e32 v176, v148, v176
	v_fma_f32 v165, v152, v165, v152
	v_fma_f32 v176, v148, v176, v148
	v_mul_f32_e32 v165, 0x3f4c422a, v165
	v_mul_f32_e32 v176, 0x3f4c422a, v176
	v_add_f32_e32 v165, v165, v165
	v_add_f32_e32 v176, v176, v176
	v_add_f32_e32 v151, 1.0, v177
	v_mul_f32_e32 v165, 0xbfb8aa3b, v165
	v_mul_f32_e32 v176, 0xbfb8aa3b, v176
	v_rcp_f32_e32 v151, v151
	v_exp_f32_e32 v165, v165
	v_exp_f32_e32 v176, v176
	v_mul_f32_e32 v177, 0x3d372713, v149
	v_mul_f32_e32 v151, v147, v151
	v_add_f32_e32 v147, 1.0, v165
	v_add_f32_e32 v165, 1.0, v176
	v_mul_f32_e32 v176, 0x3d372713, v153
	v_mul_f32_e32 v176, v153, v176
	v_mul_f32_e32 v177, v149, v177
	v_fma_f32 v176, v153, v176, v153
	v_fma_f32 v177, v149, v177, v149
	v_mul_f32_e32 v176, 0x3f4c422a, v176
	v_mul_f32_e32 v177, 0x3f4c422a, v177
	v_add_f32_e32 v176, v176, v176
	v_add_f32_e32 v177, v177, v177
	v_mul_f32_e32 v176, 0xbfb8aa3b, v176
	v_mul_f32_e32 v177, 0xbfb8aa3b, v177
	v_exp_f32_e32 v176, v176
	v_exp_f32_e32 v177, v177
	v_rcp_f32_e32 v147, v147
	v_rcp_f32_e32 v165, v165
	v_add_f32_e32 v176, 1.0, v176
	v_add_f32_e32 v177, 1.0, v177
	v_rcp_f32_e32 v176, v176
	v_rcp_f32_e32 v177, v177
	v_mul_f32_e32 v147, v152, v147
	v_mul_f32_e32 v152, v148, v165
	v_mul_f32_e32 v148, v153, v176
	v_mul_f32_e32 v149, v149, v177
	v_lshl_add_u64 v[174:175], v[162:163], 0, v[174:175]
	v_cvt_pk_bf16_f32 v146, v1, v146
	v_cvt_pk_bf16_f32 v147, v147, v148
	v_cvt_pk_bf16_f32 v148, v150, v151
	v_cvt_pk_bf16_f32 v149, v152, v149
	global_store_dwordx4 v[174:175], v[146:149], off sc0 sc1
	v_and_b32_e32 v151, 0xffff0000, v182
	v_lshlrev_b32_e32 v150, 16, v182
	v_and_b32_e32 v147, 0xffff0000, v180
	v_lshlrev_b32_e32 v146, 16, v180
	v_pk_fma_f32 v[138:139], v[30:31], v[146:147], v[138:139]
	v_pk_fma_f32 v[134:135], v[26:27], v[150:151], v[134:135]
	v_mul_f32_e32 v1, 0x3d372713, v138
	v_mul_f32_e32 v146, 0x3d372713, v134
	v_mul_f32_e32 v147, 0x3d372713, v139
	v_mul_f32_e32 v1, v138, v1
	v_mul_f32_e32 v146, v134, v146
	v_mul_f32_e32 v147, v139, v147
	v_fma_f32 v1, v138, v1, v138
	v_fma_f32 v146, v134, v146, v134
	v_fma_f32 v147, v139, v147, v139
; __device__ __forceinline__ float gelu_tanh_f(float y) { const float t = 0.7978845608028654f * (y + 0.044715f * y * y * y); return y * fast_sigmoid(2.f * t); }
; __device__ __forceinline__ u32x4 pack8(const f32x4 v0, const f32x4 v1) { u32x4 w; w.x = pk_f16(v0[0], v0[1]); w.y = pk_f16(v0[2], v0[3]); w.z = pk_f16(v1[0], v1[1]); w.w = pk_f16(v1[2], v1[3]); return w; }
; __device__ __forceinline__ void unpack8(const u32x4 w, f32x4& v0, f32x4& v1) { v0 = (f32x4){f16lo(w.x), f16hi(w.x), f16lo(w.y), f16hi(w.y)}; v1 = (f32x4){f16lo(w.z), f16hi(w.z), f16lo(w.w), f16hi(w.w)}; }
;     __device__ __forceinline__ void operator()(AccRef acc, const Unit& u, int wr, int wc, int fr, int fq) const {
;     ...
;             for (int m = 0; m < 4; ++m)
; #pragma unroll
;                 for (int bj = 0; bj < 2; ++bj) { f32x4 u0, u1; unpack8(uv[m][bj], u0, u1);
;                     f32x4 v0 = acc[ai][bj][m][0] + d0 * u0, v1 = acc[ai][bj][m][1] + d1 * u1;
; #pragma unroll
;                     for (int j = 0; j < 4; ++j) { v0[j] = gelu_tanh_f(v0[j]); v1[j] = gelu_tanh_f(v1[j]); }
;                     *(u32x4*)(Yg + (size_t)(row0 + ai * HALF + m * 16) * 512 + bj * HALF) = pack8(v0, v1); } }
	v_mul_f32_e32 v1, 0x3f4c422a, v1
	v_mul_f32_e32 v146, 0x3f4c422a, v146
	v_mul_f32_e32 v147, 0x3f4c422a, v147
	v_add_f32_e32 v1, v1, v1
	v_add_f32_e32 v146, v146, v146
	v_add_f32_e32 v147, v147, v147
	v_mul_f32_e32 v1, 0xbfb8aa3b, v1
	v_mul_f32_e32 v146, 0xbfb8aa3b, v146
	v_mul_f32_e32 v147, 0xbfb8aa3b, v147
	v_exp_f32_e32 v1, v1
	v_exp_f32_e32 v146, v146
	v_exp_f32_e32 v147, v147
	v_and_b32_e32 v149, 0xffff0000, v181
	v_lshlrev_b32_e32 v148, 16, v181
	v_pk_fma_f32 v[140:141], v[32:33], v[148:149], v[140:141]
	v_add_f32_e32 v1, 1.0, v1
	v_add_f32_e32 v146, 1.0, v146
	v_add_f32_e32 v147, 1.0, v147
	v_mul_f32_e32 v148, 0x3d372713, v135
	v_rcp_f32_e32 v1, v1
	v_rcp_f32_e32 v146, v146
	v_rcp_f32_e32 v147, v147
	v_mul_f32_e32 v148, v135, v148
	v_fma_f32 v148, v135, v148, v135
	v_and_b32_e32 v153, 0xffff0000, v183
	v_lshlrev_b32_e32 v152, 16, v183
	v_mul_f32_e32 v148, 0x3f4c422a, v148
	v_pk_fma_f32 v[136:137], v[28:29], v[152:153], v[136:137]
	v_add_f32_e32 v148, v148, v148
	v_mul_f32_e32 v148, 0xbfb8aa3b, v148
	v_mul_f32_e32 v1, v138, v1
	v_mul_f32_e32 v138, v134, v146
	v_mul_f32_e32 v134, v139, v147
	v_mul_f32_e32 v146, 0x3d372713, v140
	v_mul_f32_e32 v147, 0x3d372713, v136
	v_exp_f32_e32 v148, v148
	v_mul_f32_e32 v146, v140, v146
	v_mul_f32_e32 v147, v136, v147
	v_fma_f32 v146, v140, v146, v140
	v_fma_f32 v147, v136, v147, v136
	v_mul_f32_e32 v146, 0x3f4c422a, v146
	v_mul_f32_e32 v147, 0x3f4c422a, v147
	v_add_f32_e32 v146, v146, v146
	v_add_f32_e32 v147, v147, v147
	v_add_f32_e32 v139, 1.0, v148
	v_mul_f32_e32 v146, 0xbfb8aa3b, v146
	v_mul_f32_e32 v147, 0xbfb8aa3b, v147
	v_rcp_f32_e32 v139, v139
	v_exp_f32_e32 v146, v146
	v_exp_f32_e32 v147, v147
	v_mul_f32_e32 v148, 0x3d372713, v137
	v_mul_f32_e32 v139, v135, v139
	v_add_f32_e32 v135, 1.0, v146
	v_add_f32_e32 v146, 1.0, v147
	v_mul_f32_e32 v147, 0x3d372713, v141
	v_mul_f32_e32 v147, v141, v147
	v_mul_f32_e32 v148, v137, v148
	v_fma_f32 v147, v141, v147, v141
	v_fma_f32 v148, v137, v148, v137
	v_mul_f32_e32 v147, 0x3f4c422a, v147
	v_mul_f32_e32 v148, 0x3f4c422a, v148
	v_add_f32_e32 v147, v147, v147
	v_add_f32_e32 v148, v148, v148
	v_mul_f32_e32 v147, 0xbfb8aa3b, v147
	v_mul_f32_e32 v148, 0xbfb8aa3b, v148
	v_exp_f32_e32 v147, v147
	v_exp_f32_e32 v148, v148
	v_rcp_f32_e32 v135, v135
	v_rcp_f32_e32 v146, v146
	v_add_f32_e32 v147, 1.0, v147
	v_add_f32_e32 v148, 1.0, v148
	v_rcp_f32_e32 v147, v147
	v_rcp_f32_e32 v148, v148
	v_mul_f32_e32 v135, v140, v135
	v_mul_f32_e32 v140, v136, v146
	v_mul_f32_e32 v136, v141, v147
	v_mul_f32_e32 v137, v137, v148
	v_cvt_pk_bf16_f32 v134, v1, v134
	v_cvt_pk_bf16_f32 v135, v135, v136
	v_cvt_pk_bf16_f32 v136, v138, v139
	v_cvt_pk_bf16_f32 v137, v140, v137
	global_store_dwordx4 v[174:175], v[134:137], off offset:256 sc0 sc1
	v_and_b32_e32 v141, 0xffff0000, v160
	v_lshlrev_b32_e32 v140, 16, v160
	v_and_b32_e32 v137, 0xffff0000, v158
	v_lshlrev_b32_e32 v136, 16, v158
	v_pk_fma_f32 v[126:127], v[30:31], v[136:137], v[126:127]
	v_pk_fma_f32 v[122:123], v[26:27], v[140:141], v[122:123]
	v_mul_f32_e32 v1, 0x3d372713, v126
	v_mul_f32_e32 v136, 0x3d372713, v122
	v_mul_f32_e32 v137, 0x3d372713, v127
	v_mul_f32_e32 v1, v126, v1
	v_mul_f32_e32 v136, v122, v136
	v_mul_f32_e32 v137, v127, v137
	v_fma_f32 v1, v126, v1, v126
	v_fma_f32 v136, v122, v136, v122
	v_fma_f32 v137, v127, v137, v127
	v_mul_f32_e32 v1, 0x3f4c422a, v1
	v_mul_f32_e32 v136, 0x3f4c422a, v136
	v_mul_f32_e32 v137, 0x3f4c422a, v137
	v_add_f32_e32 v1, v1, v1
	v_add_f32_e32 v136, v136, v136
	v_add_f32_e32 v137, v137, v137
	v_mul_f32_e32 v1, 0xbfb8aa3b, v1
	v_mul_f32_e32 v136, 0xbfb8aa3b, v136
	v_mul_f32_e32 v137, 0xbfb8aa3b, v137
	v_exp_f32_e32 v1, v1
	v_exp_f32_e32 v136, v136
	v_exp_f32_e32 v137, v137
	v_and_b32_e32 v139, 0xffff0000, v159
	v_lshlrev_b32_e32 v138, 16, v159
	v_pk_fma_f32 v[128:129], v[32:33], v[138:139], v[128:129]
	v_add_f32_e32 v1, 1.0, v1
	v_add_f32_e32 v136, 1.0, v136
	v_add_f32_e32 v137, 1.0, v137
	v_mul_f32_e32 v138, 0x3d372713, v123
	v_rcp_f32_e32 v1, v1
	v_rcp_f32_e32 v136, v136
	v_rcp_f32_e32 v137, v137
	v_mul_f32_e32 v138, v123, v138
	v_fma_f32 v138, v123, v138, v123
	v_and_b32_e32 v147, 0xffff0000, v161
	v_lshlrev_b32_e32 v146, 16, v161
	v_mul_f32_e32 v138, 0x3f4c422a, v138
	v_pk_fma_f32 v[124:125], v[28:29], v[146:147], v[124:125]
	v_add_f32_e32 v138, v138, v138
	v_mul_f32_e32 v138, 0xbfb8aa3b, v138
	v_mul_f32_e32 v1, v126, v1
	v_mul_f32_e32 v126, v122, v136
	v_mul_f32_e32 v122, v127, v137
	v_mul_f32_e32 v136, 0x3d372713, v128
	v_mul_f32_e32 v137, 0x3d372713, v124
	v_exp_f32_e32 v138, v138
	v_mul_f32_e32 v136, v128, v136
	v_mul_f32_e32 v137, v124, v137
	v_fma_f32 v136, v128, v136, v128
	v_fma_f32 v137, v124, v137, v124
	v_mul_f32_e32 v136, 0x3f4c422a, v136
	v_mul_f32_e32 v137, 0x3f4c422a, v137
	v_add_f32_e32 v136, v136, v136
	v_add_f32_e32 v137, v137, v137
	v_add_f32_e32 v127, 1.0, v138
	v_mul_f32_e32 v136, 0xbfb8aa3b, v136
	v_mul_f32_e32 v137, 0xbfb8aa3b, v137
	v_rcp_f32_e32 v127, v127
	v_exp_f32_e32 v136, v136
	v_exp_f32_e32 v137, v137
	v_mul_f32_e32 v138, 0x3d372713, v125
	v_mul_f32_e32 v127, v123, v127
	v_add_f32_e32 v123, 1.0, v136
	v_add_f32_e32 v136, 1.0, v137
	v_mul_f32_e32 v137, 0x3d372713, v129
	v_mul_f32_e32 v137, v129, v137
	v_mul_f32_e32 v138, v125, v138
	v_fma_f32 v137, v129, v137, v129
	v_fma_f32 v138, v125, v138, v125
	v_mul_f32_e32 v137, 0x3f4c422a, v137
	v_mul_f32_e32 v138, 0x3f4c422a, v138
	v_add_f32_e32 v137, v137, v137
	v_add_f32_e32 v138, v138, v138
	v_mul_f32_e32 v137, 0xbfb8aa3b, v137
	v_mul_f32_e32 v138, 0xbfb8aa3b, v138
	v_exp_f32_e32 v137, v137
	v_exp_f32_e32 v138, v138
	v_rcp_f32_e32 v123, v123
	v_rcp_f32_e32 v136, v136
	v_add_f32_e32 v137, 1.0, v137
; __device__ __forceinline__ float gelu_tanh_f(float y) { const float t = 0.7978845608028654f * (y + 0.044715f * y * y * y); return y * fast_sigmoid(2.f * t); }
; __device__ __forceinline__ u32x4 pack8(const f32x4 v0, const f32x4 v1) { u32x4 w; w.x = pk_f16(v0[0], v0[1]); w.y = pk_f16(v0[2], v0[3]); w.z = pk_f16(v1[0], v1[1]); w.w = pk_f16(v1[2], v1[3]); return w; }
; __device__ __forceinline__ void unpack8(const u32x4 w, f32x4& v0, f32x4& v1) { v0 = (f32x4){f16lo(w.x), f16hi(w.x), f16lo(w.y), f16hi(w.y)}; v1 = (f32x4){f16lo(w.z), f16hi(w.z), f16lo(w.w), f16hi(w.w)}; }
;     __device__ __forceinline__ void operator()(AccRef acc, const Unit& u, int wr, int wc, int fr, int fq) const {
;     ...
;             for (int m = 0; m < 4; ++m)
; #pragma unroll
;                 for (int bj = 0; bj < 2; ++bj) { f32x4 u0, u1; unpack8(uv[m][bj], u0, u1);
;                     f32x4 v0 = acc[ai][bj][m][0] + d0 * u0, v1 = acc[ai][bj][m][1] + d1 * u1;
; #pragma unroll
;                     for (int j = 0; j < 4; ++j) { v0[j] = gelu_tanh_f(v0[j]); v1[j] = gelu_tanh_f(v1[j]); }
;                     *(u32x4*)(Yg + (size_t)(row0 + ai * HALF + m * 16) * 512 + bj * HALF) = pack8(v0, v1); } }
	v_add_f32_e32 v138, 1.0, v138
	v_rcp_f32_e32 v137, v137
	v_rcp_f32_e32 v138, v138
	v_lshlrev_b64 v[134:135], 10, v[172:173]
	v_mul_f32_e32 v123, v128, v123
	v_mul_f32_e32 v128, v124, v136
	v_mul_f32_e32 v124, v129, v137
	v_mul_f32_e32 v125, v125, v138
	v_lshl_add_u64 v[134:135], v[162:163], 0, v[134:135]
	v_cvt_pk_bf16_f32 v122, v1, v122
	v_cvt_pk_bf16_f32 v123, v123, v124
	v_cvt_pk_bf16_f32 v124, v126, v127
	v_cvt_pk_bf16_f32 v125, v128, v125
	global_store_dwordx4 v[134:135], v[122:125], off sc0 sc1
	v_and_b32_e32 v127, 0xffff0000, v156
	v_lshlrev_b32_e32 v126, 16, v156
	v_and_b32_e32 v123, 0xffff0000, v154
	v_lshlrev_b32_e32 v122, 16, v154
	v_pk_fma_f32 v[114:115], v[30:31], v[122:123], v[114:115]
	v_pk_fma_f32 v[110:111], v[26:27], v[126:127], v[110:111]
	v_mul_f32_e32 v1, 0x3d372713, v114
	v_mul_f32_e32 v122, 0x3d372713, v110
	v_mul_f32_e32 v123, 0x3d372713, v115
	v_mul_f32_e32 v1, v114, v1
	v_mul_f32_e32 v122, v110, v122
	v_mul_f32_e32 v123, v115, v123
	v_fma_f32 v1, v114, v1, v114
	v_fma_f32 v122, v110, v122, v110
	v_fma_f32 v123, v115, v123, v115
	v_mul_f32_e32 v1, 0x3f4c422a, v1
	v_mul_f32_e32 v122, 0x3f4c422a, v122
	v_mul_f32_e32 v123, 0x3f4c422a, v123
	v_add_f32_e32 v1, v1, v1
	v_add_f32_e32 v122, v122, v122
	v_add_f32_e32 v123, v123, v123
	v_mul_f32_e32 v1, 0xbfb8aa3b, v1
	v_mul_f32_e32 v122, 0xbfb8aa3b, v122
	v_mul_f32_e32 v123, 0xbfb8aa3b, v123
	v_exp_f32_e32 v1, v1
	v_exp_f32_e32 v122, v122
	v_exp_f32_e32 v123, v123
	v_and_b32_e32 v125, 0xffff0000, v155
	v_lshlrev_b32_e32 v124, 16, v155
	v_pk_fma_f32 v[116:117], v[32:33], v[124:125], v[116:117]
	v_add_f32_e32 v1, 1.0, v1
	v_add_f32_e32 v122, 1.0, v122
	v_add_f32_e32 v123, 1.0, v123
	v_mul_f32_e32 v124, 0x3d372713, v111
	v_rcp_f32_e32 v1, v1
	v_rcp_f32_e32 v122, v122
	v_rcp_f32_e32 v123, v123
	v_mul_f32_e32 v124, v111, v124
	v_fma_f32 v124, v111, v124, v111
	v_and_b32_e32 v129, 0xffff0000, v157
	v_lshlrev_b32_e32 v128, 16, v157
	v_mul_f32_e32 v124, 0x3f4c422a, v124
	v_pk_fma_f32 v[112:113], v[28:29], v[128:129], v[112:113]
	v_add_f32_e32 v124, v124, v124
	v_mul_f32_e32 v124, 0xbfb8aa3b, v124
	v_mul_f32_e32 v1, v114, v1
	v_mul_f32_e32 v114, v110, v122
	v_mul_f32_e32 v110, v115, v123
	v_mul_f32_e32 v122, 0x3d372713, v116
	v_mul_f32_e32 v123, 0x3d372713, v112
	v_exp_f32_e32 v124, v124
	v_mul_f32_e32 v122, v116, v122
	v_mul_f32_e32 v123, v112, v123
	v_fma_f32 v122, v116, v122, v116
	v_fma_f32 v123, v112, v123, v112
	v_mul_f32_e32 v122, 0x3f4c422a, v122
	v_mul_f32_e32 v123, 0x3f4c422a, v123
	v_add_f32_e32 v122, v122, v122
	v_add_f32_e32 v123, v123, v123
	v_add_f32_e32 v115, 1.0, v124
	v_mul_f32_e32 v122, 0xbfb8aa3b, v122
	v_mul_f32_e32 v123, 0xbfb8aa3b, v123
	v_rcp_f32_e32 v115, v115
	v_exp_f32_e32 v122, v122
	v_exp_f32_e32 v123, v123
	v_mul_f32_e32 v124, 0x3d372713, v113
	v_mul_f32_e32 v115, v111, v115
	v_add_f32_e32 v111, 1.0, v122
	v_add_f32_e32 v122, 1.0, v123
	v_mul_f32_e32 v123, 0x3d372713, v117
	v_mul_f32_e32 v123, v117, v123
	v_mul_f32_e32 v124, v113, v124
	v_fma_f32 v123, v117, v123, v117
	v_fma_f32 v124, v113, v124, v113
	v_mul_f32_e32 v123, 0x3f4c422a, v123
	v_mul_f32_e32 v124, 0x3f4c422a, v124
	v_add_f32_e32 v123, v123, v123
	v_add_f32_e32 v124, v124, v124
	v_mul_f32_e32 v123, 0xbfb8aa3b, v123
	v_mul_f32_e32 v124, 0xbfb8aa3b, v124
	v_exp_f32_e32 v123, v123
	v_exp_f32_e32 v124, v124
	v_rcp_f32_e32 v111, v111
	v_rcp_f32_e32 v122, v122
	v_add_f32_e32 v123, 1.0, v123
	v_add_f32_e32 v124, 1.0, v124
	v_rcp_f32_e32 v123, v123
	v_rcp_f32_e32 v124, v124
	v_mul_f32_e32 v111, v116, v111
	v_mul_f32_e32 v116, v112, v122
	v_mul_f32_e32 v112, v117, v123
	v_mul_f32_e32 v113, v113, v124
	v_cvt_pk_bf16_f32 v110, v1, v110
	v_cvt_pk_bf16_f32 v111, v111, v112
	v_cvt_pk_bf16_f32 v112, v114, v115
	v_cvt_pk_bf16_f32 v113, v116, v113
	global_store_dwordx4 v[134:135], v[110:113], off offset:256 sc0 sc1
	v_and_b32_e32 v117, 0xffff0000, v144
	v_lshlrev_b32_e32 v116, 16, v144
	v_and_b32_e32 v113, 0xffff0000, v142
	v_lshlrev_b32_e32 v112, 16, v142
	v_pk_fma_f32 v[102:103], v[30:31], v[112:113], v[102:103]
	v_pk_fma_f32 v[98:99], v[26:27], v[116:117], v[98:99]
	v_mul_f32_e32 v1, 0x3d372713, v102
	v_mul_f32_e32 v112, 0x3d372713, v98
	v_mul_f32_e32 v113, 0x3d372713, v103
	v_mul_f32_e32 v1, v102, v1
	v_mul_f32_e32 v112, v98, v112
	v_mul_f32_e32 v113, v103, v113
	v_fma_f32 v1, v102, v1, v102
	v_fma_f32 v112, v98, v112, v98
	v_fma_f32 v113, v103, v113, v103
	v_mul_f32_e32 v1, 0x3f4c422a, v1
	v_mul_f32_e32 v112, 0x3f4c422a, v112
	v_mul_f32_e32 v113, 0x3f4c422a, v113
	v_add_f32_e32 v1, v1, v1
	v_add_f32_e32 v112, v112, v112
	v_add_f32_e32 v113, v113, v113
	v_mul_f32_e32 v1, 0xbfb8aa3b, v1
	v_mul_f32_e32 v112, 0xbfb8aa3b, v112
	v_mul_f32_e32 v113, 0xbfb8aa3b, v113
	v_exp_f32_e32 v1, v1
	v_exp_f32_e32 v112, v112
	v_exp_f32_e32 v113, v113
	v_and_b32_e32 v115, 0xffff0000, v143
	v_lshlrev_b32_e32 v114, 16, v143
	v_pk_fma_f32 v[104:105], v[32:33], v[114:115], v[104:105]
	v_add_f32_e32 v1, 1.0, v1
	v_add_f32_e32 v112, 1.0, v112
	v_add_f32_e32 v113, 1.0, v113
	v_mul_f32_e32 v114, 0x3d372713, v99
	v_rcp_f32_e32 v1, v1
	v_rcp_f32_e32 v112, v112
	v_rcp_f32_e32 v113, v113
	v_mul_f32_e32 v114, v99, v114
	v_fma_f32 v114, v99, v114, v99
	v_and_b32_e32 v123, 0xffff0000, v145
	v_lshlrev_b32_e32 v122, 16, v145
	v_mul_f32_e32 v114, 0x3f4c422a, v114
	v_pk_fma_f32 v[100:101], v[28:29], v[122:123], v[100:101]
	v_add_f32_e32 v114, v114, v114
	v_mul_f32_e32 v114, 0xbfb8aa3b, v114
	v_mul_f32_e32 v1, v102, v1
	v_mul_f32_e32 v102, v98, v112
	v_mul_f32_e32 v98, v103, v113
	v_mul_f32_e32 v112, 0x3d372713, v104
	v_mul_f32_e32 v113, 0x3d372713, v100
	v_exp_f32_e32 v114, v114
	v_mul_f32_e32 v112, v104, v112
	v_mul_f32_e32 v113, v100, v113
; __device__ __forceinline__ float gelu_tanh_f(float y) { const float t = 0.7978845608028654f * (y + 0.044715f * y * y * y); return y * fast_sigmoid(2.f * t); }
; __device__ __forceinline__ u32x4 pack8(const f32x4 v0, const f32x4 v1) { u32x4 w; w.x = pk_f16(v0[0], v0[1]); w.y = pk_f16(v0[2], v0[3]); w.z = pk_f16(v1[0], v1[1]); w.w = pk_f16(v1[2], v1[3]); return w; }
; __device__ __forceinline__ void unpack8(const u32x4 w, f32x4& v0, f32x4& v1) { v0 = (f32x4){f16lo(w.x), f16hi(w.x), f16lo(w.y), f16hi(w.y)}; v1 = (f32x4){f16lo(w.z), f16hi(w.z), f16lo(w.w), f16hi(w.w)}; }
;     __device__ __forceinline__ void operator()(AccRef acc, const Unit& u, int wr, int wc, int fr, int fq) const {
;     ...
;             for (int m = 0; m < 4; ++m)
; #pragma unroll
;                 for (int bj = 0; bj < 2; ++bj) { f32x4 u0, u1; unpack8(uv[m][bj], u0, u1);
;                     f32x4 v0 = acc[ai][bj][m][0] + d0 * u0, v1 = acc[ai][bj][m][1] + d1 * u1;
; #pragma unroll
;                     for (int j = 0; j < 4; ++j) { v0[j] = gelu_tanh_f(v0[j]); v1[j] = gelu_tanh_f(v1[j]); }
;                     *(u32x4*)(Yg + (size_t)(row0 + ai * HALF + m * 16) * 512 + bj * HALF) = pack8(v0, v1); } }
	v_fma_f32 v112, v104, v112, v104
	v_fma_f32 v113, v100, v113, v100
	v_mul_f32_e32 v112, 0x3f4c422a, v112
	v_mul_f32_e32 v113, 0x3f4c422a, v113
	v_add_f32_e32 v112, v112, v112
	v_add_f32_e32 v113, v113, v113
	v_add_f32_e32 v103, 1.0, v114
	v_mul_f32_e32 v112, 0xbfb8aa3b, v112
	v_mul_f32_e32 v113, 0xbfb8aa3b, v113
	v_rcp_f32_e32 v103, v103
	v_exp_f32_e32 v112, v112
	v_exp_f32_e32 v113, v113
	v_mul_f32_e32 v114, 0x3d372713, v101
	v_mul_f32_e32 v103, v99, v103
	v_add_f32_e32 v99, 1.0, v112
	v_add_f32_e32 v112, 1.0, v113
	v_mul_f32_e32 v113, 0x3d372713, v105
	v_mul_f32_e32 v113, v105, v113
	v_mul_f32_e32 v114, v101, v114
	v_fma_f32 v113, v105, v113, v105
	v_fma_f32 v114, v101, v114, v101
	v_mul_f32_e32 v113, 0x3f4c422a, v113
	v_mul_f32_e32 v114, 0x3f4c422a, v114
	v_add_f32_e32 v113, v113, v113
	v_add_f32_e32 v114, v114, v114
	v_mul_f32_e32 v113, 0xbfb8aa3b, v113
	v_mul_f32_e32 v114, 0xbfb8aa3b, v114
	v_exp_f32_e32 v113, v113
	v_exp_f32_e32 v114, v114
	v_rcp_f32_e32 v99, v99
	v_rcp_f32_e32 v112, v112
	v_add_f32_e32 v113, 1.0, v113
	v_add_f32_e32 v114, 1.0, v114
	v_rcp_f32_e32 v113, v113
	v_rcp_f32_e32 v114, v114
	v_lshlrev_b64 v[110:111], 10, v[170:171]
	v_mul_f32_e32 v99, v104, v99
	v_mul_f32_e32 v104, v100, v112
	v_mul_f32_e32 v100, v105, v113
	v_mul_f32_e32 v101, v101, v114
	v_lshl_add_u64 v[110:111], v[162:163], 0, v[110:111]
	v_cvt_pk_bf16_f32 v98, v1, v98
	v_cvt_pk_bf16_f32 v99, v99, v100
	v_cvt_pk_bf16_f32 v100, v102, v103
	v_cvt_pk_bf16_f32 v101, v104, v101
	global_store_dwordx4 v[110:111], v[98:101], off sc0 sc1
	v_and_b32_e32 v103, 0xffff0000, v132
	v_lshlrev_b32_e32 v102, 16, v132
	v_and_b32_e32 v99, 0xffff0000, v130
	v_lshlrev_b32_e32 v98, 16, v130
	v_pk_fma_f32 v[94:95], v[30:31], v[98:99], v[94:95]
	v_pk_fma_f32 v[90:91], v[26:27], v[102:103], v[90:91]
	v_mul_f32_e32 v1, 0x3d372713, v94
	v_mul_f32_e32 v98, 0x3d372713, v90
	v_mul_f32_e32 v99, 0x3d372713, v95
	v_mul_f32_e32 v1, v94, v1
	v_mul_f32_e32 v98, v90, v98
	v_mul_f32_e32 v99, v95, v99
	v_fma_f32 v1, v94, v1, v94
	v_fma_f32 v98, v90, v98, v90
	v_fma_f32 v99, v95, v99, v95
	v_mul_f32_e32 v1, 0x3f4c422a, v1
	v_mul_f32_e32 v98, 0x3f4c422a, v98
	v_mul_f32_e32 v99, 0x3f4c422a, v99
	v_add_f32_e32 v1, v1, v1
	v_add_f32_e32 v98, v98, v98
	v_add_f32_e32 v99, v99, v99
	v_mul_f32_e32 v1, 0xbfb8aa3b, v1
	v_mul_f32_e32 v98, 0xbfb8aa3b, v98
	v_mul_f32_e32 v99, 0xbfb8aa3b, v99
	v_exp_f32_e32 v1, v1
	v_exp_f32_e32 v98, v98
	v_exp_f32_e32 v99, v99
	v_and_b32_e32 v101, 0xffff0000, v131
	v_lshlrev_b32_e32 v100, 16, v131
	v_pk_fma_f32 v[96:97], v[32:33], v[100:101], v[96:97]
	v_add_f32_e32 v1, 1.0, v1
	v_add_f32_e32 v98, 1.0, v98
	v_add_f32_e32 v99, 1.0, v99
	v_mul_f32_e32 v100, 0x3d372713, v91
	v_rcp_f32_e32 v1, v1
	v_rcp_f32_e32 v98, v98
	v_rcp_f32_e32 v99, v99
	v_mul_f32_e32 v100, v91, v100
	v_fma_f32 v100, v91, v100, v91
	v_and_b32_e32 v105, 0xffff0000, v133
	v_lshlrev_b32_e32 v104, 16, v133
	v_mul_f32_e32 v100, 0x3f4c422a, v100
	v_pk_fma_f32 v[92:93], v[28:29], v[104:105], v[92:93]
	v_add_f32_e32 v100, v100, v100
	v_mul_f32_e32 v100, 0xbfb8aa3b, v100
	v_mul_f32_e32 v1, v94, v1
	v_mul_f32_e32 v94, v90, v98
	v_mul_f32_e32 v90, v95, v99
	v_mul_f32_e32 v98, 0x3d372713, v96
	v_mul_f32_e32 v99, 0x3d372713, v92
	v_exp_f32_e32 v100, v100
	v_mul_f32_e32 v98, v96, v98
	v_mul_f32_e32 v99, v92, v99
	v_fma_f32 v98, v96, v98, v96
	v_fma_f32 v99, v92, v99, v92
	v_mul_f32_e32 v98, 0x3f4c422a, v98
	v_mul_f32_e32 v99, 0x3f4c422a, v99
	v_add_f32_e32 v98, v98, v98
	v_add_f32_e32 v99, v99, v99
	v_add_f32_e32 v95, 1.0, v100
	v_mul_f32_e32 v98, 0xbfb8aa3b, v98
	v_mul_f32_e32 v99, 0xbfb8aa3b, v99
	v_rcp_f32_e32 v95, v95
	v_exp_f32_e32 v98, v98
	v_exp_f32_e32 v99, v99
	v_mul_f32_e32 v100, 0x3d372713, v93
	v_mul_f32_e32 v95, v91, v95
	v_add_f32_e32 v91, 1.0, v98
	v_add_f32_e32 v98, 1.0, v99
	v_mul_f32_e32 v99, 0x3d372713, v97
	v_mul_f32_e32 v99, v97, v99
	v_mul_f32_e32 v100, v93, v100
	v_fma_f32 v99, v97, v99, v97
	v_fma_f32 v100, v93, v100, v93
	v_mul_f32_e32 v99, 0x3f4c422a, v99
	v_mul_f32_e32 v100, 0x3f4c422a, v100
	v_add_f32_e32 v99, v99, v99
	v_add_f32_e32 v100, v100, v100
	v_mul_f32_e32 v99, 0xbfb8aa3b, v99
	v_mul_f32_e32 v100, 0xbfb8aa3b, v100
	v_exp_f32_e32 v99, v99
	v_exp_f32_e32 v100, v100
	v_rcp_f32_e32 v91, v91
	v_rcp_f32_e32 v98, v98
	v_add_f32_e32 v99, 1.0, v99
	v_add_f32_e32 v100, 1.0, v100
	v_rcp_f32_e32 v99, v99
	v_rcp_f32_e32 v100, v100
	v_mul_f32_e32 v91, v96, v91
	v_mul_f32_e32 v96, v92, v98
	v_mul_f32_e32 v92, v97, v99
	v_mul_f32_e32 v93, v93, v100
	v_cvt_pk_bf16_f32 v90, v1, v90
	v_cvt_pk_bf16_f32 v91, v91, v92
	v_cvt_pk_bf16_f32 v92, v94, v95
	v_cvt_pk_bf16_f32 v93, v96, v93
	global_store_dwordx4 v[110:111], v[90:93], off offset:256 sc0 sc1
	v_and_b32_e32 v97, 0xffff0000, v120
	v_lshlrev_b32_e32 v96, 16, v120
	v_and_b32_e32 v93, 0xffff0000, v118
	v_lshlrev_b32_e32 v92, 16, v118
	v_pk_fma_f32 v[86:87], v[30:31], v[92:93], v[86:87]
	v_pk_fma_f32 v[82:83], v[26:27], v[96:97], v[82:83]
	v_mul_f32_e32 v1, 0x3d372713, v86
	v_mul_f32_e32 v92, 0x3d372713, v82
	v_mul_f32_e32 v93, 0x3d372713, v87
	v_mul_f32_e32 v1, v86, v1
	v_mul_f32_e32 v92, v82, v92
	v_mul_f32_e32 v93, v87, v93
	v_fma_f32 v1, v86, v1, v86
	v_fma_f32 v92, v82, v92, v82
	v_fma_f32 v93, v87, v93, v87
	v_mul_f32_e32 v1, 0x3f4c422a, v1
	v_mul_f32_e32 v92, 0x3f4c422a, v92
	v_mul_f32_e32 v93, 0x3f4c422a, v93
	v_add_f32_e32 v1, v1, v1
	v_add_f32_e32 v92, v92, v92
	v_add_f32_e32 v93, v93, v93
	v_mul_f32_e32 v1, 0xbfb8aa3b, v1
	v_mul_f32_e32 v92, 0xbfb8aa3b, v92
	v_mul_f32_e32 v93, 0xbfb8aa3b, v93
	v_exp_f32_e32 v1, v1
	v_exp_f32_e32 v92, v92
	v_exp_f32_e32 v93, v93
	v_and_b32_e32 v95, 0xffff0000, v119
	v_lshlrev_b32_e32 v94, 16, v119
; __device__ __forceinline__ float gelu_tanh_f(float y) { const float t = 0.7978845608028654f * (y + 0.044715f * y * y * y); return y * fast_sigmoid(2.f * t); }
; __device__ __forceinline__ u32x4 pack8(const f32x4 v0, const f32x4 v1) { u32x4 w; w.x = pk_f16(v0[0], v0[1]); w.y = pk_f16(v0[2], v0[3]); w.z = pk_f16(v1[0], v1[1]); w.w = pk_f16(v1[2], v1[3]); return w; }
; __device__ __forceinline__ void unpack8(const u32x4 w, f32x4& v0, f32x4& v1) { v0 = (f32x4){f16lo(w.x), f16hi(w.x), f16lo(w.y), f16hi(w.y)}; v1 = (f32x4){f16lo(w.z), f16hi(w.z), f16lo(w.w), f16hi(w.w)}; }
;     __device__ __forceinline__ void operator()(AccRef acc, const Unit& u, int wr, int wc, int fr, int fq) const {
;     ...
;         for (int ai = 0; ai < 2; ++ai) { u32x4 uv[4][2];
; #pragma unroll
;             for (int m = 0; m < 4; ++m)
; #pragma unroll
;                 for (int bj = 0; bj < 2; ++bj) uv[m][bj] = *(const u32x4*)(Xg + (size_t)(row0 + ai * HALF + m * 16) * XK + bj * HALF);
;             __builtin_amdgcn_sched_barrier(0);
; #pragma unroll
;             for (int m = 0; m < 4; ++m)
; #pragma unroll
;                 for (int bj = 0; bj < 2; ++bj) { f32x4 u0, u1; unpack8(uv[m][bj], u0, u1);
;                     f32x4 v0 = acc[ai][bj][m][0] + d0 * u0, v1 = acc[ai][bj][m][1] + d1 * u1;
; #pragma unroll
;                     for (int j = 0; j < 4; ++j) { v0[j] = gelu_tanh_f(v0[j]); v1[j] = gelu_tanh_f(v1[j]); }
;                     *(u32x4*)(Yg + (size_t)(row0 + ai * HALF + m * 16) * 512 + bj * HALF) = pack8(v0, v1); } }
	v_pk_fma_f32 v[88:89], v[32:33], v[94:95], v[88:89]
	v_add_f32_e32 v1, 1.0, v1
	v_add_f32_e32 v92, 1.0, v92
	v_add_f32_e32 v93, 1.0, v93
	v_mul_f32_e32 v94, 0x3d372713, v83
	v_rcp_f32_e32 v1, v1
	v_rcp_f32_e32 v92, v92
	v_rcp_f32_e32 v93, v93
	v_mul_f32_e32 v94, v83, v94
	v_fma_f32 v94, v83, v94, v83
	v_and_b32_e32 v99, 0xffff0000, v121
	v_lshlrev_b32_e32 v98, 16, v121
	v_mul_f32_e32 v94, 0x3f4c422a, v94
	v_pk_fma_f32 v[84:85], v[28:29], v[98:99], v[84:85]
	v_add_f32_e32 v94, v94, v94
	v_mul_f32_e32 v94, 0xbfb8aa3b, v94
	v_mul_f32_e32 v1, v86, v1
	v_mul_f32_e32 v86, v82, v92
	v_mul_f32_e32 v82, v87, v93
	v_mul_f32_e32 v92, 0x3d372713, v88
	v_mul_f32_e32 v93, 0x3d372713, v84
	v_exp_f32_e32 v94, v94
	v_mul_f32_e32 v92, v88, v92
	v_mul_f32_e32 v93, v84, v93
	v_fma_f32 v92, v88, v92, v88
	v_fma_f32 v93, v84, v93, v84
	v_mul_f32_e32 v92, 0x3f4c422a, v92
	v_mul_f32_e32 v93, 0x3f4c422a, v93
	v_add_f32_e32 v92, v92, v92
	v_add_f32_e32 v93, v93, v93
	v_add_f32_e32 v87, 1.0, v94
	v_mul_f32_e32 v92, 0xbfb8aa3b, v92
	v_mul_f32_e32 v93, 0xbfb8aa3b, v93
	v_rcp_f32_e32 v87, v87
	v_exp_f32_e32 v92, v92
	v_exp_f32_e32 v93, v93
	v_mul_f32_e32 v94, 0x3d372713, v85
	v_mul_f32_e32 v87, v83, v87
	v_add_f32_e32 v83, 1.0, v92
	v_add_f32_e32 v92, 1.0, v93
	v_mul_f32_e32 v93, 0x3d372713, v89
	v_mul_f32_e32 v93, v89, v93
	v_mul_f32_e32 v94, v85, v94
	v_fma_f32 v93, v89, v93, v89
	v_fma_f32 v94, v85, v94, v85
	v_mul_f32_e32 v93, 0x3f4c422a, v93
	v_mul_f32_e32 v94, 0x3f4c422a, v94
	v_add_f32_e32 v93, v93, v93
	v_add_f32_e32 v94, v94, v94
	v_mul_f32_e32 v93, 0xbfb8aa3b, v93
	v_mul_f32_e32 v94, 0xbfb8aa3b, v94
	v_exp_f32_e32 v93, v93
	v_exp_f32_e32 v94, v94
	v_rcp_f32_e32 v83, v83
	v_rcp_f32_e32 v92, v92
	v_add_f32_e32 v93, 1.0, v93
	v_add_f32_e32 v94, 1.0, v94
	v_rcp_f32_e32 v93, v93
	v_rcp_f32_e32 v94, v94
	v_lshlrev_b64 v[90:91], 10, v[168:169]
	v_mul_f32_e32 v83, v88, v83
	v_mul_f32_e32 v88, v84, v92
	v_mul_f32_e32 v84, v89, v93
	v_mul_f32_e32 v85, v85, v94
	v_lshl_add_u64 v[90:91], v[162:163], 0, v[90:91]
	v_cvt_pk_bf16_f32 v82, v1, v82
	v_cvt_pk_bf16_f32 v83, v83, v84
	v_cvt_pk_bf16_f32 v84, v86, v87
	v_cvt_pk_bf16_f32 v85, v88, v85
	global_store_dwordx4 v[90:91], v[82:85], off sc0 sc1
	v_and_b32_e32 v87, 0xffff0000, v108
	v_lshlrev_b32_e32 v86, 16, v108
	v_and_b32_e32 v83, 0xffff0000, v106
	v_lshlrev_b32_e32 v82, 16, v106
	v_pk_fma_f32 v[78:79], v[30:31], v[82:83], v[78:79]
	v_pk_fma_f32 v[74:75], v[26:27], v[86:87], v[74:75]
	v_mul_f32_e32 v1, 0x3d372713, v78
	v_mul_f32_e32 v82, 0x3d372713, v74
	v_mul_f32_e32 v83, 0x3d372713, v79
	v_mul_f32_e32 v1, v78, v1
	v_mul_f32_e32 v82, v74, v82
	v_mul_f32_e32 v83, v79, v83
	v_fma_f32 v1, v78, v1, v78
	v_fma_f32 v82, v74, v82, v74
	v_fma_f32 v83, v79, v83, v79
	v_mul_f32_e32 v1, 0x3f4c422a, v1
	v_mul_f32_e32 v82, 0x3f4c422a, v82
	v_mul_f32_e32 v83, 0x3f4c422a, v83
	v_add_f32_e32 v1, v1, v1
	v_add_f32_e32 v82, v82, v82
	v_add_f32_e32 v83, v83, v83
	v_mul_f32_e32 v1, 0xbfb8aa3b, v1
	v_mul_f32_e32 v82, 0xbfb8aa3b, v82
	v_mul_f32_e32 v83, 0xbfb8aa3b, v83
	v_exp_f32_e32 v1, v1
	v_exp_f32_e32 v82, v82
	v_exp_f32_e32 v83, v83
	v_and_b32_e32 v85, 0xffff0000, v107
	v_lshlrev_b32_e32 v84, 16, v107
	v_pk_fma_f32 v[80:81], v[32:33], v[84:85], v[80:81]
	v_add_f32_e32 v1, 1.0, v1
	v_add_f32_e32 v82, 1.0, v82
	v_add_f32_e32 v83, 1.0, v83
	v_mul_f32_e32 v84, 0x3d372713, v75
	v_rcp_f32_e32 v1, v1
	v_rcp_f32_e32 v82, v82
	v_rcp_f32_e32 v83, v83
	v_mul_f32_e32 v84, v75, v84
	v_fma_f32 v84, v75, v84, v75
	v_and_b32_e32 v89, 0xffff0000, v109
	v_lshlrev_b32_e32 v88, 16, v109
	v_mul_f32_e32 v84, 0x3f4c422a, v84
	v_pk_fma_f32 v[76:77], v[28:29], v[88:89], v[76:77]
	v_add_f32_e32 v84, v84, v84
	v_mul_f32_e32 v84, 0xbfb8aa3b, v84
	v_mul_f32_e32 v1, v78, v1
	v_mul_f32_e32 v78, v74, v82
	v_mul_f32_e32 v74, v79, v83
	v_mul_f32_e32 v82, 0x3d372713, v80
	v_mul_f32_e32 v83, 0x3d372713, v76
	v_exp_f32_e32 v84, v84
	v_mul_f32_e32 v82, v80, v82
	v_mul_f32_e32 v83, v76, v83
	v_fma_f32 v82, v80, v82, v80
	v_fma_f32 v83, v76, v83, v76
	v_mul_f32_e32 v82, 0x3f4c422a, v82
	v_mul_f32_e32 v83, 0x3f4c422a, v83
	v_add_f32_e32 v82, v82, v82
	v_add_f32_e32 v83, v83, v83
	v_add_f32_e32 v79, 1.0, v84
	v_mul_f32_e32 v82, 0xbfb8aa3b, v82
	v_mul_f32_e32 v83, 0xbfb8aa3b, v83
	v_rcp_f32_e32 v79, v79
	v_exp_f32_e32 v82, v82
	v_exp_f32_e32 v83, v83
	v_mul_f32_e32 v84, 0x3d372713, v77
	v_mul_f32_e32 v79, v75, v79
	v_add_f32_e32 v75, 1.0, v82
	v_add_f32_e32 v82, 1.0, v83
	v_mul_f32_e32 v83, 0x3d372713, v81
	v_mul_f32_e32 v83, v81, v83
	v_mul_f32_e32 v84, v77, v84
	v_fma_f32 v83, v81, v83, v81
	v_fma_f32 v84, v77, v84, v77
	v_mul_f32_e32 v83, 0x3f4c422a, v83
	v_mul_f32_e32 v84, 0x3f4c422a, v84
	v_add_f32_e32 v83, v83, v83
	v_add_f32_e32 v84, v84, v84
	v_mul_f32_e32 v83, 0xbfb8aa3b, v83
	v_mul_f32_e32 v84, 0xbfb8aa3b, v84
	v_exp_f32_e32 v83, v83
	v_exp_f32_e32 v84, v84
	v_rcp_f32_e32 v75, v75
	v_rcp_f32_e32 v82, v82
	v_add_f32_e32 v83, 1.0, v83
	v_add_f32_e32 v84, 1.0, v84
	v_rcp_f32_e32 v83, v83
	v_rcp_f32_e32 v84, v84
	v_mul_f32_e32 v75, v80, v75
	v_mul_f32_e32 v80, v76, v82
	v_mul_f32_e32 v76, v81, v83
	v_mul_f32_e32 v77, v77, v84
	v_cvt_pk_bf16_f32 v74, v1, v74
	v_cvt_pk_bf16_f32 v75, v75, v76
	v_cvt_pk_bf16_f32 v76, v78, v79
	v_cvt_pk_bf16_f32 v77, v80, v77
	v_add_u32_e32 v104, 0x80, v164
	global_store_dwordx4 v[90:91], v[74:77], off offset:256 sc0 sc1
	v_add_u32_e32 v102, 0x90, v164
	v_add_u32_e32 v100, 0xa0, v164
	v_mad_i64_i32 v[74:75], s[2:3], v104, s0, v[166:167]
	global_load_dwordx4 v[106:109], v[74:75], off offset:512
	global_load_dwordx4 v[110:113], v[74:75], off offset:768
	v_mad_i64_i32 v[74:75], s[2:3], v102, s0, v[166:167]
	v_add_u32_e32 v98, 0xb0, v164
	global_load_dwordx4 v[94:97], v[74:75], off offset:512
	global_load_dwordx4 v[90:93], v[74:75], off offset:768
	v_mad_i64_i32 v[74:75], s[2:3], v100, s0, v[166:167]
	v_mad_i64_i32 v[114:115], s[0:1], v98, s0, v[166:167]
	global_load_dwordx4 v[86:89], v[74:75], off offset:512
	global_load_dwordx4 v[82:85], v[74:75], off offset:768
	global_load_dwordx4 v[78:81], v[114:115], off offset:512
	s_nop 0
	global_load_dwordx4 v[74:77], v[114:115], off offset:768
	v_ashrrev_i32_e32 v105, 31, v104
	v_ashrrev_i32_e32 v103, 31, v102
	v_ashrrev_i32_e32 v101, 31, v100
	v_ashrrev_i32_e32 v99, 31, v98
	s_waitcnt vmcnt(7)
; __device__ __forceinline__ float gelu_tanh_f(float y) { const float t = 0.7978845608028654f * (y + 0.044715f * y * y * y); return y * fast_sigmoid(2.f * t); }
; __device__ __forceinline__ u32x4 pack8(const f32x4 v0, const f32x4 v1) { u32x4 w; w.x = pk_f16(v0[0], v0[1]); w.y = pk_f16(v0[2], v0[3]); w.z = pk_f16(v1[0], v1[1]); w.w = pk_f16(v1[2], v1[3]); return w; }
; __device__ __forceinline__ void unpack8(const u32x4 w, f32x4& v0, f32x4& v1) { v0 = (f32x4){f16lo(w.x), f16hi(w.x), f16lo(w.y), f16hi(w.y)}; v1 = (f32x4){f16lo(w.z), f16hi(w.z), f16lo(w.w), f16hi(w.w)}; }
;     __device__ __forceinline__ void operator()(AccRef acc, const Unit& u, int wr, int wc, int fr, int fq) const {
;     ...
;         for (int ai = 0; ai < 2; ++ai) { u32x4 uv[4][2];
; #pragma unroll
;             for (int m = 0; m < 4; ++m)
; #pragma unroll
;                 for (int bj = 0; bj < 2; ++bj) uv[m][bj] = *(const u32x4*)(Xg + (size_t)(row0 + ai * HALF + m * 16) * XK + bj * HALF);
;             __builtin_amdgcn_sched_barrier(0);
; #pragma unroll
;             for (int m = 0; m < 4; ++m)
; #pragma unroll
;                 for (int bj = 0; bj < 2; ++bj) { f32x4 u0, u1; unpack8(uv[m][bj], u0, u1);
;                     f32x4 v0 = acc[ai][bj][m][0] + d0 * u0, v1 = acc[ai][bj][m][1] + d1 * u1;
; #pragma unroll
;                     for (int j = 0; j < 4; ++j) { v0[j] = gelu_tanh_f(v0[j]); v1[j] = gelu_tanh_f(v1[j]); }
;                     *(u32x4*)(Yg + (size_t)(row0 + ai * HALF + m * 16) * 512 + bj * HALF) = pack8(v0, v1); } }
	v_and_b32_e32 v115, 0xffff0000, v106
	v_lshlrev_b32_e32 v114, 16, v106
	v_and_b32_e32 v117, 0xffff0000, v107
	v_lshlrev_b32_e32 v116, 16, v107
	v_and_b32_e32 v107, 0xffff0000, v108
	v_lshlrev_b32_e32 v106, 16, v108
	v_pk_fma_f32 v[70:71], v[30:31], v[114:115], v[70:71]
	v_pk_fma_f32 v[66:67], v[26:27], v[106:107], v[66:67]
	v_mul_f32_e32 v1, 0x3d372713, v70
	v_mul_f32_e32 v106, 0x3d372713, v66
	v_mul_f32_e32 v107, 0x3d372713, v71
	v_mul_f32_e32 v1, v70, v1
	v_mul_f32_e32 v106, v66, v106
	v_mul_f32_e32 v107, v71, v107
	v_fma_f32 v1, v70, v1, v70
	v_fma_f32 v106, v66, v106, v66
	v_fma_f32 v107, v71, v107, v71
	v_mul_f32_e32 v1, 0x3f4c422a, v1
	v_mul_f32_e32 v106, 0x3f4c422a, v106
	v_mul_f32_e32 v107, 0x3f4c422a, v107
	v_add_f32_e32 v1, v1, v1
	v_add_f32_e32 v106, v106, v106
	v_add_f32_e32 v107, v107, v107
	v_mul_f32_e32 v1, 0xbfb8aa3b, v1
	v_mul_f32_e32 v106, 0xbfb8aa3b, v106
	v_mul_f32_e32 v107, 0xbfb8aa3b, v107
	v_exp_f32_e32 v1, v1
	v_exp_f32_e32 v106, v106
	v_exp_f32_e32 v107, v107
	v_mul_f32_e32 v108, 0x3d372713, v67
	v_add_f32_e32 v1, 1.0, v1
	v_add_f32_e32 v106, 1.0, v106
	v_add_f32_e32 v107, 1.0, v107
	v_rcp_f32_e32 v1, v1
	v_rcp_f32_e32 v106, v106
	v_rcp_f32_e32 v107, v107
	v_mul_f32_e32 v108, v67, v108
	v_fma_f32 v108, v67, v108, v67
	v_and_b32_e32 v119, 0xffff0000, v109
	v_lshlrev_b32_e32 v118, 16, v109
	v_mul_f32_e32 v108, 0x3f4c422a, v108
	v_pk_fma_f32 v[72:73], v[32:33], v[116:117], v[72:73]
	v_pk_fma_f32 v[68:69], v[28:29], v[118:119], v[68:69]
	v_add_f32_e32 v108, v108, v108
	v_mul_f32_e32 v108, 0xbfb8aa3b, v108
	v_mul_f32_e32 v1, v70, v1
	v_mul_f32_e32 v70, v66, v106
	v_mul_f32_e32 v66, v71, v107
	v_mul_f32_e32 v106, 0x3d372713, v72
	v_mul_f32_e32 v107, 0x3d372713, v68
	v_exp_f32_e32 v108, v108
	v_mul_f32_e32 v106, v72, v106
	v_mul_f32_e32 v107, v68, v107
	v_fma_f32 v106, v72, v106, v72
	v_fma_f32 v107, v68, v107, v68
	v_mul_f32_e32 v106, 0x3f4c422a, v106
	v_mul_f32_e32 v107, 0x3f4c422a, v107
	v_add_f32_e32 v106, v106, v106
	v_add_f32_e32 v107, v107, v107
	v_add_f32_e32 v71, 1.0, v108
	v_mul_f32_e32 v106, 0xbfb8aa3b, v106
	v_mul_f32_e32 v107, 0xbfb8aa3b, v107
	v_rcp_f32_e32 v71, v71
	v_exp_f32_e32 v106, v106
	v_exp_f32_e32 v107, v107
	v_mul_f32_e32 v108, 0x3d372713, v69
	v_mul_f32_e32 v71, v67, v71
	v_add_f32_e32 v67, 1.0, v106
	v_add_f32_e32 v106, 1.0, v107
	v_mul_f32_e32 v107, 0x3d372713, v73
	v_mul_f32_e32 v107, v73, v107
	v_mul_f32_e32 v108, v69, v108
	v_fma_f32 v107, v73, v107, v73
	v_fma_f32 v108, v69, v108, v69
	v_mul_f32_e32 v107, 0x3f4c422a, v107
	v_mul_f32_e32 v108, 0x3f4c422a, v108
	v_add_f32_e32 v107, v107, v107
	v_add_f32_e32 v108, v108, v108
	v_mul_f32_e32 v107, 0xbfb8aa3b, v107
	v_mul_f32_e32 v108, 0xbfb8aa3b, v108
	v_exp_f32_e32 v107, v107
	v_exp_f32_e32 v108, v108
	v_rcp_f32_e32 v67, v67
	v_rcp_f32_e32 v106, v106
	v_add_f32_e32 v107, 1.0, v107
	v_add_f32_e32 v108, 1.0, v108
	v_rcp_f32_e32 v107, v107
	v_rcp_f32_e32 v108, v108
	v_lshlrev_b64 v[104:105], 10, v[104:105]
	v_mul_f32_e32 v67, v72, v67
	v_mul_f32_e32 v72, v68, v106
	v_mul_f32_e32 v68, v73, v107
	v_mul_f32_e32 v69, v69, v108
	v_lshl_add_u64 v[104:105], v[162:163], 0, v[104:105]
	v_cvt_pk_bf16_f32 v66, v1, v66
	v_cvt_pk_bf16_f32 v67, v67, v68
	v_cvt_pk_bf16_f32 v68, v70, v71
	v_cvt_pk_bf16_f32 v69, v72, v69
	global_store_dwordx4 v[104:105], v[66:69], off sc0 sc1
	s_waitcnt vmcnt(7)
	v_and_b32_e32 v71, 0xffff0000, v112
	v_lshlrev_b32_e32 v70, 16, v112
	v_and_b32_e32 v67, 0xffff0000, v110
	v_lshlrev_b32_e32 v66, 16, v110
	v_pk_fma_f32 v[62:63], v[30:31], v[66:67], v[62:63]
	v_pk_fma_f32 v[58:59], v[26:27], v[70:71], v[58:59]
	v_mul_f32_e32 v1, 0x3d372713, v62
	v_mul_f32_e32 v66, 0x3d372713, v58
	v_mul_f32_e32 v67, 0x3d372713, v63
	v_mul_f32_e32 v1, v62, v1
	v_mul_f32_e32 v66, v58, v66
	v_mul_f32_e32 v67, v63, v67
	v_fma_f32 v1, v62, v1, v62
	v_fma_f32 v66, v58, v66, v58
	v_fma_f32 v67, v63, v67, v63
	v_mul_f32_e32 v1, 0x3f4c422a, v1
	v_mul_f32_e32 v66, 0x3f4c422a, v66
	v_mul_f32_e32 v67, 0x3f4c422a, v67
	v_add_f32_e32 v1, v1, v1
	v_add_f32_e32 v66, v66, v66
	v_add_f32_e32 v67, v67, v67
	v_mul_f32_e32 v1, 0xbfb8aa3b, v1
	v_mul_f32_e32 v66, 0xbfb8aa3b, v66
	v_mul_f32_e32 v67, 0xbfb8aa3b, v67
	v_exp_f32_e32 v1, v1
	v_exp_f32_e32 v66, v66
	v_exp_f32_e32 v67, v67
	v_and_b32_e32 v69, 0xffff0000, v111
	v_lshlrev_b32_e32 v68, 16, v111
	v_pk_fma_f32 v[64:65], v[32:33], v[68:69], v[64:65]
	v_add_f32_e32 v1, 1.0, v1
	v_add_f32_e32 v66, 1.0, v66
	v_add_f32_e32 v67, 1.0, v67
	v_mul_f32_e32 v68, 0x3d372713, v59
	v_rcp_f32_e32 v1, v1
	v_rcp_f32_e32 v66, v66
	v_rcp_f32_e32 v67, v67
	v_mul_f32_e32 v68, v59, v68
	v_fma_f32 v68, v59, v68, v59
	v_and_b32_e32 v73, 0xffff0000, v113
	v_lshlrev_b32_e32 v72, 16, v113
	v_mul_f32_e32 v68, 0x3f4c422a, v68
	v_pk_fma_f32 v[60:61], v[28:29], v[72:73], v[60:61]
	v_add_f32_e32 v68, v68, v68
	v_mul_f32_e32 v68, 0xbfb8aa3b, v68
	v_mul_f32_e32 v1, v62, v1
	v_mul_f32_e32 v62, v58, v66
	v_mul_f32_e32 v58, v63, v67
	v_mul_f32_e32 v66, 0x3d372713, v64
	v_mul_f32_e32 v67, 0x3d372713, v60
	v_exp_f32_e32 v68, v68
	v_mul_f32_e32 v66, v64, v66
	v_mul_f32_e32 v67, v60, v67
	v_fma_f32 v66, v64, v66, v64
	v_fma_f32 v67, v60, v67, v60
	v_mul_f32_e32 v66, 0x3f4c422a, v66
	v_mul_f32_e32 v67, 0x3f4c422a, v67
	v_add_f32_e32 v66, v66, v66
	v_add_f32_e32 v67, v67, v67
	v_add_f32_e32 v63, 1.0, v68
	v_mul_f32_e32 v66, 0xbfb8aa3b, v66
	v_mul_f32_e32 v67, 0xbfb8aa3b, v67
	v_rcp_f32_e32 v63, v63
	v_exp_f32_e32 v66, v66
	v_exp_f32_e32 v67, v67
	v_mul_f32_e32 v68, 0x3d372713, v61
	v_mul_f32_e32 v63, v59, v63
	v_add_f32_e32 v59, 1.0, v66
	v_add_f32_e32 v66, 1.0, v67
	v_mul_f32_e32 v67, 0x3d372713, v65
	v_mul_f32_e32 v67, v65, v67
	v_mul_f32_e32 v68, v61, v68
	v_fma_f32 v67, v65, v67, v65
	v_fma_f32 v68, v61, v68, v61
	v_mul_f32_e32 v67, 0x3f4c422a, v67
	v_mul_f32_e32 v68, 0x3f4c422a, v68
	v_add_f32_e32 v67, v67, v67
	v_add_f32_e32 v68, v68, v68
	v_mul_f32_e32 v67, 0xbfb8aa3b, v67
	v_mul_f32_e32 v68, 0xbfb8aa3b, v68
	v_exp_f32_e32 v67, v67
	v_exp_f32_e32 v68, v68
	v_rcp_f32_e32 v59, v59
	v_rcp_f32_e32 v66, v66
	v_add_f32_e32 v67, 1.0, v67
	v_add_f32_e32 v68, 1.0, v68
	v_rcp_f32_e32 v67, v67
	v_rcp_f32_e32 v68, v68
	v_mul_f32_e32 v59, v64, v59
	v_mul_f32_e32 v64, v60, v66
	v_mul_f32_e32 v60, v65, v67
	v_mul_f32_e32 v61, v61, v68
	v_cvt_pk_bf16_f32 v58, v1, v58
	v_cvt_pk_bf16_f32 v59, v59, v60
	v_cvt_pk_bf16_f32 v60, v62, v63
	v_cvt_pk_bf16_f32 v61, v64, v61
	global_store_dwordx4 v[104:105], v[58:61], off offset:256 sc0 sc1
	s_waitcnt vmcnt(7)
; __device__ __forceinline__ float gelu_tanh_f(float y) { const float t = 0.7978845608028654f * (y + 0.044715f * y * y * y); return y * fast_sigmoid(2.f * t); }
; __device__ __forceinline__ u32x4 pack8(const f32x4 v0, const f32x4 v1) { u32x4 w; w.x = pk_f16(v0[0], v0[1]); w.y = pk_f16(v0[2], v0[3]); w.z = pk_f16(v1[0], v1[1]); w.w = pk_f16(v1[2], v1[3]); return w; }
; __device__ __forceinline__ void unpack8(const u32x4 w, f32x4& v0, f32x4& v1) { v0 = (f32x4){f16lo(w.x), f16hi(w.x), f16lo(w.y), f16hi(w.y)}; v1 = (f32x4){f16lo(w.z), f16hi(w.z), f16lo(w.w), f16hi(w.w)}; }
;     __device__ __forceinline__ void operator()(AccRef acc, const Unit& u, int wr, int wc, int fr, int fq) const {
;     ...
;         for (int ai = 0; ai < 2; ++ai) { u32x4 uv[4][2];
; #pragma unroll
;             for (int m = 0; m < 4; ++m)
; #pragma unroll
;                 for (int bj = 0; bj < 2; ++bj) uv[m][bj] = *(const u32x4*)(Xg + (size_t)(row0 + ai * HALF + m * 16) * XK + bj * HALF);
;             __builtin_amdgcn_sched_barrier(0);
; #pragma unroll
;             for (int m = 0; m < 4; ++m)
; #pragma unroll
;                 for (int bj = 0; bj < 2; ++bj) { f32x4 u0, u1; unpack8(uv[m][bj], u0, u1);
;                     f32x4 v0 = acc[ai][bj][m][0] + d0 * u0, v1 = acc[ai][bj][m][1] + d1 * u1;
; #pragma unroll
;                     for (int j = 0; j < 4; ++j) { v0[j] = gelu_tanh_f(v0[j]); v1[j] = gelu_tanh_f(v1[j]); }
;                     *(u32x4*)(Yg + (size_t)(row0 + ai * HALF + m * 16) * 512 + bj * HALF) = pack8(v0, v1); } }
	v_and_b32_e32 v65, 0xffff0000, v96
	v_lshlrev_b32_e32 v64, 16, v96
	v_and_b32_e32 v61, 0xffff0000, v94
	v_lshlrev_b32_e32 v60, 16, v94
	v_pk_fma_f32 v[54:55], v[30:31], v[60:61], v[54:55]
	v_pk_fma_f32 v[50:51], v[26:27], v[64:65], v[50:51]
	v_mul_f32_e32 v1, 0x3d372713, v54
	v_mul_f32_e32 v60, 0x3d372713, v50
	v_mul_f32_e32 v61, 0x3d372713, v55
	v_mul_f32_e32 v1, v54, v1
	v_mul_f32_e32 v60, v50, v60
	v_mul_f32_e32 v61, v55, v61
	v_fma_f32 v1, v54, v1, v54
	v_fma_f32 v60, v50, v60, v50
	v_fma_f32 v61, v55, v61, v55
	v_mul_f32_e32 v1, 0x3f4c422a, v1
	v_mul_f32_e32 v60, 0x3f4c422a, v60
	v_mul_f32_e32 v61, 0x3f4c422a, v61
	v_add_f32_e32 v1, v1, v1
	v_add_f32_e32 v60, v60, v60
	v_add_f32_e32 v61, v61, v61
	v_mul_f32_e32 v1, 0xbfb8aa3b, v1
	v_mul_f32_e32 v60, 0xbfb8aa3b, v60
	v_mul_f32_e32 v61, 0xbfb8aa3b, v61
	v_exp_f32_e32 v1, v1
	v_exp_f32_e32 v60, v60
	v_exp_f32_e32 v61, v61
	v_and_b32_e32 v63, 0xffff0000, v95
	v_lshlrev_b32_e32 v62, 16, v95
	v_pk_fma_f32 v[56:57], v[32:33], v[62:63], v[56:57]
	v_add_f32_e32 v1, 1.0, v1
	v_add_f32_e32 v60, 1.0, v60
	v_add_f32_e32 v61, 1.0, v61
	v_mul_f32_e32 v62, 0x3d372713, v51
	v_rcp_f32_e32 v1, v1
	v_rcp_f32_e32 v60, v60
	v_rcp_f32_e32 v61, v61
	v_mul_f32_e32 v62, v51, v62
	v_fma_f32 v62, v51, v62, v51
	v_and_b32_e32 v67, 0xffff0000, v97
	v_lshlrev_b32_e32 v66, 16, v97
	v_mul_f32_e32 v62, 0x3f4c422a, v62
	v_pk_fma_f32 v[52:53], v[28:29], v[66:67], v[52:53]
	v_add_f32_e32 v62, v62, v62
	v_mul_f32_e32 v62, 0xbfb8aa3b, v62
	v_mul_f32_e32 v1, v54, v1
	v_mul_f32_e32 v54, v50, v60
	v_mul_f32_e32 v50, v55, v61
	v_mul_f32_e32 v60, 0x3d372713, v56
	v_mul_f32_e32 v61, 0x3d372713, v52
	v_exp_f32_e32 v62, v62
	v_mul_f32_e32 v60, v56, v60
	v_mul_f32_e32 v61, v52, v61
	v_fma_f32 v60, v56, v60, v56
	v_fma_f32 v61, v52, v61, v52
	v_mul_f32_e32 v60, 0x3f4c422a, v60
	v_mul_f32_e32 v61, 0x3f4c422a, v61
	v_add_f32_e32 v60, v60, v60
	v_add_f32_e32 v61, v61, v61
	v_add_f32_e32 v55, 1.0, v62
	v_mul_f32_e32 v60, 0xbfb8aa3b, v60
	v_mul_f32_e32 v61, 0xbfb8aa3b, v61
	v_rcp_f32_e32 v55, v55
	v_exp_f32_e32 v60, v60
	v_exp_f32_e32 v61, v61
	v_mul_f32_e32 v62, 0x3d372713, v53
	v_mul_f32_e32 v55, v51, v55
	v_add_f32_e32 v51, 1.0, v60
	v_add_f32_e32 v60, 1.0, v61
	v_mul_f32_e32 v61, 0x3d372713, v57
	v_mul_f32_e32 v61, v57, v61
	v_mul_f32_e32 v62, v53, v62
	v_fma_f32 v61, v57, v61, v57
	v_fma_f32 v62, v53, v62, v53
	v_mul_f32_e32 v61, 0x3f4c422a, v61
	v_mul_f32_e32 v62, 0x3f4c422a, v62
	v_add_f32_e32 v61, v61, v61
	v_add_f32_e32 v62, v62, v62
	v_mul_f32_e32 v61, 0xbfb8aa3b, v61
	v_mul_f32_e32 v62, 0xbfb8aa3b, v62
	v_exp_f32_e32 v61, v61
	v_exp_f32_e32 v62, v62
	v_rcp_f32_e32 v51, v51
	v_rcp_f32_e32 v60, v60
	v_add_f32_e32 v61, 1.0, v61
	v_add_f32_e32 v62, 1.0, v62
	v_rcp_f32_e32 v61, v61
	v_rcp_f32_e32 v62, v62
	v_lshlrev_b64 v[58:59], 10, v[102:103]
	v_mul_f32_e32 v51, v56, v51
	v_mul_f32_e32 v56, v52, v60
	v_mul_f32_e32 v52, v57, v61
	v_mul_f32_e32 v53, v53, v62
	v_lshl_add_u64 v[58:59], v[162:163], 0, v[58:59]
	v_cvt_pk_bf16_f32 v50, v1, v50
	v_cvt_pk_bf16_f32 v51, v51, v52
	v_cvt_pk_bf16_f32 v52, v54, v55
	v_cvt_pk_bf16_f32 v53, v56, v53
	global_store_dwordx4 v[58:59], v[50:53], off sc0 sc1
	s_waitcnt vmcnt(7)
	v_and_b32_e32 v55, 0xffff0000, v92
	v_lshlrev_b32_e32 v54, 16, v92
	v_and_b32_e32 v51, 0xffff0000, v90
	v_lshlrev_b32_e32 v50, 16, v90
	v_pk_fma_f32 v[46:47], v[30:31], v[50:51], v[46:47]
	v_pk_fma_f32 v[42:43], v[26:27], v[54:55], v[42:43]
	v_mul_f32_e32 v1, 0x3d372713, v46
	v_mul_f32_e32 v50, 0x3d372713, v42
	v_mul_f32_e32 v51, 0x3d372713, v47
	v_mul_f32_e32 v1, v46, v1
	v_mul_f32_e32 v50, v42, v50
	v_mul_f32_e32 v51, v47, v51
	v_fma_f32 v1, v46, v1, v46
	v_fma_f32 v50, v42, v50, v42
	v_fma_f32 v51, v47, v51, v47
	v_mul_f32_e32 v1, 0x3f4c422a, v1
	v_mul_f32_e32 v50, 0x3f4c422a, v50
	v_mul_f32_e32 v51, 0x3f4c422a, v51
	v_add_f32_e32 v1, v1, v1
	v_add_f32_e32 v50, v50, v50
	v_add_f32_e32 v51, v51, v51
	v_mul_f32_e32 v1, 0xbfb8aa3b, v1
	v_mul_f32_e32 v50, 0xbfb8aa3b, v50
	v_mul_f32_e32 v51, 0xbfb8aa3b, v51
	v_exp_f32_e32 v1, v1
	v_exp_f32_e32 v50, v50
	v_exp_f32_e32 v51, v51
	v_and_b32_e32 v53, 0xffff0000, v91
	v_lshlrev_b32_e32 v52, 16, v91
	v_pk_fma_f32 v[48:49], v[32:33], v[52:53], v[48:49]
	v_add_f32_e32 v1, 1.0, v1
	v_add_f32_e32 v50, 1.0, v50
	v_add_f32_e32 v51, 1.0, v51
	v_mul_f32_e32 v52, 0x3d372713, v43
	v_rcp_f32_e32 v1, v1
	v_rcp_f32_e32 v50, v50
	v_rcp_f32_e32 v51, v51
	v_mul_f32_e32 v52, v43, v52
	v_fma_f32 v52, v43, v52, v43
	v_and_b32_e32 v57, 0xffff0000, v93
	v_lshlrev_b32_e32 v56, 16, v93
	v_mul_f32_e32 v52, 0x3f4c422a, v52
	v_pk_fma_f32 v[44:45], v[28:29], v[56:57], v[44:45]
	v_add_f32_e32 v52, v52, v52
	v_mul_f32_e32 v52, 0xbfb8aa3b, v52
	v_mul_f32_e32 v1, v46, v1
	v_mul_f32_e32 v46, v42, v50
	v_mul_f32_e32 v42, v47, v51
	v_mul_f32_e32 v50, 0x3d372713, v48
	v_mul_f32_e32 v51, 0x3d372713, v44
	v_exp_f32_e32 v52, v52
	v_mul_f32_e32 v50, v48, v50
	v_mul_f32_e32 v51, v44, v51
	v_fma_f32 v50, v48, v50, v48
	v_fma_f32 v51, v44, v51, v44
	v_mul_f32_e32 v50, 0x3f4c422a, v50
	v_mul_f32_e32 v51, 0x3f4c422a, v51
	v_add_f32_e32 v50, v50, v50
	v_add_f32_e32 v51, v51, v51
	v_add_f32_e32 v47, 1.0, v52
	v_mul_f32_e32 v50, 0xbfb8aa3b, v50
	v_mul_f32_e32 v51, 0xbfb8aa3b, v51
	v_rcp_f32_e32 v47, v47
	v_exp_f32_e32 v50, v50
	v_exp_f32_e32 v51, v51
	v_mul_f32_e32 v52, 0x3d372713, v45
	v_mul_f32_e32 v47, v43, v47
	v_add_f32_e32 v43, 1.0, v50
	v_add_f32_e32 v50, 1.0, v51
	v_mul_f32_e32 v51, 0x3d372713, v49
	v_mul_f32_e32 v51, v49, v51
	v_mul_f32_e32 v52, v45, v52
	v_fma_f32 v51, v49, v51, v49
	v_fma_f32 v52, v45, v52, v45
	v_mul_f32_e32 v51, 0x3f4c422a, v51
	v_mul_f32_e32 v52, 0x3f4c422a, v52
	v_add_f32_e32 v51, v51, v51
	v_add_f32_e32 v52, v52, v52
	v_mul_f32_e32 v51, 0xbfb8aa3b, v51
	v_mul_f32_e32 v52, 0xbfb8aa3b, v52
	v_exp_f32_e32 v51, v51
	v_exp_f32_e32 v52, v52
	v_rcp_f32_e32 v43, v43
	v_rcp_f32_e32 v50, v50
	v_add_f32_e32 v51, 1.0, v51
	v_add_f32_e32 v52, 1.0, v52
	v_rcp_f32_e32 v51, v51
	v_rcp_f32_e32 v52, v52
	v_mul_f32_e32 v43, v48, v43
	v_mul_f32_e32 v48, v44, v50
	v_mul_f32_e32 v44, v49, v51
	v_mul_f32_e32 v45, v45, v52
	v_cvt_pk_bf16_f32 v42, v1, v42
	v_cvt_pk_bf16_f32 v43, v43, v44
	v_cvt_pk_bf16_f32 v44, v46, v47
	v_cvt_pk_bf16_f32 v45, v48, v45
	global_store_dwordx4 v[58:59], v[42:45], off offset:256 sc0 sc1
	s_waitcnt vmcnt(7)
; __device__ __forceinline__ float gelu_tanh_f(float y) { const float t = 0.7978845608028654f * (y + 0.044715f * y * y * y); return y * fast_sigmoid(2.f * t); }
; __device__ __forceinline__ u32x4 pack8(const f32x4 v0, const f32x4 v1) { u32x4 w; w.x = pk_f16(v0[0], v0[1]); w.y = pk_f16(v0[2], v0[3]); w.z = pk_f16(v1[0], v1[1]); w.w = pk_f16(v1[2], v1[3]); return w; }
; __device__ __forceinline__ void unpack8(const u32x4 w, f32x4& v0, f32x4& v1) { v0 = (f32x4){f16lo(w.x), f16hi(w.x), f16lo(w.y), f16hi(w.y)}; v1 = (f32x4){f16lo(w.z), f16hi(w.z), f16lo(w.w), f16hi(w.w)}; }
;     __device__ __forceinline__ void operator()(AccRef acc, const Unit& u, int wr, int wc, int fr, int fq) const {
;     ...
;         for (int ai = 0; ai < 2; ++ai) { u32x4 uv[4][2];
; #pragma unroll
;             for (int m = 0; m < 4; ++m)
; #pragma unroll
;                 for (int bj = 0; bj < 2; ++bj) uv[m][bj] = *(const u32x4*)(Xg + (size_t)(row0 + ai * HALF + m * 16) * XK + bj * HALF);
;             __builtin_amdgcn_sched_barrier(0);
; #pragma unroll
;             for (int m = 0; m < 4; ++m)
; #pragma unroll
;                 for (int bj = 0; bj < 2; ++bj) { f32x4 u0, u1; unpack8(uv[m][bj], u0, u1);
;                     f32x4 v0 = acc[ai][bj][m][0] + d0 * u0, v1 = acc[ai][bj][m][1] + d1 * u1;
; #pragma unroll
;                     for (int j = 0; j < 4; ++j) { v0[j] = gelu_tanh_f(v0[j]); v1[j] = gelu_tanh_f(v1[j]); }
;                     *(u32x4*)(Yg + (size_t)(row0 + ai * HALF + m * 16) * 512 + bj * HALF) = pack8(v0, v1); } }
	v_and_b32_e32 v49, 0xffff0000, v88
	v_lshlrev_b32_e32 v48, 16, v88
	v_and_b32_e32 v45, 0xffff0000, v86
	v_lshlrev_b32_e32 v44, 16, v86
	v_pk_fma_f32 v[38:39], v[30:31], v[44:45], v[38:39]
	v_pk_fma_f32 v[34:35], v[26:27], v[48:49], v[34:35]
	v_mul_f32_e32 v1, 0x3d372713, v38
	v_mul_f32_e32 v44, 0x3d372713, v34
	v_mul_f32_e32 v45, 0x3d372713, v39
	v_mul_f32_e32 v1, v38, v1
	v_mul_f32_e32 v44, v34, v44
	v_mul_f32_e32 v45, v39, v45
	v_fma_f32 v1, v38, v1, v38
	v_fma_f32 v44, v34, v44, v34
	v_fma_f32 v45, v39, v45, v39
	v_mul_f32_e32 v1, 0x3f4c422a, v1
	v_mul_f32_e32 v44, 0x3f4c422a, v44
	v_mul_f32_e32 v45, 0x3f4c422a, v45
	v_add_f32_e32 v1, v1, v1
	v_add_f32_e32 v44, v44, v44
	v_add_f32_e32 v45, v45, v45
	v_mul_f32_e32 v1, 0xbfb8aa3b, v1
	v_mul_f32_e32 v44, 0xbfb8aa3b, v44
	v_mul_f32_e32 v45, 0xbfb8aa3b, v45
	v_exp_f32_e32 v1, v1
	v_exp_f32_e32 v44, v44
	v_exp_f32_e32 v45, v45
	v_and_b32_e32 v47, 0xffff0000, v87
	v_lshlrev_b32_e32 v46, 16, v87
	v_pk_fma_f32 v[40:41], v[32:33], v[46:47], v[40:41]
	v_add_f32_e32 v1, 1.0, v1
	v_add_f32_e32 v44, 1.0, v44
	v_add_f32_e32 v45, 1.0, v45
	v_mul_f32_e32 v46, 0x3d372713, v35
	v_rcp_f32_e32 v1, v1
	v_rcp_f32_e32 v44, v44
	v_rcp_f32_e32 v45, v45
	v_mul_f32_e32 v46, v35, v46
	v_fma_f32 v46, v35, v46, v35
	v_and_b32_e32 v51, 0xffff0000, v89
	v_lshlrev_b32_e32 v50, 16, v89
	v_mul_f32_e32 v46, 0x3f4c422a, v46
	v_pk_fma_f32 v[36:37], v[28:29], v[50:51], v[36:37]
	v_add_f32_e32 v46, v46, v46
	v_mul_f32_e32 v46, 0xbfb8aa3b, v46
	v_mul_f32_e32 v1, v38, v1
	v_mul_f32_e32 v38, v34, v44
	v_mul_f32_e32 v34, v39, v45
	v_mul_f32_e32 v44, 0x3d372713, v40
	v_mul_f32_e32 v45, 0x3d372713, v36
	v_exp_f32_e32 v46, v46
	v_mul_f32_e32 v44, v40, v44
	v_mul_f32_e32 v45, v36, v45
	v_fma_f32 v44, v40, v44, v40
	v_fma_f32 v45, v36, v45, v36
	v_mul_f32_e32 v44, 0x3f4c422a, v44
	v_mul_f32_e32 v45, 0x3f4c422a, v45
	v_add_f32_e32 v44, v44, v44
	v_add_f32_e32 v45, v45, v45
	v_add_f32_e32 v39, 1.0, v46
	v_mul_f32_e32 v44, 0xbfb8aa3b, v44
	v_mul_f32_e32 v45, 0xbfb8aa3b, v45
	v_rcp_f32_e32 v39, v39
	v_exp_f32_e32 v44, v44
	v_exp_f32_e32 v45, v45
	v_mul_f32_e32 v46, 0x3d372713, v37
	v_mul_f32_e32 v39, v35, v39
	v_add_f32_e32 v35, 1.0, v44
	v_add_f32_e32 v44, 1.0, v45
	v_mul_f32_e32 v45, 0x3d372713, v41
	v_mul_f32_e32 v45, v41, v45
	v_mul_f32_e32 v46, v37, v46
	v_fma_f32 v45, v41, v45, v41
	v_fma_f32 v46, v37, v46, v37
	v_mul_f32_e32 v45, 0x3f4c422a, v45
	v_mul_f32_e32 v46, 0x3f4c422a, v46
	v_add_f32_e32 v45, v45, v45
	v_add_f32_e32 v46, v46, v46
	v_mul_f32_e32 v45, 0xbfb8aa3b, v45
	v_mul_f32_e32 v46, 0xbfb8aa3b, v46
	v_exp_f32_e32 v45, v45
	v_exp_f32_e32 v46, v46
	v_rcp_f32_e32 v35, v35
	v_rcp_f32_e32 v44, v44
	v_add_f32_e32 v45, 1.0, v45
	v_add_f32_e32 v46, 1.0, v46
	v_rcp_f32_e32 v45, v45
	v_rcp_f32_e32 v46, v46
	v_lshlrev_b64 v[42:43], 10, v[100:101]
	v_mul_f32_e32 v35, v40, v35
	v_mul_f32_e32 v40, v36, v44
	v_mul_f32_e32 v36, v41, v45
	v_mul_f32_e32 v37, v37, v46
	v_lshl_add_u64 v[42:43], v[162:163], 0, v[42:43]
	v_cvt_pk_bf16_f32 v34, v1, v34
	v_cvt_pk_bf16_f32 v35, v35, v36
	v_cvt_pk_bf16_f32 v36, v38, v39
	v_cvt_pk_bf16_f32 v37, v40, v37
	global_store_dwordx4 v[42:43], v[34:37], off sc0 sc1
	s_waitcnt vmcnt(7)
	v_and_b32_e32 v39, 0xffff0000, v84
	v_lshlrev_b32_e32 v38, 16, v84
	v_and_b32_e32 v35, 0xffff0000, v82
	v_lshlrev_b32_e32 v34, 16, v82
	v_pk_fma_f32 v[22:23], v[30:31], v[34:35], v[22:23]
	v_pk_fma_f32 v[18:19], v[26:27], v[38:39], v[18:19]
	v_mul_f32_e32 v1, 0x3d372713, v22
	v_mul_f32_e32 v34, 0x3d372713, v18
	v_mul_f32_e32 v35, 0x3d372713, v23
	v_mul_f32_e32 v1, v22, v1
	v_mul_f32_e32 v34, v18, v34
	v_mul_f32_e32 v35, v23, v35
	v_fma_f32 v1, v22, v1, v22
	v_fma_f32 v34, v18, v34, v18
	v_fma_f32 v35, v23, v35, v23
	v_mul_f32_e32 v1, 0x3f4c422a, v1
	v_mul_f32_e32 v34, 0x3f4c422a, v34
	v_mul_f32_e32 v35, 0x3f4c422a, v35
	v_add_f32_e32 v1, v1, v1
	v_add_f32_e32 v34, v34, v34
	v_add_f32_e32 v35, v35, v35
	v_mul_f32_e32 v1, 0xbfb8aa3b, v1
	v_mul_f32_e32 v34, 0xbfb8aa3b, v34
	v_mul_f32_e32 v35, 0xbfb8aa3b, v35
	v_exp_f32_e32 v1, v1
	v_exp_f32_e32 v34, v34
	v_exp_f32_e32 v35, v35
	v_and_b32_e32 v37, 0xffff0000, v83
	v_lshlrev_b32_e32 v36, 16, v83
	v_pk_fma_f32 v[24:25], v[32:33], v[36:37], v[24:25]
	v_add_f32_e32 v1, 1.0, v1
	v_add_f32_e32 v34, 1.0, v34
	v_add_f32_e32 v35, 1.0, v35
	v_mul_f32_e32 v36, 0x3d372713, v19
	v_rcp_f32_e32 v1, v1
	v_rcp_f32_e32 v34, v34
	v_rcp_f32_e32 v35, v35
	v_mul_f32_e32 v36, v19, v36
	v_fma_f32 v36, v19, v36, v19
	v_and_b32_e32 v41, 0xffff0000, v85
	v_lshlrev_b32_e32 v40, 16, v85
	v_mul_f32_e32 v36, 0x3f4c422a, v36
	v_pk_fma_f32 v[20:21], v[28:29], v[40:41], v[20:21]
	v_add_f32_e32 v36, v36, v36
	v_mul_f32_e32 v36, 0xbfb8aa3b, v36
	v_mul_f32_e32 v1, v22, v1
	v_mul_f32_e32 v22, v18, v34
	v_mul_f32_e32 v18, v23, v35
	v_mul_f32_e32 v34, 0x3d372713, v24
	v_mul_f32_e32 v35, 0x3d372713, v20
	v_exp_f32_e32 v36, v36
	v_mul_f32_e32 v34, v24, v34
	v_mul_f32_e32 v35, v20, v35
	v_fma_f32 v34, v24, v34, v24
	v_fma_f32 v35, v20, v35, v20
	v_mul_f32_e32 v34, 0x3f4c422a, v34
	v_mul_f32_e32 v35, 0x3f4c422a, v35
	v_add_f32_e32 v34, v34, v34
	v_add_f32_e32 v35, v35, v35
	v_add_f32_e32 v23, 1.0, v36
	v_mul_f32_e32 v34, 0xbfb8aa3b, v34
	v_mul_f32_e32 v35, 0xbfb8aa3b, v35
	v_rcp_f32_e32 v23, v23
	v_exp_f32_e32 v34, v34
	v_exp_f32_e32 v35, v35
	v_mul_f32_e32 v36, 0x3d372713, v21
	v_mul_f32_e32 v23, v19, v23
	v_add_f32_e32 v19, 1.0, v34
	v_add_f32_e32 v34, 1.0, v35
	v_mul_f32_e32 v35, 0x3d372713, v25
	v_mul_f32_e32 v35, v25, v35
	v_mul_f32_e32 v36, v21, v36
	v_fma_f32 v35, v25, v35, v25
	v_fma_f32 v36, v21, v36, v21
	v_mul_f32_e32 v35, 0x3f4c422a, v35
	v_mul_f32_e32 v36, 0x3f4c422a, v36
	v_add_f32_e32 v35, v35, v35
	v_add_f32_e32 v36, v36, v36
	v_mul_f32_e32 v35, 0xbfb8aa3b, v35
	v_mul_f32_e32 v36, 0xbfb8aa3b, v36
	v_exp_f32_e32 v35, v35
	v_exp_f32_e32 v36, v36
	v_rcp_f32_e32 v19, v19
	v_rcp_f32_e32 v34, v34
	v_add_f32_e32 v35, 1.0, v35
	v_add_f32_e32 v36, 1.0, v36
	v_rcp_f32_e32 v35, v35
	v_rcp_f32_e32 v36, v36
	v_mul_f32_e32 v19, v24, v19
	v_mul_f32_e32 v24, v20, v34
	v_mul_f32_e32 v20, v25, v35
	v_mul_f32_e32 v21, v21, v36
	v_cvt_pk_bf16_f32 v18, v1, v18
	v_cvt_pk_bf16_f32 v19, v19, v20
	v_cvt_pk_bf16_f32 v20, v22, v23
	v_cvt_pk_bf16_f32 v21, v24, v21
	global_store_dwordx4 v[42:43], v[18:21], off offset:256 sc0 sc1
	s_waitcnt vmcnt(7)
; __device__ __forceinline__ float gelu_tanh_f(float y) { const float t = 0.7978845608028654f * (y + 0.044715f * y * y * y); return y * fast_sigmoid(2.f * t); }
; __device__ __forceinline__ u32x4 pack8(const f32x4 v0, const f32x4 v1) { u32x4 w; w.x = pk_f16(v0[0], v0[1]); w.y = pk_f16(v0[2], v0[3]); w.z = pk_f16(v1[0], v1[1]); w.w = pk_f16(v1[2], v1[3]); return w; }
; __device__ __forceinline__ void unpack8(const u32x4 w, f32x4& v0, f32x4& v1) { v0 = (f32x4){f16lo(w.x), f16hi(w.x), f16lo(w.y), f16hi(w.y)}; v1 = (f32x4){f16lo(w.z), f16hi(w.z), f16lo(w.w), f16hi(w.w)}; }
;     __device__ __forceinline__ void operator()(AccRef acc, const Unit& u, int wr, int wc, int fr, int fq) const {
;     ...
;         for (int ai = 0; ai < 2; ++ai) { u32x4 uv[4][2];
; #pragma unroll
;             for (int m = 0; m < 4; ++m)
; #pragma unroll
;                 for (int bj = 0; bj < 2; ++bj) uv[m][bj] = *(const u32x4*)(Xg + (size_t)(row0 + ai * HALF + m * 16) * XK + bj * HALF);
;             __builtin_amdgcn_sched_barrier(0);
; #pragma unroll
;             for (int m = 0; m < 4; ++m)
; #pragma unroll
;                 for (int bj = 0; bj < 2; ++bj) { f32x4 u0, u1; unpack8(uv[m][bj], u0, u1);
;                     f32x4 v0 = acc[ai][bj][m][0] + d0 * u0, v1 = acc[ai][bj][m][1] + d1 * u1;
; #pragma unroll
;                     for (int j = 0; j < 4; ++j) { v0[j] = gelu_tanh_f(v0[j]); v1[j] = gelu_tanh_f(v1[j]); }
;                     *(u32x4*)(Yg + (size_t)(row0 + ai * HALF + m * 16) * 512 + bj * HALF) = pack8(v0, v1); } }
	v_and_b32_e32 v25, 0xffff0000, v80
	v_lshlrev_b32_e32 v24, 16, v80
	v_and_b32_e32 v21, 0xffff0000, v78
	v_lshlrev_b32_e32 v20, 16, v78
	v_pk_fma_f32 v[14:15], v[30:31], v[20:21], v[14:15]
	v_pk_fma_f32 v[10:11], v[26:27], v[24:25], v[10:11]
	v_mul_f32_e32 v1, 0x3d372713, v14
	v_mul_f32_e32 v20, 0x3d372713, v10
	v_mul_f32_e32 v21, 0x3d372713, v15
	v_mul_f32_e32 v1, v14, v1
	v_mul_f32_e32 v20, v10, v20
	v_mul_f32_e32 v21, v15, v21
	v_fma_f32 v1, v14, v1, v14
	v_fma_f32 v20, v10, v20, v10
	v_fma_f32 v21, v15, v21, v15
	v_mul_f32_e32 v1, 0x3f4c422a, v1
	v_mul_f32_e32 v20, 0x3f4c422a, v20
	v_mul_f32_e32 v21, 0x3f4c422a, v21
	v_add_f32_e32 v1, v1, v1
	v_add_f32_e32 v20, v20, v20
	v_add_f32_e32 v21, v21, v21
	v_mul_f32_e32 v1, 0xbfb8aa3b, v1
	v_mul_f32_e32 v20, 0xbfb8aa3b, v20
	v_mul_f32_e32 v21, 0xbfb8aa3b, v21
	v_exp_f32_e32 v1, v1
	v_exp_f32_e32 v20, v20
	v_exp_f32_e32 v21, v21
	v_and_b32_e32 v23, 0xffff0000, v79
	v_lshlrev_b32_e32 v22, 16, v79
	v_pk_fma_f32 v[16:17], v[32:33], v[22:23], v[16:17]
	v_add_f32_e32 v1, 1.0, v1
	v_add_f32_e32 v20, 1.0, v20
	v_add_f32_e32 v21, 1.0, v21
	v_mul_f32_e32 v22, 0x3d372713, v11
	v_rcp_f32_e32 v1, v1
	v_rcp_f32_e32 v20, v20
	v_rcp_f32_e32 v21, v21
	v_mul_f32_e32 v22, v11, v22
	v_fma_f32 v22, v11, v22, v11
	v_and_b32_e32 v35, 0xffff0000, v81
	v_lshlrev_b32_e32 v34, 16, v81
	v_mul_f32_e32 v22, 0x3f4c422a, v22
	v_pk_fma_f32 v[12:13], v[28:29], v[34:35], v[12:13]
	v_add_f32_e32 v22, v22, v22
	v_mul_f32_e32 v22, 0xbfb8aa3b, v22
	v_mul_f32_e32 v1, v14, v1
	v_mul_f32_e32 v14, v10, v20
	v_mul_f32_e32 v10, v15, v21
	v_mul_f32_e32 v20, 0x3d372713, v16
	v_mul_f32_e32 v21, 0x3d372713, v12
	v_exp_f32_e32 v22, v22
	v_mul_f32_e32 v20, v16, v20
	v_mul_f32_e32 v21, v12, v21
	v_fma_f32 v20, v16, v20, v16
	v_fma_f32 v21, v12, v21, v12
	v_mul_f32_e32 v20, 0x3f4c422a, v20
	v_mul_f32_e32 v21, 0x3f4c422a, v21
	v_add_f32_e32 v20, v20, v20
	v_add_f32_e32 v21, v21, v21
	v_add_f32_e32 v15, 1.0, v22
	v_mul_f32_e32 v20, 0xbfb8aa3b, v20
	v_mul_f32_e32 v21, 0xbfb8aa3b, v21
	v_rcp_f32_e32 v15, v15
	v_exp_f32_e32 v20, v20
	v_exp_f32_e32 v21, v21
	v_mul_f32_e32 v22, 0x3d372713, v13
	v_mul_f32_e32 v15, v11, v15
	v_add_f32_e32 v11, 1.0, v20
	v_add_f32_e32 v20, 1.0, v21
	v_mul_f32_e32 v21, 0x3d372713, v17
	v_mul_f32_e32 v21, v17, v21
	v_mul_f32_e32 v22, v13, v22
	v_fma_f32 v21, v17, v21, v17
	v_fma_f32 v22, v13, v22, v13
	v_mul_f32_e32 v21, 0x3f4c422a, v21
	v_mul_f32_e32 v22, 0x3f4c422a, v22
	v_add_f32_e32 v21, v21, v21
	v_add_f32_e32 v22, v22, v22
	v_mul_f32_e32 v21, 0xbfb8aa3b, v21
	v_mul_f32_e32 v22, 0xbfb8aa3b, v22
	v_exp_f32_e32 v21, v21
	v_exp_f32_e32 v22, v22
	v_rcp_f32_e32 v11, v11
	v_rcp_f32_e32 v20, v20
	v_add_f32_e32 v21, 1.0, v21
	v_add_f32_e32 v22, 1.0, v22
	v_rcp_f32_e32 v21, v21
	v_rcp_f32_e32 v22, v22
	v_lshlrev_b64 v[18:19], 10, v[98:99]
	v_mul_f32_e32 v11, v16, v11
	v_mul_f32_e32 v16, v12, v20
	v_mul_f32_e32 v12, v17, v21
	v_mul_f32_e32 v13, v13, v22
	v_lshl_add_u64 v[18:19], v[162:163], 0, v[18:19]
	v_cvt_pk_bf16_f32 v10, v1, v10
	v_cvt_pk_bf16_f32 v11, v11, v12
	v_cvt_pk_bf16_f32 v12, v14, v15
	v_cvt_pk_bf16_f32 v13, v16, v13
	global_store_dwordx4 v[18:19], v[10:13], off sc0 sc1
	s_waitcnt vmcnt(7)
	v_and_b32_e32 v15, 0xffff0000, v76
	v_lshlrev_b32_e32 v14, 16, v76
	v_and_b32_e32 v11, 0xffff0000, v74
	v_lshlrev_b32_e32 v10, 16, v74
	v_pk_fma_f32 v[6:7], v[30:31], v[10:11], v[6:7]
	v_pk_fma_f32 v[2:3], v[26:27], v[14:15], v[2:3]
	v_mul_f32_e32 v1, 0x3d372713, v6
	v_mul_f32_e32 v10, 0x3d372713, v2
	v_mul_f32_e32 v11, 0x3d372713, v7
	v_mul_f32_e32 v1, v6, v1
	v_mul_f32_e32 v10, v2, v10
	v_mul_f32_e32 v11, v7, v11
	v_fma_f32 v1, v6, v1, v6
	v_fma_f32 v10, v2, v10, v2
	v_fma_f32 v11, v7, v11, v7
	v_mul_f32_e32 v1, 0x3f4c422a, v1
	v_mul_f32_e32 v10, 0x3f4c422a, v10
	v_mul_f32_e32 v11, 0x3f4c422a, v11
	v_add_f32_e32 v1, v1, v1
	v_add_f32_e32 v10, v10, v10
	v_add_f32_e32 v11, v11, v11
	v_mul_f32_e32 v1, 0xbfb8aa3b, v1
	v_mul_f32_e32 v10, 0xbfb8aa3b, v10
	v_mul_f32_e32 v11, 0xbfb8aa3b, v11
	v_exp_f32_e32 v1, v1
	v_exp_f32_e32 v10, v10
	v_exp_f32_e32 v11, v11
	v_and_b32_e32 v13, 0xffff0000, v75
	v_lshlrev_b32_e32 v12, 16, v75
	v_pk_fma_f32 v[8:9], v[32:33], v[12:13], v[8:9]
	v_add_f32_e32 v1, 1.0, v1
	v_add_f32_e32 v10, 1.0, v10
	v_add_f32_e32 v11, 1.0, v11
	v_mul_f32_e32 v12, 0x3d372713, v3
	v_rcp_f32_e32 v1, v1
	v_rcp_f32_e32 v10, v10
	v_rcp_f32_e32 v11, v11
	v_mul_f32_e32 v12, v3, v12
	v_fma_f32 v12, v3, v12, v3
	v_and_b32_e32 v17, 0xffff0000, v77
	v_lshlrev_b32_e32 v16, 16, v77
	v_mul_f32_e32 v12, 0x3f4c422a, v12
	v_pk_fma_f32 v[4:5], v[28:29], v[16:17], v[4:5]
	v_add_f32_e32 v12, v12, v12
	v_mul_f32_e32 v12, 0xbfb8aa3b, v12
	v_mul_f32_e32 v1, v6, v1
	v_mul_f32_e32 v6, v2, v10
	v_mul_f32_e32 v2, v7, v11
	v_mul_f32_e32 v10, 0x3d372713, v8
	v_mul_f32_e32 v11, 0x3d372713, v4
	v_exp_f32_e32 v12, v12
	v_mul_f32_e32 v10, v8, v10
	v_mul_f32_e32 v11, v4, v11
	v_fma_f32 v10, v8, v10, v8
	v_fma_f32 v11, v4, v11, v4
	v_mul_f32_e32 v10, 0x3f4c422a, v10
	v_mul_f32_e32 v11, 0x3f4c422a, v11
	v_add_f32_e32 v10, v10, v10
	v_add_f32_e32 v11, v11, v11
	v_add_f32_e32 v7, 1.0, v12
	v_mul_f32_e32 v10, 0xbfb8aa3b, v10
	v_mul_f32_e32 v11, 0xbfb8aa3b, v11
	v_rcp_f32_e32 v7, v7
	v_exp_f32_e32 v10, v10
	v_exp_f32_e32 v11, v11
	v_mul_f32_e32 v12, 0x3d372713, v5
	v_mul_f32_e32 v7, v3, v7
	v_add_f32_e32 v3, 1.0, v10
	v_add_f32_e32 v10, 1.0, v11
	v_mul_f32_e32 v11, 0x3d372713, v9
	v_mul_f32_e32 v11, v9, v11
	v_mul_f32_e32 v12, v5, v12
	v_fma_f32 v11, v9, v11, v9
	v_fma_f32 v12, v5, v12, v5
	v_mul_f32_e32 v11, 0x3f4c422a, v11
	v_mul_f32_e32 v12, 0x3f4c422a, v12
	v_add_f32_e32 v11, v11, v11
	v_add_f32_e32 v12, v12, v12
	v_mul_f32_e32 v11, 0xbfb8aa3b, v11
	v_mul_f32_e32 v12, 0xbfb8aa3b, v12
	v_exp_f32_e32 v11, v11
	v_exp_f32_e32 v12, v12
	v_rcp_f32_e32 v3, v3
	v_rcp_f32_e32 v10, v10
	v_add_f32_e32 v11, 1.0, v11
	v_add_f32_e32 v12, 1.0, v12
	v_rcp_f32_e32 v11, v11
	v_rcp_f32_e32 v12, v12
	v_mul_f32_e32 v3, v8, v3
	v_mul_f32_e32 v8, v4, v10
	v_mul_f32_e32 v4, v9, v11
	v_mul_f32_e32 v5, v5, v12
	v_cvt_pk_bf16_f32 v2, v1, v2
	v_cvt_pk_bf16_f32 v3, v3, v4
	v_cvt_pk_bf16_f32 v4, v6, v7
	v_cvt_pk_bf16_f32 v5, v8, v5
	global_store_dwordx4 v[18:19], v[2:5], off offset:256 sc0 sc1
	s_waitcnt vmcnt(0)
	s_mov_b32 s53, s80
	s_barrier

; __device__ __forceinline__ float fast_sigmoid(float v) { return __builtin_amdgcn_rcpf(1.f + __expf(-v)); }
; __device__ __forceinline__ u32x4 pack8(const f32x4 v0, const f32x4 v1) { u32x4 w; w.x = pk_f16(v0[0], v0[1]); w.y = pk_f16(v0[2], v0[3]); w.z = pk_f16(v1[0], v1[1]); w.w = pk_f16(v1[2], v1[3]); return w; }
; __device__ __forceinline__ void unpack8(const u32x4 w, f32x4& v0, f32x4& v1) { v0 = (f32x4){f16lo(w.x), f16hi(w.x), f16lo(w.y), f16hi(w.y)}; v1 = (f32x4){f16lo(w.z), f16hi(w.z), f16lo(w.w), f16hi(w.w)}; }
;     __device__ __forceinline__ void operator()(AccRef acc, const Unit& u, int wr, int wc, int fr, int fq) const {
;         int row0 = u.pm * 256 + wr * 64 + fr; asm volatile("" : "+v"(row0)); int col0 = u.pn * 128 + wc * 32 + 8 * fq; asm volatile("" : "+v"(col0));
;         const f32x4 b10 = *(const f32x4*)(gb + col0), b11 = *(const f32x4*)(gb + col0 + 4), b20 = *(const f32x4*)(gb + SW + col0), b21 = *(const f32x4*)(gb + SW + col0 + 4);
;         u32x4 zv[2][4];
; #pragma unroll
;         for (int ai = 0; ai < 2; ++ai)
; #pragma unroll
;             for (int m = 0; m < 4; ++m) zv[ai][m] = *(const u32x4*)(zs + (size_t)(row0 + ai * HALF + m * 16) * D + PW + col0);
;         __builtin_amdgcn_sched_barrier(0);
; #pragma unroll
;         for (int ai = 0; ai < 2; ++ai)
; #pragma unroll
;             for (int m = 0; m < 4; ++m) { const size_t o = (size_t)(row0 + ai * HALF + m * 16) * D + PW + col0;
;                 f32x4 z0, z1; unpack8(zv[ai][m], z0, z1);
;                 f32x4 y10 = acc[ai][0][m][0] + b10, y11 = acc[ai][0][m][1] + b11, y20 = acc[ai][1][m][0] + b20, y21 = acc[ai][1][m][1] + b21;
; #pragma unroll
;                 for (int j = 0; j < 4; ++j) { y10[j] = y10[j] * fast_sigmoid(y20[j]) * z0[j]; y11[j] = y11[j] * fast_sigmoid(y21[j]) * z1[j]; }
;                 *(u32x4*)(branch + o) = pack8(y10, y11); }
.LBB0_1073:
	v_lshl_add_u32 v130, s74, 8, v1
	v_lshl_or_b32 v132, s72, 7, v195
	v_ashrrev_i32_e32 v131, 31, v130
	v_lshlrev_b64 v[208:209], 12, v[130:131]
	s_mov_b64 s[18:19], 0x10000
	v_lshl_add_u64 v[210:211], v[208:209], 0, s[18:19]
	v_ashrrev_i32_e32 v133, 31, v132
	v_lshlrev_b64 v[122:123], 2, v[132:133]
	v_lshl_add_u64 v[130:131], s[28:29], 0, v[208:209]
	v_lshlrev_b64 v[180:181], 1, v[132:133]
	v_lshl_add_u64 v[132:133], s[28:29], 0, v[210:211]
	s_mov_b64 s[18:19], 0x30000
	v_lshl_add_u64 v[124:125], s[42:43], 0, v[122:123]
	v_lshl_add_u64 v[126:127], s[54:55], 0, v[122:123]
	v_lshl_add_u64 v[130:131], v[130:131], 0, v[180:181]
	v_lshl_add_u64 v[132:133], v[132:133], 0, v[180:181]
	v_lshl_add_u64 v[192:193], v[208:209], 0, s[6:7]
	v_lshl_add_u64 v[190:191], v[208:209], 0, s[18:19]
	global_load_dwordx4 v[134:137], v[124:125], off offset:16
	global_load_dwordx4 v[142:145], v[124:125], off
	s_nop 0
	global_load_dwordx4 v[122:125], v[126:127], off offset:16
	s_nop 0
	global_load_dwordx4 v[126:129], v[126:127], off
	s_nop 0
	global_load_dwordx4 v[200:203], v[130:131], off offset:2048
	global_load_dwordx4 v[204:207], v[132:133], off offset:2048
	v_lshl_add_u64 v[130:131], s[28:29], 0, v[192:193]
	v_lshl_add_u64 v[132:133], s[28:29], 0, v[190:191]
	v_lshl_add_u64 v[130:131], v[130:131], 0, v[180:181]
	v_lshl_add_u64 v[132:133], v[132:133], 0, v[180:181]
	v_lshl_add_u64 v[188:189], v[208:209], 0, s[56:57]
	v_lshl_add_u64 v[186:187], v[208:209], 0, s[58:59]
	global_load_dwordx4 v[166:169], v[130:131], off offset:2048
	global_load_dwordx4 v[162:165], v[132:133], off offset:2048
	v_lshl_add_u64 v[130:131], s[28:29], 0, v[188:189]
	v_lshl_add_u64 v[132:133], s[28:29], 0, v[186:187]
	v_lshl_add_u64 v[130:131], v[130:131], 0, v[180:181]
	v_lshl_add_u64 v[132:133], v[132:133], 0, v[180:181]
	v_lshl_add_u64 v[184:185], v[208:209], 0, s[60:61]
	v_lshl_add_u64 v[182:183], v[208:209], 0, s[62:63]
	global_load_dwordx4 v[158:161], v[130:131], off offset:2048
	global_load_dwordx4 v[154:157], v[132:133], off offset:2048
	v_lshl_add_u64 v[130:131], s[28:29], 0, v[184:185]
	v_lshl_add_u64 v[132:133], s[28:29], 0, v[182:183]
	v_lshl_add_u64 v[130:131], v[130:131], 0, v[180:181]
	v_lshl_add_u64 v[132:133], v[132:133], 0, v[180:181]
	global_load_dwordx4 v[150:153], v[130:131], off offset:2048
	s_nop 0
	global_load_dwordx4 v[130:133], v[132:133], off offset:2048
	s_waitcnt vmcnt(0)
	v_add_f32_e32 v118, v118, v126
	v_add_f32_e32 v114, v114, v122
	v_mul_f32_e32 v118, 0xbfb8aa3b, v118
	v_mul_f32_e32 v114, 0xbfb8aa3b, v114
	v_exp_f32_e32 v118, v118
	v_exp_f32_e32 v199, v114
	v_add_f32_e32 v119, v119, v127
	v_add_f32_e32 v115, v115, v123
	v_mul_f32_e32 v119, 0xbfb8aa3b, v119
	v_mul_f32_e32 v115, 0xbfb8aa3b, v115
	v_add_f32_e32 v114, 1.0, v118
	v_add_f32_e32 v118, 1.0, v199
	v_exp_f32_e32 v119, v119
	v_exp_f32_e32 v199, v115
	v_add_f32_e32 v120, v120, v128
	v_add_f32_e32 v116, v116, v124
	v_mul_f32_e32 v120, 0xbfb8aa3b, v120
	v_mul_f32_e32 v116, 0xbfb8aa3b, v116
	v_add_f32_e32 v121, v121, v129
	v_add_f32_e32 v115, 1.0, v119
	v_add_f32_e32 v119, 1.0, v199
	v_exp_f32_e32 v120, v120
	v_exp_f32_e32 v199, v116
	v_mul_f32_e32 v121, 0xbfb8aa3b, v121
	v_exp_f32_e32 v121, v121
	v_add_f32_e32 v117, v117, v125
	v_mul_f32_e32 v117, 0xbfb8aa3b, v117
	v_add_f32_e32 v116, 1.0, v120
	v_add_f32_e32 v120, 1.0, v199
	v_exp_f32_e32 v199, v117
	v_add_f32_e32 v117, 1.0, v121
	v_rcp_f32_e32 v114, v114
	v_rcp_f32_e32 v115, v115
	v_rcp_f32_e32 v116, v116
	v_rcp_f32_e32 v117, v117
	v_rcp_f32_e32 v118, v118
	v_rcp_f32_e32 v119, v119
	v_add_f32_e32 v121, 1.0, v199
	v_pk_add_f32 v[148:149], v[148:149], v[144:145]
	v_pk_add_f32 v[146:147], v[146:147], v[142:143]
	v_rcp_f32_e32 v120, v120
	v_rcp_f32_e32 v121, v121
	v_and_b32_e32 v215, 0xffff0000, v200
	v_lshlrev_b32_e32 v214, 16, v200
	v_pk_mul_f32 v[114:115], v[146:147], v[114:115]
	v_and_b32_e32 v147, 0xffff0000, v201
	v_lshlrev_b32_e32 v146, 16, v201
	v_pk_mul_f32 v[116:117], v[148:149], v[116:117]
	v_pk_add_f32 v[138:139], v[138:139], v[134:135]
	v_pk_mul_f32 v[114:115], v[114:115], v[214:215]
	v_pk_mul_f32 v[116:117], v[116:117], v[146:147]
	v_pk_add_f32 v[140:141], v[140:141], v[136:137]
	v_cvt_pk_bf16_f32 v114, v114, v115
	v_cvt_pk_bf16_f32 v115, v116, v117
	v_and_b32_e32 v117, 0xffff0000, v202
	v_lshlrev_b32_e32 v116, 16, v202
	v_pk_mul_f32 v[118:119], v[138:139], v[118:119]
	v_pk_mul_f32 v[120:121], v[140:141], v[120:121]
	v_pk_mul_f32 v[116:117], v[118:119], v[116:117]
	v_and_b32_e32 v119, 0xffff0000, v203
	v_lshlrev_b32_e32 v118, 16, v203
	v_pk_mul_f32 v[118:119], v[120:121], v[118:119]
	v_cvt_pk_bf16_f32 v116, v116, v117
	v_cvt_pk_bf16_f32 v117, v118, v119
	v_lshl_add_u64 v[118:119], s[26:27], 0, v[208:209]
	v_add_f32_e32 v102, v102, v126
	v_add_f32_e32 v98, v98, v122
	v_lshl_add_u64 v[118:119], v[118:119], 0, v[180:181]
	v_mul_f32_e32 v102, 0xbfb8aa3b, v102
	v_mul_f32_e32 v98, 0xbfb8aa3b, v98
	global_store_dwordx4 v[118:119], v[114:117], off offset:2048 sc0 sc1
	v_exp_f32_e32 v102, v102
	v_add_f32_e32 v103, v103, v127
	v_exp_f32_e32 v114, v98
	v_add_f32_e32 v99, v99, v123
	v_mul_f32_e32 v103, 0xbfb8aa3b, v103
	v_mul_f32_e32 v99, 0xbfb8aa3b, v99
	v_add_f32_e32 v98, 1.0, v102
	v_add_f32_e32 v102, 1.0, v114
	v_exp_f32_e32 v103, v103
	v_exp_f32_e32 v114, v99
	v_add_f32_e32 v104, v104, v128
	v_add_f32_e32 v100, v100, v124
	v_mul_f32_e32 v104, 0xbfb8aa3b, v104
	v_mul_f32_e32 v100, 0xbfb8aa3b, v100
	v_add_f32_e32 v105, v105, v129
	v_add_f32_e32 v99, 1.0, v103
	v_add_f32_e32 v103, 1.0, v114
	v_exp_f32_e32 v104, v104
	v_exp_f32_e32 v114, v100
	v_mul_f32_e32 v105, 0xbfb8aa3b, v105
	v_exp_f32_e32 v105, v105
	v_add_f32_e32 v101, v101, v125
; __device__ __forceinline__ float fast_sigmoid(float v) { return __builtin_amdgcn_rcpf(1.f + __expf(-v)); }
; __device__ __forceinline__ u32x4 pack8(const f32x4 v0, const f32x4 v1) { u32x4 w; w.x = pk_f16(v0[0], v0[1]); w.y = pk_f16(v0[2], v0[3]); w.z = pk_f16(v1[0], v1[1]); w.w = pk_f16(v1[2], v1[3]); return w; }
; __device__ __forceinline__ void unpack8(const u32x4 w, f32x4& v0, f32x4& v1) { v0 = (f32x4){f16lo(w.x), f16hi(w.x), f16lo(w.y), f16hi(w.y)}; v1 = (f32x4){f16lo(w.z), f16hi(w.z), f16lo(w.w), f16hi(w.w)}; }
;     __device__ __forceinline__ void operator()(AccRef acc, const Unit& u, int wr, int wc, int fr, int fq) const {
;         int row0 = u.pm * 256 + wr * 64 + fr; asm volatile("" : "+v"(row0)); int col0 = u.pn * 128 + wc * 32 + 8 * fq; asm volatile("" : "+v"(col0));
;         const f32x4 b10 = *(const f32x4*)(gb + col0), b11 = *(const f32x4*)(gb + col0 + 4), b20 = *(const f32x4*)(gb + SW + col0), b21 = *(const f32x4*)(gb + SW + col0 + 4);
;         u32x4 zv[2][4];
; #pragma unroll
;         for (int ai = 0; ai < 2; ++ai)
; #pragma unroll
;             for (int m = 0; m < 4; ++m) zv[ai][m] = *(const u32x4*)(zs + (size_t)(row0 + ai * HALF + m * 16) * D + PW + col0);
;         __builtin_amdgcn_sched_barrier(0);
; #pragma unroll
;         for (int ai = 0; ai < 2; ++ai)
; #pragma unroll
;             for (int m = 0; m < 4; ++m) { const size_t o = (size_t)(row0 + ai * HALF + m * 16) * D + PW + col0;
;                 f32x4 z0, z1; unpack8(zv[ai][m], z0, z1);
;                 f32x4 y10 = acc[ai][0][m][0] + b10, y11 = acc[ai][0][m][1] + b11, y20 = acc[ai][1][m][0] + b20, y21 = acc[ai][1][m][1] + b21;
; #pragma unroll
;                 for (int j = 0; j < 4; ++j) { y10[j] = y10[j] * fast_sigmoid(y20[j]) * z0[j]; y11[j] = y11[j] * fast_sigmoid(y21[j]) * z1[j]; }
;                 *(u32x4*)(branch + o) = pack8(y10, y11); }
	v_mul_f32_e32 v101, 0xbfb8aa3b, v101
	v_add_f32_e32 v100, 1.0, v104
	v_add_f32_e32 v104, 1.0, v114
	v_exp_f32_e32 v114, v101
	v_add_f32_e32 v101, 1.0, v105
	v_rcp_f32_e32 v98, v98
	v_rcp_f32_e32 v99, v99
	v_rcp_f32_e32 v100, v100
	v_rcp_f32_e32 v101, v101
	v_rcp_f32_e32 v102, v102
	v_rcp_f32_e32 v103, v103
	v_add_f32_e32 v105, 1.0, v114
	v_pk_add_f32 v[112:113], v[112:113], v[144:145]
	v_pk_add_f32 v[110:111], v[110:111], v[142:143]
	v_rcp_f32_e32 v104, v104
	v_rcp_f32_e32 v105, v105
	v_and_b32_e32 v115, 0xffff0000, v204
	v_lshlrev_b32_e32 v114, 16, v204
	v_pk_mul_f32 v[98:99], v[110:111], v[98:99]
	v_and_b32_e32 v111, 0xffff0000, v205
	v_lshlrev_b32_e32 v110, 16, v205
	v_pk_mul_f32 v[100:101], v[112:113], v[100:101]
	v_pk_add_f32 v[106:107], v[106:107], v[134:135]
	v_pk_mul_f32 v[98:99], v[98:99], v[114:115]
	v_pk_mul_f32 v[100:101], v[100:101], v[110:111]
	v_pk_add_f32 v[108:109], v[108:109], v[136:137]
	v_cvt_pk_bf16_f32 v98, v98, v99
	v_cvt_pk_bf16_f32 v99, v100, v101
	v_and_b32_e32 v101, 0xffff0000, v206
	v_lshlrev_b32_e32 v100, 16, v206
	v_pk_mul_f32 v[102:103], v[106:107], v[102:103]
	v_pk_mul_f32 v[104:105], v[108:109], v[104:105]
	v_pk_mul_f32 v[100:101], v[102:103], v[100:101]
	v_and_b32_e32 v103, 0xffff0000, v207
	v_lshlrev_b32_e32 v102, 16, v207
	v_pk_mul_f32 v[102:103], v[104:105], v[102:103]
	v_cvt_pk_bf16_f32 v100, v100, v101
	v_cvt_pk_bf16_f32 v101, v102, v103
	v_lshl_add_u64 v[102:103], s[26:27], 0, v[210:211]
	v_add_f32_e32 v86, v86, v126
	v_add_f32_e32 v82, v82, v122
	v_lshl_add_u64 v[102:103], v[102:103], 0, v[180:181]
	v_mul_f32_e32 v86, 0xbfb8aa3b, v86
	v_mul_f32_e32 v82, 0xbfb8aa3b, v82
	global_store_dwordx4 v[102:103], v[98:101], off offset:2048 sc0 sc1
	v_exp_f32_e32 v86, v86
	v_add_f32_e32 v87, v87, v127
	v_exp_f32_e32 v98, v82
	v_add_f32_e32 v83, v83, v123
	v_mul_f32_e32 v87, 0xbfb8aa3b, v87
	v_mul_f32_e32 v83, 0xbfb8aa3b, v83
	v_add_f32_e32 v82, 1.0, v86
	v_add_f32_e32 v86, 1.0, v98
	v_exp_f32_e32 v87, v87
	v_exp_f32_e32 v98, v83
	v_add_f32_e32 v88, v88, v128
	v_add_f32_e32 v84, v84, v124
	v_mul_f32_e32 v88, 0xbfb8aa3b, v88
	v_mul_f32_e32 v84, 0xbfb8aa3b, v84
	v_add_f32_e32 v89, v89, v129
	v_add_f32_e32 v83, 1.0, v87
	v_add_f32_e32 v87, 1.0, v98
	v_exp_f32_e32 v88, v88
	v_exp_f32_e32 v98, v84
	v_mul_f32_e32 v89, 0xbfb8aa3b, v89
	v_exp_f32_e32 v89, v89
	v_add_f32_e32 v85, v85, v125
	v_mul_f32_e32 v85, 0xbfb8aa3b, v85
	v_add_f32_e32 v84, 1.0, v88
	v_add_f32_e32 v88, 1.0, v98
	v_exp_f32_e32 v98, v85
	v_add_f32_e32 v85, 1.0, v89
	v_rcp_f32_e32 v82, v82
	v_rcp_f32_e32 v83, v83
	v_rcp_f32_e32 v84, v84
	v_rcp_f32_e32 v85, v85
	v_rcp_f32_e32 v86, v86
	v_rcp_f32_e32 v87, v87
	v_add_f32_e32 v89, 1.0, v98
	v_pk_add_f32 v[96:97], v[96:97], v[144:145]
	v_pk_add_f32 v[94:95], v[94:95], v[142:143]
	v_rcp_f32_e32 v88, v88
	v_rcp_f32_e32 v89, v89
	v_and_b32_e32 v99, 0xffff0000, v166
	v_lshlrev_b32_e32 v98, 16, v166
	v_pk_mul_f32 v[82:83], v[94:95], v[82:83]
	v_and_b32_e32 v95, 0xffff0000, v167
	v_lshlrev_b32_e32 v94, 16, v167
	v_pk_mul_f32 v[84:85], v[96:97], v[84:85]
	v_pk_add_f32 v[90:91], v[90:91], v[134:135]
	v_pk_mul_f32 v[82:83], v[82:83], v[98:99]
	v_pk_mul_f32 v[84:85], v[84:85], v[94:95]
	v_pk_add_f32 v[92:93], v[92:93], v[136:137]
	v_cvt_pk_bf16_f32 v82, v82, v83
	v_cvt_pk_bf16_f32 v83, v84, v85
	v_and_b32_e32 v85, 0xffff0000, v168
	v_lshlrev_b32_e32 v84, 16, v168
	v_pk_mul_f32 v[86:87], v[90:91], v[86:87]
	v_pk_mul_f32 v[88:89], v[92:93], v[88:89]
	v_pk_mul_f32 v[84:85], v[86:87], v[84:85]
	v_and_b32_e32 v87, 0xffff0000, v169
	v_lshlrev_b32_e32 v86, 16, v169
	v_pk_mul_f32 v[86:87], v[88:89], v[86:87]
	v_cvt_pk_bf16_f32 v84, v84, v85
	v_cvt_pk_bf16_f32 v85, v86, v87
	v_lshl_add_u64 v[86:87], s[26:27], 0, v[192:193]
	v_add_f32_e32 v70, v70, v126
	v_add_f32_e32 v66, v66, v122
	v_lshl_add_u64 v[86:87], v[86:87], 0, v[180:181]
	v_mul_f32_e32 v70, 0xbfb8aa3b, v70
	v_mul_f32_e32 v66, 0xbfb8aa3b, v66
	global_store_dwordx4 v[86:87], v[82:85], off offset:2048 sc0 sc1
	v_exp_f32_e32 v70, v70
	v_add_f32_e32 v71, v71, v127
	v_exp_f32_e32 v82, v66
	v_add_f32_e32 v67, v67, v123
	v_mul_f32_e32 v71, 0xbfb8aa3b, v71
	v_mul_f32_e32 v67, 0xbfb8aa3b, v67
	v_add_f32_e32 v66, 1.0, v70
	v_add_f32_e32 v70, 1.0, v82
	v_exp_f32_e32 v71, v71
	v_exp_f32_e32 v82, v67
	v_add_f32_e32 v72, v72, v128
	v_add_f32_e32 v68, v68, v124
	v_mul_f32_e32 v72, 0xbfb8aa3b, v72
	v_mul_f32_e32 v68, 0xbfb8aa3b, v68
	v_add_f32_e32 v73, v73, v129
	v_add_f32_e32 v67, 1.0, v71
	v_add_f32_e32 v71, 1.0, v82
	v_exp_f32_e32 v72, v72
	v_exp_f32_e32 v82, v68
	v_mul_f32_e32 v73, 0xbfb8aa3b, v73
	v_exp_f32_e32 v73, v73
	v_add_f32_e32 v69, v69, v125
	v_mul_f32_e32 v69, 0xbfb8aa3b, v69
	v_add_f32_e32 v68, 1.0, v72
	v_add_f32_e32 v72, 1.0, v82
	v_exp_f32_e32 v82, v69
	v_add_f32_e32 v69, 1.0, v73
	v_rcp_f32_e32 v66, v66
	v_rcp_f32_e32 v67, v67
	v_rcp_f32_e32 v68, v68
	v_rcp_f32_e32 v69, v69
	v_rcp_f32_e32 v70, v70
	v_rcp_f32_e32 v71, v71
	v_add_f32_e32 v73, 1.0, v82
	v_pk_add_f32 v[80:81], v[80:81], v[144:145]
	v_pk_add_f32 v[78:79], v[78:79], v[142:143]
	v_rcp_f32_e32 v72, v72
	v_rcp_f32_e32 v73, v73
	v_and_b32_e32 v83, 0xffff0000, v162
	v_lshlrev_b32_e32 v82, 16, v162
	v_pk_mul_f32 v[66:67], v[78:79], v[66:67]
	v_and_b32_e32 v79, 0xffff0000, v163
	v_lshlrev_b32_e32 v78, 16, v163
	v_pk_mul_f32 v[68:69], v[80:81], v[68:69]
	v_pk_add_f32 v[74:75], v[74:75], v[134:135]
	v_pk_mul_f32 v[66:67], v[66:67], v[82:83]
	v_pk_mul_f32 v[68:69], v[68:69], v[78:79]
	v_pk_add_f32 v[76:77], v[76:77], v[136:137]
	v_cvt_pk_bf16_f32 v66, v66, v67
	v_cvt_pk_bf16_f32 v67, v68, v69
	v_and_b32_e32 v69, 0xffff0000, v164
	v_lshlrev_b32_e32 v68, 16, v164
	v_pk_mul_f32 v[70:71], v[74:75], v[70:71]
; __device__ __forceinline__ float fast_sigmoid(float v) { return __builtin_amdgcn_rcpf(1.f + __expf(-v)); }
; __device__ __forceinline__ u32x4 pack8(const f32x4 v0, const f32x4 v1) { u32x4 w; w.x = pk_f16(v0[0], v0[1]); w.y = pk_f16(v0[2], v0[3]); w.z = pk_f16(v1[0], v1[1]); w.w = pk_f16(v1[2], v1[3]); return w; }
; __device__ __forceinline__ void unpack8(const u32x4 w, f32x4& v0, f32x4& v1) { v0 = (f32x4){f16lo(w.x), f16hi(w.x), f16lo(w.y), f16hi(w.y)}; v1 = (f32x4){f16lo(w.z), f16hi(w.z), f16lo(w.w), f16hi(w.w)}; }
;     __device__ __forceinline__ void operator()(AccRef acc, const Unit& u, int wr, int wc, int fr, int fq) const {
;         int row0 = u.pm * 256 + wr * 64 + fr; asm volatile("" : "+v"(row0)); int col0 = u.pn * 128 + wc * 32 + 8 * fq; asm volatile("" : "+v"(col0));
;         const f32x4 b10 = *(const f32x4*)(gb + col0), b11 = *(const f32x4*)(gb + col0 + 4), b20 = *(const f32x4*)(gb + SW + col0), b21 = *(const f32x4*)(gb + SW + col0 + 4);
;         u32x4 zv[2][4];
; #pragma unroll
;         for (int ai = 0; ai < 2; ++ai)
; #pragma unroll
;             for (int m = 0; m < 4; ++m) zv[ai][m] = *(const u32x4*)(zs + (size_t)(row0 + ai * HALF + m * 16) * D + PW + col0);
;         __builtin_amdgcn_sched_barrier(0);
; #pragma unroll
;         for (int ai = 0; ai < 2; ++ai)
; #pragma unroll
;             for (int m = 0; m < 4; ++m) { const size_t o = (size_t)(row0 + ai * HALF + m * 16) * D + PW + col0;
;                 f32x4 z0, z1; unpack8(zv[ai][m], z0, z1);
;                 f32x4 y10 = acc[ai][0][m][0] + b10, y11 = acc[ai][0][m][1] + b11, y20 = acc[ai][1][m][0] + b20, y21 = acc[ai][1][m][1] + b21;
; #pragma unroll
;                 for (int j = 0; j < 4; ++j) { y10[j] = y10[j] * fast_sigmoid(y20[j]) * z0[j]; y11[j] = y11[j] * fast_sigmoid(y21[j]) * z1[j]; }
;                 *(u32x4*)(branch + o) = pack8(y10, y11); }
	v_pk_mul_f32 v[72:73], v[76:77], v[72:73]
	v_pk_mul_f32 v[68:69], v[70:71], v[68:69]
	v_and_b32_e32 v71, 0xffff0000, v165
	v_lshlrev_b32_e32 v70, 16, v165
	v_pk_mul_f32 v[70:71], v[72:73], v[70:71]
	v_cvt_pk_bf16_f32 v68, v68, v69
	v_cvt_pk_bf16_f32 v69, v70, v71
	v_lshl_add_u64 v[70:71], s[26:27], 0, v[190:191]
	v_add_f32_e32 v54, v54, v126
	v_add_f32_e32 v50, v50, v122
	v_lshl_add_u64 v[70:71], v[70:71], 0, v[180:181]
	v_mul_f32_e32 v54, 0xbfb8aa3b, v54
	v_mul_f32_e32 v50, 0xbfb8aa3b, v50
	global_store_dwordx4 v[70:71], v[66:69], off offset:2048 sc0 sc1
	v_exp_f32_e32 v54, v54
	v_add_f32_e32 v55, v55, v127
	v_exp_f32_e32 v66, v50
	v_add_f32_e32 v51, v51, v123
	v_mul_f32_e32 v55, 0xbfb8aa3b, v55
	v_mul_f32_e32 v51, 0xbfb8aa3b, v51
	v_add_f32_e32 v50, 1.0, v54
	v_add_f32_e32 v54, 1.0, v66
	v_exp_f32_e32 v55, v55
	v_exp_f32_e32 v66, v51
	v_add_f32_e32 v56, v56, v128
	v_add_f32_e32 v52, v52, v124
	v_mul_f32_e32 v56, 0xbfb8aa3b, v56
	v_mul_f32_e32 v52, 0xbfb8aa3b, v52
	v_add_f32_e32 v57, v57, v129
	v_add_f32_e32 v51, 1.0, v55
	v_add_f32_e32 v55, 1.0, v66
	v_exp_f32_e32 v56, v56
	v_exp_f32_e32 v66, v52
	v_mul_f32_e32 v57, 0xbfb8aa3b, v57
	v_exp_f32_e32 v57, v57
	v_add_f32_e32 v53, v53, v125
	v_mul_f32_e32 v53, 0xbfb8aa3b, v53
	v_add_f32_e32 v52, 1.0, v56
	v_add_f32_e32 v56, 1.0, v66
	v_exp_f32_e32 v66, v53
	v_add_f32_e32 v53, 1.0, v57
	v_rcp_f32_e32 v50, v50
	v_rcp_f32_e32 v51, v51
	v_rcp_f32_e32 v52, v52
	v_rcp_f32_e32 v53, v53
	v_rcp_f32_e32 v54, v54
	v_rcp_f32_e32 v55, v55
	v_add_f32_e32 v57, 1.0, v66
	v_pk_add_f32 v[64:65], v[64:65], v[144:145]
	v_pk_add_f32 v[62:63], v[62:63], v[142:143]
	v_rcp_f32_e32 v56, v56
	v_rcp_f32_e32 v57, v57
	v_and_b32_e32 v67, 0xffff0000, v158
	v_lshlrev_b32_e32 v66, 16, v158
	v_pk_mul_f32 v[50:51], v[62:63], v[50:51]
	v_and_b32_e32 v63, 0xffff0000, v159
	v_lshlrev_b32_e32 v62, 16, v159
	v_pk_mul_f32 v[52:53], v[64:65], v[52:53]
	v_pk_add_f32 v[58:59], v[58:59], v[134:135]
	v_pk_mul_f32 v[50:51], v[50:51], v[66:67]
	v_pk_mul_f32 v[52:53], v[52:53], v[62:63]
	v_pk_add_f32 v[60:61], v[60:61], v[136:137]
	v_cvt_pk_bf16_f32 v50, v50, v51
	v_cvt_pk_bf16_f32 v51, v52, v53
	v_and_b32_e32 v53, 0xffff0000, v160
	v_lshlrev_b32_e32 v52, 16, v160
	v_pk_mul_f32 v[54:55], v[58:59], v[54:55]
	v_pk_mul_f32 v[56:57], v[60:61], v[56:57]
	v_pk_mul_f32 v[52:53], v[54:55], v[52:53]
	v_and_b32_e32 v55, 0xffff0000, v161
	v_lshlrev_b32_e32 v54, 16, v161
	v_pk_mul_f32 v[54:55], v[56:57], v[54:55]
	v_cvt_pk_bf16_f32 v52, v52, v53
	v_cvt_pk_bf16_f32 v53, v54, v55
	v_lshl_add_u64 v[54:55], s[26:27], 0, v[188:189]
	v_add_f32_e32 v38, v38, v126
	v_add_f32_e32 v34, v34, v122
	v_lshl_add_u64 v[54:55], v[54:55], 0, v[180:181]
	v_mul_f32_e32 v38, 0xbfb8aa3b, v38
	v_mul_f32_e32 v34, 0xbfb8aa3b, v34
	global_store_dwordx4 v[54:55], v[50:53], off offset:2048 sc0 sc1
	v_exp_f32_e32 v38, v38
	v_add_f32_e32 v39, v39, v127
	v_exp_f32_e32 v50, v34
	v_add_f32_e32 v35, v35, v123
	v_mul_f32_e32 v39, 0xbfb8aa3b, v39
	v_mul_f32_e32 v35, 0xbfb8aa3b, v35
	v_add_f32_e32 v34, 1.0, v38
	v_add_f32_e32 v38, 1.0, v50
	v_exp_f32_e32 v39, v39
	v_exp_f32_e32 v50, v35
	v_add_f32_e32 v40, v40, v128
	v_add_f32_e32 v36, v36, v124
	v_mul_f32_e32 v40, 0xbfb8aa3b, v40
	v_mul_f32_e32 v36, 0xbfb8aa3b, v36
	v_add_f32_e32 v41, v41, v129
	v_add_f32_e32 v35, 1.0, v39
	v_add_f32_e32 v39, 1.0, v50
	v_exp_f32_e32 v40, v40
	v_exp_f32_e32 v50, v36
	v_mul_f32_e32 v41, 0xbfb8aa3b, v41
	v_exp_f32_e32 v41, v41
	v_add_f32_e32 v37, v37, v125
	v_mul_f32_e32 v37, 0xbfb8aa3b, v37
	v_add_f32_e32 v36, 1.0, v40
	v_add_f32_e32 v40, 1.0, v50
	v_exp_f32_e32 v50, v37
	v_add_f32_e32 v37, 1.0, v41
	v_rcp_f32_e32 v34, v34
	v_rcp_f32_e32 v35, v35
	v_rcp_f32_e32 v36, v36
	v_rcp_f32_e32 v37, v37
	v_rcp_f32_e32 v38, v38
	v_rcp_f32_e32 v39, v39
	v_add_f32_e32 v41, 1.0, v50
	v_pk_add_f32 v[48:49], v[48:49], v[144:145]
	v_pk_add_f32 v[46:47], v[46:47], v[142:143]
	v_rcp_f32_e32 v40, v40
	v_rcp_f32_e32 v41, v41
	v_and_b32_e32 v51, 0xffff0000, v154
	v_lshlrev_b32_e32 v50, 16, v154
	v_pk_mul_f32 v[34:35], v[46:47], v[34:35]
	v_and_b32_e32 v47, 0xffff0000, v155
	v_lshlrev_b32_e32 v46, 16, v155
	v_pk_mul_f32 v[36:37], v[48:49], v[36:37]
	v_pk_add_f32 v[42:43], v[42:43], v[134:135]
	v_pk_mul_f32 v[34:35], v[34:35], v[50:51]
	v_pk_mul_f32 v[36:37], v[36:37], v[46:47]
	v_pk_add_f32 v[44:45], v[44:45], v[136:137]
	v_cvt_pk_bf16_f32 v34, v34, v35
	v_cvt_pk_bf16_f32 v35, v36, v37
	v_and_b32_e32 v37, 0xffff0000, v156
	v_lshlrev_b32_e32 v36, 16, v156
	v_pk_mul_f32 v[38:39], v[42:43], v[38:39]
	v_pk_mul_f32 v[40:41], v[44:45], v[40:41]
	v_pk_mul_f32 v[36:37], v[38:39], v[36:37]
	v_and_b32_e32 v39, 0xffff0000, v157
	v_lshlrev_b32_e32 v38, 16, v157
	v_pk_mul_f32 v[38:39], v[40:41], v[38:39]
	v_cvt_pk_bf16_f32 v36, v36, v37
; __device__ __forceinline__ float fast_sigmoid(float v) { return __builtin_amdgcn_rcpf(1.f + __expf(-v)); }
; #define PG8_BAR __builtin_amdgcn_s_barrier()
; template <class CF, class Epi, class Sched, bool ALIGN_EPI, bool SP2>
; __device__ __forceinline__ void gemm_phase(LAS unsigned char* lds, const char* gA, const char* gB, const Sched& S, const Epi& E, const char* gB2 = nullptr) {
;     ...
;         if (!has_next) break;
; #pragma unroll
;         for (int a = 0; a < 2; ++a)
; #pragma unroll
;             for (int b = 0; b < 2; ++b)
; #pragma unroll
;                 for (int m = 0; m < 4; ++m)
; #pragma unroll
;                     for (int n = 0; n < 2; ++n) acc[a][b][m][n] = (f32x4){0.f, 0.f, 0.f, 0.f};
;         cur = nxt; cA = nA; cB = nB; ++ui;
;         if constexpr (BMODE == 1) cT = gB2 + (size_t)cur.g * KTG + (size_t)cur.pn * 8192 + 14336;
;         if constexpr (ALIGN_EPI) { if (wr == 1) PG8_BAR; }
;     }
;     __device__ __forceinline__ void operator()(AccRef acc, const Unit& u, int wr, int wc, int fr, int fq) const {
;         int row0 = u.pm * 256 + wr * 64 + fr; asm volatile("" : "+v"(row0)); int col0 = u.pn * 128 + wc * 32 + 8 * fq; asm volatile("" : "+v"(col0));
;         const f32x4 b10 = *(const f32x4*)(gb + col0), b11 = *(const f32x4*)(gb + col0 + 4), b20 = *(const f32x4*)(gb + SW + col0), b21 = *(const f32x4*)(gb + SW + col0 + 4);
;         u32x4 zv[2][4];
; #pragma unroll
;         for (int ai = 0; ai < 2; ++ai)
; #pragma unroll
;             for (int m = 0; m < 4; ++m) zv[ai][m] = *(const u32x4*)(zs + (size_t)(row0 + ai * HALF + m * 16) * D + PW + col0);
;         __builtin_amdgcn_sched_barrier(0);
; #pragma unroll
;         for (int ai = 0; ai < 2; ++ai)
; #pragma unroll
;             for (int m = 0; m < 4; ++m) { const size_t o = (size_t)(row0 + ai * HALF + m * 16) * D + PW + col0;
;                 f32x4 z0, z1; unpack8(zv[ai][m], z0, z1);
;                 f32x4 y10 = acc[ai][0][m][0] + b10, y11 = acc[ai][0][m][1] + b11, y20 = acc[ai][1][m][0] + b20, y21 = acc[ai][1][m][1] + b21;
; #pragma unroll
;                 for (int j = 0; j < 4; ++j) { y10[j] = y10[j] * fast_sigmoid(y20[j]) * z0[j]; y11[j] = y11[j] * fast_sigmoid(y21[j]) * z1[j]; }
;                 *(u32x4*)(branch + o) = pack8(y10, y11); }
	v_cvt_pk_bf16_f32 v37, v38, v39
	v_lshl_add_u64 v[38:39], s[26:27], 0, v[186:187]
	v_add_f32_e32 v22, v22, v126
	v_add_f32_e32 v18, v18, v122
	v_lshl_add_u64 v[38:39], v[38:39], 0, v[180:181]
	v_mul_f32_e32 v22, 0xbfb8aa3b, v22
	v_mul_f32_e32 v18, 0xbfb8aa3b, v18
	global_store_dwordx4 v[38:39], v[34:37], off offset:2048 sc0 sc1
	v_exp_f32_e32 v22, v22
	v_add_f32_e32 v23, v23, v127
	v_exp_f32_e32 v34, v18
	v_add_f32_e32 v19, v19, v123
	v_mul_f32_e32 v23, 0xbfb8aa3b, v23
	v_mul_f32_e32 v19, 0xbfb8aa3b, v19
	v_add_f32_e32 v18, 1.0, v22
	v_add_f32_e32 v22, 1.0, v34
	v_exp_f32_e32 v23, v23
	v_exp_f32_e32 v34, v19
	v_add_f32_e32 v24, v24, v128
	v_add_f32_e32 v20, v20, v124
	v_mul_f32_e32 v24, 0xbfb8aa3b, v24
	v_mul_f32_e32 v20, 0xbfb8aa3b, v20
	v_add_f32_e32 v25, v25, v129
	v_add_f32_e32 v19, 1.0, v23
	v_add_f32_e32 v23, 1.0, v34
	v_exp_f32_e32 v24, v24
	v_exp_f32_e32 v34, v20
	v_mul_f32_e32 v25, 0xbfb8aa3b, v25
	v_exp_f32_e32 v25, v25
	v_add_f32_e32 v21, v21, v125
	v_mul_f32_e32 v21, 0xbfb8aa3b, v21
	v_add_f32_e32 v20, 1.0, v24
	v_add_f32_e32 v24, 1.0, v34
	v_exp_f32_e32 v34, v21
	v_add_f32_e32 v21, 1.0, v25
	v_rcp_f32_e32 v18, v18
	v_rcp_f32_e32 v19, v19
	v_rcp_f32_e32 v20, v20
	v_rcp_f32_e32 v21, v21
	v_rcp_f32_e32 v22, v22
	v_rcp_f32_e32 v23, v23
	v_add_f32_e32 v25, 1.0, v34
	v_pk_add_f32 v[32:33], v[32:33], v[144:145]
	v_pk_add_f32 v[30:31], v[30:31], v[142:143]
	v_rcp_f32_e32 v24, v24
	v_rcp_f32_e32 v25, v25
	v_and_b32_e32 v35, 0xffff0000, v150
	v_lshlrev_b32_e32 v34, 16, v150
	v_pk_mul_f32 v[18:19], v[30:31], v[18:19]
	v_and_b32_e32 v31, 0xffff0000, v151
	v_lshlrev_b32_e32 v30, 16, v151
	v_pk_mul_f32 v[20:21], v[32:33], v[20:21]
	v_pk_add_f32 v[26:27], v[26:27], v[134:135]
	v_pk_mul_f32 v[18:19], v[18:19], v[34:35]
	v_pk_mul_f32 v[20:21], v[20:21], v[30:31]
	v_pk_add_f32 v[28:29], v[28:29], v[136:137]
	v_cvt_pk_bf16_f32 v18, v18, v19
	v_cvt_pk_bf16_f32 v19, v20, v21
	v_and_b32_e32 v21, 0xffff0000, v152
	v_lshlrev_b32_e32 v20, 16, v152
	v_pk_mul_f32 v[22:23], v[26:27], v[22:23]
	v_pk_mul_f32 v[24:25], v[28:29], v[24:25]
	v_pk_mul_f32 v[20:21], v[22:23], v[20:21]
	v_and_b32_e32 v23, 0xffff0000, v153
	v_lshlrev_b32_e32 v22, 16, v153
	v_pk_mul_f32 v[22:23], v[24:25], v[22:23]
	v_cvt_pk_bf16_f32 v20, v20, v21
	v_cvt_pk_bf16_f32 v21, v22, v23
	v_lshl_add_u64 v[22:23], s[26:27], 0, v[184:185]
	v_add_f32_e32 v6, v6, v126
	v_add_f32_e32 v2, v2, v122
	v_lshl_add_u64 v[22:23], v[22:23], 0, v[180:181]
	v_mul_f32_e32 v6, 0xbfb8aa3b, v6
	v_mul_f32_e32 v2, 0xbfb8aa3b, v2
	global_store_dwordx4 v[22:23], v[18:21], off offset:2048 sc0 sc1
	v_exp_f32_e32 v6, v6
	v_add_f32_e32 v7, v7, v127
	v_exp_f32_e32 v18, v2
	v_add_f32_e32 v3, v3, v123
	v_mul_f32_e32 v7, 0xbfb8aa3b, v7
	v_mul_f32_e32 v3, 0xbfb8aa3b, v3
	v_add_f32_e32 v2, 1.0, v6
	v_add_f32_e32 v6, 1.0, v18
	v_exp_f32_e32 v7, v7
	v_exp_f32_e32 v18, v3
	v_add_f32_e32 v8, v8, v128
	v_add_f32_e32 v4, v4, v124
	v_mul_f32_e32 v8, 0xbfb8aa3b, v8
	v_mul_f32_e32 v4, 0xbfb8aa3b, v4
	v_add_f32_e32 v9, v9, v129
	v_add_f32_e32 v3, 1.0, v7
	v_add_f32_e32 v7, 1.0, v18
	v_exp_f32_e32 v8, v8
	v_exp_f32_e32 v18, v4
	v_mul_f32_e32 v9, 0xbfb8aa3b, v9
	v_exp_f32_e32 v9, v9
	v_add_f32_e32 v5, v5, v125
	v_mul_f32_e32 v5, 0xbfb8aa3b, v5
	v_add_f32_e32 v4, 1.0, v8
	v_add_f32_e32 v8, 1.0, v18
	v_exp_f32_e32 v18, v5
	v_add_f32_e32 v5, 1.0, v9
	v_rcp_f32_e32 v2, v2
	v_rcp_f32_e32 v3, v3
	v_rcp_f32_e32 v4, v4
	v_rcp_f32_e32 v5, v5
	v_rcp_f32_e32 v6, v6
	v_rcp_f32_e32 v7, v7
	v_add_f32_e32 v9, 1.0, v18
	v_pk_add_f32 v[16:17], v[16:17], v[144:145]
	v_pk_add_f32 v[14:15], v[14:15], v[142:143]
	v_rcp_f32_e32 v8, v8
	v_rcp_f32_e32 v9, v9
	v_and_b32_e32 v19, 0xffff0000, v130
	v_lshlrev_b32_e32 v18, 16, v130
	v_pk_mul_f32 v[2:3], v[14:15], v[2:3]
	v_and_b32_e32 v15, 0xffff0000, v131
	v_lshlrev_b32_e32 v14, 16, v131
	v_pk_mul_f32 v[4:5], v[16:17], v[4:5]
	v_pk_add_f32 v[10:11], v[10:11], v[134:135]
	v_pk_mul_f32 v[2:3], v[2:3], v[18:19]
	v_pk_mul_f32 v[4:5], v[4:5], v[14:15]
	v_pk_add_f32 v[12:13], v[12:13], v[136:137]
	v_cvt_pk_bf16_f32 v2, v2, v3
	v_cvt_pk_bf16_f32 v3, v4, v5
	v_and_b32_e32 v5, 0xffff0000, v132
	v_lshlrev_b32_e32 v4, 16, v132
	v_pk_mul_f32 v[6:7], v[10:11], v[6:7]
	v_pk_mul_f32 v[8:9], v[12:13], v[8:9]
	v_pk_mul_f32 v[4:5], v[6:7], v[4:5]
	v_and_b32_e32 v7, 0xffff0000, v133
	v_lshlrev_b32_e32 v6, 16, v133
	v_pk_mul_f32 v[6:7], v[8:9], v[6:7]
	v_cvt_pk_bf16_f32 v4, v4, v5
	v_cvt_pk_bf16_f32 v5, v6, v7
	v_lshl_add_u64 v[6:7], s[26:27], 0, v[182:183]
	v_lshl_add_u64 v[6:7], v[6:7], 0, v[180:181]
	s_andn2_b64 vcc, exec, s[2:3]
	s_mov_b64 s[2:3], -1
	global_store_dwordx4 v[6:7], v[2:5], off offset:2048 sc0 sc1
	s_cbranch_vccnz .LBB0_1062
	s_andn2_b64 vcc, exec, s[24:25]
	s_cbranch_vccnz .LBB0_1061
	s_barrier
	s_branch .LBB0_1061
